# all 16-byte global stores made write-through (sc1) so the L2 write-back at each grid barrier finds little dirty data
# baseline (speedup 1.0000x reference)
; __device__ __forceinline__ unsigned pk2(float lo, float hi) { unsigned r; asm volatile("v_cvt_pk_bf16_f32 %0, %1, %2" : "=v"(r) : "v"(lo), "v"(hi)); return r; }
; #define RAW_BARRIER() do { asm volatile("s_waitcnt lgkmcnt(0)" ::: "memory"); __builtin_amdgcn_s_barrier(); asm volatile("" ::: "memory"); } while (0)
;     ...
;         RAW_BARRIER();
;         { u32x4 w;
;           w.x = pk2(tile[(k8 + 0) * 65 + n], tile[(k8 + 1) * 65 + n]); w.y = pk2(tile[(k8 + 2) * 65 + n], tile[(k8 + 3) * 65 + n]);
;           w.z = pk2(tile[(k8 + 4) * 65 + n], tile[(k8 + 5) * 65 + n]); w.w = pk2(tile[(k8 + 6) * 65 + n], tile[(k8 + 7) * 65 + n]);
;           *(u32x4*)(dst + (size_t)(n0 + n) * K + k0 + k8) = w; }
;         RAW_BARRIER();
.LBB0_10:
	s_waitcnt lgkmcnt(0)
	s_barrier
	ds_read_b32 v18, v21 offset:260
	ds_read_b32 v19, v20
	s_mul_hi_i32 s20, s24, 0x78787879
	s_lshr_b32 s21, s20, 31
	s_ashr_i32 s20, s20, 5
	s_add_i32 s21, s20, s21
	s_lshl_b32 s20, s21, 6
	s_mulk_i32 s21, 0xef00
	s_add_i32 s21, s21, s22
	s_waitcnt lgkmcnt(0)
	v_cvt_pk_bf16_f32 v26, v19, v18
	ds_read2_b32 v[18:19], v21 offset0:130 offset1:195
	v_add_u32_e32 v30, s21, v13
	s_waitcnt lgkmcnt(0)
	v_cvt_pk_bf16_f32 v27, v18, v19
	ds_read2_b32 v[18:19], v24 offset0:4 offset1:69
	v_ashrrev_i32_e32 v31, 31, v30
	s_waitcnt lgkmcnt(0)
	v_cvt_pk_bf16_f32 v28, v18, v19
	ds_read2_b32 v[18:19], v24 offset0:134 offset1:199
	v_lshlrev_b64 v[30:31], 11, v[30:31]
	s_waitcnt lgkmcnt(0)
	v_cvt_pk_bf16_f32 v29, v18, v19
	v_lshl_add_u64 v[18:19], s[16:17], 0, v[30:31]
	s_ashr_i32 s21, s20, 31
	v_lshl_add_u64 v[18:19], s[20:21], 1, v[18:19]
	v_lshl_add_u64 v[18:19], v[18:19], 0, v[16:17]
	global_store_dwordx4 v[18:19], v[26:29], off sc1
	s_waitcnt lgkmcnt(0)
	s_barrier
	s_andn2_b64 vcc, exec, s[18:19]
	s_mov_b32 s22, s25
	s_mov_b32 s24, s23
	s_cbranch_vccz .LBB0_16

; #define PG8_STAGE(bufoff, gbase, voff) do { _Pragma("unroll") for (int _i = 0; _i < 2; ++_i) \
;         __builtin_amdgcn_global_load_lds((const unsigned*)((const char*)(gbase) + (voff)[_i]), (LAS unsigned*)(lds + (bufoff) + ldsw + _i * 8192), 16, 0, 0); } while (0)
; #define PG8_LDA(dst, b, h) do { _Pragma("unroll") for (int m = 0; m < 4; ++m) _Pragma("unroll") for (int k = 0; k < 2; ++k) dst[m][k] = *(const LAS bf16x8*)(lds + PG8_SA(b, h) + aoff + m * 2048 + k * 1024); } while (0)
; #define PG8_LDB(dst, b, h) do { _Pragma("unroll") for (int n = 0; n < 2; ++n) _Pragma("unroll") for (int k = 0; k < 2; ++k) dst[n][k] = *(const LAS bf16x8*)(lds + PG8_SB(b, h) + boff + n * 2048 + k * 1024); } while (0)
; #define PG8_MMA(ai, bj, At, Bt) do { __builtin_amdgcn_s_setprio(1); _Pragma("unroll") for (int m = 0; m < 4; ++m) _Pragma("unroll") for (int n = 0; n < 2; ++n) _Pragma("unroll") for (int k = 0; k < 2; ++k) \
;         acc[ai][bj][m][n] = __builtin_amdgcn_mfma_f32_16x16x32_bf16(Bt[n][k], At[m][k], acc[ai][bj][m][n], 0, 0, 0); __builtin_amdgcn_s_setprio(0); } while (0)
; #define PG8_WAIT_V(n) asm volatile("s_waitcnt vmcnt(" #n ")" ::: "memory")
;     ...
;             PG8_LDB(B0, 0, 0); PG8_SCHED; PG8_LDA(At, 0, 0); PG8_STAGE(PG8_SA(1, 1), a1 + hA, voffA);
;             PG8_WAIT_L(8); PG8_BAR; PG8_WAIT_L(0); PG8_MMA(0, 0, At, B0); PG8_BAR; PG8_SCHED;
;             PG8_LDB(B1, 0, 1); PG8_STAGE(PG8_SB(0, 0), b2, voffB);
;             PG8_BAR; PG8_WAIT_L(0); PG8_MMA(0, 1, At, B1); PG8_BAR;
;             PG8_LDA(At, 0, 1); PG8_STAGE(PG8_SA(0, 0), a2, voffA);
;             PG8_BAR; PG8_WAIT_L(0); PG8_MMA(1, 0, At, B0); PG8_BAR; PG8_SCHED;
;             PG8_STAGE(PG8_SB(0, 1), b2 + hB, voffB);
;             PG8_WAIT_V(6); PG8_BAR; PG8_MMA(1, 1, At, B1); PG8_BAR;
;             PG8_LDB(B0, 1, 0); PG8_SCHED; PG8_LDA(At, 1, 0); PG8_STAGE(PG8_SA(0, 1), a2 + hA, voffA);
;             PG8_WAIT_L(8); PG8_BAR; PG8_WAIT_L(0); PG8_MMA(0, 0, At, B0); PG8_BAR; PG8_SCHED;
;             PG8_LDB(B1, 1, 1); PG8_STAGE(PG8_SB(1, 0), b3, voffB);
;             PG8_BAR; PG8_WAIT_L(0); PG8_MMA(0, 1, At, B1); PG8_BAR;
;             PG8_LDA(At, 1, 1); PG8_STAGE(PG8_SA(1, 0), a3, voffA);
;             PG8_BAR; PG8_WAIT_L(0); PG8_MMA(1, 0, At, B0); PG8_BAR; PG8_SCHED;
;             PG8_STAGE(PG8_SB(1, 1), b3 + hB, voffB);
;             PG8_WAIT_V(6); PG8_BAR; PG8_MMA(1, 1, At, B1); PG8_BAR;
.LBB0_125:
	ds_read_b128 v[146:149], v155
	ds_read_b128 v[160:163], v155 offset:1024
	ds_read_b128 v[170:173], v155 offset:2048
	ds_read_b128 v[174:177], v155 offset:3072
	s_add_u32 s34, s30, 0xfffc0080
	s_addc_u32 s35, s31, -1
	s_cmp_eq_u32 s44, 12
	s_cselect_b32 s37, s7, s35
	s_cselect_b32 s36, s23, s34
	s_cselect_b32 s35, s21, s43
	s_cselect_b32 s34, s33, s42
	v_lshl_add_u64 v[150:151], s[30:31], 0, v[138:139]
	s_add_i32 m0, s29, 0xc000
	ds_read_b128 v[178:181], v156
	ds_read_b128 v[182:185], v156 offset:1024
	ds_read_b128 v[186:189], v156 offset:2048
	ds_read_b128 v[190:193], v156 offset:3072
	ds_read_b128 v[194:197], v156 offset:4096
	ds_read_b128 v[198:201], v156 offset:5120
	ds_read_b128 v[202:205], v156 offset:6144
	ds_read_b128 v[206:209], v156 offset:7168
	global_load_lds_dwordx4 v[150:151], off
	v_lshl_add_u64 v[150:151], s[30:31], 0, v[136:137]
	s_add_i32 m0, s29, 0xe000
	s_nop 0
	global_load_lds_dwordx4 v[150:151], off
	s_waitcnt lgkmcnt(8)
	s_barrier
	s_waitcnt lgkmcnt(0)
	s_setprio 1
	s_waitcnt lgkmcnt(0)
	v_mfma_f32_16x16x32_bf16 v[124:127], v[146:149], v[178:181], v[124:127]
	v_mfma_f32_16x16x32_bf16 v[120:123], v[170:173], v[178:181], v[120:123]
	v_mfma_f32_16x16x32_bf16 v[108:111], v[146:149], v[186:189], v[108:111]
	v_mfma_f32_16x16x32_bf16 v[104:107], v[170:173], v[186:189], v[104:107]
	v_mfma_f32_16x16x32_bf16 v[92:95], v[146:149], v[194:197], v[92:95]
	v_mfma_f32_16x16x32_bf16 v[88:91], v[170:173], v[194:197], v[88:91]
	v_mfma_f32_16x16x32_bf16 v[76:79], v[146:149], v[202:205], v[76:79]
	v_mfma_f32_16x16x32_bf16 v[72:75], v[170:173], v[202:205], v[72:75]
	v_mfma_f32_16x16x32_bf16 v[124:127], v[160:163], v[182:185], v[124:127]
	v_mfma_f32_16x16x32_bf16 v[120:123], v[174:177], v[182:185], v[120:123]
	v_mfma_f32_16x16x32_bf16 v[108:111], v[160:163], v[190:193], v[108:111]
	v_mfma_f32_16x16x32_bf16 v[104:107], v[174:177], v[190:193], v[104:107]
	v_mfma_f32_16x16x32_bf16 v[92:95], v[160:163], v[198:201], v[92:95]
	v_mfma_f32_16x16x32_bf16 v[88:91], v[174:177], v[198:201], v[88:91]
	v_mfma_f32_16x16x32_bf16 v[76:79], v[160:163], v[206:209], v[76:79]
	v_mfma_f32_16x16x32_bf16 v[72:75], v[174:177], v[206:209], v[72:75]
	s_setprio 0
	s_barrier
	s_add_i32 s45, s59, s51
	v_lshl_add_u64 v[150:151], s[34:35], 0, v[130:131]
	s_mov_b32 m0, s45
	ds_read_b128 v[210:213], v157
	ds_read_b128 v[214:217], v157 offset:1024
	ds_read_b128 v[218:221], v157 offset:2048
	ds_read_b128 v[222:225], v157 offset:3072
	global_load_lds_dwordx4 v[150:151], off
	v_lshl_add_u64 v[164:165], s[34:35], 0, v[134:135]
	s_add_i32 m0, s45, 0x2000
	s_nop 0
	global_load_lds_dwordx4 v[164:165], off
	s_barrier
	s_waitcnt lgkmcnt(0)
	s_setprio 1
	s_waitcnt lgkmcnt(0)
	v_mfma_f32_16x16x32_bf16 v[116:119], v[210:213], v[178:181], v[116:119]
	v_mfma_f32_16x16x32_bf16 v[112:115], v[218:221], v[178:181], v[112:115]
	v_mfma_f32_16x16x32_bf16 v[100:103], v[210:213], v[186:189], v[100:103]
	v_mfma_f32_16x16x32_bf16 v[96:99], v[218:221], v[186:189], v[96:99]
	v_mfma_f32_16x16x32_bf16 v[84:87], v[210:213], v[194:197], v[84:87]
	v_mfma_f32_16x16x32_bf16 v[80:83], v[218:221], v[194:197], v[80:83]
	v_mfma_f32_16x16x32_bf16 v[68:71], v[210:213], v[202:205], v[68:71]
	v_mfma_f32_16x16x32_bf16 v[64:67], v[218:221], v[202:205], v[64:67]
	v_mfma_f32_16x16x32_bf16 v[116:119], v[214:217], v[182:185], v[116:119]
	v_mfma_f32_16x16x32_bf16 v[112:115], v[222:225], v[182:185], v[112:115]
	v_mfma_f32_16x16x32_bf16 v[100:103], v[214:217], v[190:193], v[100:103]
	v_mfma_f32_16x16x32_bf16 v[96:99], v[222:225], v[190:193], v[96:99]
	v_mfma_f32_16x16x32_bf16 v[84:87], v[214:217], v[198:201], v[84:87]
	v_mfma_f32_16x16x32_bf16 v[80:83], v[222:225], v[198:201], v[80:83]
	v_mfma_f32_16x16x32_bf16 v[68:71], v[214:217], v[206:209], v[68:71]
	v_mfma_f32_16x16x32_bf16 v[64:67], v[222:225], v[206:209], v[64:67]
	s_setprio 0
	s_mov_b32 m0, s29
	v_lshl_add_u64 v[226:227], s[36:37], 0, v[128:129]
	s_barrier
	ds_read_b128 v[178:181], v156 offset:16384
	ds_read_b128 v[182:185], v156 offset:17408
	ds_read_b128 v[186:189], v156 offset:18432
	ds_read_b128 v[190:193], v156 offset:19456
	ds_read_b128 v[194:197], v156 offset:20480
	ds_read_b128 v[198:201], v156 offset:21504
	ds_read_b128 v[202:205], v156 offset:22528
	ds_read_b128 v[206:209], v156 offset:23552
	global_load_lds_dwordx4 v[226:227], off
	v_lshl_add_u64 v[228:229], s[36:37], 0, v[132:133]
	s_mov_b32 m0, s52
	s_nop 0
	global_load_lds_dwordx4 v[228:229], off
	s_barrier
	s_waitcnt lgkmcnt(0)
	s_setprio 1
	s_waitcnt lgkmcnt(0)
	v_mfma_f32_16x16x32_bf16 v[60:63], v[146:149], v[178:181], v[60:63]
	v_mfma_f32_16x16x32_bf16 v[56:59], v[170:173], v[178:181], v[56:59]
	v_mfma_f32_16x16x32_bf16 v[44:47], v[146:149], v[186:189], v[44:47]
	v_mfma_f32_16x16x32_bf16 v[40:43], v[170:173], v[186:189], v[40:43]
	v_mfma_f32_16x16x32_bf16 v[28:31], v[146:149], v[194:197], v[28:31]
	v_mfma_f32_16x16x32_bf16 v[24:27], v[170:173], v[194:197], v[24:27]
	v_mfma_f32_16x16x32_bf16 v[12:15], v[146:149], v[202:205], v[12:15]
	v_mfma_f32_16x16x32_bf16 v[8:11], v[170:173], v[202:205], v[8:11]
	v_mfma_f32_16x16x32_bf16 v[60:63], v[160:163], v[182:185], v[60:63]
	v_mfma_f32_16x16x32_bf16 v[56:59], v[174:177], v[182:185], v[56:59]
	v_mfma_f32_16x16x32_bf16 v[44:47], v[160:163], v[190:193], v[44:47]
	v_mfma_f32_16x16x32_bf16 v[40:43], v[174:177], v[190:193], v[40:43]
	v_mfma_f32_16x16x32_bf16 v[28:31], v[160:163], v[198:201], v[28:31]
	v_mfma_f32_16x16x32_bf16 v[24:27], v[174:177], v[198:201], v[24:27]
	v_mfma_f32_16x16x32_bf16 v[12:15], v[160:163], v[206:209], v[12:15]
	v_mfma_f32_16x16x32_bf16 v[8:11], v[174:177], v[206:209], v[8:11]
	s_setprio 0
	s_barrier
; #define PG8_STAGE(bufoff, gbase, voff) do { _Pragma("unroll") for (int _i = 0; _i < 2; ++_i) \
;         __builtin_amdgcn_global_load_lds((const unsigned*)((const char*)(gbase) + (voff)[_i]), (LAS unsigned*)(lds + (bufoff) + ldsw + _i * 8192), 16, 0, 0); } while (0)
; #define PG8_LDA(dst, b, h) do { _Pragma("unroll") for (int m = 0; m < 4; ++m) _Pragma("unroll") for (int k = 0; k < 2; ++k) dst[m][k] = *(const LAS bf16x8*)(lds + PG8_SA(b, h) + aoff + m * 2048 + k * 1024); } while (0)
; #define PG8_LDB(dst, b, h) do { _Pragma("unroll") for (int n = 0; n < 2; ++n) _Pragma("unroll") for (int k = 0; k < 2; ++k) dst[n][k] = *(const LAS bf16x8*)(lds + PG8_SB(b, h) + boff + n * 2048 + k * 1024); } while (0)
; #define PG8_MMA(ai, bj, At, Bt) do { __builtin_amdgcn_s_setprio(1); _Pragma("unroll") for (int m = 0; m < 4; ++m) _Pragma("unroll") for (int n = 0; n < 2; ++n) _Pragma("unroll") for (int k = 0; k < 2; ++k) \
;         acc[ai][bj][m][n] = __builtin_amdgcn_mfma_f32_16x16x32_bf16(Bt[n][k], At[m][k], acc[ai][bj][m][n], 0, 0, 0); __builtin_amdgcn_s_setprio(0); } while (0)
; #define PG8_WAIT_V(n) asm volatile("s_waitcnt vmcnt(" #n ")" ::: "memory")
;     ...
;             PG8_LDB(B0, 0, 0); PG8_SCHED; PG8_LDA(At, 0, 0); PG8_STAGE(PG8_SA(1, 1), a1 + hA, voffA);
;             PG8_WAIT_L(8); PG8_BAR; PG8_WAIT_L(0); PG8_MMA(0, 0, At, B0); PG8_BAR; PG8_SCHED;
;             PG8_LDB(B1, 0, 1); PG8_STAGE(PG8_SB(0, 0), b2, voffB);
;             PG8_BAR; PG8_WAIT_L(0); PG8_MMA(0, 1, At, B1); PG8_BAR;
;             PG8_LDA(At, 0, 1); PG8_STAGE(PG8_SA(0, 0), a2, voffA);
;             PG8_BAR; PG8_WAIT_L(0); PG8_MMA(1, 0, At, B0); PG8_BAR; PG8_SCHED;
;             PG8_STAGE(PG8_SB(0, 1), b2 + hB, voffB);
;             PG8_WAIT_V(6); PG8_BAR; PG8_MMA(1, 1, At, B1); PG8_BAR;
;             PG8_LDB(B0, 1, 0); PG8_SCHED; PG8_LDA(At, 1, 0); PG8_STAGE(PG8_SA(0, 1), a2 + hA, voffA);
;             PG8_WAIT_L(8); PG8_BAR; PG8_WAIT_L(0); PG8_MMA(0, 0, At, B0); PG8_BAR; PG8_SCHED;
;             PG8_LDB(B1, 1, 1); PG8_STAGE(PG8_SB(1, 0), b3, voffB);
;             PG8_BAR; PG8_WAIT_L(0); PG8_MMA(0, 1, At, B1); PG8_BAR;
;             PG8_LDA(At, 1, 1); PG8_STAGE(PG8_SA(1, 0), a3, voffA);
;             PG8_BAR; PG8_WAIT_L(0); PG8_MMA(1, 0, At, B0); PG8_BAR; PG8_SCHED;
;             PG8_STAGE(PG8_SB(1, 1), b3 + hB, voffB);
;             PG8_WAIT_V(6); PG8_BAR; PG8_MMA(1, 1, At, B1); PG8_BAR;
	s_add_u32 s64, s34, 0x40000
	s_addc_u32 s65, s35, 0
	s_add_i32 s45, s60, s51
	v_lshl_add_u64 v[146:147], s[64:65], 0, v[130:131]
	s_mov_b32 m0, s45
	s_nop 0
	global_load_lds_dwordx4 v[146:147], off
	v_lshl_add_u64 v[146:147], s[64:65], 0, v[134:135]
	s_add_i32 m0, s45, 0x2000
	s_nop 0
	global_load_lds_dwordx4 v[146:147], off
	s_waitcnt vmcnt(6)
	s_barrier
	s_setprio 1
	v_mfma_f32_16x16x32_bf16 v[52:55], v[210:213], v[178:181], v[52:55]
	v_mfma_f32_16x16x32_bf16 v[48:51], v[218:221], v[178:181], v[48:51]
	v_mfma_f32_16x16x32_bf16 v[36:39], v[210:213], v[186:189], v[36:39]
	v_mfma_f32_16x16x32_bf16 v[32:35], v[218:221], v[186:189], v[32:35]
	v_mfma_f32_16x16x32_bf16 v[20:23], v[210:213], v[194:197], v[20:23]
	v_mfma_f32_16x16x32_bf16 v[16:19], v[218:221], v[194:197], v[16:19]
	v_mfma_f32_16x16x32_bf16 v[4:7], v[210:213], v[202:205], v[4:7]
	v_mfma_f32_16x16x32_bf16 v[0:3], v[218:221], v[202:205], v[0:3]
	v_mfma_f32_16x16x32_bf16 v[52:55], v[214:217], v[182:185], v[52:55]
	v_mfma_f32_16x16x32_bf16 v[48:51], v[222:225], v[182:185], v[48:51]
	v_mfma_f32_16x16x32_bf16 v[36:39], v[214:217], v[190:193], v[36:39]
	v_mfma_f32_16x16x32_bf16 v[32:35], v[222:225], v[190:193], v[32:35]
	v_mfma_f32_16x16x32_bf16 v[20:23], v[214:217], v[198:201], v[20:23]
	v_mfma_f32_16x16x32_bf16 v[16:19], v[222:225], v[198:201], v[16:19]
	v_mfma_f32_16x16x32_bf16 v[4:7], v[214:217], v[206:209], v[4:7]
	v_mfma_f32_16x16x32_bf16 v[0:3], v[222:225], v[206:209], v[0:3]
	s_setprio 0
	s_add_i32 s45, 0, 0x18000
	v_add_u32_e32 v159, s45, v153
	s_barrier
	ds_read_b128 v[146:149], v159
	ds_read_b128 v[160:163], v159 offset:1024
	ds_read_b128 v[170:173], v159 offset:2048
	ds_read_b128 v[174:177], v159 offset:3072
	s_add_u32 s36, s36, 0x40000
	s_addc_u32 s37, s37, 0
	s_mov_b32 m0, s53
	v_lshl_add_u64 v[210:211], s[36:37], 0, v[128:129]
	ds_read_b128 v[178:181], v156 offset:32768
	ds_read_b128 v[182:185], v156 offset:33792
	ds_read_b128 v[186:189], v156 offset:34816
	ds_read_b128 v[190:193], v156 offset:35840
	ds_read_b128 v[194:197], v156 offset:36864
	ds_read_b128 v[198:201], v156 offset:37888
	ds_read_b128 v[202:205], v156 offset:38912
	ds_read_b128 v[206:209], v156 offset:39936
	global_load_lds_dwordx4 v[210:211], off
	v_lshl_add_u64 v[210:211], s[36:37], 0, v[132:133]
	s_mov_b32 m0, s54
	s_nop 0
	global_load_lds_dwordx4 v[210:211], off
	s_waitcnt lgkmcnt(8)
	s_barrier
	s_waitcnt lgkmcnt(0)
	s_setprio 1
	s_waitcnt lgkmcnt(0)
	v_mfma_f32_16x16x32_bf16 v[124:127], v[146:149], v[178:181], v[124:127]
	v_mfma_f32_16x16x32_bf16 v[120:123], v[170:173], v[178:181], v[120:123]
	v_mfma_f32_16x16x32_bf16 v[108:111], v[146:149], v[186:189], v[108:111]
	v_mfma_f32_16x16x32_bf16 v[104:107], v[170:173], v[186:189], v[104:107]
	v_mfma_f32_16x16x32_bf16 v[92:95], v[146:149], v[194:197], v[92:95]
	v_mfma_f32_16x16x32_bf16 v[88:91], v[170:173], v[194:197], v[88:91]
	v_mfma_f32_16x16x32_bf16 v[76:79], v[146:149], v[202:205], v[76:79]
	v_mfma_f32_16x16x32_bf16 v[72:75], v[170:173], v[202:205], v[72:75]
	v_mfma_f32_16x16x32_bf16 v[124:127], v[160:163], v[182:185], v[124:127]
	v_mfma_f32_16x16x32_bf16 v[120:123], v[174:177], v[182:185], v[120:123]
	v_mfma_f32_16x16x32_bf16 v[108:111], v[160:163], v[190:193], v[108:111]
	v_mfma_f32_16x16x32_bf16 v[104:107], v[174:177], v[190:193], v[104:107]
	v_mfma_f32_16x16x32_bf16 v[92:95], v[160:163], v[198:201], v[92:95]
	v_mfma_f32_16x16x32_bf16 v[88:91], v[174:177], v[198:201], v[88:91]
	v_mfma_f32_16x16x32_bf16 v[76:79], v[160:163], v[206:209], v[76:79]
	v_mfma_f32_16x16x32_bf16 v[72:75], v[174:177], v[206:209], v[72:75]
	s_setprio 0
	s_barrier
	s_add_i32 s36, 0, 0x1c000
	s_add_i32 s37, s45, s51
	v_add_u32_e32 v159, s36, v153
	v_lshl_add_u64 v[150:151], v[150:151], 0, s[18:19]
	s_mov_b32 m0, s37
	ds_read_b128 v[210:213], v159
	ds_read_b128 v[214:217], v159 offset:1024
	ds_read_b128 v[218:221], v159 offset:2048
	ds_read_b128 v[222:225], v159 offset:3072
	global_load_lds_dwordx4 v[150:151], off
	v_lshl_add_u64 v[150:151], v[164:165], 0, s[18:19]
	s_add_i32 m0, s37, 0x2000
	s_nop 0
	global_load_lds_dwordx4 v[150:151], off
	s_barrier
	s_waitcnt lgkmcnt(0)
	s_setprio 1
	s_waitcnt lgkmcnt(0)
	v_mfma_f32_16x16x32_bf16 v[116:119], v[210:213], v[178:181], v[116:119]
	v_mfma_f32_16x16x32_bf16 v[112:115], v[218:221], v[178:181], v[112:115]
	v_mfma_f32_16x16x32_bf16 v[100:103], v[210:213], v[186:189], v[100:103]
	v_mfma_f32_16x16x32_bf16 v[96:99], v[218:221], v[186:189], v[96:99]
	v_mfma_f32_16x16x32_bf16 v[84:87], v[210:213], v[194:197], v[84:87]
	v_mfma_f32_16x16x32_bf16 v[80:83], v[218:221], v[194:197], v[80:83]
	v_mfma_f32_16x16x32_bf16 v[68:71], v[210:213], v[202:205], v[68:71]
	v_mfma_f32_16x16x32_bf16 v[64:67], v[218:221], v[202:205], v[64:67]
	v_mfma_f32_16x16x32_bf16 v[116:119], v[214:217], v[182:185], v[116:119]
	v_mfma_f32_16x16x32_bf16 v[112:115], v[222:225], v[182:185], v[112:115]
	v_mfma_f32_16x16x32_bf16 v[100:103], v[214:217], v[190:193], v[100:103]
	v_mfma_f32_16x16x32_bf16 v[96:99], v[222:225], v[190:193], v[96:99]
	v_mfma_f32_16x16x32_bf16 v[84:87], v[214:217], v[198:201], v[84:87]
	v_mfma_f32_16x16x32_bf16 v[80:83], v[222:225], v[198:201], v[80:83]
	v_mfma_f32_16x16x32_bf16 v[68:71], v[214:217], v[206:209], v[68:71]
	v_mfma_f32_16x16x32_bf16 v[64:67], v[222:225], v[206:209], v[64:67]
	s_setprio 0
	s_mov_b32 m0, s56
	v_lshl_add_u64 v[150:151], v[226:227], 0, s[18:19]
	s_barrier
	ds_read_b128 v[178:181], v156 offset:49152
	ds_read_b128 v[182:185], v156 offset:50176
	ds_read_b128 v[186:189], v156 offset:51200
	ds_read_b128 v[190:193], v156 offset:52224
	ds_read_b128 v[194:197], v156 offset:53248
	ds_read_b128 v[198:201], v156 offset:54272
	ds_read_b128 v[202:205], v156 offset:55296
	ds_read_b128 v[206:209], v156 offset:56320
	global_load_lds_dwordx4 v[150:151], off
	v_lshl_add_u64 v[150:151], v[228:229], 0, s[18:19]
	s_mov_b32 m0, s57
	s_nop 0
	global_load_lds_dwordx4 v[150:151], off
	s_barrier
; #define PG8_STAGE(bufoff, gbase, voff) do { _Pragma("unroll") for (int _i = 0; _i < 2; ++_i) \
;         __builtin_amdgcn_global_load_lds((const unsigned*)((const char*)(gbase) + (voff)[_i]), (LAS unsigned*)(lds + (bufoff) + ldsw + _i * 8192), 16, 0, 0); } while (0)
; #define PG8_LDA(dst, b, h) do { _Pragma("unroll") for (int m = 0; m < 4; ++m) _Pragma("unroll") for (int k = 0; k < 2; ++k) dst[m][k] = *(const LAS bf16x8*)(lds + PG8_SA(b, h) + aoff + m * 2048 + k * 1024); } while (0)
; #define PG8_LDB(dst, b, h) do { _Pragma("unroll") for (int n = 0; n < 2; ++n) _Pragma("unroll") for (int k = 0; k < 2; ++k) dst[n][k] = *(const LAS bf16x8*)(lds + PG8_SB(b, h) + boff + n * 2048 + k * 1024); } while (0)
; #define PG8_WAIT_V(n) asm volatile("s_waitcnt vmcnt(" #n ")" ::: "memory")
;     ...
;             PG8_LDB(B0, 0, 0); PG8_SCHED; PG8_LDA(At, 0, 0); PG8_STAGE(PG8_SA(1, 1), a1 + hA, voffA);
;             PG8_WAIT_L(8); PG8_BAR; PG8_WAIT_L(0); PG8_MMA(0, 0, At, B0); PG8_BAR; PG8_SCHED;
;             PG8_LDB(B1, 0, 1); PG8_STAGE(PG8_SB(0, 0), b2, voffB);
;             PG8_BAR; PG8_WAIT_L(0); PG8_MMA(0, 1, At, B1); PG8_BAR;
;             PG8_LDA(At, 0, 1); PG8_STAGE(PG8_SA(0, 0), a2, voffA);
;             PG8_BAR; PG8_WAIT_L(0); PG8_MMA(1, 0, At, B0); PG8_BAR; PG8_SCHED;
;             PG8_STAGE(PG8_SB(0, 1), b2 + hB, voffB);
;             PG8_WAIT_V(6); PG8_BAR; PG8_MMA(1, 1, At, B1); PG8_BAR;
;             PG8_LDB(B0, 1, 0); PG8_SCHED; PG8_LDA(At, 1, 0); PG8_STAGE(PG8_SA(0, 1), a2 + hA, voffA);
;             PG8_WAIT_L(8); PG8_BAR; PG8_WAIT_L(0); PG8_MMA(0, 0, At, B0); PG8_BAR; PG8_SCHED;
;             PG8_LDB(B1, 1, 1); PG8_STAGE(PG8_SB(1, 0), b3, voffB);
;             PG8_BAR; PG8_WAIT_L(0); PG8_MMA(0, 1, At, B1); PG8_BAR;
;             PG8_LDA(At, 1, 1); PG8_STAGE(PG8_SA(1, 0), a3, voffA);
;             PG8_BAR; PG8_WAIT_L(0); PG8_MMA(1, 0, At, B0); PG8_BAR; PG8_SCHED;
;             PG8_STAGE(PG8_SB(1, 1), b3 + hB, voffB);
;             PG8_WAIT_V(6); PG8_BAR; PG8_MMA(1, 1, At, B1); PG8_BAR;
; __device__ __forceinline__ float row_rstd(const float* ssq, int row) {
;     const f32x4* p = (const f32x4*)(ssq + (size_t)row * 16);
;     const f32x4 a = p[0], b = p[1], c = p[2], d = p[3];
;     const float s = ((a[0] + a[1]) + (a[2] + a[3])) + ((b[0] + b[1]) + (b[2] + b[3])) + ((c[0] + c[1]) + (c[2] + c[3])) + ((d[0] + d[1]) + (d[2] + d[3]));
	s_waitcnt lgkmcnt(0)
	s_setprio 1
	s_waitcnt lgkmcnt(0)
	v_mfma_f32_16x16x32_bf16 v[60:63], v[146:149], v[178:181], v[60:63]
	v_mfma_f32_16x16x32_bf16 v[56:59], v[170:173], v[178:181], v[56:59]
	v_mfma_f32_16x16x32_bf16 v[44:47], v[146:149], v[186:189], v[44:47]
	v_mfma_f32_16x16x32_bf16 v[40:43], v[170:173], v[186:189], v[40:43]
	v_mfma_f32_16x16x32_bf16 v[28:31], v[146:149], v[194:197], v[28:31]
	v_mfma_f32_16x16x32_bf16 v[24:27], v[170:173], v[194:197], v[24:27]
	v_mfma_f32_16x16x32_bf16 v[12:15], v[146:149], v[202:205], v[12:15]
	v_mfma_f32_16x16x32_bf16 v[8:11], v[170:173], v[202:205], v[8:11]
	v_mfma_f32_16x16x32_bf16 v[60:63], v[160:163], v[182:185], v[60:63]
	v_mfma_f32_16x16x32_bf16 v[56:59], v[174:177], v[182:185], v[56:59]
	v_mfma_f32_16x16x32_bf16 v[44:47], v[160:163], v[190:193], v[44:47]
	v_mfma_f32_16x16x32_bf16 v[40:43], v[174:177], v[190:193], v[40:43]
	v_mfma_f32_16x16x32_bf16 v[28:31], v[160:163], v[198:201], v[28:31]
	v_mfma_f32_16x16x32_bf16 v[24:27], v[174:177], v[198:201], v[24:27]
	v_mfma_f32_16x16x32_bf16 v[12:15], v[160:163], v[206:209], v[12:15]
	v_mfma_f32_16x16x32_bf16 v[8:11], v[174:177], v[206:209], v[8:11]
	s_setprio 0
	s_barrier
	s_add_u32 s34, s34, 0x40080
	s_addc_u32 s35, s35, 0
	s_add_i32 s36, s36, s51
	v_lshl_add_u64 v[146:147], s[34:35], 0, v[130:131]
	s_mov_b32 m0, s36
	s_nop 0
	global_load_lds_dwordx4 v[146:147], off
	v_lshl_add_u64 v[146:147], s[34:35], 0, v[134:135]
	s_add_i32 m0, s36, 0x2000
	s_nop 0
	global_load_lds_dwordx4 v[146:147], off
	s_waitcnt vmcnt(6)
	s_barrier
	s_setprio 1
	v_mfma_f32_16x16x32_bf16 v[52:55], v[210:213], v[178:181], v[52:55]
	v_mfma_f32_16x16x32_bf16 v[48:51], v[218:221], v[178:181], v[48:51]
	v_mfma_f32_16x16x32_bf16 v[36:39], v[210:213], v[186:189], v[36:39]
	v_mfma_f32_16x16x32_bf16 v[32:35], v[218:221], v[186:189], v[32:35]
	v_mfma_f32_16x16x32_bf16 v[20:23], v[210:213], v[194:197], v[20:23]
	v_mfma_f32_16x16x32_bf16 v[16:19], v[218:221], v[194:197], v[16:19]
	v_mfma_f32_16x16x32_bf16 v[4:7], v[210:213], v[202:205], v[4:7]
	v_mfma_f32_16x16x32_bf16 v[0:3], v[218:221], v[202:205], v[0:3]
	v_mfma_f32_16x16x32_bf16 v[52:55], v[214:217], v[182:185], v[52:55]
	v_mfma_f32_16x16x32_bf16 v[48:51], v[222:225], v[182:185], v[48:51]
	v_mfma_f32_16x16x32_bf16 v[36:39], v[214:217], v[190:193], v[36:39]
	v_mfma_f32_16x16x32_bf16 v[32:35], v[222:225], v[190:193], v[32:35]
	v_mfma_f32_16x16x32_bf16 v[20:23], v[214:217], v[198:201], v[20:23]
	v_mfma_f32_16x16x32_bf16 v[16:19], v[222:225], v[198:201], v[16:19]
	v_mfma_f32_16x16x32_bf16 v[4:7], v[214:217], v[206:209], v[4:7]
	v_mfma_f32_16x16x32_bf16 v[0:3], v[222:225], v[206:209], v[0:3]
	s_setprio 0
	s_add_i32 s44, s44, 2
	s_add_u32 s42, s42, 0x100
	s_addc_u32 s43, s43, 0
	s_add_u32 s30, s30, 0x100
	s_addc_u32 s31, s31, 0
	s_cmp_gt_u32 s44, 13
	s_barrier
	s_cbranch_scc0 .LBB0_125
	v_lshl_add_u32 v150, s28, 8, v152
	v_ashrrev_i32_e32 v151, 31, v150
	v_lshlrev_b64 v[146:147], 6, v[150:151]
	v_lshl_add_u64 v[146:147], s[16:17], 0, v[146:147]
	v_subrev_u32_e32 v186, s16, v146
	v_add_u32_e32 v187, 0x0, v186
	global_load_dwordx4 v[188:191], v187, s[16:17]
	v_add_u32_e32 v187, 0x20, v186
	global_load_dwordx4 v[192:195], v187, s[16:17]
	v_add_u32_e32 v187, 0x10, v186
	global_load_dwordx4 v[196:199], v187, s[16:17]
	v_add_u32_e32 v187, 0x30, v186
	global_load_dwordx4 v[200:203], v187, s[16:17]
	v_add_u32_e32 v187, 0x400, v186
	global_load_dwordx4 v[204:207], v187, s[16:17]
	v_add_u32_e32 v187, 0x410, v186
	global_load_dwordx4 v[208:211], v187, s[16:17]
	v_add_u32_e32 v187, 0x420, v186
	global_load_dwordx4 v[212:215], v187, s[16:17]
	v_add_u32_e32 v187, 0x430, v186
	global_load_dwordx4 v[216:219], v187, s[16:17]
	v_add_u32_e32 v187, 0x800, v186
	global_load_dwordx4 v[220:223], v187, s[16:17]
	v_add_u32_e32 v187, 0x810, v186
	global_load_dwordx4 v[232:235], v187, s[16:17]
	v_add_u32_e32 v187, 0x820, v186
	global_load_dwordx4 v[236:239], v187, s[16:17]
	v_add_u32_e32 v187, 0x830, v186
	global_load_dwordx4 v[240:243], v187, s[16:17]
	v_lshl_or_b32 v148, s6, 8, v154
	v_mov_b64_e32 v[146:147], s[14:15]
	v_ashrrev_i32_e32 v149, 31, v148
	v_mad_i64_i32 v[164:165], s[6:7], v150, s62, v[146:147]
	v_or_b32_e32 v182, 16, v150
	v_lshlrev_b64 v[148:149], 1, v[148:149]
	v_ashrrev_i32_e32 v183, 31, v182
	s_mov_b64 s[34:35], s[24:25]
	s_mov_b32 s28, s22
	s_mov_b64 s[30:31], s[26:27]
	s_waitcnt vmcnt(8)
; __device__ __forceinline__ float bflo(unsigned w) { return __uint_as_float(w << 16); }
; __device__ __forceinline__ float bfhi(unsigned w) { return __uint_as_float(w & 0xffff0000u); }
; __device__ __forceinline__ unsigned pk2(float lo, float hi) { unsigned r; asm volatile("v_cvt_pk_bf16_f32 %0, %1, %2" : "=v"(r) : "v"(lo), "v"(hi)); return r; }
; __device__ __forceinline__ float row_rstd(const float* ssq, int row) {
;     const f32x4* p = (const f32x4*)(ssq + (size_t)row * 16);
;     const f32x4 a = p[0], b = p[1], c = p[2], d = p[3];
;     const float s = ((a[0] + a[1]) + (a[2] + a[3])) + ((b[0] + b[1]) + (b[2] + b[3])) + ((c[0] + c[1]) + (c[2] + c[3])) + ((d[0] + d[1]) + (d[2] + d[3]));
;     return rsqrtf(s * (1.0f / 1024.0f) + 1e-6f);
; }
; __device__ __forceinline__ u32x4 pack8(const f32x4 v0, const f32x4 v1) { u32x4 w; w.x = pk2(v0[0], v0[1]); w.y = pk2(v0[2], v0[3]); w.z = pk2(v1[0], v1[1]); w.w = pk2(v1[2], v1[3]); return w; }
; __device__ __forceinline__ void unpack8(const u32x4 w, f32x4& v0, f32x4& v1) { v0 = (f32x4){bflo(w.x), bfhi(w.x), bflo(w.y), bfhi(w.y)}; v1 = (f32x4){bflo(w.z), bfhi(w.z), bflo(w.w), bfhi(w.w)}; }
;     __device__ __forceinline__ void operator()(const f32x4 (&acc)[2][2][4][2], const Unit& u, int wr, int wc, int fr, int fq) const {
;         const int row0 = u.pm * 256 + wr * 64 + fr, col0 = u.pn * 256 + wc * 32 + 8 * fq;
; #pragma unroll
;         for (int ai = 0; ai < 2; ++ai)
; #pragma unroll
;             for (int m = 0; m < 4; ++m) {
;                 const int row = row0 + ai * 128 + m * 16; const float rs = row_rstd(ssq, row);
;                 bf16_t* rowp = O + (size_t)row * ldc + col0;
; #pragma unroll
;                 for (int bj = 0; bj < 2; ++bj) { f32x4 v0 = acc[ai][bj][m][0] * rs, v1 = acc[ai][bj][m][1] * rs;
;                     if (ACT == 1) {
; #pragma unroll
;                         for (int j = 0; j < 4; ++j) { const float a = fmaxf(v0[j], 0.f), b = fmaxf(v1[j], 0.f); v0[j] = a * a; v1[j] = b * b; } }
;                     *(u32x4*)(rowp + bj * 128) = pack8(v0, v1); }
	v_mov_b32_e32 v160, v188
	v_mov_b32_e32 v161, v189
	v_mov_b32_e32 v162, v190
	v_mov_b32_e32 v163, v191
	v_mov_b32_e32 v170, v192
	v_mov_b32_e32 v171, v193
	v_mov_b32_e32 v172, v194
	v_mov_b32_e32 v173, v195
	v_mov_b32_e32 v174, v196
	v_mov_b32_e32 v175, v197
	v_mov_b32_e32 v176, v198
	v_mov_b32_e32 v177, v199
	v_mov_b32_e32 v178, v200
	v_mov_b32_e32 v179, v201
	v_mov_b32_e32 v180, v202
	v_mov_b32_e32 v181, v203
	v_add_u32_e32 v187, 0xc00, v186
	global_load_dwordx4 v[188:191], v187, s[16:17]
	v_add_u32_e32 v187, 0xc10, v186
	global_load_dwordx4 v[192:195], v187, s[16:17]
	v_add_u32_e32 v187, 0xc20, v186
	global_load_dwordx4 v[196:199], v187, s[16:17]
	v_add_u32_e32 v187, 0xc30, v186
	global_load_dwordx4 v[200:203], v187, s[16:17]
	v_mov_b32_e32 v184, v161
	v_mov_b32_e32 v185, v162
	v_mov_b32_e32 v161, v163
	v_add_f32_e32 v162, v170, v171
	v_add_f32_e32 v170, v172, v173
	v_mov_b32_e32 v172, v175
	v_mov_b32_e32 v173, v176
	v_mov_b32_e32 v175, v177
	v_mov_b32_e32 v163, v180
	v_mov_b32_e32 v171, v181
	v_pk_add_f32 v[160:161], v[184:185], v[160:161]
	v_pk_add_f32 v[172:173], v[172:173], v[174:175]
	v_pk_add_f32 v[162:163], v[162:163], v[170:171]
	v_pk_add_f32 v[160:161], v[160:161], v[160:161] op_sel:[0,1] op_sel_hi:[1,0]
	v_pk_add_f32 v[170:171], v[172:173], v[172:173] op_sel:[0,1] op_sel_hi:[1,0]
	v_mov_b32_e32 v161, v178
	v_mov_b32_e32 v171, v179
	v_pk_add_f32 v[160:161], v[160:161], v[170:171]
	s_nop 0
	v_pk_add_f32 v[160:161], v[160:161], v[162:163]
	v_lshlrev_b64 v[162:163], 6, v[182:183]
	v_add_f32_e32 v151, v160, v161
	v_fmamk_f32 v151, v151, 0x3a800000, v158
	v_mul_f32_e32 v159, 0x4b800000, v151
	v_cmp_gt_f32_e32 vcc, s61, v151
	v_lshl_add_u64 v[160:161], v[164:165], 0, v[148:149]
	v_lshl_add_u64 v[162:163], s[16:17], 0, v[162:163]
	v_cndmask_b32_e32 v151, v151, v159, vcc
	v_rsq_f32_e32 v151, v151
	s_nop 0
	v_mul_f32_e32 v159, 0x45800000, v151
	v_cndmask_b32_e32 v164, v151, v159, vcc
	v_pk_mul_f32 v[126:127], v[126:127], v[164:165] op_sel_hi:[1,0]
	v_pk_mul_f32 v[124:125], v[124:125], v[164:165] op_sel_hi:[1,0]
	v_pk_mul_f32 v[122:123], v[122:123], v[164:165] op_sel_hi:[1,0]
	v_pk_mul_f32 v[120:121], v[120:121], v[164:165] op_sel_hi:[1,0]
	v_pk_mul_f32 v[118:119], v[118:119], v[164:165] op_sel_hi:[1,0]
	v_pk_mul_f32 v[116:117], v[116:117], v[164:165] op_sel_hi:[1,0]
	v_pk_mul_f32 v[170:171], v[114:115], v[164:165] op_sel_hi:[1,0]
	v_pk_mul_f32 v[164:165], v[112:113], v[164:165] op_sel_hi:[1,0]
	v_cvt_pk_bf16_f32 v112, v124, v125
	v_cvt_pk_bf16_f32 v113, v126, v127
	v_cvt_pk_bf16_f32 v114, v120, v121
	v_cvt_pk_bf16_f32 v115, v122, v123
	global_store_dwordx4 v[160:161], v[112:115], off sc1
	s_nop 1
	v_cvt_pk_bf16_f32 v112, v116, v117
	v_cvt_pk_bf16_f32 v113, v118, v119
	v_cvt_pk_bf16_f32 v114, v164, v165
	v_cvt_pk_bf16_f32 v115, v170, v171
	global_store_dwordx4 v[160:161], v[112:115], off offset:256 sc1
	s_nop 0
	v_or_b32_e32 v160, 32, v150
	v_mad_i64_i32 v[162:163], s[6:7], v182, s62, v[146:147]
	v_ashrrev_i32_e32 v161, 31, v160
	s_waitcnt vmcnt(10)
	v_mov_b32_e32 v112, v204
	v_mov_b32_e32 v113, v205
	v_mov_b32_e32 v114, v206
	v_mov_b32_e32 v115, v207
	v_mov_b32_e32 v116, v208
	v_mov_b32_e32 v117, v209
	v_mov_b32_e32 v118, v210
	v_mov_b32_e32 v119, v211
	v_mov_b32_e32 v120, v212
	v_mov_b32_e32 v121, v213
	v_mov_b32_e32 v122, v214
	v_mov_b32_e32 v123, v215
	v_mov_b32_e32 v124, v216
	v_mov_b32_e32 v125, v217
	v_mov_b32_e32 v126, v218
	v_mov_b32_e32 v127, v219
	v_add_u32_e32 v187, 0x2000, v186
	global_load_dwordx4 v[204:207], v187, s[16:17]
	v_add_u32_e32 v187, 0x2010, v186
	global_load_dwordx4 v[208:211], v187, s[16:17]
	v_add_u32_e32 v187, 0x2020, v186
	global_load_dwordx4 v[212:215], v187, s[16:17]
	v_add_u32_e32 v187, 0x2030, v186
	global_load_dwordx4 v[216:219], v187, s[16:17]
	v_mov_b32_e32 v164, v113
	v_mov_b32_e32 v165, v114
	v_mov_b32_e32 v113, v115
	v_mov_b32_e32 v114, v117
	v_mov_b32_e32 v115, v118
	v_mov_b32_e32 v117, v119
	v_pk_add_f32 v[112:113], v[164:165], v[112:113]
	v_pk_add_f32 v[114:115], v[114:115], v[116:117]
	v_pk_add_f32 v[112:113], v[112:113], v[112:113] op_sel:[0,1] op_sel_hi:[1,0]
	v_pk_add_f32 v[114:115], v[114:115], v[114:115] op_sel:[0,1] op_sel_hi:[1,0]
	v_add_f32_e32 v118, v120, v121
	v_add_f32_e32 v120, v122, v123
	v_mov_b32_e32 v119, v126
	v_mov_b32_e32 v121, v127
	v_mov_b32_e32 v113, v124
	v_mov_b32_e32 v115, v125
	v_pk_add_f32 v[116:117], v[118:119], v[120:121]
	v_pk_add_f32 v[112:113], v[112:113], v[114:115]
	v_lshlrev_b64 v[114:115], 6, v[160:161]
	v_pk_add_f32 v[112:113], v[112:113], v[116:117]
	v_lshl_add_u64 v[114:115], s[16:17], 0, v[114:115]
	v_add_f32_e32 v112, v112, v113
	v_fmamk_f32 v112, v112, 0x3a800000, v158
	v_mul_f32_e32 v113, 0x4b800000, v112
	v_cmp_gt_f32_e32 vcc, s61, v112
	s_nop 1
	v_cndmask_b32_e32 v112, v112, v113, vcc
	v_rsq_f32_e32 v116, v112
	v_lshl_add_u64 v[112:113], v[162:163], 0, v[148:149]
	v_mul_f32_e32 v117, 0x45800000, v116
	v_cndmask_b32_e32 v116, v116, v117, vcc
	v_pk_mul_f32 v[110:111], v[110:111], v[116:117] op_sel_hi:[1,0]
	v_pk_mul_f32 v[108:109], v[108:109], v[116:117] op_sel_hi:[1,0]
	v_pk_mul_f32 v[106:107], v[106:107], v[116:117] op_sel_hi:[1,0]
	v_pk_mul_f32 v[104:105], v[104:105], v[116:117] op_sel_hi:[1,0]
	v_pk_mul_f32 v[102:103], v[102:103], v[116:117] op_sel_hi:[1,0]
	v_pk_mul_f32 v[100:101], v[100:101], v[116:117] op_sel_hi:[1,0]
	v_pk_mul_f32 v[118:119], v[98:99], v[116:117] op_sel_hi:[1,0]
	v_pk_mul_f32 v[116:117], v[96:97], v[116:117] op_sel_hi:[1,0]
	v_cvt_pk_bf16_f32 v96, v108, v109
	v_cvt_pk_bf16_f32 v97, v110, v111
	v_cvt_pk_bf16_f32 v98, v104, v105
	v_cvt_pk_bf16_f32 v99, v106, v107
	global_store_dwordx4 v[112:113], v[96:99], off sc1
	s_nop 1
	v_cvt_pk_bf16_f32 v96, v100, v101
	v_cvt_pk_bf16_f32 v97, v102, v103
	v_cvt_pk_bf16_f32 v98, v116, v117
	v_cvt_pk_bf16_f32 v99, v118, v119
	global_store_dwordx4 v[112:113], v[96:99], off offset:256 sc1
	s_nop 0
	v_or_b32_e32 v112, 48, v150
	v_mad_i64_i32 v[114:115], s[6:7], v160, s62, v[146:147]
	v_ashrrev_i32_e32 v113, 31, v112
	s_waitcnt vmcnt(12)
; __device__ __forceinline__ float bflo(unsigned w) { return __uint_as_float(w << 16); }
; __device__ __forceinline__ float bfhi(unsigned w) { return __uint_as_float(w & 0xffff0000u); }
; __device__ __forceinline__ unsigned pk2(float lo, float hi) { unsigned r; asm volatile("v_cvt_pk_bf16_f32 %0, %1, %2" : "=v"(r) : "v"(lo), "v"(hi)); return r; }
; __device__ __forceinline__ float row_rstd(const float* ssq, int row) {
;     const f32x4* p = (const f32x4*)(ssq + (size_t)row * 16);
;     const f32x4 a = p[0], b = p[1], c = p[2], d = p[3];
;     const float s = ((a[0] + a[1]) + (a[2] + a[3])) + ((b[0] + b[1]) + (b[2] + b[3])) + ((c[0] + c[1]) + (c[2] + c[3])) + ((d[0] + d[1]) + (d[2] + d[3]));
;     return rsqrtf(s * (1.0f / 1024.0f) + 1e-6f);
; }
; __device__ __forceinline__ u32x4 pack8(const f32x4 v0, const f32x4 v1) { u32x4 w; w.x = pk2(v0[0], v0[1]); w.y = pk2(v0[2], v0[3]); w.z = pk2(v1[0], v1[1]); w.w = pk2(v1[2], v1[3]); return w; }
; __device__ __forceinline__ void unpack8(const u32x4 w, f32x4& v0, f32x4& v1) { v0 = (f32x4){bflo(w.x), bfhi(w.x), bflo(w.y), bfhi(w.y)}; v1 = (f32x4){bflo(w.z), bfhi(w.z), bflo(w.w), bfhi(w.w)}; }
;     __device__ __forceinline__ void operator()(const f32x4 (&acc)[2][2][4][2], const Unit& u, int wr, int wc, int fr, int fq) const {
;         const int row0 = u.pm * 256 + wr * 64 + fr, col0 = u.pn * 256 + wc * 32 + 8 * fq;
; #pragma unroll
;         for (int ai = 0; ai < 2; ++ai)
; #pragma unroll
;             for (int m = 0; m < 4; ++m) {
;                 const int row = row0 + ai * 128 + m * 16; const float rs = row_rstd(ssq, row);
;                 bf16_t* rowp = O + (size_t)row * ldc + col0;
; #pragma unroll
;                 for (int bj = 0; bj < 2; ++bj) { f32x4 v0 = acc[ai][bj][m][0] * rs, v1 = acc[ai][bj][m][1] * rs;
;                     if (ACT == 1) {
; #pragma unroll
;                         for (int j = 0; j < 4; ++j) { const float a = fmaxf(v0[j], 0.f), b = fmaxf(v1[j], 0.f); v0[j] = a * a; v1[j] = b * b; } }
;                     *(u32x4*)(rowp + bj * 128) = pack8(v0, v1); }
	v_mov_b32_e32 v96, v220
	v_mov_b32_e32 v97, v221
	v_mov_b32_e32 v98, v222
	v_mov_b32_e32 v99, v223
	v_mov_b32_e32 v100, v232
	v_mov_b32_e32 v101, v233
	v_mov_b32_e32 v102, v234
	v_mov_b32_e32 v103, v235
	v_mov_b32_e32 v104, v236
	v_mov_b32_e32 v105, v237
	v_mov_b32_e32 v106, v238
	v_mov_b32_e32 v107, v239
	v_mov_b32_e32 v108, v240
	v_mov_b32_e32 v109, v241
	v_mov_b32_e32 v110, v242
	v_mov_b32_e32 v111, v243
	v_add_u32_e32 v187, 0x2400, v186
	global_load_dwordx4 v[220:223], v187, s[16:17]
	v_add_u32_e32 v187, 0x2410, v186
	global_load_dwordx4 v[232:235], v187, s[16:17]
	v_add_u32_e32 v187, 0x2420, v186
	global_load_dwordx4 v[236:239], v187, s[16:17]
	v_add_u32_e32 v187, 0x2430, v186
	global_load_dwordx4 v[240:243], v187, s[16:17]
	v_mov_b32_e32 v116, v97
	v_mov_b32_e32 v117, v98
	v_mov_b32_e32 v97, v99
	v_mov_b32_e32 v98, v101
	v_mov_b32_e32 v99, v102
	v_mov_b32_e32 v101, v103
	v_pk_add_f32 v[96:97], v[116:117], v[96:97]
	v_pk_add_f32 v[98:99], v[98:99], v[100:101]
	v_pk_add_f32 v[96:97], v[96:97], v[96:97] op_sel:[0,1] op_sel_hi:[1,0]
	v_pk_add_f32 v[98:99], v[98:99], v[98:99] op_sel:[0,1] op_sel_hi:[1,0]
	v_add_f32_e32 v102, v104, v105
	v_add_f32_e32 v104, v106, v107
	v_mov_b32_e32 v103, v110
	v_mov_b32_e32 v105, v111
	v_mov_b32_e32 v97, v108
	v_mov_b32_e32 v99, v109
	v_pk_add_f32 v[100:101], v[102:103], v[104:105]
	v_pk_add_f32 v[96:97], v[96:97], v[98:99]
	v_lshlrev_b64 v[98:99], 6, v[112:113]
	v_pk_add_f32 v[96:97], v[96:97], v[100:101]
	v_lshl_add_u64 v[98:99], s[16:17], 0, v[98:99]
	v_add_f32_e32 v96, v96, v97
	v_fmamk_f32 v96, v96, 0x3a800000, v158
	v_mul_f32_e32 v97, 0x4b800000, v96
	v_cmp_gt_f32_e32 vcc, s61, v96
	s_nop 1
	v_cndmask_b32_e32 v96, v96, v97, vcc
	v_rsq_f32_e32 v100, v96
	v_lshl_add_u64 v[96:97], v[114:115], 0, v[148:149]
	v_mul_f32_e32 v101, 0x45800000, v100
	v_cndmask_b32_e32 v100, v100, v101, vcc
	v_pk_mul_f32 v[94:95], v[94:95], v[100:101] op_sel_hi:[1,0]
	v_pk_mul_f32 v[92:93], v[92:93], v[100:101] op_sel_hi:[1,0]
	v_pk_mul_f32 v[90:91], v[90:91], v[100:101] op_sel_hi:[1,0]
	v_pk_mul_f32 v[88:89], v[88:89], v[100:101] op_sel_hi:[1,0]
	v_pk_mul_f32 v[86:87], v[86:87], v[100:101] op_sel_hi:[1,0]
	v_pk_mul_f32 v[84:85], v[84:85], v[100:101] op_sel_hi:[1,0]
	v_pk_mul_f32 v[102:103], v[82:83], v[100:101] op_sel_hi:[1,0]
	v_pk_mul_f32 v[100:101], v[80:81], v[100:101] op_sel_hi:[1,0]
	v_cvt_pk_bf16_f32 v80, v92, v93
	v_cvt_pk_bf16_f32 v81, v94, v95
	v_cvt_pk_bf16_f32 v82, v88, v89
	v_cvt_pk_bf16_f32 v83, v90, v91
	global_store_dwordx4 v[96:97], v[80:83], off sc1
	s_nop 1
	v_cvt_pk_bf16_f32 v80, v84, v85
	v_cvt_pk_bf16_f32 v81, v86, v87
	v_cvt_pk_bf16_f32 v82, v100, v101
	v_cvt_pk_bf16_f32 v83, v102, v103
	global_store_dwordx4 v[96:97], v[80:83], off offset:256 sc1
	s_nop 0
	v_add_u32_e32 v96, 0x80, v150
	v_mad_i64_i32 v[98:99], s[6:7], v112, s62, v[146:147]
	v_ashrrev_i32_e32 v97, 31, v96
	s_waitcnt vmcnt(14)
	v_mov_b32_e32 v80, v188
	v_mov_b32_e32 v81, v189
	v_mov_b32_e32 v82, v190
	v_mov_b32_e32 v83, v191
	v_mov_b32_e32 v84, v192
	v_mov_b32_e32 v85, v193
	v_mov_b32_e32 v86, v194
	v_mov_b32_e32 v87, v195
	v_mov_b32_e32 v88, v196
	v_mov_b32_e32 v89, v197
	v_mov_b32_e32 v90, v198
	v_mov_b32_e32 v91, v199
	v_mov_b32_e32 v92, v200
	v_mov_b32_e32 v93, v201
	v_mov_b32_e32 v94, v202
	v_mov_b32_e32 v95, v203
	v_add_u32_e32 v187, 0x2800, v186
	global_load_dwordx4 v[188:191], v187, s[16:17]
	v_add_u32_e32 v187, 0x2810, v186
	global_load_dwordx4 v[192:195], v187, s[16:17]
	v_add_u32_e32 v187, 0x2820, v186
	global_load_dwordx4 v[196:199], v187, s[16:17]
	v_add_u32_e32 v187, 0x2830, v186
	global_load_dwordx4 v[200:203], v187, s[16:17]
	v_mov_b32_e32 v100, v81
	v_mov_b32_e32 v101, v82
	v_mov_b32_e32 v81, v83
	v_mov_b32_e32 v82, v85
	v_mov_b32_e32 v83, v86
	v_mov_b32_e32 v85, v87
	v_pk_add_f32 v[80:81], v[100:101], v[80:81]
	v_pk_add_f32 v[82:83], v[82:83], v[84:85]
	v_pk_add_f32 v[80:81], v[80:81], v[80:81] op_sel:[0,1] op_sel_hi:[1,0]
	v_pk_add_f32 v[82:83], v[82:83], v[82:83] op_sel:[0,1] op_sel_hi:[1,0]
	v_add_f32_e32 v86, v88, v89
	v_add_f32_e32 v88, v90, v91
	v_mov_b32_e32 v87, v94
	v_mov_b32_e32 v89, v95
	v_mov_b32_e32 v81, v92
	v_mov_b32_e32 v83, v93
	v_pk_add_f32 v[84:85], v[86:87], v[88:89]
	v_pk_add_f32 v[80:81], v[80:81], v[82:83]
	v_lshlrev_b64 v[82:83], 6, v[96:97]
	v_pk_add_f32 v[80:81], v[80:81], v[84:85]
	v_lshl_add_u64 v[82:83], s[16:17], 0, v[82:83]
	v_add_f32_e32 v80, v80, v81
	v_fmamk_f32 v80, v80, 0x3a800000, v158
	v_mul_f32_e32 v81, 0x4b800000, v80
	v_cmp_gt_f32_e32 vcc, s61, v80
	s_nop 1
	v_cndmask_b32_e32 v80, v80, v81, vcc
	v_rsq_f32_e32 v84, v80
	v_lshl_add_u64 v[80:81], v[98:99], 0, v[148:149]
	v_mul_f32_e32 v85, 0x45800000, v84
	v_cndmask_b32_e32 v84, v84, v85, vcc
	v_pk_mul_f32 v[78:79], v[78:79], v[84:85] op_sel_hi:[1,0]
	v_pk_mul_f32 v[76:77], v[76:77], v[84:85] op_sel_hi:[1,0]
	v_pk_mul_f32 v[74:75], v[74:75], v[84:85] op_sel_hi:[1,0]
	v_pk_mul_f32 v[72:73], v[72:73], v[84:85] op_sel_hi:[1,0]
	v_pk_mul_f32 v[70:71], v[70:71], v[84:85] op_sel_hi:[1,0]
	v_pk_mul_f32 v[68:69], v[68:69], v[84:85] op_sel_hi:[1,0]
	v_pk_mul_f32 v[86:87], v[66:67], v[84:85] op_sel_hi:[1,0]
	v_pk_mul_f32 v[84:85], v[64:65], v[84:85] op_sel_hi:[1,0]
	v_cvt_pk_bf16_f32 v64, v76, v77
	v_cvt_pk_bf16_f32 v65, v78, v79
	v_cvt_pk_bf16_f32 v66, v72, v73
	v_cvt_pk_bf16_f32 v67, v74, v75
	global_store_dwordx4 v[80:81], v[64:67], off sc1
	s_nop 1
	v_cvt_pk_bf16_f32 v64, v68, v69
	v_cvt_pk_bf16_f32 v65, v70, v71
	v_cvt_pk_bf16_f32 v66, v84, v85
	v_cvt_pk_bf16_f32 v67, v86, v87
	global_store_dwordx4 v[80:81], v[64:67], off offset:256 sc1
	s_nop 0
	v_add_u32_e32 v80, 0x90, v150
	v_mad_i64_i32 v[82:83], s[6:7], v96, s62, v[146:147]
	v_ashrrev_i32_e32 v81, 31, v80
	s_waitcnt vmcnt(14)
; __device__ __forceinline__ float bflo(unsigned w) { return __uint_as_float(w << 16); }
; __device__ __forceinline__ float bfhi(unsigned w) { return __uint_as_float(w & 0xffff0000u); }
; __device__ __forceinline__ unsigned pk2(float lo, float hi) { unsigned r; asm volatile("v_cvt_pk_bf16_f32 %0, %1, %2" : "=v"(r) : "v"(lo), "v"(hi)); return r; }
; __device__ __forceinline__ float row_rstd(const float* ssq, int row) {
;     const f32x4* p = (const f32x4*)(ssq + (size_t)row * 16);
;     const f32x4 a = p[0], b = p[1], c = p[2], d = p[3];
;     const float s = ((a[0] + a[1]) + (a[2] + a[3])) + ((b[0] + b[1]) + (b[2] + b[3])) + ((c[0] + c[1]) + (c[2] + c[3])) + ((d[0] + d[1]) + (d[2] + d[3]));
;     return rsqrtf(s * (1.0f / 1024.0f) + 1e-6f);
; }
; __device__ __forceinline__ u32x4 pack8(const f32x4 v0, const f32x4 v1) { u32x4 w; w.x = pk2(v0[0], v0[1]); w.y = pk2(v0[2], v0[3]); w.z = pk2(v1[0], v1[1]); w.w = pk2(v1[2], v1[3]); return w; }
; __device__ __forceinline__ void unpack8(const u32x4 w, f32x4& v0, f32x4& v1) { v0 = (f32x4){bflo(w.x), bfhi(w.x), bflo(w.y), bfhi(w.y)}; v1 = (f32x4){bflo(w.z), bfhi(w.z), bflo(w.w), bfhi(w.w)}; }
;     __device__ __forceinline__ void operator()(const f32x4 (&acc)[2][2][4][2], const Unit& u, int wr, int wc, int fr, int fq) const {
;         const int row0 = u.pm * 256 + wr * 64 + fr, col0 = u.pn * 256 + wc * 32 + 8 * fq;
; #pragma unroll
;         for (int ai = 0; ai < 2; ++ai)
; #pragma unroll
;             for (int m = 0; m < 4; ++m) {
;                 const int row = row0 + ai * 128 + m * 16; const float rs = row_rstd(ssq, row);
;                 bf16_t* rowp = O + (size_t)row * ldc + col0;
; #pragma unroll
;                 for (int bj = 0; bj < 2; ++bj) { f32x4 v0 = acc[ai][bj][m][0] * rs, v1 = acc[ai][bj][m][1] * rs;
;                     if (ACT == 1) {
; #pragma unroll
;                         for (int j = 0; j < 4; ++j) { const float a = fmaxf(v0[j], 0.f), b = fmaxf(v1[j], 0.f); v0[j] = a * a; v1[j] = b * b; } }
;                     *(u32x4*)(rowp + bj * 128) = pack8(v0, v1); }
	v_mov_b32_e32 v64, v204
	v_mov_b32_e32 v65, v205
	v_mov_b32_e32 v66, v206
	v_mov_b32_e32 v67, v207
	v_mov_b32_e32 v68, v208
	v_mov_b32_e32 v69, v209
	v_mov_b32_e32 v70, v210
	v_mov_b32_e32 v71, v211
	v_mov_b32_e32 v72, v212
	v_mov_b32_e32 v73, v213
	v_mov_b32_e32 v74, v214
	v_mov_b32_e32 v75, v215
	v_mov_b32_e32 v76, v216
	v_mov_b32_e32 v77, v217
	v_mov_b32_e32 v78, v218
	v_mov_b32_e32 v79, v219
	v_add_u32_e32 v187, 0x2c00, v186
	global_load_dwordx4 v[204:207], v187, s[16:17]
	v_add_u32_e32 v187, 0x2c10, v186
	global_load_dwordx4 v[208:211], v187, s[16:17]
	v_add_u32_e32 v187, 0x2c20, v186
	global_load_dwordx4 v[212:215], v187, s[16:17]
	v_add_u32_e32 v187, 0x2c30, v186
	global_load_dwordx4 v[216:219], v187, s[16:17]
	v_mov_b32_e32 v84, v65
	v_mov_b32_e32 v85, v66
	v_mov_b32_e32 v65, v67
	v_mov_b32_e32 v66, v69
	v_mov_b32_e32 v67, v70
	v_mov_b32_e32 v69, v71
	v_pk_add_f32 v[64:65], v[84:85], v[64:65]
	v_pk_add_f32 v[66:67], v[66:67], v[68:69]
	v_pk_add_f32 v[64:65], v[64:65], v[64:65] op_sel:[0,1] op_sel_hi:[1,0]
	v_pk_add_f32 v[66:67], v[66:67], v[66:67] op_sel:[0,1] op_sel_hi:[1,0]
	v_add_f32_e32 v70, v72, v73
	v_add_f32_e32 v72, v74, v75
	v_mov_b32_e32 v71, v78
	v_mov_b32_e32 v73, v79
	v_mov_b32_e32 v65, v76
	v_mov_b32_e32 v67, v77
	v_pk_add_f32 v[68:69], v[70:71], v[72:73]
	v_pk_add_f32 v[64:65], v[64:65], v[66:67]
	v_lshlrev_b64 v[66:67], 6, v[80:81]
	v_pk_add_f32 v[64:65], v[64:65], v[68:69]
	v_lshl_add_u64 v[66:67], s[16:17], 0, v[66:67]
	v_add_f32_e32 v64, v64, v65
	v_fmamk_f32 v64, v64, 0x3a800000, v158
	v_mul_f32_e32 v65, 0x4b800000, v64
	v_cmp_gt_f32_e32 vcc, s61, v64
	s_nop 1
	v_cndmask_b32_e32 v64, v64, v65, vcc
	v_rsq_f32_e32 v68, v64
	v_lshl_add_u64 v[64:65], v[82:83], 0, v[148:149]
	v_mul_f32_e32 v69, 0x45800000, v68
	v_cndmask_b32_e32 v68, v68, v69, vcc
	v_pk_mul_f32 v[62:63], v[62:63], v[68:69] op_sel_hi:[1,0]
	v_pk_mul_f32 v[60:61], v[60:61], v[68:69] op_sel_hi:[1,0]
	v_pk_mul_f32 v[58:59], v[58:59], v[68:69] op_sel_hi:[1,0]
	v_pk_mul_f32 v[56:57], v[56:57], v[68:69] op_sel_hi:[1,0]
	v_pk_mul_f32 v[54:55], v[54:55], v[68:69] op_sel_hi:[1,0]
	v_pk_mul_f32 v[52:53], v[52:53], v[68:69] op_sel_hi:[1,0]
	v_pk_mul_f32 v[70:71], v[50:51], v[68:69] op_sel_hi:[1,0]
	v_pk_mul_f32 v[68:69], v[48:49], v[68:69] op_sel_hi:[1,0]
	v_cvt_pk_bf16_f32 v48, v60, v61
	v_cvt_pk_bf16_f32 v49, v62, v63
	v_cvt_pk_bf16_f32 v50, v56, v57
	v_cvt_pk_bf16_f32 v51, v58, v59
	global_store_dwordx4 v[64:65], v[48:51], off sc1
	s_nop 1
	v_cvt_pk_bf16_f32 v48, v52, v53
	v_cvt_pk_bf16_f32 v49, v54, v55
	v_cvt_pk_bf16_f32 v50, v68, v69
	v_cvt_pk_bf16_f32 v51, v70, v71
	global_store_dwordx4 v[64:65], v[48:51], off offset:256 sc1
	s_nop 0
	v_add_u32_e32 v64, 0xa0, v150
	v_mad_i64_i32 v[66:67], s[6:7], v80, s62, v[146:147]
	v_ashrrev_i32_e32 v65, 31, v64
	s_waitcnt vmcnt(14)
	v_mov_b32_e32 v48, v220
	v_mov_b32_e32 v49, v221
	v_mov_b32_e32 v50, v222
	v_mov_b32_e32 v51, v223
	v_mov_b32_e32 v52, v232
	v_mov_b32_e32 v53, v233
	v_mov_b32_e32 v54, v234
	v_mov_b32_e32 v55, v235
	v_mov_b32_e32 v56, v236
	v_mov_b32_e32 v57, v237
	v_mov_b32_e32 v58, v238
	v_mov_b32_e32 v59, v239
	v_mov_b32_e32 v60, v240
	v_mov_b32_e32 v61, v241
	v_mov_b32_e32 v62, v242
	v_mov_b32_e32 v63, v243
	v_mov_b32_e32 v68, v49
	v_mov_b32_e32 v69, v50
	v_mov_b32_e32 v49, v51
	v_mov_b32_e32 v50, v53
	v_mov_b32_e32 v51, v54
	v_mov_b32_e32 v53, v55
	v_pk_add_f32 v[48:49], v[68:69], v[48:49]
	v_pk_add_f32 v[50:51], v[50:51], v[52:53]
	v_pk_add_f32 v[48:49], v[48:49], v[48:49] op_sel:[0,1] op_sel_hi:[1,0]
	v_pk_add_f32 v[50:51], v[50:51], v[50:51] op_sel:[0,1] op_sel_hi:[1,0]
	v_add_f32_e32 v54, v56, v57
	v_add_f32_e32 v56, v58, v59
	v_mov_b32_e32 v55, v62
	v_mov_b32_e32 v57, v63
	v_mov_b32_e32 v49, v60
	v_mov_b32_e32 v51, v61
	v_pk_add_f32 v[52:53], v[54:55], v[56:57]
	v_pk_add_f32 v[48:49], v[48:49], v[50:51]
	v_lshlrev_b64 v[50:51], 6, v[64:65]
	v_pk_add_f32 v[48:49], v[48:49], v[52:53]
	v_lshl_add_u64 v[50:51], s[16:17], 0, v[50:51]
	v_add_f32_e32 v48, v48, v49
	v_fmamk_f32 v48, v48, 0x3a800000, v158
	v_mul_f32_e32 v49, 0x4b800000, v48
	v_cmp_gt_f32_e32 vcc, s61, v48
	s_nop 1
	v_cndmask_b32_e32 v48, v48, v49, vcc
	v_rsq_f32_e32 v52, v48
	v_lshl_add_u64 v[48:49], v[66:67], 0, v[148:149]
	v_mul_f32_e32 v53, 0x45800000, v52
	v_cndmask_b32_e32 v52, v52, v53, vcc
	v_pk_mul_f32 v[46:47], v[46:47], v[52:53] op_sel_hi:[1,0]
	v_pk_mul_f32 v[44:45], v[44:45], v[52:53] op_sel_hi:[1,0]
	v_pk_mul_f32 v[42:43], v[42:43], v[52:53] op_sel_hi:[1,0]
	v_pk_mul_f32 v[40:41], v[40:41], v[52:53] op_sel_hi:[1,0]
	v_pk_mul_f32 v[38:39], v[38:39], v[52:53] op_sel_hi:[1,0]
	v_pk_mul_f32 v[36:37], v[36:37], v[52:53] op_sel_hi:[1,0]
	v_pk_mul_f32 v[54:55], v[34:35], v[52:53] op_sel_hi:[1,0]
	v_pk_mul_f32 v[52:53], v[32:33], v[52:53] op_sel_hi:[1,0]
	v_cvt_pk_bf16_f32 v32, v44, v45
	v_cvt_pk_bf16_f32 v33, v46, v47
	v_cvt_pk_bf16_f32 v34, v40, v41
	v_cvt_pk_bf16_f32 v35, v42, v43
	global_store_dwordx4 v[48:49], v[32:35], off sc1
	s_nop 1
	v_cvt_pk_bf16_f32 v32, v36, v37
	v_cvt_pk_bf16_f32 v33, v38, v39
	v_cvt_pk_bf16_f32 v34, v52, v53
	v_cvt_pk_bf16_f32 v35, v54, v55
	global_store_dwordx4 v[48:49], v[32:35], off offset:256 sc1
	s_nop 0
	v_add_u32_e32 v48, 0xb0, v150
	v_mad_i64_i32 v[50:51], s[6:7], v64, s62, v[146:147]
	v_ashrrev_i32_e32 v49, 31, v48
	s_mov_b32 s6, s20
	s_waitcnt vmcnt(10)
; __device__ __forceinline__ float bflo(unsigned w) { return __uint_as_float(w << 16); }
; __device__ __forceinline__ float bfhi(unsigned w) { return __uint_as_float(w & 0xffff0000u); }
; __device__ __forceinline__ unsigned pk2(float lo, float hi) { unsigned r; asm volatile("v_cvt_pk_bf16_f32 %0, %1, %2" : "=v"(r) : "v"(lo), "v"(hi)); return r; }
; __device__ __forceinline__ float row_rstd(const float* ssq, int row) {
;     const f32x4* p = (const f32x4*)(ssq + (size_t)row * 16);
;     const f32x4 a = p[0], b = p[1], c = p[2], d = p[3];
;     const float s = ((a[0] + a[1]) + (a[2] + a[3])) + ((b[0] + b[1]) + (b[2] + b[3])) + ((c[0] + c[1]) + (c[2] + c[3])) + ((d[0] + d[1]) + (d[2] + d[3]));
;     return rsqrtf(s * (1.0f / 1024.0f) + 1e-6f);
; }
; __device__ __forceinline__ u32x4 pack8(const f32x4 v0, const f32x4 v1) { u32x4 w; w.x = pk2(v0[0], v0[1]); w.y = pk2(v0[2], v0[3]); w.z = pk2(v1[0], v1[1]); w.w = pk2(v1[2], v1[3]); return w; }
; __device__ __forceinline__ void unpack8(const u32x4 w, f32x4& v0, f32x4& v1) { v0 = (f32x4){bflo(w.x), bfhi(w.x), bflo(w.y), bfhi(w.y)}; v1 = (f32x4){bflo(w.z), bfhi(w.z), bflo(w.w), bfhi(w.w)}; }
;     __device__ __forceinline__ void operator()(const f32x4 (&acc)[2][2][4][2], const Unit& u, int wr, int wc, int fr, int fq) const {
;         const int row0 = u.pm * 256 + wr * 64 + fr, col0 = u.pn * 256 + wc * 32 + 8 * fq;
; #pragma unroll
;         for (int ai = 0; ai < 2; ++ai)
; #pragma unroll
;             for (int m = 0; m < 4; ++m) {
;                 const int row = row0 + ai * 128 + m * 16; const float rs = row_rstd(ssq, row);
;                 bf16_t* rowp = O + (size_t)row * ldc + col0;
; #pragma unroll
;                 for (int bj = 0; bj < 2; ++bj) { f32x4 v0 = acc[ai][bj][m][0] * rs, v1 = acc[ai][bj][m][1] * rs;
;                     if (ACT == 1) {
; #pragma unroll
;                         for (int j = 0; j < 4; ++j) { const float a = fmaxf(v0[j], 0.f), b = fmaxf(v1[j], 0.f); v0[j] = a * a; v1[j] = b * b; } }
;                     *(u32x4*)(rowp + bj * 128) = pack8(v0, v1); }
	v_mov_b32_e32 v32, v188
	v_mov_b32_e32 v33, v189
	v_mov_b32_e32 v34, v190
	v_mov_b32_e32 v35, v191
	v_mov_b32_e32 v36, v192
	v_mov_b32_e32 v37, v193
	v_mov_b32_e32 v38, v194
	v_mov_b32_e32 v39, v195
	v_mov_b32_e32 v40, v196
	v_mov_b32_e32 v41, v197
	v_mov_b32_e32 v42, v198
	v_mov_b32_e32 v43, v199
	v_mov_b32_e32 v44, v200
	v_mov_b32_e32 v45, v201
	v_mov_b32_e32 v46, v202
	v_mov_b32_e32 v47, v203
	v_mov_b32_e32 v52, v33
	v_mov_b32_e32 v53, v34
	v_mov_b32_e32 v33, v35
	v_mov_b32_e32 v34, v37
	v_mov_b32_e32 v35, v38
	v_mov_b32_e32 v37, v39
	v_pk_add_f32 v[32:33], v[52:53], v[32:33]
	v_pk_add_f32 v[34:35], v[34:35], v[36:37]
	v_pk_add_f32 v[32:33], v[32:33], v[32:33] op_sel:[0,1] op_sel_hi:[1,0]
	v_pk_add_f32 v[34:35], v[34:35], v[34:35] op_sel:[0,1] op_sel_hi:[1,0]
	v_add_f32_e32 v38, v40, v41
	v_add_f32_e32 v40, v42, v43
	v_mov_b32_e32 v39, v46
	v_mov_b32_e32 v41, v47
	v_mov_b32_e32 v33, v44
	v_mov_b32_e32 v35, v45
	v_pk_add_f32 v[36:37], v[38:39], v[40:41]
	v_pk_add_f32 v[32:33], v[32:33], v[34:35]
	v_lshlrev_b64 v[34:35], 6, v[48:49]
	v_pk_add_f32 v[32:33], v[32:33], v[36:37]
	v_lshl_add_u64 v[34:35], s[16:17], 0, v[34:35]
	v_add_f32_e32 v32, v32, v33
	v_fmamk_f32 v32, v32, 0x3a800000, v158
	v_mul_f32_e32 v33, 0x4b800000, v32
	v_cmp_gt_f32_e32 vcc, s61, v32
	s_nop 1
	v_cndmask_b32_e32 v32, v32, v33, vcc
	v_rsq_f32_e32 v36, v32
	v_lshl_add_u64 v[32:33], v[50:51], 0, v[148:149]
	v_mul_f32_e32 v37, 0x45800000, v36
	v_cndmask_b32_e32 v36, v36, v37, vcc
	v_pk_mul_f32 v[30:31], v[30:31], v[36:37] op_sel_hi:[1,0]
	v_pk_mul_f32 v[28:29], v[28:29], v[36:37] op_sel_hi:[1,0]
	v_pk_mul_f32 v[26:27], v[26:27], v[36:37] op_sel_hi:[1,0]
	v_pk_mul_f32 v[24:25], v[24:25], v[36:37] op_sel_hi:[1,0]
	v_pk_mul_f32 v[22:23], v[22:23], v[36:37] op_sel_hi:[1,0]
	v_pk_mul_f32 v[20:21], v[20:21], v[36:37] op_sel_hi:[1,0]
	v_pk_mul_f32 v[38:39], v[18:19], v[36:37] op_sel_hi:[1,0]
	v_pk_mul_f32 v[36:37], v[16:17], v[36:37] op_sel_hi:[1,0]
	v_cvt_pk_bf16_f32 v16, v28, v29
	v_cvt_pk_bf16_f32 v17, v30, v31
	v_cvt_pk_bf16_f32 v18, v24, v25
	v_cvt_pk_bf16_f32 v19, v26, v27
	global_store_dwordx4 v[32:33], v[16:19], off sc1
	s_and_b64 vcc, exec, s[8:9]
	s_nop 0
	v_cvt_pk_bf16_f32 v16, v20, v21
	v_cvt_pk_bf16_f32 v17, v22, v23
	v_cvt_pk_bf16_f32 v18, v36, v37
	v_cvt_pk_bf16_f32 v19, v38, v39
	global_store_dwordx4 v[32:33], v[16:19], off offset:256 sc1
	s_nop 0
	s_waitcnt vmcnt(6)
	v_mov_b32_e32 v16, v204
	v_mov_b32_e32 v17, v205
	v_mov_b32_e32 v18, v206
	v_mov_b32_e32 v19, v207
	v_mov_b32_e32 v20, v208
	v_mov_b32_e32 v21, v209
	v_mov_b32_e32 v22, v210
	v_mov_b32_e32 v23, v211
	v_mov_b32_e32 v24, v212
	v_mov_b32_e32 v25, v213
	v_mov_b32_e32 v26, v214
	v_mov_b32_e32 v27, v215
	v_mov_b32_e32 v28, v216
	v_mov_b32_e32 v29, v217
	v_mov_b32_e32 v30, v218
	v_mov_b32_e32 v31, v219
	v_mov_b32_e32 v32, v17
	v_mov_b32_e32 v33, v18
	v_mov_b32_e32 v17, v19
	v_mov_b32_e32 v18, v21
	v_mov_b32_e32 v19, v22
	v_mov_b32_e32 v21, v23
	v_pk_add_f32 v[16:17], v[32:33], v[16:17]
	v_pk_add_f32 v[18:19], v[18:19], v[20:21]
	v_pk_add_f32 v[16:17], v[16:17], v[16:17] op_sel:[0,1] op_sel_hi:[1,0]
	v_pk_add_f32 v[18:19], v[18:19], v[18:19] op_sel:[0,1] op_sel_hi:[1,0]
	v_add_f32_e32 v22, v24, v25
	v_add_f32_e32 v24, v26, v27
	v_mov_b32_e32 v23, v30
	v_mov_b32_e32 v25, v31
	v_mov_b32_e32 v17, v28
	v_mov_b32_e32 v19, v29
	v_pk_add_f32 v[20:21], v[22:23], v[24:25]
	v_pk_add_f32 v[16:17], v[16:17], v[18:19]
	s_nop 0
	v_pk_add_f32 v[16:17], v[16:17], v[20:21]
	s_nop 0
	v_add_f32_e32 v16, v16, v17
	v_fmamk_f32 v16, v16, 0x3a800000, v158
	v_mul_f32_e32 v17, 0x4b800000, v16
	v_cmp_gt_f32_e64 s[8:9], s61, v16
	s_nop 1
	v_cndmask_b32_e64 v16, v16, v17, s[8:9]
	v_rsq_f32_e32 v18, v16
	v_mad_i64_i32 v[16:17], s[24:25], v48, s62, v[146:147]
	v_lshl_add_u64 v[16:17], v[16:17], 0, v[148:149]
	v_mul_f32_e32 v19, 0x45800000, v18
	v_cndmask_b32_e64 v18, v18, v19, s[8:9]
	v_pk_mul_f32 v[14:15], v[14:15], v[18:19] op_sel_hi:[1,0]
	v_pk_mul_f32 v[12:13], v[12:13], v[18:19] op_sel_hi:[1,0]
	v_pk_mul_f32 v[10:11], v[10:11], v[18:19] op_sel_hi:[1,0]
	v_pk_mul_f32 v[8:9], v[8:9], v[18:19] op_sel_hi:[1,0]
	v_pk_mul_f32 v[6:7], v[6:7], v[18:19] op_sel_hi:[1,0]
	v_pk_mul_f32 v[4:5], v[4:5], v[18:19] op_sel_hi:[1,0]
	v_pk_mul_f32 v[20:21], v[2:3], v[18:19] op_sel_hi:[1,0]
	v_pk_mul_f32 v[18:19], v[0:1], v[18:19] op_sel_hi:[1,0]
	v_cvt_pk_bf16_f32 v0, v12, v13
	v_cvt_pk_bf16_f32 v1, v14, v15
	v_cvt_pk_bf16_f32 v2, v8, v9
	v_cvt_pk_bf16_f32 v3, v10, v11
	global_store_dwordx4 v[16:17], v[0:3], off sc1
	s_nop 1
	v_cvt_pk_bf16_f32 v0, v4, v5
	v_cvt_pk_bf16_f32 v1, v6, v7
	v_cvt_pk_bf16_f32 v2, v18, v19
	v_cvt_pk_bf16_f32 v3, v20, v21
	global_store_dwordx4 v[16:17], v[0:3], off offset:256 sc1
	s_cbranch_vccz .LBB0_118
	s_waitcnt vmcnt(0)
	s_cmpk_gt_u32 s40, 0xff
	s_cbranch_scc1 .LBB0_129
	s_barrier

; __device__ __forceinline__ unsigned pk2(float lo, float hi) { unsigned r; asm volatile("v_cvt_pk_bf16_f32 %0, %1, %2" : "=v"(r) : "v"(lo), "v"(hi)); return r; }
; #define RAW_BARRIER() do { asm volatile("s_waitcnt lgkmcnt(0)" ::: "memory"); __builtin_amdgcn_s_barrier(); asm volatile("" ::: "memory"); } while (0)
;     ...
;         RAW_BARRIER();
;         { u32x4 w;
;           w.x = pk2(tile[(k8 + 0) * 65 + n], tile[(k8 + 1) * 65 + n]); w.y = pk2(tile[(k8 + 2) * 65 + n], tile[(k8 + 3) * 65 + n]);
;           w.z = pk2(tile[(k8 + 4) * 65 + n], tile[(k8 + 5) * 65 + n]); w.w = pk2(tile[(k8 + 6) * 65 + n], tile[(k8 + 7) * 65 + n]);
;           *(u32x4*)(dst + (size_t)(n0 + n) * K + k0 + k8) = w; }
;         RAW_BARRIER();
.LBB0_133:
	s_waitcnt lgkmcnt(0)
	s_barrier
	ds_read_b32 v20, v16 offset:260
	ds_read_b32 v21, v15
	s_ashr_i32 s16, s18, 31
	s_lshr_b32 s16, s16, 28
	s_add_i32 s16, s18, s16
	s_ashr_i32 s17, s16, 4
	v_add_u32_e32 v26, s21, v13
	s_lshl_b32 s16, s17, 6
	s_lshl_b32 s17, s17, 10
	s_waitcnt lgkmcnt(0)
	v_cvt_pk_bf16_f32 v20, v21, v20
	ds_read2_b32 v[22:23], v16 offset0:130 offset1:195
	v_subrev_u32_e32 v26, s17, v26
	s_waitcnt lgkmcnt(0)
	v_cvt_pk_bf16_f32 v21, v22, v23
	ds_read2_b32 v[22:23], v19 offset0:4 offset1:69
	v_ashrrev_i32_e32 v27, 31, v26
	s_waitcnt lgkmcnt(0)
	v_cvt_pk_bf16_f32 v22, v22, v23
	ds_read2_b32 v[24:25], v19 offset0:134 offset1:199
	v_lshlrev_b64 v[26:27], 10, v[26:27]
	s_waitcnt lgkmcnt(0)
	v_cvt_pk_bf16_f32 v23, v24, v25
	v_lshl_add_u64 v[24:25], s[12:13], 0, v[26:27]
	s_ashr_i32 s17, s16, 31
	v_lshl_add_u64 v[24:25], s[16:17], 1, v[24:25]
	v_lshl_add_u64 v[24:25], v[24:25], 0, v[10:11]
	global_store_dwordx4 v[24:25], v[20:23], off sc1
	s_waitcnt lgkmcnt(0)
	s_barrier
	s_andn2_b64 vcc, exec, s[14:15]
	s_mov_b32 s21, s22
	s_mov_b32 s18, s20
	s_cbranch_vccz .LBB0_138

; __device__ __forceinline__ unsigned pk2(float lo, float hi) { unsigned r; asm volatile("v_cvt_pk_bf16_f32 %0, %1, %2" : "=v"(r) : "v"(lo), "v"(hi)); return r; }
; #define RAW_BARRIER() do { asm volatile("s_waitcnt lgkmcnt(0)" ::: "memory"); __builtin_amdgcn_s_barrier(); asm volatile("" ::: "memory"); } while (0)
;     ...
;         RAW_BARRIER();
;         { u32x4 w;
;           w.x = pk2(tile[(k8 + 0) * 65 + n], tile[(k8 + 1) * 65 + n]); w.y = pk2(tile[(k8 + 2) * 65 + n], tile[(k8 + 3) * 65 + n]);
;           w.z = pk2(tile[(k8 + 4) * 65 + n], tile[(k8 + 5) * 65 + n]); w.w = pk2(tile[(k8 + 6) * 65 + n], tile[(k8 + 7) * 65 + n]);
;           *(u32x4*)(dst + (size_t)(n0 + n) * K + k0 + k8) = w; }
;         RAW_BARRIER();
.LBB0_149:
	s_waitcnt lgkmcnt(0)
	s_barrier
	ds_read_b32 v20, v16 offset:260
	ds_read_b32 v21, v15
	s_ashr_i32 s16, s18, 31
	s_lshr_b32 s16, s16, 28
	s_add_i32 s16, s18, s16
	s_ashr_i32 s17, s16, 4
	v_add_u32_e32 v26, s21, v13
	s_lshl_b32 s16, s17, 6
	s_lshl_b32 s17, s17, 10
	s_waitcnt lgkmcnt(0)
	v_cvt_pk_bf16_f32 v20, v21, v20
	ds_read2_b32 v[22:23], v16 offset0:130 offset1:195
	v_subrev_u32_e32 v26, s17, v26
	s_waitcnt lgkmcnt(0)
	v_cvt_pk_bf16_f32 v21, v22, v23
	ds_read2_b32 v[22:23], v19 offset0:4 offset1:69
	v_ashrrev_i32_e32 v27, 31, v26
	s_waitcnt lgkmcnt(0)
	v_cvt_pk_bf16_f32 v22, v22, v23
	ds_read2_b32 v[24:25], v19 offset0:134 offset1:199
	v_lshlrev_b64 v[26:27], 11, v[26:27]
	s_waitcnt lgkmcnt(0)
	v_cvt_pk_bf16_f32 v23, v24, v25
	v_lshl_add_u64 v[24:25], s[12:13], 0, v[26:27]
	s_ashr_i32 s17, s16, 31
	v_lshl_add_u64 v[24:25], s[16:17], 1, v[24:25]
	v_lshl_add_u64 v[24:25], v[24:25], 0, v[10:11]
	global_store_dwordx4 v[24:25], v[20:23], off sc1
	s_waitcnt lgkmcnt(0)
	s_barrier
	s_andn2_b64 vcc, exec, s[14:15]
	s_mov_b32 s21, s22
	s_mov_b32 s18, s20
	s_cbranch_vccz .LBB0_154

; __device__ __forceinline__ unsigned pk2(float lo, float hi) { unsigned r; asm volatile("v_cvt_pk_bf16_f32 %0, %1, %2" : "=v"(r) : "v"(lo), "v"(hi)); return r; }
; #define RAW_BARRIER() do { asm volatile("s_waitcnt lgkmcnt(0)" ::: "memory"); __builtin_amdgcn_s_barrier(); asm volatile("" ::: "memory"); } while (0)
;     ...
;         RAW_BARRIER();
;         { u32x4 w;
;           w.x = pk2(tile[(k8 + 0) * 65 + n], tile[(k8 + 1) * 65 + n]); w.y = pk2(tile[(k8 + 2) * 65 + n], tile[(k8 + 3) * 65 + n]);
;           w.z = pk2(tile[(k8 + 4) * 65 + n], tile[(k8 + 5) * 65 + n]); w.w = pk2(tile[(k8 + 6) * 65 + n], tile[(k8 + 7) * 65 + n]);
;           *(u32x4*)(dst + (size_t)(n0 + n) * K + k0 + k8) = w; }
;         RAW_BARRIER();
.LBB0_159:
	s_waitcnt lgkmcnt(0)
	s_barrier
	ds_read_b32 v16, v20 offset:260
	ds_read_b32 v17, v19
	s_ashr_i32 s18, s7, 31
	s_lshr_b32 s18, s18, 26
	s_add_i32 s7, s7, s18
	s_and_b32 s18, s7, 0xffffffc0
	s_lshl_b32 s7, s7, 6
	v_add_u32_e32 v27, s21, v13
	s_and_b32 s7, s7, 0xfffff000
	s_waitcnt lgkmcnt(0)
	v_cvt_pk_bf16_f32 v24, v17, v16
	ds_read2_b32 v[16:17], v20 offset0:130 offset1:195
	v_subrev_u32_e32 v28, s7, v27
	s_waitcnt lgkmcnt(0)
	v_cvt_pk_bf16_f32 v25, v16, v17
	ds_read2_b32 v[16:17], v23 offset0:4 offset1:69
	v_ashrrev_i32_e32 v29, 31, v28
	s_waitcnt lgkmcnt(0)
	v_cvt_pk_bf16_f32 v26, v16, v17
	ds_read2_b32 v[16:17], v23 offset0:134 offset1:199
	v_lshlrev_b64 v[28:29], 11, v[28:29]
	s_waitcnt lgkmcnt(0)
	v_cvt_pk_bf16_f32 v27, v16, v17
	v_lshl_add_u64 v[16:17], s[14:15], 0, v[28:29]
	s_ashr_i32 s19, s18, 31
	v_lshl_add_u64 v[16:17], s[18:19], 1, v[16:17]
	v_lshl_add_u64 v[16:17], v[16:17], 0, v[14:15]
	global_store_dwordx4 v[16:17], v[24:27], off sc1
	s_waitcnt lgkmcnt(0)
	s_barrier
	s_andn2_b64 vcc, exec, s[16:17]
	s_mov_b32 s21, s23
	s_mov_b32 s7, s22
	s_cbranch_vccz .LBB0_165

; __device__ __forceinline__ float sigmoidf_(float x) { return 1.0f / (1.0f + __expf(-x)); }
; __device__ __forceinline__ float tanhf_(float x) { return 1.0f - 2.0f / (__expf(2.0f * x) + 1.0f); }
; __device__ __forceinline__ u32x4 pack8(const f32x4 v0, const f32x4 v1) { u32x4 w; w.x = pk2(v0[0], v0[1]); w.y = pk2(v0[2], v0[3]); w.z = pk2(v1[0], v1[1]); w.w = pk2(v1[2], v1[3]); return w; }
; __device__ void phase_e1(int l) {
;     ...
;             for (int j = 0; j < 4; ++j) { x0[j] = tanhf_(x0[j]); x1[j] = tanhf_(x1[j]); } }
;         else if (v >= 16) {
; #pragma unroll
;             for (int j = 0; j < 4; ++j) { x0[j] = sigmoidf_(x0[j]); x1[j] = sigmoidf_(x1[j]); } }
;         *(u32x4*)(Lb + (size_t)tok * 256 + v * 8) = pack8(x0, x1);
.LBB0_221:
	s_or_b64 exec, exec, s[12:13]
	v_ashrrev_i32_e32 v21, 31, v20
	v_add_u32_e32 v23, s52, v23
	v_cvt_pk_bf16_f32 v4, v4, v5
	v_cvt_pk_bf16_f32 v5, v0, v1
	v_lshlrev_b64 v[0:1], 9, v[20:21]
	v_cmp_lt_i32_e32 vcc, s26, v23
	v_lshl_add_u64 v[0:1], v[18:19], 0, v[0:1]
	s_or_b64 s[16:17], vcc, s[16:17]
	v_cvt_pk_bf16_f32 v6, v6, v7
	v_cvt_pk_bf16_f32 v7, v2, v3
	global_store_dwordx4 v[0:1], v[4:7], off sc1
	s_andn2_b64 exec, exec, s[16:17]
	s_cbranch_execz .LBB0_234

; __device__ __forceinline__ u32x4 pack8(const f32x4 v0, const f32x4 v1) { u32x4 w; w.x = pk2(v0[0], v0[1]); w.y = pk2(v0[2], v0[3]); w.z = pk2(v1[0], v1[1]); w.w = pk2(v1[2], v1[3]); return w; }
; __device__ void phase_e1(int l) {
;     ...
;         const int cnt = tk.is_s ? win : min(tk.t + 1, win);
;         const float inv = 1.0f / (float)cnt;
;         s0 = s0 * inv - u0; s1 = s1 * inv - u1;
;         *(u32x4*)(pbuf + (size_t)tok * 512 + c) = pack8(s0, s1);
.LBB0_237:
	s_andn2_saveexec_b64 s[8:9], s[10:11]
	s_or_b64 exec, exec, s[8:9]
	s_waitcnt vmcnt(0)
	v_min_u32_e32 v8, v27, v26
	v_cndmask_b32_e32 v8, v26, v8, vcc
	v_cvt_f32_ubyte0_e32 v8, v8
	v_div_scale_f32 v9, s[8:9], v8, v8, 1.0
	v_rcp_f32_e32 v10, v9
	v_ashrrev_i32_e32 v17, 31, v16
	v_add_u32_e32 v51, s52, v51
	v_fma_f32 v11, -v9, v10, 1.0
	v_fmac_f32_e32 v10, v11, v10
	v_div_scale_f32 v11, vcc, 1.0, v8, 1.0
	v_mul_f32_e32 v26, v11, v10
	v_fma_f32 v27, -v9, v26, v11
	v_fmac_f32_e32 v26, v27, v10
	v_fma_f32 v9, -v9, v26, v11
	v_div_fmas_f32 v9, v9, v10, v26
	v_div_fixup_f32 v8, v9, v8, 1.0
	v_xor_b32_e32 v11, 0x80000000, v25
	v_xor_b32_e32 v10, 0x80000000, v24
	v_pk_fma_f32 v[2:3], v[2:3], v[8:9], v[10:11] op_sel_hi:[1,0,1]
	v_pk_fma_f32 v[0:1], v[0:1], v[8:9], v[20:21] op_sel_hi:[1,0,1] neg_lo:[0,0,1] neg_hi:[0,0,1]
	v_pk_fma_f32 v[4:5], v[4:5], v[8:9], v[18:19] op_sel_hi:[1,0,1] neg_lo:[0,0,1] neg_hi:[0,0,1]
	v_cvt_pk_bf16_f32 v0, v0, v1
	v_cvt_pk_bf16_f32 v1, v2, v3
	v_cmp_lt_i32_e32 vcc, s42, v51
	v_cvt_pk_bf16_f32 v2, v4, v5
	v_lshlrev_b64 v[4:5], 10, v[16:17]
	v_lshl_add_u64 v[4:5], s[62:63], 0, v[4:5]
	v_xor_b32_e32 v11, 0x80000000, v23
	v_xor_b32_e32 v10, 0x80000000, v22
	v_lshl_add_u64 v[4:5], v[4:5], 0, v[14:15]
	s_or_b64 s[66:67], vcc, s[66:67]
	v_pk_fma_f32 v[6:7], v[6:7], v[8:9], v[10:11] op_sel_hi:[1,0,1]
	s_nop 0
	v_cvt_pk_bf16_f32 v3, v6, v7
	global_store_dwordx4 v[4:5], v[0:3], off sc1
	s_andn2_b64 exec, exec, s[66:67]
	s_cbranch_execz .LBB0_255

; #define PG8_STAGE(bufoff, gbase, voff) do { _Pragma("unroll") for (int _i = 0; _i < 2; ++_i) \
;         __builtin_amdgcn_global_load_lds((const unsigned*)((const char*)(gbase) + (voff)[_i]), (LAS unsigned*)(lds + (bufoff) + ldsw + _i * 8192), 16, 0, 0); } while (0)
; #define PG8_LDA(dst, b, h) do { _Pragma("unroll") for (int m = 0; m < 4; ++m) _Pragma("unroll") for (int k = 0; k < 2; ++k) dst[m][k] = *(const LAS bf16x8*)(lds + PG8_SA(b, h) + aoff + m * 2048 + k * 1024); } while (0)
; #define PG8_LDB(dst, b, h) do { _Pragma("unroll") for (int n = 0; n < 2; ++n) _Pragma("unroll") for (int k = 0; k < 2; ++k) dst[n][k] = *(const LAS bf16x8*)(lds + PG8_SB(b, h) + boff + n * 2048 + k * 1024); } while (0)
; #define PG8_MMA(ai, bj, At, Bt) do { __builtin_amdgcn_s_setprio(1); _Pragma("unroll") for (int m = 0; m < 4; ++m) _Pragma("unroll") for (int n = 0; n < 2; ++n) _Pragma("unroll") for (int k = 0; k < 2; ++k) \
;         acc[ai][bj][m][n] = __builtin_amdgcn_mfma_f32_16x16x32_bf16(Bt[n][k], At[m][k], acc[ai][bj][m][n], 0, 0, 0); __builtin_amdgcn_s_setprio(0); } while (0)
; #define PG8_WAIT_V(n) asm volatile("s_waitcnt vmcnt(" #n ")" ::: "memory")
;     ...
;             PG8_LDB(B0, 0, 0); PG8_SCHED; PG8_LDA(At, 0, 0); PG8_STAGE(PG8_SA(1, 1), a1 + hA, voffA);
;             PG8_WAIT_L(8); PG8_BAR; PG8_WAIT_L(0); PG8_MMA(0, 0, At, B0); PG8_BAR; PG8_SCHED;
;             PG8_LDB(B1, 0, 1); PG8_STAGE(PG8_SB(0, 0), b2, voffB);
;             PG8_BAR; PG8_WAIT_L(0); PG8_MMA(0, 1, At, B1); PG8_BAR;
;             PG8_LDA(At, 0, 1); PG8_STAGE(PG8_SA(0, 0), a2, voffA);
;             PG8_BAR; PG8_WAIT_L(0); PG8_MMA(1, 0, At, B0); PG8_BAR; PG8_SCHED;
;             PG8_STAGE(PG8_SB(0, 1), b2 + hB, voffB);
;             PG8_WAIT_V(6); PG8_BAR; PG8_MMA(1, 1, At, B1); PG8_BAR;
;             PG8_LDB(B0, 1, 0); PG8_SCHED; PG8_LDA(At, 1, 0); PG8_STAGE(PG8_SA(0, 1), a2 + hA, voffA);
;             PG8_WAIT_L(8); PG8_BAR; PG8_WAIT_L(0); PG8_MMA(0, 0, At, B0); PG8_BAR; PG8_SCHED;
;             PG8_LDB(B1, 1, 1); PG8_STAGE(PG8_SB(1, 0), b3, voffB);
;             PG8_BAR; PG8_WAIT_L(0); PG8_MMA(0, 1, At, B1); PG8_BAR;
;             PG8_LDA(At, 1, 1); PG8_STAGE(PG8_SA(1, 0), a3, voffA);
;             PG8_BAR; PG8_WAIT_L(0); PG8_MMA(1, 0, At, B0); PG8_BAR; PG8_SCHED;
;             PG8_STAGE(PG8_SB(1, 1), b3 + hB, voffB);
;             PG8_WAIT_V(6); PG8_BAR; PG8_MMA(1, 1, At, B1); PG8_BAR;
.LBB0_344:
	ds_read_b128 v[128:131], v173
	ds_read_b128 v[132:135], v173 offset:1024
	ds_read_b128 v[136:139], v173 offset:2048
	ds_read_b128 v[140:143], v173 offset:3072
	s_add_u32 s34, s30, 0xfffe0080
	s_addc_u32 s35, s31, -1
	s_cmp_eq_u32 s44, 4
	s_cselect_b32 s37, s7, s35
	s_cselect_b32 s36, s23, s34
	s_cselect_b32 s35, s21, s43
	s_cselect_b32 s34, s33, s42
	v_lshl_add_u64 v[204:205], s[30:31], 0, v[156:157]
	s_add_i32 m0, s29, 0xc000
	ds_read_b128 v[162:165], v174
	ds_read_b128 v[176:179], v174 offset:1024
	ds_read_b128 v[180:183], v174 offset:2048
	ds_read_b128 v[184:187], v174 offset:3072
	ds_read_b128 v[188:191], v174 offset:4096
	ds_read_b128 v[192:195], v174 offset:5120
	ds_read_b128 v[196:199], v174 offset:6144
	ds_read_b128 v[200:203], v174 offset:7168
	global_load_lds_dwordx4 v[204:205], off
	v_lshl_add_u64 v[204:205], s[30:31], 0, v[154:155]
	s_add_i32 m0, s29, 0xe000
	s_nop 0
	global_load_lds_dwordx4 v[204:205], off
	s_waitcnt lgkmcnt(8)
	s_barrier
	s_waitcnt lgkmcnt(0)
	s_setprio 1
	s_waitcnt lgkmcnt(0)
	v_mfma_f32_16x16x32_bf16 v[124:127], v[128:131], v[162:165], v[124:127]
	v_mfma_f32_16x16x32_bf16 v[120:123], v[136:139], v[162:165], v[120:123]
	v_mfma_f32_16x16x32_bf16 v[116:119], v[128:131], v[180:183], v[116:119]
	v_mfma_f32_16x16x32_bf16 v[112:115], v[136:139], v[180:183], v[112:115]
	v_mfma_f32_16x16x32_bf16 v[108:111], v[128:131], v[188:191], v[108:111]
	v_mfma_f32_16x16x32_bf16 v[100:103], v[136:139], v[188:191], v[100:103]
	v_mfma_f32_16x16x32_bf16 v[92:95], v[128:131], v[196:199], v[92:95]
	v_mfma_f32_16x16x32_bf16 v[80:83], v[136:139], v[196:199], v[80:83]
	v_mfma_f32_16x16x32_bf16 v[124:127], v[132:135], v[176:179], v[124:127]
	v_mfma_f32_16x16x32_bf16 v[120:123], v[140:143], v[176:179], v[120:123]
	v_mfma_f32_16x16x32_bf16 v[116:119], v[132:135], v[184:187], v[116:119]
	v_mfma_f32_16x16x32_bf16 v[112:115], v[140:143], v[184:187], v[112:115]
	v_mfma_f32_16x16x32_bf16 v[108:111], v[132:135], v[192:195], v[108:111]
	v_mfma_f32_16x16x32_bf16 v[100:103], v[140:143], v[192:195], v[100:103]
	v_mfma_f32_16x16x32_bf16 v[92:95], v[132:135], v[200:203], v[92:95]
	v_mfma_f32_16x16x32_bf16 v[80:83], v[140:143], v[200:203], v[80:83]
	s_setprio 0
	s_barrier
	s_add_i32 s45, s62, s40
	v_lshl_add_u64 v[220:221], s[34:35], 0, v[150:151]
	s_mov_b32 m0, s45
	ds_read_b128 v[204:207], v175
	ds_read_b128 v[208:211], v175 offset:1024
	ds_read_b128 v[212:215], v175 offset:2048
	ds_read_b128 v[216:219], v175 offset:3072
	global_load_lds_dwordx4 v[220:221], off
	v_lshl_add_u64 v[222:223], s[34:35], 0, v[146:147]
	s_add_i32 m0, s45, 0x2000
	s_nop 0
	global_load_lds_dwordx4 v[222:223], off
	s_barrier
	s_waitcnt lgkmcnt(0)
	s_setprio 1
	s_waitcnt lgkmcnt(0)
	v_mfma_f32_16x16x32_bf16 v[104:107], v[204:207], v[162:165], v[104:107]
	v_mfma_f32_16x16x32_bf16 v[96:99], v[212:215], v[162:165], v[96:99]
	v_mfma_f32_16x16x32_bf16 v[88:91], v[204:207], v[180:183], v[88:91]
	v_mfma_f32_16x16x32_bf16 v[84:87], v[212:215], v[180:183], v[84:87]
	v_mfma_f32_16x16x32_bf16 v[76:79], v[204:207], v[188:191], v[76:79]
	v_mfma_f32_16x16x32_bf16 v[72:75], v[212:215], v[188:191], v[72:75]
	v_mfma_f32_16x16x32_bf16 v[68:71], v[204:207], v[196:199], v[68:71]
	v_mfma_f32_16x16x32_bf16 v[64:67], v[212:215], v[196:199], v[64:67]
	v_mfma_f32_16x16x32_bf16 v[104:107], v[208:211], v[176:179], v[104:107]
	v_mfma_f32_16x16x32_bf16 v[96:99], v[216:219], v[176:179], v[96:99]
	v_mfma_f32_16x16x32_bf16 v[88:91], v[208:211], v[184:187], v[88:91]
	v_mfma_f32_16x16x32_bf16 v[84:87], v[216:219], v[184:187], v[84:87]
	v_mfma_f32_16x16x32_bf16 v[76:79], v[208:211], v[192:195], v[76:79]
	v_mfma_f32_16x16x32_bf16 v[72:75], v[216:219], v[192:195], v[72:75]
	v_mfma_f32_16x16x32_bf16 v[68:71], v[208:211], v[200:203], v[68:71]
	v_mfma_f32_16x16x32_bf16 v[64:67], v[216:219], v[200:203], v[64:67]
	s_setprio 0
	s_mov_b32 m0, s29
	v_lshl_add_u64 v[224:225], s[36:37], 0, v[152:153]
	s_barrier
	ds_read_b128 v[162:165], v174 offset:16384
	ds_read_b128 v[176:179], v174 offset:17408
	ds_read_b128 v[180:183], v174 offset:18432
	ds_read_b128 v[184:187], v174 offset:19456
	ds_read_b128 v[188:191], v174 offset:20480
	ds_read_b128 v[192:195], v174 offset:21504
	ds_read_b128 v[196:199], v174 offset:22528
	ds_read_b128 v[200:203], v174 offset:23552
	global_load_lds_dwordx4 v[224:225], off
	v_lshl_add_u64 v[226:227], s[36:37], 0, v[148:149]
	s_mov_b32 m0, s53
	s_nop 0
	global_load_lds_dwordx4 v[226:227], off
	s_barrier
	s_waitcnt lgkmcnt(0)
	s_setprio 1
	s_waitcnt lgkmcnt(0)
	v_mfma_f32_16x16x32_bf16 v[60:63], v[128:131], v[162:165], v[60:63]
	v_mfma_f32_16x16x32_bf16 v[56:59], v[136:139], v[162:165], v[56:59]
	v_mfma_f32_16x16x32_bf16 v[48:51], v[128:131], v[180:183], v[48:51]
	v_mfma_f32_16x16x32_bf16 v[40:43], v[136:139], v[180:183], v[40:43]
	v_mfma_f32_16x16x32_bf16 v[32:35], v[128:131], v[188:191], v[32:35]
	v_mfma_f32_16x16x32_bf16 v[24:27], v[136:139], v[188:191], v[24:27]
	v_mfma_f32_16x16x32_bf16 v[16:19], v[128:131], v[196:199], v[16:19]
	v_mfma_f32_16x16x32_bf16 v[8:11], v[136:139], v[196:199], v[8:11]
	v_mfma_f32_16x16x32_bf16 v[60:63], v[132:135], v[176:179], v[60:63]
	v_mfma_f32_16x16x32_bf16 v[56:59], v[140:143], v[176:179], v[56:59]
	v_mfma_f32_16x16x32_bf16 v[48:51], v[132:135], v[184:187], v[48:51]
	v_mfma_f32_16x16x32_bf16 v[40:43], v[140:143], v[184:187], v[40:43]
	v_mfma_f32_16x16x32_bf16 v[32:35], v[132:135], v[192:195], v[32:35]
	v_mfma_f32_16x16x32_bf16 v[24:27], v[140:143], v[192:195], v[24:27]
	v_mfma_f32_16x16x32_bf16 v[16:19], v[132:135], v[200:203], v[16:19]
	v_mfma_f32_16x16x32_bf16 v[8:11], v[140:143], v[200:203], v[8:11]
	s_setprio 0
	s_barrier
; #define PG8_STAGE(bufoff, gbase, voff) do { _Pragma("unroll") for (int _i = 0; _i < 2; ++_i) \
;         __builtin_amdgcn_global_load_lds((const unsigned*)((const char*)(gbase) + (voff)[_i]), (LAS unsigned*)(lds + (bufoff) + ldsw + _i * 8192), 16, 0, 0); } while (0)
; #define PG8_LDA(dst, b, h) do { _Pragma("unroll") for (int m = 0; m < 4; ++m) _Pragma("unroll") for (int k = 0; k < 2; ++k) dst[m][k] = *(const LAS bf16x8*)(lds + PG8_SA(b, h) + aoff + m * 2048 + k * 1024); } while (0)
; #define PG8_LDB(dst, b, h) do { _Pragma("unroll") for (int n = 0; n < 2; ++n) _Pragma("unroll") for (int k = 0; k < 2; ++k) dst[n][k] = *(const LAS bf16x8*)(lds + PG8_SB(b, h) + boff + n * 2048 + k * 1024); } while (0)
; #define PG8_MMA(ai, bj, At, Bt) do { __builtin_amdgcn_s_setprio(1); _Pragma("unroll") for (int m = 0; m < 4; ++m) _Pragma("unroll") for (int n = 0; n < 2; ++n) _Pragma("unroll") for (int k = 0; k < 2; ++k) \
;         acc[ai][bj][m][n] = __builtin_amdgcn_mfma_f32_16x16x32_bf16(Bt[n][k], At[m][k], acc[ai][bj][m][n], 0, 0, 0); __builtin_amdgcn_s_setprio(0); } while (0)
; #define PG8_WAIT_V(n) asm volatile("s_waitcnt vmcnt(" #n ")" ::: "memory")
;     ...
;             PG8_LDB(B0, 0, 0); PG8_SCHED; PG8_LDA(At, 0, 0); PG8_STAGE(PG8_SA(1, 1), a1 + hA, voffA);
;             PG8_WAIT_L(8); PG8_BAR; PG8_WAIT_L(0); PG8_MMA(0, 0, At, B0); PG8_BAR; PG8_SCHED;
;             PG8_LDB(B1, 0, 1); PG8_STAGE(PG8_SB(0, 0), b2, voffB);
;             PG8_BAR; PG8_WAIT_L(0); PG8_MMA(0, 1, At, B1); PG8_BAR;
;             PG8_LDA(At, 0, 1); PG8_STAGE(PG8_SA(0, 0), a2, voffA);
;             PG8_BAR; PG8_WAIT_L(0); PG8_MMA(1, 0, At, B0); PG8_BAR; PG8_SCHED;
;             PG8_STAGE(PG8_SB(0, 1), b2 + hB, voffB);
;             PG8_WAIT_V(6); PG8_BAR; PG8_MMA(1, 1, At, B1); PG8_BAR;
;             PG8_LDB(B0, 1, 0); PG8_SCHED; PG8_LDA(At, 1, 0); PG8_STAGE(PG8_SA(0, 1), a2 + hA, voffA);
;             PG8_WAIT_L(8); PG8_BAR; PG8_WAIT_L(0); PG8_MMA(0, 0, At, B0); PG8_BAR; PG8_SCHED;
;             PG8_LDB(B1, 1, 1); PG8_STAGE(PG8_SB(1, 0), b3, voffB);
;             PG8_BAR; PG8_WAIT_L(0); PG8_MMA(0, 1, At, B1); PG8_BAR;
;             PG8_LDA(At, 1, 1); PG8_STAGE(PG8_SA(1, 0), a3, voffA);
;             PG8_BAR; PG8_WAIT_L(0); PG8_MMA(1, 0, At, B0); PG8_BAR; PG8_SCHED;
;             PG8_STAGE(PG8_SB(1, 1), b3 + hB, voffB);
;             PG8_WAIT_V(6); PG8_BAR; PG8_MMA(1, 1, At, B1); PG8_BAR;
	s_add_u32 s66, s34, 0x20000
	s_addc_u32 s67, s35, 0
	s_add_i32 s45, s63, s40
	v_lshl_add_u64 v[128:129], s[66:67], 0, v[150:151]
	s_mov_b32 m0, s45
	s_nop 0
	global_load_lds_dwordx4 v[128:129], off
	v_lshl_add_u64 v[128:129], s[66:67], 0, v[146:147]
	s_add_i32 m0, s45, 0x2000
	s_nop 0
	global_load_lds_dwordx4 v[128:129], off
	s_waitcnt vmcnt(6)
	s_barrier
	s_setprio 1
	v_mfma_f32_16x16x32_bf16 v[52:55], v[204:207], v[162:165], v[52:55]
	v_mfma_f32_16x16x32_bf16 v[44:47], v[212:215], v[162:165], v[44:47]
	v_mfma_f32_16x16x32_bf16 v[36:39], v[204:207], v[180:183], v[36:39]
	v_mfma_f32_16x16x32_bf16 v[28:31], v[212:215], v[180:183], v[28:31]
	v_mfma_f32_16x16x32_bf16 v[20:23], v[204:207], v[188:191], v[20:23]
	v_mfma_f32_16x16x32_bf16 v[12:15], v[212:215], v[188:191], v[12:15]
	v_mfma_f32_16x16x32_bf16 v[4:7], v[204:207], v[196:199], v[4:7]
	v_mfma_f32_16x16x32_bf16 v[0:3], v[212:215], v[196:199], v[0:3]
	v_mfma_f32_16x16x32_bf16 v[52:55], v[208:211], v[176:179], v[52:55]
	v_mfma_f32_16x16x32_bf16 v[44:47], v[216:219], v[176:179], v[44:47]
	v_mfma_f32_16x16x32_bf16 v[36:39], v[208:211], v[184:187], v[36:39]
	v_mfma_f32_16x16x32_bf16 v[28:31], v[216:219], v[184:187], v[28:31]
	v_mfma_f32_16x16x32_bf16 v[20:23], v[208:211], v[192:195], v[20:23]
	v_mfma_f32_16x16x32_bf16 v[12:15], v[216:219], v[192:195], v[12:15]
	v_mfma_f32_16x16x32_bf16 v[4:7], v[208:211], v[200:203], v[4:7]
	v_mfma_f32_16x16x32_bf16 v[0:3], v[216:219], v[200:203], v[0:3]
	s_setprio 0
	s_add_i32 s45, 0, 0x18000
	v_add_u32_e32 v140, s45, v171
	s_barrier
	ds_read_b128 v[128:131], v140
	ds_read_b128 v[132:135], v140 offset:1024
	ds_read_b128 v[136:139], v140 offset:2048
	ds_read_b128 v[140:143], v140 offset:3072
	s_add_u32 s36, s36, 0x20000
	s_addc_u32 s37, s37, 0
	s_mov_b32 m0, s56
	v_lshl_add_u64 v[204:205], s[36:37], 0, v[152:153]
	ds_read_b128 v[162:165], v174 offset:32768
	ds_read_b128 v[176:179], v174 offset:33792
	ds_read_b128 v[180:183], v174 offset:34816
	ds_read_b128 v[184:187], v174 offset:35840
	ds_read_b128 v[188:191], v174 offset:36864
	ds_read_b128 v[192:195], v174 offset:37888
	ds_read_b128 v[196:199], v174 offset:38912
	ds_read_b128 v[200:203], v174 offset:39936
	global_load_lds_dwordx4 v[204:205], off
	v_lshl_add_u64 v[204:205], s[36:37], 0, v[148:149]
	s_mov_b32 m0, s57
	s_nop 0
	global_load_lds_dwordx4 v[204:205], off
	s_waitcnt lgkmcnt(8)
	s_barrier
	s_waitcnt lgkmcnt(0)
	s_setprio 1
	s_waitcnt lgkmcnt(0)
	v_mfma_f32_16x16x32_bf16 v[124:127], v[128:131], v[162:165], v[124:127]
	v_mfma_f32_16x16x32_bf16 v[120:123], v[136:139], v[162:165], v[120:123]
	v_mfma_f32_16x16x32_bf16 v[116:119], v[128:131], v[180:183], v[116:119]
	v_mfma_f32_16x16x32_bf16 v[112:115], v[136:139], v[180:183], v[112:115]
	v_mfma_f32_16x16x32_bf16 v[108:111], v[128:131], v[188:191], v[108:111]
	v_mfma_f32_16x16x32_bf16 v[100:103], v[136:139], v[188:191], v[100:103]
	v_mfma_f32_16x16x32_bf16 v[92:95], v[128:131], v[196:199], v[92:95]
	v_mfma_f32_16x16x32_bf16 v[80:83], v[136:139], v[196:199], v[80:83]
	v_mfma_f32_16x16x32_bf16 v[124:127], v[132:135], v[176:179], v[124:127]
	v_mfma_f32_16x16x32_bf16 v[120:123], v[140:143], v[176:179], v[120:123]
	v_mfma_f32_16x16x32_bf16 v[116:119], v[132:135], v[184:187], v[116:119]
	v_mfma_f32_16x16x32_bf16 v[112:115], v[140:143], v[184:187], v[112:115]
	v_mfma_f32_16x16x32_bf16 v[108:111], v[132:135], v[192:195], v[108:111]
	v_mfma_f32_16x16x32_bf16 v[100:103], v[140:143], v[192:195], v[100:103]
	v_mfma_f32_16x16x32_bf16 v[92:95], v[132:135], v[200:203], v[92:95]
	v_mfma_f32_16x16x32_bf16 v[80:83], v[140:143], v[200:203], v[80:83]
	s_setprio 0
	s_barrier
	s_add_i32 s36, 0, 0x1c000
	s_add_i32 s37, s45, s40
	v_add_u32_e32 v216, s36, v171
	v_lshl_add_u64 v[220:221], v[220:221], 0, s[18:19]
	s_mov_b32 m0, s37
	ds_read_b128 v[204:207], v216
	ds_read_b128 v[208:211], v216 offset:1024
	ds_read_b128 v[212:215], v216 offset:2048
	ds_read_b128 v[216:219], v216 offset:3072
	global_load_lds_dwordx4 v[220:221], off
	v_lshl_add_u64 v[220:221], v[222:223], 0, s[18:19]
	s_add_i32 m0, s37, 0x2000
	s_nop 0
	global_load_lds_dwordx4 v[220:221], off
	s_barrier
	s_waitcnt lgkmcnt(0)
	s_setprio 1
	s_waitcnt lgkmcnt(0)
	v_mfma_f32_16x16x32_bf16 v[104:107], v[204:207], v[162:165], v[104:107]
	v_mfma_f32_16x16x32_bf16 v[96:99], v[212:215], v[162:165], v[96:99]
	v_mfma_f32_16x16x32_bf16 v[88:91], v[204:207], v[180:183], v[88:91]
	v_mfma_f32_16x16x32_bf16 v[84:87], v[212:215], v[180:183], v[84:87]
	v_mfma_f32_16x16x32_bf16 v[76:79], v[204:207], v[188:191], v[76:79]
	v_mfma_f32_16x16x32_bf16 v[72:75], v[212:215], v[188:191], v[72:75]
	v_mfma_f32_16x16x32_bf16 v[68:71], v[204:207], v[196:199], v[68:71]
	v_mfma_f32_16x16x32_bf16 v[64:67], v[212:215], v[196:199], v[64:67]
	v_mfma_f32_16x16x32_bf16 v[104:107], v[208:211], v[176:179], v[104:107]
	v_mfma_f32_16x16x32_bf16 v[96:99], v[216:219], v[176:179], v[96:99]
	v_mfma_f32_16x16x32_bf16 v[88:91], v[208:211], v[184:187], v[88:91]
	v_mfma_f32_16x16x32_bf16 v[84:87], v[216:219], v[184:187], v[84:87]
	v_mfma_f32_16x16x32_bf16 v[76:79], v[208:211], v[192:195], v[76:79]
	v_mfma_f32_16x16x32_bf16 v[72:75], v[216:219], v[192:195], v[72:75]
	v_mfma_f32_16x16x32_bf16 v[68:71], v[208:211], v[200:203], v[68:71]
	v_mfma_f32_16x16x32_bf16 v[64:67], v[216:219], v[200:203], v[64:67]
	s_setprio 0
	s_mov_b32 m0, s58
	v_lshl_add_u64 v[220:221], v[224:225], 0, s[18:19]
	s_barrier
	ds_read_b128 v[162:165], v174 offset:49152
	ds_read_b128 v[176:179], v174 offset:50176
	ds_read_b128 v[180:183], v174 offset:51200
	ds_read_b128 v[184:187], v174 offset:52224
	ds_read_b128 v[188:191], v174 offset:53248
	ds_read_b128 v[192:195], v174 offset:54272
	ds_read_b128 v[196:199], v174 offset:55296
	ds_read_b128 v[200:203], v174 offset:56320
	global_load_lds_dwordx4 v[220:221], off
	v_lshl_add_u64 v[220:221], v[226:227], 0, s[18:19]
	s_mov_b32 m0, s59
	s_nop 0
	global_load_lds_dwordx4 v[220:221], off
	s_barrier
; #define PG8_STAGE(bufoff, gbase, voff) do { _Pragma("unroll") for (int _i = 0; _i < 2; ++_i) \
;         __builtin_amdgcn_global_load_lds((const unsigned*)((const char*)(gbase) + (voff)[_i]), (LAS unsigned*)(lds + (bufoff) + ldsw + _i * 8192), 16, 0, 0); } while (0)
; #define PG8_LDA(dst, b, h) do { _Pragma("unroll") for (int m = 0; m < 4; ++m) _Pragma("unroll") for (int k = 0; k < 2; ++k) dst[m][k] = *(const LAS bf16x8*)(lds + PG8_SA(b, h) + aoff + m * 2048 + k * 1024); } while (0)
; #define PG8_LDB(dst, b, h) do { _Pragma("unroll") for (int n = 0; n < 2; ++n) _Pragma("unroll") for (int k = 0; k < 2; ++k) dst[n][k] = *(const LAS bf16x8*)(lds + PG8_SB(b, h) + boff + n * 2048 + k * 1024); } while (0)
;     ...
;             PG8_LDB(B0, 0, 0); PG8_SCHED; PG8_LDA(At, 0, 0); PG8_STAGE(PG8_SA(1, 1), a1 + hA, voffA);
;             PG8_WAIT_L(8); PG8_BAR; PG8_WAIT_L(0); PG8_MMA(0, 0, At, B0); PG8_BAR; PG8_SCHED;
;             PG8_LDB(B1, 0, 1); PG8_STAGE(PG8_SB(0, 0), b2, voffB);
;             PG8_BAR; PG8_WAIT_L(0); PG8_MMA(0, 1, At, B1); PG8_BAR;
;             PG8_LDA(At, 0, 1); PG8_STAGE(PG8_SA(0, 0), a2, voffA);
;             PG8_BAR; PG8_WAIT_L(0); PG8_MMA(1, 0, At, B0); PG8_BAR; PG8_SCHED;
;             PG8_STAGE(PG8_SB(0, 1), b2 + hB, voffB);
;             PG8_WAIT_V(6); PG8_BAR; PG8_MMA(1, 1, At, B1); PG8_BAR;
;             PG8_LDB(B0, 1, 0); PG8_SCHED; PG8_LDA(At, 1, 0); PG8_STAGE(PG8_SA(0, 1), a2 + hA, voffA);
;             PG8_WAIT_L(8); PG8_BAR; PG8_WAIT_L(0); PG8_MMA(0, 0, At, B0); PG8_BAR; PG8_SCHED;
;             PG8_LDB(B1, 1, 1); PG8_STAGE(PG8_SB(1, 0), b3, voffB);
;             PG8_BAR; PG8_WAIT_L(0); PG8_MMA(0, 1, At, B1); PG8_BAR;
;             PG8_LDA(At, 1, 1); PG8_STAGE(PG8_SA(1, 0), a3, voffA);
;             PG8_BAR; PG8_WAIT_L(0); PG8_MMA(1, 0, At, B0); PG8_BAR; PG8_SCHED;
;             PG8_STAGE(PG8_SB(1, 1), b3 + hB, voffB);
;             PG8_WAIT_V(6); PG8_BAR; PG8_MMA(1, 1, At, B1); PG8_BAR;
;     __device__ __forceinline__ void operator()(const f32x4 (&acc)[2][2][4][2], const Unit& u, int wr, int wc, int fr, int fq) const {
;         const int row0 = u.pm * 256 + wr * 64 + fr, col0 = u.pn * 256 + wc * 32 + 8 * fq;
;         f32x4 bv[2][2];
; #pragma unroll
;         for (int bj = 0; bj < 2; ++bj)
; #pragma unroll
;             for (int n = 0; n < 2; ++n) bv[bj][n] = *(const f32x4*)(scale + col0 + bj * 128 + 4 * n);
	s_waitcnt lgkmcnt(0)
	s_setprio 1
	s_waitcnt lgkmcnt(0)
	v_mfma_f32_16x16x32_bf16 v[60:63], v[128:131], v[162:165], v[60:63]
	v_mfma_f32_16x16x32_bf16 v[56:59], v[136:139], v[162:165], v[56:59]
	v_mfma_f32_16x16x32_bf16 v[48:51], v[128:131], v[180:183], v[48:51]
	v_mfma_f32_16x16x32_bf16 v[40:43], v[136:139], v[180:183], v[40:43]
	v_mfma_f32_16x16x32_bf16 v[32:35], v[128:131], v[188:191], v[32:35]
	v_mfma_f32_16x16x32_bf16 v[24:27], v[136:139], v[188:191], v[24:27]
	v_mfma_f32_16x16x32_bf16 v[16:19], v[128:131], v[196:199], v[16:19]
	v_mfma_f32_16x16x32_bf16 v[8:11], v[136:139], v[196:199], v[8:11]
	v_mfma_f32_16x16x32_bf16 v[60:63], v[132:135], v[176:179], v[60:63]
	v_mfma_f32_16x16x32_bf16 v[56:59], v[140:143], v[176:179], v[56:59]
	v_mfma_f32_16x16x32_bf16 v[48:51], v[132:135], v[184:187], v[48:51]
	v_mfma_f32_16x16x32_bf16 v[40:43], v[140:143], v[184:187], v[40:43]
	v_mfma_f32_16x16x32_bf16 v[32:35], v[132:135], v[192:195], v[32:35]
	v_mfma_f32_16x16x32_bf16 v[24:27], v[140:143], v[192:195], v[24:27]
	v_mfma_f32_16x16x32_bf16 v[16:19], v[132:135], v[200:203], v[16:19]
	v_mfma_f32_16x16x32_bf16 v[8:11], v[140:143], v[200:203], v[8:11]
	s_setprio 0
	s_barrier
	s_add_u32 s34, s34, 0x20080
	s_addc_u32 s35, s35, 0
	s_add_i32 s36, s36, s40
	v_lshl_add_u64 v[128:129], s[34:35], 0, v[150:151]
	s_mov_b32 m0, s36
	s_nop 0
	global_load_lds_dwordx4 v[128:129], off
	v_lshl_add_u64 v[128:129], s[34:35], 0, v[146:147]
	s_add_i32 m0, s36, 0x2000
	s_nop 0
	global_load_lds_dwordx4 v[128:129], off
	s_waitcnt vmcnt(6)
	s_barrier
	s_setprio 1
	v_mfma_f32_16x16x32_bf16 v[52:55], v[204:207], v[162:165], v[52:55]
	v_mfma_f32_16x16x32_bf16 v[44:47], v[212:215], v[162:165], v[44:47]
	v_mfma_f32_16x16x32_bf16 v[36:39], v[204:207], v[180:183], v[36:39]
	v_mfma_f32_16x16x32_bf16 v[28:31], v[212:215], v[180:183], v[28:31]
	v_mfma_f32_16x16x32_bf16 v[20:23], v[204:207], v[188:191], v[20:23]
	v_mfma_f32_16x16x32_bf16 v[12:15], v[212:215], v[188:191], v[12:15]
	v_mfma_f32_16x16x32_bf16 v[4:7], v[204:207], v[196:199], v[4:7]
	v_mfma_f32_16x16x32_bf16 v[0:3], v[212:215], v[196:199], v[0:3]
	v_mfma_f32_16x16x32_bf16 v[52:55], v[208:211], v[176:179], v[52:55]
	v_mfma_f32_16x16x32_bf16 v[44:47], v[216:219], v[176:179], v[44:47]
	v_mfma_f32_16x16x32_bf16 v[36:39], v[208:211], v[184:187], v[36:39]
	v_mfma_f32_16x16x32_bf16 v[28:31], v[216:219], v[184:187], v[28:31]
	v_mfma_f32_16x16x32_bf16 v[20:23], v[208:211], v[192:195], v[20:23]
	v_mfma_f32_16x16x32_bf16 v[12:15], v[216:219], v[192:195], v[12:15]
	v_mfma_f32_16x16x32_bf16 v[4:7], v[208:211], v[200:203], v[4:7]
	v_mfma_f32_16x16x32_bf16 v[0:3], v[216:219], v[200:203], v[0:3]
	s_setprio 0
	s_add_i32 s44, s44, 2
	s_add_u32 s42, s42, 0x100
	s_addc_u32 s43, s43, 0
	s_add_u32 s30, s30, 0x100
	s_addc_u32 s31, s31, 0
	s_cmp_gt_u32 s44, 5
	s_barrier
	s_cbranch_scc0 .LBB0_344
	v_lshl_or_b32 v164, s6, 8, v172
	v_ashrrev_i32_e32 v165, 31, v164
	v_lshl_add_u64 v[128:129], v[164:165], 2, s[16:17]
	global_load_dwordx4 v[140:143], v[128:129], off
	global_load_dwordx4 v[136:139], v[128:129], off offset:16
	global_load_dwordx4 v[132:135], v[128:129], off offset:512
	s_nop 0
	global_load_dwordx4 v[128:131], v[128:129], off offset:528
	v_lshl_add_u32 v188, s28, 8, v170
	v_mov_b64_e32 v[162:163], s[14:15]
	v_mad_i64_i32 v[176:177], s[6:7], v188, s64, v[162:163]
	v_lshlrev_b64 v[164:165], 1, v[164:165]
	v_or_b32_e32 v178, 16, v188
	v_lshl_add_u64 v[176:177], v[176:177], 0, v[164:165]
	v_mad_i64_i32 v[178:179], s[6:7], v178, s64, v[162:163]
	v_or_b32_e32 v180, 32, v188
	v_lshl_add_u64 v[178:179], v[178:179], 0, v[164:165]
	v_mad_i64_i32 v[180:181], s[6:7], v180, s64, v[162:163]
	v_or_b32_e32 v182, 48, v188
	v_lshl_add_u64 v[180:181], v[180:181], 0, v[164:165]
	v_mad_i64_i32 v[182:183], s[6:7], v182, s64, v[162:163]
	v_lshl_add_u64 v[182:183], v[182:183], 0, v[164:165]
	s_and_b64 vcc, exec, s[8:9]
	s_mov_b32 s28, s22
	s_mov_b64 s[30:31], s[26:27]
	s_mov_b64 s[34:35], s[24:25]
	s_waitcnt vmcnt(0)
; __device__ __forceinline__ u32x4 pack8(const f32x4 v0, const f32x4 v1) { u32x4 w; w.x = pk2(v0[0], v0[1]); w.y = pk2(v0[2], v0[3]); w.z = pk2(v1[0], v1[1]); w.w = pk2(v1[2], v1[3]); return w; }
;     __device__ __forceinline__ void operator()(const f32x4 (&acc)[2][2][4][2], const Unit& u, int wr, int wc, int fr, int fq) const {
;     ...
; #pragma unroll
;         for (int ai = 0; ai < 2; ++ai)
; #pragma unroll
;             for (int m = 0; m < 4; ++m) {
;                 bf16_t* rowp = z + (size_t)(row0 + ai * 128 + m * 16) * DIN + O_U + col0;
; #pragma unroll
;                 for (int bj = 0; bj < 2; ++bj) *(u32x4*)(rowp + bj * 128) = pack8(acc[ai][bj][m][0] * bv[bj][0], acc[ai][bj][m][1] * bv[bj][1]);
;             }
	v_pk_mul_f32 v[124:125], v[124:125], v[140:141]
	v_pk_mul_f32 v[126:127], v[126:127], v[142:143]
	v_pk_mul_f32 v[122:123], v[122:123], v[138:139]
	v_pk_mul_f32 v[186:187], v[64:65], v[128:129]
	v_cvt_pk_bf16_f32 v64, v124, v125
	v_pk_mul_f32 v[120:121], v[120:121], v[136:137]
	v_pk_mul_f32 v[104:105], v[104:105], v[132:133]
	v_pk_mul_f32 v[184:185], v[66:67], v[130:131]
	v_cvt_pk_bf16_f32 v65, v126, v127
	v_cvt_pk_bf16_f32 v66, v120, v121
	v_cvt_pk_bf16_f32 v67, v122, v123
	global_store_dwordx4 v[176:177], v[64:67], off offset:3584 sc1
	v_pk_mul_f32 v[106:107], v[106:107], v[134:135]
	v_pk_mul_f32 v[98:99], v[98:99], v[130:131]
	v_cvt_pk_bf16_f32 v64, v104, v105
	v_pk_mul_f32 v[96:97], v[96:97], v[128:129]
	v_pk_mul_f32 v[116:117], v[116:117], v[140:141]
	v_cvt_pk_bf16_f32 v65, v106, v107
	v_cvt_pk_bf16_f32 v66, v96, v97
	v_cvt_pk_bf16_f32 v67, v98, v99
	global_store_dwordx4 v[176:177], v[64:67], off offset:3840 sc1
	v_pk_mul_f32 v[118:119], v[118:119], v[142:143]
	v_pk_mul_f32 v[114:115], v[114:115], v[138:139]
	v_cvt_pk_bf16_f32 v64, v116, v117
	v_pk_mul_f32 v[112:113], v[112:113], v[136:137]
	v_pk_mul_f32 v[88:89], v[88:89], v[132:133]
	v_cvt_pk_bf16_f32 v65, v118, v119
	v_cvt_pk_bf16_f32 v66, v112, v113
	v_cvt_pk_bf16_f32 v67, v114, v115
	global_store_dwordx4 v[178:179], v[64:67], off offset:3584 sc1
	v_pk_mul_f32 v[90:91], v[90:91], v[134:135]
	v_pk_mul_f32 v[86:87], v[86:87], v[130:131]
	v_cvt_pk_bf16_f32 v64, v88, v89
	v_pk_mul_f32 v[84:85], v[84:85], v[128:129]
	v_pk_mul_f32 v[108:109], v[108:109], v[140:141]
	v_cvt_pk_bf16_f32 v65, v90, v91
	v_cvt_pk_bf16_f32 v66, v84, v85
	v_cvt_pk_bf16_f32 v67, v86, v87
	global_store_dwordx4 v[178:179], v[64:67], off offset:3840 sc1
	v_pk_mul_f32 v[110:111], v[110:111], v[142:143]
	v_pk_mul_f32 v[102:103], v[102:103], v[138:139]
	v_cvt_pk_bf16_f32 v64, v108, v109
	v_pk_mul_f32 v[100:101], v[100:101], v[136:137]
	v_pk_mul_f32 v[76:77], v[76:77], v[132:133]
	v_cvt_pk_bf16_f32 v65, v110, v111
	v_cvt_pk_bf16_f32 v66, v100, v101
	v_cvt_pk_bf16_f32 v67, v102, v103
	global_store_dwordx4 v[180:181], v[64:67], off offset:3584 sc1
	v_pk_mul_f32 v[78:79], v[78:79], v[134:135]
	v_pk_mul_f32 v[74:75], v[74:75], v[130:131]
	v_cvt_pk_bf16_f32 v64, v76, v77
	v_pk_mul_f32 v[72:73], v[72:73], v[128:129]
	v_pk_mul_f32 v[92:93], v[92:93], v[140:141]
	v_cvt_pk_bf16_f32 v65, v78, v79
	v_cvt_pk_bf16_f32 v66, v72, v73
	v_cvt_pk_bf16_f32 v67, v74, v75
	global_store_dwordx4 v[180:181], v[64:67], off offset:3840 sc1
	v_pk_mul_f32 v[94:95], v[94:95], v[142:143]
	v_pk_mul_f32 v[82:83], v[82:83], v[138:139]
	v_cvt_pk_bf16_f32 v64, v92, v93
	v_pk_mul_f32 v[80:81], v[80:81], v[136:137]
	v_pk_mul_f32 v[68:69], v[68:69], v[132:133]
	v_cvt_pk_bf16_f32 v65, v94, v95
	v_cvt_pk_bf16_f32 v66, v80, v81
	v_cvt_pk_bf16_f32 v67, v82, v83
	global_store_dwordx4 v[182:183], v[64:67], off offset:3584 sc1
	v_pk_mul_f32 v[70:71], v[70:71], v[134:135]
	v_pk_mul_f32 v[62:63], v[62:63], v[142:143]
	v_cvt_pk_bf16_f32 v64, v68, v69
	v_cvt_pk_bf16_f32 v65, v70, v71
	v_cvt_pk_bf16_f32 v66, v186, v187
	v_cvt_pk_bf16_f32 v67, v184, v185
	global_store_dwordx4 v[182:183], v[64:67], off offset:3840 sc1
	v_pk_mul_f32 v[60:61], v[60:61], v[140:141]
	v_pk_mul_f32 v[52:53], v[52:53], v[132:133]
	v_add_u32_e32 v64, 0x80, v188
	v_mad_i64_i32 v[64:65], s[6:7], v64, s64, v[162:163]
	v_lshl_add_u64 v[64:65], v[64:65], 0, v[164:165]
	v_pk_mul_f32 v[66:67], v[58:59], v[138:139]
	v_pk_mul_f32 v[58:59], v[56:57], v[136:137]
	v_cvt_pk_bf16_f32 v56, v60, v61
	v_cvt_pk_bf16_f32 v57, v62, v63
	v_pk_mul_f32 v[54:55], v[54:55], v[134:135]
	v_cvt_pk_bf16_f32 v58, v58, v59
	v_cvt_pk_bf16_f32 v59, v66, v67
	global_store_dwordx4 v[64:65], v[56:59], off offset:3584 sc1
	v_pk_mul_f32 v[48:49], v[48:49], v[140:141]
	v_pk_mul_f32 v[36:37], v[36:37], v[132:133]
	v_pk_mul_f32 v[56:57], v[46:47], v[130:131]
	v_pk_mul_f32 v[46:47], v[44:45], v[128:129]
	v_cvt_pk_bf16_f32 v44, v52, v53
	v_cvt_pk_bf16_f32 v45, v54, v55
	v_pk_mul_f32 v[38:39], v[38:39], v[134:135]
	v_cvt_pk_bf16_f32 v46, v46, v47
	v_cvt_pk_bf16_f32 v47, v56, v57
	global_store_dwordx4 v[64:65], v[44:47], off offset:3840 sc1
	v_pk_mul_f32 v[32:33], v[32:33], v[140:141]
	v_pk_mul_f32 v[20:21], v[20:21], v[132:133]
	v_add_u32_e32 v44, 0x90, v188
	v_mad_i64_i32 v[44:45], s[6:7], v44, s64, v[162:163]
	v_lshl_add_u64 v[44:45], v[44:45], 0, v[164:165]
	v_pk_mul_f32 v[46:47], v[50:51], v[142:143]
	v_pk_mul_f32 v[50:51], v[42:43], v[138:139]
	v_pk_mul_f32 v[42:43], v[40:41], v[136:137]
	v_cvt_pk_bf16_f32 v40, v48, v49
	v_cvt_pk_bf16_f32 v41, v46, v47
	v_pk_mul_f32 v[22:23], v[22:23], v[134:135]
	v_cvt_pk_bf16_f32 v42, v42, v43
	v_cvt_pk_bf16_f32 v43, v50, v51
	global_store_dwordx4 v[44:45], v[40:43], off offset:3584 sc1
	v_pk_mul_f32 v[16:17], v[16:17], v[140:141]
	v_pk_mul_f32 v[6:7], v[6:7], v[134:135]
	v_pk_mul_f32 v[40:41], v[30:31], v[130:131]
	v_pk_mul_f32 v[30:31], v[28:29], v[128:129]
	v_cvt_pk_bf16_f32 v28, v36, v37
	v_cvt_pk_bf16_f32 v29, v38, v39
	v_pk_mul_f32 v[4:5], v[4:5], v[132:133]
	v_cvt_pk_bf16_f32 v30, v30, v31
	v_cvt_pk_bf16_f32 v31, v40, v41
	global_store_dwordx4 v[44:45], v[28:31], off offset:3840 sc1
	s_nop 1
	v_add_u32_e32 v28, 0xa0, v188
	v_mad_i64_i32 v[28:29], s[6:7], v28, s64, v[162:163]
	v_lshl_add_u64 v[28:29], v[28:29], 0, v[164:165]
	v_pk_mul_f32 v[30:31], v[34:35], v[142:143]
	v_pk_mul_f32 v[34:35], v[26:27], v[138:139]
	v_pk_mul_f32 v[26:27], v[24:25], v[136:137]
	v_cvt_pk_bf16_f32 v24, v32, v33
	v_cvt_pk_bf16_f32 v25, v30, v31
	s_nop 0
	v_cvt_pk_bf16_f32 v26, v26, v27
	v_cvt_pk_bf16_f32 v27, v34, v35
	global_store_dwordx4 v[28:29], v[24:27], off offset:3584 sc1
	s_nop 1
	v_pk_mul_f32 v[24:25], v[14:15], v[130:131]
	v_pk_mul_f32 v[14:15], v[12:13], v[128:129]
	v_cvt_pk_bf16_f32 v12, v20, v21
	v_cvt_pk_bf16_f32 v13, v22, v23
	s_nop 0
	v_cvt_pk_bf16_f32 v14, v14, v15
	v_cvt_pk_bf16_f32 v15, v24, v25
	global_store_dwordx4 v[28:29], v[12:15], off offset:3840 sc1
	s_nop 1
	v_add_u32_e32 v12, 0xb0, v188
	v_mad_i64_i32 v[12:13], s[6:7], v12, s64, v[162:163]
	v_lshl_add_u64 v[12:13], v[12:13], 0, v[164:165]
	v_pk_mul_f32 v[14:15], v[18:19], v[142:143]
	v_pk_mul_f32 v[18:19], v[10:11], v[138:139]
	v_pk_mul_f32 v[10:11], v[8:9], v[136:137]
	v_cvt_pk_bf16_f32 v8, v16, v17
	v_cvt_pk_bf16_f32 v9, v14, v15
	s_mov_b32 s6, s20
	v_cvt_pk_bf16_f32 v10, v10, v11
	v_cvt_pk_bf16_f32 v11, v18, v19
	global_store_dwordx4 v[12:13], v[8:11], off offset:3584 sc1
	s_nop 1
	v_pk_mul_f32 v[8:9], v[2:3], v[130:131]
	v_pk_mul_f32 v[2:3], v[0:1], v[128:129]
	v_cvt_pk_bf16_f32 v0, v4, v5
	v_cvt_pk_bf16_f32 v1, v6, v7
	s_nop 0
	v_cvt_pk_bf16_f32 v2, v2, v3
	v_cvt_pk_bf16_f32 v3, v8, v9
	global_store_dwordx4 v[12:13], v[0:3], off offset:3840 sc1
	s_cbranch_vccz .LBB0_341
	s_waitcnt vmcnt(0)
	s_cmpk_gt_u32 s39, 0xff
	s_cbranch_scc1 .LBB0_348
	s_barrier

; __device__ void phase_scan(int l, unsigned char* lds) {
;     ...
;             if (jb.last) *(f32x4*)(out + (jb.is_s ? OUT_SWKV : OUT_PWKV) + sidx) = (f32x4){s01.x, s01.y, s23.x, s23.y};
.LBB0_542:
	s_ashr_i32 s19, s18, 31
	s_and_b64 s[8:9], s[66:67], exec
	s_cselect_b32 s7, s82, 0x4fd4000
	s_add_u32 s7, s62, s7
	s_addc_u32 s20, s63, 0
	s_lshl_b64 s[8:9], s[18:19], 17
	v_lshl_add_u64 v[20:21], v[20:21], 0, s[64:65]
	s_add_u32 s8, s7, s8
	s_addc_u32 s9, s20, s9
	v_lshlrev_b64 v[20:21], 8, v[20:21]
	v_lshl_add_u64 v[20:21], s[8:9], 0, v[20:21]
	v_mov_b32_e32 v91, v19
	v_lshl_add_u64 v[20:21], v[20:21], 0, v[90:91]
	global_store_dwordx4 v[20:21], v[22:25], off sc1
	s_branch .LBB0_474

; #define PG8_STAGE(bufoff, gbase, voff) do { _Pragma("unroll") for (int _i = 0; _i < 2; ++_i) \
;         __builtin_amdgcn_global_load_lds((const unsigned*)((const char*)(gbase) + (voff)[_i]), (LAS unsigned*)(lds + (bufoff) + ldsw + _i * 8192), 16, 0, 0); } while (0)
; #define PG8_LDA(dst, b, h) do { _Pragma("unroll") for (int m = 0; m < 4; ++m) _Pragma("unroll") for (int k = 0; k < 2; ++k) dst[m][k] = *(const LAS bf16x8*)(lds + PG8_SA(b, h) + aoff + m * 2048 + k * 1024); } while (0)
; #define PG8_LDB(dst, b, h) do { _Pragma("unroll") for (int n = 0; n < 2; ++n) _Pragma("unroll") for (int k = 0; k < 2; ++k) dst[n][k] = *(const LAS bf16x8*)(lds + PG8_SB(b, h) + boff + n * 2048 + k * 1024); } while (0)
; #define PG8_MMA(ai, bj, At, Bt) do { __builtin_amdgcn_s_setprio(1); _Pragma("unroll") for (int m = 0; m < 4; ++m) _Pragma("unroll") for (int n = 0; n < 2; ++n) _Pragma("unroll") for (int k = 0; k < 2; ++k) \
;         acc[ai][bj][m][n] = __builtin_amdgcn_mfma_f32_16x16x32_bf16(Bt[n][k], At[m][k], acc[ai][bj][m][n], 0, 0, 0); __builtin_amdgcn_s_setprio(0); } while (0)
; #define PG8_WAIT_V(n) asm volatile("s_waitcnt vmcnt(" #n ")" ::: "memory")
;     ...
;             PG8_LDB(B0, 0, 0); PG8_SCHED; PG8_LDA(At, 0, 0); PG8_STAGE(PG8_SA(1, 1), a1 + hA, voffA);
;             PG8_WAIT_L(8); PG8_BAR; PG8_WAIT_L(0); PG8_MMA(0, 0, At, B0); PG8_BAR; PG8_SCHED;
;             PG8_LDB(B1, 0, 1); PG8_STAGE(PG8_SB(0, 0), b2, voffB);
;             PG8_BAR; PG8_WAIT_L(0); PG8_MMA(0, 1, At, B1); PG8_BAR;
;             PG8_LDA(At, 0, 1); PG8_STAGE(PG8_SA(0, 0), a2, voffA);
;             PG8_BAR; PG8_WAIT_L(0); PG8_MMA(1, 0, At, B0); PG8_BAR; PG8_SCHED;
;             PG8_STAGE(PG8_SB(0, 1), b2 + hB, voffB);
;             PG8_WAIT_V(6); PG8_BAR; PG8_MMA(1, 1, At, B1); PG8_BAR;
;             PG8_LDB(B0, 1, 0); PG8_SCHED; PG8_LDA(At, 1, 0); PG8_STAGE(PG8_SA(0, 1), a2 + hA, voffA);
;             PG8_WAIT_L(8); PG8_BAR; PG8_WAIT_L(0); PG8_MMA(0, 0, At, B0); PG8_BAR; PG8_SCHED;
;             PG8_LDB(B1, 1, 1); PG8_STAGE(PG8_SB(1, 0), b3, voffB);
;             PG8_BAR; PG8_WAIT_L(0); PG8_MMA(0, 1, At, B1); PG8_BAR;
;             PG8_LDA(At, 1, 1); PG8_STAGE(PG8_SA(1, 0), a3, voffA);
;             PG8_BAR; PG8_WAIT_L(0); PG8_MMA(1, 0, At, B0); PG8_BAR; PG8_SCHED;
;             PG8_STAGE(PG8_SB(1, 1), b3 + hB, voffB);
;             PG8_WAIT_V(6); PG8_BAR; PG8_MMA(1, 1, At, B1); PG8_BAR;
.LBB0_627:
	ds_read_b128 v[146:149], v157
	ds_read_b128 v[150:153], v157 offset:1024
	ds_read_b128 v[160:163], v157 offset:2048
	ds_read_b128 v[170:173], v157 offset:3072
	s_add_u32 s12, s14, 0x100
	s_addc_u32 s13, s15, 0
	s_cmp_eq_u32 s42, 4
	s_cselect_b32 s19, s31, s13
	s_cselect_b32 s18, s30, s12
	s_cselect_b32 s17, s8, s33
	s_cselect_b32 s16, s9, s29
	v_lshl_add_u64 v[164:165], s[14:15], 0, v[138:139]
	s_add_i32 m0, s39, 0xc000
	ds_read_b128 v[174:177], v158
	ds_read_b128 v[178:181], v158 offset:1024
	ds_read_b128 v[182:185], v158 offset:2048
	ds_read_b128 v[186:189], v158 offset:3072
	ds_read_b128 v[190:193], v158 offset:4096
	ds_read_b128 v[194:197], v158 offset:5120
	ds_read_b128 v[198:201], v158 offset:6144
	ds_read_b128 v[202:205], v158 offset:7168
	global_load_lds_dwordx4 v[164:165], off
	v_lshl_add_u64 v[164:165], s[14:15], 0, v[136:137]
	s_add_i32 m0, s39, 0xe000
	s_nop 0
	global_load_lds_dwordx4 v[164:165], off
	s_waitcnt lgkmcnt(8)
	s_barrier
	s_waitcnt lgkmcnt(0)
	s_setprio 1
	s_waitcnt lgkmcnt(0)
	v_mfma_f32_16x16x32_bf16 v[124:127], v[146:149], v[174:177], v[124:127]
	v_mfma_f32_16x16x32_bf16 v[120:123], v[160:163], v[174:177], v[120:123]
	v_mfma_f32_16x16x32_bf16 v[108:111], v[146:149], v[182:185], v[108:111]
	v_mfma_f32_16x16x32_bf16 v[104:107], v[160:163], v[182:185], v[104:107]
	v_mfma_f32_16x16x32_bf16 v[92:95], v[146:149], v[190:193], v[92:95]
	v_mfma_f32_16x16x32_bf16 v[88:91], v[160:163], v[190:193], v[88:91]
	v_mfma_f32_16x16x32_bf16 v[76:79], v[146:149], v[198:201], v[76:79]
	v_mfma_f32_16x16x32_bf16 v[72:75], v[160:163], v[198:201], v[72:75]
	v_mfma_f32_16x16x32_bf16 v[124:127], v[150:153], v[178:181], v[124:127]
	v_mfma_f32_16x16x32_bf16 v[120:123], v[170:173], v[178:181], v[120:123]
	v_mfma_f32_16x16x32_bf16 v[108:111], v[150:153], v[186:189], v[108:111]
	v_mfma_f32_16x16x32_bf16 v[104:107], v[170:173], v[186:189], v[104:107]
	v_mfma_f32_16x16x32_bf16 v[92:95], v[150:153], v[194:197], v[92:95]
	v_mfma_f32_16x16x32_bf16 v[88:91], v[170:173], v[194:197], v[88:91]
	v_mfma_f32_16x16x32_bf16 v[76:79], v[150:153], v[202:205], v[76:79]
	v_mfma_f32_16x16x32_bf16 v[72:75], v[170:173], v[202:205], v[72:75]
	s_setprio 0
	s_barrier
	s_add_i32 s14, s59, s37
	v_lshl_add_u64 v[164:165], s[16:17], 0, v[132:133]
	s_mov_b32 m0, s14
	ds_read_b128 v[206:209], v159
	ds_read_b128 v[210:213], v159 offset:1024
	ds_read_b128 v[214:217], v159 offset:2048
	ds_read_b128 v[218:221], v159 offset:3072
	global_load_lds_dwordx4 v[164:165], off
	v_lshl_add_u64 v[222:223], s[16:17], 0, v[128:129]
	s_add_i32 m0, s14, 0x2000
	s_nop 0
	global_load_lds_dwordx4 v[222:223], off
	s_barrier
	s_waitcnt lgkmcnt(0)
	s_setprio 1
	s_waitcnt lgkmcnt(0)
	v_mfma_f32_16x16x32_bf16 v[116:119], v[206:209], v[174:177], v[116:119]
	v_mfma_f32_16x16x32_bf16 v[112:115], v[214:217], v[174:177], v[112:115]
	v_mfma_f32_16x16x32_bf16 v[100:103], v[206:209], v[182:185], v[100:103]
	v_mfma_f32_16x16x32_bf16 v[96:99], v[214:217], v[182:185], v[96:99]
	v_mfma_f32_16x16x32_bf16 v[84:87], v[206:209], v[190:193], v[84:87]
	v_mfma_f32_16x16x32_bf16 v[80:83], v[214:217], v[190:193], v[80:83]
	v_mfma_f32_16x16x32_bf16 v[68:71], v[206:209], v[198:201], v[68:71]
	v_mfma_f32_16x16x32_bf16 v[64:67], v[214:217], v[198:201], v[64:67]
	v_mfma_f32_16x16x32_bf16 v[116:119], v[210:213], v[178:181], v[116:119]
	v_mfma_f32_16x16x32_bf16 v[112:115], v[218:221], v[178:181], v[112:115]
	v_mfma_f32_16x16x32_bf16 v[100:103], v[210:213], v[186:189], v[100:103]
	v_mfma_f32_16x16x32_bf16 v[96:99], v[218:221], v[186:189], v[96:99]
	v_mfma_f32_16x16x32_bf16 v[84:87], v[210:213], v[194:197], v[84:87]
	v_mfma_f32_16x16x32_bf16 v[80:83], v[218:221], v[194:197], v[80:83]
	v_mfma_f32_16x16x32_bf16 v[68:71], v[210:213], v[202:205], v[68:71]
	v_mfma_f32_16x16x32_bf16 v[64:67], v[218:221], v[202:205], v[64:67]
	s_setprio 0
	s_mov_b32 m0, s39
	v_lshl_add_u64 v[224:225], s[18:19], 0, v[134:135]
	s_barrier
	ds_read_b128 v[174:177], v158 offset:16384
	ds_read_b128 v[178:181], v158 offset:17408
	ds_read_b128 v[182:185], v158 offset:18432
	ds_read_b128 v[186:189], v158 offset:19456
	ds_read_b128 v[190:193], v158 offset:20480
	ds_read_b128 v[194:197], v158 offset:21504
	ds_read_b128 v[198:201], v158 offset:22528
	ds_read_b128 v[202:205], v158 offset:23552
	global_load_lds_dwordx4 v[224:225], off
	v_lshl_add_u64 v[226:227], s[18:19], 0, v[130:131]
	s_mov_b32 m0, s51
	s_nop 0
	global_load_lds_dwordx4 v[226:227], off
	s_barrier
	s_waitcnt lgkmcnt(0)
	s_setprio 1
	s_waitcnt lgkmcnt(0)
	v_mfma_f32_16x16x32_bf16 v[60:63], v[146:149], v[174:177], v[60:63]
	v_mfma_f32_16x16x32_bf16 v[56:59], v[160:163], v[174:177], v[56:59]
	v_mfma_f32_16x16x32_bf16 v[44:47], v[146:149], v[182:185], v[44:47]
	v_mfma_f32_16x16x32_bf16 v[40:43], v[160:163], v[182:185], v[40:43]
	v_mfma_f32_16x16x32_bf16 v[28:31], v[146:149], v[190:193], v[28:31]
	v_mfma_f32_16x16x32_bf16 v[24:27], v[160:163], v[190:193], v[24:27]
	v_mfma_f32_16x16x32_bf16 v[12:15], v[146:149], v[198:201], v[12:15]
	v_mfma_f32_16x16x32_bf16 v[8:11], v[160:163], v[198:201], v[8:11]
	v_mfma_f32_16x16x32_bf16 v[60:63], v[150:153], v[178:181], v[60:63]
	v_mfma_f32_16x16x32_bf16 v[56:59], v[170:173], v[178:181], v[56:59]
	v_mfma_f32_16x16x32_bf16 v[44:47], v[150:153], v[186:189], v[44:47]
	v_mfma_f32_16x16x32_bf16 v[40:43], v[170:173], v[186:189], v[40:43]
	v_mfma_f32_16x16x32_bf16 v[28:31], v[150:153], v[194:197], v[28:31]
	v_mfma_f32_16x16x32_bf16 v[24:27], v[170:173], v[194:197], v[24:27]
	v_mfma_f32_16x16x32_bf16 v[12:15], v[150:153], v[202:205], v[12:15]
	v_mfma_f32_16x16x32_bf16 v[8:11], v[170:173], v[202:205], v[8:11]
	s_setprio 0
	s_barrier
; #define PG8_STAGE(bufoff, gbase, voff) do { _Pragma("unroll") for (int _i = 0; _i < 2; ++_i) \
;         __builtin_amdgcn_global_load_lds((const unsigned*)((const char*)(gbase) + (voff)[_i]), (LAS unsigned*)(lds + (bufoff) + ldsw + _i * 8192), 16, 0, 0); } while (0)
; #define PG8_LDA(dst, b, h) do { _Pragma("unroll") for (int m = 0; m < 4; ++m) _Pragma("unroll") for (int k = 0; k < 2; ++k) dst[m][k] = *(const LAS bf16x8*)(lds + PG8_SA(b, h) + aoff + m * 2048 + k * 1024); } while (0)
; #define PG8_LDB(dst, b, h) do { _Pragma("unroll") for (int n = 0; n < 2; ++n) _Pragma("unroll") for (int k = 0; k < 2; ++k) dst[n][k] = *(const LAS bf16x8*)(lds + PG8_SB(b, h) + boff + n * 2048 + k * 1024); } while (0)
; #define PG8_MMA(ai, bj, At, Bt) do { __builtin_amdgcn_s_setprio(1); _Pragma("unroll") for (int m = 0; m < 4; ++m) _Pragma("unroll") for (int n = 0; n < 2; ++n) _Pragma("unroll") for (int k = 0; k < 2; ++k) \
;         acc[ai][bj][m][n] = __builtin_amdgcn_mfma_f32_16x16x32_bf16(Bt[n][k], At[m][k], acc[ai][bj][m][n], 0, 0, 0); __builtin_amdgcn_s_setprio(0); } while (0)
; #define PG8_WAIT_V(n) asm volatile("s_waitcnt vmcnt(" #n ")" ::: "memory")
;     ...
;             PG8_LDB(B0, 0, 0); PG8_SCHED; PG8_LDA(At, 0, 0); PG8_STAGE(PG8_SA(1, 1), a1 + hA, voffA);
;             PG8_WAIT_L(8); PG8_BAR; PG8_WAIT_L(0); PG8_MMA(0, 0, At, B0); PG8_BAR; PG8_SCHED;
;             PG8_LDB(B1, 0, 1); PG8_STAGE(PG8_SB(0, 0), b2, voffB);
;             PG8_BAR; PG8_WAIT_L(0); PG8_MMA(0, 1, At, B1); PG8_BAR;
;             PG8_LDA(At, 0, 1); PG8_STAGE(PG8_SA(0, 0), a2, voffA);
;             PG8_BAR; PG8_WAIT_L(0); PG8_MMA(1, 0, At, B0); PG8_BAR; PG8_SCHED;
;             PG8_STAGE(PG8_SB(0, 1), b2 + hB, voffB);
;             PG8_WAIT_V(6); PG8_BAR; PG8_MMA(1, 1, At, B1); PG8_BAR;
;             PG8_LDB(B0, 1, 0); PG8_SCHED; PG8_LDA(At, 1, 0); PG8_STAGE(PG8_SA(0, 1), a2 + hA, voffA);
;             PG8_WAIT_L(8); PG8_BAR; PG8_WAIT_L(0); PG8_MMA(0, 0, At, B0); PG8_BAR; PG8_SCHED;
;             PG8_LDB(B1, 1, 1); PG8_STAGE(PG8_SB(1, 0), b3, voffB);
;             PG8_BAR; PG8_WAIT_L(0); PG8_MMA(0, 1, At, B1); PG8_BAR;
;             PG8_LDA(At, 1, 1); PG8_STAGE(PG8_SA(1, 0), a3, voffA);
;             PG8_BAR; PG8_WAIT_L(0); PG8_MMA(1, 0, At, B0); PG8_BAR; PG8_SCHED;
;             PG8_STAGE(PG8_SB(1, 1), b3 + hB, voffB);
;             PG8_WAIT_V(6); PG8_BAR; PG8_MMA(1, 1, At, B1); PG8_BAR;
	s_add_u32 s14, s16, 0x20000
	s_addc_u32 s15, s17, 0
	s_add_i32 s43, s60, s37
	v_lshl_add_u64 v[146:147], s[14:15], 0, v[132:133]
	s_mov_b32 m0, s43
	s_nop 0
	global_load_lds_dwordx4 v[146:147], off
	v_lshl_add_u64 v[146:147], s[14:15], 0, v[128:129]
	s_add_i32 m0, s43, 0x2000
	s_nop 0
	global_load_lds_dwordx4 v[146:147], off
	s_waitcnt vmcnt(6)
	s_barrier
	s_setprio 1
	v_mfma_f32_16x16x32_bf16 v[52:55], v[206:209], v[174:177], v[52:55]
	v_mfma_f32_16x16x32_bf16 v[48:51], v[214:217], v[174:177], v[48:51]
	v_mfma_f32_16x16x32_bf16 v[36:39], v[206:209], v[182:185], v[36:39]
	v_mfma_f32_16x16x32_bf16 v[32:35], v[214:217], v[182:185], v[32:35]
	v_mfma_f32_16x16x32_bf16 v[20:23], v[206:209], v[190:193], v[20:23]
	v_mfma_f32_16x16x32_bf16 v[16:19], v[214:217], v[190:193], v[16:19]
	v_mfma_f32_16x16x32_bf16 v[4:7], v[206:209], v[198:201], v[4:7]
	v_mfma_f32_16x16x32_bf16 v[0:3], v[214:217], v[198:201], v[0:3]
	v_mfma_f32_16x16x32_bf16 v[52:55], v[210:213], v[178:181], v[52:55]
	v_mfma_f32_16x16x32_bf16 v[48:51], v[218:221], v[178:181], v[48:51]
	v_mfma_f32_16x16x32_bf16 v[36:39], v[210:213], v[186:189], v[36:39]
	v_mfma_f32_16x16x32_bf16 v[32:35], v[218:221], v[186:189], v[32:35]
	v_mfma_f32_16x16x32_bf16 v[20:23], v[210:213], v[194:197], v[20:23]
	v_mfma_f32_16x16x32_bf16 v[16:19], v[218:221], v[194:197], v[16:19]
	v_mfma_f32_16x16x32_bf16 v[4:7], v[210:213], v[202:205], v[4:7]
	v_mfma_f32_16x16x32_bf16 v[0:3], v[218:221], v[202:205], v[0:3]
	s_setprio 0
	s_add_i32 s43, 0, 0x18000
	v_add_u32_e32 v170, s43, v155
	s_barrier
	ds_read_b128 v[146:149], v170
	ds_read_b128 v[150:153], v170 offset:1024
	ds_read_b128 v[160:163], v170 offset:2048
	ds_read_b128 v[170:173], v170 offset:3072
	s_add_u32 s14, s18, 0x110000
	s_addc_u32 s15, s19, 0
	s_mov_b32 m0, s53
	v_lshl_add_u64 v[206:207], s[14:15], 0, v[134:135]
	ds_read_b128 v[174:177], v158 offset:32768
	ds_read_b128 v[178:181], v158 offset:33792
	ds_read_b128 v[182:185], v158 offset:34816
	ds_read_b128 v[186:189], v158 offset:35840
	ds_read_b128 v[190:193], v158 offset:36864
	ds_read_b128 v[194:197], v158 offset:37888
	ds_read_b128 v[198:201], v158 offset:38912
	ds_read_b128 v[202:205], v158 offset:39936
	global_load_lds_dwordx4 v[206:207], off
	v_lshl_add_u64 v[206:207], s[14:15], 0, v[130:131]
	s_mov_b32 m0, s54
	s_nop 0
	global_load_lds_dwordx4 v[206:207], off
	s_waitcnt lgkmcnt(8)
	s_barrier
	s_waitcnt lgkmcnt(0)
	s_setprio 1
	s_waitcnt lgkmcnt(0)
	v_mfma_f32_16x16x32_bf16 v[124:127], v[146:149], v[174:177], v[124:127]
	v_mfma_f32_16x16x32_bf16 v[120:123], v[160:163], v[174:177], v[120:123]
	v_mfma_f32_16x16x32_bf16 v[108:111], v[146:149], v[182:185], v[108:111]
	v_mfma_f32_16x16x32_bf16 v[104:107], v[160:163], v[182:185], v[104:107]
	v_mfma_f32_16x16x32_bf16 v[92:95], v[146:149], v[190:193], v[92:95]
	v_mfma_f32_16x16x32_bf16 v[88:91], v[160:163], v[190:193], v[88:91]
	v_mfma_f32_16x16x32_bf16 v[76:79], v[146:149], v[198:201], v[76:79]
	v_mfma_f32_16x16x32_bf16 v[72:75], v[160:163], v[198:201], v[72:75]
	v_mfma_f32_16x16x32_bf16 v[124:127], v[150:153], v[178:181], v[124:127]
	v_mfma_f32_16x16x32_bf16 v[120:123], v[170:173], v[178:181], v[120:123]
	v_mfma_f32_16x16x32_bf16 v[108:111], v[150:153], v[186:189], v[108:111]
	v_mfma_f32_16x16x32_bf16 v[104:107], v[170:173], v[186:189], v[104:107]
	v_mfma_f32_16x16x32_bf16 v[92:95], v[150:153], v[194:197], v[92:95]
	v_mfma_f32_16x16x32_bf16 v[88:91], v[170:173], v[194:197], v[88:91]
	v_mfma_f32_16x16x32_bf16 v[76:79], v[150:153], v[202:205], v[76:79]
	v_mfma_f32_16x16x32_bf16 v[72:75], v[170:173], v[202:205], v[72:75]
	s_setprio 0
	s_barrier
	s_add_i32 s18, 0, 0x1c000
	s_add_i32 s14, s43, s37
	v_add_u32_e32 v218, s18, v155
	v_lshl_add_u64 v[164:165], v[164:165], 0, s[26:27]
	s_mov_b32 m0, s14
	ds_read_b128 v[206:209], v218
	ds_read_b128 v[210:213], v218 offset:1024
	ds_read_b128 v[214:217], v218 offset:2048
	ds_read_b128 v[218:221], v218 offset:3072
	global_load_lds_dwordx4 v[164:165], off
	v_lshl_add_u64 v[164:165], v[222:223], 0, s[26:27]
	s_add_i32 m0, s14, 0x2000
	s_nop 0
	global_load_lds_dwordx4 v[164:165], off
	s_barrier
	s_waitcnt lgkmcnt(0)
	s_setprio 1
	s_waitcnt lgkmcnt(0)
	v_mfma_f32_16x16x32_bf16 v[116:119], v[206:209], v[174:177], v[116:119]
	v_mfma_f32_16x16x32_bf16 v[112:115], v[214:217], v[174:177], v[112:115]
	v_mfma_f32_16x16x32_bf16 v[100:103], v[206:209], v[182:185], v[100:103]
	v_mfma_f32_16x16x32_bf16 v[96:99], v[214:217], v[182:185], v[96:99]
	v_mfma_f32_16x16x32_bf16 v[84:87], v[206:209], v[190:193], v[84:87]
	v_mfma_f32_16x16x32_bf16 v[80:83], v[214:217], v[190:193], v[80:83]
	v_mfma_f32_16x16x32_bf16 v[68:71], v[206:209], v[198:201], v[68:71]
	v_mfma_f32_16x16x32_bf16 v[64:67], v[214:217], v[198:201], v[64:67]
	v_mfma_f32_16x16x32_bf16 v[116:119], v[210:213], v[178:181], v[116:119]
	v_mfma_f32_16x16x32_bf16 v[112:115], v[218:221], v[178:181], v[112:115]
	v_mfma_f32_16x16x32_bf16 v[100:103], v[210:213], v[186:189], v[100:103]
	v_mfma_f32_16x16x32_bf16 v[96:99], v[218:221], v[186:189], v[96:99]
	v_mfma_f32_16x16x32_bf16 v[84:87], v[210:213], v[194:197], v[84:87]
	v_mfma_f32_16x16x32_bf16 v[80:83], v[218:221], v[194:197], v[80:83]
	v_mfma_f32_16x16x32_bf16 v[68:71], v[210:213], v[202:205], v[68:71]
	v_mfma_f32_16x16x32_bf16 v[64:67], v[218:221], v[202:205], v[64:67]
	s_setprio 0
	s_mov_b32 m0, s56
	v_lshl_add_u64 v[164:165], v[224:225], 0, s[26:27]
	s_barrier
	ds_read_b128 v[174:177], v158 offset:49152
	ds_read_b128 v[178:181], v158 offset:50176
	ds_read_b128 v[182:185], v158 offset:51200
	ds_read_b128 v[186:189], v158 offset:52224
	ds_read_b128 v[190:193], v158 offset:53248
	ds_read_b128 v[194:197], v158 offset:54272
	ds_read_b128 v[198:201], v158 offset:55296
	ds_read_b128 v[202:205], v158 offset:56320
	global_load_lds_dwordx4 v[164:165], off
	v_lshl_add_u64 v[164:165], v[226:227], 0, s[26:27]
	s_mov_b32 m0, s57
	s_nop 0
	global_load_lds_dwordx4 v[164:165], off
	s_barrier
; __device__ __forceinline__ float sigmoidf_(float x) { return 1.0f / (1.0f + __expf(-x)); }
; #define PG8_STAGE(bufoff, gbase, voff) do { _Pragma("unroll") for (int _i = 0; _i < 2; ++_i) \
;         __builtin_amdgcn_global_load_lds((const unsigned*)((const char*)(gbase) + (voff)[_i]), (LAS unsigned*)(lds + (bufoff) + ldsw + _i * 8192), 16, 0, 0); } while (0)
; #define PG8_WAIT_V(n) asm volatile("s_waitcnt vmcnt(" #n ")" ::: "memory")
; #define PG8_WAIT_L(n) asm volatile("s_waitcnt lgkmcnt(" #n ")" ::: "memory")
;     ...
;             PG8_LDB(B0, 0, 0); PG8_SCHED; PG8_LDA(At, 0, 0); PG8_STAGE(PG8_SA(1, 1), a1 + hA, voffA);
;             PG8_WAIT_L(8); PG8_BAR; PG8_WAIT_L(0); PG8_MMA(0, 0, At, B0); PG8_BAR; PG8_SCHED;
;             PG8_LDB(B1, 0, 1); PG8_STAGE(PG8_SB(0, 0), b2, voffB);
;             PG8_BAR; PG8_WAIT_L(0); PG8_MMA(0, 1, At, B1); PG8_BAR;
;             PG8_LDA(At, 0, 1); PG8_STAGE(PG8_SA(0, 0), a2, voffA);
;             PG8_BAR; PG8_WAIT_L(0); PG8_MMA(1, 0, At, B0); PG8_BAR; PG8_SCHED;
;             PG8_STAGE(PG8_SB(0, 1), b2 + hB, voffB);
;             PG8_WAIT_V(6); PG8_BAR; PG8_MMA(1, 1, At, B1); PG8_BAR;
;             PG8_LDB(B0, 1, 0); PG8_SCHED; PG8_LDA(At, 1, 0); PG8_STAGE(PG8_SA(0, 1), a2 + hA, voffA);
;             PG8_WAIT_L(8); PG8_BAR; PG8_WAIT_L(0); PG8_MMA(0, 0, At, B0); PG8_BAR; PG8_SCHED;
;             PG8_LDB(B1, 1, 1); PG8_STAGE(PG8_SB(1, 0), b3, voffB);
;             PG8_BAR; PG8_WAIT_L(0); PG8_MMA(0, 1, At, B1); PG8_BAR;
;             PG8_LDA(At, 1, 1); PG8_STAGE(PG8_SA(1, 0), a3, voffA);
;             PG8_BAR; PG8_WAIT_L(0); PG8_MMA(1, 0, At, B0); PG8_BAR; PG8_SCHED;
;             PG8_STAGE(PG8_SB(1, 1), b3 + hB, voffB);
;             PG8_WAIT_V(6); PG8_BAR; PG8_MMA(1, 1, At, B1); PG8_BAR;
;     __device__ __forceinline__ void operator()(const f32x4 (&acc)[2][2][4][2], const Unit& u, int wr, int wc, int fr, int fq) const {
;     ...
;                 bf16_t* rowp = z + (size_t)(row0 + ai * 128 + m * 16) * DIN + col0;
; #pragma unroll
;                 for (int bj = 0; bj < 2; ++bj) {
;                     const u32x4 gw = *(const u32x4*)(rowp + (MODE == 0 ? O_GB : O_GA) + bj * 128);
;                     f32x4 g0, g1; unpack8(gw, g0, g1);
;                     f32x4 v0, v1;
; #pragma unroll
;                     for (int j = 0; j < 4; ++j) { v0[j] = sigmoidf_(g0[j]) * acc[ai][bj][m][0][j]; v1[j] = sigmoidf_(g1[j]) * acc[ai][bj][m][1][j]; }
	s_waitcnt lgkmcnt(0)
	s_setprio 1
	s_waitcnt lgkmcnt(0)
	v_mfma_f32_16x16x32_bf16 v[60:63], v[146:149], v[174:177], v[60:63]
	v_mfma_f32_16x16x32_bf16 v[56:59], v[160:163], v[174:177], v[56:59]
	v_mfma_f32_16x16x32_bf16 v[44:47], v[146:149], v[182:185], v[44:47]
	v_mfma_f32_16x16x32_bf16 v[40:43], v[160:163], v[182:185], v[40:43]
	v_mfma_f32_16x16x32_bf16 v[28:31], v[146:149], v[190:193], v[28:31]
	v_mfma_f32_16x16x32_bf16 v[24:27], v[160:163], v[190:193], v[24:27]
	v_mfma_f32_16x16x32_bf16 v[12:15], v[146:149], v[198:201], v[12:15]
	v_mfma_f32_16x16x32_bf16 v[8:11], v[160:163], v[198:201], v[8:11]
	v_mfma_f32_16x16x32_bf16 v[60:63], v[150:153], v[178:181], v[60:63]
	v_mfma_f32_16x16x32_bf16 v[56:59], v[170:173], v[178:181], v[56:59]
	v_mfma_f32_16x16x32_bf16 v[44:47], v[150:153], v[186:189], v[44:47]
	v_mfma_f32_16x16x32_bf16 v[40:43], v[170:173], v[186:189], v[40:43]
	v_mfma_f32_16x16x32_bf16 v[28:31], v[150:153], v[194:197], v[28:31]
	v_mfma_f32_16x16x32_bf16 v[24:27], v[170:173], v[194:197], v[24:27]
	v_mfma_f32_16x16x32_bf16 v[12:15], v[150:153], v[202:205], v[12:15]
	v_mfma_f32_16x16x32_bf16 v[8:11], v[170:173], v[202:205], v[8:11]
	s_setprio 0
	s_barrier
	s_add_u32 s14, s16, 0x20080
	s_addc_u32 s15, s17, 0
	s_add_i32 s16, s18, s37
	v_lshl_add_u64 v[146:147], s[14:15], 0, v[132:133]
	s_mov_b32 m0, s16
	s_nop 0
	global_load_lds_dwordx4 v[146:147], off
	v_lshl_add_u64 v[146:147], s[14:15], 0, v[128:129]
	s_add_i32 m0, s16, 0x2000
	s_nop 0
	global_load_lds_dwordx4 v[146:147], off
	s_waitcnt vmcnt(6)
	s_barrier
	s_setprio 1
	v_mfma_f32_16x16x32_bf16 v[52:55], v[206:209], v[174:177], v[52:55]
	v_mfma_f32_16x16x32_bf16 v[48:51], v[214:217], v[174:177], v[48:51]
	v_mfma_f32_16x16x32_bf16 v[36:39], v[206:209], v[182:185], v[36:39]
	v_mfma_f32_16x16x32_bf16 v[32:35], v[214:217], v[182:185], v[32:35]
	v_mfma_f32_16x16x32_bf16 v[20:23], v[206:209], v[190:193], v[20:23]
	v_mfma_f32_16x16x32_bf16 v[16:19], v[214:217], v[190:193], v[16:19]
	v_mfma_f32_16x16x32_bf16 v[4:7], v[206:209], v[198:201], v[4:7]
	v_mfma_f32_16x16x32_bf16 v[0:3], v[214:217], v[198:201], v[0:3]
	v_mfma_f32_16x16x32_bf16 v[52:55], v[210:213], v[178:181], v[52:55]
	v_mfma_f32_16x16x32_bf16 v[48:51], v[218:221], v[178:181], v[48:51]
	v_mfma_f32_16x16x32_bf16 v[36:39], v[210:213], v[186:189], v[36:39]
	v_mfma_f32_16x16x32_bf16 v[32:35], v[218:221], v[186:189], v[32:35]
	v_mfma_f32_16x16x32_bf16 v[20:23], v[210:213], v[194:197], v[20:23]
	v_mfma_f32_16x16x32_bf16 v[16:19], v[218:221], v[194:197], v[16:19]
	v_mfma_f32_16x16x32_bf16 v[4:7], v[210:213], v[202:205], v[4:7]
	v_mfma_f32_16x16x32_bf16 v[0:3], v[218:221], v[202:205], v[0:3]
	s_setprio 0
	s_add_i32 s42, s42, 2
	s_add_u32 s29, s29, 0x100
	s_addc_u32 s33, s33, 0
	s_cmp_gt_u32 s42, 5
	s_mov_b64 s[14:15], s[12:13]
	s_barrier
	s_cbranch_scc0 .LBB0_627
	v_lshl_or_b32 v148, s7, 8, v156
	v_lshl_add_u32 v160, s6, 8, v154
	v_ashrrev_i32_e32 v149, 31, v148
	v_mov_b64_e32 v[146:147], s[24:25]
	v_mad_i64_i32 v[150:151], s[6:7], v160, s61, v[146:147]
	v_lshlrev_b64 v[148:149], 1, v[148:149]
	v_lshl_add_u64 v[150:151], v[150:151], 0, v[148:149]
	v_add_co_u32_e32 v152, vcc, 0x1000, v150
	s_nop 1
	v_addc_co_u32_e32 v153, vcc, 0, v151, vcc
	v_subrev_u32_e32 v198, s24, v150
	v_add_u32_e32 v199, 0x1a00, v198
	global_load_dwordx4 v[200:203], v199, s[24:25]
	v_add_u32_e32 v199, 0x1b00, v198
	global_load_dwordx4 v[204:207], v199, s[24:25]
	v_add_u32_e32 v199, 0x23a00, v198
	global_load_dwordx4 v[208:211], v199, s[24:25]
	v_add_u32_e32 v199, 0x23b00, v198
	global_load_dwordx4 v[212:215], v199, s[24:25]
	v_add_u32_e32 v199, 0x45a00, v198
	global_load_dwordx4 v[216:219], v199, s[24:25]
	v_add_u32_e32 v199, 0x45b00, v198
	global_load_dwordx4 v[232:235], v199, s[24:25]
	v_add_u32_e32 v199, 0x67a00, v198
	global_load_dwordx4 v[236:239], v199, s[24:25]
	v_add_u32_e32 v199, 0x67b00, v198
	global_load_dwordx4 v[240:243], v199, s[24:25]
	v_add_u32_e32 v199, 0x111a00, v198
	global_load_dwordx4 v[244:247], v199, s[24:25]
	v_add_u32_e32 v199, 0x111b00, v198
	global_load_dwordx4 v[248:251], v199, s[24:25]
	v_add_u32_e32 v199, 0x133a00, v198
	global_load_dwordx4 v[252:255], v199, s[24:25]
	s_waitcnt vmcnt(10)
	v_mov_b32_e32 v162, v200
	v_mov_b32_e32 v163, v201
	v_mov_b32_e32 v164, v202
	v_mov_b32_e32 v165, v203
	v_add_u32_e32 v199, 0x133b00, v198
	global_load_dwordx4 v[200:203], v199, s[24:25]
	v_lshlrev_b32_e32 v161, 16, v162
	v_lshlrev_b32_e32 v171, 16, v164
	v_mul_f32_e32 v161, 0xbfb8aa3b, v161
	v_and_b32_e32 v162, 0xffff0000, v162
	v_mul_f32_e32 v171, 0xbfb8aa3b, v171
	v_exp_f32_e32 v161, v161
	v_and_b32_e32 v164, 0xffff0000, v164
	v_mul_f32_e32 v162, 0xbfb8aa3b, v162
	v_exp_f32_e32 v171, v171
	v_mul_f32_e32 v164, 0xbfb8aa3b, v164
	v_exp_f32_e32 v162, v162
	v_exp_f32_e32 v164, v164
	v_add_f32_e32 v161, 1.0, v161
	v_add_f32_e32 v171, 1.0, v171
	v_div_scale_f32 v173, s[6:7], v161, v161, 1.0
	v_add_f32_e32 v162, 1.0, v162
	v_div_scale_f32 v175, s[6:7], v171, v171, 1.0
	v_rcp_f32_e32 v183, v173
	v_lshlrev_b32_e32 v170, 16, v163
	v_add_f32_e32 v164, 1.0, v164
	v_div_scale_f32 v177, s[6:7], v162, v162, 1.0
	v_rcp_f32_e32 v184, v175
	v_mul_f32_e32 v170, 0xbfb8aa3b, v170
	v_div_scale_f32 v179, s[6:7], v164, v164, 1.0
	v_rcp_f32_e32 v185, v177
	v_exp_f32_e32 v170, v170
	v_rcp_f32_e32 v186, v179
	v_fma_f32 v188, -v173, v183, 1.0
	v_div_scale_f32 v174, vcc, 1.0, v161, 1.0
	v_fma_f32 v189, -v175, v184, 1.0
	v_fmac_f32_e32 v183, v188, v183
	v_div_scale_f32 v176, s[12:13], 1.0, v171, 1.0
	v_fma_f32 v190, -v177, v185, 1.0
	v_fmac_f32_e32 v184, v189, v184
	v_mul_f32_e32 v188, v174, v183
	v_add_f32_e32 v170, 1.0, v170
	v_div_scale_f32 v178, s[14:15], 1.0, v162, 1.0
; __device__ __forceinline__ float sigmoidf_(float x) { return 1.0f / (1.0f + __expf(-x)); }
; __device__ __forceinline__ u32x4 pack8(const f32x4 v0, const f32x4 v1) { u32x4 w; w.x = pk2(v0[0], v0[1]); w.y = pk2(v0[2], v0[3]); w.z = pk2(v1[0], v1[1]); w.w = pk2(v1[2], v1[3]); return w; }
; __device__ __forceinline__ void unpack8(const u32x4 w, f32x4& v0, f32x4& v1) { v0 = (f32x4){bflo(w.x), bfhi(w.x), bflo(w.y), bfhi(w.y)}; v1 = (f32x4){bflo(w.z), bfhi(w.z), bflo(w.w), bfhi(w.w)}; }
;     __device__ __forceinline__ void operator()(const f32x4 (&acc)[2][2][4][2], const Unit& u, int wr, int wc, int fr, int fq) const {
;     ...
;                 bf16_t* rowp = z + (size_t)(row0 + ai * 128 + m * 16) * DIN + col0;
; #pragma unroll
;                 for (int bj = 0; bj < 2; ++bj) {
;                     const u32x4 gw = *(const u32x4*)(rowp + (MODE == 0 ? O_GB : O_GA) + bj * 128);
;                     f32x4 g0, g1; unpack8(gw, g0, g1);
;                     f32x4 v0, v1;
; #pragma unroll
;                     for (int j = 0; j < 4; ++j) { v0[j] = sigmoidf_(g0[j]) * acc[ai][bj][m][0][j]; v1[j] = sigmoidf_(g1[j]) * acc[ai][bj][m][1][j]; }
;                     if (MODE == 1) { const u32x4 mw = *(const u32x4*)(rowp + bj * 128); f32x4 m0, m1; unpack8(mw, m0, m1); v0 += m0; v1 += m1; }
;                     *(u32x4*)(rowp + bj * 128) = pack8(v0, v1); }
	v_fma_f32 v191, -v179, v186, 1.0
	v_fmac_f32_e32 v185, v190, v185
	v_mul_f32_e32 v189, v176, v184
	v_fma_f32 v193, -v173, v188, v174
	v_div_scale_f32 v180, s[16:17], 1.0, v164, 1.0
	v_div_scale_f32 v181, s[6:7], v170, v170, 1.0
	v_fmac_f32_e32 v186, v191, v186
	v_mul_f32_e32 v190, v178, v185
	v_fma_f32 v194, -v175, v189, v176
	v_fmac_f32_e32 v188, v193, v183
	v_lshlrev_b32_e32 v172, 16, v165
	v_rcp_f32_e32 v187, v181
	v_mul_f32_e32 v191, v180, v186
	v_fma_f32 v195, -v177, v190, v178
	v_fmac_f32_e32 v189, v194, v184
	v_fma_f32 v173, -v173, v188, v174
	v_mul_f32_e32 v172, 0xbfb8aa3b, v172
	v_fma_f32 v196, -v179, v191, v180
	v_fmac_f32_e32 v190, v195, v185
	v_fma_f32 v174, -v175, v189, v176
	v_div_fmas_f32 v173, v173, v183, v188
	s_mov_b64 vcc, s[12:13]
	v_exp_f32_e32 v172, v172
	v_fmac_f32_e32 v191, v196, v186
	v_fma_f32 v175, -v177, v190, v178
	v_div_fixup_f32 v161, v173, v161, 1.0
	v_div_fmas_f32 v173, v174, v184, v189
	s_mov_b64 vcc, s[14:15]
	v_fma_f32 v176, -v179, v191, v180
	v_mul_f32_e32 v124, v124, v161
	v_div_fixup_f32 v161, v173, v171, 1.0
	v_div_fmas_f32 v171, v175, v185, v190
	s_mov_b64 vcc, s[16:17]
	v_fma_f32 v192, -v181, v187, 1.0
	v_mul_f32_e32 v161, v120, v161
	v_div_fixup_f32 v120, v171, v162, 1.0
	v_div_fmas_f32 v162, v176, v186, v191
	v_div_scale_f32 v182, s[18:19], 1.0, v170, 1.0
	v_fmac_f32_e32 v187, v192, v187
	v_mul_f32_e32 v120, v125, v120
	v_div_fixup_f32 v125, v162, v164, 1.0
	v_mul_f32_e32 v192, v182, v187
	v_mul_f32_e32 v125, v121, v125
	v_add_f32_e32 v121, 1.0, v172
	v_fma_f32 v197, -v181, v192, v182
	v_div_scale_f32 v162, s[6:7], v121, v121, 1.0
	v_fmac_f32_e32 v192, v197, v187
	v_rcp_f32_e32 v164, v162
	v_fma_f32 v177, -v181, v192, v182
	s_mov_b64 vcc, s[18:19]
	v_and_b32_e32 v163, 0xffff0000, v163
	v_div_fmas_f32 v171, v177, v187, v192
	v_div_fixup_f32 v170, v171, v170, 1.0
	v_mul_f32_e32 v163, 0xbfb8aa3b, v163
	v_mul_f32_e32 v126, v126, v170
	v_fma_f32 v170, -v162, v164, 1.0
	v_exp_f32_e32 v163, v163
	v_fmac_f32_e32 v164, v170, v164
	v_div_scale_f32 v170, vcc, 1.0, v121, 1.0
	v_mul_f32_e32 v171, v170, v164
	v_fma_f32 v172, -v162, v171, v170
	v_fmac_f32_e32 v171, v172, v164
	v_add_f32_e32 v163, 1.0, v163
	v_fma_f32 v162, -v162, v171, v170
	v_div_scale_f32 v170, s[6:7], v163, v163, 1.0
	v_rcp_f32_e32 v172, v170
	v_and_b32_e32 v165, 0xffff0000, v165
	v_div_fmas_f32 v162, v162, v164, v171
	v_mul_f32_e32 v164, 0xbfb8aa3b, v165
	v_div_fixup_f32 v121, v162, v121, 1.0
	v_exp_f32_e32 v164, v164
	v_mul_f32_e32 v162, v122, v121
	v_fma_f32 v121, -v170, v172, 1.0
	v_fmac_f32_e32 v172, v121, v172
	v_div_scale_f32 v121, vcc, 1.0, v163, 1.0
	v_mul_f32_e32 v122, v121, v172
	v_fma_f32 v165, -v170, v122, v121
	v_add_f32_e32 v164, 1.0, v164
	v_fmac_f32_e32 v122, v165, v172
	v_div_scale_f32 v165, s[6:7], v164, v164, 1.0
	v_fma_f32 v121, -v170, v122, v121
	v_rcp_f32_e32 v170, v165
	v_div_fmas_f32 v121, v121, v172, v122
	v_div_fixup_f32 v121, v121, v163, 1.0
	v_mul_f32_e32 v121, v127, v121
	v_fma_f32 v122, -v165, v170, 1.0
	v_fmac_f32_e32 v170, v122, v170
	v_div_scale_f32 v122, vcc, 1.0, v164, 1.0
	v_mul_f32_e32 v127, v122, v170
	v_fma_f32 v163, -v165, v127, v122
	v_fmac_f32_e32 v127, v163, v170
	v_fma_f32 v122, -v165, v127, v122
	v_div_fmas_f32 v122, v122, v170, v127
	v_div_fixup_f32 v122, v122, v164, 1.0
	v_mul_f32_e32 v123, v123, v122
	v_cvt_pk_bf16_f32 v120, v124, v120
	v_cvt_pk_bf16_f32 v121, v126, v121
	v_cvt_pk_bf16_f32 v122, v161, v125
	v_cvt_pk_bf16_f32 v123, v162, v123
	s_mov_b64 s[16:17], s[34:35]
	global_store_dwordx4 v[150:151], v[120:123], off sc1
	s_mov_b64 s[14:15], s[30:31]
	s_waitcnt vmcnt(11)
	v_mov_b32_e32 v124, v204
	v_mov_b32_e32 v125, v205
	v_mov_b32_e32 v126, v206
	v_mov_b32_e32 v127, v207
	v_add_u32_e32 v199, 0x155a00, v198
	global_load_dwordx4 v[204:207], v199, s[24:25]
	v_lshlrev_b32_e32 v120, 16, v124
	v_mul_f32_e32 v120, 0xbfb8aa3b, v120
	v_exp_f32_e32 v120, v120
	v_and_b32_e32 v121, 0xffff0000, v124
	v_lshlrev_b32_e32 v124, 16, v126
	v_mul_f32_e32 v124, 0xbfb8aa3b, v124
	v_add_f32_e32 v120, 1.0, v120
	v_exp_f32_e32 v124, v124
	v_div_scale_f32 v152, s[6:7], v120, v120, 1.0
	v_rcp_f32_e32 v162, v152
	v_add_f32_e32 v124, 1.0, v124
	v_div_scale_f32 v161, s[6:7], v124, v124, 1.0
	v_fma_f32 v165, -v152, v162, 1.0
	v_div_scale_f32 v153, vcc, 1.0, v120, 1.0
	v_rcp_f32_e32 v163, v161
	v_fmac_f32_e32 v162, v165, v162
	v_mul_f32_e32 v121, 0xbfb8aa3b, v121
	v_mul_f32_e32 v165, v153, v162
	v_exp_f32_e32 v121, v121
	v_fma_f32 v171, -v152, v165, v153
	v_fmac_f32_e32 v165, v171, v162
	v_fma_f32 v170, -v161, v163, 1.0
	v_fma_f32 v152, -v152, v165, v153
	v_div_scale_f32 v164, s[12:13], 1.0, v124, 1.0
	v_fmac_f32_e32 v163, v170, v163
	v_div_fmas_f32 v152, v152, v162, v165
	v_add_f32_e32 v121, 1.0, v121
	v_mul_f32_e32 v170, v164, v163
	v_div_fixup_f32 v120, v152, v120, 1.0
	v_fma_f32 v172, -v161, v170, v164
	v_mul_f32_e32 v116, v116, v120
	v_div_scale_f32 v120, s[6:7], v121, v121, 1.0
	v_fmac_f32_e32 v170, v172, v163
	v_rcp_f32_e32 v152, v120
	v_fma_f32 v153, -v161, v170, v164
	s_mov_b64 vcc, s[12:13]
	v_div_fmas_f32 v153, v153, v163, v170
	v_lshlrev_b32_e32 v122, 16, v125
	v_and_b32_e32 v123, 0xffff0000, v125
	v_and_b32_e32 v125, 0xffff0000, v126
	v_div_fixup_f32 v124, v153, v124, 1.0
	v_mul_f32_e32 v112, v112, v124
	v_fma_f32 v124, -v120, v152, 1.0
	v_mul_f32_e32 v125, 0xbfb8aa3b, v125
	v_fmac_f32_e32 v152, v124, v152
	v_div_scale_f32 v124, vcc, 1.0, v121, 1.0
	v_exp_f32_e32 v125, v125
	v_mul_f32_e32 v153, v124, v152
	v_fma_f32 v161, -v120, v153, v124
	v_fmac_f32_e32 v153, v161, v152
	v_fma_f32 v120, -v120, v153, v124
	v_add_f32_e32 v124, 1.0, v125
	v_div_scale_f32 v125, s[6:7], v124, v124, 1.0
	v_rcp_f32_e32 v161, v125
; __device__ __forceinline__ float sigmoidf_(float x) { return 1.0f / (1.0f + __expf(-x)); }
; __device__ __forceinline__ u32x4 pack8(const f32x4 v0, const f32x4 v1) { u32x4 w; w.x = pk2(v0[0], v0[1]); w.y = pk2(v0[2], v0[3]); w.z = pk2(v1[0], v1[1]); w.w = pk2(v1[2], v1[3]); return w; }
; __device__ __forceinline__ void unpack8(const u32x4 w, f32x4& v0, f32x4& v1) { v0 = (f32x4){bflo(w.x), bfhi(w.x), bflo(w.y), bfhi(w.y)}; v1 = (f32x4){bflo(w.z), bfhi(w.z), bflo(w.w), bfhi(w.w)}; }
;     __device__ __forceinline__ void operator()(const f32x4 (&acc)[2][2][4][2], const Unit& u, int wr, int wc, int fr, int fq) const {
;     ...
;                 bf16_t* rowp = z + (size_t)(row0 + ai * 128 + m * 16) * DIN + col0;
; #pragma unroll
;                 for (int bj = 0; bj < 2; ++bj) {
;                     const u32x4 gw = *(const u32x4*)(rowp + (MODE == 0 ? O_GB : O_GA) + bj * 128);
;                     f32x4 g0, g1; unpack8(gw, g0, g1);
;                     f32x4 v0, v1;
; #pragma unroll
;                     for (int j = 0; j < 4; ++j) { v0[j] = sigmoidf_(g0[j]) * acc[ai][bj][m][0][j]; v1[j] = sigmoidf_(g1[j]) * acc[ai][bj][m][1][j]; }
;                     if (MODE == 1) { const u32x4 mw = *(const u32x4*)(rowp + bj * 128); f32x4 m0, m1; unpack8(mw, m0, m1); v0 += m0; v1 += m1; }
;                     *(u32x4*)(rowp + bj * 128) = pack8(v0, v1); }
	v_div_fmas_f32 v120, v120, v152, v153
	v_div_fixup_f32 v120, v120, v121, 1.0
	v_mul_f32_e32 v122, 0xbfb8aa3b, v122
	v_mul_f32_e32 v117, v117, v120
	v_fma_f32 v120, -v125, v161, 1.0
	v_exp_f32_e32 v122, v122
	v_fmac_f32_e32 v161, v120, v161
	v_div_scale_f32 v120, vcc, 1.0, v124, 1.0
	v_mul_f32_e32 v121, v120, v161
	v_fma_f32 v152, -v125, v121, v120
	v_fmac_f32_e32 v121, v152, v161
	v_add_f32_e32 v122, 1.0, v122
	v_fma_f32 v120, -v125, v121, v120
	v_div_scale_f32 v125, s[6:7], v122, v122, 1.0
	v_rcp_f32_e32 v152, v125
	v_lshlrev_b32_e32 v126, 16, v127
	v_div_fmas_f32 v120, v120, v161, v121
	v_div_fixup_f32 v120, v120, v124, 1.0
	v_mul_f32_e32 v124, 0xbfb8aa3b, v126
	v_mul_f32_e32 v113, v113, v120
	v_fma_f32 v120, -v125, v152, 1.0
	v_exp_f32_e32 v124, v124
	v_fmac_f32_e32 v152, v120, v152
	v_div_scale_f32 v120, vcc, 1.0, v122, 1.0
	v_mul_f32_e32 v121, v120, v152
	v_fma_f32 v126, -v125, v121, v120
	v_fmac_f32_e32 v121, v126, v152
	v_add_f32_e32 v124, 1.0, v124
	v_fma_f32 v120, -v125, v121, v120
	v_div_scale_f32 v125, s[6:7], v124, v124, 1.0
	v_rcp_f32_e32 v126, v125
	v_div_fmas_f32 v120, v120, v152, v121
	v_div_fixup_f32 v120, v120, v122, 1.0
	v_mul_f32_e32 v122, 0xbfb8aa3b, v123
	v_exp_f32_e32 v122, v122
	v_mul_f32_e32 v118, v118, v120
	v_fma_f32 v120, -v125, v126, 1.0
	v_fmac_f32_e32 v126, v120, v126
	v_div_scale_f32 v120, vcc, 1.0, v124, 1.0
	v_mul_f32_e32 v121, v120, v126
	v_fma_f32 v123, -v125, v121, v120
	v_add_f32_e32 v122, 1.0, v122
	v_fmac_f32_e32 v121, v123, v126
	v_div_scale_f32 v123, s[6:7], v122, v122, 1.0
	v_fma_f32 v120, -v125, v121, v120
	v_rcp_f32_e32 v125, v123
	v_div_fmas_f32 v120, v120, v126, v121
	v_and_b32_e32 v127, 0xffff0000, v127
	v_div_fixup_f32 v120, v120, v124, 1.0
	v_mul_f32_e32 v120, v114, v120
	v_fma_f32 v114, -v123, v125, 1.0
	v_mul_f32_e32 v124, 0xbfb8aa3b, v127
	v_fmac_f32_e32 v125, v114, v125
	v_div_scale_f32 v114, vcc, 1.0, v122, 1.0
	v_exp_f32_e32 v124, v124
	v_mul_f32_e32 v121, v114, v125
	v_fma_f32 v126, -v123, v121, v114
	v_fmac_f32_e32 v121, v126, v125
	v_fma_f32 v114, -v123, v121, v114
	v_add_f32_e32 v123, 1.0, v124
	v_div_scale_f32 v124, s[6:7], v123, v123, 1.0
	v_rcp_f32_e32 v126, v124
	v_div_fmas_f32 v114, v114, v125, v121
	v_div_fixup_f32 v114, v114, v122, 1.0
	v_mul_f32_e32 v119, v119, v114
	v_fma_f32 v114, -v124, v126, 1.0
	v_fmac_f32_e32 v126, v114, v126
	v_div_scale_f32 v114, vcc, 1.0, v123, 1.0
	v_mul_f32_e32 v121, v114, v126
	v_fma_f32 v122, -v124, v121, v114
	v_fmac_f32_e32 v121, v122, v126
	v_fma_f32 v114, -v124, v121, v114
	v_div_fmas_f32 v114, v114, v126, v121
	v_div_fixup_f32 v114, v114, v123, 1.0
	v_mul_f32_e32 v121, v115, v114
	v_cvt_pk_bf16_f32 v114, v116, v117
	v_cvt_pk_bf16_f32 v115, v118, v119
	v_cvt_pk_bf16_f32 v116, v112, v113
	v_or_b32_e32 v112, 16, v160
	v_mad_i64_i32 v[112:113], s[6:7], v112, s61, v[146:147]
	v_lshl_add_u64 v[112:113], v[112:113], 0, v[148:149]
	v_add_co_u32_e32 v122, vcc, s62, v112
	v_cvt_pk_bf16_f32 v117, v120, v121
	global_store_dwordx4 v[150:151], v[114:117], off offset:256 sc1
	s_nop 0
	v_addc_co_u32_e32 v123, vcc, 0, v113, vcc
	s_waitcnt vmcnt(12)
	v_mov_b32_e32 v118, v208
	v_mov_b32_e32 v119, v209
	v_mov_b32_e32 v120, v210
	v_mov_b32_e32 v121, v211
	v_add_u32_e32 v199, 0x155b00, v198
	global_load_dwordx4 v[208:211], v199, s[24:25]
	v_lshlrev_b32_e32 v114, 16, v118
	v_mul_f32_e32 v114, 0xbfb8aa3b, v114
	v_exp_f32_e32 v114, v114
	v_lshlrev_b32_e32 v116, 16, v119
	v_and_b32_e32 v117, 0xffff0000, v119
	v_and_b32_e32 v115, 0xffff0000, v118
	v_add_f32_e32 v114, 1.0, v114
	v_div_scale_f32 v119, s[6:7], v114, v114, 1.0
	v_rcp_f32_e32 v124, v119
	v_lshlrev_b32_e32 v118, 16, v120
	v_mul_f32_e32 v118, 0xbfb8aa3b, v118
	v_exp_f32_e32 v118, v118
	v_fma_f32 v126, -v119, v124, 1.0
	v_fmac_f32_e32 v124, v126, v124
	v_div_scale_f32 v126, vcc, 1.0, v114, 1.0
	v_mul_f32_e32 v127, v126, v124
	v_fma_f32 v150, -v119, v127, v126
	v_fmac_f32_e32 v127, v150, v124
	v_add_f32_e32 v118, 1.0, v118
	v_fma_f32 v119, -v119, v127, v126
	v_div_scale_f32 v126, s[6:7], v118, v118, 1.0
	v_rcp_f32_e32 v150, v126
	v_div_fmas_f32 v119, v119, v124, v127
	v_mul_f32_e32 v115, 0xbfb8aa3b, v115
	v_div_fixup_f32 v114, v119, v114, 1.0
	v_exp_f32_e32 v115, v115
	v_mul_f32_e32 v108, v108, v114
	v_fma_f32 v114, -v126, v150, 1.0
	v_fmac_f32_e32 v150, v114, v150
	v_div_scale_f32 v114, vcc, 1.0, v118, 1.0
	v_mul_f32_e32 v119, v114, v150
	v_fma_f32 v124, -v126, v119, v114
	v_add_f32_e32 v115, 1.0, v115
	v_fmac_f32_e32 v119, v124, v150
	v_div_scale_f32 v124, s[6:7], v115, v115, 1.0
	v_fma_f32 v114, -v126, v119, v114
	v_rcp_f32_e32 v126, v124
	v_and_b32_e32 v120, 0xffff0000, v120
	v_div_fmas_f32 v114, v114, v150, v119
	v_mul_f32_e32 v119, 0xbfb8aa3b, v120
	v_div_fixup_f32 v114, v114, v118, 1.0
	v_exp_f32_e32 v119, v119
	v_mul_f32_e32 v114, v104, v114
	v_fma_f32 v104, -v124, v126, 1.0
	v_fmac_f32_e32 v126, v104, v126
	v_div_scale_f32 v104, vcc, 1.0, v115, 1.0
	v_mul_f32_e32 v118, v104, v126
	v_fma_f32 v120, -v124, v118, v104
	v_add_f32_e32 v119, 1.0, v119
	v_fmac_f32_e32 v118, v120, v126
	v_div_scale_f32 v120, s[6:7], v119, v119, 1.0
	v_fma_f32 v104, -v124, v118, v104
	v_rcp_f32_e32 v124, v120
	v_div_fmas_f32 v104, v104, v126, v118
	v_mul_f32_e32 v116, 0xbfb8aa3b, v116
	v_div_fixup_f32 v104, v104, v115, 1.0
	v_exp_f32_e32 v116, v116
	v_mul_f32_e32 v104, v109, v104
	v_fma_f32 v109, -v120, v124, 1.0
	v_fmac_f32_e32 v124, v109, v124
	v_div_scale_f32 v109, vcc, 1.0, v119, 1.0
	v_mul_f32_e32 v115, v109, v124
	v_fma_f32 v118, -v120, v115, v109
	v_add_f32_e32 v116, 1.0, v116
	v_fmac_f32_e32 v115, v118, v124
	v_div_scale_f32 v118, s[6:7], v116, v116, 1.0
	v_fma_f32 v109, -v120, v115, v109
	v_rcp_f32_e32 v120, v118
; __device__ __forceinline__ float sigmoidf_(float x) { return 1.0f / (1.0f + __expf(-x)); }
; __device__ __forceinline__ u32x4 pack8(const f32x4 v0, const f32x4 v1) { u32x4 w; w.x = pk2(v0[0], v0[1]); w.y = pk2(v0[2], v0[3]); w.z = pk2(v1[0], v1[1]); w.w = pk2(v1[2], v1[3]); return w; }
; __device__ __forceinline__ void unpack8(const u32x4 w, f32x4& v0, f32x4& v1) { v0 = (f32x4){bflo(w.x), bfhi(w.x), bflo(w.y), bfhi(w.y)}; v1 = (f32x4){bflo(w.z), bfhi(w.z), bflo(w.w), bfhi(w.w)}; }
;     __device__ __forceinline__ void operator()(const f32x4 (&acc)[2][2][4][2], const Unit& u, int wr, int wc, int fr, int fq) const {
;     ...
;                 bf16_t* rowp = z + (size_t)(row0 + ai * 128 + m * 16) * DIN + col0;
; #pragma unroll
;                 for (int bj = 0; bj < 2; ++bj) {
;                     const u32x4 gw = *(const u32x4*)(rowp + (MODE == 0 ? O_GB : O_GA) + bj * 128);
;                     f32x4 g0, g1; unpack8(gw, g0, g1);
;                     f32x4 v0, v1;
; #pragma unroll
;                     for (int j = 0; j < 4; ++j) { v0[j] = sigmoidf_(g0[j]) * acc[ai][bj][m][0][j]; v1[j] = sigmoidf_(g1[j]) * acc[ai][bj][m][1][j]; }
;                     if (MODE == 1) { const u32x4 mw = *(const u32x4*)(rowp + bj * 128); f32x4 m0, m1; unpack8(mw, m0, m1); v0 += m0; v1 += m1; }
;                     *(u32x4*)(rowp + bj * 128) = pack8(v0, v1); }
	v_div_fmas_f32 v109, v109, v124, v115
	v_lshlrev_b32_e32 v125, 16, v121
	v_div_fixup_f32 v109, v109, v119, 1.0
	v_mul_f32_e32 v109, v105, v109
	v_fma_f32 v105, -v118, v120, 1.0
	v_mul_f32_e32 v119, 0xbfb8aa3b, v125
	v_fmac_f32_e32 v120, v105, v120
	v_div_scale_f32 v105, vcc, 1.0, v116, 1.0
	v_exp_f32_e32 v119, v119
	v_mul_f32_e32 v115, v105, v120
	v_fma_f32 v124, -v118, v115, v105
	v_fmac_f32_e32 v115, v124, v120
	v_fma_f32 v105, -v118, v115, v105
	v_add_f32_e32 v118, 1.0, v119
	v_div_scale_f32 v119, s[6:7], v118, v118, 1.0
	v_rcp_f32_e32 v124, v119
	v_div_fmas_f32 v105, v105, v120, v115
	v_div_fixup_f32 v105, v105, v116, 1.0
	v_mul_f32_e32 v116, 0xbfb8aa3b, v117
	v_exp_f32_e32 v116, v116
	v_mul_f32_e32 v105, v110, v105
	v_fma_f32 v110, -v119, v124, 1.0
	v_fmac_f32_e32 v124, v110, v124
	v_div_scale_f32 v110, vcc, 1.0, v118, 1.0
	v_mul_f32_e32 v115, v110, v124
	v_fma_f32 v117, -v119, v115, v110
	v_add_f32_e32 v116, 1.0, v116
	v_fmac_f32_e32 v115, v117, v124
	v_div_scale_f32 v117, s[6:7], v116, v116, 1.0
	v_fma_f32 v110, -v119, v115, v110
	v_rcp_f32_e32 v119, v117
	v_div_fmas_f32 v110, v110, v124, v115
	v_and_b32_e32 v121, 0xffff0000, v121
	v_div_fixup_f32 v110, v110, v118, 1.0
	v_mul_f32_e32 v110, v106, v110
	v_fma_f32 v106, -v117, v119, 1.0
	v_mul_f32_e32 v118, 0xbfb8aa3b, v121
	v_fmac_f32_e32 v119, v106, v119
	v_div_scale_f32 v106, vcc, 1.0, v116, 1.0
	v_exp_f32_e32 v118, v118
	v_mul_f32_e32 v115, v106, v119
	v_fma_f32 v120, -v117, v115, v106
	v_fmac_f32_e32 v115, v120, v119
	v_fma_f32 v106, -v117, v115, v106
	v_add_f32_e32 v117, 1.0, v118
	v_div_scale_f32 v118, s[6:7], v117, v117, 1.0
	v_rcp_f32_e32 v120, v118
	v_div_fmas_f32 v106, v106, v119, v115
	v_div_fixup_f32 v106, v106, v116, 1.0
	v_mul_f32_e32 v106, v111, v106
	v_fma_f32 v111, -v118, v120, 1.0
	v_fmac_f32_e32 v120, v111, v120
	v_div_scale_f32 v111, vcc, 1.0, v117, 1.0
	v_mul_f32_e32 v115, v111, v120
	v_fma_f32 v116, -v118, v115, v111
	v_fmac_f32_e32 v115, v116, v120
	v_fma_f32 v111, -v118, v115, v111
	v_div_fmas_f32 v111, v111, v120, v115
	v_div_fixup_f32 v111, v111, v117, 1.0
	v_mul_f32_e32 v107, v107, v111
	v_cvt_pk_bf16_f32 v104, v108, v104
	v_cvt_pk_bf16_f32 v105, v105, v106
	v_cvt_pk_bf16_f32 v106, v114, v109
	v_cvt_pk_bf16_f32 v107, v110, v107
	s_waitcnt vmcnt(12)
	v_mov_b32_e32 v108, v212
	v_mov_b32_e32 v109, v213
	v_mov_b32_e32 v110, v214
	v_mov_b32_e32 v111, v215
	v_add_u32_e32 v199, 0x177a00, v198
	global_load_dwordx4 v[212:215], v199, s[24:25]
	v_lshlrev_b32_e32 v115, 16, v111
	global_store_dwordx4 v[112:113], v[104:107], off sc1
	v_and_b32_e32 v111, 0xffff0000, v111
	s_nop 0
	v_lshlrev_b32_e32 v104, 16, v108
	v_mul_f32_e32 v104, 0xbfb8aa3b, v104
	v_exp_f32_e32 v104, v104
	v_lshlrev_b32_e32 v106, 16, v109
	v_and_b32_e32 v107, 0xffff0000, v109
	v_and_b32_e32 v105, 0xffff0000, v108
	v_add_f32_e32 v104, 1.0, v104
	v_div_scale_f32 v109, s[6:7], v104, v104, 1.0
	v_rcp_f32_e32 v114, v109
	v_lshlrev_b32_e32 v108, 16, v110
	v_mul_f32_e32 v108, 0xbfb8aa3b, v108
	v_exp_f32_e32 v108, v108
	v_fma_f32 v116, -v109, v114, 1.0
	v_fmac_f32_e32 v114, v116, v114
	v_div_scale_f32 v116, vcc, 1.0, v104, 1.0
	v_mul_f32_e32 v117, v116, v114
	v_fma_f32 v118, -v109, v117, v116
	v_fmac_f32_e32 v117, v118, v114
	v_add_f32_e32 v108, 1.0, v108
	v_fma_f32 v109, -v109, v117, v116
	v_div_scale_f32 v116, s[6:7], v108, v108, 1.0
	v_rcp_f32_e32 v118, v116
	v_div_fmas_f32 v109, v109, v114, v117
	v_mul_f32_e32 v105, 0xbfb8aa3b, v105
	v_div_fixup_f32 v104, v109, v104, 1.0
	v_exp_f32_e32 v105, v105
	v_mul_f32_e32 v100, v100, v104
	v_fma_f32 v104, -v116, v118, 1.0
	v_fmac_f32_e32 v118, v104, v118
	v_div_scale_f32 v104, vcc, 1.0, v108, 1.0
	v_mul_f32_e32 v109, v104, v118
	v_fma_f32 v114, -v116, v109, v104
	v_add_f32_e32 v105, 1.0, v105
	v_fmac_f32_e32 v109, v114, v118
	v_div_scale_f32 v114, s[6:7], v105, v105, 1.0
	v_fma_f32 v104, -v116, v109, v104
	v_rcp_f32_e32 v116, v114
	v_and_b32_e32 v110, 0xffff0000, v110
	v_div_fmas_f32 v104, v104, v118, v109
	v_mul_f32_e32 v109, 0xbfb8aa3b, v110
	v_div_fixup_f32 v104, v104, v108, 1.0
	v_exp_f32_e32 v109, v109
	v_mul_f32_e32 v96, v96, v104
	v_fma_f32 v104, -v114, v116, 1.0
	v_fmac_f32_e32 v116, v104, v116
	v_div_scale_f32 v104, vcc, 1.0, v105, 1.0
	v_mul_f32_e32 v108, v104, v116
	v_fma_f32 v110, -v114, v108, v104
	v_add_f32_e32 v109, 1.0, v109
	v_fmac_f32_e32 v108, v110, v116
	v_div_scale_f32 v110, s[6:7], v109, v109, 1.0
	v_fma_f32 v104, -v114, v108, v104
	v_rcp_f32_e32 v114, v110
	v_div_fmas_f32 v104, v104, v116, v108
	v_mul_f32_e32 v106, 0xbfb8aa3b, v106
	v_div_fixup_f32 v104, v104, v105, 1.0
	v_exp_f32_e32 v106, v106
	v_mul_f32_e32 v101, v101, v104
	v_fma_f32 v104, -v110, v114, 1.0
	v_fmac_f32_e32 v114, v104, v114
	v_div_scale_f32 v104, vcc, 1.0, v109, 1.0
	v_mul_f32_e32 v105, v104, v114
	v_fma_f32 v108, -v110, v105, v104
	v_add_f32_e32 v106, 1.0, v106
	v_fmac_f32_e32 v105, v108, v114
	v_div_scale_f32 v108, s[6:7], v106, v106, 1.0
	v_fma_f32 v104, -v110, v105, v104
	v_rcp_f32_e32 v110, v108
	v_div_fmas_f32 v104, v104, v114, v105
	v_div_fixup_f32 v104, v104, v109, 1.0
	v_mul_f32_e32 v97, v97, v104
	v_fma_f32 v104, -v108, v110, 1.0
	v_mul_f32_e32 v109, 0xbfb8aa3b, v115
	v_fmac_f32_e32 v110, v104, v110
	v_div_scale_f32 v104, vcc, 1.0, v106, 1.0
	v_exp_f32_e32 v109, v109
	v_mul_f32_e32 v105, v104, v110
	v_fma_f32 v114, -v108, v105, v104
	v_fmac_f32_e32 v105, v114, v110
	v_fma_f32 v104, -v108, v105, v104
	v_add_f32_e32 v108, 1.0, v109
	v_div_scale_f32 v109, s[6:7], v108, v108, 1.0
	v_rcp_f32_e32 v114, v109
	v_div_fmas_f32 v104, v104, v110, v105
	v_div_fixup_f32 v104, v104, v106, 1.0
	v_mul_f32_e32 v106, 0xbfb8aa3b, v107
	v_exp_f32_e32 v106, v106
	v_mul_f32_e32 v102, v102, v104
; __device__ __forceinline__ float sigmoidf_(float x) { return 1.0f / (1.0f + __expf(-x)); }
; __device__ __forceinline__ u32x4 pack8(const f32x4 v0, const f32x4 v1) { u32x4 w; w.x = pk2(v0[0], v0[1]); w.y = pk2(v0[2], v0[3]); w.z = pk2(v1[0], v1[1]); w.w = pk2(v1[2], v1[3]); return w; }
; __device__ __forceinline__ void unpack8(const u32x4 w, f32x4& v0, f32x4& v1) { v0 = (f32x4){bflo(w.x), bfhi(w.x), bflo(w.y), bfhi(w.y)}; v1 = (f32x4){bflo(w.z), bfhi(w.z), bflo(w.w), bfhi(w.w)}; }
;     __device__ __forceinline__ void operator()(const f32x4 (&acc)[2][2][4][2], const Unit& u, int wr, int wc, int fr, int fq) const {
;     ...
;                 bf16_t* rowp = z + (size_t)(row0 + ai * 128 + m * 16) * DIN + col0;
; #pragma unroll
;                 for (int bj = 0; bj < 2; ++bj) {
;                     const u32x4 gw = *(const u32x4*)(rowp + (MODE == 0 ? O_GB : O_GA) + bj * 128);
;                     f32x4 g0, g1; unpack8(gw, g0, g1);
;                     f32x4 v0, v1;
; #pragma unroll
;                     for (int j = 0; j < 4; ++j) { v0[j] = sigmoidf_(g0[j]) * acc[ai][bj][m][0][j]; v1[j] = sigmoidf_(g1[j]) * acc[ai][bj][m][1][j]; }
;                     if (MODE == 1) { const u32x4 mw = *(const u32x4*)(rowp + bj * 128); f32x4 m0, m1; unpack8(mw, m0, m1); v0 += m0; v1 += m1; }
;                     *(u32x4*)(rowp + bj * 128) = pack8(v0, v1); }
	v_fma_f32 v104, -v109, v114, 1.0
	v_fmac_f32_e32 v114, v104, v114
	v_div_scale_f32 v104, vcc, 1.0, v108, 1.0
	v_mul_f32_e32 v105, v104, v114
	v_fma_f32 v107, -v109, v105, v104
	v_add_f32_e32 v106, 1.0, v106
	v_fmac_f32_e32 v105, v107, v114
	v_div_scale_f32 v107, s[6:7], v106, v106, 1.0
	v_fma_f32 v104, -v109, v105, v104
	v_rcp_f32_e32 v109, v107
	v_div_fmas_f32 v104, v104, v114, v105
	v_div_fixup_f32 v104, v104, v108, 1.0
	v_mul_f32_e32 v104, v98, v104
	v_fma_f32 v98, -v107, v109, 1.0
	v_mul_f32_e32 v108, 0xbfb8aa3b, v111
	v_fmac_f32_e32 v109, v98, v109
	v_div_scale_f32 v98, vcc, 1.0, v106, 1.0
	v_exp_f32_e32 v108, v108
	v_mul_f32_e32 v105, v98, v109
	v_fma_f32 v110, -v107, v105, v98
	v_fmac_f32_e32 v105, v110, v109
	v_fma_f32 v98, -v107, v105, v98
	v_add_f32_e32 v107, 1.0, v108
	v_div_scale_f32 v108, s[6:7], v107, v107, 1.0
	v_rcp_f32_e32 v110, v108
	v_div_fmas_f32 v98, v98, v109, v105
	v_div_fixup_f32 v98, v98, v106, 1.0
	v_mul_f32_e32 v103, v103, v98
	v_fma_f32 v98, -v108, v110, 1.0
	v_fmac_f32_e32 v110, v98, v110
	v_div_scale_f32 v98, vcc, 1.0, v107, 1.0
	v_mul_f32_e32 v105, v98, v110
	v_fma_f32 v106, -v108, v105, v98
	v_fmac_f32_e32 v105, v106, v110
	v_fma_f32 v98, -v108, v105, v98
	v_div_fmas_f32 v98, v98, v110, v105
	v_div_fixup_f32 v98, v98, v107, 1.0
	v_mul_f32_e32 v105, v99, v98
	v_cvt_pk_bf16_f32 v98, v100, v101
	v_cvt_pk_bf16_f32 v99, v102, v103
	v_cvt_pk_bf16_f32 v100, v96, v97
	v_or_b32_e32 v96, 32, v160
	v_mad_i64_i32 v[96:97], s[6:7], v96, s61, v[146:147]
	v_lshl_add_u64 v[96:97], v[96:97], 0, v[148:149]
	v_add_co_u32_e32 v106, vcc, s62, v96
	v_cvt_pk_bf16_f32 v101, v104, v105
	global_store_dwordx4 v[112:113], v[98:101], off offset:256 sc1
	s_nop 0
	v_addc_co_u32_e32 v107, vcc, 0, v97, vcc
	s_waitcnt vmcnt(14)
	v_mov_b32_e32 v102, v216
	v_mov_b32_e32 v103, v217
	v_mov_b32_e32 v104, v218
	v_mov_b32_e32 v105, v219
	v_add_u32_e32 v199, 0x177b00, v198
	global_load_dwordx4 v[216:219], v199, s[24:25]
	v_lshlrev_b32_e32 v98, 16, v102
	v_mul_f32_e32 v98, 0xbfb8aa3b, v98
	v_exp_f32_e32 v98, v98
	v_lshlrev_b32_e32 v100, 16, v103
	v_and_b32_e32 v101, 0xffff0000, v103
	v_and_b32_e32 v99, 0xffff0000, v102
	v_add_f32_e32 v98, 1.0, v98
	v_div_scale_f32 v103, s[6:7], v98, v98, 1.0
	v_rcp_f32_e32 v108, v103
	v_lshlrev_b32_e32 v102, 16, v104
	v_mul_f32_e32 v102, 0xbfb8aa3b, v102
	v_exp_f32_e32 v102, v102
	v_fma_f32 v110, -v103, v108, 1.0
	v_fmac_f32_e32 v108, v110, v108
	v_div_scale_f32 v110, vcc, 1.0, v98, 1.0
	v_mul_f32_e32 v111, v110, v108
	v_fma_f32 v112, -v103, v111, v110
	v_fmac_f32_e32 v111, v112, v108
	v_add_f32_e32 v102, 1.0, v102
	v_fma_f32 v103, -v103, v111, v110
	v_div_scale_f32 v110, s[6:7], v102, v102, 1.0
	v_rcp_f32_e32 v112, v110
	v_div_fmas_f32 v103, v103, v108, v111
	v_mul_f32_e32 v99, 0xbfb8aa3b, v99
	v_div_fixup_f32 v98, v103, v98, 1.0
	v_exp_f32_e32 v99, v99
	v_mul_f32_e32 v92, v92, v98
	v_fma_f32 v98, -v110, v112, 1.0
	v_fmac_f32_e32 v112, v98, v112
	v_div_scale_f32 v98, vcc, 1.0, v102, 1.0
	v_mul_f32_e32 v103, v98, v112
	v_fma_f32 v108, -v110, v103, v98
	v_add_f32_e32 v99, 1.0, v99
	v_fmac_f32_e32 v103, v108, v112
	v_div_scale_f32 v108, s[6:7], v99, v99, 1.0
	v_fma_f32 v98, -v110, v103, v98
	v_rcp_f32_e32 v110, v108
	v_and_b32_e32 v104, 0xffff0000, v104
	v_div_fmas_f32 v98, v98, v112, v103
	v_mul_f32_e32 v103, 0xbfb8aa3b, v104
	v_div_fixup_f32 v98, v98, v102, 1.0
	v_exp_f32_e32 v103, v103
	v_mul_f32_e32 v98, v88, v98
	v_fma_f32 v88, -v108, v110, 1.0
	v_fmac_f32_e32 v110, v88, v110
	v_div_scale_f32 v88, vcc, 1.0, v99, 1.0
	v_mul_f32_e32 v102, v88, v110
	v_fma_f32 v104, -v108, v102, v88
	v_add_f32_e32 v103, 1.0, v103
	v_fmac_f32_e32 v102, v104, v110
	v_div_scale_f32 v104, s[6:7], v103, v103, 1.0
	v_fma_f32 v88, -v108, v102, v88
	v_rcp_f32_e32 v108, v104
	v_div_fmas_f32 v88, v88, v110, v102
	v_mul_f32_e32 v100, 0xbfb8aa3b, v100
	v_div_fixup_f32 v88, v88, v99, 1.0
	v_exp_f32_e32 v100, v100
	v_mul_f32_e32 v88, v93, v88
	v_fma_f32 v93, -v104, v108, 1.0
	v_fmac_f32_e32 v108, v93, v108
	v_div_scale_f32 v93, vcc, 1.0, v103, 1.0
	v_mul_f32_e32 v99, v93, v108
	v_fma_f32 v102, -v104, v99, v93
	v_add_f32_e32 v100, 1.0, v100
	v_fmac_f32_e32 v99, v102, v108
	v_div_scale_f32 v102, s[6:7], v100, v100, 1.0
	v_fma_f32 v93, -v104, v99, v93
	v_rcp_f32_e32 v104, v102
	v_div_fmas_f32 v93, v93, v108, v99
	v_lshlrev_b32_e32 v109, 16, v105
	v_div_fixup_f32 v93, v93, v103, 1.0
	v_mul_f32_e32 v93, v89, v93
	v_fma_f32 v89, -v102, v104, 1.0
	v_mul_f32_e32 v103, 0xbfb8aa3b, v109
	v_fmac_f32_e32 v104, v89, v104
	v_div_scale_f32 v89, vcc, 1.0, v100, 1.0
	v_exp_f32_e32 v103, v103
	v_mul_f32_e32 v99, v89, v104
	v_fma_f32 v108, -v102, v99, v89
	v_fmac_f32_e32 v99, v108, v104
	v_fma_f32 v89, -v102, v99, v89
	v_add_f32_e32 v102, 1.0, v103
	v_div_scale_f32 v103, s[6:7], v102, v102, 1.0
	v_rcp_f32_e32 v108, v103
	v_div_fmas_f32 v89, v89, v104, v99
	v_div_fixup_f32 v89, v89, v100, 1.0
	v_mul_f32_e32 v100, 0xbfb8aa3b, v101
	v_exp_f32_e32 v100, v100
	v_mul_f32_e32 v89, v94, v89
	v_fma_f32 v94, -v103, v108, 1.0
	v_fmac_f32_e32 v108, v94, v108
	v_div_scale_f32 v94, vcc, 1.0, v102, 1.0
	v_mul_f32_e32 v99, v94, v108
	v_fma_f32 v101, -v103, v99, v94
	v_add_f32_e32 v100, 1.0, v100
	v_fmac_f32_e32 v99, v101, v108
	v_div_scale_f32 v101, s[6:7], v100, v100, 1.0
	v_fma_f32 v94, -v103, v99, v94
	v_rcp_f32_e32 v103, v101
	v_div_fmas_f32 v94, v94, v108, v99
	v_and_b32_e32 v105, 0xffff0000, v105
	v_div_fixup_f32 v94, v94, v102, 1.0
	v_mul_f32_e32 v94, v90, v94
	v_fma_f32 v90, -v101, v103, 1.0
	v_mul_f32_e32 v102, 0xbfb8aa3b, v105
	v_fmac_f32_e32 v103, v90, v103
	v_div_scale_f32 v90, vcc, 1.0, v100, 1.0
	v_exp_f32_e32 v102, v102
	v_mul_f32_e32 v99, v90, v103
	v_fma_f32 v104, -v101, v99, v90
	v_fmac_f32_e32 v99, v104, v103
	v_fma_f32 v90, -v101, v99, v90
	v_add_f32_e32 v101, 1.0, v102
	v_div_scale_f32 v102, s[6:7], v101, v101, 1.0
	v_rcp_f32_e32 v104, v102
	v_div_fmas_f32 v90, v90, v103, v99
	v_div_fixup_f32 v90, v90, v100, 1.0
	v_mul_f32_e32 v90, v95, v90
	v_fma_f32 v95, -v102, v104, 1.0
	v_fmac_f32_e32 v104, v95, v104
	v_div_scale_f32 v95, vcc, 1.0, v101, 1.0
	v_mul_f32_e32 v99, v95, v104
	v_fma_f32 v100, -v102, v99, v95
	v_fmac_f32_e32 v99, v100, v104
	v_fma_f32 v95, -v102, v99, v95
	v_div_fmas_f32 v95, v95, v104, v99
	v_div_fixup_f32 v95, v95, v101, 1.0
	v_mul_f32_e32 v91, v91, v95
	v_cvt_pk_bf16_f32 v88, v92, v88
	v_cvt_pk_bf16_f32 v89, v89, v90
	v_cvt_pk_bf16_f32 v90, v98, v93
	v_cvt_pk_bf16_f32 v91, v94, v91
	s_waitcnt vmcnt(14)
; __device__ __forceinline__ float sigmoidf_(float x) { return 1.0f / (1.0f + __expf(-x)); }
; __device__ __forceinline__ u32x4 pack8(const f32x4 v0, const f32x4 v1) { u32x4 w; w.x = pk2(v0[0], v0[1]); w.y = pk2(v0[2], v0[3]); w.z = pk2(v1[0], v1[1]); w.w = pk2(v1[2], v1[3]); return w; }
; __device__ __forceinline__ void unpack8(const u32x4 w, f32x4& v0, f32x4& v1) { v0 = (f32x4){bflo(w.x), bfhi(w.x), bflo(w.y), bfhi(w.y)}; v1 = (f32x4){bflo(w.z), bfhi(w.z), bflo(w.w), bfhi(w.w)}; }
;     __device__ __forceinline__ void operator()(const f32x4 (&acc)[2][2][4][2], const Unit& u, int wr, int wc, int fr, int fq) const {
;     ...
;                 bf16_t* rowp = z + (size_t)(row0 + ai * 128 + m * 16) * DIN + col0;
; #pragma unroll
;                 for (int bj = 0; bj < 2; ++bj) {
;                     const u32x4 gw = *(const u32x4*)(rowp + (MODE == 0 ? O_GB : O_GA) + bj * 128);
;                     f32x4 g0, g1; unpack8(gw, g0, g1);
;                     f32x4 v0, v1;
; #pragma unroll
;                     for (int j = 0; j < 4; ++j) { v0[j] = sigmoidf_(g0[j]) * acc[ai][bj][m][0][j]; v1[j] = sigmoidf_(g1[j]) * acc[ai][bj][m][1][j]; }
;                     if (MODE == 1) { const u32x4 mw = *(const u32x4*)(rowp + bj * 128); f32x4 m0, m1; unpack8(mw, m0, m1); v0 += m0; v1 += m1; }
;                     *(u32x4*)(rowp + bj * 128) = pack8(v0, v1); }
	v_mov_b32_e32 v92, v232
	v_mov_b32_e32 v93, v233
	v_mov_b32_e32 v94, v234
	v_mov_b32_e32 v95, v235
	v_lshlrev_b32_e32 v99, 16, v95
	global_store_dwordx4 v[96:97], v[88:91], off sc1
	v_and_b32_e32 v95, 0xffff0000, v95
	s_nop 0
	v_lshlrev_b32_e32 v88, 16, v92
	v_mul_f32_e32 v88, 0xbfb8aa3b, v88
	v_exp_f32_e32 v88, v88
	v_lshlrev_b32_e32 v90, 16, v93
	v_and_b32_e32 v91, 0xffff0000, v93
	v_and_b32_e32 v89, 0xffff0000, v92
	v_add_f32_e32 v88, 1.0, v88
	v_div_scale_f32 v93, s[6:7], v88, v88, 1.0
	v_rcp_f32_e32 v98, v93
	v_lshlrev_b32_e32 v92, 16, v94
	v_mul_f32_e32 v92, 0xbfb8aa3b, v92
	v_exp_f32_e32 v92, v92
	v_fma_f32 v100, -v93, v98, 1.0
	v_fmac_f32_e32 v98, v100, v98
	v_div_scale_f32 v100, vcc, 1.0, v88, 1.0
	v_mul_f32_e32 v101, v100, v98
	v_fma_f32 v102, -v93, v101, v100
	v_fmac_f32_e32 v101, v102, v98
	v_add_f32_e32 v92, 1.0, v92
	v_fma_f32 v93, -v93, v101, v100
	v_div_scale_f32 v100, s[6:7], v92, v92, 1.0
	v_rcp_f32_e32 v102, v100
	v_div_fmas_f32 v93, v93, v98, v101
	v_mul_f32_e32 v89, 0xbfb8aa3b, v89
	v_div_fixup_f32 v88, v93, v88, 1.0
	v_exp_f32_e32 v89, v89
	v_mul_f32_e32 v84, v84, v88
	v_fma_f32 v88, -v100, v102, 1.0
	v_fmac_f32_e32 v102, v88, v102
	v_div_scale_f32 v88, vcc, 1.0, v92, 1.0
	v_mul_f32_e32 v93, v88, v102
	v_fma_f32 v98, -v100, v93, v88
	v_add_f32_e32 v89, 1.0, v89
	v_fmac_f32_e32 v93, v98, v102
	v_div_scale_f32 v98, s[6:7], v89, v89, 1.0
	v_fma_f32 v88, -v100, v93, v88
	v_rcp_f32_e32 v100, v98
	v_and_b32_e32 v94, 0xffff0000, v94
	v_div_fmas_f32 v88, v88, v102, v93
	v_mul_f32_e32 v93, 0xbfb8aa3b, v94
	v_div_fixup_f32 v88, v88, v92, 1.0
	v_exp_f32_e32 v93, v93
	v_mul_f32_e32 v80, v80, v88
	v_fma_f32 v88, -v98, v100, 1.0
	v_fmac_f32_e32 v100, v88, v100
	v_div_scale_f32 v88, vcc, 1.0, v89, 1.0
	v_mul_f32_e32 v92, v88, v100
	v_fma_f32 v94, -v98, v92, v88
	v_add_f32_e32 v93, 1.0, v93
	v_fmac_f32_e32 v92, v94, v100
	v_div_scale_f32 v94, s[6:7], v93, v93, 1.0
	v_fma_f32 v88, -v98, v92, v88
	v_rcp_f32_e32 v98, v94
	v_div_fmas_f32 v88, v88, v100, v92
	v_mul_f32_e32 v90, 0xbfb8aa3b, v90
	v_div_fixup_f32 v88, v88, v89, 1.0
	v_exp_f32_e32 v90, v90
	v_mul_f32_e32 v85, v85, v88
	v_fma_f32 v88, -v94, v98, 1.0
	v_fmac_f32_e32 v98, v88, v98
	v_div_scale_f32 v88, vcc, 1.0, v93, 1.0
	v_mul_f32_e32 v89, v88, v98
	v_fma_f32 v92, -v94, v89, v88
	v_add_f32_e32 v90, 1.0, v90
	v_fmac_f32_e32 v89, v92, v98
	v_div_scale_f32 v92, s[6:7], v90, v90, 1.0
	v_fma_f32 v88, -v94, v89, v88
	v_rcp_f32_e32 v94, v92
	v_div_fmas_f32 v88, v88, v98, v89
	v_div_fixup_f32 v88, v88, v93, 1.0
	v_mul_f32_e32 v81, v81, v88
	v_fma_f32 v88, -v92, v94, 1.0
	v_mul_f32_e32 v93, 0xbfb8aa3b, v99
	v_fmac_f32_e32 v94, v88, v94
	v_div_scale_f32 v88, vcc, 1.0, v90, 1.0
	v_exp_f32_e32 v93, v93
	v_mul_f32_e32 v89, v88, v94
	v_fma_f32 v98, -v92, v89, v88
	v_fmac_f32_e32 v89, v98, v94
	v_fma_f32 v88, -v92, v89, v88
	v_add_f32_e32 v92, 1.0, v93
	v_div_scale_f32 v93, s[6:7], v92, v92, 1.0
	v_rcp_f32_e32 v98, v93
	v_div_fmas_f32 v88, v88, v94, v89
	v_div_fixup_f32 v88, v88, v90, 1.0
	v_mul_f32_e32 v90, 0xbfb8aa3b, v91
	v_exp_f32_e32 v90, v90
	v_mul_f32_e32 v86, v86, v88
	v_fma_f32 v88, -v93, v98, 1.0
	v_fmac_f32_e32 v98, v88, v98
	v_div_scale_f32 v88, vcc, 1.0, v92, 1.0
	v_mul_f32_e32 v89, v88, v98
	v_fma_f32 v91, -v93, v89, v88
	v_add_f32_e32 v90, 1.0, v90
	v_fmac_f32_e32 v89, v91, v98
	v_div_scale_f32 v91, s[6:7], v90, v90, 1.0
	v_fma_f32 v88, -v93, v89, v88
	v_rcp_f32_e32 v93, v91
	v_div_fmas_f32 v88, v88, v98, v89
	v_div_fixup_f32 v88, v88, v92, 1.0
	v_mul_f32_e32 v88, v82, v88
	v_fma_f32 v82, -v91, v93, 1.0
	v_mul_f32_e32 v92, 0xbfb8aa3b, v95
	v_fmac_f32_e32 v93, v82, v93
	v_div_scale_f32 v82, vcc, 1.0, v90, 1.0
	v_exp_f32_e32 v92, v92
	v_mul_f32_e32 v89, v82, v93
	v_fma_f32 v94, -v91, v89, v82
	v_fmac_f32_e32 v89, v94, v93
	v_fma_f32 v82, -v91, v89, v82
	v_add_f32_e32 v91, 1.0, v92
	v_div_scale_f32 v92, s[6:7], v91, v91, 1.0
	v_rcp_f32_e32 v94, v92
	v_div_fmas_f32 v82, v82, v93, v89
	v_div_fixup_f32 v82, v82, v90, 1.0
	v_mul_f32_e32 v87, v87, v82
	v_fma_f32 v82, -v92, v94, 1.0
	v_fmac_f32_e32 v94, v82, v94
	v_div_scale_f32 v82, vcc, 1.0, v91, 1.0
	v_mul_f32_e32 v89, v82, v94
	v_fma_f32 v90, -v92, v89, v82
	v_fmac_f32_e32 v89, v90, v94
	v_fma_f32 v82, -v92, v89, v82
	v_div_fmas_f32 v82, v82, v94, v89
	v_div_fixup_f32 v82, v82, v91, 1.0
	v_mul_f32_e32 v89, v83, v82
	v_cvt_pk_bf16_f32 v82, v84, v85
	v_cvt_pk_bf16_f32 v83, v86, v87
	v_cvt_pk_bf16_f32 v84, v80, v81
	v_or_b32_e32 v80, 48, v160
	v_mad_i64_i32 v[80:81], s[6:7], v80, s61, v[146:147]
	v_lshl_add_u64 v[80:81], v[80:81], 0, v[148:149]
	v_add_co_u32_e32 v90, vcc, s62, v80
	v_cvt_pk_bf16_f32 v85, v88, v89
	global_store_dwordx4 v[96:97], v[82:85], off offset:256 sc1
	s_nop 0
	v_addc_co_u32_e32 v91, vcc, 0, v81, vcc
	s_waitcnt vmcnt(15)
; __device__ __forceinline__ float sigmoidf_(float x) { return 1.0f / (1.0f + __expf(-x)); }
; __device__ __forceinline__ u32x4 pack8(const f32x4 v0, const f32x4 v1) { u32x4 w; w.x = pk2(v0[0], v0[1]); w.y = pk2(v0[2], v0[3]); w.z = pk2(v1[0], v1[1]); w.w = pk2(v1[2], v1[3]); return w; }
; __device__ __forceinline__ void unpack8(const u32x4 w, f32x4& v0, f32x4& v1) { v0 = (f32x4){bflo(w.x), bfhi(w.x), bflo(w.y), bfhi(w.y)}; v1 = (f32x4){bflo(w.z), bfhi(w.z), bflo(w.w), bfhi(w.w)}; }
;     __device__ __forceinline__ void operator()(const f32x4 (&acc)[2][2][4][2], const Unit& u, int wr, int wc, int fr, int fq) const {
;     ...
;                     const u32x4 gw = *(const u32x4*)(rowp + (MODE == 0 ? O_GB : O_GA) + bj * 128);
;                     f32x4 g0, g1; unpack8(gw, g0, g1);
;                     f32x4 v0, v1;
; #pragma unroll
;                     for (int j = 0; j < 4; ++j) { v0[j] = sigmoidf_(g0[j]) * acc[ai][bj][m][0][j]; v1[j] = sigmoidf_(g1[j]) * acc[ai][bj][m][1][j]; }
;                     if (MODE == 1) { const u32x4 mw = *(const u32x4*)(rowp + bj * 128); f32x4 m0, m1; unpack8(mw, m0, m1); v0 += m0; v1 += m1; }
;                     *(u32x4*)(rowp + bj * 128) = pack8(v0, v1); }
	v_mov_b32_e32 v86, v236
	v_mov_b32_e32 v87, v237
	v_mov_b32_e32 v88, v238
	v_mov_b32_e32 v89, v239
	v_lshlrev_b32_e32 v82, 16, v86
	v_mul_f32_e32 v82, 0xbfb8aa3b, v82
	v_exp_f32_e32 v82, v82
	v_lshlrev_b32_e32 v84, 16, v87
	v_and_b32_e32 v85, 0xffff0000, v87
	v_and_b32_e32 v83, 0xffff0000, v86
	v_add_f32_e32 v82, 1.0, v82
	v_div_scale_f32 v87, s[6:7], v82, v82, 1.0
	v_rcp_f32_e32 v92, v87
	v_lshlrev_b32_e32 v86, 16, v88
	v_mul_f32_e32 v86, 0xbfb8aa3b, v86
	v_exp_f32_e32 v86, v86
	v_fma_f32 v94, -v87, v92, 1.0
	v_fmac_f32_e32 v92, v94, v92
	v_div_scale_f32 v94, vcc, 1.0, v82, 1.0
	v_mul_f32_e32 v95, v94, v92
	v_fma_f32 v96, -v87, v95, v94
	v_fmac_f32_e32 v95, v96, v92
	v_add_f32_e32 v86, 1.0, v86
	v_fma_f32 v87, -v87, v95, v94
	v_div_scale_f32 v94, s[6:7], v86, v86, 1.0
	v_rcp_f32_e32 v96, v94
	v_div_fmas_f32 v87, v87, v92, v95
	v_mul_f32_e32 v83, 0xbfb8aa3b, v83
	v_div_fixup_f32 v82, v87, v82, 1.0
	v_exp_f32_e32 v83, v83
	v_mul_f32_e32 v76, v76, v82
	v_fma_f32 v82, -v94, v96, 1.0
	v_fmac_f32_e32 v96, v82, v96
	v_div_scale_f32 v82, vcc, 1.0, v86, 1.0
	v_mul_f32_e32 v87, v82, v96
	v_fma_f32 v92, -v94, v87, v82
	v_add_f32_e32 v83, 1.0, v83
	v_fmac_f32_e32 v87, v92, v96
	v_div_scale_f32 v92, s[6:7], v83, v83, 1.0
	v_fma_f32 v82, -v94, v87, v82
	v_rcp_f32_e32 v94, v92
	v_and_b32_e32 v88, 0xffff0000, v88
	v_div_fmas_f32 v82, v82, v96, v87
	v_mul_f32_e32 v87, 0xbfb8aa3b, v88
	v_div_fixup_f32 v82, v82, v86, 1.0
	v_exp_f32_e32 v87, v87
	v_mul_f32_e32 v82, v72, v82
	v_fma_f32 v72, -v92, v94, 1.0
	v_fmac_f32_e32 v94, v72, v94
	v_div_scale_f32 v72, vcc, 1.0, v83, 1.0
	v_mul_f32_e32 v86, v72, v94
	v_fma_f32 v88, -v92, v86, v72
	v_add_f32_e32 v87, 1.0, v87
	v_fmac_f32_e32 v86, v88, v94
	v_div_scale_f32 v88, s[6:7], v87, v87, 1.0
	v_fma_f32 v72, -v92, v86, v72
	v_rcp_f32_e32 v92, v88
	v_div_fmas_f32 v72, v72, v94, v86
	v_mul_f32_e32 v84, 0xbfb8aa3b, v84
	v_div_fixup_f32 v72, v72, v83, 1.0
	v_exp_f32_e32 v84, v84
	v_mul_f32_e32 v72, v77, v72
	v_fma_f32 v77, -v88, v92, 1.0
	v_fmac_f32_e32 v92, v77, v92
	v_div_scale_f32 v77, vcc, 1.0, v87, 1.0
	v_mul_f32_e32 v83, v77, v92
	v_fma_f32 v86, -v88, v83, v77
	v_add_f32_e32 v84, 1.0, v84
	v_fmac_f32_e32 v83, v86, v92
	v_div_scale_f32 v86, s[6:7], v84, v84, 1.0
	v_fma_f32 v77, -v88, v83, v77
	v_rcp_f32_e32 v88, v86
	v_div_fmas_f32 v77, v77, v92, v83
	v_lshlrev_b32_e32 v93, 16, v89
	v_div_fixup_f32 v77, v77, v87, 1.0
	v_mul_f32_e32 v77, v73, v77
	v_fma_f32 v73, -v86, v88, 1.0
	v_mul_f32_e32 v87, 0xbfb8aa3b, v93
	v_fmac_f32_e32 v88, v73, v88
	v_div_scale_f32 v73, vcc, 1.0, v84, 1.0
	v_exp_f32_e32 v87, v87
	v_mul_f32_e32 v83, v73, v88
	v_fma_f32 v92, -v86, v83, v73
	v_fmac_f32_e32 v83, v92, v88
	v_fma_f32 v73, -v86, v83, v73
	v_add_f32_e32 v86, 1.0, v87
	v_div_scale_f32 v87, s[6:7], v86, v86, 1.0
	v_rcp_f32_e32 v92, v87
	v_div_fmas_f32 v73, v73, v88, v83
	v_div_fixup_f32 v73, v73, v84, 1.0
	v_mul_f32_e32 v84, 0xbfb8aa3b, v85
	v_exp_f32_e32 v84, v84
	v_mul_f32_e32 v73, v78, v73
	v_fma_f32 v78, -v87, v92, 1.0
	v_fmac_f32_e32 v92, v78, v92
	v_div_scale_f32 v78, vcc, 1.0, v86, 1.0
	v_mul_f32_e32 v83, v78, v92
	v_fma_f32 v85, -v87, v83, v78
	v_add_f32_e32 v84, 1.0, v84
	v_fmac_f32_e32 v83, v85, v92
	v_div_scale_f32 v85, s[6:7], v84, v84, 1.0
	v_fma_f32 v78, -v87, v83, v78
	v_rcp_f32_e32 v87, v85
	v_div_fmas_f32 v78, v78, v92, v83
	v_and_b32_e32 v89, 0xffff0000, v89
	v_div_fixup_f32 v78, v78, v86, 1.0
	v_mul_f32_e32 v78, v74, v78
	v_fma_f32 v74, -v85, v87, 1.0
	v_mul_f32_e32 v86, 0xbfb8aa3b, v89
	v_fmac_f32_e32 v87, v74, v87
	v_div_scale_f32 v74, vcc, 1.0, v84, 1.0
	v_exp_f32_e32 v86, v86
	v_mul_f32_e32 v83, v74, v87
	v_fma_f32 v88, -v85, v83, v74
	v_fmac_f32_e32 v83, v88, v87
	v_fma_f32 v74, -v85, v83, v74
	v_add_f32_e32 v85, 1.0, v86
	v_div_scale_f32 v86, s[6:7], v85, v85, 1.0
	v_rcp_f32_e32 v88, v86
	v_div_fmas_f32 v74, v74, v87, v83
	v_div_fixup_f32 v74, v74, v84, 1.0
	v_mul_f32_e32 v74, v79, v74
	v_fma_f32 v79, -v86, v88, 1.0
	v_fmac_f32_e32 v88, v79, v88
	v_div_scale_f32 v79, vcc, 1.0, v85, 1.0
	v_mul_f32_e32 v83, v79, v88
	v_fma_f32 v84, -v86, v83, v79
	v_fmac_f32_e32 v83, v84, v88
	v_fma_f32 v79, -v86, v83, v79
	v_div_fmas_f32 v79, v79, v88, v83
	v_div_fixup_f32 v79, v79, v85, 1.0
	v_mul_f32_e32 v75, v75, v79
	v_cvt_pk_bf16_f32 v72, v76, v72
	v_cvt_pk_bf16_f32 v73, v73, v74
	v_cvt_pk_bf16_f32 v74, v82, v77
	v_cvt_pk_bf16_f32 v75, v78, v75
	s_waitcnt vmcnt(14)
; __device__ __forceinline__ float sigmoidf_(float x) { return 1.0f / (1.0f + __expf(-x)); }
; __device__ __forceinline__ u32x4 pack8(const f32x4 v0, const f32x4 v1) { u32x4 w; w.x = pk2(v0[0], v0[1]); w.y = pk2(v0[2], v0[3]); w.z = pk2(v1[0], v1[1]); w.w = pk2(v1[2], v1[3]); return w; }
; __device__ __forceinline__ void unpack8(const u32x4 w, f32x4& v0, f32x4& v1) { v0 = (f32x4){bflo(w.x), bfhi(w.x), bflo(w.y), bfhi(w.y)}; v1 = (f32x4){bflo(w.z), bfhi(w.z), bflo(w.w), bfhi(w.w)}; }
;     __device__ __forceinline__ void operator()(const f32x4 (&acc)[2][2][4][2], const Unit& u, int wr, int wc, int fr, int fq) const {
;     ...
;                 bf16_t* rowp = z + (size_t)(row0 + ai * 128 + m * 16) * DIN + col0;
; #pragma unroll
;                 for (int bj = 0; bj < 2; ++bj) {
;                     const u32x4 gw = *(const u32x4*)(rowp + (MODE == 0 ? O_GB : O_GA) + bj * 128);
;                     f32x4 g0, g1; unpack8(gw, g0, g1);
;                     f32x4 v0, v1;
; #pragma unroll
;                     for (int j = 0; j < 4; ++j) { v0[j] = sigmoidf_(g0[j]) * acc[ai][bj][m][0][j]; v1[j] = sigmoidf_(g1[j]) * acc[ai][bj][m][1][j]; }
;                     if (MODE == 1) { const u32x4 mw = *(const u32x4*)(rowp + bj * 128); f32x4 m0, m1; unpack8(mw, m0, m1); v0 += m0; v1 += m1; }
;                     *(u32x4*)(rowp + bj * 128) = pack8(v0, v1); }
	v_mov_b32_e32 v76, v240
	v_mov_b32_e32 v77, v241
	v_mov_b32_e32 v78, v242
	v_mov_b32_e32 v79, v243
	v_lshlrev_b32_e32 v83, 16, v79
	global_store_dwordx4 v[80:81], v[72:75], off sc1
	v_and_b32_e32 v79, 0xffff0000, v79
	s_nop 0
	v_lshlrev_b32_e32 v72, 16, v76
	v_mul_f32_e32 v72, 0xbfb8aa3b, v72
	v_exp_f32_e32 v72, v72
	v_lshlrev_b32_e32 v74, 16, v77
	v_and_b32_e32 v75, 0xffff0000, v77
	v_and_b32_e32 v73, 0xffff0000, v76
	v_add_f32_e32 v72, 1.0, v72
	v_div_scale_f32 v77, s[6:7], v72, v72, 1.0
	v_rcp_f32_e32 v82, v77
	v_lshlrev_b32_e32 v76, 16, v78
	v_mul_f32_e32 v76, 0xbfb8aa3b, v76
	v_exp_f32_e32 v76, v76
	v_fma_f32 v84, -v77, v82, 1.0
	v_fmac_f32_e32 v82, v84, v82
	v_div_scale_f32 v84, vcc, 1.0, v72, 1.0
	v_mul_f32_e32 v85, v84, v82
	v_fma_f32 v86, -v77, v85, v84
	v_fmac_f32_e32 v85, v86, v82
	v_add_f32_e32 v76, 1.0, v76
	v_fma_f32 v77, -v77, v85, v84
	v_div_scale_f32 v84, s[6:7], v76, v76, 1.0
	v_rcp_f32_e32 v86, v84
	v_div_fmas_f32 v77, v77, v82, v85
	v_mul_f32_e32 v73, 0xbfb8aa3b, v73
	v_div_fixup_f32 v72, v77, v72, 1.0
	v_exp_f32_e32 v73, v73
	v_mul_f32_e32 v68, v68, v72
	v_fma_f32 v72, -v84, v86, 1.0
	v_fmac_f32_e32 v86, v72, v86
	v_div_scale_f32 v72, vcc, 1.0, v76, 1.0
	v_mul_f32_e32 v77, v72, v86
	v_fma_f32 v82, -v84, v77, v72
	v_add_f32_e32 v73, 1.0, v73
	v_fmac_f32_e32 v77, v82, v86
	v_div_scale_f32 v82, s[6:7], v73, v73, 1.0
	v_fma_f32 v72, -v84, v77, v72
	v_rcp_f32_e32 v84, v82
	v_and_b32_e32 v78, 0xffff0000, v78
	v_div_fmas_f32 v72, v72, v86, v77
	v_mul_f32_e32 v77, 0xbfb8aa3b, v78
	v_div_fixup_f32 v72, v72, v76, 1.0
	v_exp_f32_e32 v77, v77
	v_mul_f32_e32 v64, v64, v72
	v_fma_f32 v72, -v82, v84, 1.0
	v_fmac_f32_e32 v84, v72, v84
	v_div_scale_f32 v72, vcc, 1.0, v73, 1.0
	v_mul_f32_e32 v76, v72, v84
	v_fma_f32 v78, -v82, v76, v72
	v_add_f32_e32 v77, 1.0, v77
	v_fmac_f32_e32 v76, v78, v84
	v_div_scale_f32 v78, s[6:7], v77, v77, 1.0
	v_fma_f32 v72, -v82, v76, v72
	v_rcp_f32_e32 v82, v78
	v_div_fmas_f32 v72, v72, v84, v76
	v_mul_f32_e32 v74, 0xbfb8aa3b, v74
	v_div_fixup_f32 v72, v72, v73, 1.0
	v_exp_f32_e32 v74, v74
	v_mul_f32_e32 v69, v69, v72
	v_fma_f32 v72, -v78, v82, 1.0
	v_fmac_f32_e32 v82, v72, v82
	v_div_scale_f32 v72, vcc, 1.0, v77, 1.0
	v_mul_f32_e32 v73, v72, v82
	v_fma_f32 v76, -v78, v73, v72
	v_add_f32_e32 v74, 1.0, v74
	v_fmac_f32_e32 v73, v76, v82
	v_div_scale_f32 v76, s[6:7], v74, v74, 1.0
	v_fma_f32 v72, -v78, v73, v72
	v_rcp_f32_e32 v78, v76
	v_div_fmas_f32 v72, v72, v82, v73
	v_div_fixup_f32 v72, v72, v77, 1.0
	v_mul_f32_e32 v65, v65, v72
	v_fma_f32 v72, -v76, v78, 1.0
	v_mul_f32_e32 v77, 0xbfb8aa3b, v83
	v_fmac_f32_e32 v78, v72, v78
	v_div_scale_f32 v72, vcc, 1.0, v74, 1.0
	v_exp_f32_e32 v77, v77
	v_mul_f32_e32 v73, v72, v78
	v_fma_f32 v82, -v76, v73, v72
	v_fmac_f32_e32 v73, v82, v78
	v_fma_f32 v72, -v76, v73, v72
	v_add_f32_e32 v76, 1.0, v77
	v_div_scale_f32 v77, s[6:7], v76, v76, 1.0
	v_rcp_f32_e32 v82, v77
	v_div_fmas_f32 v72, v72, v78, v73
	v_div_fixup_f32 v72, v72, v74, 1.0
	v_mul_f32_e32 v74, 0xbfb8aa3b, v75
	v_exp_f32_e32 v74, v74
	v_mul_f32_e32 v70, v70, v72
	v_fma_f32 v72, -v77, v82, 1.0
	v_fmac_f32_e32 v82, v72, v82
	v_div_scale_f32 v72, vcc, 1.0, v76, 1.0
	v_mul_f32_e32 v73, v72, v82
	v_fma_f32 v75, -v77, v73, v72
	v_add_f32_e32 v74, 1.0, v74
	v_fmac_f32_e32 v73, v75, v82
	v_div_scale_f32 v75, s[6:7], v74, v74, 1.0
	v_fma_f32 v72, -v77, v73, v72
	v_rcp_f32_e32 v77, v75
	v_div_fmas_f32 v72, v72, v82, v73
	v_div_fixup_f32 v72, v72, v76, 1.0
	v_mul_f32_e32 v72, v66, v72
	v_fma_f32 v66, -v75, v77, 1.0
	v_mul_f32_e32 v76, 0xbfb8aa3b, v79
	v_fmac_f32_e32 v77, v66, v77
	v_div_scale_f32 v66, vcc, 1.0, v74, 1.0
	v_exp_f32_e32 v76, v76
	v_mul_f32_e32 v73, v66, v77
	v_fma_f32 v78, -v75, v73, v66
	v_fmac_f32_e32 v73, v78, v77
	v_fma_f32 v66, -v75, v73, v66
	v_add_f32_e32 v75, 1.0, v76
	v_div_scale_f32 v76, s[6:7], v75, v75, 1.0
	v_rcp_f32_e32 v78, v76
	v_div_fmas_f32 v66, v66, v77, v73
	v_div_fixup_f32 v66, v66, v74, 1.0
	v_mul_f32_e32 v71, v71, v66
	v_fma_f32 v66, -v76, v78, 1.0
	v_fmac_f32_e32 v78, v66, v78
	v_div_scale_f32 v66, vcc, 1.0, v75, 1.0
	v_mul_f32_e32 v73, v66, v78
	v_fma_f32 v74, -v76, v73, v66
	v_fmac_f32_e32 v73, v74, v78
	v_fma_f32 v66, -v76, v73, v66
	v_div_fmas_f32 v66, v66, v78, v73
	v_div_fixup_f32 v66, v66, v75, 1.0
	v_mul_f32_e32 v73, v67, v66
	v_cvt_pk_bf16_f32 v66, v68, v69
	v_cvt_pk_bf16_f32 v67, v70, v71
	v_cvt_pk_bf16_f32 v68, v64, v65
	v_add_u32_e32 v64, 0x80, v160
	v_mad_i64_i32 v[64:65], s[6:7], v64, s61, v[146:147]
	v_lshl_add_u64 v[64:65], v[64:65], 0, v[148:149]
	v_add_co_u32_e32 v74, vcc, s62, v64
	v_cvt_pk_bf16_f32 v69, v72, v73
	global_store_dwordx4 v[80:81], v[66:69], off offset:256 sc1
	s_nop 0
	v_addc_co_u32_e32 v75, vcc, 0, v65, vcc
	s_waitcnt vmcnt(15)
; __device__ __forceinline__ float sigmoidf_(float x) { return 1.0f / (1.0f + __expf(-x)); }
; __device__ __forceinline__ u32x4 pack8(const f32x4 v0, const f32x4 v1) { u32x4 w; w.x = pk2(v0[0], v0[1]); w.y = pk2(v0[2], v0[3]); w.z = pk2(v1[0], v1[1]); w.w = pk2(v1[2], v1[3]); return w; }
; __device__ __forceinline__ void unpack8(const u32x4 w, f32x4& v0, f32x4& v1) { v0 = (f32x4){bflo(w.x), bfhi(w.x), bflo(w.y), bfhi(w.y)}; v1 = (f32x4){bflo(w.z), bfhi(w.z), bflo(w.w), bfhi(w.w)}; }
;     __device__ __forceinline__ void operator()(const f32x4 (&acc)[2][2][4][2], const Unit& u, int wr, int wc, int fr, int fq) const {
;     ...
;                     const u32x4 gw = *(const u32x4*)(rowp + (MODE == 0 ? O_GB : O_GA) + bj * 128);
;                     f32x4 g0, g1; unpack8(gw, g0, g1);
;                     f32x4 v0, v1;
; #pragma unroll
;                     for (int j = 0; j < 4; ++j) { v0[j] = sigmoidf_(g0[j]) * acc[ai][bj][m][0][j]; v1[j] = sigmoidf_(g1[j]) * acc[ai][bj][m][1][j]; }
;                     if (MODE == 1) { const u32x4 mw = *(const u32x4*)(rowp + bj * 128); f32x4 m0, m1; unpack8(mw, m0, m1); v0 += m0; v1 += m1; }
;                     *(u32x4*)(rowp + bj * 128) = pack8(v0, v1); }
	v_mov_b32_e32 v70, v244
	v_mov_b32_e32 v71, v245
	v_mov_b32_e32 v72, v246
	v_mov_b32_e32 v73, v247
	v_lshlrev_b32_e32 v66, 16, v70
	v_mul_f32_e32 v66, 0xbfb8aa3b, v66
	v_exp_f32_e32 v66, v66
	v_lshlrev_b32_e32 v68, 16, v71
	v_and_b32_e32 v69, 0xffff0000, v71
	v_and_b32_e32 v67, 0xffff0000, v70
	v_add_f32_e32 v66, 1.0, v66
	v_div_scale_f32 v71, s[6:7], v66, v66, 1.0
	v_rcp_f32_e32 v76, v71
	v_lshlrev_b32_e32 v70, 16, v72
	v_mul_f32_e32 v70, 0xbfb8aa3b, v70
	v_exp_f32_e32 v70, v70
	v_fma_f32 v78, -v71, v76, 1.0
	v_fmac_f32_e32 v76, v78, v76
	v_div_scale_f32 v78, vcc, 1.0, v66, 1.0
	v_mul_f32_e32 v79, v78, v76
	v_fma_f32 v80, -v71, v79, v78
	v_fmac_f32_e32 v79, v80, v76
	v_add_f32_e32 v70, 1.0, v70
	v_fma_f32 v71, -v71, v79, v78
	v_div_scale_f32 v78, s[6:7], v70, v70, 1.0
	v_rcp_f32_e32 v80, v78
	v_div_fmas_f32 v71, v71, v76, v79
	v_mul_f32_e32 v67, 0xbfb8aa3b, v67
	v_div_fixup_f32 v66, v71, v66, 1.0
	v_exp_f32_e32 v67, v67
	v_mul_f32_e32 v60, v60, v66
	v_fma_f32 v66, -v78, v80, 1.0
	v_fmac_f32_e32 v80, v66, v80
	v_div_scale_f32 v66, vcc, 1.0, v70, 1.0
	v_mul_f32_e32 v71, v66, v80
	v_fma_f32 v76, -v78, v71, v66
	v_add_f32_e32 v67, 1.0, v67
	v_fmac_f32_e32 v71, v76, v80
	v_div_scale_f32 v76, s[6:7], v67, v67, 1.0
	v_fma_f32 v66, -v78, v71, v66
	v_rcp_f32_e32 v78, v76
	v_and_b32_e32 v72, 0xffff0000, v72
	v_div_fmas_f32 v66, v66, v80, v71
	v_mul_f32_e32 v71, 0xbfb8aa3b, v72
	v_div_fixup_f32 v66, v66, v70, 1.0
	v_exp_f32_e32 v71, v71
	v_mul_f32_e32 v66, v56, v66
	v_fma_f32 v56, -v76, v78, 1.0
	v_fmac_f32_e32 v78, v56, v78
	v_div_scale_f32 v56, vcc, 1.0, v67, 1.0
	v_mul_f32_e32 v70, v56, v78
	v_fma_f32 v72, -v76, v70, v56
	v_add_f32_e32 v71, 1.0, v71
	v_fmac_f32_e32 v70, v72, v78
	v_div_scale_f32 v72, s[6:7], v71, v71, 1.0
	v_fma_f32 v56, -v76, v70, v56
	v_rcp_f32_e32 v76, v72
	v_div_fmas_f32 v56, v56, v78, v70
	v_mul_f32_e32 v68, 0xbfb8aa3b, v68
	v_div_fixup_f32 v56, v56, v67, 1.0
	v_exp_f32_e32 v68, v68
	v_mul_f32_e32 v56, v61, v56
	v_fma_f32 v61, -v72, v76, 1.0
	v_fmac_f32_e32 v76, v61, v76
	v_div_scale_f32 v61, vcc, 1.0, v71, 1.0
	v_mul_f32_e32 v67, v61, v76
	v_fma_f32 v70, -v72, v67, v61
	v_add_f32_e32 v68, 1.0, v68
	v_fmac_f32_e32 v67, v70, v76
	v_div_scale_f32 v70, s[6:7], v68, v68, 1.0
	v_fma_f32 v61, -v72, v67, v61
	v_rcp_f32_e32 v72, v70
	v_div_fmas_f32 v61, v61, v76, v67
	v_lshlrev_b32_e32 v77, 16, v73
	v_div_fixup_f32 v61, v61, v71, 1.0
	v_mul_f32_e32 v61, v57, v61
	v_fma_f32 v57, -v70, v72, 1.0
	v_mul_f32_e32 v71, 0xbfb8aa3b, v77
	v_fmac_f32_e32 v72, v57, v72
	v_div_scale_f32 v57, vcc, 1.0, v68, 1.0
	v_exp_f32_e32 v71, v71
	v_mul_f32_e32 v67, v57, v72
	v_fma_f32 v76, -v70, v67, v57
	v_fmac_f32_e32 v67, v76, v72
	v_fma_f32 v57, -v70, v67, v57
	v_add_f32_e32 v70, 1.0, v71
	v_div_scale_f32 v71, s[6:7], v70, v70, 1.0
	v_rcp_f32_e32 v76, v71
	v_div_fmas_f32 v57, v57, v72, v67
	v_div_fixup_f32 v57, v57, v68, 1.0
	v_mul_f32_e32 v68, 0xbfb8aa3b, v69
	v_exp_f32_e32 v68, v68
	v_mul_f32_e32 v57, v62, v57
	v_fma_f32 v62, -v71, v76, 1.0
	v_fmac_f32_e32 v76, v62, v76
	v_div_scale_f32 v62, vcc, 1.0, v70, 1.0
	v_mul_f32_e32 v67, v62, v76
	v_fma_f32 v69, -v71, v67, v62
	v_add_f32_e32 v68, 1.0, v68
	v_fmac_f32_e32 v67, v69, v76
	v_div_scale_f32 v69, s[6:7], v68, v68, 1.0
	v_fma_f32 v62, -v71, v67, v62
	v_rcp_f32_e32 v71, v69
	v_div_fmas_f32 v62, v62, v76, v67
	v_and_b32_e32 v73, 0xffff0000, v73
	v_div_fixup_f32 v62, v62, v70, 1.0
	v_mul_f32_e32 v62, v58, v62
	v_fma_f32 v58, -v69, v71, 1.0
	v_mul_f32_e32 v70, 0xbfb8aa3b, v73
	v_fmac_f32_e32 v71, v58, v71
	v_div_scale_f32 v58, vcc, 1.0, v68, 1.0
	v_exp_f32_e32 v70, v70
	v_mul_f32_e32 v67, v58, v71
	v_fma_f32 v72, -v69, v67, v58
	v_fmac_f32_e32 v67, v72, v71
	v_fma_f32 v58, -v69, v67, v58
	v_add_f32_e32 v69, 1.0, v70
	v_div_scale_f32 v70, s[6:7], v69, v69, 1.0
	v_rcp_f32_e32 v72, v70
	v_div_fmas_f32 v58, v58, v71, v67
	v_div_fixup_f32 v58, v58, v68, 1.0
	v_mul_f32_e32 v58, v63, v58
	v_fma_f32 v63, -v70, v72, 1.0
	v_fmac_f32_e32 v72, v63, v72
	v_div_scale_f32 v63, vcc, 1.0, v69, 1.0
	v_mul_f32_e32 v67, v63, v72
	v_fma_f32 v68, -v70, v67, v63
	v_fmac_f32_e32 v67, v68, v72
	v_fma_f32 v63, -v70, v67, v63
	v_div_fmas_f32 v63, v63, v72, v67
	v_div_fixup_f32 v63, v63, v69, 1.0
	v_mul_f32_e32 v59, v59, v63
	v_cvt_pk_bf16_f32 v56, v60, v56
	v_cvt_pk_bf16_f32 v57, v57, v58
	v_cvt_pk_bf16_f32 v58, v66, v61
	v_cvt_pk_bf16_f32 v59, v62, v59
	s_waitcnt vmcnt(14)
; __device__ __forceinline__ float sigmoidf_(float x) { return 1.0f / (1.0f + __expf(-x)); }
; __device__ __forceinline__ u32x4 pack8(const f32x4 v0, const f32x4 v1) { u32x4 w; w.x = pk2(v0[0], v0[1]); w.y = pk2(v0[2], v0[3]); w.z = pk2(v1[0], v1[1]); w.w = pk2(v1[2], v1[3]); return w; }
; __device__ __forceinline__ void unpack8(const u32x4 w, f32x4& v0, f32x4& v1) { v0 = (f32x4){bflo(w.x), bfhi(w.x), bflo(w.y), bfhi(w.y)}; v1 = (f32x4){bflo(w.z), bfhi(w.z), bflo(w.w), bfhi(w.w)}; }
;     __device__ __forceinline__ void operator()(const f32x4 (&acc)[2][2][4][2], const Unit& u, int wr, int wc, int fr, int fq) const {
;     ...
;                 bf16_t* rowp = z + (size_t)(row0 + ai * 128 + m * 16) * DIN + col0;
; #pragma unroll
;                 for (int bj = 0; bj < 2; ++bj) {
;                     const u32x4 gw = *(const u32x4*)(rowp + (MODE == 0 ? O_GB : O_GA) + bj * 128);
;                     f32x4 g0, g1; unpack8(gw, g0, g1);
;                     f32x4 v0, v1;
; #pragma unroll
;                     for (int j = 0; j < 4; ++j) { v0[j] = sigmoidf_(g0[j]) * acc[ai][bj][m][0][j]; v1[j] = sigmoidf_(g1[j]) * acc[ai][bj][m][1][j]; }
;                     if (MODE == 1) { const u32x4 mw = *(const u32x4*)(rowp + bj * 128); f32x4 m0, m1; unpack8(mw, m0, m1); v0 += m0; v1 += m1; }
;                     *(u32x4*)(rowp + bj * 128) = pack8(v0, v1); }
	v_mov_b32_e32 v60, v248
	v_mov_b32_e32 v61, v249
	v_mov_b32_e32 v62, v250
	v_mov_b32_e32 v63, v251
	v_lshlrev_b32_e32 v67, 16, v63
	global_store_dwordx4 v[64:65], v[56:59], off sc1
	v_and_b32_e32 v63, 0xffff0000, v63
	s_nop 0
	v_lshlrev_b32_e32 v56, 16, v60
	v_mul_f32_e32 v56, 0xbfb8aa3b, v56
	v_exp_f32_e32 v56, v56
	v_lshlrev_b32_e32 v58, 16, v61
	v_and_b32_e32 v59, 0xffff0000, v61
	v_and_b32_e32 v57, 0xffff0000, v60
	v_add_f32_e32 v56, 1.0, v56
	v_div_scale_f32 v61, s[6:7], v56, v56, 1.0
	v_rcp_f32_e32 v66, v61
	v_lshlrev_b32_e32 v60, 16, v62
	v_mul_f32_e32 v60, 0xbfb8aa3b, v60
	v_exp_f32_e32 v60, v60
	v_fma_f32 v68, -v61, v66, 1.0
	v_fmac_f32_e32 v66, v68, v66
	v_div_scale_f32 v68, vcc, 1.0, v56, 1.0
	v_mul_f32_e32 v69, v68, v66
	v_fma_f32 v70, -v61, v69, v68
	v_fmac_f32_e32 v69, v70, v66
	v_add_f32_e32 v60, 1.0, v60
	v_fma_f32 v61, -v61, v69, v68
	v_div_scale_f32 v68, s[6:7], v60, v60, 1.0
	v_rcp_f32_e32 v70, v68
	v_div_fmas_f32 v61, v61, v66, v69
	v_mul_f32_e32 v57, 0xbfb8aa3b, v57
	v_div_fixup_f32 v56, v61, v56, 1.0
	v_exp_f32_e32 v57, v57
	v_mul_f32_e32 v52, v52, v56
	v_fma_f32 v56, -v68, v70, 1.0
	v_fmac_f32_e32 v70, v56, v70
	v_div_scale_f32 v56, vcc, 1.0, v60, 1.0
	v_mul_f32_e32 v61, v56, v70
	v_fma_f32 v66, -v68, v61, v56
	v_add_f32_e32 v57, 1.0, v57
	v_fmac_f32_e32 v61, v66, v70
	v_div_scale_f32 v66, s[6:7], v57, v57, 1.0
	v_fma_f32 v56, -v68, v61, v56
	v_rcp_f32_e32 v68, v66
	v_and_b32_e32 v62, 0xffff0000, v62
	v_div_fmas_f32 v56, v56, v70, v61
	v_mul_f32_e32 v61, 0xbfb8aa3b, v62
	v_div_fixup_f32 v56, v56, v60, 1.0
	v_exp_f32_e32 v61, v61
	v_mul_f32_e32 v48, v48, v56
	v_fma_f32 v56, -v66, v68, 1.0
	v_fmac_f32_e32 v68, v56, v68
	v_div_scale_f32 v56, vcc, 1.0, v57, 1.0
	v_mul_f32_e32 v60, v56, v68
	v_fma_f32 v62, -v66, v60, v56
	v_add_f32_e32 v61, 1.0, v61
	v_fmac_f32_e32 v60, v62, v68
	v_div_scale_f32 v62, s[6:7], v61, v61, 1.0
	v_fma_f32 v56, -v66, v60, v56
	v_rcp_f32_e32 v66, v62
	v_div_fmas_f32 v56, v56, v68, v60
	v_mul_f32_e32 v58, 0xbfb8aa3b, v58
	v_div_fixup_f32 v56, v56, v57, 1.0
	v_exp_f32_e32 v58, v58
	v_mul_f32_e32 v53, v53, v56
	v_fma_f32 v56, -v62, v66, 1.0
	v_fmac_f32_e32 v66, v56, v66
	v_div_scale_f32 v56, vcc, 1.0, v61, 1.0
	v_mul_f32_e32 v57, v56, v66
	v_fma_f32 v60, -v62, v57, v56
	v_add_f32_e32 v58, 1.0, v58
	v_fmac_f32_e32 v57, v60, v66
	v_div_scale_f32 v60, s[6:7], v58, v58, 1.0
	v_fma_f32 v56, -v62, v57, v56
	v_rcp_f32_e32 v62, v60
	v_div_fmas_f32 v56, v56, v66, v57
	v_div_fixup_f32 v56, v56, v61, 1.0
	v_mul_f32_e32 v49, v49, v56
	v_fma_f32 v56, -v60, v62, 1.0
	v_mul_f32_e32 v61, 0xbfb8aa3b, v67
	v_fmac_f32_e32 v62, v56, v62
	v_div_scale_f32 v56, vcc, 1.0, v58, 1.0
	v_exp_f32_e32 v61, v61
	v_mul_f32_e32 v57, v56, v62
	v_fma_f32 v66, -v60, v57, v56
	v_fmac_f32_e32 v57, v66, v62
	v_fma_f32 v56, -v60, v57, v56
	v_add_f32_e32 v60, 1.0, v61
	v_div_scale_f32 v61, s[6:7], v60, v60, 1.0
	v_rcp_f32_e32 v66, v61
	v_div_fmas_f32 v56, v56, v62, v57
	v_div_fixup_f32 v56, v56, v58, 1.0
	v_mul_f32_e32 v58, 0xbfb8aa3b, v59
	v_exp_f32_e32 v58, v58
	v_mul_f32_e32 v54, v54, v56
	v_fma_f32 v56, -v61, v66, 1.0
	v_fmac_f32_e32 v66, v56, v66
	v_div_scale_f32 v56, vcc, 1.0, v60, 1.0
	v_mul_f32_e32 v57, v56, v66
	v_fma_f32 v59, -v61, v57, v56
	v_add_f32_e32 v58, 1.0, v58
	v_fmac_f32_e32 v57, v59, v66
	v_div_scale_f32 v59, s[6:7], v58, v58, 1.0
	v_fma_f32 v56, -v61, v57, v56
	v_rcp_f32_e32 v61, v59
	v_div_fmas_f32 v56, v56, v66, v57
	v_div_fixup_f32 v56, v56, v60, 1.0
	v_mul_f32_e32 v56, v50, v56
	v_fma_f32 v50, -v59, v61, 1.0
	v_mul_f32_e32 v60, 0xbfb8aa3b, v63
	v_fmac_f32_e32 v61, v50, v61
	v_div_scale_f32 v50, vcc, 1.0, v58, 1.0
	v_exp_f32_e32 v60, v60
	v_mul_f32_e32 v57, v50, v61
	v_fma_f32 v62, -v59, v57, v50
	v_fmac_f32_e32 v57, v62, v61
	v_fma_f32 v50, -v59, v57, v50
	v_add_f32_e32 v59, 1.0, v60
	v_div_scale_f32 v60, s[6:7], v59, v59, 1.0
	v_rcp_f32_e32 v62, v60
	v_div_fmas_f32 v50, v50, v61, v57
	v_div_fixup_f32 v50, v50, v58, 1.0
	v_mul_f32_e32 v55, v55, v50
	v_fma_f32 v50, -v60, v62, 1.0
	v_fmac_f32_e32 v62, v50, v62
	v_div_scale_f32 v50, vcc, 1.0, v59, 1.0
	v_mul_f32_e32 v57, v50, v62
	v_fma_f32 v58, -v60, v57, v50
	v_fmac_f32_e32 v57, v58, v62
	v_fma_f32 v50, -v60, v57, v50
	v_div_fmas_f32 v50, v50, v62, v57
	v_div_fixup_f32 v50, v50, v59, 1.0
	v_mul_f32_e32 v57, v51, v50
	v_cvt_pk_bf16_f32 v50, v52, v53
	v_cvt_pk_bf16_f32 v51, v54, v55
	v_cvt_pk_bf16_f32 v52, v48, v49
	v_add_u32_e32 v48, 0x90, v160
	v_mad_i64_i32 v[48:49], s[6:7], v48, s61, v[146:147]
	v_lshl_add_u64 v[48:49], v[48:49], 0, v[148:149]
	v_add_co_u32_e32 v58, vcc, s62, v48
	v_cvt_pk_bf16_f32 v53, v56, v57
	global_store_dwordx4 v[64:65], v[50:53], off offset:256 sc1
	s_nop 0
	v_addc_co_u32_e32 v59, vcc, 0, v49, vcc
	s_waitcnt vmcnt(15)
; __device__ __forceinline__ float sigmoidf_(float x) { return 1.0f / (1.0f + __expf(-x)); }
; __device__ __forceinline__ u32x4 pack8(const f32x4 v0, const f32x4 v1) { u32x4 w; w.x = pk2(v0[0], v0[1]); w.y = pk2(v0[2], v0[3]); w.z = pk2(v1[0], v1[1]); w.w = pk2(v1[2], v1[3]); return w; }
; __device__ __forceinline__ void unpack8(const u32x4 w, f32x4& v0, f32x4& v1) { v0 = (f32x4){bflo(w.x), bfhi(w.x), bflo(w.y), bfhi(w.y)}; v1 = (f32x4){bflo(w.z), bfhi(w.z), bflo(w.w), bfhi(w.w)}; }
;     __device__ __forceinline__ void operator()(const f32x4 (&acc)[2][2][4][2], const Unit& u, int wr, int wc, int fr, int fq) const {
;     ...
;                     const u32x4 gw = *(const u32x4*)(rowp + (MODE == 0 ? O_GB : O_GA) + bj * 128);
;                     f32x4 g0, g1; unpack8(gw, g0, g1);
;                     f32x4 v0, v1;
; #pragma unroll
;                     for (int j = 0; j < 4; ++j) { v0[j] = sigmoidf_(g0[j]) * acc[ai][bj][m][0][j]; v1[j] = sigmoidf_(g1[j]) * acc[ai][bj][m][1][j]; }
;                     if (MODE == 1) { const u32x4 mw = *(const u32x4*)(rowp + bj * 128); f32x4 m0, m1; unpack8(mw, m0, m1); v0 += m0; v1 += m1; }
;                     *(u32x4*)(rowp + bj * 128) = pack8(v0, v1); }
	v_mov_b32_e32 v54, v252
	v_mov_b32_e32 v55, v253
	v_mov_b32_e32 v56, v254
	v_mov_b32_e32 v57, v255
	v_lshlrev_b32_e32 v50, 16, v54
	v_mul_f32_e32 v50, 0xbfb8aa3b, v50
	v_exp_f32_e32 v50, v50
	v_lshlrev_b32_e32 v52, 16, v55
	v_and_b32_e32 v53, 0xffff0000, v55
	v_and_b32_e32 v51, 0xffff0000, v54
	v_add_f32_e32 v50, 1.0, v50
	v_div_scale_f32 v55, s[6:7], v50, v50, 1.0
	v_rcp_f32_e32 v60, v55
	v_lshlrev_b32_e32 v54, 16, v56
	v_mul_f32_e32 v54, 0xbfb8aa3b, v54
	v_exp_f32_e32 v54, v54
	v_fma_f32 v62, -v55, v60, 1.0
	v_fmac_f32_e32 v60, v62, v60
	v_div_scale_f32 v62, vcc, 1.0, v50, 1.0
	v_mul_f32_e32 v63, v62, v60
	v_fma_f32 v64, -v55, v63, v62
	v_fmac_f32_e32 v63, v64, v60
	v_add_f32_e32 v54, 1.0, v54
	v_fma_f32 v55, -v55, v63, v62
	v_div_scale_f32 v62, s[6:7], v54, v54, 1.0
	v_rcp_f32_e32 v64, v62
	v_div_fmas_f32 v55, v55, v60, v63
	v_mul_f32_e32 v51, 0xbfb8aa3b, v51
	v_div_fixup_f32 v50, v55, v50, 1.0
	v_exp_f32_e32 v51, v51
	v_mul_f32_e32 v44, v44, v50
	v_fma_f32 v50, -v62, v64, 1.0
	v_fmac_f32_e32 v64, v50, v64
	v_div_scale_f32 v50, vcc, 1.0, v54, 1.0
	v_mul_f32_e32 v55, v50, v64
	v_fma_f32 v60, -v62, v55, v50
	v_add_f32_e32 v51, 1.0, v51
	v_fmac_f32_e32 v55, v60, v64
	v_div_scale_f32 v60, s[6:7], v51, v51, 1.0
	v_fma_f32 v50, -v62, v55, v50
	v_rcp_f32_e32 v62, v60
	v_and_b32_e32 v56, 0xffff0000, v56
	v_div_fmas_f32 v50, v50, v64, v55
	v_mul_f32_e32 v55, 0xbfb8aa3b, v56
	v_div_fixup_f32 v50, v50, v54, 1.0
	v_exp_f32_e32 v55, v55
	v_mul_f32_e32 v50, v40, v50
	v_fma_f32 v40, -v60, v62, 1.0
	v_fmac_f32_e32 v62, v40, v62
	v_div_scale_f32 v40, vcc, 1.0, v51, 1.0
	v_mul_f32_e32 v54, v40, v62
	v_fma_f32 v56, -v60, v54, v40
	v_add_f32_e32 v55, 1.0, v55
	v_fmac_f32_e32 v54, v56, v62
	v_div_scale_f32 v56, s[6:7], v55, v55, 1.0
	v_fma_f32 v40, -v60, v54, v40
	v_rcp_f32_e32 v60, v56
	v_div_fmas_f32 v40, v40, v62, v54
	v_mul_f32_e32 v52, 0xbfb8aa3b, v52
	v_div_fixup_f32 v40, v40, v51, 1.0
	v_exp_f32_e32 v52, v52
	v_mul_f32_e32 v40, v45, v40
	v_fma_f32 v45, -v56, v60, 1.0
	v_fmac_f32_e32 v60, v45, v60
	v_div_scale_f32 v45, vcc, 1.0, v55, 1.0
	v_mul_f32_e32 v51, v45, v60
	v_fma_f32 v54, -v56, v51, v45
	v_add_f32_e32 v52, 1.0, v52
	v_fmac_f32_e32 v51, v54, v60
	v_div_scale_f32 v54, s[6:7], v52, v52, 1.0
	v_fma_f32 v45, -v56, v51, v45
	v_rcp_f32_e32 v56, v54
	v_div_fmas_f32 v45, v45, v60, v51
	v_lshlrev_b32_e32 v61, 16, v57
	v_div_fixup_f32 v45, v45, v55, 1.0
	v_mul_f32_e32 v45, v41, v45
	v_fma_f32 v41, -v54, v56, 1.0
	v_mul_f32_e32 v55, 0xbfb8aa3b, v61
	v_fmac_f32_e32 v56, v41, v56
	v_div_scale_f32 v41, vcc, 1.0, v52, 1.0
	v_exp_f32_e32 v55, v55
	v_mul_f32_e32 v51, v41, v56
	v_fma_f32 v60, -v54, v51, v41
	v_fmac_f32_e32 v51, v60, v56
	v_fma_f32 v41, -v54, v51, v41
	v_add_f32_e32 v54, 1.0, v55
	v_div_scale_f32 v55, s[6:7], v54, v54, 1.0
	v_rcp_f32_e32 v60, v55
	v_div_fmas_f32 v41, v41, v56, v51
	v_div_fixup_f32 v41, v41, v52, 1.0
	v_mul_f32_e32 v52, 0xbfb8aa3b, v53
	v_exp_f32_e32 v52, v52
	v_mul_f32_e32 v41, v46, v41
	v_fma_f32 v46, -v55, v60, 1.0
	v_fmac_f32_e32 v60, v46, v60
	v_div_scale_f32 v46, vcc, 1.0, v54, 1.0
	v_mul_f32_e32 v51, v46, v60
	v_fma_f32 v53, -v55, v51, v46
	v_add_f32_e32 v52, 1.0, v52
	v_fmac_f32_e32 v51, v53, v60
	v_div_scale_f32 v53, s[6:7], v52, v52, 1.0
	v_fma_f32 v46, -v55, v51, v46
	v_rcp_f32_e32 v55, v53
	v_div_fmas_f32 v46, v46, v60, v51
	v_and_b32_e32 v57, 0xffff0000, v57
	v_div_fixup_f32 v46, v46, v54, 1.0
	v_mul_f32_e32 v46, v42, v46
	v_fma_f32 v42, -v53, v55, 1.0
	v_mul_f32_e32 v54, 0xbfb8aa3b, v57
	v_fmac_f32_e32 v55, v42, v55
	v_div_scale_f32 v42, vcc, 1.0, v52, 1.0
	v_exp_f32_e32 v54, v54
	v_mul_f32_e32 v51, v42, v55
	v_fma_f32 v56, -v53, v51, v42
	v_fmac_f32_e32 v51, v56, v55
	v_fma_f32 v42, -v53, v51, v42
	v_add_f32_e32 v53, 1.0, v54
	v_div_scale_f32 v54, s[6:7], v53, v53, 1.0
	v_rcp_f32_e32 v56, v54
	v_div_fmas_f32 v42, v42, v55, v51
	v_div_fixup_f32 v42, v42, v52, 1.0
	v_mul_f32_e32 v42, v47, v42
	v_fma_f32 v47, -v54, v56, 1.0
	v_fmac_f32_e32 v56, v47, v56
	v_div_scale_f32 v47, vcc, 1.0, v53, 1.0
	v_mul_f32_e32 v51, v47, v56
	v_fma_f32 v52, -v54, v51, v47
	v_fmac_f32_e32 v51, v52, v56
	v_fma_f32 v47, -v54, v51, v47
	v_div_fmas_f32 v47, v47, v56, v51
	v_div_fixup_f32 v47, v47, v53, 1.0
	v_mul_f32_e32 v43, v43, v47
	v_cvt_pk_bf16_f32 v40, v44, v40
	v_cvt_pk_bf16_f32 v41, v41, v42
	v_cvt_pk_bf16_f32 v42, v50, v45
	v_cvt_pk_bf16_f32 v43, v46, v43
	s_waitcnt vmcnt(14)
; __device__ __forceinline__ float sigmoidf_(float x) { return 1.0f / (1.0f + __expf(-x)); }
; __device__ __forceinline__ u32x4 pack8(const f32x4 v0, const f32x4 v1) { u32x4 w; w.x = pk2(v0[0], v0[1]); w.y = pk2(v0[2], v0[3]); w.z = pk2(v1[0], v1[1]); w.w = pk2(v1[2], v1[3]); return w; }
; __device__ __forceinline__ void unpack8(const u32x4 w, f32x4& v0, f32x4& v1) { v0 = (f32x4){bflo(w.x), bfhi(w.x), bflo(w.y), bfhi(w.y)}; v1 = (f32x4){bflo(w.z), bfhi(w.z), bflo(w.w), bfhi(w.w)}; }
;     __device__ __forceinline__ void operator()(const f32x4 (&acc)[2][2][4][2], const Unit& u, int wr, int wc, int fr, int fq) const {
;     ...
;                 bf16_t* rowp = z + (size_t)(row0 + ai * 128 + m * 16) * DIN + col0;
; #pragma unroll
;                 for (int bj = 0; bj < 2; ++bj) {
;                     const u32x4 gw = *(const u32x4*)(rowp + (MODE == 0 ? O_GB : O_GA) + bj * 128);
;                     f32x4 g0, g1; unpack8(gw, g0, g1);
;                     f32x4 v0, v1;
; #pragma unroll
;                     for (int j = 0; j < 4; ++j) { v0[j] = sigmoidf_(g0[j]) * acc[ai][bj][m][0][j]; v1[j] = sigmoidf_(g1[j]) * acc[ai][bj][m][1][j]; }
;                     if (MODE == 1) { const u32x4 mw = *(const u32x4*)(rowp + bj * 128); f32x4 m0, m1; unpack8(mw, m0, m1); v0 += m0; v1 += m1; }
;                     *(u32x4*)(rowp + bj * 128) = pack8(v0, v1); }
	v_mov_b32_e32 v44, v200
	v_mov_b32_e32 v45, v201
	v_mov_b32_e32 v46, v202
	v_mov_b32_e32 v47, v203
	v_lshlrev_b32_e32 v51, 16, v47
	global_store_dwordx4 v[48:49], v[40:43], off sc1
	v_and_b32_e32 v47, 0xffff0000, v47
	s_nop 0
	v_lshlrev_b32_e32 v40, 16, v44
	v_mul_f32_e32 v40, 0xbfb8aa3b, v40
	v_exp_f32_e32 v40, v40
	v_lshlrev_b32_e32 v42, 16, v45
	v_and_b32_e32 v43, 0xffff0000, v45
	v_and_b32_e32 v41, 0xffff0000, v44
	v_add_f32_e32 v40, 1.0, v40
	v_div_scale_f32 v45, s[6:7], v40, v40, 1.0
	v_rcp_f32_e32 v50, v45
	v_lshlrev_b32_e32 v44, 16, v46
	v_mul_f32_e32 v44, 0xbfb8aa3b, v44
	v_exp_f32_e32 v44, v44
	v_fma_f32 v52, -v45, v50, 1.0
	v_fmac_f32_e32 v50, v52, v50
	v_div_scale_f32 v52, vcc, 1.0, v40, 1.0
	v_mul_f32_e32 v53, v52, v50
	v_fma_f32 v54, -v45, v53, v52
	v_fmac_f32_e32 v53, v54, v50
	v_add_f32_e32 v44, 1.0, v44
	v_fma_f32 v45, -v45, v53, v52
	v_div_scale_f32 v52, s[6:7], v44, v44, 1.0
	v_rcp_f32_e32 v54, v52
	v_div_fmas_f32 v45, v45, v50, v53
	v_mul_f32_e32 v41, 0xbfb8aa3b, v41
	v_div_fixup_f32 v40, v45, v40, 1.0
	v_exp_f32_e32 v41, v41
	v_mul_f32_e32 v36, v36, v40
	v_fma_f32 v40, -v52, v54, 1.0
	v_fmac_f32_e32 v54, v40, v54
	v_div_scale_f32 v40, vcc, 1.0, v44, 1.0
	v_mul_f32_e32 v45, v40, v54
	v_fma_f32 v50, -v52, v45, v40
	v_add_f32_e32 v41, 1.0, v41
	v_fmac_f32_e32 v45, v50, v54
	v_div_scale_f32 v50, s[6:7], v41, v41, 1.0
	v_fma_f32 v40, -v52, v45, v40
	v_rcp_f32_e32 v52, v50
	v_and_b32_e32 v46, 0xffff0000, v46
	v_div_fmas_f32 v40, v40, v54, v45
	v_mul_f32_e32 v45, 0xbfb8aa3b, v46
	v_div_fixup_f32 v40, v40, v44, 1.0
	v_exp_f32_e32 v45, v45
	v_mul_f32_e32 v32, v32, v40
	v_fma_f32 v40, -v50, v52, 1.0
	v_fmac_f32_e32 v52, v40, v52
	v_div_scale_f32 v40, vcc, 1.0, v41, 1.0
	v_mul_f32_e32 v44, v40, v52
	v_fma_f32 v46, -v50, v44, v40
	v_add_f32_e32 v45, 1.0, v45
	v_fmac_f32_e32 v44, v46, v52
	v_div_scale_f32 v46, s[6:7], v45, v45, 1.0
	v_fma_f32 v40, -v50, v44, v40
	v_rcp_f32_e32 v50, v46
	v_div_fmas_f32 v40, v40, v52, v44
	v_mul_f32_e32 v42, 0xbfb8aa3b, v42
	v_div_fixup_f32 v40, v40, v41, 1.0
	v_exp_f32_e32 v42, v42
	v_mul_f32_e32 v37, v37, v40
	v_fma_f32 v40, -v46, v50, 1.0
	v_fmac_f32_e32 v50, v40, v50
	v_div_scale_f32 v40, vcc, 1.0, v45, 1.0
	v_mul_f32_e32 v41, v40, v50
	v_fma_f32 v44, -v46, v41, v40
	v_add_f32_e32 v42, 1.0, v42
	v_fmac_f32_e32 v41, v44, v50
	v_div_scale_f32 v44, s[6:7], v42, v42, 1.0
	v_fma_f32 v40, -v46, v41, v40
	v_rcp_f32_e32 v46, v44
	v_div_fmas_f32 v40, v40, v50, v41
	v_div_fixup_f32 v40, v40, v45, 1.0
	v_mul_f32_e32 v33, v33, v40
	v_fma_f32 v40, -v44, v46, 1.0
	v_mul_f32_e32 v45, 0xbfb8aa3b, v51
	v_fmac_f32_e32 v46, v40, v46
	v_div_scale_f32 v40, vcc, 1.0, v42, 1.0
	v_exp_f32_e32 v45, v45
	v_mul_f32_e32 v41, v40, v46
	v_fma_f32 v50, -v44, v41, v40
	v_fmac_f32_e32 v41, v50, v46
	v_fma_f32 v40, -v44, v41, v40
	v_add_f32_e32 v44, 1.0, v45
	v_div_scale_f32 v45, s[6:7], v44, v44, 1.0
	v_rcp_f32_e32 v50, v45
	v_div_fmas_f32 v40, v40, v46, v41
	v_div_fixup_f32 v40, v40, v42, 1.0
	v_mul_f32_e32 v42, 0xbfb8aa3b, v43
	v_exp_f32_e32 v42, v42
	v_mul_f32_e32 v38, v38, v40
	v_fma_f32 v40, -v45, v50, 1.0
	v_fmac_f32_e32 v50, v40, v50
	v_div_scale_f32 v40, vcc, 1.0, v44, 1.0
	v_mul_f32_e32 v41, v40, v50
	v_fma_f32 v43, -v45, v41, v40
	v_add_f32_e32 v42, 1.0, v42
	v_fmac_f32_e32 v41, v43, v50
	v_div_scale_f32 v43, s[6:7], v42, v42, 1.0
	v_fma_f32 v40, -v45, v41, v40
	v_rcp_f32_e32 v45, v43
	v_div_fmas_f32 v40, v40, v50, v41
	v_div_fixup_f32 v40, v40, v44, 1.0
	v_mul_f32_e32 v40, v34, v40
	v_fma_f32 v34, -v43, v45, 1.0
	v_mul_f32_e32 v44, 0xbfb8aa3b, v47
	v_fmac_f32_e32 v45, v34, v45
	v_div_scale_f32 v34, vcc, 1.0, v42, 1.0
	v_exp_f32_e32 v44, v44
	v_mul_f32_e32 v41, v34, v45
	v_fma_f32 v46, -v43, v41, v34
	v_fmac_f32_e32 v41, v46, v45
	v_fma_f32 v34, -v43, v41, v34
	v_add_f32_e32 v43, 1.0, v44
	v_div_scale_f32 v44, s[6:7], v43, v43, 1.0
	v_rcp_f32_e32 v46, v44
	v_div_fmas_f32 v34, v34, v45, v41
	v_div_fixup_f32 v34, v34, v42, 1.0
	v_mul_f32_e32 v39, v39, v34
	v_fma_f32 v34, -v44, v46, 1.0
	v_fmac_f32_e32 v46, v34, v46
	v_div_scale_f32 v34, vcc, 1.0, v43, 1.0
	v_mul_f32_e32 v41, v34, v46
	v_fma_f32 v42, -v44, v41, v34
	v_fmac_f32_e32 v41, v42, v46
	v_fma_f32 v34, -v44, v41, v34
	v_div_fmas_f32 v34, v34, v46, v41
	v_div_fixup_f32 v34, v34, v43, 1.0
	v_mul_f32_e32 v41, v35, v34
	v_cvt_pk_bf16_f32 v34, v36, v37
	v_cvt_pk_bf16_f32 v35, v38, v39
	v_cvt_pk_bf16_f32 v36, v32, v33
	v_add_u32_e32 v32, 0xa0, v160
	v_mad_i64_i32 v[32:33], s[6:7], v32, s61, v[146:147]
	v_lshl_add_u64 v[32:33], v[32:33], 0, v[148:149]
	v_add_co_u32_e32 v42, vcc, s62, v32
	v_cvt_pk_bf16_f32 v37, v40, v41
	global_store_dwordx4 v[48:49], v[34:37], off offset:256 sc1
	s_nop 0
	v_addc_co_u32_e32 v43, vcc, 0, v33, vcc
	s_waitcnt vmcnt(14)
; __device__ __forceinline__ float sigmoidf_(float x) { return 1.0f / (1.0f + __expf(-x)); }
; __device__ __forceinline__ u32x4 pack8(const f32x4 v0, const f32x4 v1) { u32x4 w; w.x = pk2(v0[0], v0[1]); w.y = pk2(v0[2], v0[3]); w.z = pk2(v1[0], v1[1]); w.w = pk2(v1[2], v1[3]); return w; }
; __device__ __forceinline__ void unpack8(const u32x4 w, f32x4& v0, f32x4& v1) { v0 = (f32x4){bflo(w.x), bfhi(w.x), bflo(w.y), bfhi(w.y)}; v1 = (f32x4){bflo(w.z), bfhi(w.z), bflo(w.w), bfhi(w.w)}; }
;     __device__ __forceinline__ void operator()(const f32x4 (&acc)[2][2][4][2], const Unit& u, int wr, int wc, int fr, int fq) const {
;     ...
;                     const u32x4 gw = *(const u32x4*)(rowp + (MODE == 0 ? O_GB : O_GA) + bj * 128);
;                     f32x4 g0, g1; unpack8(gw, g0, g1);
;                     f32x4 v0, v1;
; #pragma unroll
;                     for (int j = 0; j < 4; ++j) { v0[j] = sigmoidf_(g0[j]) * acc[ai][bj][m][0][j]; v1[j] = sigmoidf_(g1[j]) * acc[ai][bj][m][1][j]; }
;                     if (MODE == 1) { const u32x4 mw = *(const u32x4*)(rowp + bj * 128); f32x4 m0, m1; unpack8(mw, m0, m1); v0 += m0; v1 += m1; }
;                     *(u32x4*)(rowp + bj * 128) = pack8(v0, v1); }
	v_mov_b32_e32 v38, v204
	v_mov_b32_e32 v39, v205
	v_mov_b32_e32 v40, v206
	v_mov_b32_e32 v41, v207
	v_lshlrev_b32_e32 v34, 16, v38
	v_mul_f32_e32 v34, 0xbfb8aa3b, v34
	v_exp_f32_e32 v34, v34
	v_lshlrev_b32_e32 v36, 16, v39
	v_and_b32_e32 v37, 0xffff0000, v39
	v_and_b32_e32 v35, 0xffff0000, v38
	v_add_f32_e32 v34, 1.0, v34
	v_div_scale_f32 v39, s[6:7], v34, v34, 1.0
	v_rcp_f32_e32 v44, v39
	v_lshlrev_b32_e32 v38, 16, v40
	v_mul_f32_e32 v38, 0xbfb8aa3b, v38
	v_exp_f32_e32 v38, v38
	v_fma_f32 v46, -v39, v44, 1.0
	v_fmac_f32_e32 v44, v46, v44
	v_div_scale_f32 v46, vcc, 1.0, v34, 1.0
	v_mul_f32_e32 v47, v46, v44
	v_fma_f32 v48, -v39, v47, v46
	v_fmac_f32_e32 v47, v48, v44
	v_add_f32_e32 v38, 1.0, v38
	v_fma_f32 v39, -v39, v47, v46
	v_div_scale_f32 v46, s[6:7], v38, v38, 1.0
	v_rcp_f32_e32 v48, v46
	v_div_fmas_f32 v39, v39, v44, v47
	v_mul_f32_e32 v35, 0xbfb8aa3b, v35
	v_div_fixup_f32 v34, v39, v34, 1.0
	v_exp_f32_e32 v35, v35
	v_mul_f32_e32 v28, v28, v34
	v_fma_f32 v34, -v46, v48, 1.0
	v_fmac_f32_e32 v48, v34, v48
	v_div_scale_f32 v34, vcc, 1.0, v38, 1.0
	v_mul_f32_e32 v39, v34, v48
	v_fma_f32 v44, -v46, v39, v34
	v_add_f32_e32 v35, 1.0, v35
	v_fmac_f32_e32 v39, v44, v48
	v_div_scale_f32 v44, s[6:7], v35, v35, 1.0
	v_fma_f32 v34, -v46, v39, v34
	v_rcp_f32_e32 v46, v44
	v_and_b32_e32 v40, 0xffff0000, v40
	v_div_fmas_f32 v34, v34, v48, v39
	v_mul_f32_e32 v39, 0xbfb8aa3b, v40
	v_div_fixup_f32 v34, v34, v38, 1.0
	v_exp_f32_e32 v39, v39
	v_mul_f32_e32 v34, v24, v34
	v_fma_f32 v24, -v44, v46, 1.0
	v_fmac_f32_e32 v46, v24, v46
	v_div_scale_f32 v24, vcc, 1.0, v35, 1.0
	v_mul_f32_e32 v38, v24, v46
	v_fma_f32 v40, -v44, v38, v24
	v_add_f32_e32 v39, 1.0, v39
	v_fmac_f32_e32 v38, v40, v46
	v_div_scale_f32 v40, s[6:7], v39, v39, 1.0
	v_fma_f32 v24, -v44, v38, v24
	v_rcp_f32_e32 v44, v40
	v_div_fmas_f32 v24, v24, v46, v38
	v_mul_f32_e32 v36, 0xbfb8aa3b, v36
	v_div_fixup_f32 v24, v24, v35, 1.0
	v_exp_f32_e32 v36, v36
	v_mul_f32_e32 v24, v29, v24
	v_fma_f32 v29, -v40, v44, 1.0
	v_fmac_f32_e32 v44, v29, v44
	v_div_scale_f32 v29, vcc, 1.0, v39, 1.0
	v_mul_f32_e32 v35, v29, v44
	v_fma_f32 v38, -v40, v35, v29
	v_add_f32_e32 v36, 1.0, v36
	v_fmac_f32_e32 v35, v38, v44
	v_div_scale_f32 v38, s[6:7], v36, v36, 1.0
	v_fma_f32 v29, -v40, v35, v29
	v_rcp_f32_e32 v40, v38
	v_div_fmas_f32 v29, v29, v44, v35
	v_lshlrev_b32_e32 v45, 16, v41
	v_div_fixup_f32 v29, v29, v39, 1.0
	v_mul_f32_e32 v29, v25, v29
	v_fma_f32 v25, -v38, v40, 1.0
	v_mul_f32_e32 v39, 0xbfb8aa3b, v45
	v_fmac_f32_e32 v40, v25, v40
	v_div_scale_f32 v25, vcc, 1.0, v36, 1.0
	v_exp_f32_e32 v39, v39
	v_mul_f32_e32 v35, v25, v40
	v_fma_f32 v44, -v38, v35, v25
	v_fmac_f32_e32 v35, v44, v40
	v_fma_f32 v25, -v38, v35, v25
	v_add_f32_e32 v38, 1.0, v39
	v_div_scale_f32 v39, s[6:7], v38, v38, 1.0
	v_rcp_f32_e32 v44, v39
	v_div_fmas_f32 v25, v25, v40, v35
	v_div_fixup_f32 v25, v25, v36, 1.0
	v_mul_f32_e32 v36, 0xbfb8aa3b, v37
	v_exp_f32_e32 v36, v36
	v_mul_f32_e32 v25, v30, v25
	v_fma_f32 v30, -v39, v44, 1.0
	v_fmac_f32_e32 v44, v30, v44
	v_div_scale_f32 v30, vcc, 1.0, v38, 1.0
	v_mul_f32_e32 v35, v30, v44
	v_fma_f32 v37, -v39, v35, v30
	v_add_f32_e32 v36, 1.0, v36
	v_fmac_f32_e32 v35, v37, v44
	v_div_scale_f32 v37, s[6:7], v36, v36, 1.0
	v_fma_f32 v30, -v39, v35, v30
	v_rcp_f32_e32 v39, v37
	v_div_fmas_f32 v30, v30, v44, v35
	v_and_b32_e32 v41, 0xffff0000, v41
	v_div_fixup_f32 v30, v30, v38, 1.0
	v_mul_f32_e32 v30, v26, v30
	v_fma_f32 v26, -v37, v39, 1.0
	v_mul_f32_e32 v38, 0xbfb8aa3b, v41
	v_fmac_f32_e32 v39, v26, v39
	v_div_scale_f32 v26, vcc, 1.0, v36, 1.0
	v_exp_f32_e32 v38, v38
	v_mul_f32_e32 v35, v26, v39
	v_fma_f32 v40, -v37, v35, v26
	v_fmac_f32_e32 v35, v40, v39
	v_fma_f32 v26, -v37, v35, v26
	v_add_f32_e32 v37, 1.0, v38
	v_div_scale_f32 v38, s[6:7], v37, v37, 1.0
	v_rcp_f32_e32 v40, v38
	v_div_fmas_f32 v26, v26, v39, v35
	v_div_fixup_f32 v26, v26, v36, 1.0
	v_mul_f32_e32 v26, v31, v26
	v_fma_f32 v31, -v38, v40, 1.0
	v_fmac_f32_e32 v40, v31, v40
	v_div_scale_f32 v31, vcc, 1.0, v37, 1.0
	v_mul_f32_e32 v35, v31, v40
	v_fma_f32 v36, -v38, v35, v31
	v_fmac_f32_e32 v35, v36, v40
	v_fma_f32 v31, -v38, v35, v31
	v_div_fmas_f32 v31, v31, v40, v35
	v_div_fixup_f32 v31, v31, v37, 1.0
	v_mul_f32_e32 v27, v27, v31
	v_cvt_pk_bf16_f32 v24, v28, v24
	v_cvt_pk_bf16_f32 v25, v25, v26
	v_cvt_pk_bf16_f32 v26, v34, v29
	v_cvt_pk_bf16_f32 v27, v30, v27
	s_waitcnt vmcnt(12)
; __device__ __forceinline__ float sigmoidf_(float x) { return 1.0f / (1.0f + __expf(-x)); }
; __device__ __forceinline__ u32x4 pack8(const f32x4 v0, const f32x4 v1) { u32x4 w; w.x = pk2(v0[0], v0[1]); w.y = pk2(v0[2], v0[3]); w.z = pk2(v1[0], v1[1]); w.w = pk2(v1[2], v1[3]); return w; }
; __device__ __forceinline__ void unpack8(const u32x4 w, f32x4& v0, f32x4& v1) { v0 = (f32x4){bflo(w.x), bfhi(w.x), bflo(w.y), bfhi(w.y)}; v1 = (f32x4){bflo(w.z), bfhi(w.z), bflo(w.w), bfhi(w.w)}; }
;     __device__ __forceinline__ void operator()(const f32x4 (&acc)[2][2][4][2], const Unit& u, int wr, int wc, int fr, int fq) const {
;     ...
;                 bf16_t* rowp = z + (size_t)(row0 + ai * 128 + m * 16) * DIN + col0;
; #pragma unroll
;                 for (int bj = 0; bj < 2; ++bj) {
;                     const u32x4 gw = *(const u32x4*)(rowp + (MODE == 0 ? O_GB : O_GA) + bj * 128);
;                     f32x4 g0, g1; unpack8(gw, g0, g1);
;                     f32x4 v0, v1;
; #pragma unroll
;                     for (int j = 0; j < 4; ++j) { v0[j] = sigmoidf_(g0[j]) * acc[ai][bj][m][0][j]; v1[j] = sigmoidf_(g1[j]) * acc[ai][bj][m][1][j]; }
;                     if (MODE == 1) { const u32x4 mw = *(const u32x4*)(rowp + bj * 128); f32x4 m0, m1; unpack8(mw, m0, m1); v0 += m0; v1 += m1; }
;                     *(u32x4*)(rowp + bj * 128) = pack8(v0, v1); }
	v_mov_b32_e32 v28, v208
	v_mov_b32_e32 v29, v209
	v_mov_b32_e32 v30, v210
	v_mov_b32_e32 v31, v211
	v_lshlrev_b32_e32 v35, 16, v31
	global_store_dwordx4 v[32:33], v[24:27], off sc1
	v_and_b32_e32 v31, 0xffff0000, v31
	s_nop 0
	v_lshlrev_b32_e32 v24, 16, v28
	v_mul_f32_e32 v24, 0xbfb8aa3b, v24
	v_exp_f32_e32 v24, v24
	v_lshlrev_b32_e32 v26, 16, v29
	v_and_b32_e32 v27, 0xffff0000, v29
	v_and_b32_e32 v25, 0xffff0000, v28
	v_add_f32_e32 v24, 1.0, v24
	v_div_scale_f32 v29, s[6:7], v24, v24, 1.0
	v_rcp_f32_e32 v34, v29
	v_lshlrev_b32_e32 v28, 16, v30
	v_mul_f32_e32 v28, 0xbfb8aa3b, v28
	v_exp_f32_e32 v28, v28
	v_fma_f32 v36, -v29, v34, 1.0
	v_fmac_f32_e32 v34, v36, v34
	v_div_scale_f32 v36, vcc, 1.0, v24, 1.0
	v_mul_f32_e32 v37, v36, v34
	v_fma_f32 v38, -v29, v37, v36
	v_fmac_f32_e32 v37, v38, v34
	v_add_f32_e32 v28, 1.0, v28
	v_fma_f32 v29, -v29, v37, v36
	v_div_scale_f32 v36, s[6:7], v28, v28, 1.0
	v_rcp_f32_e32 v38, v36
	v_div_fmas_f32 v29, v29, v34, v37
	v_mul_f32_e32 v25, 0xbfb8aa3b, v25
	v_div_fixup_f32 v24, v29, v24, 1.0
	v_exp_f32_e32 v25, v25
	v_mul_f32_e32 v20, v20, v24
	v_fma_f32 v24, -v36, v38, 1.0
	v_fmac_f32_e32 v38, v24, v38
	v_div_scale_f32 v24, vcc, 1.0, v28, 1.0
	v_mul_f32_e32 v29, v24, v38
	v_fma_f32 v34, -v36, v29, v24
	v_add_f32_e32 v25, 1.0, v25
	v_fmac_f32_e32 v29, v34, v38
	v_div_scale_f32 v34, s[6:7], v25, v25, 1.0
	v_fma_f32 v24, -v36, v29, v24
	v_rcp_f32_e32 v36, v34
	v_and_b32_e32 v30, 0xffff0000, v30
	v_div_fmas_f32 v24, v24, v38, v29
	v_mul_f32_e32 v29, 0xbfb8aa3b, v30
	v_div_fixup_f32 v24, v24, v28, 1.0
	v_exp_f32_e32 v29, v29
	v_mul_f32_e32 v16, v16, v24
	v_fma_f32 v24, -v34, v36, 1.0
	v_fmac_f32_e32 v36, v24, v36
	v_div_scale_f32 v24, vcc, 1.0, v25, 1.0
	v_mul_f32_e32 v28, v24, v36
	v_fma_f32 v30, -v34, v28, v24
	v_add_f32_e32 v29, 1.0, v29
	v_fmac_f32_e32 v28, v30, v36
	v_div_scale_f32 v30, s[6:7], v29, v29, 1.0
	v_fma_f32 v24, -v34, v28, v24
	v_rcp_f32_e32 v34, v30
	v_div_fmas_f32 v24, v24, v36, v28
	v_mul_f32_e32 v26, 0xbfb8aa3b, v26
	v_div_fixup_f32 v24, v24, v25, 1.0
	v_exp_f32_e32 v26, v26
	v_mul_f32_e32 v21, v21, v24
	v_fma_f32 v24, -v30, v34, 1.0
	v_fmac_f32_e32 v34, v24, v34
	v_div_scale_f32 v24, vcc, 1.0, v29, 1.0
	v_mul_f32_e32 v25, v24, v34
	v_fma_f32 v28, -v30, v25, v24
	v_add_f32_e32 v26, 1.0, v26
	v_fmac_f32_e32 v25, v28, v34
	v_div_scale_f32 v28, s[6:7], v26, v26, 1.0
	v_fma_f32 v24, -v30, v25, v24
	v_rcp_f32_e32 v30, v28
	v_div_fmas_f32 v24, v24, v34, v25
	v_div_fixup_f32 v24, v24, v29, 1.0
	v_mul_f32_e32 v17, v17, v24
	v_fma_f32 v24, -v28, v30, 1.0
	v_mul_f32_e32 v29, 0xbfb8aa3b, v35
	v_fmac_f32_e32 v30, v24, v30
	v_div_scale_f32 v24, vcc, 1.0, v26, 1.0
	v_exp_f32_e32 v29, v29
	v_mul_f32_e32 v25, v24, v30
	v_fma_f32 v34, -v28, v25, v24
	v_fmac_f32_e32 v25, v34, v30
	v_fma_f32 v24, -v28, v25, v24
	v_add_f32_e32 v28, 1.0, v29
	v_div_scale_f32 v29, s[6:7], v28, v28, 1.0
	v_rcp_f32_e32 v34, v29
	v_div_fmas_f32 v24, v24, v30, v25
	v_div_fixup_f32 v24, v24, v26, 1.0
	v_mul_f32_e32 v26, 0xbfb8aa3b, v27
	v_exp_f32_e32 v26, v26
	v_mul_f32_e32 v22, v22, v24
	v_fma_f32 v24, -v29, v34, 1.0
	v_fmac_f32_e32 v34, v24, v34
	v_div_scale_f32 v24, vcc, 1.0, v28, 1.0
	v_mul_f32_e32 v25, v24, v34
	v_fma_f32 v27, -v29, v25, v24
	v_add_f32_e32 v26, 1.0, v26
	v_fmac_f32_e32 v25, v27, v34
	v_div_scale_f32 v27, s[6:7], v26, v26, 1.0
	v_fma_f32 v24, -v29, v25, v24
	v_rcp_f32_e32 v29, v27
	v_div_fmas_f32 v24, v24, v34, v25
	v_div_fixup_f32 v24, v24, v28, 1.0
	v_mul_f32_e32 v24, v18, v24
	v_fma_f32 v18, -v27, v29, 1.0
	v_mul_f32_e32 v28, 0xbfb8aa3b, v31
	v_fmac_f32_e32 v29, v18, v29
	v_div_scale_f32 v18, vcc, 1.0, v26, 1.0
	v_exp_f32_e32 v28, v28
	v_mul_f32_e32 v25, v18, v29
	v_fma_f32 v30, -v27, v25, v18
	v_fmac_f32_e32 v25, v30, v29
	v_fma_f32 v18, -v27, v25, v18
	v_add_f32_e32 v27, 1.0, v28
	v_div_scale_f32 v28, s[6:7], v27, v27, 1.0
	v_rcp_f32_e32 v30, v28
	v_div_fmas_f32 v18, v18, v29, v25
	v_div_fixup_f32 v18, v18, v26, 1.0
	v_mul_f32_e32 v23, v23, v18
	v_fma_f32 v18, -v28, v30, 1.0
	v_fmac_f32_e32 v30, v18, v30
	v_div_scale_f32 v18, vcc, 1.0, v27, 1.0
	v_mul_f32_e32 v25, v18, v30
	v_fma_f32 v26, -v28, v25, v18
	v_fmac_f32_e32 v25, v26, v30
	v_fma_f32 v18, -v28, v25, v18
	v_div_fmas_f32 v18, v18, v30, v25
	v_div_fixup_f32 v18, v18, v27, 1.0
	v_mul_f32_e32 v25, v19, v18
	v_cvt_pk_bf16_f32 v18, v20, v21
	v_cvt_pk_bf16_f32 v19, v22, v23
	v_cvt_pk_bf16_f32 v20, v16, v17
	v_add_u32_e32 v16, 0xb0, v160
	v_mad_i64_i32 v[16:17], s[6:7], v16, s61, v[146:147]
	v_lshl_add_u64 v[16:17], v[16:17], 0, v[148:149]
	v_add_co_u32_e32 v26, vcc, s62, v16
	v_cvt_pk_bf16_f32 v21, v24, v25
	global_store_dwordx4 v[32:33], v[18:21], off offset:256 sc1
	s_nop 0
	v_addc_co_u32_e32 v27, vcc, 0, v17, vcc
	s_waitcnt vmcnt(13)
; __device__ __forceinline__ float sigmoidf_(float x) { return 1.0f / (1.0f + __expf(-x)); }
; __device__ __forceinline__ u32x4 pack8(const f32x4 v0, const f32x4 v1) { u32x4 w; w.x = pk2(v0[0], v0[1]); w.y = pk2(v0[2], v0[3]); w.z = pk2(v1[0], v1[1]); w.w = pk2(v1[2], v1[3]); return w; }
; __device__ __forceinline__ void unpack8(const u32x4 w, f32x4& v0, f32x4& v1) { v0 = (f32x4){bflo(w.x), bfhi(w.x), bflo(w.y), bfhi(w.y)}; v1 = (f32x4){bflo(w.z), bfhi(w.z), bflo(w.w), bfhi(w.w)}; }
;     __device__ __forceinline__ void operator()(const f32x4 (&acc)[2][2][4][2], const Unit& u, int wr, int wc, int fr, int fq) const {
;     ...
;                     const u32x4 gw = *(const u32x4*)(rowp + (MODE == 0 ? O_GB : O_GA) + bj * 128);
;                     f32x4 g0, g1; unpack8(gw, g0, g1);
;                     f32x4 v0, v1;
; #pragma unroll
;                     for (int j = 0; j < 4; ++j) { v0[j] = sigmoidf_(g0[j]) * acc[ai][bj][m][0][j]; v1[j] = sigmoidf_(g1[j]) * acc[ai][bj][m][1][j]; }
;                     if (MODE == 1) { const u32x4 mw = *(const u32x4*)(rowp + bj * 128); f32x4 m0, m1; unpack8(mw, m0, m1); v0 += m0; v1 += m1; }
;                     *(u32x4*)(rowp + bj * 128) = pack8(v0, v1); }
	v_mov_b32_e32 v22, v212
	v_mov_b32_e32 v23, v213
	v_mov_b32_e32 v24, v214
	v_mov_b32_e32 v25, v215
	v_lshlrev_b32_e32 v18, 16, v22
	v_mul_f32_e32 v18, 0xbfb8aa3b, v18
	v_exp_f32_e32 v18, v18
	v_lshlrev_b32_e32 v20, 16, v23
	v_and_b32_e32 v21, 0xffff0000, v23
	v_and_b32_e32 v19, 0xffff0000, v22
	v_add_f32_e32 v18, 1.0, v18
	v_div_scale_f32 v23, s[6:7], v18, v18, 1.0
	v_rcp_f32_e32 v28, v23
	v_lshlrev_b32_e32 v22, 16, v24
	v_mul_f32_e32 v22, 0xbfb8aa3b, v22
	v_exp_f32_e32 v22, v22
	v_fma_f32 v30, -v23, v28, 1.0
	v_fmac_f32_e32 v28, v30, v28
	v_div_scale_f32 v30, vcc, 1.0, v18, 1.0
	v_mul_f32_e32 v31, v30, v28
	v_fma_f32 v32, -v23, v31, v30
	v_fmac_f32_e32 v31, v32, v28
	v_add_f32_e32 v22, 1.0, v22
	v_fma_f32 v23, -v23, v31, v30
	v_div_scale_f32 v30, s[6:7], v22, v22, 1.0
	v_rcp_f32_e32 v32, v30
	v_div_fmas_f32 v23, v23, v28, v31
	v_mul_f32_e32 v19, 0xbfb8aa3b, v19
	v_div_fixup_f32 v18, v23, v18, 1.0
	v_exp_f32_e32 v19, v19
	v_mul_f32_e32 v12, v12, v18
	v_fma_f32 v18, -v30, v32, 1.0
	v_fmac_f32_e32 v32, v18, v32
	v_div_scale_f32 v18, vcc, 1.0, v22, 1.0
	v_mul_f32_e32 v23, v18, v32
	v_fma_f32 v28, -v30, v23, v18
	v_add_f32_e32 v19, 1.0, v19
	v_fmac_f32_e32 v23, v28, v32
	v_div_scale_f32 v28, s[6:7], v19, v19, 1.0
	v_fma_f32 v18, -v30, v23, v18
	v_rcp_f32_e32 v30, v28
	v_and_b32_e32 v24, 0xffff0000, v24
	v_div_fmas_f32 v18, v18, v32, v23
	v_mul_f32_e32 v23, 0xbfb8aa3b, v24
	v_div_fixup_f32 v18, v18, v22, 1.0
	v_exp_f32_e32 v23, v23
	v_mul_f32_e32 v18, v8, v18
	v_fma_f32 v8, -v28, v30, 1.0
	v_fmac_f32_e32 v30, v8, v30
	v_div_scale_f32 v8, vcc, 1.0, v19, 1.0
	v_mul_f32_e32 v22, v8, v30
	v_fma_f32 v24, -v28, v22, v8
	v_add_f32_e32 v23, 1.0, v23
	v_fmac_f32_e32 v22, v24, v30
	v_div_scale_f32 v24, s[6:7], v23, v23, 1.0
	v_fma_f32 v8, -v28, v22, v8
	v_rcp_f32_e32 v28, v24
	v_div_fmas_f32 v8, v8, v30, v22
	v_mul_f32_e32 v20, 0xbfb8aa3b, v20
	v_div_fixup_f32 v8, v8, v19, 1.0
	v_exp_f32_e32 v20, v20
	v_mul_f32_e32 v8, v13, v8
	v_fma_f32 v13, -v24, v28, 1.0
	v_fmac_f32_e32 v28, v13, v28
	v_div_scale_f32 v13, vcc, 1.0, v23, 1.0
	v_mul_f32_e32 v19, v13, v28
	v_fma_f32 v22, -v24, v19, v13
	v_add_f32_e32 v20, 1.0, v20
	v_fmac_f32_e32 v19, v22, v28
	v_div_scale_f32 v22, s[6:7], v20, v20, 1.0
	v_fma_f32 v13, -v24, v19, v13
	v_rcp_f32_e32 v24, v22
	v_div_fmas_f32 v13, v13, v28, v19
	v_lshlrev_b32_e32 v29, 16, v25
	v_div_fixup_f32 v13, v13, v23, 1.0
	v_mul_f32_e32 v13, v9, v13
	v_fma_f32 v9, -v22, v24, 1.0
	v_mul_f32_e32 v23, 0xbfb8aa3b, v29
	v_fmac_f32_e32 v24, v9, v24
	v_div_scale_f32 v9, vcc, 1.0, v20, 1.0
	v_exp_f32_e32 v23, v23
	v_mul_f32_e32 v19, v9, v24
	v_fma_f32 v28, -v22, v19, v9
	v_fmac_f32_e32 v19, v28, v24
	v_fma_f32 v9, -v22, v19, v9
	v_add_f32_e32 v22, 1.0, v23
	v_div_scale_f32 v23, s[6:7], v22, v22, 1.0
	v_rcp_f32_e32 v28, v23
	v_div_fmas_f32 v9, v9, v24, v19
	v_div_fixup_f32 v9, v9, v20, 1.0
	v_mul_f32_e32 v20, 0xbfb8aa3b, v21
	v_exp_f32_e32 v20, v20
	v_mul_f32_e32 v9, v14, v9
	v_fma_f32 v14, -v23, v28, 1.0
	v_fmac_f32_e32 v28, v14, v28
	v_div_scale_f32 v14, vcc, 1.0, v22, 1.0
	v_mul_f32_e32 v19, v14, v28
	v_fma_f32 v21, -v23, v19, v14
	v_add_f32_e32 v20, 1.0, v20
	v_fmac_f32_e32 v19, v21, v28
	v_div_scale_f32 v21, s[6:7], v20, v20, 1.0
	v_fma_f32 v14, -v23, v19, v14
	v_rcp_f32_e32 v23, v21
	v_div_fmas_f32 v14, v14, v28, v19
	v_and_b32_e32 v25, 0xffff0000, v25
	v_div_fixup_f32 v14, v14, v22, 1.0
	v_mul_f32_e32 v14, v10, v14
	v_fma_f32 v10, -v21, v23, 1.0
	v_mul_f32_e32 v22, 0xbfb8aa3b, v25
	v_fmac_f32_e32 v23, v10, v23
	v_div_scale_f32 v10, vcc, 1.0, v20, 1.0
	v_exp_f32_e32 v22, v22
	v_mul_f32_e32 v19, v10, v23
	v_fma_f32 v24, -v21, v19, v10
	v_fmac_f32_e32 v19, v24, v23
	v_fma_f32 v10, -v21, v19, v10
	v_add_f32_e32 v21, 1.0, v22
	v_div_scale_f32 v22, s[6:7], v21, v21, 1.0
	v_rcp_f32_e32 v24, v22
	v_div_fmas_f32 v10, v10, v23, v19
	v_div_fixup_f32 v10, v10, v20, 1.0
	v_mul_f32_e32 v10, v15, v10
	v_fma_f32 v15, -v22, v24, 1.0
	v_fmac_f32_e32 v24, v15, v24
	v_div_scale_f32 v15, vcc, 1.0, v21, 1.0
	v_mul_f32_e32 v19, v15, v24
	v_fma_f32 v20, -v22, v19, v15
	v_fmac_f32_e32 v19, v20, v24
	v_fma_f32 v15, -v22, v19, v15
	v_div_fmas_f32 v15, v15, v24, v19
	v_div_fixup_f32 v15, v15, v21, 1.0
	v_mul_f32_e32 v11, v11, v15
	v_cvt_pk_bf16_f32 v8, v12, v8
	v_cvt_pk_bf16_f32 v9, v9, v10
	v_cvt_pk_bf16_f32 v10, v18, v13
	v_cvt_pk_bf16_f32 v11, v14, v11
	s_waitcnt vmcnt(10)
; __device__ __forceinline__ float sigmoidf_(float x) { return 1.0f / (1.0f + __expf(-x)); }
; #define PG8_WAIT_V(n) asm volatile("s_waitcnt vmcnt(" #n ")" ::: "memory")
; #define PG8_BAR __builtin_amdgcn_s_barrier()
; __device__ __forceinline__ u32x4 pack8(const f32x4 v0, const f32x4 v1) { u32x4 w; w.x = pk2(v0[0], v0[1]); w.y = pk2(v0[2], v0[3]); w.z = pk2(v1[0], v1[1]); w.w = pk2(v1[2], v1[3]); return w; }
; __device__ __forceinline__ void unpack8(const u32x4 w, f32x4& v0, f32x4& v1) { v0 = (f32x4){bflo(w.x), bfhi(w.x), bflo(w.y), bfhi(w.y)}; v1 = (f32x4){bflo(w.z), bfhi(w.z), bflo(w.w), bfhi(w.w)}; }
;     ...
;     PG8_WAIT_V(0);
;     if (wr == 0) PG8_BAR;
;     PG8_BAR;
;     __device__ __forceinline__ void operator()(const f32x4 (&acc)[2][2][4][2], const Unit& u, int wr, int wc, int fr, int fq) const {
;     ...
;                 bf16_t* rowp = z + (size_t)(row0 + ai * 128 + m * 16) * DIN + col0;
; #pragma unroll
;                 for (int bj = 0; bj < 2; ++bj) {
;                     const u32x4 gw = *(const u32x4*)(rowp + (MODE == 0 ? O_GB : O_GA) + bj * 128);
;                     f32x4 g0, g1; unpack8(gw, g0, g1);
;                     f32x4 v0, v1;
; #pragma unroll
;                     for (int j = 0; j < 4; ++j) { v0[j] = sigmoidf_(g0[j]) * acc[ai][bj][m][0][j]; v1[j] = sigmoidf_(g1[j]) * acc[ai][bj][m][1][j]; }
;                     if (MODE == 1) { const u32x4 mw = *(const u32x4*)(rowp + bj * 128); f32x4 m0, m1; unpack8(mw, m0, m1); v0 += m0; v1 += m1; }
;                     *(u32x4*)(rowp + bj * 128) = pack8(v0, v1); }
	v_mov_b32_e32 v12, v216
	v_mov_b32_e32 v13, v217
	v_mov_b32_e32 v14, v218
	v_mov_b32_e32 v15, v219
	v_lshlrev_b32_e32 v19, 16, v15
	global_store_dwordx4 v[16:17], v[8:11], off sc1
	v_and_b32_e32 v15, 0xffff0000, v15
	s_nop 0
	v_lshlrev_b32_e32 v8, 16, v12
	v_mul_f32_e32 v8, 0xbfb8aa3b, v8
	v_exp_f32_e32 v8, v8
	v_lshlrev_b32_e32 v10, 16, v13
	v_and_b32_e32 v11, 0xffff0000, v13
	v_and_b32_e32 v9, 0xffff0000, v12
	v_add_f32_e32 v8, 1.0, v8
	v_div_scale_f32 v13, s[6:7], v8, v8, 1.0
	v_rcp_f32_e32 v18, v13
	v_lshlrev_b32_e32 v12, 16, v14
	v_mul_f32_e32 v12, 0xbfb8aa3b, v12
	v_exp_f32_e32 v12, v12
	v_fma_f32 v20, -v13, v18, 1.0
	v_fmac_f32_e32 v18, v20, v18
	v_div_scale_f32 v20, vcc, 1.0, v8, 1.0
	v_mul_f32_e32 v21, v20, v18
	v_fma_f32 v22, -v13, v21, v20
	v_fmac_f32_e32 v21, v22, v18
	v_add_f32_e32 v12, 1.0, v12
	v_fma_f32 v13, -v13, v21, v20
	v_div_scale_f32 v20, s[6:7], v12, v12, 1.0
	v_rcp_f32_e32 v22, v20
	v_div_fmas_f32 v13, v13, v18, v21
	v_mul_f32_e32 v9, 0xbfb8aa3b, v9
	v_div_fixup_f32 v8, v13, v8, 1.0
	v_exp_f32_e32 v9, v9
	v_mul_f32_e32 v4, v4, v8
	v_fma_f32 v8, -v20, v22, 1.0
	v_fmac_f32_e32 v22, v8, v22
	v_div_scale_f32 v8, vcc, 1.0, v12, 1.0
	v_mul_f32_e32 v13, v8, v22
	v_fma_f32 v18, -v20, v13, v8
	v_add_f32_e32 v9, 1.0, v9
	v_fmac_f32_e32 v13, v18, v22
	v_div_scale_f32 v18, s[6:7], v9, v9, 1.0
	v_fma_f32 v8, -v20, v13, v8
	v_rcp_f32_e32 v20, v18
	v_and_b32_e32 v14, 0xffff0000, v14
	v_div_fmas_f32 v8, v8, v22, v13
	v_mul_f32_e32 v13, 0xbfb8aa3b, v14
	v_div_fixup_f32 v8, v8, v12, 1.0
	v_exp_f32_e32 v13, v13
	v_mul_f32_e32 v8, v0, v8
	v_fma_f32 v0, -v18, v20, 1.0
	v_fmac_f32_e32 v20, v0, v20
	v_div_scale_f32 v0, vcc, 1.0, v9, 1.0
	v_mul_f32_e32 v12, v0, v20
	v_fma_f32 v14, -v18, v12, v0
	v_add_f32_e32 v13, 1.0, v13
	v_fmac_f32_e32 v12, v14, v20
	v_div_scale_f32 v14, s[6:7], v13, v13, 1.0
	v_fma_f32 v0, -v18, v12, v0
	v_rcp_f32_e32 v18, v14
	v_div_fmas_f32 v0, v0, v20, v12
	v_mul_f32_e32 v10, 0xbfb8aa3b, v10
	v_div_fixup_f32 v0, v0, v9, 1.0
	v_exp_f32_e32 v10, v10
	v_mul_f32_e32 v0, v5, v0
	v_fma_f32 v5, -v14, v18, 1.0
	v_fmac_f32_e32 v18, v5, v18
	v_div_scale_f32 v5, vcc, 1.0, v13, 1.0
	v_mul_f32_e32 v9, v5, v18
	v_fma_f32 v12, -v14, v9, v5
	v_add_f32_e32 v10, 1.0, v10
	v_fmac_f32_e32 v9, v12, v18
	v_div_scale_f32 v12, s[6:7], v10, v10, 1.0
	v_fma_f32 v5, -v14, v9, v5
	v_rcp_f32_e32 v14, v12
	v_div_fmas_f32 v5, v5, v18, v9
	v_div_fixup_f32 v5, v5, v13, 1.0
	v_mul_f32_e32 v5, v1, v5
	v_fma_f32 v1, -v12, v14, 1.0
	v_mul_f32_e32 v13, 0xbfb8aa3b, v19
	v_fmac_f32_e32 v14, v1, v14
	v_div_scale_f32 v1, vcc, 1.0, v10, 1.0
	v_exp_f32_e32 v13, v13
	v_mul_f32_e32 v9, v1, v14
	v_fma_f32 v18, -v12, v9, v1
	v_fmac_f32_e32 v9, v18, v14
	v_fma_f32 v1, -v12, v9, v1
	v_add_f32_e32 v12, 1.0, v13
	v_div_scale_f32 v13, s[6:7], v12, v12, 1.0
	v_rcp_f32_e32 v18, v13
	v_div_fmas_f32 v1, v1, v14, v9
	v_div_fixup_f32 v1, v1, v10, 1.0
	v_mul_f32_e32 v10, 0xbfb8aa3b, v11
	v_exp_f32_e32 v10, v10
	v_mul_f32_e32 v1, v6, v1
	v_fma_f32 v6, -v13, v18, 1.0
	v_fmac_f32_e32 v18, v6, v18
	v_div_scale_f32 v6, vcc, 1.0, v12, 1.0
	v_mul_f32_e32 v9, v6, v18
	v_fma_f32 v11, -v13, v9, v6
	v_add_f32_e32 v10, 1.0, v10
	v_fmac_f32_e32 v9, v11, v18
	v_div_scale_f32 v11, s[6:7], v10, v10, 1.0
	v_fma_f32 v6, -v13, v9, v6
	v_rcp_f32_e32 v13, v11
	v_div_fmas_f32 v6, v6, v18, v9
	v_div_fixup_f32 v6, v6, v12, 1.0
	v_mul_f32_e32 v6, v2, v6
	v_fma_f32 v2, -v11, v13, 1.0
	v_mul_f32_e32 v12, 0xbfb8aa3b, v15
	v_fmac_f32_e32 v13, v2, v13
	v_div_scale_f32 v2, vcc, 1.0, v10, 1.0
	v_exp_f32_e32 v12, v12
	v_mul_f32_e32 v9, v2, v13
	v_fma_f32 v14, -v11, v9, v2
	v_fmac_f32_e32 v9, v14, v13
	v_fma_f32 v2, -v11, v9, v2
	v_add_f32_e32 v11, 1.0, v12
	v_div_scale_f32 v12, s[6:7], v11, v11, 1.0
	v_rcp_f32_e32 v14, v12
	v_div_fmas_f32 v2, v2, v13, v9
	v_div_fixup_f32 v2, v2, v10, 1.0
	v_mul_f32_e32 v2, v7, v2
	v_fma_f32 v7, -v12, v14, 1.0
	v_fmac_f32_e32 v14, v7, v14
	v_div_scale_f32 v7, vcc, 1.0, v11, 1.0
	v_mul_f32_e32 v9, v7, v14
	v_fma_f32 v10, -v12, v9, v7
	v_fmac_f32_e32 v9, v10, v14
	v_fma_f32 v7, -v12, v9, v7
	v_div_fmas_f32 v7, v7, v14, v9
	v_div_fixup_f32 v7, v7, v11, 1.0
	v_mul_f32_e32 v3, v3, v7
	s_and_b64 vcc, exec, s[10:11]
	s_mov_b32 s7, s28
	s_mov_b32 s6, s63
	v_cvt_pk_bf16_f32 v0, v4, v0
	v_cvt_pk_bf16_f32 v1, v1, v2
	v_cvt_pk_bf16_f32 v2, v8, v5
	v_cvt_pk_bf16_f32 v3, v6, v3
	global_store_dwordx4 v[16:17], v[0:3], off offset:256 sc1
	s_cbranch_vccz .LBB0_622
	s_waitcnt vmcnt(0)
	s_cmpk_gt_u32 s36, 0xff
	s_cbranch_scc1 .LBB0_631
	s_barrier

; __device__ __forceinline__ unsigned pk2(float lo, float hi) { unsigned r; asm volatile("v_cvt_pk_bf16_f32 %0, %1, %2" : "=v"(r) : "v"(lo), "v"(hi)); return r; }
;     __device__ __forceinline__ void operator()(const f32x4 (&acc)[2][2][4][2], const Unit& u, int wr, int wc, int fr, int fq) const {
;         const int row0 = u.pm * 256 + wr * 64 + fr, col0 = u.pn * 256 + wc * 32 + 4 * fq;
;         const float* xo = (u.pm < 64) ? xoldA : (xoldB - (size_t)T_P * DM);
; #pragma unroll
;         for (int ai = 0; ai < 2; ++ai)
; #pragma unroll
;             for (int m = 0; m < 4; ++m) {
;                 const int row = row0 + ai * 128 + m * 16; const size_t ro = (size_t)row * DM + col0;
;                 float s = 0.f;
; #pragma unroll
;                 for (int bj = 0; bj < 2; ++bj)
; #pragma unroll
;                     for (int n = 0; n < 2; ++n) {
;                         const size_t o = ro + bj * 128 + n * 16;
;                         const f32x4 xn = *(const f32x4*)(xo + o) + acc[ai][bj][m][n];
;                         *(f32x4*)(xf + o) = xn;
;                         u32x2 w; w.x = pk2(xn[0], xn[1]); w.y = pk2(xn[2], xn[3]); *(u32x2*)(xb + o) = w;
;                         s += (xn[0] * xn[0] + xn[1] * xn[1]) + (xn[2] * xn[2] + xn[3] * xn[3]);
;                     }
;                 s += __shfl_xor(s, 16); s += __shfl_xor(s, 32);
;                 if (fq == 0) ssq[(size_t)row * 16 + u.pn * 4 + wc] = s;
.LBB0_781:
	v_lshl_add_u32 v146, s83, 8, v148
	v_lshl_or_b32 v142, s56, 8, v150
	v_ashrrev_i32_e32 v147, 31, v146
	v_ashrrev_i32_e32 v143, 31, v142
	v_lshlrev_b64 v[154:155], 10, v[146:147]
	s_cmp_lt_i32 s83, 64
	v_lshl_add_u64 v[158:159], v[154:155], 0, v[142:143]
	s_cselect_b32 s17, s23, -1
	s_cselect_b32 s16, s22, 0xfc000000
	v_lshlrev_b64 v[160:161], 2, v[158:159]
	v_lshl_add_u64 v[162:163], s[16:17], 0, v[160:161]
	v_subrev_u32_e32 v172, s16, v162
	v_add_u32_e32 v173, 0x0, v172
	global_load_dwordx4 v[174:177], v173, s[16:17]
	v_add_u32_e32 v173, 0x40, v172
	global_load_dwordx4 v[178:181], v173, s[16:17]
	v_add_u32_e32 v173, 0x200, v172
	global_load_dwordx4 v[182:185], v173, s[16:17]
	v_add_u32_e32 v173, 0x240, v172
	global_load_dwordx4 v[186:189], v173, s[16:17]
	v_add_u32_e32 v173, 0x10000, v172
	global_load_dwordx4 v[190:193], v173, s[16:17]
	v_add_u32_e32 v173, 0x10040, v172
	global_load_dwordx4 v[194:197], v173, s[16:17]
	v_add_u32_e32 v173, 0x10200, v172
	global_load_dwordx4 v[198:201], v173, s[16:17]
	v_add_u32_e32 v173, 0x10240, v172
	global_load_dwordx4 v[202:205], v173, s[16:17]
	v_add_u32_e32 v173, 0x20000, v172
	global_load_dwordx4 v[206:209], v173, s[16:17]
	v_add_u32_e32 v173, 0x20040, v172
	global_load_dwordx4 v[210:213], v173, s[16:17]
	v_add_u32_e32 v173, 0x20200, v172
	global_load_dwordx4 v[214:217], v173, s[16:17]
	v_add_u32_e32 v173, 0x20240, v172
	global_load_dwordx4 v[218:221], v173, s[16:17]
	v_add_u32_e32 v173, 0x30000, v172
	global_load_dwordx4 v[232:235], v173, s[16:17]
	v_add_u32_e32 v173, 0x30040, v172
	global_load_dwordx4 v[236:239], v173, s[16:17]
	v_add_u32_e32 v173, 0x30200, v172
	global_load_dwordx4 v[240:243], v173, s[16:17]
	v_add_u32_e32 v173, 0x30240, v172
	global_load_dwordx4 v[244:247], v173, s[16:17]
	v_add_u32_e32 v173, 0x80000, v172
	global_load_dwordx4 v[248:251], v173, s[16:17]
	v_add_u32_e32 v173, 0x80040, v172
	global_load_dwordx4 v[252:255], v173, s[16:17]
	v_lshl_add_u64 v[164:165], v[158:159], 1, s[24:25]
	v_lshl_add_u64 v[170:171], s[28:29], 0, v[160:161]
	v_xor_b32_e32 v153, 32, v152
	s_lshl_b32 s56, s56, 2
	s_ashr_i32 s57, s56, 31
	s_waitcnt vmcnt(17)
	v_mov_b32_e32 v154, v174
	v_mov_b32_e32 v155, v175
	v_mov_b32_e32 v156, v176
	v_mov_b32_e32 v157, v177
	v_add_u32_e32 v173, 0x80200, v172
	global_load_dwordx4 v[174:177], v173, s[16:17]
	v_pk_add_f32 v[126:127], v[126:127], v[156:157]
	v_pk_add_f32 v[124:125], v[124:125], v[154:155]
	global_store_dwordx4 v[170:171], v[124:127], off sc1
	v_cvt_pk_bf16_f32 v154, v124, v125
	v_cvt_pk_bf16_f32 v155, v126, v127
	global_store_dwordx2 v[164:165], v[154:155], off
	s_waitcnt vmcnt(19)
	v_mov_b32_e32 v154, v178
	v_mov_b32_e32 v155, v179
	v_mov_b32_e32 v156, v180
	v_mov_b32_e32 v157, v181
	v_add_u32_e32 v173, 0x80240, v172
	global_load_dwordx4 v[178:181], v173, s[16:17]
	v_pk_add_f32 v[122:123], v[122:123], v[156:157]
	v_pk_add_f32 v[120:121], v[120:121], v[154:155]
	global_store_dwordx4 v[170:171], v[120:123], off offset:64 sc1
	v_cvt_pk_bf16_f32 v154, v120, v121
	v_cvt_pk_bf16_f32 v155, v122, v123
	global_store_dwordx2 v[164:165], v[154:155], off offset:32
	s_waitcnt vmcnt(21)
	v_mov_b32_e32 v154, v182
	v_mov_b32_e32 v155, v183
	v_mov_b32_e32 v156, v184
	v_mov_b32_e32 v157, v185
	v_add_u32_e32 v173, 0x90000, v172
	global_load_dwordx4 v[182:185], v173, s[16:17]
	v_pk_add_f32 v[156:157], v[118:119], v[156:157]
	v_pk_add_f32 v[154:155], v[116:117], v[154:155]
	global_store_dwordx4 v[170:171], v[154:157], off offset:512 sc1
	v_cvt_pk_bf16_f32 v116, v154, v155
	v_cvt_pk_bf16_f32 v117, v156, v157
	global_store_dwordx2 v[164:165], v[116:117], off offset:256
	v_mul_f32_e32 v118, v125, v125
	v_mul_f32_e32 v119, v127, v127
	v_fmac_f32_e32 v118, v124, v124
	v_fmac_f32_e32 v119, v126, v126
	v_add_f32_e32 v118, v118, v119
	v_mul_f32_e32 v119, v121, v121
	v_mul_f32_e32 v121, v123, v123
	v_fmac_f32_e32 v119, v120, v120
	v_fmac_f32_e32 v121, v122, v122
	v_add_f32_e32 v119, v119, v121
	v_add_f32_e32 v118, v118, v119
	v_mul_f32_e32 v119, v155, v155
	v_mul_f32_e32 v120, v157, v157
	v_fmac_f32_e32 v119, v154, v154
	v_fmac_f32_e32 v120, v156, v156
	v_add_f32_e32 v119, v119, v120
	v_and_b32_e32 v117, 64, v152
	v_add_f32_e32 v122, v118, v119
	v_xor_b32_e32 v116, 16, v152
	v_add_u32_e32 v117, 64, v117
	v_cmp_lt_i32_e32 vcc, v116, v117
	s_waitcnt vmcnt(23)
	v_mov_b32_e32 v158, v186
	v_mov_b32_e32 v159, v187
	v_mov_b32_e32 v160, v188
	v_mov_b32_e32 v161, v189
	v_add_u32_e32 v173, 0x90040, v172
	global_load_dwordx4 v[186:189], v173, s[16:17]
	v_pk_add_f32 v[120:121], v[114:115], v[160:161]
	v_pk_add_f32 v[118:119], v[112:113], v[158:159]
	v_mul_f32_e32 v113, v121, v121
	v_mul_f32_e32 v112, v119, v119
	v_fmac_f32_e32 v112, v118, v118
	v_fmac_f32_e32 v113, v120, v120
	v_cndmask_b32_e32 v116, v152, v116, vcc
	v_add_f32_e32 v112, v112, v113
	v_lshlrev_b32_e32 v116, 2, v116
	v_add_f32_e32 v112, v122, v112
	ds_bpermute_b32 v113, v116, v112
	v_cmp_lt_i32_e32 vcc, v153, v117
	global_store_dwordx4 v[170:171], v[118:121], off offset:576 sc1
	s_waitcnt lgkmcnt(0)
	v_add_f32_e32 v112, v112, v113
	v_cndmask_b32_e32 v114, v152, v153, vcc
	v_lshlrev_b32_e32 v114, 2, v114
	ds_bpermute_b32 v113, v114, v112
	v_cvt_pk_bf16_f32 v118, v118, v119
	v_cvt_pk_bf16_f32 v119, v120, v121
	global_store_dwordx2 v[164:165], v[118:119], off offset:288
	s_and_saveexec_b64 s[58:59], s[12:13]
	s_cbranch_execz .LBB0_783
	s_waitcnt lgkmcnt(0)
	v_add_f32_e32 v115, v112, v113
	v_lshlrev_b64 v[112:113], 6, v[146:147]
	v_lshl_add_u64 v[112:113], s[26:27], 0, v[112:113]
	v_lshl_add_u64 v[112:113], s[56:57], 2, v[112:113]
	s_lshl_b32 s36, s74, 2
	v_lshl_add_u64 v[112:113], v[112:113], 0, s[36:37]
	global_store_dword v[112:113], v115, off
; __device__ __forceinline__ unsigned pk2(float lo, float hi) { unsigned r; asm volatile("v_cvt_pk_bf16_f32 %0, %1, %2" : "=v"(r) : "v"(lo), "v"(hi)); return r; }
;     __device__ __forceinline__ void operator()(const f32x4 (&acc)[2][2][4][2], const Unit& u, int wr, int wc, int fr, int fq) const {
;     ...
;                 const int row = row0 + ai * 128 + m * 16; const size_t ro = (size_t)row * DM + col0;
;                 float s = 0.f;
; #pragma unroll
;                 for (int bj = 0; bj < 2; ++bj)
; #pragma unroll
;                     for (int n = 0; n < 2; ++n) {
;                         const size_t o = ro + bj * 128 + n * 16;
;                         const f32x4 xn = *(const f32x4*)(xo + o) + acc[ai][bj][m][n];
;                         *(f32x4*)(xf + o) = xn;
;                         u32x2 w; w.x = pk2(xn[0], xn[1]); w.y = pk2(xn[2], xn[3]); *(u32x2*)(xb + o) = w;
;                         s += (xn[0] * xn[0] + xn[1] * xn[1]) + (xn[2] * xn[2] + xn[3] * xn[3]);
;                     }
;                 s += __shfl_xor(s, 16); s += __shfl_xor(s, 32);
;                 if (fq == 0) ssq[(size_t)row * 16 + u.pn * 4 + wc] = s;
.LBB0_783:
	s_or_b64 exec, exec, s[58:59]
	v_or_b32_e32 v112, 16, v146
	s_waitcnt lgkmcnt(0)
	v_ashrrev_i32_e32 v113, 31, v112
	v_lshlrev_b64 v[118:119], 10, v[112:113]
	v_lshl_add_u64 v[122:123], v[118:119], 0, v[142:143]
	v_lshlrev_b64 v[124:125], 2, v[122:123]
	v_lshl_add_u64 v[126:127], s[16:17], 0, v[124:125]
	v_lshl_add_u64 v[122:123], v[122:123], 1, s[24:25]
	v_lshl_add_u64 v[124:125], s[28:29], 0, v[124:125]
	s_waitcnt vmcnt(25)
	v_mov_b32_e32 v118, v190
	v_mov_b32_e32 v119, v191
	v_mov_b32_e32 v120, v192
	v_mov_b32_e32 v121, v193
	v_add_u32_e32 v173, 0x90200, v172
	global_load_dwordx4 v[190:193], v173, s[16:17]
	v_pk_add_f32 v[110:111], v[110:111], v[120:121]
	v_pk_add_f32 v[108:109], v[108:109], v[118:119]
	global_store_dwordx4 v[124:125], v[108:111], off sc1
	v_cvt_pk_bf16_f32 v118, v108, v109
	v_cvt_pk_bf16_f32 v119, v110, v111
	global_store_dwordx2 v[122:123], v[118:119], off
	v_mul_f32_e32 v109, v109, v109
	v_mul_f32_e32 v111, v111, v111
	v_fmac_f32_e32 v109, v108, v108
	v_fmac_f32_e32 v111, v110, v110
	v_add_f32_e32 v108, v109, v111
	s_waitcnt vmcnt(27)
	v_mov_b32_e32 v118, v194
	v_mov_b32_e32 v119, v195
	v_mov_b32_e32 v120, v196
	v_mov_b32_e32 v121, v197
	v_add_u32_e32 v173, 0x90240, v172
	global_load_dwordx4 v[194:197], v173, s[16:17]
	v_pk_add_f32 v[106:107], v[106:107], v[120:121]
	v_pk_add_f32 v[104:105], v[104:105], v[118:119]
	global_store_dwordx4 v[124:125], v[104:107], off offset:64 sc1
	v_cvt_pk_bf16_f32 v118, v104, v105
	v_cvt_pk_bf16_f32 v119, v106, v107
	global_store_dwordx2 v[122:123], v[118:119], off offset:32
	v_mul_f32_e32 v105, v105, v105
	v_mul_f32_e32 v107, v107, v107
	v_fmac_f32_e32 v105, v104, v104
	v_fmac_f32_e32 v107, v106, v106
	v_add_f32_e32 v104, v105, v107
	v_add_f32_e32 v104, v108, v104
	s_waitcnt vmcnt(29)
	v_mov_b32_e32 v118, v198
	v_mov_b32_e32 v119, v199
	v_mov_b32_e32 v120, v200
	v_mov_b32_e32 v121, v201
	v_add_u32_e32 v173, 0xa0000, v172
	global_load_dwordx4 v[198:201], v173, s[16:17]
	v_pk_add_f32 v[102:103], v[102:103], v[120:121]
	v_pk_add_f32 v[100:101], v[100:101], v[118:119]
	global_store_dwordx4 v[124:125], v[100:103], off offset:512 sc1
	v_cvt_pk_bf16_f32 v118, v100, v101
	v_cvt_pk_bf16_f32 v119, v102, v103
	global_store_dwordx2 v[122:123], v[118:119], off offset:256
	v_mul_f32_e32 v101, v101, v101
	v_mul_f32_e32 v103, v103, v103
	v_fmac_f32_e32 v101, v100, v100
	v_fmac_f32_e32 v103, v102, v102
	v_add_f32_e32 v100, v101, v103
	v_add_f32_e32 v102, v104, v100
	s_waitcnt vmcnt(31)
	v_mov_b32_e32 v118, v202
	v_mov_b32_e32 v119, v203
	v_mov_b32_e32 v120, v204
	v_mov_b32_e32 v121, v205
	v_add_u32_e32 v173, 0xa0040, v172
	global_load_dwordx4 v[202:205], v173, s[16:17]
	v_pk_add_f32 v[100:101], v[98:99], v[120:121]
	v_pk_add_f32 v[98:99], v[96:97], v[118:119]
	v_mul_f32_e32 v97, v101, v101
	v_mul_f32_e32 v96, v99, v99
	v_fmac_f32_e32 v96, v98, v98
	v_fmac_f32_e32 v97, v100, v100
	v_add_f32_e32 v96, v96, v97
	v_add_f32_e32 v96, v102, v96
	ds_bpermute_b32 v97, v116, v96
	global_store_dwordx4 v[124:125], v[98:101], off offset:576 sc1
	s_waitcnt lgkmcnt(0)
	v_add_f32_e32 v96, v96, v97
	ds_bpermute_b32 v97, v114, v96
	v_cvt_pk_bf16_f32 v98, v98, v99
	v_cvt_pk_bf16_f32 v99, v100, v101
	global_store_dwordx2 v[122:123], v[98:99], off offset:288
	s_and_saveexec_b64 s[58:59], s[12:13]
	s_cbranch_execz .LBB0_785
	s_waitcnt lgkmcnt(0)
	v_add_f32_e32 v98, v96, v97
	v_lshlrev_b64 v[96:97], 6, v[112:113]
	v_lshl_add_u64 v[96:97], s[26:27], 0, v[96:97]
	v_lshl_add_u64 v[96:97], s[56:57], 2, v[96:97]
	s_lshl_b32 s36, s74, 2
	v_lshl_add_u64 v[96:97], v[96:97], 0, s[36:37]
	global_store_dword v[96:97], v98, off
.LBB0_785:
	s_or_b64 exec, exec, s[58:59]
	v_or_b32_e32 v96, 32, v146
	s_waitcnt lgkmcnt(0)
	v_ashrrev_i32_e32 v97, 31, v96
	v_lshlrev_b64 v[98:99], 10, v[96:97]
	v_lshl_add_u64 v[102:103], v[98:99], 0, v[142:143]
	v_lshlrev_b64 v[104:105], 2, v[102:103]
	v_lshl_add_u64 v[106:107], s[16:17], 0, v[104:105]
	v_lshl_add_u64 v[102:103], v[102:103], 1, s[24:25]
	v_lshl_add_u64 v[104:105], s[28:29], 0, v[104:105]
	s_waitcnt vmcnt(33)
	v_mov_b32_e32 v98, v206
	v_mov_b32_e32 v99, v207
	v_mov_b32_e32 v100, v208
	v_mov_b32_e32 v101, v209
	v_add_u32_e32 v173, 0xa0200, v172
	global_load_dwordx4 v[206:209], v173, s[16:17]
	v_pk_add_f32 v[94:95], v[94:95], v[100:101]
	v_pk_add_f32 v[92:93], v[92:93], v[98:99]
	global_store_dwordx4 v[104:105], v[92:95], off sc1
	v_cvt_pk_bf16_f32 v98, v92, v93
	v_cvt_pk_bf16_f32 v99, v94, v95
	global_store_dwordx2 v[102:103], v[98:99], off
	v_mul_f32_e32 v93, v93, v93
	v_mul_f32_e32 v95, v95, v95
	v_fmac_f32_e32 v93, v92, v92
	v_fmac_f32_e32 v95, v94, v94
	v_add_f32_e32 v92, v93, v95
	s_waitcnt vmcnt(35)
	v_mov_b32_e32 v98, v210
	v_mov_b32_e32 v99, v211
	v_mov_b32_e32 v100, v212
	v_mov_b32_e32 v101, v213
	v_add_u32_e32 v173, 0xa0240, v172
	global_load_dwordx4 v[210:213], v173, s[16:17]
	v_pk_add_f32 v[90:91], v[90:91], v[100:101]
	v_pk_add_f32 v[88:89], v[88:89], v[98:99]
	global_store_dwordx4 v[104:105], v[88:91], off offset:64 sc1
	v_cvt_pk_bf16_f32 v98, v88, v89
	v_cvt_pk_bf16_f32 v99, v90, v91
	global_store_dwordx2 v[102:103], v[98:99], off offset:32
	v_mul_f32_e32 v89, v89, v89
	v_mul_f32_e32 v91, v91, v91
	v_fmac_f32_e32 v89, v88, v88
	v_fmac_f32_e32 v91, v90, v90
	v_add_f32_e32 v88, v89, v91
	v_add_f32_e32 v88, v92, v88
	s_waitcnt vmcnt(37)
	v_mov_b32_e32 v98, v214
	v_mov_b32_e32 v99, v215
	v_mov_b32_e32 v100, v216
	v_mov_b32_e32 v101, v217
	v_add_u32_e32 v173, 0xb0000, v172
	global_load_dwordx4 v[214:217], v173, s[16:17]
	v_pk_add_f32 v[86:87], v[86:87], v[100:101]
	v_pk_add_f32 v[84:85], v[84:85], v[98:99]
	global_store_dwordx4 v[104:105], v[84:87], off offset:512 sc1
	v_cvt_pk_bf16_f32 v98, v84, v85
	v_cvt_pk_bf16_f32 v99, v86, v87
	global_store_dwordx2 v[102:103], v[98:99], off offset:256
	v_mul_f32_e32 v85, v85, v85
	v_mul_f32_e32 v87, v87, v87
	v_fmac_f32_e32 v85, v84, v84
	v_fmac_f32_e32 v87, v86, v86
	v_add_f32_e32 v84, v85, v87
	v_add_f32_e32 v86, v88, v84
	s_waitcnt vmcnt(39)
	v_mov_b32_e32 v98, v218
	v_mov_b32_e32 v99, v219
	v_mov_b32_e32 v100, v220
	v_mov_b32_e32 v101, v221
	v_add_u32_e32 v173, 0xb0040, v172
	global_load_dwordx4 v[218:221], v173, s[16:17]
	v_pk_add_f32 v[84:85], v[82:83], v[100:101]
	v_pk_add_f32 v[82:83], v[80:81], v[98:99]
	v_mul_f32_e32 v81, v85, v85
	v_mul_f32_e32 v80, v83, v83
	v_fmac_f32_e32 v80, v82, v82
	v_fmac_f32_e32 v81, v84, v84
	v_add_f32_e32 v80, v80, v81
	v_add_f32_e32 v80, v86, v80
	ds_bpermute_b32 v81, v116, v80
	global_store_dwordx4 v[104:105], v[82:85], off offset:576 sc1
	s_waitcnt lgkmcnt(0)
	v_add_f32_e32 v80, v80, v81
	ds_bpermute_b32 v81, v114, v80
	v_cvt_pk_bf16_f32 v82, v82, v83
	v_cvt_pk_bf16_f32 v83, v84, v85
	global_store_dwordx2 v[102:103], v[82:83], off offset:288
	s_and_saveexec_b64 s[58:59], s[12:13]
	s_cbranch_execz .LBB0_787
; __device__ __forceinline__ unsigned pk2(float lo, float hi) { unsigned r; asm volatile("v_cvt_pk_bf16_f32 %0, %1, %2" : "=v"(r) : "v"(lo), "v"(hi)); return r; }
;     __device__ __forceinline__ void operator()(const f32x4 (&acc)[2][2][4][2], const Unit& u, int wr, int wc, int fr, int fq) const {
;     ...
;                 const int row = row0 + ai * 128 + m * 16; const size_t ro = (size_t)row * DM + col0;
;                 float s = 0.f;
; #pragma unroll
;                 for (int bj = 0; bj < 2; ++bj)
; #pragma unroll
;                     for (int n = 0; n < 2; ++n) {
;                         const size_t o = ro + bj * 128 + n * 16;
;                         const f32x4 xn = *(const f32x4*)(xo + o) + acc[ai][bj][m][n];
;                         *(f32x4*)(xf + o) = xn;
;                         u32x2 w; w.x = pk2(xn[0], xn[1]); w.y = pk2(xn[2], xn[3]); *(u32x2*)(xb + o) = w;
;                         s += (xn[0] * xn[0] + xn[1] * xn[1]) + (xn[2] * xn[2] + xn[3] * xn[3]);
;                     }
;                 s += __shfl_xor(s, 16); s += __shfl_xor(s, 32);
;                 if (fq == 0) ssq[(size_t)row * 16 + u.pn * 4 + wc] = s;
	s_waitcnt lgkmcnt(0)
	v_add_f32_e32 v82, v80, v81
	v_lshlrev_b64 v[80:81], 6, v[96:97]
	v_lshl_add_u64 v[80:81], s[26:27], 0, v[80:81]
	v_lshl_add_u64 v[80:81], s[56:57], 2, v[80:81]
	s_lshl_b32 s36, s74, 2
	v_lshl_add_u64 v[80:81], v[80:81], 0, s[36:37]
	global_store_dword v[80:81], v82, off
.LBB0_787:
	s_or_b64 exec, exec, s[58:59]
	v_or_b32_e32 v80, 48, v146
	s_waitcnt lgkmcnt(0)
	v_ashrrev_i32_e32 v81, 31, v80
	v_lshlrev_b64 v[82:83], 10, v[80:81]
	v_lshl_add_u64 v[86:87], v[82:83], 0, v[142:143]
	v_lshlrev_b64 v[88:89], 2, v[86:87]
	v_lshl_add_u64 v[90:91], s[16:17], 0, v[88:89]
	v_lshl_add_u64 v[86:87], v[86:87], 1, s[24:25]
	v_lshl_add_u64 v[88:89], s[28:29], 0, v[88:89]
	s_waitcnt vmcnt(41)
	v_mov_b32_e32 v82, v232
	v_mov_b32_e32 v83, v233
	v_mov_b32_e32 v84, v234
	v_mov_b32_e32 v85, v235
	v_add_u32_e32 v173, 0xb0200, v172
	global_load_dwordx4 v[232:235], v173, s[16:17]
	v_pk_add_f32 v[78:79], v[78:79], v[84:85]
	v_pk_add_f32 v[76:77], v[76:77], v[82:83]
	global_store_dwordx4 v[88:89], v[76:79], off sc1
	v_cvt_pk_bf16_f32 v82, v76, v77
	v_cvt_pk_bf16_f32 v83, v78, v79
	global_store_dwordx2 v[86:87], v[82:83], off
	v_mul_f32_e32 v77, v77, v77
	v_mul_f32_e32 v79, v79, v79
	v_fmac_f32_e32 v77, v76, v76
	v_fmac_f32_e32 v79, v78, v78
	v_add_f32_e32 v76, v77, v79
	s_waitcnt vmcnt(43)
	v_mov_b32_e32 v82, v236
	v_mov_b32_e32 v83, v237
	v_mov_b32_e32 v84, v238
	v_mov_b32_e32 v85, v239
	v_add_u32_e32 v173, 0xb0240, v172
	global_load_dwordx4 v[236:239], v173, s[16:17]
	v_pk_add_f32 v[74:75], v[74:75], v[84:85]
	v_pk_add_f32 v[72:73], v[72:73], v[82:83]
	global_store_dwordx4 v[88:89], v[72:75], off offset:64 sc1
	v_cvt_pk_bf16_f32 v82, v72, v73
	v_cvt_pk_bf16_f32 v83, v74, v75
	global_store_dwordx2 v[86:87], v[82:83], off offset:32
	v_mul_f32_e32 v73, v73, v73
	v_mul_f32_e32 v75, v75, v75
	v_fmac_f32_e32 v73, v72, v72
	v_fmac_f32_e32 v75, v74, v74
	v_add_f32_e32 v72, v73, v75
	v_add_f32_e32 v72, v76, v72
	s_waitcnt vmcnt(45)
	v_mov_b32_e32 v82, v240
	v_mov_b32_e32 v83, v241
	v_mov_b32_e32 v84, v242
	v_mov_b32_e32 v85, v243
	v_pk_add_f32 v[70:71], v[70:71], v[84:85]
	v_pk_add_f32 v[68:69], v[68:69], v[82:83]
	global_store_dwordx4 v[88:89], v[68:71], off offset:512 sc1
	v_cvt_pk_bf16_f32 v82, v68, v69
	v_cvt_pk_bf16_f32 v83, v70, v71
	global_store_dwordx2 v[86:87], v[82:83], off offset:256
	v_mul_f32_e32 v69, v69, v69
	v_mul_f32_e32 v71, v71, v71
	v_fmac_f32_e32 v69, v68, v68
	v_fmac_f32_e32 v71, v70, v70
	v_add_f32_e32 v68, v69, v71
	v_add_f32_e32 v70, v72, v68
	s_waitcnt vmcnt(46)
	v_mov_b32_e32 v82, v244
	v_mov_b32_e32 v83, v245
	v_mov_b32_e32 v84, v246
	v_mov_b32_e32 v85, v247
	v_pk_add_f32 v[68:69], v[66:67], v[84:85]
	v_pk_add_f32 v[66:67], v[64:65], v[82:83]
	v_mul_f32_e32 v65, v69, v69
	v_mul_f32_e32 v64, v67, v67
	v_fmac_f32_e32 v64, v66, v66
	v_fmac_f32_e32 v65, v68, v68
	v_add_f32_e32 v64, v64, v65
	v_add_f32_e32 v64, v70, v64
	ds_bpermute_b32 v65, v116, v64
	global_store_dwordx4 v[88:89], v[66:69], off offset:576 sc1
	s_waitcnt lgkmcnt(0)
	v_add_f32_e32 v64, v64, v65
	ds_bpermute_b32 v65, v114, v64
	v_cvt_pk_bf16_f32 v66, v66, v67
	v_cvt_pk_bf16_f32 v67, v68, v69
	global_store_dwordx2 v[86:87], v[66:67], off offset:288
	s_and_saveexec_b64 s[58:59], s[12:13]
	s_cbranch_execz .LBB0_789
	s_waitcnt lgkmcnt(0)
	v_add_f32_e32 v66, v64, v65
	v_lshlrev_b64 v[64:65], 6, v[80:81]
	v_lshl_add_u64 v[64:65], s[26:27], 0, v[64:65]
	v_lshl_add_u64 v[64:65], s[56:57], 2, v[64:65]
	s_lshl_b32 s36, s74, 2
	v_lshl_add_u64 v[64:65], v[64:65], 0, s[36:37]
	global_store_dword v[64:65], v66, off
.LBB0_789:
	s_or_b64 exec, exec, s[58:59]
	v_add_u32_e32 v64, 0x80, v146
	s_waitcnt lgkmcnt(0)
	v_ashrrev_i32_e32 v65, 31, v64
	v_lshlrev_b64 v[66:67], 10, v[64:65]
	v_lshl_add_u64 v[70:71], v[66:67], 0, v[142:143]
	v_lshlrev_b64 v[72:73], 2, v[70:71]
	v_lshl_add_u64 v[74:75], s[16:17], 0, v[72:73]
	v_lshl_add_u64 v[70:71], v[70:71], 1, s[24:25]
	v_lshl_add_u64 v[72:73], s[28:29], 0, v[72:73]
	s_waitcnt vmcnt(47)
	v_mov_b32_e32 v66, v248
	v_mov_b32_e32 v67, v249
	v_mov_b32_e32 v68, v250
	v_mov_b32_e32 v69, v251
	v_pk_add_f32 v[62:63], v[62:63], v[68:69]
	v_pk_add_f32 v[60:61], v[60:61], v[66:67]
	global_store_dwordx4 v[72:73], v[60:63], off sc1
	v_cvt_pk_bf16_f32 v66, v60, v61
	v_cvt_pk_bf16_f32 v67, v62, v63
	global_store_dwordx2 v[70:71], v[66:67], off
	v_mul_f32_e32 v61, v61, v61
	v_mul_f32_e32 v63, v63, v63
	v_fmac_f32_e32 v61, v60, v60
	v_fmac_f32_e32 v63, v62, v62
	v_add_f32_e32 v60, v61, v63
	s_waitcnt vmcnt(48)
	v_mov_b32_e32 v66, v252
	v_mov_b32_e32 v67, v253
	v_mov_b32_e32 v68, v254
	v_mov_b32_e32 v69, v255
	v_pk_add_f32 v[58:59], v[58:59], v[68:69]
	v_pk_add_f32 v[56:57], v[56:57], v[66:67]
	global_store_dwordx4 v[72:73], v[56:59], off offset:64 sc1
	v_cvt_pk_bf16_f32 v66, v56, v57
	v_cvt_pk_bf16_f32 v67, v58, v59
	global_store_dwordx2 v[70:71], v[66:67], off offset:32
	v_mul_f32_e32 v57, v57, v57
	v_mul_f32_e32 v59, v59, v59
	v_fmac_f32_e32 v57, v56, v56
	v_fmac_f32_e32 v59, v58, v58
	v_add_f32_e32 v56, v57, v59
	v_add_f32_e32 v56, v60, v56
	s_waitcnt vmcnt(49)
	v_mov_b32_e32 v66, v174
	v_mov_b32_e32 v67, v175
	v_mov_b32_e32 v68, v176
	v_mov_b32_e32 v69, v177
	v_pk_add_f32 v[54:55], v[54:55], v[68:69]
	v_pk_add_f32 v[52:53], v[52:53], v[66:67]
	global_store_dwordx4 v[72:73], v[52:55], off offset:512 sc1
	v_cvt_pk_bf16_f32 v66, v52, v53
	v_cvt_pk_bf16_f32 v67, v54, v55
	global_store_dwordx2 v[70:71], v[66:67], off offset:256
	v_mul_f32_e32 v53, v53, v53
	v_mul_f32_e32 v55, v55, v55
	v_fmac_f32_e32 v53, v52, v52
	v_fmac_f32_e32 v55, v54, v54
	v_add_f32_e32 v52, v53, v55
	v_add_f32_e32 v54, v56, v52
	s_waitcnt vmcnt(48)
	v_mov_b32_e32 v66, v178
	v_mov_b32_e32 v67, v179
	v_mov_b32_e32 v68, v180
	v_mov_b32_e32 v69, v181
	v_pk_add_f32 v[52:53], v[50:51], v[68:69]
	v_pk_add_f32 v[50:51], v[48:49], v[66:67]
	v_mul_f32_e32 v49, v53, v53
	v_mul_f32_e32 v48, v51, v51
	v_fmac_f32_e32 v48, v50, v50
	v_fmac_f32_e32 v49, v52, v52
	v_add_f32_e32 v48, v48, v49
	v_add_f32_e32 v48, v54, v48
	ds_bpermute_b32 v49, v116, v48
	global_store_dwordx4 v[72:73], v[50:53], off offset:576 sc1
	s_waitcnt lgkmcnt(0)
	v_add_f32_e32 v48, v48, v49
	ds_bpermute_b32 v49, v114, v48
	v_cvt_pk_bf16_f32 v50, v50, v51
	v_cvt_pk_bf16_f32 v51, v52, v53
	global_store_dwordx2 v[70:71], v[50:51], off offset:288
	s_and_saveexec_b64 s[58:59], s[12:13]
	s_cbranch_execz .LBB0_791
	s_waitcnt lgkmcnt(0)
	v_add_f32_e32 v50, v48, v49
	v_lshlrev_b64 v[48:49], 6, v[64:65]
	v_lshl_add_u64 v[48:49], s[26:27], 0, v[48:49]
	v_lshl_add_u64 v[48:49], s[56:57], 2, v[48:49]
	s_lshl_b32 s36, s74, 2
	v_lshl_add_u64 v[48:49], v[48:49], 0, s[36:37]
	global_store_dword v[48:49], v50, off
; __device__ __forceinline__ unsigned pk2(float lo, float hi) { unsigned r; asm volatile("v_cvt_pk_bf16_f32 %0, %1, %2" : "=v"(r) : "v"(lo), "v"(hi)); return r; }
;     __device__ __forceinline__ void operator()(const f32x4 (&acc)[2][2][4][2], const Unit& u, int wr, int wc, int fr, int fq) const {
;     ...
;                 const int row = row0 + ai * 128 + m * 16; const size_t ro = (size_t)row * DM + col0;
;                 float s = 0.f;
; #pragma unroll
;                 for (int bj = 0; bj < 2; ++bj)
; #pragma unroll
;                     for (int n = 0; n < 2; ++n) {
;                         const size_t o = ro + bj * 128 + n * 16;
;                         const f32x4 xn = *(const f32x4*)(xo + o) + acc[ai][bj][m][n];
;                         *(f32x4*)(xf + o) = xn;
;                         u32x2 w; w.x = pk2(xn[0], xn[1]); w.y = pk2(xn[2], xn[3]); *(u32x2*)(xb + o) = w;
;                         s += (xn[0] * xn[0] + xn[1] * xn[1]) + (xn[2] * xn[2] + xn[3] * xn[3]);
;                     }
;                 s += __shfl_xor(s, 16); s += __shfl_xor(s, 32);
;                 if (fq == 0) ssq[(size_t)row * 16 + u.pn * 4 + wc] = s;
.LBB0_791:
	s_or_b64 exec, exec, s[58:59]
	v_add_u32_e32 v48, 0x90, v146
	s_waitcnt lgkmcnt(0)
	v_ashrrev_i32_e32 v49, 31, v48
	v_lshlrev_b64 v[50:51], 10, v[48:49]
	v_lshl_add_u64 v[54:55], v[50:51], 0, v[142:143]
	v_lshlrev_b64 v[56:57], 2, v[54:55]
	v_lshl_add_u64 v[58:59], s[16:17], 0, v[56:57]
	v_lshl_add_u64 v[54:55], v[54:55], 1, s[24:25]
	v_lshl_add_u64 v[56:57], s[28:29], 0, v[56:57]
	s_waitcnt vmcnt(47)
	v_mov_b32_e32 v50, v182
	v_mov_b32_e32 v51, v183
	v_mov_b32_e32 v52, v184
	v_mov_b32_e32 v53, v185
	v_pk_add_f32 v[46:47], v[46:47], v[52:53]
	v_pk_add_f32 v[44:45], v[44:45], v[50:51]
	global_store_dwordx4 v[56:57], v[44:47], off sc1
	v_cvt_pk_bf16_f32 v50, v44, v45
	v_cvt_pk_bf16_f32 v51, v46, v47
	global_store_dwordx2 v[54:55], v[50:51], off
	v_mul_f32_e32 v45, v45, v45
	v_mul_f32_e32 v47, v47, v47
	v_fmac_f32_e32 v45, v44, v44
	v_fmac_f32_e32 v47, v46, v46
	v_add_f32_e32 v44, v45, v47
	s_waitcnt vmcnt(46)
	v_mov_b32_e32 v50, v186
	v_mov_b32_e32 v51, v187
	v_mov_b32_e32 v52, v188
	v_mov_b32_e32 v53, v189
	v_pk_add_f32 v[42:43], v[42:43], v[52:53]
	v_pk_add_f32 v[40:41], v[40:41], v[50:51]
	global_store_dwordx4 v[56:57], v[40:43], off offset:64 sc1
	v_cvt_pk_bf16_f32 v50, v40, v41
	v_cvt_pk_bf16_f32 v51, v42, v43
	global_store_dwordx2 v[54:55], v[50:51], off offset:32
	v_mul_f32_e32 v41, v41, v41
	v_mul_f32_e32 v43, v43, v43
	v_fmac_f32_e32 v41, v40, v40
	v_fmac_f32_e32 v43, v42, v42
	v_add_f32_e32 v40, v41, v43
	v_add_f32_e32 v40, v44, v40
	s_waitcnt vmcnt(45)
	v_mov_b32_e32 v50, v190
	v_mov_b32_e32 v51, v191
	v_mov_b32_e32 v52, v192
	v_mov_b32_e32 v53, v193
	v_pk_add_f32 v[38:39], v[38:39], v[52:53]
	v_pk_add_f32 v[36:37], v[36:37], v[50:51]
	global_store_dwordx4 v[56:57], v[36:39], off offset:512 sc1
	v_cvt_pk_bf16_f32 v50, v36, v37
	v_cvt_pk_bf16_f32 v51, v38, v39
	global_store_dwordx2 v[54:55], v[50:51], off offset:256
	v_mul_f32_e32 v37, v37, v37
	v_mul_f32_e32 v39, v39, v39
	v_fmac_f32_e32 v37, v36, v36
	v_fmac_f32_e32 v39, v38, v38
	v_add_f32_e32 v36, v37, v39
	v_add_f32_e32 v38, v40, v36
	s_waitcnt vmcnt(44)
	v_mov_b32_e32 v50, v194
	v_mov_b32_e32 v51, v195
	v_mov_b32_e32 v52, v196
	v_mov_b32_e32 v53, v197
	v_pk_add_f32 v[36:37], v[34:35], v[52:53]
	v_pk_add_f32 v[34:35], v[32:33], v[50:51]
	v_mul_f32_e32 v33, v37, v37
	v_mul_f32_e32 v32, v35, v35
	v_fmac_f32_e32 v32, v34, v34
	v_fmac_f32_e32 v33, v36, v36
	v_add_f32_e32 v32, v32, v33
	v_add_f32_e32 v32, v38, v32
	ds_bpermute_b32 v33, v116, v32
	global_store_dwordx4 v[56:57], v[34:37], off offset:576 sc1
	s_waitcnt lgkmcnt(0)
	v_add_f32_e32 v32, v32, v33
	ds_bpermute_b32 v33, v114, v32
	v_cvt_pk_bf16_f32 v34, v34, v35
	v_cvt_pk_bf16_f32 v35, v36, v37
	global_store_dwordx2 v[54:55], v[34:35], off offset:288
	s_and_saveexec_b64 s[58:59], s[12:13]
	s_cbranch_execz .LBB0_793
	s_waitcnt lgkmcnt(0)
	v_add_f32_e32 v34, v32, v33
	v_lshlrev_b64 v[32:33], 6, v[48:49]
	v_lshl_add_u64 v[32:33], s[26:27], 0, v[32:33]
	v_lshl_add_u64 v[32:33], s[56:57], 2, v[32:33]
	s_lshl_b32 s36, s74, 2
	v_lshl_add_u64 v[32:33], v[32:33], 0, s[36:37]
	global_store_dword v[32:33], v34, off
; __device__ __forceinline__ unsigned pk2(float lo, float hi) { unsigned r; asm volatile("v_cvt_pk_bf16_f32 %0, %1, %2" : "=v"(r) : "v"(lo), "v"(hi)); return r; }
;     __device__ __forceinline__ void operator()(const f32x4 (&acc)[2][2][4][2], const Unit& u, int wr, int wc, int fr, int fq) const {
;     ...
;                 const int row = row0 + ai * 128 + m * 16; const size_t ro = (size_t)row * DM + col0;
;                 float s = 0.f;
; #pragma unroll
;                 for (int bj = 0; bj < 2; ++bj)
; #pragma unroll
;                     for (int n = 0; n < 2; ++n) {
;                         const size_t o = ro + bj * 128 + n * 16;
;                         const f32x4 xn = *(const f32x4*)(xo + o) + acc[ai][bj][m][n];
;                         *(f32x4*)(xf + o) = xn;
;                         u32x2 w; w.x = pk2(xn[0], xn[1]); w.y = pk2(xn[2], xn[3]); *(u32x2*)(xb + o) = w;
;                         s += (xn[0] * xn[0] + xn[1] * xn[1]) + (xn[2] * xn[2] + xn[3] * xn[3]);
;                     }
;                 s += __shfl_xor(s, 16); s += __shfl_xor(s, 32);
;                 if (fq == 0) ssq[(size_t)row * 16 + u.pn * 4 + wc] = s;
.LBB0_793:
	s_or_b64 exec, exec, s[58:59]
	v_add_u32_e32 v32, 0xa0, v146
	s_waitcnt lgkmcnt(0)
	v_ashrrev_i32_e32 v33, 31, v32
	v_lshlrev_b64 v[34:35], 10, v[32:33]
	v_lshl_add_u64 v[38:39], v[34:35], 0, v[142:143]
	v_lshlrev_b64 v[40:41], 2, v[38:39]
	v_lshl_add_u64 v[42:43], s[16:17], 0, v[40:41]
	v_lshl_add_u64 v[38:39], v[38:39], 1, s[24:25]
	v_lshl_add_u64 v[40:41], s[28:29], 0, v[40:41]
	s_waitcnt vmcnt(43)
	v_mov_b32_e32 v34, v198
	v_mov_b32_e32 v35, v199
	v_mov_b32_e32 v36, v200
	v_mov_b32_e32 v37, v201
	v_pk_add_f32 v[30:31], v[30:31], v[36:37]
	v_pk_add_f32 v[28:29], v[28:29], v[34:35]
	global_store_dwordx4 v[40:41], v[28:31], off sc1
	v_cvt_pk_bf16_f32 v34, v28, v29
	v_cvt_pk_bf16_f32 v35, v30, v31
	global_store_dwordx2 v[38:39], v[34:35], off
	v_mul_f32_e32 v29, v29, v29
	v_mul_f32_e32 v31, v31, v31
	v_fmac_f32_e32 v29, v28, v28
	v_fmac_f32_e32 v31, v30, v30
	v_add_f32_e32 v28, v29, v31
	s_waitcnt vmcnt(42)
	v_mov_b32_e32 v34, v202
	v_mov_b32_e32 v35, v203
	v_mov_b32_e32 v36, v204
	v_mov_b32_e32 v37, v205
	v_pk_add_f32 v[26:27], v[26:27], v[36:37]
	v_pk_add_f32 v[24:25], v[24:25], v[34:35]
	global_store_dwordx4 v[40:41], v[24:27], off offset:64 sc1
	v_cvt_pk_bf16_f32 v34, v24, v25
	v_cvt_pk_bf16_f32 v35, v26, v27
	global_store_dwordx2 v[38:39], v[34:35], off offset:32
	v_mul_f32_e32 v25, v25, v25
	v_mul_f32_e32 v27, v27, v27
	v_fmac_f32_e32 v25, v24, v24
	v_fmac_f32_e32 v27, v26, v26
	v_add_f32_e32 v24, v25, v27
	v_add_f32_e32 v24, v28, v24
	s_waitcnt vmcnt(41)
	v_mov_b32_e32 v34, v206
	v_mov_b32_e32 v35, v207
	v_mov_b32_e32 v36, v208
	v_mov_b32_e32 v37, v209
	v_pk_add_f32 v[22:23], v[22:23], v[36:37]
	v_pk_add_f32 v[20:21], v[20:21], v[34:35]
	global_store_dwordx4 v[40:41], v[20:23], off offset:512 sc1
	v_cvt_pk_bf16_f32 v34, v20, v21
	v_cvt_pk_bf16_f32 v35, v22, v23
	global_store_dwordx2 v[38:39], v[34:35], off offset:256
	v_mul_f32_e32 v21, v21, v21
	v_mul_f32_e32 v23, v23, v23
	v_fmac_f32_e32 v21, v20, v20
	v_fmac_f32_e32 v23, v22, v22
	v_add_f32_e32 v20, v21, v23
	v_add_f32_e32 v22, v24, v20
	s_waitcnt vmcnt(40)
	v_mov_b32_e32 v34, v210
	v_mov_b32_e32 v35, v211
	v_mov_b32_e32 v36, v212
	v_mov_b32_e32 v37, v213
	v_pk_add_f32 v[20:21], v[18:19], v[36:37]
	v_pk_add_f32 v[18:19], v[16:17], v[34:35]
	v_mul_f32_e32 v17, v21, v21
	v_mul_f32_e32 v16, v19, v19
	v_fmac_f32_e32 v16, v18, v18
	v_fmac_f32_e32 v17, v20, v20
	v_add_f32_e32 v16, v16, v17
	v_add_f32_e32 v16, v22, v16
	ds_bpermute_b32 v17, v116, v16
	global_store_dwordx4 v[40:41], v[18:21], off offset:576 sc1
	s_waitcnt lgkmcnt(0)
	v_add_f32_e32 v16, v16, v17
	ds_bpermute_b32 v17, v114, v16
	v_cvt_pk_bf16_f32 v18, v18, v19
	v_cvt_pk_bf16_f32 v19, v20, v21
	global_store_dwordx2 v[38:39], v[18:19], off offset:288
	s_and_saveexec_b64 s[58:59], s[12:13]
	s_cbranch_execz .LBB0_795
	s_waitcnt lgkmcnt(0)
	v_add_f32_e32 v18, v16, v17
	v_lshlrev_b64 v[16:17], 6, v[32:33]
	v_lshl_add_u64 v[16:17], s[26:27], 0, v[16:17]
	v_lshl_add_u64 v[16:17], s[56:57], 2, v[16:17]
	s_lshl_b32 s36, s74, 2
	v_lshl_add_u64 v[16:17], v[16:17], 0, s[36:37]
	global_store_dword v[16:17], v18, off
.LBB0_795:
	s_or_b64 exec, exec, s[58:59]
	v_add_u32_e32 v16, 0xb0, v146
	s_waitcnt lgkmcnt(0)
	v_ashrrev_i32_e32 v17, 31, v16
	v_lshlrev_b64 v[18:19], 10, v[16:17]
	v_lshl_add_u64 v[22:23], v[18:19], 0, v[142:143]
	v_lshlrev_b64 v[24:25], 2, v[22:23]
	v_lshl_add_u64 v[26:27], s[16:17], 0, v[24:25]
	v_lshl_add_u64 v[22:23], v[22:23], 1, s[24:25]
	v_lshl_add_u64 v[24:25], s[28:29], 0, v[24:25]
	s_waitcnt vmcnt(39)
	v_mov_b32_e32 v18, v214
	v_mov_b32_e32 v19, v215
	v_mov_b32_e32 v20, v216
	v_mov_b32_e32 v21, v217
	v_pk_add_f32 v[14:15], v[14:15], v[20:21]
	v_pk_add_f32 v[12:13], v[12:13], v[18:19]
	global_store_dwordx4 v[24:25], v[12:15], off sc1
	v_cvt_pk_bf16_f32 v18, v12, v13
	v_cvt_pk_bf16_f32 v19, v14, v15
	global_store_dwordx2 v[22:23], v[18:19], off
	v_mul_f32_e32 v13, v13, v13
	v_mul_f32_e32 v15, v15, v15
	v_fmac_f32_e32 v13, v12, v12
	v_fmac_f32_e32 v15, v14, v14
	v_add_f32_e32 v12, v13, v15
	s_waitcnt vmcnt(38)
	v_mov_b32_e32 v18, v218
	v_mov_b32_e32 v19, v219
	v_mov_b32_e32 v20, v220
	v_mov_b32_e32 v21, v221
	v_pk_add_f32 v[10:11], v[10:11], v[20:21]
	v_pk_add_f32 v[8:9], v[8:9], v[18:19]
	global_store_dwordx4 v[24:25], v[8:11], off offset:64 sc1
	v_cvt_pk_bf16_f32 v18, v8, v9
	v_cvt_pk_bf16_f32 v19, v10, v11
	global_store_dwordx2 v[22:23], v[18:19], off offset:32
	v_mul_f32_e32 v9, v9, v9
	v_mul_f32_e32 v11, v11, v11
	v_fmac_f32_e32 v9, v8, v8
	v_fmac_f32_e32 v11, v10, v10
	v_add_f32_e32 v8, v9, v11
	v_add_f32_e32 v8, v12, v8
	s_waitcnt vmcnt(37)
	v_mov_b32_e32 v18, v232
	v_mov_b32_e32 v19, v233
	v_mov_b32_e32 v20, v234
	v_mov_b32_e32 v21, v235
	v_pk_add_f32 v[6:7], v[6:7], v[20:21]
	v_pk_add_f32 v[4:5], v[4:5], v[18:19]
	global_store_dwordx4 v[24:25], v[4:7], off offset:512 sc1
	v_cvt_pk_bf16_f32 v18, v4, v5
	v_cvt_pk_bf16_f32 v19, v6, v7
	global_store_dwordx2 v[22:23], v[18:19], off offset:256
	v_mul_f32_e32 v5, v5, v5
	v_mul_f32_e32 v7, v7, v7
	v_fmac_f32_e32 v5, v4, v4
	v_fmac_f32_e32 v7, v6, v6
	v_add_f32_e32 v4, v5, v7
	v_add_f32_e32 v6, v8, v4
	s_waitcnt vmcnt(36)
	v_mov_b32_e32 v18, v236
	v_mov_b32_e32 v19, v237
	v_mov_b32_e32 v20, v238
	v_mov_b32_e32 v21, v239
	v_pk_add_f32 v[4:5], v[2:3], v[20:21]
	v_pk_add_f32 v[2:3], v[0:1], v[18:19]
	v_mul_f32_e32 v1, v5, v5
	v_mul_f32_e32 v0, v3, v3
	v_fmac_f32_e32 v0, v2, v2
	v_fmac_f32_e32 v1, v4, v4
	v_add_f32_e32 v0, v0, v1
	v_add_f32_e32 v0, v6, v0
	ds_bpermute_b32 v1, v116, v0
	global_store_dwordx4 v[24:25], v[2:5], off offset:576 sc1
	s_waitcnt lgkmcnt(0)
	v_add_f32_e32 v0, v0, v1
	ds_bpermute_b32 v1, v114, v0
	v_cvt_pk_bf16_f32 v2, v2, v3
	v_cvt_pk_bf16_f32 v3, v4, v5
	global_store_dwordx2 v[22:23], v[2:3], off offset:288
	s_and_saveexec_b64 s[16:17], s[12:13]
	s_cbranch_execz .LBB0_754
	s_waitcnt lgkmcnt(0)
	v_add_f32_e32 v2, v0, v1
	v_lshlrev_b64 v[0:1], 6, v[16:17]
	v_lshl_add_u64 v[0:1], s[26:27], 0, v[0:1]
	v_lshl_add_u64 v[0:1], s[56:57], 2, v[0:1]
	s_lshl_b32 s36, s74, 2
	v_lshl_add_u64 v[0:1], v[0:1], 0, s[36:37]
	global_store_dword v[0:1], v2, off
	s_branch .LBB0_754

;     __device__ __forceinline__ void operator()(const f32x4 (&acc)[2][2][4][2], const Unit& u, int wr, int wc, int fr, int fq) const {
;         const int row0 = u.pm * 256 + wr * 64 + fr, col0 = u.pn * 256 + wc * 32 + 4 * fq;
; #pragma unroll
;         for (int ai = 0; ai < 2; ++ai)
; #pragma unroll
;             for (int m = 0; m < 4; ++m) { float* rowp = part + (size_t)(row0 + ai * 128 + m * 16) * DM + col0;
; #pragma unroll
;                 for (int bj = 0; bj < 2; ++bj)
; #pragma unroll
;                     for (int n = 0; n < 2; ++n) *(f32x4*)(rowp + bj * 128 + n * 16) = acc[ai][bj][m][n]; }
.LBB0_827:
	v_lshl_add_u32 v146, s93, 8, v139
	v_lshl_or_b32 v148, s36, 8, v141
	v_ashrrev_i32_e32 v147, 31, v146
	v_ashrrev_i32_e32 v149, 31, v148
	v_lshlrev_b64 v[150:151], 12, v[146:147]
	v_lshl_add_u64 v[150:151], s[54:55], 0, v[150:151]
	v_lshlrev_b64 v[148:149], 2, v[148:149]
	v_lshl_add_u64 v[150:151], v[150:151], 0, v[148:149]
	global_store_dwordx4 v[150:151], v[124:127], off sc1
	global_store_dwordx4 v[150:151], v[120:123], off offset:64 sc1
	global_store_dwordx4 v[150:151], v[108:111], off offset:512 sc1
	global_store_dwordx4 v[150:151], v[100:103], off offset:576 sc1
	s_mov_b32 s36, 0x80000
	s_mov_b64 s[38:39], 0x80000
	v_or_b32_e32 v100, 16, v146
	v_ashrrev_i32_e32 v101, 31, v100
	v_lshlrev_b64 v[100:101], 12, v[100:101]
	v_lshl_add_u64 v[100:101], s[54:55], 0, v[100:101]
	v_lshl_add_u64 v[100:101], v[100:101], 0, v[148:149]
	global_store_dwordx4 v[100:101], v[116:119], off sc1
	global_store_dwordx4 v[100:101], v[112:115], off offset:64 sc1
	global_store_dwordx4 v[100:101], v[92:95], off offset:512 sc1
	global_store_dwordx4 v[100:101], v[84:87], off offset:576 sc1
	s_mov_b32 s93, s42
	s_mov_b64 s[40:41], s[64:65]
	v_or_b32_e32 v84, 32, v146
	v_ashrrev_i32_e32 v85, 31, v84
	v_lshlrev_b64 v[84:85], 12, v[84:85]
	v_lshl_add_u64 v[84:85], s[54:55], 0, v[84:85]
	v_lshl_add_u64 v[84:85], v[84:85], 0, v[148:149]
	global_store_dwordx4 v[84:85], v[104:107], off sc1
	global_store_dwordx4 v[84:85], v[96:99], off offset:64 sc1
	global_store_dwordx4 v[84:85], v[76:79], off offset:512 sc1
	global_store_dwordx4 v[84:85], v[72:75], off offset:576 sc1
	s_nop 1
	v_or_b32_e32 v72, 48, v146
	v_ashrrev_i32_e32 v73, 31, v72
	v_lshlrev_b64 v[72:73], 12, v[72:73]
	v_lshl_add_u64 v[72:73], s[54:55], 0, v[72:73]
	v_lshl_add_u64 v[72:73], v[72:73], 0, v[148:149]
	global_store_dwordx4 v[72:73], v[88:91], off sc1
	global_store_dwordx4 v[72:73], v[80:83], off offset:64 sc1
	global_store_dwordx4 v[72:73], v[68:71], off offset:512 sc1
	global_store_dwordx4 v[72:73], v[64:67], off offset:576 sc1
	s_nop 1
	v_add_co_u32_e32 v66, vcc, s36, v150
	s_mov_b32 s36, 0x90000
	s_nop 0
	v_addc_co_u32_e32 v67, vcc, 0, v151, vcc
	v_lshl_add_u64 v[64:65], v[150:151], 0, s[38:39]
	global_store_dwordx4 v[66:67], v[60:63], off sc1
	global_store_dwordx4 v[64:65], v[56:59], off offset:64 sc1
	global_store_dwordx4 v[64:65], v[44:47], off offset:512 sc1
	global_store_dwordx4 v[64:65], v[36:39], off offset:576 sc1
	s_mov_b64 s[38:39], 0x90000
	s_nop 0
	v_add_co_u32_e32 v38, vcc, s36, v150
	s_mov_b32 s36, 0xa0000
	s_nop 0
	v_addc_co_u32_e32 v39, vcc, 0, v151, vcc
	v_lshl_add_u64 v[36:37], v[150:151], 0, s[38:39]
	global_store_dwordx4 v[38:39], v[52:55], off sc1
	global_store_dwordx4 v[36:37], v[48:51], off offset:64 sc1
	global_store_dwordx4 v[36:37], v[28:31], off offset:512 sc1
	global_store_dwordx4 v[36:37], v[20:23], off offset:576 sc1
	s_mov_b64 s[38:39], 0xa0000
	s_nop 0
	v_add_co_u32_e32 v22, vcc, s36, v150
	v_lshl_add_u64 v[20:21], v[150:151], 0, s[38:39]
	s_nop 0
	v_addc_co_u32_e32 v23, vcc, 0, v151, vcc
	global_store_dwordx4 v[22:23], v[40:43], off sc1
	global_store_dwordx4 v[20:21], v[32:35], off offset:64 sc1
	global_store_dwordx4 v[20:21], v[12:15], off offset:512 sc1
	global_store_dwordx4 v[20:21], v[8:11], off offset:576 sc1
	s_mov_b64 s[38:39], 0xb0000
	s_mov_b32 s36, s58
	v_add_co_u32_e32 v10, vcc, 0xb0000, v150
	v_lshl_add_u64 v[8:9], v[150:151], 0, s[38:39]
	s_nop 0
	v_addc_co_u32_e32 v11, vcc, 0, v151, vcc
	s_and_b64 vcc, exec, s[56:57]
	s_mov_b64 s[38:39], s[62:63]
	global_store_dwordx4 v[10:11], v[24:27], off sc1
	global_store_dwordx4 v[8:9], v[16:19], off offset:64 sc1
	global_store_dwordx4 v[8:9], v[4:7], off offset:512 sc1
	global_store_dwordx4 v[8:9], v[0:3], off offset:576 sc1
	s_cbranch_vccnz .LBB0_854

; __device__ __forceinline__ unsigned pk2(float lo, float hi) { unsigned r; asm volatile("v_cvt_pk_bf16_f32 %0, %1, %2" : "=v"(r) : "v"(lo), "v"(hi)); return r; }
; #define RAW_BARRIER() do { asm volatile("s_waitcnt lgkmcnt(0)" ::: "memory"); __builtin_amdgcn_s_barrier(); asm volatile("" ::: "memory"); } while (0)
;     ...
;         RAW_BARRIER();
;         { u32x4 w;
;           w.x = pk2(tile[(k8 + 0) * 65 + n], tile[(k8 + 1) * 65 + n]); w.y = pk2(tile[(k8 + 2) * 65 + n], tile[(k8 + 3) * 65 + n]);
;           w.z = pk2(tile[(k8 + 4) * 65 + n], tile[(k8 + 5) * 65 + n]); w.w = pk2(tile[(k8 + 6) * 65 + n], tile[(k8 + 7) * 65 + n]);
;           *(u32x4*)(dst + (size_t)(n0 + n) * K + k0 + k8) = w; }
;         RAW_BARRIER();
.LBB0_872:
	s_waitcnt lgkmcnt(0)
	s_barrier
	ds_read_b32 v20, v16 offset:260
	ds_read_b32 v21, v15
	s_ashr_i32 s16, s9, 31
	v_add_u32_e32 v26, s7, v13
	s_lshr_b32 s7, s16, 28
	s_add_i32 s7, s9, s7
	s_ashr_i32 s7, s7, 4
	s_lshl_b32 s16, s7, 6
	s_lshl_b32 s7, s7, 10
	s_waitcnt lgkmcnt(0)
	v_cvt_pk_bf16_f32 v20, v21, v20
	ds_read2_b32 v[22:23], v16 offset0:130 offset1:195
	v_subrev_u32_e32 v26, s7, v26
	s_waitcnt lgkmcnt(0)
	v_cvt_pk_bf16_f32 v21, v22, v23
	ds_read2_b32 v[22:23], v19 offset0:4 offset1:69
	v_ashrrev_i32_e32 v27, 31, v26
	s_waitcnt lgkmcnt(0)
	v_cvt_pk_bf16_f32 v22, v22, v23
	ds_read2_b32 v[24:25], v19 offset0:134 offset1:199
	v_lshlrev_b64 v[26:27], 13, v[26:27]
	s_waitcnt lgkmcnt(0)
	v_cvt_pk_bf16_f32 v23, v24, v25
	v_lshl_add_u64 v[24:25], s[12:13], 0, v[26:27]
	s_ashr_i32 s17, s16, 31
	v_lshl_add_u64 v[24:25], s[16:17], 1, v[24:25]
	v_lshl_add_u64 v[24:25], v[24:25], 0, v[10:11]
	global_store_dwordx4 v[24:25], v[20:23], off sc1
	s_waitcnt lgkmcnt(0)
	s_barrier
	s_andn2_b64 vcc, exec, s[14:15]
	s_mov_b32 s7, s18
	s_mov_b32 s9, s8
	s_cbranch_vccz .LBB0_877

; __device__ __forceinline__ unsigned pk2(float lo, float hi) { unsigned r; asm volatile("v_cvt_pk_bf16_f32 %0, %1, %2" : "=v"(r) : "v"(lo), "v"(hi)); return r; }
;     ...
;         __syncthreads();
;         const int lane = threadIdx.x & 63, wv = threadIdx.x >> 6;
;         const int rbase = u.pm * 256 + (kq * 4 + u.pn) * 16 + wv * 2;
; #pragma unroll
;         for (int rr = 0; rr < 2; ++rr) {
;             const int row = rbase + rr; float sq = 0.f;
; #pragma unroll
;             for (int i = 0; i < 4; ++i) {
;                 const size_t o = (size_t)row * DM + i * 256 + lane * 4;
;                 f32x4 v = *(const f32x4*)(xold + o);
; #pragma unroll
;                 for (int q = 0; q < 4; ++q) v += *(const f32x4*)(part + (size_t)q * 1024 * DM + o);
;                 *(f32x4*)(xf_s + o) = v;
;                 u32x2 w; w.x = pk2(v[0], v[1]); w.y = pk2(v[2], v[3]); *(u32x2*)(xb_s + o) = w;
;                 sq += (v[0] * v[0] + v[1] * v[1]) + (v[2] * v[2] + v[3] * v[3]);
;             }
.LBB0_879:
	s_or_b64 exec, exec, s[10:11]
	s_add_u32 s22, s28, 0x4000000
	s_addc_u32 s23, s29, 0
	s_add_u32 s20, s20, 0x2000000
	s_addc_u32 s21, s21, 0
	s_lshr_b32 s8, s81, 2
	v_lshrrev_b32_e32 v0, 5, v166
	s_and_b32 s8, s8, 0xffffffc
	v_and_b32_e32 v0, 30, v0
	s_add_i32 s6, s6, s8
	v_lshl_or_b32 v0, s7, 8, v0
	v_lshl_add_u32 v2, s6, 4, v0
	v_ashrrev_i32_e32 v3, 31, v2
	v_lshlrev_b32_e32 v0, 2, v167
	v_lshlrev_b64 v[4:5], 10, v[2:3]
	v_or_b32_e32 v4, v4, v0
	v_lshlrev_b64 v[26:27], 2, v[4:5]
	v_lshl_add_u64 v[40:41], s[16:17], 0, v[26:27]
	s_mov_b32 s6, 0x400000
	v_add_co_u32_e32 v42, vcc, s6, v40
	s_mov_b32 s7, 0x800000
	s_nop 0
	v_addc_co_u32_e32 v43, vcc, 0, v41, vcc
	v_lshl_add_u64 v[38:39], s[14:15], 0, v[26:27]
	v_add_co_u32_e32 v44, vcc, s7, v40
	s_barrier
	global_load_dwordx4 v[6:9], v[38:39], off
	v_addc_co_u32_e32 v45, vcc, 0, v41, vcc
	s_mov_b32 s8, 0xc00000
	global_load_dwordx4 v[10:13], v[40:41], off
	global_load_dwordx4 v[14:17], v[42:43], off
	v_add_co_u32_e32 v46, vcc, s8, v40
	global_load_dwordx4 v[18:21], v[44:45], off
	s_nop 0
	v_addc_co_u32_e32 v47, vcc, 0, v41, vcc
	global_load_dwordx4 v[22:25], v[46:47], off
	v_lshl_add_u64 v[28:29], v[4:5], 1, s[20:21]
	v_lshl_add_u64 v[26:27], s[22:23], 0, v[26:27]
	v_mov_b32_e32 v31, v5
	v_or_b32_e32 v30, 0x100, v4
	v_lshl_add_u64 v[32:33], v[30:31], 2, s[22:23]
	v_lshl_add_u64 v[30:31], v[30:31], 1, s[20:21]
	v_mov_b32_e32 v35, v5
	v_or_b32_e32 v34, 0x200, v4
	v_lshl_add_u64 v[36:37], v[34:35], 2, s[22:23]
	v_lshl_add_u64 v[34:35], v[34:35], 1, s[20:21]
	v_mov_b32_e32 v1, 0
	v_or_b32_e32 v4, 0x300, v4
	s_mov_b64 s[24:25], 0x100000
	v_cmp_gt_u32_e64 s[10:11], 16, v167
	v_cmp_eq_u32_e32 vcc, 0, v167
	global_load_dwordx4 v[186:189], v[38:39], off offset:1024
	global_load_dwordx4 v[190:193], v[40:41], off offset:1024
	global_load_dwordx4 v[194:197], v[42:43], off offset:1024
	global_load_dwordx4 v[198:201], v[44:45], off offset:1024
	global_load_dwordx4 v[202:205], v[46:47], off offset:1024
	global_load_dwordx4 v[206:209], v[38:39], off offset:2048
	global_load_dwordx4 v[210:213], v[40:41], off offset:2048
	global_load_dwordx4 v[214:217], v[42:43], off offset:2048
	global_load_dwordx4 v[218:221], v[44:45], off offset:2048
	global_load_dwordx4 v[222:225], v[46:47], off offset:2048
	global_load_dwordx4 v[226:229], v[38:39], off offset:3072
	global_load_dwordx4 v[232:235], v[40:41], off offset:3072
	global_load_dwordx4 v[236:239], v[42:43], off offset:3072
	global_load_dwordx4 v[240:243], v[44:45], off offset:3072
	global_load_dwordx4 v[244:247], v[46:47], off offset:3072
	s_waitcnt vmcnt(18)
	v_pk_add_f32 v[8:9], v[8:9], v[12:13]
	v_pk_add_f32 v[6:7], v[6:7], v[10:11]
	s_waitcnt vmcnt(17)
	v_pk_add_f32 v[8:9], v[8:9], v[16:17]
	v_pk_add_f32 v[6:7], v[6:7], v[14:15]
	s_waitcnt vmcnt(16)
	v_pk_add_f32 v[8:9], v[8:9], v[20:21]
	v_pk_add_f32 v[6:7], v[6:7], v[18:19]
	s_waitcnt vmcnt(15)
	v_pk_add_f32 v[8:9], v[8:9], v[24:25]
	v_pk_add_f32 v[6:7], v[6:7], v[22:23]
	global_store_dwordx4 v[26:27], v[6:9], off sc1
	v_cvt_pk_bf16_f32 v10, v6, v7
	v_cvt_pk_bf16_f32 v11, v8, v9
	global_store_dwordx2 v[28:29], v[10:11], off
	s_nop 0
	v_mul_f32_e32 v7, v7, v7
	v_mul_f32_e32 v9, v9, v9
	v_fmac_f32_e32 v7, v6, v6
	v_fmac_f32_e32 v9, v8, v8
	v_add_f32_e32 v6, v7, v9
	s_waitcnt vmcnt(12)
	v_mov_b32_e32 v10, v186
	v_mov_b32_e32 v11, v187
	v_mov_b32_e32 v12, v188
	v_mov_b32_e32 v13, v189
	v_mov_b32_e32 v14, v190
	v_mov_b32_e32 v15, v191
	v_mov_b32_e32 v16, v192
	v_mov_b32_e32 v17, v193
	v_mov_b32_e32 v18, v194
	v_mov_b32_e32 v19, v195
	v_mov_b32_e32 v20, v196
	v_mov_b32_e32 v21, v197
	v_mov_b32_e32 v22, v198
	v_mov_b32_e32 v23, v199
	v_mov_b32_e32 v24, v200
	v_mov_b32_e32 v25, v201
	v_mov_b32_e32 v26, v202
	v_mov_b32_e32 v27, v203
	v_mov_b32_e32 v28, v204
	v_mov_b32_e32 v29, v205
	v_pk_add_f32 v[12:13], v[12:13], v[16:17]
	v_pk_add_f32 v[10:11], v[10:11], v[14:15]
	v_pk_add_f32 v[12:13], v[12:13], v[20:21]
	v_pk_add_f32 v[10:11], v[10:11], v[18:19]
	v_pk_add_f32 v[12:13], v[12:13], v[24:25]
	v_pk_add_f32 v[10:11], v[10:11], v[22:23]
	v_pk_add_f32 v[12:13], v[12:13], v[28:29]
	v_pk_add_f32 v[10:11], v[10:11], v[26:27]
	global_store_dwordx4 v[32:33], v[10:13], off sc1
	v_cvt_pk_bf16_f32 v14, v10, v11
	v_cvt_pk_bf16_f32 v15, v12, v13
	global_store_dwordx2 v[30:31], v[14:15], off
	s_nop 0
	v_mul_f32_e32 v7, v11, v11
	v_mul_f32_e32 v8, v13, v13
	v_fmac_f32_e32 v7, v10, v10
	v_fmac_f32_e32 v8, v12, v12
	v_add_f32_e32 v7, v7, v8
	v_add_f32_e32 v6, v6, v7
	s_waitcnt vmcnt(9)
	v_mov_b32_e32 v14, v206
	v_mov_b32_e32 v15, v207
	v_mov_b32_e32 v16, v208
	v_mov_b32_e32 v17, v209
	v_mov_b32_e32 v18, v210
	v_mov_b32_e32 v19, v211
	v_mov_b32_e32 v20, v212
	v_mov_b32_e32 v21, v213
	v_mov_b32_e32 v22, v214
	v_mov_b32_e32 v23, v215
	v_mov_b32_e32 v24, v216
	v_mov_b32_e32 v25, v217
	v_mov_b32_e32 v26, v218
	v_mov_b32_e32 v27, v219
	v_mov_b32_e32 v28, v220
	v_mov_b32_e32 v29, v221
	v_mov_b32_e32 v30, v222
	v_mov_b32_e32 v31, v223
	v_mov_b32_e32 v32, v224
	v_mov_b32_e32 v33, v225
	v_pk_add_f32 v[16:17], v[16:17], v[20:21]
	v_pk_add_f32 v[14:15], v[14:15], v[18:19]
	v_pk_add_f32 v[16:17], v[16:17], v[24:25]
	v_pk_add_f32 v[14:15], v[14:15], v[22:23]
	v_pk_add_f32 v[16:17], v[16:17], v[28:29]
	v_pk_add_f32 v[14:15], v[14:15], v[26:27]
	v_pk_add_f32 v[16:17], v[16:17], v[32:33]
	v_pk_add_f32 v[14:15], v[14:15], v[30:31]
	global_store_dwordx4 v[36:37], v[14:17], off sc1
	v_cvt_pk_bf16_f32 v18, v14, v15
	v_cvt_pk_bf16_f32 v19, v16, v17
	global_store_dwordx2 v[34:35], v[18:19], off
	s_nop 0
	v_mul_f32_e32 v7, v15, v15
	v_mul_f32_e32 v8, v17, v17
	v_fmac_f32_e32 v7, v14, v14
	v_fmac_f32_e32 v8, v16, v16
	v_add_f32_e32 v7, v7, v8
	v_add_f32_e32 v10, v6, v7
	v_mbcnt_hi_u32_b32 v40, -1, v168
	v_lshl_add_u64 v[38:39], s[18:19], 0, v[0:1]
	v_and_b32_e32 v1, 64, v40
	v_xor_b32_e32 v41, 32, v40
	v_add_u32_e32 v44, 64, v1
	v_cmp_lt_i32_e64 s[12:13], v41, v44
	v_xor_b32_e32 v42, 16, v40
	v_xor_b32_e32 v43, 8, v40
	v_cndmask_b32_e64 v1, v40, v41, s[12:13]
	v_lshlrev_b32_e32 v1, 2, v1
	v_cmp_lt_i32_e64 s[12:13], v42, v44
	v_xor_b32_e32 v11, 2, v40
	v_xor_b32_e32 v12, 1, v40
	s_waitcnt vmcnt(6)
; __device__ __forceinline__ unsigned pk2(float lo, float hi) { unsigned r; asm volatile("v_cvt_pk_bf16_f32 %0, %1, %2" : "=v"(r) : "v"(lo), "v"(hi)); return r; }
;     ...
;             for (int i = 0; i < 4; ++i) {
;                 const size_t o = (size_t)row * DM + i * 256 + lane * 4;
;                 f32x4 v = *(const f32x4*)(xold + o);
; #pragma unroll
;                 for (int q = 0; q < 4; ++q) v += *(const f32x4*)(part + (size_t)q * 1024 * DM + o);
;                 *(f32x4*)(xf_s + o) = v;
;                 u32x2 w; w.x = pk2(v[0], v[1]); w.y = pk2(v[2], v[3]); *(u32x2*)(xb_s + o) = w;
;                 sq += (v[0] * v[0] + v[1] * v[1]) + (v[2] * v[2] + v[3] * v[3]);
;             }
; #pragma unroll
;             for (int o = 32; o >= 1; o >>= 1) sq += __shfl_xor(sq, o);
;             if (lane < 16) ssq_s[(size_t)row * 16 + lane] = lane == 0 ? sq : 0.f;
;         }
	v_mov_b32_e32 v18, v226
	v_mov_b32_e32 v19, v227
	v_mov_b32_e32 v20, v228
	v_mov_b32_e32 v21, v229
	v_mov_b32_e32 v22, v232
	v_mov_b32_e32 v23, v233
	v_mov_b32_e32 v24, v234
	v_mov_b32_e32 v25, v235
	v_mov_b32_e32 v26, v236
	v_mov_b32_e32 v27, v237
	v_mov_b32_e32 v28, v238
	v_mov_b32_e32 v29, v239
	v_mov_b32_e32 v30, v240
	v_mov_b32_e32 v31, v241
	v_mov_b32_e32 v32, v242
	v_mov_b32_e32 v33, v243
	v_mov_b32_e32 v34, v244
	v_mov_b32_e32 v35, v245
	v_mov_b32_e32 v36, v246
	v_mov_b32_e32 v37, v247
	v_pk_add_f32 v[6:7], v[20:21], v[24:25]
	v_pk_add_f32 v[8:9], v[18:19], v[22:23]
	v_pk_add_f32 v[6:7], v[6:7], v[28:29]
	v_pk_add_f32 v[8:9], v[8:9], v[26:27]
	v_pk_add_f32 v[6:7], v[6:7], v[32:33]
	v_pk_add_f32 v[8:9], v[8:9], v[30:31]
	v_pk_add_f32 v[18:19], v[6:7], v[36:37]
	v_pk_add_f32 v[16:17], v[8:9], v[34:35]
	v_mul_f32_e32 v7, v19, v19
	v_mul_f32_e32 v6, v17, v17
	v_fmac_f32_e32 v6, v16, v16
	v_fmac_f32_e32 v7, v18, v18
	v_add_f32_e32 v6, v6, v7
	v_add_f32_e32 v6, v10, v6
	ds_bpermute_b32 v7, v1, v6
	v_cndmask_b32_e64 v8, v40, v42, s[12:13]
	v_lshlrev_b32_e32 v8, 2, v8
	v_cmp_lt_i32_e64 s[12:13], v43, v44
	v_xor_b32_e32 v10, 4, v40
	s_waitcnt lgkmcnt(0)
	v_add_f32_e32 v6, v6, v7
	ds_bpermute_b32 v7, v8, v6
	v_cndmask_b32_e64 v9, v40, v43, s[12:13]
	v_lshlrev_b32_e32 v9, 2, v9
	v_cmp_lt_i32_e64 s[12:13], v10, v44
	s_waitcnt lgkmcnt(0)
	v_add_f32_e32 v6, v6, v7
	ds_bpermute_b32 v7, v9, v6
	v_cndmask_b32_e64 v10, v40, v10, s[12:13]
	v_lshlrev_b32_e32 v10, 2, v10
	v_cmp_lt_i32_e64 s[12:13], v11, v44
	s_waitcnt lgkmcnt(0)
	v_add_f32_e32 v13, v6, v7
	ds_bpermute_b32 v14, v10, v13
	v_cndmask_b32_e64 v11, v40, v11, s[12:13]
	v_lshlrev_b32_e32 v11, 2, v11
	v_cmp_lt_i32_e64 s[12:13], v12, v44
	v_lshl_add_u64 v[6:7], v[38:39], 0, s[24:25]
	s_waitcnt lgkmcnt(0)
	v_add_f32_e32 v14, v13, v14
	ds_bpermute_b32 v15, v11, v14
	v_cndmask_b32_e64 v20, v40, v12, s[12:13]
	v_lshl_add_u64 v[12:13], v[4:5], 2, s[22:23]
	global_store_dwordx4 v[12:13], v[16:19], off sc1
	v_lshlrev_b32_e32 v12, 2, v20
	s_waitcnt lgkmcnt(0)
	v_add_f32_e32 v13, v14, v15
	ds_bpermute_b32 v14, v12, v13
	v_lshl_add_u64 v[4:5], v[4:5], 1, s[20:21]
	v_cvt_pk_bf16_f32 v16, v16, v17
	v_cvt_pk_bf16_f32 v17, v18, v19
	global_store_dwordx2 v[4:5], v[16:17], off
	s_and_saveexec_b64 s[12:13], s[10:11]
	s_cbranch_execz .LBB0_881
	v_lshlrev_b64 v[4:5], 6, v[2:3]
	s_waitcnt lgkmcnt(0)
	v_add_f32_e32 v3, v13, v14
	v_lshl_add_u64 v[4:5], v[6:7], 0, v[4:5]
	v_cndmask_b32_e32 v3, 0, v3, vcc
	global_store_dword v[4:5], v3, off
.LBB0_881:
	s_or_b64 exec, exec, s[12:13]
	v_or_b32_e32 v2, 1, v2
	v_ashrrev_i32_e32 v3, 31, v2
	v_lshlrev_b64 v[4:5], 10, v[2:3]
	v_or_b32_e32 v4, v4, v0
	v_lshlrev_b64 v[34:35], 2, v[4:5]
	v_lshl_add_u64 v[48:49], s[16:17], 0, v[34:35]
	v_add_co_u32_e64 v50, s[12:13], s6, v48
	v_lshl_add_u64 v[46:47], s[14:15], 0, v[34:35]
	s_nop 0
	v_addc_co_u32_e64 v51, s[12:13], 0, v49, s[12:13]
	v_add_co_u32_e64 v52, s[12:13], s7, v48
	s_waitcnt lgkmcnt(0)
	global_load_dwordx4 v[14:17], v[46:47], off
	v_addc_co_u32_e64 v53, s[12:13], 0, v49, s[12:13]
	global_load_dwordx4 v[18:21], v[48:49], off
	global_load_dwordx4 v[22:25], v[50:51], off
	v_add_co_u32_e64 v54, s[12:13], s8, v48
	global_load_dwordx4 v[26:29], v[52:53], off
	s_nop 0
	v_addc_co_u32_e64 v55, s[12:13], 0, v49, s[12:13]
	global_load_dwordx4 v[30:33], v[54:55], off
	v_lshl_add_u64 v[36:37], v[4:5], 1, s[20:21]
	v_lshl_add_u64 v[34:35], s[22:23], 0, v[34:35]
	v_mov_b32_e32 v39, v5
	v_or_b32_e32 v38, 0x100, v4
	v_lshl_add_u64 v[40:41], v[38:39], 2, s[22:23]
	v_lshl_add_u64 v[38:39], v[38:39], 1, s[20:21]
	v_mov_b32_e32 v43, v5
	v_or_b32_e32 v42, 0x200, v4
	v_lshl_add_u64 v[44:45], v[42:43], 2, s[22:23]
	v_lshl_add_u64 v[42:43], v[42:43], 1, s[20:21]
	v_or_b32_e32 v4, 0x300, v4
	global_load_dwordx4 v[186:189], v[46:47], off offset:1024
	global_load_dwordx4 v[190:193], v[48:49], off offset:1024
	global_load_dwordx4 v[194:197], v[50:51], off offset:1024
	global_load_dwordx4 v[198:201], v[52:53], off offset:1024
	global_load_dwordx4 v[202:205], v[54:55], off offset:1024
	global_load_dwordx4 v[206:209], v[46:47], off offset:2048
	global_load_dwordx4 v[210:213], v[48:49], off offset:2048
	global_load_dwordx4 v[214:217], v[50:51], off offset:2048
	global_load_dwordx4 v[218:221], v[52:53], off offset:2048
	global_load_dwordx4 v[222:225], v[54:55], off offset:2048
	global_load_dwordx4 v[226:229], v[46:47], off offset:3072
	global_load_dwordx4 v[232:235], v[48:49], off offset:3072
	global_load_dwordx4 v[236:239], v[50:51], off offset:3072
	global_load_dwordx4 v[240:243], v[52:53], off offset:3072
	global_load_dwordx4 v[244:247], v[54:55], off offset:3072
	s_waitcnt vmcnt(18)
	v_pk_add_f32 v[16:17], v[16:17], v[20:21]
	v_pk_add_f32 v[14:15], v[14:15], v[18:19]
	s_waitcnt vmcnt(17)
	v_pk_add_f32 v[16:17], v[16:17], v[24:25]
	v_pk_add_f32 v[14:15], v[14:15], v[22:23]
	s_waitcnt vmcnt(16)
; __device__ __forceinline__ unsigned pk2(float lo, float hi) { unsigned r; asm volatile("v_cvt_pk_bf16_f32 %0, %1, %2" : "=v"(r) : "v"(lo), "v"(hi)); return r; }
;     ...
;         const int lane = threadIdx.x & 63, wv = threadIdx.x >> 6;
;         const int rbase = u.pm * 256 + (kq * 4 + u.pn) * 16 + wv * 2;
; #pragma unroll
;         for (int rr = 0; rr < 2; ++rr) {
;             const int row = rbase + rr; float sq = 0.f;
; #pragma unroll
;             for (int i = 0; i < 4; ++i) {
;                 const size_t o = (size_t)row * DM + i * 256 + lane * 4;
;                 f32x4 v = *(const f32x4*)(xold + o);
; #pragma unroll
;                 for (int q = 0; q < 4; ++q) v += *(const f32x4*)(part + (size_t)q * 1024 * DM + o);
;                 *(f32x4*)(xf_s + o) = v;
;                 u32x2 w; w.x = pk2(v[0], v[1]); w.y = pk2(v[2], v[3]); *(u32x2*)(xb_s + o) = w;
;                 sq += (v[0] * v[0] + v[1] * v[1]) + (v[2] * v[2] + v[3] * v[3]);
;             }
; #pragma unroll
;             for (int o = 32; o >= 1; o >>= 1) sq += __shfl_xor(sq, o);
;             if (lane < 16) ssq_s[(size_t)row * 16 + lane] = lane == 0 ? sq : 0.f;
;         }
	v_pk_add_f32 v[16:17], v[16:17], v[28:29]
	v_pk_add_f32 v[14:15], v[14:15], v[26:27]
	s_waitcnt vmcnt(15)
	v_pk_add_f32 v[16:17], v[16:17], v[32:33]
	v_pk_add_f32 v[14:15], v[14:15], v[30:31]
	global_store_dwordx4 v[34:35], v[14:17], off sc1
	v_cvt_pk_bf16_f32 v18, v14, v15
	v_cvt_pk_bf16_f32 v19, v16, v17
	global_store_dwordx2 v[36:37], v[18:19], off
	s_nop 0
	v_mul_f32_e32 v0, v15, v15
	v_mul_f32_e32 v13, v17, v17
	v_fmac_f32_e32 v0, v14, v14
	v_fmac_f32_e32 v13, v16, v16
	v_add_f32_e32 v0, v0, v13
	s_waitcnt vmcnt(12)
	v_mov_b32_e32 v18, v186
	v_mov_b32_e32 v19, v187
	v_mov_b32_e32 v20, v188
	v_mov_b32_e32 v21, v189
	v_mov_b32_e32 v22, v190
	v_mov_b32_e32 v23, v191
	v_mov_b32_e32 v24, v192
	v_mov_b32_e32 v25, v193
	v_mov_b32_e32 v26, v194
	v_mov_b32_e32 v27, v195
	v_mov_b32_e32 v28, v196
	v_mov_b32_e32 v29, v197
	v_mov_b32_e32 v30, v198
	v_mov_b32_e32 v31, v199
	v_mov_b32_e32 v32, v200
	v_mov_b32_e32 v33, v201
	v_mov_b32_e32 v34, v202
	v_mov_b32_e32 v35, v203
	v_mov_b32_e32 v36, v204
	v_mov_b32_e32 v37, v205
	v_pk_add_f32 v[20:21], v[20:21], v[24:25]
	v_pk_add_f32 v[18:19], v[18:19], v[22:23]
	v_pk_add_f32 v[20:21], v[20:21], v[28:29]
	v_pk_add_f32 v[18:19], v[18:19], v[26:27]
	v_pk_add_f32 v[20:21], v[20:21], v[32:33]
	v_pk_add_f32 v[18:19], v[18:19], v[30:31]
	v_pk_add_f32 v[20:21], v[20:21], v[36:37]
	v_pk_add_f32 v[18:19], v[18:19], v[34:35]
	global_store_dwordx4 v[40:41], v[18:21], off sc1
	v_cvt_pk_bf16_f32 v22, v18, v19
	v_cvt_pk_bf16_f32 v23, v20, v21
	global_store_dwordx2 v[38:39], v[22:23], off
	s_nop 0
	v_mul_f32_e32 v13, v19, v19
	v_mul_f32_e32 v14, v21, v21
	v_fmac_f32_e32 v13, v18, v18
	v_fmac_f32_e32 v14, v20, v20
	v_add_f32_e32 v13, v13, v14
	v_add_f32_e32 v0, v0, v13
	s_waitcnt vmcnt(9)
	v_mov_b32_e32 v22, v206
	v_mov_b32_e32 v23, v207
	v_mov_b32_e32 v24, v208
	v_mov_b32_e32 v25, v209
	v_mov_b32_e32 v26, v210
	v_mov_b32_e32 v27, v211
	v_mov_b32_e32 v28, v212
	v_mov_b32_e32 v29, v213
	v_mov_b32_e32 v30, v214
	v_mov_b32_e32 v31, v215
	v_mov_b32_e32 v32, v216
	v_mov_b32_e32 v33, v217
	v_mov_b32_e32 v34, v218
	v_mov_b32_e32 v35, v219
	v_mov_b32_e32 v36, v220
	v_mov_b32_e32 v37, v221
	v_mov_b32_e32 v38, v222
	v_mov_b32_e32 v39, v223
	v_mov_b32_e32 v40, v224
	v_mov_b32_e32 v41, v225
	v_pk_add_f32 v[24:25], v[24:25], v[28:29]
	v_pk_add_f32 v[22:23], v[22:23], v[26:27]
	v_pk_add_f32 v[24:25], v[24:25], v[32:33]
	v_pk_add_f32 v[22:23], v[22:23], v[30:31]
	v_pk_add_f32 v[24:25], v[24:25], v[36:37]
	v_pk_add_f32 v[22:23], v[22:23], v[34:35]
	v_pk_add_f32 v[24:25], v[24:25], v[40:41]
	v_pk_add_f32 v[22:23], v[22:23], v[38:39]
	global_store_dwordx4 v[44:45], v[22:25], off sc1
	v_cvt_pk_bf16_f32 v26, v22, v23
	v_cvt_pk_bf16_f32 v27, v24, v25
	global_store_dwordx2 v[42:43], v[26:27], off
	s_nop 0
	v_mul_f32_e32 v13, v23, v23
	v_mul_f32_e32 v14, v25, v25
	v_fmac_f32_e32 v13, v22, v22
	v_fmac_f32_e32 v14, v24, v24
	v_add_f32_e32 v13, v13, v14
	v_add_f32_e32 v0, v0, v13
	s_waitcnt vmcnt(6)
	v_mov_b32_e32 v26, v226
	v_mov_b32_e32 v27, v227
	v_mov_b32_e32 v28, v228
	v_mov_b32_e32 v29, v229
	v_mov_b32_e32 v30, v232
	v_mov_b32_e32 v31, v233
	v_mov_b32_e32 v32, v234
	v_mov_b32_e32 v33, v235
	v_mov_b32_e32 v34, v236
	v_mov_b32_e32 v35, v237
	v_mov_b32_e32 v36, v238
	v_mov_b32_e32 v37, v239
	v_mov_b32_e32 v38, v240
	v_mov_b32_e32 v39, v241
	v_mov_b32_e32 v40, v242
	v_mov_b32_e32 v41, v243
	v_mov_b32_e32 v42, v244
	v_mov_b32_e32 v43, v245
	v_mov_b32_e32 v44, v246
	v_mov_b32_e32 v45, v247
	v_pk_add_f32 v[14:15], v[28:29], v[32:33]
	v_pk_add_f32 v[16:17], v[26:27], v[30:31]
	v_pk_add_f32 v[14:15], v[14:15], v[36:37]
	v_pk_add_f32 v[16:17], v[16:17], v[34:35]
	v_pk_add_f32 v[14:15], v[14:15], v[40:41]
	v_pk_add_f32 v[18:19], v[16:17], v[38:39]
	v_pk_add_f32 v[16:17], v[14:15], v[44:45]
	v_pk_add_f32 v[14:15], v[18:19], v[42:43]
	v_mul_f32_e32 v18, v17, v17
	v_mul_f32_e32 v13, v15, v15
	v_fmac_f32_e32 v13, v14, v14
	v_fmac_f32_e32 v18, v16, v16
	v_add_f32_e32 v13, v13, v18
	v_add_f32_e32 v0, v0, v13
	ds_bpermute_b32 v1, v1, v0
	s_waitcnt lgkmcnt(0)
	v_add_f32_e32 v0, v0, v1
	ds_bpermute_b32 v1, v8, v0
	s_waitcnt lgkmcnt(0)
	v_add_f32_e32 v0, v0, v1
	ds_bpermute_b32 v1, v9, v0
	s_waitcnt lgkmcnt(0)
	v_add_f32_e32 v0, v0, v1
	ds_bpermute_b32 v1, v10, v0
	s_waitcnt lgkmcnt(0)
	v_add_f32_e32 v8, v0, v1
	ds_bpermute_b32 v9, v11, v8
	v_lshl_add_u64 v[0:1], v[4:5], 2, s[22:23]
	global_store_dwordx4 v[0:1], v[14:17], off sc1
	v_lshl_add_u64 v[4:5], v[4:5], 1, s[20:21]
	s_waitcnt lgkmcnt(0)
	v_add_f32_e32 v0, v8, v9
	ds_bpermute_b32 v1, v12, v0
	v_cvt_pk_bf16_f32 v8, v14, v15
	v_cvt_pk_bf16_f32 v9, v16, v17
	global_store_dwordx2 v[4:5], v[8:9], off
	s_and_saveexec_b64 s[12:13], s[10:11]
	s_cbranch_execz .LBB0_883
	v_lshlrev_b64 v[2:3], 6, v[2:3]
	s_waitcnt lgkmcnt(0)
	v_add_f32_e32 v0, v0, v1
	v_lshl_add_u64 v[2:3], v[6:7], 0, v[2:3]
	v_cndmask_b32_e32 v0, 0, v0, vcc
	global_store_dword v[2:3], v0, off

; __device__ __forceinline__ unsigned pk2(float lo, float hi) { unsigned r; asm volatile("v_cvt_pk_bf16_f32 %0, %1, %2" : "=v"(r) : "v"(lo), "v"(hi)); return r; }
; #define RAW_BARRIER() do { asm volatile("s_waitcnt lgkmcnt(0)" ::: "memory"); __builtin_amdgcn_s_barrier(); asm volatile("" ::: "memory"); } while (0)
;     ...
;         RAW_BARRIER();
;         { u32x4 w;
;           w.x = pk2(tile[(k8 + 0) * 65 + n], tile[(k8 + 1) * 65 + n]); w.y = pk2(tile[(k8 + 2) * 65 + n], tile[(k8 + 3) * 65 + n]);
;           w.z = pk2(tile[(k8 + 4) * 65 + n], tile[(k8 + 5) * 65 + n]); w.w = pk2(tile[(k8 + 6) * 65 + n], tile[(k8 + 7) * 65 + n]);
;           *(u32x4*)(dst + (size_t)(n0 + n) * K + k0 + k8) = w; }
;         RAW_BARRIER();
.LBB0_887:
	s_waitcnt lgkmcnt(0)
	s_barrier
	ds_read_b32 v20, v16 offset:260
	ds_read_b32 v21, v15
	v_add_u32_e32 v24, s9, v13
	s_add_i32 s14, s7, 0xfffffe00
	v_ashrrev_i32_e32 v25, 31, v24
	s_and_b32 s9, s14, 0x7fffffc0
	v_lshlrev_b64 v[24:25], 13, v[24:25]
	s_lshl_b32 s14, s9, 1
	v_lshl_add_u64 v[24:25], s[12:13], 0, v[24:25]
	s_waitcnt lgkmcnt(0)
	v_cvt_pk_bf16_f32 v20, v21, v20
	ds_read2_b32 v[22:23], v16 offset0:130 offset1:195
	v_lshl_add_u64 v[24:25], v[24:25], 0, s[14:15]
	s_waitcnt lgkmcnt(0)
	v_cvt_pk_bf16_f32 v21, v22, v23
	ds_read2_b32 v[22:23], v19 offset0:4 offset1:69
	v_lshl_add_u64 v[24:25], v[24:25], 0, v[10:11]
	s_waitcnt lgkmcnt(0)
	v_cvt_pk_bf16_f32 v22, v22, v23
	ds_read2_b32 v[26:27], v19 offset0:134 offset1:199
	s_waitcnt lgkmcnt(0)
	v_cvt_pk_bf16_f32 v23, v26, v27
	global_store_dwordx4 v[24:25], v[20:23], off sc1
	s_waitcnt lgkmcnt(0)
	s_barrier
	s_addk_i32 s6, 0x80
	s_addk_i32 s7, 0x200
	s_addk_i32 s8, 0x2000
	s_and_b64 vcc, exec, s[16:17]
	s_cbranch_vccnz .LBB0_890

; __device__ __forceinline__ unsigned pk2(float lo, float hi) { unsigned r; asm volatile("v_cvt_pk_bf16_f32 %0, %1, %2" : "=v"(r) : "v"(lo), "v"(hi)); return r; }
;     __device__ __forceinline__ void operator()(const f32x4 (&acc)[2][2][4][2], const Unit& u, int wr, int wc, int fr, int fq) const {
;         const int row0 = u.pm * 256 + wr * 64 + fr, col0 = u.pn * 256 + wc * 32 + 4 * fq;
;         const float* xo = (u.pm < 64) ? xoldA : (xoldB - (size_t)T_P * DM);
; #pragma unroll
;         for (int ai = 0; ai < 2; ++ai)
; #pragma unroll
;             for (int m = 0; m < 4; ++m) {
;                 const int row = row0 + ai * 128 + m * 16; const size_t ro = (size_t)row * DM + col0;
;                 float s = 0.f;
; #pragma unroll
;                 for (int bj = 0; bj < 2; ++bj)
; #pragma unroll
;                     for (int n = 0; n < 2; ++n) {
;                         const size_t o = ro + bj * 128 + n * 16;
;                         const f32x4 xn = *(const f32x4*)(xo + o) + acc[ai][bj][m][n];
;                         *(f32x4*)(xf + o) = xn;
;                         u32x2 w; w.x = pk2(xn[0], xn[1]); w.y = pk2(xn[2], xn[3]); *(u32x2*)(xb + o) = w;
;                         s += (xn[0] * xn[0] + xn[1] * xn[1]) + (xn[2] * xn[2] + xn[3] * xn[3]);
;                     }
;                 s += __shfl_xor(s, 16); s += __shfl_xor(s, 32);
;                 if (fq == 0) ssq[(size_t)row * 16 + u.pn * 4 + wc] = s;
;             }
;     }
.LBB0_1037:
	v_lshl_add_u32 v138, s58, 8, v140
	v_lshl_or_b32 v136, s56, 8, v142
	v_ashrrev_i32_e32 v139, 31, v138
	v_ashrrev_i32_e32 v137, 31, v136
	v_lshlrev_b64 v[148:149], 10, v[138:139]
	s_cmp_lt_i32 s58, 64
	v_lshl_add_u64 v[152:153], v[148:149], 0, v[136:137]
	s_cselect_b32 s17, s21, -1
	s_cselect_b32 s16, s20, 0xfc000000
	v_lshlrev_b64 v[154:155], 2, v[152:153]
	v_lshl_add_u64 v[156:157], s[16:17], 0, v[154:155]
	v_subrev_u32_e32 v162, s16, v156
	v_add_u32_e32 v163, 0x0, v162
	global_load_dwordx4 v[170:173], v163, s[16:17]
	v_add_u32_e32 v163, 0x40, v162
	global_load_dwordx4 v[174:177], v163, s[16:17]
	v_add_u32_e32 v163, 0x200, v162
	global_load_dwordx4 v[178:181], v163, s[16:17]
	v_add_u32_e32 v163, 0x240, v162
	global_load_dwordx4 v[182:185], v163, s[16:17]
	v_add_u32_e32 v163, 0x10000, v162
	global_load_dwordx4 v[186:189], v163, s[16:17]
	v_add_u32_e32 v163, 0x10040, v162
	global_load_dwordx4 v[190:193], v163, s[16:17]
	v_add_u32_e32 v163, 0x10200, v162
	global_load_dwordx4 v[194:197], v163, s[16:17]
	v_add_u32_e32 v163, 0x10240, v162
	global_load_dwordx4 v[198:201], v163, s[16:17]
	v_add_u32_e32 v163, 0x20000, v162
	global_load_dwordx4 v[202:205], v163, s[16:17]
	v_add_u32_e32 v163, 0x20040, v162
	global_load_dwordx4 v[206:209], v163, s[16:17]
	v_add_u32_e32 v163, 0x20200, v162
	global_load_dwordx4 v[210:213], v163, s[16:17]
	v_add_u32_e32 v163, 0x20240, v162
	global_load_dwordx4 v[232:235], v163, s[16:17]
	v_add_u32_e32 v163, 0x30000, v162
	global_load_dwordx4 v[236:239], v163, s[16:17]
	v_add_u32_e32 v163, 0x30040, v162
	global_load_dwordx4 v[240:243], v163, s[16:17]
	v_add_u32_e32 v163, 0x30200, v162
	global_load_dwordx4 v[244:247], v163, s[16:17]
	v_add_u32_e32 v163, 0x30240, v162
	global_load_dwordx4 v[248:251], v163, s[16:17]
	v_add_u32_e32 v163, 0x80000, v162
	global_load_dwordx4 v[252:255], v163, s[16:17]
	v_lshl_add_u64 v[158:159], v[152:153], 1, s[26:27]
	v_lshl_add_u64 v[160:161], s[20:21], 0, v[154:155]
	v_xor_b32_e32 v147, 32, v146
	s_lshl_b32 s56, s56, 2
	s_ashr_i32 s57, s56, 31
	s_waitcnt vmcnt(16)
	v_mov_b32_e32 v148, v170
	v_mov_b32_e32 v149, v171
	v_mov_b32_e32 v150, v172
	v_mov_b32_e32 v151, v173
	v_add_u32_e32 v163, 0x80040, v162
	global_load_dwordx4 v[170:173], v163, s[16:17]
	v_pk_add_f32 v[126:127], v[126:127], v[150:151]
	v_pk_add_f32 v[124:125], v[124:125], v[148:149]
	global_store_dwordx4 v[160:161], v[124:127], off sc1
	v_cvt_pk_bf16_f32 v148, v124, v125
	v_cvt_pk_bf16_f32 v149, v126, v127
	global_store_dwordx2 v[158:159], v[148:149], off
	s_waitcnt vmcnt(18)
	v_mov_b32_e32 v148, v174
	v_mov_b32_e32 v149, v175
	v_mov_b32_e32 v150, v176
	v_mov_b32_e32 v151, v177
	v_add_u32_e32 v163, 0x80200, v162
	global_load_dwordx4 v[174:177], v163, s[16:17]
	v_pk_add_f32 v[122:123], v[122:123], v[150:151]
	v_pk_add_f32 v[120:121], v[120:121], v[148:149]
	global_store_dwordx4 v[160:161], v[120:123], off offset:64 sc1
	v_cvt_pk_bf16_f32 v148, v120, v121
	v_cvt_pk_bf16_f32 v149, v122, v123
	global_store_dwordx2 v[158:159], v[148:149], off offset:32
	s_waitcnt vmcnt(20)
	v_mov_b32_e32 v148, v178
	v_mov_b32_e32 v149, v179
	v_mov_b32_e32 v150, v180
	v_mov_b32_e32 v151, v181
	v_add_u32_e32 v163, 0x80240, v162
	global_load_dwordx4 v[178:181], v163, s[16:17]
	v_pk_add_f32 v[150:151], v[118:119], v[150:151]
	v_pk_add_f32 v[148:149], v[116:117], v[148:149]
	global_store_dwordx4 v[160:161], v[148:151], off offset:512 sc1
	v_cvt_pk_bf16_f32 v116, v148, v149
	v_cvt_pk_bf16_f32 v117, v150, v151
	global_store_dwordx2 v[158:159], v[116:117], off offset:256
	v_mul_f32_e32 v118, v125, v125
	v_mul_f32_e32 v119, v127, v127
	v_fmac_f32_e32 v118, v124, v124
	v_fmac_f32_e32 v119, v126, v126
	v_add_f32_e32 v118, v118, v119
	v_mul_f32_e32 v119, v121, v121
	v_mul_f32_e32 v121, v123, v123
	v_fmac_f32_e32 v119, v120, v120
	v_fmac_f32_e32 v121, v122, v122
	v_add_f32_e32 v119, v119, v121
	v_add_f32_e32 v118, v118, v119
	v_mul_f32_e32 v119, v149, v149
	v_mul_f32_e32 v120, v151, v151
	v_fmac_f32_e32 v119, v148, v148
	v_fmac_f32_e32 v120, v150, v150
	v_add_f32_e32 v119, v119, v120
	v_and_b32_e32 v117, 64, v146
	v_add_f32_e32 v122, v118, v119
	v_xor_b32_e32 v116, 16, v146
	v_add_u32_e32 v117, 64, v117
	v_cmp_lt_i32_e32 vcc, v116, v117
	s_waitcnt vmcnt(22)
	v_mov_b32_e32 v152, v182
	v_mov_b32_e32 v153, v183
	v_mov_b32_e32 v154, v184
	v_mov_b32_e32 v155, v185
	v_add_u32_e32 v163, 0x90000, v162
	global_load_dwordx4 v[182:185], v163, s[16:17]
	v_pk_add_f32 v[120:121], v[114:115], v[154:155]
	v_pk_add_f32 v[118:119], v[112:113], v[152:153]
	v_mul_f32_e32 v113, v121, v121
	v_mul_f32_e32 v112, v119, v119
	v_fmac_f32_e32 v112, v118, v118
	v_fmac_f32_e32 v113, v120, v120
	v_cndmask_b32_e32 v116, v146, v116, vcc
	v_add_f32_e32 v112, v112, v113
	v_lshlrev_b32_e32 v116, 2, v116
	v_add_f32_e32 v112, v122, v112
	ds_bpermute_b32 v113, v116, v112
	v_cmp_lt_i32_e32 vcc, v147, v117
	global_store_dwordx4 v[160:161], v[118:121], off offset:576 sc1
	s_waitcnt lgkmcnt(0)
	v_add_f32_e32 v112, v112, v113
	v_cndmask_b32_e32 v114, v146, v147, vcc
	v_lshlrev_b32_e32 v114, 2, v114
	ds_bpermute_b32 v113, v114, v112
	v_cvt_pk_bf16_f32 v118, v118, v119
	v_cvt_pk_bf16_f32 v119, v120, v121
	global_store_dwordx2 v[158:159], v[118:119], off offset:288
	s_and_saveexec_b64 s[58:59], s[12:13]
	s_cbranch_execz .LBB0_1039
	s_waitcnt lgkmcnt(0)
	v_add_f32_e32 v115, v112, v113
	v_lshlrev_b64 v[112:113], 6, v[138:139]
	v_lshl_add_u64 v[112:113], s[28:29], 0, v[112:113]
	v_lshl_add_u64 v[112:113], s[56:57], 2, v[112:113]
	s_lshl_b32 s30, s84, 2
	v_lshl_add_u64 v[112:113], v[112:113], 0, s[30:31]
	global_store_dword v[112:113], v115, off
; __device__ __forceinline__ unsigned pk2(float lo, float hi) { unsigned r; asm volatile("v_cvt_pk_bf16_f32 %0, %1, %2" : "=v"(r) : "v"(lo), "v"(hi)); return r; }
;     __device__ __forceinline__ void operator()(const f32x4 (&acc)[2][2][4][2], const Unit& u, int wr, int wc, int fr, int fq) const {
;         const int row0 = u.pm * 256 + wr * 64 + fr, col0 = u.pn * 256 + wc * 32 + 4 * fq;
;         const float* xo = (u.pm < 64) ? xoldA : (xoldB - (size_t)T_P * DM);
; #pragma unroll
;         for (int ai = 0; ai < 2; ++ai)
; #pragma unroll
;             for (int m = 0; m < 4; ++m) {
;                 const int row = row0 + ai * 128 + m * 16; const size_t ro = (size_t)row * DM + col0;
;                 float s = 0.f;
; #pragma unroll
;                 for (int bj = 0; bj < 2; ++bj)
; #pragma unroll
;                     for (int n = 0; n < 2; ++n) {
;                         const size_t o = ro + bj * 128 + n * 16;
;                         const f32x4 xn = *(const f32x4*)(xo + o) + acc[ai][bj][m][n];
;                         *(f32x4*)(xf + o) = xn;
;                         u32x2 w; w.x = pk2(xn[0], xn[1]); w.y = pk2(xn[2], xn[3]); *(u32x2*)(xb + o) = w;
;                         s += (xn[0] * xn[0] + xn[1] * xn[1]) + (xn[2] * xn[2] + xn[3] * xn[3]);
;                     }
;                 s += __shfl_xor(s, 16); s += __shfl_xor(s, 32);
;                 if (fq == 0) ssq[(size_t)row * 16 + u.pn * 4 + wc] = s;
;             }
;     }
.LBB0_1039:
	s_or_b64 exec, exec, s[58:59]
	v_or_b32_e32 v112, 16, v138
	s_waitcnt lgkmcnt(0)
	v_ashrrev_i32_e32 v113, 31, v112
	v_lshlrev_b64 v[118:119], 10, v[112:113]
	v_lshl_add_u64 v[122:123], v[118:119], 0, v[136:137]
	v_lshlrev_b64 v[124:125], 2, v[122:123]
	v_lshl_add_u64 v[126:127], s[16:17], 0, v[124:125]
	v_lshl_add_u64 v[122:123], v[122:123], 1, s[26:27]
	v_lshl_add_u64 v[124:125], s[20:21], 0, v[124:125]
	s_waitcnt vmcnt(24)
	v_mov_b32_e32 v118, v186
	v_mov_b32_e32 v119, v187
	v_mov_b32_e32 v120, v188
	v_mov_b32_e32 v121, v189
	v_add_u32_e32 v163, 0x90040, v162
	global_load_dwordx4 v[186:189], v163, s[16:17]
	v_pk_add_f32 v[110:111], v[110:111], v[120:121]
	v_pk_add_f32 v[108:109], v[108:109], v[118:119]
	global_store_dwordx4 v[124:125], v[108:111], off sc1
	v_cvt_pk_bf16_f32 v118, v108, v109
	v_cvt_pk_bf16_f32 v119, v110, v111
	global_store_dwordx2 v[122:123], v[118:119], off
	v_mul_f32_e32 v109, v109, v109
	v_mul_f32_e32 v111, v111, v111
	v_fmac_f32_e32 v109, v108, v108
	v_fmac_f32_e32 v111, v110, v110
	v_add_f32_e32 v108, v109, v111
	s_waitcnt vmcnt(26)
	v_mov_b32_e32 v118, v190
	v_mov_b32_e32 v119, v191
	v_mov_b32_e32 v120, v192
	v_mov_b32_e32 v121, v193
	v_add_u32_e32 v163, 0x90200, v162
	global_load_dwordx4 v[190:193], v163, s[16:17]
	v_pk_add_f32 v[106:107], v[106:107], v[120:121]
	v_pk_add_f32 v[104:105], v[104:105], v[118:119]
	global_store_dwordx4 v[124:125], v[104:107], off offset:64 sc1
	v_cvt_pk_bf16_f32 v118, v104, v105
	v_cvt_pk_bf16_f32 v119, v106, v107
	global_store_dwordx2 v[122:123], v[118:119], off offset:32
	v_mul_f32_e32 v105, v105, v105
	v_mul_f32_e32 v107, v107, v107
	v_fmac_f32_e32 v105, v104, v104
	v_fmac_f32_e32 v107, v106, v106
	v_add_f32_e32 v104, v105, v107
	v_add_f32_e32 v104, v108, v104
	s_waitcnt vmcnt(28)
	v_mov_b32_e32 v118, v194
	v_mov_b32_e32 v119, v195
	v_mov_b32_e32 v120, v196
	v_mov_b32_e32 v121, v197
	v_add_u32_e32 v163, 0x90240, v162
	global_load_dwordx4 v[194:197], v163, s[16:17]
	v_pk_add_f32 v[102:103], v[102:103], v[120:121]
	v_pk_add_f32 v[100:101], v[100:101], v[118:119]
	global_store_dwordx4 v[124:125], v[100:103], off offset:512 sc1
	v_cvt_pk_bf16_f32 v118, v100, v101
	v_cvt_pk_bf16_f32 v119, v102, v103
	global_store_dwordx2 v[122:123], v[118:119], off offset:256
	v_mul_f32_e32 v101, v101, v101
	v_mul_f32_e32 v103, v103, v103
	v_fmac_f32_e32 v101, v100, v100
	v_fmac_f32_e32 v103, v102, v102
	v_add_f32_e32 v100, v101, v103
	v_add_f32_e32 v102, v104, v100
	s_waitcnt vmcnt(30)
	v_mov_b32_e32 v118, v198
	v_mov_b32_e32 v119, v199
	v_mov_b32_e32 v120, v200
	v_mov_b32_e32 v121, v201
	v_add_u32_e32 v163, 0xa0000, v162
	global_load_dwordx4 v[198:201], v163, s[16:17]
	v_pk_add_f32 v[100:101], v[98:99], v[120:121]
	v_pk_add_f32 v[98:99], v[96:97], v[118:119]
	v_mul_f32_e32 v97, v101, v101
	v_mul_f32_e32 v96, v99, v99
	v_fmac_f32_e32 v96, v98, v98
	v_fmac_f32_e32 v97, v100, v100
	v_add_f32_e32 v96, v96, v97
	v_add_f32_e32 v96, v102, v96
	ds_bpermute_b32 v97, v116, v96
	global_store_dwordx4 v[124:125], v[98:101], off offset:576 sc1
	s_waitcnt lgkmcnt(0)
	v_add_f32_e32 v96, v96, v97
	ds_bpermute_b32 v97, v114, v96
	v_cvt_pk_bf16_f32 v98, v98, v99
	v_cvt_pk_bf16_f32 v99, v100, v101
	global_store_dwordx2 v[122:123], v[98:99], off offset:288
	s_and_saveexec_b64 s[58:59], s[12:13]
	s_cbranch_execz .LBB0_1041
	s_waitcnt lgkmcnt(0)
	v_add_f32_e32 v98, v96, v97
	v_lshlrev_b64 v[96:97], 6, v[112:113]
	v_lshl_add_u64 v[96:97], s[28:29], 0, v[96:97]
	v_lshl_add_u64 v[96:97], s[56:57], 2, v[96:97]
	s_lshl_b32 s30, s84, 2
	v_lshl_add_u64 v[96:97], v[96:97], 0, s[30:31]
	global_store_dword v[96:97], v98, off
.LBB0_1041:
	s_or_b64 exec, exec, s[58:59]
	v_or_b32_e32 v96, 32, v138
	s_waitcnt lgkmcnt(0)
	v_ashrrev_i32_e32 v97, 31, v96
	v_lshlrev_b64 v[98:99], 10, v[96:97]
	v_lshl_add_u64 v[102:103], v[98:99], 0, v[136:137]
	v_lshlrev_b64 v[104:105], 2, v[102:103]
	v_lshl_add_u64 v[106:107], s[16:17], 0, v[104:105]
	v_lshl_add_u64 v[102:103], v[102:103], 1, s[26:27]
	v_lshl_add_u64 v[104:105], s[20:21], 0, v[104:105]
	s_waitcnt vmcnt(32)
	v_mov_b32_e32 v98, v202
	v_mov_b32_e32 v99, v203
	v_mov_b32_e32 v100, v204
	v_mov_b32_e32 v101, v205
	v_add_u32_e32 v163, 0xa0040, v162
	global_load_dwordx4 v[202:205], v163, s[16:17]
	v_pk_add_f32 v[94:95], v[94:95], v[100:101]
	v_pk_add_f32 v[92:93], v[92:93], v[98:99]
	global_store_dwordx4 v[104:105], v[92:95], off sc1
	v_cvt_pk_bf16_f32 v98, v92, v93
	v_cvt_pk_bf16_f32 v99, v94, v95
	global_store_dwordx2 v[102:103], v[98:99], off
	v_mul_f32_e32 v93, v93, v93
	v_mul_f32_e32 v95, v95, v95
	v_fmac_f32_e32 v93, v92, v92
	v_fmac_f32_e32 v95, v94, v94
	v_add_f32_e32 v92, v93, v95
	s_waitcnt vmcnt(34)
	v_mov_b32_e32 v98, v206
	v_mov_b32_e32 v99, v207
	v_mov_b32_e32 v100, v208
	v_mov_b32_e32 v101, v209
	v_add_u32_e32 v163, 0xa0200, v162
	global_load_dwordx4 v[206:209], v163, s[16:17]
	v_pk_add_f32 v[90:91], v[90:91], v[100:101]
	v_pk_add_f32 v[88:89], v[88:89], v[98:99]
	global_store_dwordx4 v[104:105], v[88:91], off offset:64 sc1
	v_cvt_pk_bf16_f32 v98, v88, v89
	v_cvt_pk_bf16_f32 v99, v90, v91
	global_store_dwordx2 v[102:103], v[98:99], off offset:32
	v_mul_f32_e32 v89, v89, v89
	v_mul_f32_e32 v91, v91, v91
	v_fmac_f32_e32 v89, v88, v88
	v_fmac_f32_e32 v91, v90, v90
	v_add_f32_e32 v88, v89, v91
	v_add_f32_e32 v88, v92, v88
	s_waitcnt vmcnt(36)
	v_mov_b32_e32 v98, v210
	v_mov_b32_e32 v99, v211
	v_mov_b32_e32 v100, v212
	v_mov_b32_e32 v101, v213
	v_add_u32_e32 v163, 0xa0240, v162
	global_load_dwordx4 v[210:213], v163, s[16:17]
	v_pk_add_f32 v[86:87], v[86:87], v[100:101]
	v_pk_add_f32 v[84:85], v[84:85], v[98:99]
	global_store_dwordx4 v[104:105], v[84:87], off offset:512 sc1
	v_cvt_pk_bf16_f32 v98, v84, v85
	v_cvt_pk_bf16_f32 v99, v86, v87
	global_store_dwordx2 v[102:103], v[98:99], off offset:256
	v_mul_f32_e32 v85, v85, v85
	v_mul_f32_e32 v87, v87, v87
	v_fmac_f32_e32 v85, v84, v84
	v_fmac_f32_e32 v87, v86, v86
	v_add_f32_e32 v84, v85, v87
	v_add_f32_e32 v86, v88, v84
	s_waitcnt vmcnt(38)
	v_mov_b32_e32 v98, v232
	v_mov_b32_e32 v99, v233
	v_mov_b32_e32 v100, v234
	v_mov_b32_e32 v101, v235
	v_add_u32_e32 v163, 0xb0000, v162
	global_load_dwordx4 v[232:235], v163, s[16:17]
	v_pk_add_f32 v[84:85], v[82:83], v[100:101]
	v_pk_add_f32 v[82:83], v[80:81], v[98:99]
	v_mul_f32_e32 v81, v85, v85
	v_mul_f32_e32 v80, v83, v83
	v_fmac_f32_e32 v80, v82, v82
	v_fmac_f32_e32 v81, v84, v84
	v_add_f32_e32 v80, v80, v81
	v_add_f32_e32 v80, v86, v80
	ds_bpermute_b32 v81, v116, v80
	global_store_dwordx4 v[104:105], v[82:85], off offset:576 sc1
	s_waitcnt lgkmcnt(0)
	v_add_f32_e32 v80, v80, v81
	ds_bpermute_b32 v81, v114, v80
	v_cvt_pk_bf16_f32 v82, v82, v83
	v_cvt_pk_bf16_f32 v83, v84, v85
	global_store_dwordx2 v[102:103], v[82:83], off offset:288
	s_and_saveexec_b64 s[58:59], s[12:13]
	s_cbranch_execz .LBB0_1043
; __device__ __forceinline__ unsigned pk2(float lo, float hi) { unsigned r; asm volatile("v_cvt_pk_bf16_f32 %0, %1, %2" : "=v"(r) : "v"(lo), "v"(hi)); return r; }
;     __device__ __forceinline__ void operator()(const f32x4 (&acc)[2][2][4][2], const Unit& u, int wr, int wc, int fr, int fq) const {
;         const int row0 = u.pm * 256 + wr * 64 + fr, col0 = u.pn * 256 + wc * 32 + 4 * fq;
;         const float* xo = (u.pm < 64) ? xoldA : (xoldB - (size_t)T_P * DM);
; #pragma unroll
;         for (int ai = 0; ai < 2; ++ai)
; #pragma unroll
;             for (int m = 0; m < 4; ++m) {
;                 const int row = row0 + ai * 128 + m * 16; const size_t ro = (size_t)row * DM + col0;
;                 float s = 0.f;
; #pragma unroll
;                 for (int bj = 0; bj < 2; ++bj)
; #pragma unroll
;                     for (int n = 0; n < 2; ++n) {
;                         const size_t o = ro + bj * 128 + n * 16;
;                         const f32x4 xn = *(const f32x4*)(xo + o) + acc[ai][bj][m][n];
;                         *(f32x4*)(xf + o) = xn;
;                         u32x2 w; w.x = pk2(xn[0], xn[1]); w.y = pk2(xn[2], xn[3]); *(u32x2*)(xb + o) = w;
;                         s += (xn[0] * xn[0] + xn[1] * xn[1]) + (xn[2] * xn[2] + xn[3] * xn[3]);
;                     }
;                 s += __shfl_xor(s, 16); s += __shfl_xor(s, 32);
;                 if (fq == 0) ssq[(size_t)row * 16 + u.pn * 4 + wc] = s;
;             }
;     }
	s_waitcnt lgkmcnt(0)
	v_add_f32_e32 v82, v80, v81
	v_lshlrev_b64 v[80:81], 6, v[96:97]
	v_lshl_add_u64 v[80:81], s[28:29], 0, v[80:81]
	v_lshl_add_u64 v[80:81], s[56:57], 2, v[80:81]
	s_lshl_b32 s30, s84, 2
	v_lshl_add_u64 v[80:81], v[80:81], 0, s[30:31]
	global_store_dword v[80:81], v82, off
.LBB0_1043:
	s_or_b64 exec, exec, s[58:59]
	v_or_b32_e32 v80, 48, v138
	s_waitcnt lgkmcnt(0)
	v_ashrrev_i32_e32 v81, 31, v80
	v_lshlrev_b64 v[82:83], 10, v[80:81]
	v_lshl_add_u64 v[86:87], v[82:83], 0, v[136:137]
	v_lshlrev_b64 v[88:89], 2, v[86:87]
	v_lshl_add_u64 v[90:91], s[16:17], 0, v[88:89]
	v_lshl_add_u64 v[86:87], v[86:87], 1, s[26:27]
	v_lshl_add_u64 v[88:89], s[20:21], 0, v[88:89]
	s_waitcnt vmcnt(40)
	v_mov_b32_e32 v82, v236
	v_mov_b32_e32 v83, v237
	v_mov_b32_e32 v84, v238
	v_mov_b32_e32 v85, v239
	v_add_u32_e32 v163, 0xb0040, v162
	global_load_dwordx4 v[236:239], v163, s[16:17]
	v_pk_add_f32 v[78:79], v[78:79], v[84:85]
	v_pk_add_f32 v[76:77], v[76:77], v[82:83]
	global_store_dwordx4 v[88:89], v[76:79], off sc1
	v_cvt_pk_bf16_f32 v82, v76, v77
	v_cvt_pk_bf16_f32 v83, v78, v79
	global_store_dwordx2 v[86:87], v[82:83], off
	v_mul_f32_e32 v77, v77, v77
	v_mul_f32_e32 v79, v79, v79
	v_fmac_f32_e32 v77, v76, v76
	v_fmac_f32_e32 v79, v78, v78
	v_add_f32_e32 v76, v77, v79
	s_waitcnt vmcnt(42)
	v_mov_b32_e32 v82, v240
	v_mov_b32_e32 v83, v241
	v_mov_b32_e32 v84, v242
	v_mov_b32_e32 v85, v243
	v_add_u32_e32 v163, 0xb0200, v162
	global_load_dwordx4 v[240:243], v163, s[16:17]
	v_pk_add_f32 v[74:75], v[74:75], v[84:85]
	v_pk_add_f32 v[72:73], v[72:73], v[82:83]
	global_store_dwordx4 v[88:89], v[72:75], off offset:64 sc1
	v_cvt_pk_bf16_f32 v82, v72, v73
	v_cvt_pk_bf16_f32 v83, v74, v75
	global_store_dwordx2 v[86:87], v[82:83], off offset:32
	v_mul_f32_e32 v73, v73, v73
	v_mul_f32_e32 v75, v75, v75
	v_fmac_f32_e32 v73, v72, v72
	v_fmac_f32_e32 v75, v74, v74
	v_add_f32_e32 v72, v73, v75
	v_add_f32_e32 v72, v76, v72
	s_waitcnt vmcnt(44)
	v_mov_b32_e32 v82, v244
	v_mov_b32_e32 v83, v245
	v_mov_b32_e32 v84, v246
	v_mov_b32_e32 v85, v247
	v_add_u32_e32 v163, 0xb0240, v162
	global_load_dwordx4 v[244:247], v163, s[16:17]
	v_pk_add_f32 v[70:71], v[70:71], v[84:85]
	v_pk_add_f32 v[68:69], v[68:69], v[82:83]
	global_store_dwordx4 v[88:89], v[68:71], off offset:512 sc1
	v_cvt_pk_bf16_f32 v82, v68, v69
	v_cvt_pk_bf16_f32 v83, v70, v71
	global_store_dwordx2 v[86:87], v[82:83], off offset:256
	v_mul_f32_e32 v69, v69, v69
	v_mul_f32_e32 v71, v71, v71
	v_fmac_f32_e32 v69, v68, v68
	v_fmac_f32_e32 v71, v70, v70
	v_add_f32_e32 v68, v69, v71
	v_add_f32_e32 v70, v72, v68
	s_waitcnt vmcnt(46)
	v_mov_b32_e32 v82, v248
	v_mov_b32_e32 v83, v249
	v_mov_b32_e32 v84, v250
	v_mov_b32_e32 v85, v251
	v_pk_add_f32 v[68:69], v[66:67], v[84:85]
	v_pk_add_f32 v[66:67], v[64:65], v[82:83]
	v_mul_f32_e32 v65, v69, v69
	v_mul_f32_e32 v64, v67, v67
	v_fmac_f32_e32 v64, v66, v66
	v_fmac_f32_e32 v65, v68, v68
	v_add_f32_e32 v64, v64, v65
	v_add_f32_e32 v64, v70, v64
	ds_bpermute_b32 v65, v116, v64
	global_store_dwordx4 v[88:89], v[66:69], off offset:576 sc1
	s_waitcnt lgkmcnt(0)
	v_add_f32_e32 v64, v64, v65
	ds_bpermute_b32 v65, v114, v64
	v_cvt_pk_bf16_f32 v66, v66, v67
	v_cvt_pk_bf16_f32 v67, v68, v69
	global_store_dwordx2 v[86:87], v[66:67], off offset:288
	s_and_saveexec_b64 s[58:59], s[12:13]
	s_cbranch_execz .LBB0_1045
	s_waitcnt lgkmcnt(0)
	v_add_f32_e32 v66, v64, v65
	v_lshlrev_b64 v[64:65], 6, v[80:81]
	v_lshl_add_u64 v[64:65], s[28:29], 0, v[64:65]
	v_lshl_add_u64 v[64:65], s[56:57], 2, v[64:65]
	s_lshl_b32 s30, s84, 2
	v_lshl_add_u64 v[64:65], v[64:65], 0, s[30:31]
	global_store_dword v[64:65], v66, off
.LBB0_1045:
	s_or_b64 exec, exec, s[58:59]
	v_add_u32_e32 v64, 0x80, v138
	s_waitcnt lgkmcnt(0)
	v_ashrrev_i32_e32 v65, 31, v64
	v_lshlrev_b64 v[66:67], 10, v[64:65]
	v_lshl_add_u64 v[70:71], v[66:67], 0, v[136:137]
	v_lshlrev_b64 v[72:73], 2, v[70:71]
	v_lshl_add_u64 v[74:75], s[16:17], 0, v[72:73]
	v_lshl_add_u64 v[70:71], v[70:71], 1, s[26:27]
	v_lshl_add_u64 v[72:73], s[20:21], 0, v[72:73]
	s_waitcnt vmcnt(47)
	v_mov_b32_e32 v66, v252
	v_mov_b32_e32 v67, v253
	v_mov_b32_e32 v68, v254
	v_mov_b32_e32 v69, v255
	v_pk_add_f32 v[62:63], v[62:63], v[68:69]
	v_pk_add_f32 v[60:61], v[60:61], v[66:67]
	global_store_dwordx4 v[72:73], v[60:63], off sc1
	v_cvt_pk_bf16_f32 v66, v60, v61
	v_cvt_pk_bf16_f32 v67, v62, v63
	global_store_dwordx2 v[70:71], v[66:67], off
	v_mul_f32_e32 v61, v61, v61
	v_mul_f32_e32 v63, v63, v63
	v_fmac_f32_e32 v61, v60, v60
	v_fmac_f32_e32 v63, v62, v62
	v_add_f32_e32 v60, v61, v63
	s_waitcnt vmcnt(48)
	v_mov_b32_e32 v66, v170
	v_mov_b32_e32 v67, v171
	v_mov_b32_e32 v68, v172
	v_mov_b32_e32 v69, v173
	v_pk_add_f32 v[58:59], v[58:59], v[68:69]
	v_pk_add_f32 v[56:57], v[56:57], v[66:67]
	global_store_dwordx4 v[72:73], v[56:59], off offset:64 sc1
	v_cvt_pk_bf16_f32 v66, v56, v57
	v_cvt_pk_bf16_f32 v67, v58, v59
	global_store_dwordx2 v[70:71], v[66:67], off offset:32
	v_mul_f32_e32 v57, v57, v57
	v_mul_f32_e32 v59, v59, v59
	v_fmac_f32_e32 v57, v56, v56
	v_fmac_f32_e32 v59, v58, v58
	v_add_f32_e32 v56, v57, v59
	v_add_f32_e32 v56, v60, v56
	s_waitcnt vmcnt(47)
	v_mov_b32_e32 v66, v174
	v_mov_b32_e32 v67, v175
	v_mov_b32_e32 v68, v176
	v_mov_b32_e32 v69, v177
	v_pk_add_f32 v[54:55], v[54:55], v[68:69]
	v_pk_add_f32 v[52:53], v[52:53], v[66:67]
	global_store_dwordx4 v[72:73], v[52:55], off offset:512 sc1
	v_cvt_pk_bf16_f32 v66, v52, v53
	v_cvt_pk_bf16_f32 v67, v54, v55
	global_store_dwordx2 v[70:71], v[66:67], off offset:256
	v_mul_f32_e32 v53, v53, v53
	v_mul_f32_e32 v55, v55, v55
	v_fmac_f32_e32 v53, v52, v52
	v_fmac_f32_e32 v55, v54, v54
	v_add_f32_e32 v52, v53, v55
	v_add_f32_e32 v54, v56, v52
	s_waitcnt vmcnt(46)
	v_mov_b32_e32 v66, v178
	v_mov_b32_e32 v67, v179
	v_mov_b32_e32 v68, v180
	v_mov_b32_e32 v69, v181
	v_pk_add_f32 v[52:53], v[50:51], v[68:69]
	v_pk_add_f32 v[50:51], v[48:49], v[66:67]
	v_mul_f32_e32 v49, v53, v53
	v_mul_f32_e32 v48, v51, v51
	v_fmac_f32_e32 v48, v50, v50
	v_fmac_f32_e32 v49, v52, v52
	v_add_f32_e32 v48, v48, v49
	v_add_f32_e32 v48, v54, v48
	ds_bpermute_b32 v49, v116, v48
	global_store_dwordx4 v[72:73], v[50:53], off offset:576 sc1
	s_waitcnt lgkmcnt(0)
	v_add_f32_e32 v48, v48, v49
	ds_bpermute_b32 v49, v114, v48
	v_cvt_pk_bf16_f32 v50, v50, v51
	v_cvt_pk_bf16_f32 v51, v52, v53
	global_store_dwordx2 v[70:71], v[50:51], off offset:288
	s_and_saveexec_b64 s[58:59], s[12:13]
	s_cbranch_execz .LBB0_1047
	s_waitcnt lgkmcnt(0)
	v_add_f32_e32 v50, v48, v49
	v_lshlrev_b64 v[48:49], 6, v[64:65]
	v_lshl_add_u64 v[48:49], s[28:29], 0, v[48:49]
	v_lshl_add_u64 v[48:49], s[56:57], 2, v[48:49]
	s_lshl_b32 s30, s84, 2
	v_lshl_add_u64 v[48:49], v[48:49], 0, s[30:31]
	global_store_dword v[48:49], v50, off
; __device__ __forceinline__ unsigned pk2(float lo, float hi) { unsigned r; asm volatile("v_cvt_pk_bf16_f32 %0, %1, %2" : "=v"(r) : "v"(lo), "v"(hi)); return r; }
;     __device__ __forceinline__ void operator()(const f32x4 (&acc)[2][2][4][2], const Unit& u, int wr, int wc, int fr, int fq) const {
;         const int row0 = u.pm * 256 + wr * 64 + fr, col0 = u.pn * 256 + wc * 32 + 4 * fq;
;         const float* xo = (u.pm < 64) ? xoldA : (xoldB - (size_t)T_P * DM);
; #pragma unroll
;         for (int ai = 0; ai < 2; ++ai)
; #pragma unroll
;             for (int m = 0; m < 4; ++m) {
;                 const int row = row0 + ai * 128 + m * 16; const size_t ro = (size_t)row * DM + col0;
;                 float s = 0.f;
; #pragma unroll
;                 for (int bj = 0; bj < 2; ++bj)
; #pragma unroll
;                     for (int n = 0; n < 2; ++n) {
;                         const size_t o = ro + bj * 128 + n * 16;
;                         const f32x4 xn = *(const f32x4*)(xo + o) + acc[ai][bj][m][n];
;                         *(f32x4*)(xf + o) = xn;
;                         u32x2 w; w.x = pk2(xn[0], xn[1]); w.y = pk2(xn[2], xn[3]); *(u32x2*)(xb + o) = w;
;                         s += (xn[0] * xn[0] + xn[1] * xn[1]) + (xn[2] * xn[2] + xn[3] * xn[3]);
;                     }
;                 s += __shfl_xor(s, 16); s += __shfl_xor(s, 32);
;                 if (fq == 0) ssq[(size_t)row * 16 + u.pn * 4 + wc] = s;
;             }
;     }
.LBB0_1047:
	s_or_b64 exec, exec, s[58:59]
	v_add_u32_e32 v48, 0x90, v138
	s_waitcnt lgkmcnt(0)
	v_ashrrev_i32_e32 v49, 31, v48
	v_lshlrev_b64 v[50:51], 10, v[48:49]
	v_lshl_add_u64 v[54:55], v[50:51], 0, v[136:137]
	v_lshlrev_b64 v[56:57], 2, v[54:55]
	v_lshl_add_u64 v[58:59], s[16:17], 0, v[56:57]
	v_lshl_add_u64 v[54:55], v[54:55], 1, s[26:27]
	v_lshl_add_u64 v[56:57], s[20:21], 0, v[56:57]
	s_waitcnt vmcnt(45)
	v_mov_b32_e32 v50, v182
	v_mov_b32_e32 v51, v183
	v_mov_b32_e32 v52, v184
	v_mov_b32_e32 v53, v185
	v_pk_add_f32 v[46:47], v[46:47], v[52:53]
	v_pk_add_f32 v[44:45], v[44:45], v[50:51]
	global_store_dwordx4 v[56:57], v[44:47], off sc1
	v_cvt_pk_bf16_f32 v50, v44, v45
	v_cvt_pk_bf16_f32 v51, v46, v47
	global_store_dwordx2 v[54:55], v[50:51], off
	v_mul_f32_e32 v45, v45, v45
	v_mul_f32_e32 v47, v47, v47
	v_fmac_f32_e32 v45, v44, v44
	v_fmac_f32_e32 v47, v46, v46
	v_add_f32_e32 v44, v45, v47
	s_waitcnt vmcnt(44)
	v_mov_b32_e32 v50, v186
	v_mov_b32_e32 v51, v187
	v_mov_b32_e32 v52, v188
	v_mov_b32_e32 v53, v189
	v_pk_add_f32 v[42:43], v[42:43], v[52:53]
	v_pk_add_f32 v[40:41], v[40:41], v[50:51]
	global_store_dwordx4 v[56:57], v[40:43], off offset:64 sc1
	v_cvt_pk_bf16_f32 v50, v40, v41
	v_cvt_pk_bf16_f32 v51, v42, v43
	global_store_dwordx2 v[54:55], v[50:51], off offset:32
	v_mul_f32_e32 v41, v41, v41
	v_mul_f32_e32 v43, v43, v43
	v_fmac_f32_e32 v41, v40, v40
	v_fmac_f32_e32 v43, v42, v42
	v_add_f32_e32 v40, v41, v43
	v_add_f32_e32 v40, v44, v40
	s_waitcnt vmcnt(43)
	v_mov_b32_e32 v50, v190
	v_mov_b32_e32 v51, v191
	v_mov_b32_e32 v52, v192
	v_mov_b32_e32 v53, v193
	v_pk_add_f32 v[38:39], v[38:39], v[52:53]
	v_pk_add_f32 v[36:37], v[36:37], v[50:51]
	global_store_dwordx4 v[56:57], v[36:39], off offset:512 sc1
	v_cvt_pk_bf16_f32 v50, v36, v37
	v_cvt_pk_bf16_f32 v51, v38, v39
	global_store_dwordx2 v[54:55], v[50:51], off offset:256
	v_mul_f32_e32 v37, v37, v37
	v_mul_f32_e32 v39, v39, v39
	v_fmac_f32_e32 v37, v36, v36
	v_fmac_f32_e32 v39, v38, v38
	v_add_f32_e32 v36, v37, v39
	v_add_f32_e32 v38, v40, v36
	s_waitcnt vmcnt(42)
	v_mov_b32_e32 v50, v194
	v_mov_b32_e32 v51, v195
	v_mov_b32_e32 v52, v196
	v_mov_b32_e32 v53, v197
	v_pk_add_f32 v[36:37], v[34:35], v[52:53]
	v_pk_add_f32 v[34:35], v[32:33], v[50:51]
	v_mul_f32_e32 v33, v37, v37
	v_mul_f32_e32 v32, v35, v35
	v_fmac_f32_e32 v32, v34, v34
	v_fmac_f32_e32 v33, v36, v36
	v_add_f32_e32 v32, v32, v33
	v_add_f32_e32 v32, v38, v32
	ds_bpermute_b32 v33, v116, v32
	global_store_dwordx4 v[56:57], v[34:37], off offset:576 sc1
	s_waitcnt lgkmcnt(0)
	v_add_f32_e32 v32, v32, v33
	ds_bpermute_b32 v33, v114, v32
	v_cvt_pk_bf16_f32 v34, v34, v35
	v_cvt_pk_bf16_f32 v35, v36, v37
	global_store_dwordx2 v[54:55], v[34:35], off offset:288
	s_and_saveexec_b64 s[58:59], s[12:13]
	s_cbranch_execz .LBB0_1049
	s_waitcnt lgkmcnt(0)
	v_add_f32_e32 v34, v32, v33
	v_lshlrev_b64 v[32:33], 6, v[48:49]
	v_lshl_add_u64 v[32:33], s[28:29], 0, v[32:33]
	v_lshl_add_u64 v[32:33], s[56:57], 2, v[32:33]
	s_lshl_b32 s30, s84, 2
	v_lshl_add_u64 v[32:33], v[32:33], 0, s[30:31]
	global_store_dword v[32:33], v34, off
; __device__ __forceinline__ unsigned pk2(float lo, float hi) { unsigned r; asm volatile("v_cvt_pk_bf16_f32 %0, %1, %2" : "=v"(r) : "v"(lo), "v"(hi)); return r; }
;     __device__ __forceinline__ void operator()(const f32x4 (&acc)[2][2][4][2], const Unit& u, int wr, int wc, int fr, int fq) const {
;         const int row0 = u.pm * 256 + wr * 64 + fr, col0 = u.pn * 256 + wc * 32 + 4 * fq;
;         const float* xo = (u.pm < 64) ? xoldA : (xoldB - (size_t)T_P * DM);
; #pragma unroll
;         for (int ai = 0; ai < 2; ++ai)
; #pragma unroll
;             for (int m = 0; m < 4; ++m) {
;                 const int row = row0 + ai * 128 + m * 16; const size_t ro = (size_t)row * DM + col0;
;                 float s = 0.f;
; #pragma unroll
;                 for (int bj = 0; bj < 2; ++bj)
; #pragma unroll
;                     for (int n = 0; n < 2; ++n) {
;                         const size_t o = ro + bj * 128 + n * 16;
;                         const f32x4 xn = *(const f32x4*)(xo + o) + acc[ai][bj][m][n];
;                         *(f32x4*)(xf + o) = xn;
;                         u32x2 w; w.x = pk2(xn[0], xn[1]); w.y = pk2(xn[2], xn[3]); *(u32x2*)(xb + o) = w;
;                         s += (xn[0] * xn[0] + xn[1] * xn[1]) + (xn[2] * xn[2] + xn[3] * xn[3]);
;                     }
;                 s += __shfl_xor(s, 16); s += __shfl_xor(s, 32);
;                 if (fq == 0) ssq[(size_t)row * 16 + u.pn * 4 + wc] = s;
;             }
;     }
.LBB0_1049:
	s_or_b64 exec, exec, s[58:59]
	v_add_u32_e32 v32, 0xa0, v138
	s_waitcnt lgkmcnt(0)
	v_ashrrev_i32_e32 v33, 31, v32
	v_lshlrev_b64 v[34:35], 10, v[32:33]
	v_lshl_add_u64 v[38:39], v[34:35], 0, v[136:137]
	v_lshlrev_b64 v[40:41], 2, v[38:39]
	v_lshl_add_u64 v[42:43], s[16:17], 0, v[40:41]
	v_lshl_add_u64 v[38:39], v[38:39], 1, s[26:27]
	v_lshl_add_u64 v[40:41], s[20:21], 0, v[40:41]
	s_waitcnt vmcnt(41)
	v_mov_b32_e32 v34, v198
	v_mov_b32_e32 v35, v199
	v_mov_b32_e32 v36, v200
	v_mov_b32_e32 v37, v201
	v_pk_add_f32 v[30:31], v[30:31], v[36:37]
	v_pk_add_f32 v[28:29], v[28:29], v[34:35]
	global_store_dwordx4 v[40:41], v[28:31], off sc1
	v_cvt_pk_bf16_f32 v34, v28, v29
	v_cvt_pk_bf16_f32 v35, v30, v31
	global_store_dwordx2 v[38:39], v[34:35], off
	v_mul_f32_e32 v29, v29, v29
	v_mul_f32_e32 v31, v31, v31
	v_fmac_f32_e32 v29, v28, v28
	v_fmac_f32_e32 v31, v30, v30
	v_add_f32_e32 v28, v29, v31
	s_waitcnt vmcnt(40)
	v_mov_b32_e32 v34, v202
	v_mov_b32_e32 v35, v203
	v_mov_b32_e32 v36, v204
	v_mov_b32_e32 v37, v205
	v_pk_add_f32 v[26:27], v[26:27], v[36:37]
	v_pk_add_f32 v[24:25], v[24:25], v[34:35]
	global_store_dwordx4 v[40:41], v[24:27], off offset:64 sc1
	v_cvt_pk_bf16_f32 v34, v24, v25
	v_cvt_pk_bf16_f32 v35, v26, v27
	global_store_dwordx2 v[38:39], v[34:35], off offset:32
	v_mul_f32_e32 v25, v25, v25
	v_mul_f32_e32 v27, v27, v27
	v_fmac_f32_e32 v25, v24, v24
	v_fmac_f32_e32 v27, v26, v26
	v_add_f32_e32 v24, v25, v27
	v_add_f32_e32 v24, v28, v24
	s_waitcnt vmcnt(39)
	v_mov_b32_e32 v34, v206
	v_mov_b32_e32 v35, v207
	v_mov_b32_e32 v36, v208
	v_mov_b32_e32 v37, v209
	v_pk_add_f32 v[22:23], v[22:23], v[36:37]
	v_pk_add_f32 v[20:21], v[20:21], v[34:35]
	global_store_dwordx4 v[40:41], v[20:23], off offset:512 sc1
	v_cvt_pk_bf16_f32 v34, v20, v21
	v_cvt_pk_bf16_f32 v35, v22, v23
	global_store_dwordx2 v[38:39], v[34:35], off offset:256
	v_mul_f32_e32 v21, v21, v21
	v_mul_f32_e32 v23, v23, v23
	v_fmac_f32_e32 v21, v20, v20
	v_fmac_f32_e32 v23, v22, v22
	v_add_f32_e32 v20, v21, v23
	v_add_f32_e32 v22, v24, v20
	s_waitcnt vmcnt(38)
	v_mov_b32_e32 v34, v210
	v_mov_b32_e32 v35, v211
	v_mov_b32_e32 v36, v212
	v_mov_b32_e32 v37, v213
	v_pk_add_f32 v[20:21], v[18:19], v[36:37]
	v_pk_add_f32 v[18:19], v[16:17], v[34:35]
	v_mul_f32_e32 v17, v21, v21
	v_mul_f32_e32 v16, v19, v19
	v_fmac_f32_e32 v16, v18, v18
	v_fmac_f32_e32 v17, v20, v20
	v_add_f32_e32 v16, v16, v17
	v_add_f32_e32 v16, v22, v16
	ds_bpermute_b32 v17, v116, v16
	global_store_dwordx4 v[40:41], v[18:21], off offset:576 sc1
	s_waitcnt lgkmcnt(0)
	v_add_f32_e32 v16, v16, v17
	ds_bpermute_b32 v17, v114, v16
	v_cvt_pk_bf16_f32 v18, v18, v19
	v_cvt_pk_bf16_f32 v19, v20, v21
	global_store_dwordx2 v[38:39], v[18:19], off offset:288
	s_and_saveexec_b64 s[58:59], s[12:13]
	s_cbranch_execz .LBB0_1051
	s_waitcnt lgkmcnt(0)
	v_add_f32_e32 v18, v16, v17
	v_lshlrev_b64 v[16:17], 6, v[32:33]
	v_lshl_add_u64 v[16:17], s[28:29], 0, v[16:17]
	v_lshl_add_u64 v[16:17], s[56:57], 2, v[16:17]
	s_lshl_b32 s30, s84, 2
	v_lshl_add_u64 v[16:17], v[16:17], 0, s[30:31]
	global_store_dword v[16:17], v18, off
.LBB0_1051:
	s_or_b64 exec, exec, s[58:59]
	v_add_u32_e32 v16, 0xb0, v138
	s_waitcnt lgkmcnt(0)
	v_ashrrev_i32_e32 v17, 31, v16
	v_lshlrev_b64 v[18:19], 10, v[16:17]
	v_lshl_add_u64 v[22:23], v[18:19], 0, v[136:137]
	v_lshlrev_b64 v[24:25], 2, v[22:23]
	v_lshl_add_u64 v[26:27], s[16:17], 0, v[24:25]
	v_lshl_add_u64 v[22:23], v[22:23], 1, s[26:27]
	v_lshl_add_u64 v[24:25], s[20:21], 0, v[24:25]
	s_waitcnt vmcnt(37)
	v_mov_b32_e32 v18, v232
	v_mov_b32_e32 v19, v233
	v_mov_b32_e32 v20, v234
	v_mov_b32_e32 v21, v235
	v_pk_add_f32 v[14:15], v[14:15], v[20:21]
	v_pk_add_f32 v[12:13], v[12:13], v[18:19]
	global_store_dwordx4 v[24:25], v[12:15], off sc1
	v_cvt_pk_bf16_f32 v18, v12, v13
	v_cvt_pk_bf16_f32 v19, v14, v15
	global_store_dwordx2 v[22:23], v[18:19], off
	v_mul_f32_e32 v13, v13, v13
	v_mul_f32_e32 v15, v15, v15
	v_fmac_f32_e32 v13, v12, v12
	v_fmac_f32_e32 v15, v14, v14
	v_add_f32_e32 v12, v13, v15
	s_waitcnt vmcnt(36)
	v_mov_b32_e32 v18, v236
	v_mov_b32_e32 v19, v237
	v_mov_b32_e32 v20, v238
	v_mov_b32_e32 v21, v239
	v_pk_add_f32 v[10:11], v[10:11], v[20:21]
	v_pk_add_f32 v[8:9], v[8:9], v[18:19]
	global_store_dwordx4 v[24:25], v[8:11], off offset:64 sc1
	v_cvt_pk_bf16_f32 v18, v8, v9
	v_cvt_pk_bf16_f32 v19, v10, v11
	global_store_dwordx2 v[22:23], v[18:19], off offset:32
	v_mul_f32_e32 v9, v9, v9
	v_mul_f32_e32 v11, v11, v11
	v_fmac_f32_e32 v9, v8, v8
	v_fmac_f32_e32 v11, v10, v10
	v_add_f32_e32 v8, v9, v11
	v_add_f32_e32 v8, v12, v8
	s_waitcnt vmcnt(35)
	v_mov_b32_e32 v18, v240
	v_mov_b32_e32 v19, v241
	v_mov_b32_e32 v20, v242
	v_mov_b32_e32 v21, v243
	v_pk_add_f32 v[6:7], v[6:7], v[20:21]
	v_pk_add_f32 v[4:5], v[4:5], v[18:19]
	global_store_dwordx4 v[24:25], v[4:7], off offset:512 sc1
	v_cvt_pk_bf16_f32 v18, v4, v5
	v_cvt_pk_bf16_f32 v19, v6, v7
	global_store_dwordx2 v[22:23], v[18:19], off offset:256
	v_mul_f32_e32 v5, v5, v5
	v_mul_f32_e32 v7, v7, v7
	v_fmac_f32_e32 v5, v4, v4
	v_fmac_f32_e32 v7, v6, v6
	v_add_f32_e32 v4, v5, v7
	v_add_f32_e32 v6, v8, v4
	s_waitcnt vmcnt(34)
	v_mov_b32_e32 v18, v244
	v_mov_b32_e32 v19, v245
	v_mov_b32_e32 v20, v246
	v_mov_b32_e32 v21, v247
	v_pk_add_f32 v[4:5], v[2:3], v[20:21]
	v_pk_add_f32 v[2:3], v[0:1], v[18:19]
	v_mul_f32_e32 v1, v5, v5
	v_mul_f32_e32 v0, v3, v3
	v_fmac_f32_e32 v0, v2, v2
	v_fmac_f32_e32 v1, v4, v4
	v_add_f32_e32 v0, v0, v1
	v_add_f32_e32 v0, v6, v0
	ds_bpermute_b32 v1, v116, v0
	global_store_dwordx4 v[24:25], v[2:5], off offset:576 sc1
	s_waitcnt lgkmcnt(0)
	v_add_f32_e32 v0, v0, v1
	ds_bpermute_b32 v1, v114, v0
	v_cvt_pk_bf16_f32 v2, v2, v3
	v_cvt_pk_bf16_f32 v3, v4, v5
	global_store_dwordx2 v[22:23], v[2:3], off offset:288
	s_and_saveexec_b64 s[16:17], s[12:13]
	s_cbranch_execz .LBB0_1012
	s_waitcnt lgkmcnt(0)
	v_add_f32_e32 v2, v0, v1
	v_lshlrev_b64 v[0:1], 6, v[16:17]
	v_lshl_add_u64 v[0:1], s[28:29], 0, v[0:1]
	v_lshl_add_u64 v[0:1], s[56:57], 2, v[0:1]
	s_lshl_b32 s30, s84, 2
	v_lshl_add_u64 v[0:1], v[0:1], 0, s[30:31]
	global_store_dword v[0:1], v2, off
	s_branch .LBB0_1012

;     __device__ __forceinline__ void operator()(const f32x4 (&acc)[2][2][4][2], const Unit& u, int wr, int wc, int fr, int fq) const {
;         const int row0 = u.pm * 256 + wr * 64 + fr, col0 = u.pn * 256 + wc * 32 + 4 * fq;
; #pragma unroll
;         for (int ai = 0; ai < 2; ++ai)
; #pragma unroll
;             for (int m = 0; m < 4; ++m) { float* rowp = part + (size_t)(row0 + ai * 128 + m * 16) * DM + col0;
; #pragma unroll
;                 for (int bj = 0; bj < 2; ++bj)
; #pragma unroll
;                     for (int n = 0; n < 2; ++n) *(f32x4*)(rowp + bj * 128 + n * 16) = acc[ai][bj][m][n]; }
;     }
.LBB0_1081:
	v_lshl_add_u32 v138, s28, 8, v133
	v_lshl_or_b32 v140, s7, 8, v135
	v_ashrrev_i32_e32 v139, 31, v138
	v_ashrrev_i32_e32 v141, 31, v140
	v_lshlrev_b64 v[142:143], 12, v[138:139]
	v_lshl_add_u64 v[142:143], s[36:37], 0, v[142:143]
	v_lshlrev_b64 v[140:141], 2, v[140:141]
	v_lshl_add_u64 v[142:143], v[142:143], 0, v[140:141]
	global_store_dwordx4 v[142:143], v[124:127], off sc1
	global_store_dwordx4 v[142:143], v[120:123], off offset:64 sc1
	global_store_dwordx4 v[142:143], v[108:111], off offset:512 sc1
	global_store_dwordx4 v[142:143], v[100:103], off offset:576 sc1
	s_mov_b32 s7, 0x80000
	s_mov_b64 s[8:9], 0x80000
	v_or_b32_e32 v100, 16, v138
	v_ashrrev_i32_e32 v101, 31, v100
	v_lshlrev_b64 v[100:101], 12, v[100:101]
	v_lshl_add_u64 v[100:101], s[36:37], 0, v[100:101]
	v_lshl_add_u64 v[100:101], v[100:101], 0, v[140:141]
	global_store_dwordx4 v[100:101], v[116:119], off sc1
	global_store_dwordx4 v[100:101], v[112:115], off offset:64 sc1
	global_store_dwordx4 v[100:101], v[92:95], off offset:512 sc1
	global_store_dwordx4 v[100:101], v[84:87], off offset:576 sc1
	s_mov_b32 s28, s54
	s_mov_b64 s[34:35], s[60:61]
	v_or_b32_e32 v84, 32, v138
	v_ashrrev_i32_e32 v85, 31, v84
	v_lshlrev_b64 v[84:85], 12, v[84:85]
	v_lshl_add_u64 v[84:85], s[36:37], 0, v[84:85]
	v_lshl_add_u64 v[84:85], v[84:85], 0, v[140:141]
	global_store_dwordx4 v[84:85], v[104:107], off sc1
	global_store_dwordx4 v[84:85], v[96:99], off offset:64 sc1
	global_store_dwordx4 v[84:85], v[76:79], off offset:512 sc1
	global_store_dwordx4 v[84:85], v[72:75], off offset:576 sc1
	s_mov_b64 s[30:31], s[56:57]
	s_nop 0
	v_or_b32_e32 v72, 48, v138
	v_ashrrev_i32_e32 v73, 31, v72
	v_lshlrev_b64 v[72:73], 12, v[72:73]
	v_lshl_add_u64 v[72:73], s[36:37], 0, v[72:73]
	v_lshl_add_u64 v[72:73], v[72:73], 0, v[140:141]
	global_store_dwordx4 v[72:73], v[88:91], off sc1
	global_store_dwordx4 v[72:73], v[80:83], off offset:64 sc1
	global_store_dwordx4 v[72:73], v[68:71], off offset:512 sc1
	global_store_dwordx4 v[72:73], v[64:67], off offset:576 sc1
	s_nop 1
	v_add_co_u32_e32 v66, vcc, s7, v142
	s_mov_b32 s7, 0x90000
	s_nop 0
	v_addc_co_u32_e32 v67, vcc, 0, v143, vcc
	v_lshl_add_u64 v[64:65], v[142:143], 0, s[8:9]
	global_store_dwordx4 v[66:67], v[60:63], off sc1
	global_store_dwordx4 v[64:65], v[56:59], off offset:64 sc1
	global_store_dwordx4 v[64:65], v[44:47], off offset:512 sc1
	global_store_dwordx4 v[64:65], v[36:39], off offset:576 sc1
	s_mov_b64 s[8:9], 0x90000
	s_nop 0
	v_add_co_u32_e32 v38, vcc, s7, v142
	s_mov_b32 s7, 0xa0000
	s_nop 0
	v_addc_co_u32_e32 v39, vcc, 0, v143, vcc
	v_lshl_add_u64 v[36:37], v[142:143], 0, s[8:9]
	global_store_dwordx4 v[38:39], v[52:55], off sc1
	global_store_dwordx4 v[36:37], v[48:51], off offset:64 sc1
	global_store_dwordx4 v[36:37], v[28:31], off offset:512 sc1
	global_store_dwordx4 v[36:37], v[20:23], off offset:576 sc1
	s_mov_b64 s[8:9], 0xa0000
	s_nop 0
	v_add_co_u32_e32 v22, vcc, s7, v142
	v_lshl_add_u64 v[20:21], v[142:143], 0, s[8:9]
	s_nop 0
	v_addc_co_u32_e32 v23, vcc, 0, v143, vcc
	global_store_dwordx4 v[22:23], v[40:43], off sc1
	global_store_dwordx4 v[20:21], v[32:35], off offset:64 sc1
	global_store_dwordx4 v[20:21], v[12:15], off offset:512 sc1
	global_store_dwordx4 v[20:21], v[8:11], off offset:576 sc1
	s_mov_b64 s[8:9], 0xb0000
	s_mov_b32 s7, s40
	v_add_co_u32_e32 v10, vcc, 0xb0000, v142
	v_lshl_add_u64 v[8:9], v[142:143], 0, s[8:9]
	s_nop 0
	v_addc_co_u32_e32 v11, vcc, 0, v143, vcc
	s_and_b64 vcc, exec, s[38:39]
	global_store_dwordx4 v[10:11], v[24:27], off sc1
	global_store_dwordx4 v[8:9], v[16:19], off offset:64 sc1
	global_store_dwordx4 v[8:9], v[4:7], off offset:512 sc1
	global_store_dwordx4 v[8:9], v[0:3], off offset:576 sc1
	s_cbranch_vccnz .LBB0_1106

; __device__ __forceinline__ unsigned pk2(float lo, float hi) { unsigned r; asm volatile("v_cvt_pk_bf16_f32 %0, %1, %2" : "=v"(r) : "v"(lo), "v"(hi)); return r; }
; #define RAW_BARRIER() do { asm volatile("s_waitcnt lgkmcnt(0)" ::: "memory"); __builtin_amdgcn_s_barrier(); asm volatile("" ::: "memory"); } while (0)
;     ...
;         RAW_BARRIER();
;         { u32x4 w;
;           w.x = pk2(tile[(k8 + 0) * 65 + n], tile[(k8 + 1) * 65 + n]); w.y = pk2(tile[(k8 + 2) * 65 + n], tile[(k8 + 3) * 65 + n]);
;           w.z = pk2(tile[(k8 + 4) * 65 + n], tile[(k8 + 5) * 65 + n]); w.w = pk2(tile[(k8 + 6) * 65 + n], tile[(k8 + 7) * 65 + n]);
;           *(u32x4*)(dst + (size_t)(n0 + n) * K + k0 + k8) = w; }
;         RAW_BARRIER();
.LBB0_1124:
	s_waitcnt lgkmcnt(0)
	s_barrier
	ds_read_b32 v13, v20 offset:260
	ds_read_b32 v23, v19
	s_mul_hi_i32 s16, s18, 0x78787879
	s_lshr_b32 s17, s16, 31
	s_ashr_i32 s16, s16, 5
	s_add_i32 s17, s16, s17
	s_lshl_b32 s16, s17, 6
	s_mulk_i32 s17, 0xef00
	s_waitcnt lgkmcnt(0)
	v_cvt_pk_bf16_f32 v24, v23, v13
	ds_read2_b32 v[26:27], v20 offset0:130 offset1:195
	v_add_u32_e32 v13, 0x400, v20
	s_add_i32 s17, s17, s8
	s_waitcnt lgkmcnt(0)
	v_cvt_pk_bf16_f32 v25, v26, v27
	ds_read2_b32 v[26:27], v13 offset0:4 offset1:69
	v_add_u32_e32 v30, s17, v17
	s_waitcnt lgkmcnt(0)
	v_cvt_pk_bf16_f32 v26, v26, v27
	ds_read2_b32 v[28:29], v13 offset0:134 offset1:199
	v_ashrrev_i32_e32 v31, 31, v30
	s_waitcnt lgkmcnt(0)
	v_cvt_pk_bf16_f32 v27, v28, v29
	v_lshlrev_b64 v[28:29], 11, v[30:31]
	v_lshl_add_u64 v[28:29], s[10:11], 0, v[28:29]
	s_ashr_i32 s17, s16, 31
	v_lshl_add_u64 v[28:29], s[16:17], 1, v[28:29]
	v_lshl_add_u64 v[28:29], v[28:29], 0, v[10:11]
	global_store_dwordx4 v[28:29], v[24:27], off sc1
	s_waitcnt lgkmcnt(0)
	s_barrier
	s_andn2_b64 vcc, exec, s[14:15]
	s_mov_b32 s8, s19
	s_mov_b32 s18, s9
	s_cbranch_vccz .LBB0_1129

; __device__ __forceinline__ unsigned pk2(float lo, float hi) { unsigned r; asm volatile("v_cvt_pk_bf16_f32 %0, %1, %2" : "=v"(r) : "v"(lo), "v"(hi)); return r; }
; #define RAW_BARRIER() do { asm volatile("s_waitcnt lgkmcnt(0)" ::: "memory"); __builtin_amdgcn_s_barrier(); asm volatile("" ::: "memory"); } while (0)
;     ...
;         RAW_BARRIER();
;         { u32x4 w;
;           w.x = pk2(tile[(k8 + 0) * 65 + n], tile[(k8 + 1) * 65 + n]); w.y = pk2(tile[(k8 + 2) * 65 + n], tile[(k8 + 3) * 65 + n]);
;           w.z = pk2(tile[(k8 + 4) * 65 + n], tile[(k8 + 5) * 65 + n]); w.w = pk2(tile[(k8 + 6) * 65 + n], tile[(k8 + 7) * 65 + n]);
;           *(u32x4*)(dst + (size_t)(n0 + n) * K + k0 + k8) = w; }
;         RAW_BARRIER();
.LBB0_1132:
	s_waitcnt lgkmcnt(0)
	s_barrier
	ds_read_b32 v20, v16 offset:260
	ds_read_b32 v21, v15
	s_ashr_i32 s16, s9, 31
	v_add_u32_e32 v26, s7, v13
	s_lshr_b32 s7, s16, 28
	s_add_i32 s7, s9, s7
	s_ashr_i32 s7, s7, 4
	s_lshl_b32 s16, s7, 6
	s_lshl_b32 s7, s7, 10
	s_waitcnt lgkmcnt(0)
	v_cvt_pk_bf16_f32 v20, v21, v20
	ds_read2_b32 v[22:23], v16 offset0:130 offset1:195
	v_subrev_u32_e32 v26, s7, v26
	s_waitcnt lgkmcnt(0)
	v_cvt_pk_bf16_f32 v21, v22, v23
	ds_read2_b32 v[22:23], v19 offset0:4 offset1:69
	v_ashrrev_i32_e32 v27, 31, v26
	s_waitcnt lgkmcnt(0)
	v_cvt_pk_bf16_f32 v22, v22, v23
	ds_read2_b32 v[24:25], v19 offset0:134 offset1:199
	v_lshlrev_b64 v[26:27], 10, v[26:27]
	s_waitcnt lgkmcnt(0)
	v_cvt_pk_bf16_f32 v23, v24, v25
	v_lshl_add_u64 v[24:25], s[10:11], 0, v[26:27]
	s_ashr_i32 s17, s16, 31
	v_lshl_add_u64 v[24:25], s[16:17], 1, v[24:25]
	v_lshl_add_u64 v[24:25], v[24:25], 0, v[10:11]
	global_store_dwordx4 v[24:25], v[20:23], off sc1
	s_waitcnt lgkmcnt(0)
	s_barrier
	s_andn2_b64 vcc, exec, s[14:15]
	s_mov_b32 s7, s18
	s_mov_b32 s9, s8
	s_cbranch_vccz .LBB0_1137

; __device__ __forceinline__ unsigned pk2(float lo, float hi) { unsigned r; asm volatile("v_cvt_pk_bf16_f32 %0, %1, %2" : "=v"(r) : "v"(lo), "v"(hi)); return r; }
; #define RAW_BARRIER() do { asm volatile("s_waitcnt lgkmcnt(0)" ::: "memory"); __builtin_amdgcn_s_barrier(); asm volatile("" ::: "memory"); } while (0)
;     ...
;         RAW_BARRIER();
;         { u32x4 w;
;           w.x = pk2(tile[(k8 + 0) * 65 + n], tile[(k8 + 1) * 65 + n]); w.y = pk2(tile[(k8 + 2) * 65 + n], tile[(k8 + 3) * 65 + n]);
;           w.z = pk2(tile[(k8 + 4) * 65 + n], tile[(k8 + 5) * 65 + n]); w.w = pk2(tile[(k8 + 6) * 65 + n], tile[(k8 + 7) * 65 + n]);
;           *(u32x4*)(dst + (size_t)(n0 + n) * K + k0 + k8) = w; }
;         RAW_BARRIER();
.LBB0_1148:
	s_waitcnt lgkmcnt(0)
	s_barrier
	ds_read_b32 v20, v16 offset:260
	ds_read_b32 v21, v15
	s_ashr_i32 s16, s9, 31
	v_add_u32_e32 v26, s7, v13
	s_lshr_b32 s7, s16, 28
	s_add_i32 s7, s9, s7
	s_ashr_i32 s7, s7, 4
	s_lshl_b32 s16, s7, 6
	s_lshl_b32 s7, s7, 10
	s_waitcnt lgkmcnt(0)
	v_cvt_pk_bf16_f32 v20, v21, v20
	ds_read2_b32 v[22:23], v16 offset0:130 offset1:195
	v_subrev_u32_e32 v26, s7, v26
	s_waitcnt lgkmcnt(0)
	v_cvt_pk_bf16_f32 v21, v22, v23
	ds_read2_b32 v[22:23], v19 offset0:4 offset1:69
	v_ashrrev_i32_e32 v27, 31, v26
	s_waitcnt lgkmcnt(0)
	v_cvt_pk_bf16_f32 v22, v22, v23
	ds_read2_b32 v[24:25], v19 offset0:134 offset1:199
	v_lshlrev_b64 v[26:27], 11, v[26:27]
	s_waitcnt lgkmcnt(0)
	v_cvt_pk_bf16_f32 v23, v24, v25
	v_lshl_add_u64 v[24:25], s[10:11], 0, v[26:27]
	s_ashr_i32 s17, s16, 31
	v_lshl_add_u64 v[24:25], s[16:17], 1, v[24:25]
	v_lshl_add_u64 v[24:25], v[24:25], 0, v[10:11]
	global_store_dwordx4 v[24:25], v[20:23], off sc1
	s_waitcnt lgkmcnt(0)
	s_barrier
	s_andn2_b64 vcc, exec, s[14:15]
	s_mov_b32 s7, s18
	s_mov_b32 s9, s8
	s_cbranch_vccz .LBB0_1160

; __device__ __forceinline__ unsigned pk2(float lo, float hi) { unsigned r; asm volatile("v_cvt_pk_bf16_f32 %0, %1, %2" : "=v"(r) : "v"(lo), "v"(hi)); return r; }
;     ...
;     if (c < 64) {
;         const int kq = c >> 4; Unit u; S.init(1024, DM, G, c & 15); S.next(0, u);
;         unsigned* ctr = cnt + 64 * u.pm;
;         asm volatile("s_waitcnt vmcnt(0)" ::: "memory");
;         __syncthreads();
;         if (threadIdx.x == 0) {
;             __builtin_amdgcn_fence(__ATOMIC_RELEASE, "agent");
;             asm volatile("s_waitcnt vmcnt(0)" ::: "memory");
;             (void)__hip_atomic_fetch_add(ctr, 1u, __ATOMIC_RELAXED, __HIP_MEMORY_SCOPE_AGENT);
;             unsigned sp = 0;
;             while (__hip_atomic_load(ctr, __ATOMIC_RELAXED, __HIP_MEMORY_SCOPE_AGENT) < 16u) { __builtin_amdgcn_s_sleep(1); if (++sp > (1u << 22)) break; }
;             __builtin_amdgcn_fence(__ATOMIC_ACQUIRE, "agent");
;             asm volatile("s_waitcnt vmcnt(0)" ::: "memory");
;         }
;         __syncthreads();
;         const int lane = threadIdx.x & 63, wv = threadIdx.x >> 6;
;         const int rbase = u.pm * 256 + (kq * 4 + u.pn) * 16 + wv * 2;
; #pragma unroll
;         for (int rr = 0; rr < 2; ++rr) {
;             const int row = rbase + rr; float sq = 0.f;
; #pragma unroll
;             for (int i = 0; i < 4; ++i) {
;                 const size_t o = (size_t)row * DM + i * 256 + lane * 4;
;                 f32x4 v = *(const f32x4*)(xold + o);
; #pragma unroll
;                 for (int q = 0; q < 4; ++q) v += *(const f32x4*)(part + (size_t)q * 1024 * DM + o);
;                 *(f32x4*)(xf_s + o) = v;
;                 u32x2 w; w.x = pk2(v[0], v[1]); w.y = pk2(v[2], v[3]); *(u32x2*)(xb_s + o) = w;
;                 sq += (v[0] * v[0] + v[1] * v[1]) + (v[2] * v[2] + v[3] * v[3]);
;             }
; #pragma unroll
;             for (int o = 32; o >= 1; o >>= 1) sq += __shfl_xor(sq, o);
;             if (lane < 16) ssq_s[(size_t)row * 16 + lane] = lane == 0 ? sq : 0.f;
;         }
.LBB0_1154:
	s_or_b64 exec, exec, s[10:11]
	s_add_u32 s18, s20, 0x4000000
	s_addc_u32 s19, s21, 0
	s_add_u32 s16, s16, 0x2000000
	s_addc_u32 s17, s17, 0
	s_lshr_b32 s8, s70, 2
	v_lshrrev_b32_e32 v0, 5, v166
	s_and_b32 s8, s8, 0xffffffc
	v_and_b32_e32 v0, 30, v0
	s_add_i32 s6, s6, s8
	v_lshl_or_b32 v0, s7, 8, v0
	v_lshl_add_u32 v2, s6, 4, v0
	v_ashrrev_i32_e32 v3, 31, v2
	v_lshlrev_b32_e32 v0, 2, v167
	v_lshlrev_b64 v[4:5], 10, v[2:3]
	v_or_b32_e32 v4, v4, v0
	v_lshlrev_b64 v[10:11], 2, v[4:5]
	v_lshl_add_u64 v[38:39], s[14:15], 0, v[10:11]
	s_mov_b32 s6, 0x400000
	v_add_co_u32_e32 v40, vcc, s6, v38
	s_mov_b32 s7, 0x800000
	s_nop 0
	v_addc_co_u32_e32 v41, vcc, 0, v39, vcc
	v_lshl_add_u64 v[26:27], s[18:19], 0, v[10:11]
	v_add_co_u32_e32 v42, vcc, s7, v38
	s_barrier
	global_load_dwordx4 v[6:9], v[26:27], off
	v_addc_co_u32_e32 v43, vcc, 0, v39, vcc
	s_mov_b32 s8, 0xc00000
	global_load_dwordx4 v[10:13], v[38:39], off
	global_load_dwordx4 v[14:17], v[40:41], off
	v_add_co_u32_e32 v44, vcc, s8, v38
	global_load_dwordx4 v[18:21], v[42:43], off
	s_nop 0
	v_addc_co_u32_e32 v45, vcc, 0, v39, vcc
	global_load_dwordx4 v[22:25], v[44:45], off
	v_mov_b32_e32 v31, v5
	v_lshl_add_u64 v[28:29], v[4:5], 1, s[16:17]
	v_or_b32_e32 v30, 0x100, v4
	v_lshl_add_u64 v[32:33], v[30:31], 2, s[18:19]
	v_mov_b32_e32 v35, v5
	v_or_b32_e32 v34, 0x200, v4
	v_lshl_add_u64 v[30:31], v[30:31], 1, s[16:17]
	v_lshl_add_u64 v[36:37], v[34:35], 2, s[18:19]
	v_or_b32_e32 v4, 0x300, v4
	v_lshl_add_u64 v[34:35], v[34:35], 1, s[16:17]
	v_lshl_add_u64 v[46:47], v[4:5], 2, s[18:19]
	v_mov_b32_e32 v1, 0
	s_mov_b64 s[20:21], 0x100000
	v_cmp_gt_u32_e64 s[10:11], 16, v167
	v_cmp_eq_u32_e32 vcc, 0, v167
	v_lshl_add_u64 v[4:5], v[4:5], 1, s[16:17]
	global_load_dwordx4 v[186:189], v[32:33], off
	global_load_dwordx4 v[190:193], v[38:39], off offset:1024
	global_load_dwordx4 v[194:197], v[40:41], off offset:1024
	global_load_dwordx4 v[198:201], v[42:43], off offset:1024
	global_load_dwordx4 v[202:205], v[44:45], off offset:1024
	global_load_dwordx4 v[206:209], v[36:37], off
	global_load_dwordx4 v[210:213], v[38:39], off offset:2048
	global_load_dwordx4 v[214:217], v[40:41], off offset:2048
	global_load_dwordx4 v[218:221], v[42:43], off offset:2048
	global_load_dwordx4 v[222:225], v[44:45], off offset:2048
	global_load_dwordx4 v[226:229], v[46:47], off
	global_load_dwordx4 v[232:235], v[38:39], off offset:3072
	global_load_dwordx4 v[236:239], v[40:41], off offset:3072
	global_load_dwordx4 v[240:243], v[42:43], off offset:3072
	global_load_dwordx4 v[244:247], v[44:45], off offset:3072
	s_waitcnt vmcnt(18)
	v_pk_add_f32 v[8:9], v[8:9], v[12:13]
	v_pk_add_f32 v[6:7], v[6:7], v[10:11]
	s_waitcnt vmcnt(17)
	v_pk_add_f32 v[8:9], v[8:9], v[16:17]
	v_pk_add_f32 v[6:7], v[6:7], v[14:15]
	s_waitcnt vmcnt(16)
	v_pk_add_f32 v[8:9], v[8:9], v[20:21]
	v_pk_add_f32 v[6:7], v[6:7], v[18:19]
	s_waitcnt vmcnt(15)
	v_pk_add_f32 v[8:9], v[8:9], v[24:25]
	v_pk_add_f32 v[6:7], v[6:7], v[22:23]
	global_store_dwordx4 v[26:27], v[6:9], off sc1
	v_cvt_pk_bf16_f32 v10, v6, v7
	v_cvt_pk_bf16_f32 v11, v8, v9
	global_store_dwordx2 v[28:29], v[10:11], off
	s_nop 0
	v_mul_f32_e32 v7, v7, v7
	v_mul_f32_e32 v9, v9, v9
	v_fmac_f32_e32 v7, v6, v6
	v_fmac_f32_e32 v9, v8, v8
	v_add_f32_e32 v6, v7, v9
	s_waitcnt vmcnt(12)
	v_mov_b32_e32 v10, v186
	v_mov_b32_e32 v11, v187
	v_mov_b32_e32 v12, v188
	v_mov_b32_e32 v13, v189
	v_mov_b32_e32 v14, v190
	v_mov_b32_e32 v15, v191
	v_mov_b32_e32 v16, v192
	v_mov_b32_e32 v17, v193
	v_mov_b32_e32 v18, v194
	v_mov_b32_e32 v19, v195
	v_mov_b32_e32 v20, v196
	v_mov_b32_e32 v21, v197
	v_mov_b32_e32 v22, v198
	v_mov_b32_e32 v23, v199
	v_mov_b32_e32 v24, v200
	v_mov_b32_e32 v25, v201
	v_mov_b32_e32 v26, v202
	v_mov_b32_e32 v27, v203
	v_mov_b32_e32 v28, v204
	v_mov_b32_e32 v29, v205
	v_pk_add_f32 v[12:13], v[12:13], v[16:17]
	v_pk_add_f32 v[10:11], v[10:11], v[14:15]
	v_pk_add_f32 v[12:13], v[12:13], v[20:21]
	v_pk_add_f32 v[10:11], v[10:11], v[18:19]
	v_pk_add_f32 v[12:13], v[12:13], v[24:25]
	v_pk_add_f32 v[10:11], v[10:11], v[22:23]
	v_pk_add_f32 v[12:13], v[12:13], v[28:29]
	v_pk_add_f32 v[10:11], v[10:11], v[26:27]
	global_store_dwordx4 v[32:33], v[10:13], off sc1
	v_cvt_pk_bf16_f32 v14, v10, v11
	v_cvt_pk_bf16_f32 v15, v12, v13
	global_store_dwordx2 v[30:31], v[14:15], off
	s_nop 0
	v_mul_f32_e32 v7, v11, v11
	v_mul_f32_e32 v8, v13, v13
	v_fmac_f32_e32 v7, v10, v10
	v_fmac_f32_e32 v8, v12, v12
	v_add_f32_e32 v7, v7, v8
	v_add_f32_e32 v6, v6, v7
	s_waitcnt vmcnt(9)
	v_mov_b32_e32 v14, v206
	v_mov_b32_e32 v15, v207
	v_mov_b32_e32 v16, v208
	v_mov_b32_e32 v17, v209
	v_mov_b32_e32 v18, v210
	v_mov_b32_e32 v19, v211
	v_mov_b32_e32 v20, v212
	v_mov_b32_e32 v21, v213
	v_mov_b32_e32 v22, v214
	v_mov_b32_e32 v23, v215
	v_mov_b32_e32 v24, v216
	v_mov_b32_e32 v25, v217
	v_mov_b32_e32 v26, v218
	v_mov_b32_e32 v27, v219
	v_mov_b32_e32 v28, v220
	v_mov_b32_e32 v29, v221
	v_mov_b32_e32 v30, v222
	v_mov_b32_e32 v31, v223
	v_mov_b32_e32 v32, v224
	v_mov_b32_e32 v33, v225
	v_pk_add_f32 v[16:17], v[16:17], v[20:21]
	v_pk_add_f32 v[14:15], v[14:15], v[18:19]
	v_pk_add_f32 v[16:17], v[16:17], v[24:25]
	v_pk_add_f32 v[14:15], v[14:15], v[22:23]
	v_pk_add_f32 v[16:17], v[16:17], v[28:29]
	v_pk_add_f32 v[14:15], v[14:15], v[26:27]
	v_pk_add_f32 v[16:17], v[16:17], v[32:33]
	v_pk_add_f32 v[14:15], v[14:15], v[30:31]
	global_store_dwordx4 v[36:37], v[14:17], off sc1
	v_cvt_pk_bf16_f32 v18, v14, v15
	v_cvt_pk_bf16_f32 v19, v16, v17
	global_store_dwordx2 v[34:35], v[18:19], off
	s_nop 0
	v_mul_f32_e32 v7, v15, v15
	v_mul_f32_e32 v8, v17, v17
	v_fmac_f32_e32 v7, v14, v14
	v_fmac_f32_e32 v8, v16, v16
	v_add_f32_e32 v7, v7, v8
	v_add_f32_e32 v10, v6, v7
	v_mbcnt_hi_u32_b32 v40, -1, v168
	v_lshl_add_u64 v[38:39], s[12:13], 0, v[0:1]
	v_and_b32_e32 v1, 64, v40
	v_xor_b32_e32 v41, 32, v40
	v_add_u32_e32 v43, 64, v1
	v_cmp_lt_i32_e64 s[12:13], v41, v43
	v_xor_b32_e32 v42, 16, v40
	v_xor_b32_e32 v11, 2, v40
	v_cndmask_b32_e64 v1, v40, v41, s[12:13]
	v_lshlrev_b32_e32 v1, 2, v1
	v_cmp_lt_i32_e64 s[12:13], v42, v43
	v_xor_b32_e32 v12, 1, v40
	s_waitcnt vmcnt(6)
; __device__ __forceinline__ unsigned pk2(float lo, float hi) { unsigned r; asm volatile("v_cvt_pk_bf16_f32 %0, %1, %2" : "=v"(r) : "v"(lo), "v"(hi)); return r; }
;     ...
;         const int lane = threadIdx.x & 63, wv = threadIdx.x >> 6;
;         const int rbase = u.pm * 256 + (kq * 4 + u.pn) * 16 + wv * 2;
; #pragma unroll
;         for (int rr = 0; rr < 2; ++rr) {
;             const int row = rbase + rr; float sq = 0.f;
; #pragma unroll
;             for (int i = 0; i < 4; ++i) {
;                 const size_t o = (size_t)row * DM + i * 256 + lane * 4;
;                 f32x4 v = *(const f32x4*)(xold + o);
; #pragma unroll
;                 for (int q = 0; q < 4; ++q) v += *(const f32x4*)(part + (size_t)q * 1024 * DM + o);
;                 *(f32x4*)(xf_s + o) = v;
;                 u32x2 w; w.x = pk2(v[0], v[1]); w.y = pk2(v[2], v[3]); *(u32x2*)(xb_s + o) = w;
;                 sq += (v[0] * v[0] + v[1] * v[1]) + (v[2] * v[2] + v[3] * v[3]);
;             }
; #pragma unroll
;             for (int o = 32; o >= 1; o >>= 1) sq += __shfl_xor(sq, o);
;             if (lane < 16) ssq_s[(size_t)row * 16 + lane] = lane == 0 ? sq : 0.f;
;         }
	v_mov_b32_e32 v18, v226
	v_mov_b32_e32 v19, v227
	v_mov_b32_e32 v20, v228
	v_mov_b32_e32 v21, v229
	v_mov_b32_e32 v22, v232
	v_mov_b32_e32 v23, v233
	v_mov_b32_e32 v24, v234
	v_mov_b32_e32 v25, v235
	v_mov_b32_e32 v26, v236
	v_mov_b32_e32 v27, v237
	v_mov_b32_e32 v28, v238
	v_mov_b32_e32 v29, v239
	v_mov_b32_e32 v30, v240
	v_mov_b32_e32 v31, v241
	v_mov_b32_e32 v32, v242
	v_mov_b32_e32 v33, v243
	v_mov_b32_e32 v34, v244
	v_mov_b32_e32 v35, v245
	v_mov_b32_e32 v36, v246
	v_mov_b32_e32 v37, v247
	v_pk_add_f32 v[6:7], v[20:21], v[24:25]
	v_pk_add_f32 v[8:9], v[18:19], v[22:23]
	v_pk_add_f32 v[6:7], v[6:7], v[28:29]
	v_pk_add_f32 v[8:9], v[8:9], v[26:27]
	v_pk_add_f32 v[6:7], v[6:7], v[32:33]
	v_pk_add_f32 v[8:9], v[8:9], v[30:31]
	v_pk_add_f32 v[18:19], v[6:7], v[36:37]
	v_pk_add_f32 v[16:17], v[8:9], v[34:35]
	v_mul_f32_e32 v7, v19, v19
	v_mul_f32_e32 v6, v17, v17
	v_fmac_f32_e32 v6, v16, v16
	v_fmac_f32_e32 v7, v18, v18
	v_add_f32_e32 v6, v6, v7
	v_add_f32_e32 v6, v10, v6
	ds_bpermute_b32 v7, v1, v6
	v_cndmask_b32_e64 v8, v40, v42, s[12:13]
	v_lshlrev_b32_e32 v8, 2, v8
	v_xor_b32_e32 v9, 8, v40
	v_cmp_lt_i32_e64 s[12:13], v9, v43
	s_waitcnt lgkmcnt(0)
	v_add_f32_e32 v6, v6, v7
	ds_bpermute_b32 v7, v8, v6
	v_cndmask_b32_e64 v9, v40, v9, s[12:13]
	v_lshlrev_b32_e32 v9, 2, v9
	v_xor_b32_e32 v10, 4, v40
	v_cmp_lt_i32_e64 s[12:13], v10, v43
	s_waitcnt lgkmcnt(0)
	v_add_f32_e32 v6, v6, v7
	ds_bpermute_b32 v7, v9, v6
	v_cndmask_b32_e64 v10, v40, v10, s[12:13]
	v_lshlrev_b32_e32 v10, 2, v10
	v_cmp_lt_i32_e64 s[12:13], v11, v43
	global_store_dwordx4 v[46:47], v[16:19], off sc1
	s_waitcnt lgkmcnt(0)
	v_add_f32_e32 v6, v6, v7
	ds_bpermute_b32 v7, v10, v6
	v_cndmask_b32_e64 v11, v40, v11, s[12:13]
	v_lshlrev_b32_e32 v11, 2, v11
	v_cmp_lt_i32_e64 s[12:13], v12, v43
	v_cvt_pk_bf16_f32 v16, v16, v17
	s_waitcnt lgkmcnt(0)
	v_add_f32_e32 v13, v6, v7
	ds_bpermute_b32 v14, v11, v13
	v_cndmask_b32_e64 v12, v40, v12, s[12:13]
	v_lshlrev_b32_e32 v12, 2, v12
	v_lshl_add_u64 v[6:7], v[38:39], 0, s[20:21]
	v_cvt_pk_bf16_f32 v17, v18, v19
	s_waitcnt lgkmcnt(0)
	v_add_f32_e32 v13, v13, v14
	ds_bpermute_b32 v14, v12, v13
	global_store_dwordx2 v[4:5], v[16:17], off
	s_and_saveexec_b64 s[12:13], s[10:11]
	s_cbranch_execz .LBB0_1156
	v_lshlrev_b64 v[4:5], 6, v[2:3]
	s_waitcnt lgkmcnt(0)
	v_add_f32_e32 v3, v13, v14
	v_lshl_add_u64 v[4:5], v[6:7], 0, v[4:5]
	v_cndmask_b32_e32 v3, 0, v3, vcc
	global_store_dword v[4:5], v3, off
.LBB0_1156:
	s_or_b64 exec, exec, s[12:13]
	v_or_b32_e32 v2, 1, v2
	v_ashrrev_i32_e32 v3, 31, v2
	v_lshlrev_b64 v[4:5], 10, v[2:3]
	v_or_b32_e32 v4, v4, v0
	v_lshlrev_b64 v[18:19], 2, v[4:5]
	v_lshl_add_u64 v[46:47], s[14:15], 0, v[18:19]
	v_add_co_u32_e64 v48, s[12:13], s6, v46
	v_lshl_add_u64 v[34:35], s[18:19], 0, v[18:19]
	s_nop 0
	v_addc_co_u32_e64 v49, s[12:13], 0, v47, s[12:13]
	v_add_co_u32_e64 v50, s[12:13], s7, v46
	s_waitcnt lgkmcnt(0)
	global_load_dwordx4 v[14:17], v[34:35], off
	v_addc_co_u32_e64 v51, s[12:13], 0, v47, s[12:13]
	global_load_dwordx4 v[18:21], v[46:47], off
	global_load_dwordx4 v[22:25], v[48:49], off
	v_add_co_u32_e64 v52, s[12:13], s8, v46
	global_load_dwordx4 v[26:29], v[50:51], off
	s_nop 0
	v_addc_co_u32_e64 v53, s[12:13], 0, v47, s[12:13]
	global_load_dwordx4 v[30:33], v[52:53], off
	v_mov_b32_e32 v39, v5
	v_lshl_add_u64 v[36:37], v[4:5], 1, s[16:17]
	v_or_b32_e32 v38, 0x100, v4
	v_lshl_add_u64 v[40:41], v[38:39], 2, s[18:19]
	v_mov_b32_e32 v43, v5
	v_or_b32_e32 v42, 0x200, v4
	v_lshl_add_u64 v[38:39], v[38:39], 1, s[16:17]
	v_lshl_add_u64 v[44:45], v[42:43], 2, s[18:19]
	v_or_b32_e32 v4, 0x300, v4
	v_lshl_add_u64 v[42:43], v[42:43], 1, s[16:17]
	v_lshl_add_u64 v[54:55], v[4:5], 2, s[18:19]
	v_lshl_add_u64 v[4:5], v[4:5], 1, s[16:17]
	global_load_dwordx4 v[186:189], v[40:41], off
	global_load_dwordx4 v[190:193], v[46:47], off offset:1024
	global_load_dwordx4 v[194:197], v[48:49], off offset:1024
	global_load_dwordx4 v[198:201], v[50:51], off offset:1024
	global_load_dwordx4 v[202:205], v[52:53], off offset:1024
	global_load_dwordx4 v[206:209], v[44:45], off
	global_load_dwordx4 v[210:213], v[46:47], off offset:2048
	global_load_dwordx4 v[214:217], v[48:49], off offset:2048
	global_load_dwordx4 v[218:221], v[50:51], off offset:2048
	global_load_dwordx4 v[222:225], v[52:53], off offset:2048
	global_load_dwordx4 v[226:229], v[54:55], off
	global_load_dwordx4 v[232:235], v[46:47], off offset:3072
	global_load_dwordx4 v[236:239], v[48:49], off offset:3072
	global_load_dwordx4 v[240:243], v[50:51], off offset:3072
	global_load_dwordx4 v[244:247], v[52:53], off offset:3072
	s_waitcnt vmcnt(18)
	v_pk_add_f32 v[16:17], v[16:17], v[20:21]
	v_pk_add_f32 v[14:15], v[14:15], v[18:19]
	s_waitcnt vmcnt(17)
	v_pk_add_f32 v[16:17], v[16:17], v[24:25]
	v_pk_add_f32 v[14:15], v[14:15], v[22:23]
	s_waitcnt vmcnt(16)
; __device__ __forceinline__ unsigned pk2(float lo, float hi) { unsigned r; asm volatile("v_cvt_pk_bf16_f32 %0, %1, %2" : "=v"(r) : "v"(lo), "v"(hi)); return r; }
;     ...
;         const int lane = threadIdx.x & 63, wv = threadIdx.x >> 6;
;         const int rbase = u.pm * 256 + (kq * 4 + u.pn) * 16 + wv * 2;
; #pragma unroll
;         for (int rr = 0; rr < 2; ++rr) {
;             const int row = rbase + rr; float sq = 0.f;
; #pragma unroll
;             for (int i = 0; i < 4; ++i) {
;                 const size_t o = (size_t)row * DM + i * 256 + lane * 4;
;                 f32x4 v = *(const f32x4*)(xold + o);
; #pragma unroll
;                 for (int q = 0; q < 4; ++q) v += *(const f32x4*)(part + (size_t)q * 1024 * DM + o);
;                 *(f32x4*)(xf_s + o) = v;
;                 u32x2 w; w.x = pk2(v[0], v[1]); w.y = pk2(v[2], v[3]); *(u32x2*)(xb_s + o) = w;
;                 sq += (v[0] * v[0] + v[1] * v[1]) + (v[2] * v[2] + v[3] * v[3]);
;             }
; #pragma unroll
;             for (int o = 32; o >= 1; o >>= 1) sq += __shfl_xor(sq, o);
;             if (lane < 16) ssq_s[(size_t)row * 16 + lane] = lane == 0 ? sq : 0.f;
;         }
	v_pk_add_f32 v[16:17], v[16:17], v[28:29]
	v_pk_add_f32 v[14:15], v[14:15], v[26:27]
	s_waitcnt vmcnt(15)
	v_pk_add_f32 v[16:17], v[16:17], v[32:33]
	v_pk_add_f32 v[14:15], v[14:15], v[30:31]
	global_store_dwordx4 v[34:35], v[14:17], off sc1
	v_cvt_pk_bf16_f32 v18, v14, v15
	v_cvt_pk_bf16_f32 v19, v16, v17
	global_store_dwordx2 v[36:37], v[18:19], off
	s_nop 0
	v_mul_f32_e32 v0, v15, v15
	v_mul_f32_e32 v13, v17, v17
	v_fmac_f32_e32 v0, v14, v14
	v_fmac_f32_e32 v13, v16, v16
	v_add_f32_e32 v0, v0, v13
	s_waitcnt vmcnt(12)
	v_mov_b32_e32 v18, v186
	v_mov_b32_e32 v19, v187
	v_mov_b32_e32 v20, v188
	v_mov_b32_e32 v21, v189
	v_mov_b32_e32 v22, v190
	v_mov_b32_e32 v23, v191
	v_mov_b32_e32 v24, v192
	v_mov_b32_e32 v25, v193
	v_mov_b32_e32 v26, v194
	v_mov_b32_e32 v27, v195
	v_mov_b32_e32 v28, v196
	v_mov_b32_e32 v29, v197
	v_mov_b32_e32 v30, v198
	v_mov_b32_e32 v31, v199
	v_mov_b32_e32 v32, v200
	v_mov_b32_e32 v33, v201
	v_mov_b32_e32 v34, v202
	v_mov_b32_e32 v35, v203
	v_mov_b32_e32 v36, v204
	v_mov_b32_e32 v37, v205
	v_pk_add_f32 v[20:21], v[20:21], v[24:25]
	v_pk_add_f32 v[18:19], v[18:19], v[22:23]
	v_pk_add_f32 v[20:21], v[20:21], v[28:29]
	v_pk_add_f32 v[18:19], v[18:19], v[26:27]
	v_pk_add_f32 v[20:21], v[20:21], v[32:33]
	v_pk_add_f32 v[18:19], v[18:19], v[30:31]
	v_pk_add_f32 v[20:21], v[20:21], v[36:37]
	v_pk_add_f32 v[18:19], v[18:19], v[34:35]
	global_store_dwordx4 v[40:41], v[18:21], off sc1
	v_cvt_pk_bf16_f32 v22, v18, v19
	v_cvt_pk_bf16_f32 v23, v20, v21
	global_store_dwordx2 v[38:39], v[22:23], off
	s_nop 0
	v_mul_f32_e32 v13, v19, v19
	v_mul_f32_e32 v14, v21, v21
	v_fmac_f32_e32 v13, v18, v18
	v_fmac_f32_e32 v14, v20, v20
	v_add_f32_e32 v13, v13, v14
	v_add_f32_e32 v0, v0, v13
	s_waitcnt vmcnt(9)
	v_mov_b32_e32 v22, v206
	v_mov_b32_e32 v23, v207
	v_mov_b32_e32 v24, v208
	v_mov_b32_e32 v25, v209
	v_mov_b32_e32 v26, v210
	v_mov_b32_e32 v27, v211
	v_mov_b32_e32 v28, v212
	v_mov_b32_e32 v29, v213
	v_mov_b32_e32 v30, v214
	v_mov_b32_e32 v31, v215
	v_mov_b32_e32 v32, v216
	v_mov_b32_e32 v33, v217
	v_mov_b32_e32 v34, v218
	v_mov_b32_e32 v35, v219
	v_mov_b32_e32 v36, v220
	v_mov_b32_e32 v37, v221
	v_mov_b32_e32 v38, v222
	v_mov_b32_e32 v39, v223
	v_mov_b32_e32 v40, v224
	v_mov_b32_e32 v41, v225
	v_pk_add_f32 v[24:25], v[24:25], v[28:29]
	v_pk_add_f32 v[22:23], v[22:23], v[26:27]
	v_pk_add_f32 v[24:25], v[24:25], v[32:33]
	v_pk_add_f32 v[22:23], v[22:23], v[30:31]
	v_pk_add_f32 v[24:25], v[24:25], v[36:37]
	v_pk_add_f32 v[22:23], v[22:23], v[34:35]
	v_pk_add_f32 v[24:25], v[24:25], v[40:41]
	v_pk_add_f32 v[22:23], v[22:23], v[38:39]
	global_store_dwordx4 v[44:45], v[22:25], off sc1
	v_cvt_pk_bf16_f32 v26, v22, v23
	v_cvt_pk_bf16_f32 v27, v24, v25
	global_store_dwordx2 v[42:43], v[26:27], off
	s_nop 0
	v_mul_f32_e32 v13, v23, v23
	v_mul_f32_e32 v14, v25, v25
	v_fmac_f32_e32 v13, v22, v22
	v_fmac_f32_e32 v14, v24, v24
	v_add_f32_e32 v13, v13, v14
	v_add_f32_e32 v0, v0, v13
	s_waitcnt vmcnt(6)
	v_mov_b32_e32 v26, v226
	v_mov_b32_e32 v27, v227
	v_mov_b32_e32 v28, v228
	v_mov_b32_e32 v29, v229
	v_mov_b32_e32 v30, v232
	v_mov_b32_e32 v31, v233
	v_mov_b32_e32 v32, v234
	v_mov_b32_e32 v33, v235
	v_mov_b32_e32 v34, v236
	v_mov_b32_e32 v35, v237
	v_mov_b32_e32 v36, v238
	v_mov_b32_e32 v37, v239
	v_mov_b32_e32 v38, v240
	v_mov_b32_e32 v39, v241
	v_mov_b32_e32 v40, v242
	v_mov_b32_e32 v41, v243
	v_mov_b32_e32 v42, v244
	v_mov_b32_e32 v43, v245
	v_mov_b32_e32 v44, v246
	v_mov_b32_e32 v45, v247
	v_pk_add_f32 v[14:15], v[28:29], v[32:33]
	v_pk_add_f32 v[16:17], v[26:27], v[30:31]
	v_pk_add_f32 v[14:15], v[14:15], v[36:37]
	v_pk_add_f32 v[16:17], v[16:17], v[34:35]
	v_pk_add_f32 v[14:15], v[14:15], v[40:41]
	v_pk_add_f32 v[18:19], v[16:17], v[38:39]
	v_pk_add_f32 v[16:17], v[14:15], v[44:45]
	v_pk_add_f32 v[14:15], v[18:19], v[42:43]
	v_mul_f32_e32 v18, v17, v17
	v_mul_f32_e32 v13, v15, v15
	v_fmac_f32_e32 v13, v14, v14
	v_fmac_f32_e32 v18, v16, v16
	v_add_f32_e32 v13, v13, v18
	v_add_f32_e32 v0, v0, v13
	ds_bpermute_b32 v1, v1, v0
	global_store_dwordx4 v[54:55], v[14:17], off sc1
	s_waitcnt lgkmcnt(0)
	v_add_f32_e32 v0, v0, v1
	ds_bpermute_b32 v1, v8, v0
	v_cvt_pk_bf16_f32 v8, v14, v15
	s_waitcnt lgkmcnt(0)
	v_add_f32_e32 v0, v0, v1
	ds_bpermute_b32 v1, v9, v0
	v_cvt_pk_bf16_f32 v9, v16, v17
	global_store_dwordx2 v[4:5], v[8:9], off
	s_waitcnt lgkmcnt(0)
	v_add_f32_e32 v0, v0, v1
	ds_bpermute_b32 v1, v10, v0
	s_waitcnt lgkmcnt(0)
	v_add_f32_e32 v0, v0, v1
	ds_bpermute_b32 v1, v11, v0
	s_waitcnt lgkmcnt(0)
	v_add_f32_e32 v0, v0, v1
	ds_bpermute_b32 v1, v12, v0
	s_and_saveexec_b64 s[12:13], s[10:11]
	s_cbranch_execz .LBB0_1158
	v_lshlrev_b64 v[2:3], 6, v[2:3]
	s_waitcnt lgkmcnt(0)
	v_add_f32_e32 v0, v0, v1
	v_lshl_add_u64 v[2:3], v[6:7], 0, v[2:3]
	v_cndmask_b32_e32 v0, 0, v0, vcc
	global_store_dword v[2:3], v0, off

; __device__ __forceinline__ unsigned pk2(float lo, float hi) { unsigned r; asm volatile("v_cvt_pk_bf16_f32 %0, %1, %2" : "=v"(r) : "v"(lo), "v"(hi)); return r; }
; #define RAW_BARRIER() do { asm volatile("s_waitcnt lgkmcnt(0)" ::: "memory"); __builtin_amdgcn_s_barrier(); asm volatile("" ::: "memory"); } while (0)
;     ...
;         RAW_BARRIER();
;         { u32x4 w;
;           w.x = pk2(tile[(k8 + 0) * 65 + n], tile[(k8 + 1) * 65 + n]); w.y = pk2(tile[(k8 + 2) * 65 + n], tile[(k8 + 3) * 65 + n]);
;           w.z = pk2(tile[(k8 + 4) * 65 + n], tile[(k8 + 5) * 65 + n]); w.w = pk2(tile[(k8 + 6) * 65 + n], tile[(k8 + 7) * 65 + n]);
;           *(u32x4*)(dst + (size_t)(n0 + n) * K + k0 + k8) = w; }
;         RAW_BARRIER();
.LBB0_1186:
	s_mul_hi_u32 s18, s22, 0xf0f0f0f1
	s_waitcnt lgkmcnt(0)
	s_barrier
	s_lshr_b32 s22, s18, 6
	ds_read_b32 v11, v17 offset:260
	ds_read_b32 v21, v16
	s_mulk_i32 s22, 0x1100
	v_subrev_u32_e32 v26, s22, v18
	v_ashrrev_i32_e32 v27, 31, v26
	v_lshlrev_b64 v[26:27], 11, v[26:27]
	s_andn2_b32 s18, s18, 63
	v_lshl_add_u64 v[26:27], s[10:11], 0, v[26:27]
	s_waitcnt lgkmcnt(0)
	v_cvt_pk_bf16_f32 v22, v21, v11
	ds_read2_b32 v[24:25], v17 offset0:130 offset1:195
	v_add_u32_e32 v11, 0x400, v17
	v_lshl_add_u64 v[26:27], s[18:19], 1, v[26:27]
	s_waitcnt lgkmcnt(0)
	v_cvt_pk_bf16_f32 v23, v24, v25
	ds_read2_b32 v[24:25], v11 offset0:4 offset1:69
	v_lshl_add_u64 v[26:27], v[26:27], 0, v[8:9]
	s_waitcnt lgkmcnt(0)
	v_cvt_pk_bf16_f32 v24, v24, v25
	ds_read2_b32 v[28:29], v11 offset0:134 offset1:199
	s_waitcnt lgkmcnt(0)
	v_cvt_pk_bf16_f32 v25, v28, v29
	global_store_dwordx4 v[26:27], v[22:25], off sc1
	s_waitcnt lgkmcnt(0)
	s_barrier
	v_add_u32_e32 v18, 0x2000, v18
	s_addk_i32 s8, 0x2000
	s_addk_i32 s80, 0x80
	s_andn2_b64 vcc, exec, s[20:21]
	s_mov_b32 s22, s9
	s_cbranch_vccz .LBB0_1189

; __device__ __forceinline__ unsigned pk2(float lo, float hi) { unsigned r; asm volatile("v_cvt_pk_bf16_f32 %0, %1, %2" : "=v"(r) : "v"(lo), "v"(hi)); return r; }
; #define KP(f) ((decltype(Params::f))karg_ptr<(int)offsetof(Params, f)>())
; #define RAW_BARRIER() do { asm volatile("s_waitcnt lgkmcnt(0)" ::: "memory"); __builtin_amdgcn_s_barrier(); asm volatile("" ::: "memory"); } while (0)
;     ...
;     if (t < ntiles) { const int k0 = (t / ntn) * 64, n0 = (t % ntn) * 64;
;         v0 = *(const f32x4*)(src + (size_t)(k0 + r) * N + n0 + c4); v1 = *(const f32x4*)(src + (size_t)(k0 + r + 32) * N + n0 + c4);
;         if (gain) { g0 = gain[k0 + r]; g1 = gain[k0 + r + 32]; } }
;     for (; t < ntiles; t += nwg) {
;         const int k0 = (t / ntn) * 64, n0 = (t % ntn) * 64;
;         tile[r * 65 + c4 + 0] = v0[0] * g0; tile[r * 65 + c4 + 1] = v0[1] * g0; tile[r * 65 + c4 + 2] = v0[2] * g0; tile[r * 65 + c4 + 3] = v0[3] * g0;
;         tile[(r + 32) * 65 + c4 + 0] = v1[0] * g1; tile[(r + 32) * 65 + c4 + 1] = v1[1] * g1; tile[(r + 32) * 65 + c4 + 2] = v1[2] * g1; tile[(r + 32) * 65 + c4 + 3] = v1[3] * g1;
;         const int tn = t + nwg;
;         if (tn < ntiles) { const int k1 = (tn / ntn) * 64, n1 = (tn % ntn) * 64;
;             v0 = *(const f32x4*)(src + (size_t)(k1 + r) * N + n1 + c4); v1 = *(const f32x4*)(src + (size_t)(k1 + r + 32) * N + n1 + c4);
;             if (gain) { g0 = gain[k1 + r]; g1 = gain[k1 + r + 32]; } }
;         RAW_BARRIER();
;         { u32x4 w;
;           w.x = pk2(tile[(k8 + 0) * 65 + n], tile[(k8 + 1) * 65 + n]); w.y = pk2(tile[(k8 + 2) * 65 + n], tile[(k8 + 3) * 65 + n]);
;           w.z = pk2(tile[(k8 + 4) * 65 + n], tile[(k8 + 5) * 65 + n]); w.w = pk2(tile[(k8 + 6) * 65 + n], tile[(k8 + 7) * 65 + n]);
;           *(u32x4*)(dst + (size_t)(n0 + n) * K + k0 + k8) = w; }
;         RAW_BARRIER();
; __device__ __forceinline__ void run_phase(int type, int l, unsigned char* shm) {
;     ...
;             transpose_convert(KP(w_b_up) + (size_t)512 * DM, 512, DM, nullptr, KP(BupT), (float*)shm, 64, 128);
;             transpose_convert(KP(w_a_up) + (size_t)512 * DM, 512, DM, nullptr, KP(AupT), (float*)shm, 64, 128);
.LBB0_1189:
	s_load_dwordx2 s[16:17], s[0:1], 0xa8
	s_waitcnt lgkmcnt(0)
	s_load_dwordx2 s[14:15], s[0:1], 0xf8
	s_waitcnt lgkmcnt(0)
	s_waitcnt vmcnt(0) lgkmcnt(0)
	v_cndmask_b32_e64 v1, 0, 1, s[12:13]
	v_mov_b32_e32 v0, v166
	v_cmp_ne_u32_e64 s[10:11], 1, v1
	s_andn2_b64 vcc, exec, s[12:13]
	s_cbranch_vccnz .LBB0_1191
	s_lshl_b32 s7, s6, 2
	v_ashrrev_i32_e32 v1, 4, v0
	v_lshlrev_b32_e32 v2, 4, v0
	s_and_b32 s7, s7, 0x1c0
	v_and_b32_e32 v10, 0xf0, v2
	v_add_u32_e32 v2, s7, v1
	s_lshl_b32 s8, s2, 6
	v_ashrrev_i32_e32 v3, 31, v2
	s_and_b32 s8, s8, 0x3c0
	v_lshlrev_b64 v[2:3], 12, v[2:3]
	s_mov_b32 s13, 0
	s_lshl_b32 s12, s8, 2
	v_lshl_add_u64 v[2:3], s[16:17], 0, v[2:3]
	v_mov_b32_e32 v11, 0
	v_lshl_add_u64 v[2:3], v[2:3], 0, s[12:13]
	v_lshl_add_u64 v[6:7], v[2:3], 0, v[10:11]
	s_mov_b32 s12, 0x200000
	v_add_co_u32_e32 v2, vcc, s12, v6
	s_mov_b32 s9, 0x220000
	s_nop 0
	v_addc_co_u32_e32 v3, vcc, 0, v7, vcc
	global_load_dwordx4 v[2:5], v[2:3], off
	v_add_co_u32_e32 v6, vcc, s9, v6
	v_ashrrev_i32_e32 v12, 3, v0
	s_nop 0
	v_addc_co_u32_e32 v7, vcc, 0, v7, vcc
	global_load_dwordx4 v[6:9], v[6:7], off
	v_lshlrev_b32_e32 v0, 3, v0
	s_movk_i32 s9, 0x104
	v_and_b32_e32 v13, 56, v0
	v_mul_lo_u32 v1, v1, s9
	v_mul_u32_u24_e32 v14, 0x41, v13
	v_add3_u32 v15, 0, v1, v10
	v_add3_u32 v1, 0, v10, v1
	v_lshlrev_b32_e32 v0, 2, v12
	v_lshlrev_b32_e32 v10, 2, v14
	v_add_u32_e32 v14, 0x2080, v15
	v_add_u32_e32 v15, 0x2088, v15
	v_add3_u32 v16, 0, v0, v10
	v_add3_u32 v10, 0, v10, v0
	s_lshl_b32 s12, s7, 1
	s_waitcnt vmcnt(1)
	ds_write2_b32 v1, v2, v3 offset1:1
	ds_write2_b32 v1, v4, v5 offset0:2 offset1:3
	s_waitcnt vmcnt(0)
	ds_write2_b32 v14, v6, v7 offset1:1
	ds_write2_b32 v15, v8, v9 offset1:1
	s_waitcnt lgkmcnt(0)
	s_barrier
	ds_read_b32 v0, v10 offset:260
	ds_read_b32 v1, v16
	v_add_u32_e32 v4, s8, v12
	v_ashrrev_i32_e32 v5, 31, v4
	v_lshlrev_b64 v[4:5], 10, v[4:5]
	v_lshl_add_u64 v[4:5], s[14:15], 0, v[4:5]
	s_waitcnt lgkmcnt(0)
	v_cvt_pk_bf16_f32 v0, v1, v0
	ds_read2_b32 v[2:3], v10 offset0:130 offset1:195
	v_add_u32_e32 v6, 0x400, v10
	v_lshl_add_u64 v[4:5], v[4:5], 0, s[12:13]
	v_lshlrev_b32_e32 v10, 1, v13
	s_waitcnt lgkmcnt(0)
	v_cvt_pk_bf16_f32 v1, v2, v3
	ds_read2_b32 v[2:3], v6 offset0:4 offset1:69
	v_lshl_add_u64 v[4:5], v[4:5], 0, v[10:11]
	s_waitcnt lgkmcnt(0)
	v_cvt_pk_bf16_f32 v2, v2, v3
	ds_read2_b32 v[6:7], v6 offset0:134 offset1:199
	s_waitcnt lgkmcnt(0)
	v_cvt_pk_bf16_f32 v3, v6, v7
	global_store_dwordx4 v[4:5], v[0:3], off sc1
	s_waitcnt lgkmcnt(0)
	s_barrier
.LBB0_1191:
	s_load_dwordx2 s[16:17], s[0:1], 0x90
	s_waitcnt lgkmcnt(0)
	s_load_dwordx2 s[12:13], s[0:1], 0x100
	s_waitcnt lgkmcnt(0)
	s_nop 0
	v_mov_b32_e32 v0, v166
	s_and_b64 vcc, exec, s[10:11]
	s_cbranch_vccnz .LBB0_1193
	s_lshl_b32 s7, s6, 2
	v_ashrrev_i32_e32 v1, 4, v0
	v_lshlrev_b32_e32 v2, 4, v0
	s_and_b32 s7, s7, 0x1c0
	v_and_b32_e32 v10, 0xf0, v2
	v_add_u32_e32 v2, s7, v1
	s_lshl_b32 s8, s2, 6
	v_ashrrev_i32_e32 v3, 31, v2
	s_and_b32 s8, s8, 0x3c0
	v_lshlrev_b64 v[2:3], 12, v[2:3]
	s_mov_b32 s15, 0
	s_lshl_b32 s14, s8, 2
	v_lshl_add_u64 v[2:3], s[16:17], 0, v[2:3]
	v_mov_b32_e32 v11, 0
	v_lshl_add_u64 v[2:3], v[2:3], 0, s[14:15]
	v_lshl_add_u64 v[6:7], v[2:3], 0, v[10:11]
	s_mov_b32 s14, 0x200000
	v_add_co_u32_e32 v2, vcc, s14, v6
	s_mov_b32 s9, 0x220000
	s_nop 0
	v_addc_co_u32_e32 v3, vcc, 0, v7, vcc
	global_load_dwordx4 v[2:5], v[2:3], off
	v_add_co_u32_e32 v6, vcc, s9, v6
	v_ashrrev_i32_e32 v12, 3, v0
	s_nop 0
	v_addc_co_u32_e32 v7, vcc, 0, v7, vcc
	global_load_dwordx4 v[6:9], v[6:7], off
	v_lshlrev_b32_e32 v0, 3, v0
	s_movk_i32 s9, 0x104
	v_and_b32_e32 v13, 56, v0
	v_mul_lo_u32 v1, v1, s9
	v_mul_u32_u24_e32 v14, 0x41, v13
	v_add3_u32 v15, 0, v1, v10
	v_add3_u32 v1, 0, v10, v1
	v_lshlrev_b32_e32 v0, 2, v12
	v_lshlrev_b32_e32 v10, 2, v14
	v_add_u32_e32 v14, 0x2080, v15
	v_add_u32_e32 v15, 0x2088, v15
	v_add3_u32 v16, 0, v0, v10
	v_add3_u32 v10, 0, v10, v0
	s_lshl_b32 s14, s7, 1
	s_waitcnt vmcnt(1)
	ds_write2_b32 v1, v2, v3 offset1:1
	ds_write2_b32 v1, v4, v5 offset0:2 offset1:3
	s_waitcnt vmcnt(0)
	ds_write2_b32 v14, v6, v7 offset1:1
	ds_write2_b32 v15, v8, v9 offset1:1
	s_waitcnt lgkmcnt(0)
	s_barrier
	ds_read_b32 v0, v10 offset:260
	ds_read_b32 v1, v16
	v_add_u32_e32 v4, s8, v12
	v_ashrrev_i32_e32 v5, 31, v4
	v_lshlrev_b64 v[4:5], 10, v[4:5]
	v_lshl_add_u64 v[4:5], s[12:13], 0, v[4:5]
	s_waitcnt lgkmcnt(0)
	v_cvt_pk_bf16_f32 v0, v1, v0
	ds_read2_b32 v[2:3], v10 offset0:130 offset1:195
	v_add_u32_e32 v6, 0x400, v10
	v_lshl_add_u64 v[4:5], v[4:5], 0, s[14:15]
	v_lshlrev_b32_e32 v10, 1, v13
	s_waitcnt lgkmcnt(0)
	v_cvt_pk_bf16_f32 v1, v2, v3
	ds_read2_b32 v[2:3], v6 offset0:4 offset1:69
	v_lshl_add_u64 v[4:5], v[4:5], 0, v[10:11]
	s_waitcnt lgkmcnt(0)
	v_cvt_pk_bf16_f32 v2, v2, v3
	ds_read2_b32 v[6:7], v6 offset0:134 offset1:199
	s_waitcnt lgkmcnt(0)
	v_cvt_pk_bf16_f32 v3, v6, v7
	global_store_dwordx4 v[4:5], v[0:3], off sc1
	s_waitcnt lgkmcnt(0)
	s_barrier

; __device__ __forceinline__ unsigned pk2(float lo, float hi) { unsigned r; asm volatile("v_cvt_pk_bf16_f32 %0, %1, %2" : "=v"(r) : "v"(lo), "v"(hi)); return r; }
; #define RAW_BARRIER() do { asm volatile("s_waitcnt lgkmcnt(0)" ::: "memory"); __builtin_amdgcn_s_barrier(); asm volatile("" ::: "memory"); } while (0)
;     ...
;         RAW_BARRIER();
;         { u32x4 w;
;           w.x = pk2(tile[(k8 + 0) * 65 + n], tile[(k8 + 1) * 65 + n]); w.y = pk2(tile[(k8 + 2) * 65 + n], tile[(k8 + 3) * 65 + n]);
;           w.z = pk2(tile[(k8 + 4) * 65 + n], tile[(k8 + 5) * 65 + n]); w.w = pk2(tile[(k8 + 6) * 65 + n], tile[(k8 + 7) * 65 + n]);
;           *(u32x4*)(dst + (size_t)(n0 + n) * K + k0 + k8) = w; }
;         RAW_BARRIER();
.LBB0_1195:
	s_waitcnt lgkmcnt(0)
	s_barrier
	ds_read_b32 v20, v16 offset:260
	ds_read_b32 v21, v15
	v_add_u32_e32 v24, s9, v13
	s_add_i32 s14, s7, 0xfffffe00
	v_ashrrev_i32_e32 v25, 31, v24
	s_and_b32 s9, s14, 0x7fffffc0
	v_lshlrev_b64 v[24:25], 11, v[24:25]
	s_lshl_b32 s14, s9, 1
	v_lshl_add_u64 v[24:25], s[12:13], 0, v[24:25]
	s_waitcnt lgkmcnt(0)
	v_cvt_pk_bf16_f32 v20, v21, v20
	ds_read2_b32 v[22:23], v16 offset0:130 offset1:195
	v_lshl_add_u64 v[24:25], v[24:25], 0, s[14:15]
	s_waitcnt lgkmcnt(0)
	v_cvt_pk_bf16_f32 v21, v22, v23
	ds_read2_b32 v[22:23], v19 offset0:4 offset1:69
	v_lshl_add_u64 v[24:25], v[24:25], 0, v[10:11]
	s_waitcnt lgkmcnt(0)
	v_cvt_pk_bf16_f32 v22, v22, v23
	ds_read2_b32 v[26:27], v19 offset0:134 offset1:199
	s_waitcnt lgkmcnt(0)
	v_cvt_pk_bf16_f32 v23, v26, v27
	global_store_dwordx4 v[24:25], v[20:23], off sc1
	s_waitcnt lgkmcnt(0)
	s_barrier
	s_addk_i32 s6, 0x80
	s_addk_i32 s7, 0x200
	s_andn2_b64 vcc, exec, s[16:17]
	s_addk_i32 s8, 0x2000
	s_cbranch_vccz .LBB0_1198

; #define PG8_STAGE(bufoff, gbase, voff) do { _Pragma("unroll") for (int _i = 0; _i < 2; ++_i) \
;         __builtin_amdgcn_global_load_lds((const unsigned*)((const char*)(gbase) + (voff)[_i]), (LAS unsigned*)(lds + (bufoff) + ldsw + _i * 8192), 16, 0, 0); } while (0)
; #define PG8_LDA(dst, b, h) do { _Pragma("unroll") for (int m = 0; m < 4; ++m) _Pragma("unroll") for (int k = 0; k < 2; ++k) dst[m][k] = *(const LAS bf16x8*)(lds + PG8_SA(b, h) + aoff + m * 2048 + k * 1024); } while (0)
; #define PG8_LDB(dst, b, h) do { _Pragma("unroll") for (int n = 0; n < 2; ++n) _Pragma("unroll") for (int k = 0; k < 2; ++k) dst[n][k] = *(const LAS bf16x8*)(lds + PG8_SB(b, h) + boff + n * 2048 + k * 1024); } while (0)
; #define PG8_MMA(ai, bj, At, Bt) do { __builtin_amdgcn_s_setprio(1); _Pragma("unroll") for (int m = 0; m < 4; ++m) _Pragma("unroll") for (int n = 0; n < 2; ++n) _Pragma("unroll") for (int k = 0; k < 2; ++k) \
;         acc[ai][bj][m][n] = __builtin_amdgcn_mfma_f32_16x16x32_bf16(Bt[n][k], At[m][k], acc[ai][bj][m][n], 0, 0, 0); __builtin_amdgcn_s_setprio(0); } while (0)
; #define PG8_WAIT_V(n) asm volatile("s_waitcnt vmcnt(" #n ")" ::: "memory")
; #define PG8_WAIT_L(n) asm volatile("s_waitcnt lgkmcnt(" #n ")" ::: "memory")
; #define PG8_BAR __builtin_amdgcn_s_barrier()
; #define PG8_SCHED __builtin_amdgcn_sched_barrier(0)
;     ...
;             PG8_LDB(B0, 0, 0); PG8_SCHED; PG8_LDA(At, 0, 0); PG8_STAGE(PG8_SA(1, 1), a1 + hA, voffA);
;             PG8_WAIT_L(8); PG8_BAR; PG8_WAIT_L(0); PG8_MMA(0, 0, At, B0); PG8_BAR; PG8_SCHED;
;             PG8_LDB(B1, 0, 1); PG8_STAGE(PG8_SB(0, 0), b2, voffB);
;             PG8_BAR; PG8_WAIT_L(0); PG8_MMA(0, 1, At, B1); PG8_BAR;
;             PG8_LDA(At, 0, 1); PG8_STAGE(PG8_SA(0, 0), a2, voffA);
;             PG8_BAR; PG8_WAIT_L(0); PG8_MMA(1, 0, At, B0); PG8_BAR; PG8_SCHED;
;             PG8_STAGE(PG8_SB(0, 1), b2 + hB, voffB);
;             PG8_WAIT_V(6); PG8_BAR; PG8_MMA(1, 1, At, B1); PG8_BAR;
.LBB0_1288:
	ds_read_b128 v[146:149], v155
	ds_read_b128 v[160:163], v155 offset:1024
	ds_read_b128 v[170:173], v155 offset:2048
	ds_read_b128 v[174:177], v155 offset:3072
	s_add_u32 s36, s34, 0xfffc0080
	s_addc_u32 s37, s35, -1
	s_cmp_eq_u32 s42, 12
	s_cselect_b32 s39, s7, s37
	s_cselect_b32 s38, s8, s36
	s_cselect_b32 s37, s9, s33
	s_cselect_b32 s36, s23, s25
	v_lshl_add_u64 v[150:151], s[34:35], 0, v[138:139]
	s_add_i32 m0, s31, 0xc000
	ds_read_b128 v[178:181], v156
	ds_read_b128 v[182:185], v156 offset:1024
	ds_read_b128 v[186:189], v156 offset:2048
	ds_read_b128 v[190:193], v156 offset:3072
	ds_read_b128 v[194:197], v156 offset:4096
	ds_read_b128 v[198:201], v156 offset:5120
	ds_read_b128 v[202:205], v156 offset:6144
	ds_read_b128 v[206:209], v156 offset:7168
	global_load_lds_dwordx4 v[150:151], off
	v_lshl_add_u64 v[150:151], s[34:35], 0, v[136:137]
	s_add_i32 m0, s31, 0xe000
	s_nop 0
	global_load_lds_dwordx4 v[150:151], off
	s_waitcnt lgkmcnt(8)
	s_barrier
	s_waitcnt lgkmcnt(0)
	s_setprio 1
	s_waitcnt lgkmcnt(0)
	v_mfma_f32_16x16x32_bf16 v[124:127], v[146:149], v[178:181], v[124:127]
	v_mfma_f32_16x16x32_bf16 v[120:123], v[170:173], v[178:181], v[120:123]
	v_mfma_f32_16x16x32_bf16 v[108:111], v[146:149], v[186:189], v[108:111]
	v_mfma_f32_16x16x32_bf16 v[104:107], v[170:173], v[186:189], v[104:107]
	v_mfma_f32_16x16x32_bf16 v[92:95], v[146:149], v[194:197], v[92:95]
	v_mfma_f32_16x16x32_bf16 v[88:91], v[170:173], v[194:197], v[88:91]
	v_mfma_f32_16x16x32_bf16 v[76:79], v[146:149], v[202:205], v[76:79]
	v_mfma_f32_16x16x32_bf16 v[72:75], v[170:173], v[202:205], v[72:75]
	v_mfma_f32_16x16x32_bf16 v[124:127], v[160:163], v[182:185], v[124:127]
	v_mfma_f32_16x16x32_bf16 v[120:123], v[174:177], v[182:185], v[120:123]
	v_mfma_f32_16x16x32_bf16 v[108:111], v[160:163], v[190:193], v[108:111]
	v_mfma_f32_16x16x32_bf16 v[104:107], v[174:177], v[190:193], v[104:107]
	v_mfma_f32_16x16x32_bf16 v[92:95], v[160:163], v[198:201], v[92:95]
	v_mfma_f32_16x16x32_bf16 v[88:91], v[174:177], v[198:201], v[88:91]
	v_mfma_f32_16x16x32_bf16 v[76:79], v[160:163], v[206:209], v[76:79]
	v_mfma_f32_16x16x32_bf16 v[72:75], v[174:177], v[206:209], v[72:75]
	s_setprio 0
	s_barrier
	s_add_i32 s43, s63, s55
	v_lshl_add_u64 v[150:151], s[36:37], 0, v[130:131]
	s_mov_b32 m0, s43
	ds_read_b128 v[210:213], v157
	ds_read_b128 v[214:217], v157 offset:1024
	ds_read_b128 v[218:221], v157 offset:2048
	ds_read_b128 v[222:225], v157 offset:3072
	global_load_lds_dwordx4 v[150:151], off
	v_lshl_add_u64 v[164:165], s[36:37], 0, v[134:135]
	s_add_i32 m0, s43, 0x2000
	s_nop 0
	global_load_lds_dwordx4 v[164:165], off
	s_barrier
	s_waitcnt lgkmcnt(0)
	s_setprio 1
	s_waitcnt lgkmcnt(0)
	v_mfma_f32_16x16x32_bf16 v[116:119], v[210:213], v[178:181], v[116:119]
	v_mfma_f32_16x16x32_bf16 v[112:115], v[218:221], v[178:181], v[112:115]
	v_mfma_f32_16x16x32_bf16 v[100:103], v[210:213], v[186:189], v[100:103]
	v_mfma_f32_16x16x32_bf16 v[96:99], v[218:221], v[186:189], v[96:99]
	v_mfma_f32_16x16x32_bf16 v[84:87], v[210:213], v[194:197], v[84:87]
	v_mfma_f32_16x16x32_bf16 v[80:83], v[218:221], v[194:197], v[80:83]
	v_mfma_f32_16x16x32_bf16 v[68:71], v[210:213], v[202:205], v[68:71]
	v_mfma_f32_16x16x32_bf16 v[64:67], v[218:221], v[202:205], v[64:67]
	v_mfma_f32_16x16x32_bf16 v[116:119], v[214:217], v[182:185], v[116:119]
	v_mfma_f32_16x16x32_bf16 v[112:115], v[222:225], v[182:185], v[112:115]
	v_mfma_f32_16x16x32_bf16 v[100:103], v[214:217], v[190:193], v[100:103]
	v_mfma_f32_16x16x32_bf16 v[96:99], v[222:225], v[190:193], v[96:99]
	v_mfma_f32_16x16x32_bf16 v[84:87], v[214:217], v[198:201], v[84:87]
	v_mfma_f32_16x16x32_bf16 v[80:83], v[222:225], v[198:201], v[80:83]
	v_mfma_f32_16x16x32_bf16 v[68:71], v[214:217], v[206:209], v[68:71]
	v_mfma_f32_16x16x32_bf16 v[64:67], v[222:225], v[206:209], v[64:67]
	s_setprio 0
	s_mov_b32 m0, s31
	v_lshl_add_u64 v[226:227], s[38:39], 0, v[128:129]
	s_barrier
	ds_read_b128 v[178:181], v156 offset:16384
	ds_read_b128 v[182:185], v156 offset:17408
	ds_read_b128 v[186:189], v156 offset:18432
	ds_read_b128 v[190:193], v156 offset:19456
	ds_read_b128 v[194:197], v156 offset:20480
	ds_read_b128 v[198:201], v156 offset:21504
	ds_read_b128 v[202:205], v156 offset:22528
	ds_read_b128 v[206:209], v156 offset:23552
	global_load_lds_dwordx4 v[226:227], off
	v_lshl_add_u64 v[228:229], s[38:39], 0, v[132:133]
	s_mov_b32 m0, s56
	s_nop 0
	global_load_lds_dwordx4 v[228:229], off
	s_barrier
	s_waitcnt lgkmcnt(0)
	s_setprio 1
	s_waitcnt lgkmcnt(0)
	v_mfma_f32_16x16x32_bf16 v[60:63], v[146:149], v[178:181], v[60:63]
	v_mfma_f32_16x16x32_bf16 v[56:59], v[170:173], v[178:181], v[56:59]
	v_mfma_f32_16x16x32_bf16 v[44:47], v[146:149], v[186:189], v[44:47]
	v_mfma_f32_16x16x32_bf16 v[40:43], v[170:173], v[186:189], v[40:43]
	v_mfma_f32_16x16x32_bf16 v[28:31], v[146:149], v[194:197], v[28:31]
	v_mfma_f32_16x16x32_bf16 v[24:27], v[170:173], v[194:197], v[24:27]
	v_mfma_f32_16x16x32_bf16 v[12:15], v[146:149], v[202:205], v[12:15]
	v_mfma_f32_16x16x32_bf16 v[8:11], v[170:173], v[202:205], v[8:11]
	v_mfma_f32_16x16x32_bf16 v[60:63], v[160:163], v[182:185], v[60:63]
	v_mfma_f32_16x16x32_bf16 v[56:59], v[174:177], v[182:185], v[56:59]
	v_mfma_f32_16x16x32_bf16 v[44:47], v[160:163], v[190:193], v[44:47]
	v_mfma_f32_16x16x32_bf16 v[40:43], v[174:177], v[190:193], v[40:43]
	v_mfma_f32_16x16x32_bf16 v[28:31], v[160:163], v[198:201], v[28:31]
	v_mfma_f32_16x16x32_bf16 v[24:27], v[174:177], v[198:201], v[24:27]
	v_mfma_f32_16x16x32_bf16 v[12:15], v[160:163], v[206:209], v[12:15]
	v_mfma_f32_16x16x32_bf16 v[8:11], v[174:177], v[206:209], v[8:11]
	s_setprio 0
	s_barrier
; #define PG8_STAGE(bufoff, gbase, voff) do { _Pragma("unroll") for (int _i = 0; _i < 2; ++_i) \
;         __builtin_amdgcn_global_load_lds((const unsigned*)((const char*)(gbase) + (voff)[_i]), (LAS unsigned*)(lds + (bufoff) + ldsw + _i * 8192), 16, 0, 0); } while (0)
; #define PG8_LDA(dst, b, h) do { _Pragma("unroll") for (int m = 0; m < 4; ++m) _Pragma("unroll") for (int k = 0; k < 2; ++k) dst[m][k] = *(const LAS bf16x8*)(lds + PG8_SA(b, h) + aoff + m * 2048 + k * 1024); } while (0)
; #define PG8_LDB(dst, b, h) do { _Pragma("unroll") for (int n = 0; n < 2; ++n) _Pragma("unroll") for (int k = 0; k < 2; ++k) dst[n][k] = *(const LAS bf16x8*)(lds + PG8_SB(b, h) + boff + n * 2048 + k * 1024); } while (0)
; #define PG8_MMA(ai, bj, At, Bt) do { __builtin_amdgcn_s_setprio(1); _Pragma("unroll") for (int m = 0; m < 4; ++m) _Pragma("unroll") for (int n = 0; n < 2; ++n) _Pragma("unroll") for (int k = 0; k < 2; ++k) \
;         acc[ai][bj][m][n] = __builtin_amdgcn_mfma_f32_16x16x32_bf16(Bt[n][k], At[m][k], acc[ai][bj][m][n], 0, 0, 0); __builtin_amdgcn_s_setprio(0); } while (0)
; #define PG8_WAIT_V(n) asm volatile("s_waitcnt vmcnt(" #n ")" ::: "memory")
; #define PG8_WAIT_L(n) asm volatile("s_waitcnt lgkmcnt(" #n ")" ::: "memory")
; #define PG8_BAR __builtin_amdgcn_s_barrier()
; #define PG8_SCHED __builtin_amdgcn_sched_barrier(0)
;     ...
;             PG8_WAIT_V(6); PG8_BAR; PG8_MMA(1, 1, At, B1); PG8_BAR;
;             PG8_LDB(B0, 1, 0); PG8_SCHED; PG8_LDA(At, 1, 0); PG8_STAGE(PG8_SA(0, 1), a2 + hA, voffA);
;             PG8_WAIT_L(8); PG8_BAR; PG8_WAIT_L(0); PG8_MMA(0, 0, At, B0); PG8_BAR; PG8_SCHED;
;             PG8_LDB(B1, 1, 1); PG8_STAGE(PG8_SB(1, 0), b3, voffB);
;             PG8_BAR; PG8_WAIT_L(0); PG8_MMA(0, 1, At, B1); PG8_BAR;
;             PG8_LDA(At, 1, 1); PG8_STAGE(PG8_SA(1, 0), a3, voffA);
;             PG8_BAR; PG8_WAIT_L(0); PG8_MMA(1, 0, At, B0); PG8_BAR; PG8_SCHED;
	s_add_u32 s44, s36, 0x40000
	s_addc_u32 s45, s37, 0
	s_add_i32 s43, s64, s55
	v_lshl_add_u64 v[146:147], s[44:45], 0, v[130:131]
	s_mov_b32 m0, s43
	s_nop 0
	global_load_lds_dwordx4 v[146:147], off
	v_lshl_add_u64 v[146:147], s[44:45], 0, v[134:135]
	s_add_i32 m0, s43, 0x2000
	s_nop 0
	global_load_lds_dwordx4 v[146:147], off
	s_waitcnt vmcnt(6)
	s_barrier
	s_setprio 1
	v_mfma_f32_16x16x32_bf16 v[52:55], v[210:213], v[178:181], v[52:55]
	v_mfma_f32_16x16x32_bf16 v[48:51], v[218:221], v[178:181], v[48:51]
	v_mfma_f32_16x16x32_bf16 v[36:39], v[210:213], v[186:189], v[36:39]
	v_mfma_f32_16x16x32_bf16 v[32:35], v[218:221], v[186:189], v[32:35]
	v_mfma_f32_16x16x32_bf16 v[20:23], v[210:213], v[194:197], v[20:23]
	v_mfma_f32_16x16x32_bf16 v[16:19], v[218:221], v[194:197], v[16:19]
	v_mfma_f32_16x16x32_bf16 v[4:7], v[210:213], v[202:205], v[4:7]
	v_mfma_f32_16x16x32_bf16 v[0:3], v[218:221], v[202:205], v[0:3]
	v_mfma_f32_16x16x32_bf16 v[52:55], v[214:217], v[182:185], v[52:55]
	v_mfma_f32_16x16x32_bf16 v[48:51], v[222:225], v[182:185], v[48:51]
	v_mfma_f32_16x16x32_bf16 v[36:39], v[214:217], v[190:193], v[36:39]
	v_mfma_f32_16x16x32_bf16 v[32:35], v[222:225], v[190:193], v[32:35]
	v_mfma_f32_16x16x32_bf16 v[20:23], v[214:217], v[198:201], v[20:23]
	v_mfma_f32_16x16x32_bf16 v[16:19], v[222:225], v[198:201], v[16:19]
	v_mfma_f32_16x16x32_bf16 v[4:7], v[214:217], v[206:209], v[4:7]
	v_mfma_f32_16x16x32_bf16 v[0:3], v[222:225], v[206:209], v[0:3]
	s_setprio 0
	s_add_i32 s43, 0, 0x18000
	v_add_u32_e32 v159, s43, v153
	s_barrier
	ds_read_b128 v[146:149], v159
	ds_read_b128 v[160:163], v159 offset:1024
	ds_read_b128 v[170:173], v159 offset:2048
	ds_read_b128 v[174:177], v159 offset:3072
	s_add_u32 s38, s38, 0x40000
	s_addc_u32 s39, s39, 0
	s_mov_b32 m0, s57
	v_lshl_add_u64 v[210:211], s[38:39], 0, v[128:129]
	ds_read_b128 v[178:181], v156 offset:32768
	ds_read_b128 v[182:185], v156 offset:33792
	ds_read_b128 v[186:189], v156 offset:34816
	ds_read_b128 v[190:193], v156 offset:35840
	ds_read_b128 v[194:197], v156 offset:36864
	ds_read_b128 v[198:201], v156 offset:37888
	ds_read_b128 v[202:205], v156 offset:38912
	ds_read_b128 v[206:209], v156 offset:39936
	global_load_lds_dwordx4 v[210:211], off
	v_lshl_add_u64 v[210:211], s[38:39], 0, v[132:133]
	s_mov_b32 m0, s58
	s_nop 0
	global_load_lds_dwordx4 v[210:211], off
	s_waitcnt lgkmcnt(8)
	s_barrier
	s_waitcnt lgkmcnt(0)
	s_setprio 1
	s_waitcnt lgkmcnt(0)
	v_mfma_f32_16x16x32_bf16 v[124:127], v[146:149], v[178:181], v[124:127]
	v_mfma_f32_16x16x32_bf16 v[120:123], v[170:173], v[178:181], v[120:123]
	v_mfma_f32_16x16x32_bf16 v[108:111], v[146:149], v[186:189], v[108:111]
	v_mfma_f32_16x16x32_bf16 v[104:107], v[170:173], v[186:189], v[104:107]
	v_mfma_f32_16x16x32_bf16 v[92:95], v[146:149], v[194:197], v[92:95]
	v_mfma_f32_16x16x32_bf16 v[88:91], v[170:173], v[194:197], v[88:91]
	v_mfma_f32_16x16x32_bf16 v[76:79], v[146:149], v[202:205], v[76:79]
	v_mfma_f32_16x16x32_bf16 v[72:75], v[170:173], v[202:205], v[72:75]
	v_mfma_f32_16x16x32_bf16 v[124:127], v[160:163], v[182:185], v[124:127]
	v_mfma_f32_16x16x32_bf16 v[120:123], v[174:177], v[182:185], v[120:123]
	v_mfma_f32_16x16x32_bf16 v[108:111], v[160:163], v[190:193], v[108:111]
	v_mfma_f32_16x16x32_bf16 v[104:107], v[174:177], v[190:193], v[104:107]
	v_mfma_f32_16x16x32_bf16 v[92:95], v[160:163], v[198:201], v[92:95]
	v_mfma_f32_16x16x32_bf16 v[88:91], v[174:177], v[198:201], v[88:91]
	v_mfma_f32_16x16x32_bf16 v[76:79], v[160:163], v[206:209], v[76:79]
	v_mfma_f32_16x16x32_bf16 v[72:75], v[174:177], v[206:209], v[72:75]
	s_setprio 0
	s_barrier
	s_add_i32 s38, 0, 0x1c000
	s_add_i32 s39, s43, s55
	v_add_u32_e32 v159, s38, v153
	v_lshl_add_u64 v[150:151], v[150:151], 0, s[20:21]
	s_mov_b32 m0, s39
	ds_read_b128 v[210:213], v159
	ds_read_b128 v[214:217], v159 offset:1024
	ds_read_b128 v[218:221], v159 offset:2048
	ds_read_b128 v[222:225], v159 offset:3072
	global_load_lds_dwordx4 v[150:151], off
	v_lshl_add_u64 v[150:151], v[164:165], 0, s[20:21]
	s_add_i32 m0, s39, 0x2000
	s_nop 0
	global_load_lds_dwordx4 v[150:151], off
	s_barrier
	s_waitcnt lgkmcnt(0)
	s_setprio 1
	s_waitcnt lgkmcnt(0)
	v_mfma_f32_16x16x32_bf16 v[116:119], v[210:213], v[178:181], v[116:119]
	v_mfma_f32_16x16x32_bf16 v[112:115], v[218:221], v[178:181], v[112:115]
	v_mfma_f32_16x16x32_bf16 v[100:103], v[210:213], v[186:189], v[100:103]
	v_mfma_f32_16x16x32_bf16 v[96:99], v[218:221], v[186:189], v[96:99]
	v_mfma_f32_16x16x32_bf16 v[84:87], v[210:213], v[194:197], v[84:87]
	v_mfma_f32_16x16x32_bf16 v[80:83], v[218:221], v[194:197], v[80:83]
	v_mfma_f32_16x16x32_bf16 v[68:71], v[210:213], v[202:205], v[68:71]
	v_mfma_f32_16x16x32_bf16 v[64:67], v[218:221], v[202:205], v[64:67]
	v_mfma_f32_16x16x32_bf16 v[116:119], v[214:217], v[182:185], v[116:119]
	v_mfma_f32_16x16x32_bf16 v[112:115], v[222:225], v[182:185], v[112:115]
	v_mfma_f32_16x16x32_bf16 v[100:103], v[214:217], v[190:193], v[100:103]
	v_mfma_f32_16x16x32_bf16 v[96:99], v[222:225], v[190:193], v[96:99]
	v_mfma_f32_16x16x32_bf16 v[84:87], v[214:217], v[198:201], v[84:87]
	v_mfma_f32_16x16x32_bf16 v[80:83], v[222:225], v[198:201], v[80:83]
	v_mfma_f32_16x16x32_bf16 v[68:71], v[214:217], v[206:209], v[68:71]
	v_mfma_f32_16x16x32_bf16 v[64:67], v[222:225], v[206:209], v[64:67]
	s_setprio 0
	s_mov_b32 m0, s60
	v_lshl_add_u64 v[150:151], v[226:227], 0, s[20:21]
	s_barrier
	ds_read_b128 v[178:181], v156 offset:49152
	ds_read_b128 v[182:185], v156 offset:50176
	ds_read_b128 v[186:189], v156 offset:51200
	ds_read_b128 v[190:193], v156 offset:52224
	ds_read_b128 v[194:197], v156 offset:53248
	ds_read_b128 v[198:201], v156 offset:54272
	ds_read_b128 v[202:205], v156 offset:55296
	ds_read_b128 v[206:209], v156 offset:56320
	global_load_lds_dwordx4 v[150:151], off
	v_lshl_add_u64 v[150:151], v[228:229], 0, s[20:21]
	s_mov_b32 m0, s61
	s_nop 0
	global_load_lds_dwordx4 v[150:151], off
	s_barrier
; #define PG8_STAGE(bufoff, gbase, voff) do { _Pragma("unroll") for (int _i = 0; _i < 2; ++_i) \
;         __builtin_amdgcn_global_load_lds((const unsigned*)((const char*)(gbase) + (voff)[_i]), (LAS unsigned*)(lds + (bufoff) + ldsw + _i * 8192), 16, 0, 0); } while (0)
; #define PG8_MMA(ai, bj, At, Bt) do { __builtin_amdgcn_s_setprio(1); _Pragma("unroll") for (int m = 0; m < 4; ++m) _Pragma("unroll") for (int n = 0; n < 2; ++n) _Pragma("unroll") for (int k = 0; k < 2; ++k) \
;         acc[ai][bj][m][n] = __builtin_amdgcn_mfma_f32_16x16x32_bf16(Bt[n][k], At[m][k], acc[ai][bj][m][n], 0, 0, 0); __builtin_amdgcn_s_setprio(0); } while (0)
; #define PG8_WAIT_V(n) asm volatile("s_waitcnt vmcnt(" #n ")" ::: "memory")
; #define PG8_WAIT_L(n) asm volatile("s_waitcnt lgkmcnt(" #n ")" ::: "memory")
; #define PG8_BAR __builtin_amdgcn_s_barrier()
; #define PG8_SCHED __builtin_amdgcn_sched_barrier(0)
;     ...
;             PG8_BAR; PG8_WAIT_L(0); PG8_MMA(1, 0, At, B0); PG8_BAR; PG8_SCHED;
;             PG8_STAGE(PG8_SB(1, 1), b3 + hB, voffB);
;             PG8_WAIT_V(6); PG8_BAR; PG8_MMA(1, 1, At, B1); PG8_BAR;
; __device__ __forceinline__ float row_rstd(const float* ssq, int row) {
;     const f32x4* p = (const f32x4*)(ssq + (size_t)row * 16);
;     const f32x4 a = p[0], b = p[1], c = p[2], d = p[3];
;     const float s = ((a[0] + a[1]) + (a[2] + a[3])) + ((b[0] + b[1]) + (b[2] + b[3])) + ((c[0] + c[1]) + (c[2] + c[3])) + ((d[0] + d[1]) + (d[2] + d[3]));
;     return rsqrtf(s * (1.0f / 1024.0f) + 1e-6f);
	s_waitcnt lgkmcnt(0)
	s_setprio 1
	s_waitcnt lgkmcnt(0)
	v_mfma_f32_16x16x32_bf16 v[60:63], v[146:149], v[178:181], v[60:63]
	v_mfma_f32_16x16x32_bf16 v[56:59], v[170:173], v[178:181], v[56:59]
	v_mfma_f32_16x16x32_bf16 v[44:47], v[146:149], v[186:189], v[44:47]
	v_mfma_f32_16x16x32_bf16 v[40:43], v[170:173], v[186:189], v[40:43]
	v_mfma_f32_16x16x32_bf16 v[28:31], v[146:149], v[194:197], v[28:31]
	v_mfma_f32_16x16x32_bf16 v[24:27], v[170:173], v[194:197], v[24:27]
	v_mfma_f32_16x16x32_bf16 v[12:15], v[146:149], v[202:205], v[12:15]
	v_mfma_f32_16x16x32_bf16 v[8:11], v[170:173], v[202:205], v[8:11]
	v_mfma_f32_16x16x32_bf16 v[60:63], v[160:163], v[182:185], v[60:63]
	v_mfma_f32_16x16x32_bf16 v[56:59], v[174:177], v[182:185], v[56:59]
	v_mfma_f32_16x16x32_bf16 v[44:47], v[160:163], v[190:193], v[44:47]
	v_mfma_f32_16x16x32_bf16 v[40:43], v[174:177], v[190:193], v[40:43]
	v_mfma_f32_16x16x32_bf16 v[28:31], v[160:163], v[198:201], v[28:31]
	v_mfma_f32_16x16x32_bf16 v[24:27], v[174:177], v[198:201], v[24:27]
	v_mfma_f32_16x16x32_bf16 v[12:15], v[160:163], v[206:209], v[12:15]
	v_mfma_f32_16x16x32_bf16 v[8:11], v[174:177], v[206:209], v[8:11]
	s_setprio 0
	s_barrier
	s_add_u32 s36, s36, 0x40080
	s_addc_u32 s37, s37, 0
	s_add_i32 s38, s38, s55
	v_lshl_add_u64 v[146:147], s[36:37], 0, v[130:131]
	s_mov_b32 m0, s38
	s_nop 0
	global_load_lds_dwordx4 v[146:147], off
	v_lshl_add_u64 v[146:147], s[36:37], 0, v[134:135]
	s_add_i32 m0, s38, 0x2000
	s_nop 0
	global_load_lds_dwordx4 v[146:147], off
	s_waitcnt vmcnt(6)
	s_barrier
	s_setprio 1
	v_mfma_f32_16x16x32_bf16 v[52:55], v[210:213], v[178:181], v[52:55]
	v_mfma_f32_16x16x32_bf16 v[48:51], v[218:221], v[178:181], v[48:51]
	v_mfma_f32_16x16x32_bf16 v[36:39], v[210:213], v[186:189], v[36:39]
	v_mfma_f32_16x16x32_bf16 v[32:35], v[218:221], v[186:189], v[32:35]
	v_mfma_f32_16x16x32_bf16 v[20:23], v[210:213], v[194:197], v[20:23]
	v_mfma_f32_16x16x32_bf16 v[16:19], v[218:221], v[194:197], v[16:19]
	v_mfma_f32_16x16x32_bf16 v[4:7], v[210:213], v[202:205], v[4:7]
	v_mfma_f32_16x16x32_bf16 v[0:3], v[218:221], v[202:205], v[0:3]
	v_mfma_f32_16x16x32_bf16 v[52:55], v[214:217], v[182:185], v[52:55]
	v_mfma_f32_16x16x32_bf16 v[48:51], v[222:225], v[182:185], v[48:51]
	v_mfma_f32_16x16x32_bf16 v[36:39], v[214:217], v[190:193], v[36:39]
	v_mfma_f32_16x16x32_bf16 v[32:35], v[222:225], v[190:193], v[32:35]
	v_mfma_f32_16x16x32_bf16 v[20:23], v[214:217], v[198:201], v[20:23]
	v_mfma_f32_16x16x32_bf16 v[16:19], v[222:225], v[198:201], v[16:19]
	v_mfma_f32_16x16x32_bf16 v[4:7], v[214:217], v[206:209], v[4:7]
	v_mfma_f32_16x16x32_bf16 v[0:3], v[222:225], v[206:209], v[0:3]
	s_setprio 0
	s_add_i32 s42, s42, 2
	s_add_u32 s25, s25, 0x100
	s_addc_u32 s33, s33, 0
	s_add_u32 s34, s34, 0x100
	s_addc_u32 s35, s35, 0
	s_cmp_gt_u32 s42, 13
	s_barrier
	s_cbranch_scc0 .LBB0_1288
	v_lshl_add_u32 v150, s30, 8, v152
	v_ashrrev_i32_e32 v151, 31, v150
	v_lshlrev_b64 v[146:147], 6, v[150:151]
	v_lshl_add_u64 v[146:147], s[18:19], 0, v[146:147]
	v_subrev_u32_e32 v186, s18, v146
	v_add_u32_e32 v187, 0x0, v186
	global_load_dwordx4 v[188:191], v187, s[18:19]
	v_add_u32_e32 v187, 0x10, v186
	global_load_dwordx4 v[192:195], v187, s[18:19]
	v_add_u32_e32 v187, 0x20, v186
	global_load_dwordx4 v[196:199], v187, s[18:19]
	v_add_u32_e32 v187, 0x30, v186
	global_load_dwordx4 v[200:203], v187, s[18:19]
	v_add_u32_e32 v187, 0x400, v186
	global_load_dwordx4 v[204:207], v187, s[18:19]
	v_add_u32_e32 v187, 0x410, v186
	global_load_dwordx4 v[208:211], v187, s[18:19]
	v_add_u32_e32 v187, 0x420, v186
	global_load_dwordx4 v[212:215], v187, s[18:19]
	v_add_u32_e32 v187, 0x430, v186
	global_load_dwordx4 v[216:219], v187, s[18:19]
	v_add_u32_e32 v187, 0x800, v186
	global_load_dwordx4 v[220:223], v187, s[18:19]
	v_add_u32_e32 v187, 0x810, v186
	global_load_dwordx4 v[232:235], v187, s[18:19]
	v_add_u32_e32 v187, 0x820, v186
	global_load_dwordx4 v[236:239], v187, s[18:19]
	v_add_u32_e32 v187, 0x830, v186
	global_load_dwordx4 v[240:243], v187, s[18:19]
	v_lshl_or_b32 v148, s6, 8, v154
	v_mov_b64_e32 v[146:147], s[16:17]
	v_ashrrev_i32_e32 v149, 31, v148
	v_mad_i64_i32 v[164:165], s[6:7], v150, s66, v[146:147]
	v_or_b32_e32 v182, 16, v150
	v_lshlrev_b64 v[148:149], 1, v[148:149]
	v_ashrrev_i32_e32 v183, 31, v182
	s_mov_b32 s30, s24
	s_mov_b64 s[34:35], s[28:29]
	s_mov_b64 s[36:37], s[26:27]
	s_waitcnt vmcnt(8)
; __device__ __forceinline__ u32x4 pack8(const f32x4 v0, const f32x4 v1) { u32x4 w; w.x = pk2(v0[0], v0[1]); w.y = pk2(v0[2], v0[3]); w.z = pk2(v1[0], v1[1]); w.w = pk2(v1[2], v1[3]); return w; }
; __device__ __forceinline__ float row_rstd(const float* ssq, int row) {
;     const f32x4* p = (const f32x4*)(ssq + (size_t)row * 16);
;     const f32x4 a = p[0], b = p[1], c = p[2], d = p[3];
;     const float s = ((a[0] + a[1]) + (a[2] + a[3])) + ((b[0] + b[1]) + (b[2] + b[3])) + ((c[0] + c[1]) + (c[2] + c[3])) + ((d[0] + d[1]) + (d[2] + d[3]));
;     return rsqrtf(s * (1.0f / 1024.0f) + 1e-6f);
;     __device__ __forceinline__ void operator()(const f32x4 (&acc)[2][2][4][2], const Unit& u, int wr, int wc, int fr, int fq) const {
;         const int row0 = u.pm * 256 + wr * 64 + fr, col0 = u.pn * 256 + wc * 32 + 8 * fq;
; #pragma unroll
;         for (int ai = 0; ai < 2; ++ai)
; #pragma unroll
;             for (int m = 0; m < 4; ++m) {
;                 const int row = row0 + ai * 128 + m * 16; const float rs = row_rstd(ssq, row);
;                 bf16_t* rowp = O + (size_t)row * ldc + col0;
; #pragma unroll
;                 for (int bj = 0; bj < 2; ++bj) { f32x4 v0 = acc[ai][bj][m][0] * rs, v1 = acc[ai][bj][m][1] * rs;
;                     if (ACT == 1) {
; #pragma unroll
;                         for (int j = 0; j < 4; ++j) { const float a = fmaxf(v0[j], 0.f), b = fmaxf(v1[j], 0.f); v0[j] = a * a; v1[j] = b * b; } }
;                     *(u32x4*)(rowp + bj * 128) = pack8(v0, v1); }
;             }
	v_mov_b32_e32 v160, v188
	v_mov_b32_e32 v161, v189
	v_mov_b32_e32 v162, v190
	v_mov_b32_e32 v163, v191
	v_mov_b32_e32 v170, v192
	v_mov_b32_e32 v171, v193
	v_mov_b32_e32 v172, v194
	v_mov_b32_e32 v173, v195
	v_mov_b32_e32 v174, v196
	v_mov_b32_e32 v175, v197
	v_mov_b32_e32 v176, v198
	v_mov_b32_e32 v177, v199
	v_mov_b32_e32 v178, v200
	v_mov_b32_e32 v179, v201
	v_mov_b32_e32 v180, v202
	v_mov_b32_e32 v181, v203
	v_add_u32_e32 v187, 0xc00, v186
	global_load_dwordx4 v[188:191], v187, s[18:19]
	v_add_u32_e32 v187, 0xc10, v186
	global_load_dwordx4 v[192:195], v187, s[18:19]
	v_add_u32_e32 v187, 0xc20, v186
	global_load_dwordx4 v[196:199], v187, s[18:19]
	v_add_u32_e32 v187, 0xc30, v186
	global_load_dwordx4 v[200:203], v187, s[18:19]
	v_mov_b32_e32 v184, v161
	v_mov_b32_e32 v185, v162
	v_mov_b32_e32 v161, v163
	v_mov_b32_e32 v162, v171
	v_mov_b32_e32 v163, v172
	v_mov_b32_e32 v171, v173
	v_pk_add_f32 v[160:161], v[184:185], v[160:161]
	v_pk_add_f32 v[162:163], v[162:163], v[170:171]
	v_pk_add_f32 v[160:161], v[160:161], v[160:161] op_sel:[0,1] op_sel_hi:[1,0]
	v_pk_add_f32 v[162:163], v[162:163], v[162:163] op_sel:[0,1] op_sel_hi:[1,0]
	v_add_f32_e32 v172, v174, v175
	v_add_f32_e32 v174, v176, v177
	v_mov_b32_e32 v173, v180
	v_mov_b32_e32 v175, v181
	v_mov_b32_e32 v161, v178
	v_mov_b32_e32 v163, v179
	v_pk_add_f32 v[170:171], v[172:173], v[174:175]
	v_pk_add_f32 v[160:161], v[160:161], v[162:163]
	v_lshlrev_b64 v[162:163], 6, v[182:183]
	v_pk_add_f32 v[160:161], v[160:161], v[170:171]
	v_lshl_add_u64 v[162:163], s[18:19], 0, v[162:163]
	v_add_f32_e32 v151, v160, v161
	v_fmamk_f32 v151, v151, 0x3a800000, v158
	v_mul_f32_e32 v159, 0x4b800000, v151
	v_cmp_gt_f32_e32 vcc, s65, v151
	v_lshl_add_u64 v[160:161], v[164:165], 0, v[148:149]
	s_nop 0
	v_cndmask_b32_e32 v151, v151, v159, vcc
	v_rsq_f32_e32 v151, v151
	s_nop 0
	v_mul_f32_e32 v159, 0x45800000, v151
	v_cndmask_b32_e32 v164, v151, v159, vcc
	v_pk_mul_f32 v[126:127], v[126:127], v[164:165] op_sel_hi:[1,0]
	v_pk_mul_f32 v[124:125], v[124:125], v[164:165] op_sel_hi:[1,0]
	v_pk_mul_f32 v[122:123], v[122:123], v[164:165] op_sel_hi:[1,0]
	v_pk_mul_f32 v[120:121], v[120:121], v[164:165] op_sel_hi:[1,0]
	v_pk_mul_f32 v[118:119], v[118:119], v[164:165] op_sel_hi:[1,0]
	v_pk_mul_f32 v[116:117], v[116:117], v[164:165] op_sel_hi:[1,0]
	v_pk_mul_f32 v[170:171], v[114:115], v[164:165] op_sel_hi:[1,0]
	v_pk_mul_f32 v[164:165], v[112:113], v[164:165] op_sel_hi:[1,0]
	v_cvt_pk_bf16_f32 v112, v124, v125
	v_cvt_pk_bf16_f32 v113, v126, v127
	v_cvt_pk_bf16_f32 v114, v120, v121
	v_cvt_pk_bf16_f32 v115, v122, v123
	global_store_dwordx4 v[160:161], v[112:115], off sc1
	s_nop 1
	v_cvt_pk_bf16_f32 v112, v116, v117
	v_cvt_pk_bf16_f32 v113, v118, v119
	v_cvt_pk_bf16_f32 v114, v164, v165
	v_cvt_pk_bf16_f32 v115, v170, v171
	global_store_dwordx4 v[160:161], v[112:115], off offset:256 sc1
	s_nop 0
	v_or_b32_e32 v160, 32, v150
	v_mad_i64_i32 v[162:163], s[6:7], v182, s66, v[146:147]
	v_ashrrev_i32_e32 v161, 31, v160
	s_waitcnt vmcnt(10)
	v_mov_b32_e32 v112, v204
	v_mov_b32_e32 v113, v205
	v_mov_b32_e32 v114, v206
	v_mov_b32_e32 v115, v207
	v_mov_b32_e32 v116, v208
	v_mov_b32_e32 v117, v209
	v_mov_b32_e32 v118, v210
	v_mov_b32_e32 v119, v211
	v_mov_b32_e32 v120, v212
	v_mov_b32_e32 v121, v213
	v_mov_b32_e32 v122, v214
	v_mov_b32_e32 v123, v215
	v_mov_b32_e32 v124, v216
	v_mov_b32_e32 v125, v217
	v_mov_b32_e32 v126, v218
	v_mov_b32_e32 v127, v219
	v_add_u32_e32 v187, 0x2000, v186
	global_load_dwordx4 v[204:207], v187, s[18:19]
	v_add_u32_e32 v187, 0x2010, v186
	global_load_dwordx4 v[208:211], v187, s[18:19]
	v_add_u32_e32 v187, 0x2020, v186
	global_load_dwordx4 v[212:215], v187, s[18:19]
	v_add_u32_e32 v187, 0x2030, v186
	global_load_dwordx4 v[216:219], v187, s[18:19]
	v_mov_b32_e32 v164, v113
	v_mov_b32_e32 v165, v114
	v_mov_b32_e32 v113, v115
	v_mov_b32_e32 v114, v117
	v_mov_b32_e32 v115, v118
	v_mov_b32_e32 v117, v119
	v_pk_add_f32 v[112:113], v[164:165], v[112:113]
	v_pk_add_f32 v[114:115], v[114:115], v[116:117]
	v_pk_add_f32 v[112:113], v[112:113], v[112:113] op_sel:[0,1] op_sel_hi:[1,0]
	v_pk_add_f32 v[114:115], v[114:115], v[114:115] op_sel:[0,1] op_sel_hi:[1,0]
	v_add_f32_e32 v118, v120, v121
	v_add_f32_e32 v120, v122, v123
	v_mov_b32_e32 v119, v126
	v_mov_b32_e32 v121, v127
	v_mov_b32_e32 v113, v124
	v_mov_b32_e32 v115, v125
	v_pk_add_f32 v[116:117], v[118:119], v[120:121]
	v_pk_add_f32 v[112:113], v[112:113], v[114:115]
	v_lshlrev_b64 v[114:115], 6, v[160:161]
	v_pk_add_f32 v[112:113], v[112:113], v[116:117]
	v_lshl_add_u64 v[114:115], s[18:19], 0, v[114:115]
	v_add_f32_e32 v112, v112, v113
	v_fmamk_f32 v112, v112, 0x3a800000, v158
	v_mul_f32_e32 v113, 0x4b800000, v112
	v_cmp_gt_f32_e32 vcc, s65, v112
	s_nop 1
	v_cndmask_b32_e32 v112, v112, v113, vcc
	v_rsq_f32_e32 v116, v112
	v_lshl_add_u64 v[112:113], v[162:163], 0, v[148:149]
	v_mul_f32_e32 v117, 0x45800000, v116
	v_cndmask_b32_e32 v116, v116, v117, vcc
	v_pk_mul_f32 v[110:111], v[110:111], v[116:117] op_sel_hi:[1,0]
	v_pk_mul_f32 v[108:109], v[108:109], v[116:117] op_sel_hi:[1,0]
	v_pk_mul_f32 v[106:107], v[106:107], v[116:117] op_sel_hi:[1,0]
	v_pk_mul_f32 v[104:105], v[104:105], v[116:117] op_sel_hi:[1,0]
	v_pk_mul_f32 v[102:103], v[102:103], v[116:117] op_sel_hi:[1,0]
	v_pk_mul_f32 v[100:101], v[100:101], v[116:117] op_sel_hi:[1,0]
	v_pk_mul_f32 v[118:119], v[98:99], v[116:117] op_sel_hi:[1,0]
	v_pk_mul_f32 v[116:117], v[96:97], v[116:117] op_sel_hi:[1,0]
	v_cvt_pk_bf16_f32 v96, v108, v109
	v_cvt_pk_bf16_f32 v97, v110, v111
	v_cvt_pk_bf16_f32 v98, v104, v105
	v_cvt_pk_bf16_f32 v99, v106, v107
	global_store_dwordx4 v[112:113], v[96:99], off sc1
	s_nop 1
	v_cvt_pk_bf16_f32 v96, v100, v101
	v_cvt_pk_bf16_f32 v97, v102, v103
	v_cvt_pk_bf16_f32 v98, v116, v117
	v_cvt_pk_bf16_f32 v99, v118, v119
	global_store_dwordx4 v[112:113], v[96:99], off offset:256 sc1
	s_nop 0
	v_or_b32_e32 v112, 48, v150
	v_mad_i64_i32 v[114:115], s[6:7], v160, s66, v[146:147]
	v_ashrrev_i32_e32 v113, 31, v112
	s_waitcnt vmcnt(12)
; __device__ __forceinline__ u32x4 pack8(const f32x4 v0, const f32x4 v1) { u32x4 w; w.x = pk2(v0[0], v0[1]); w.y = pk2(v0[2], v0[3]); w.z = pk2(v1[0], v1[1]); w.w = pk2(v1[2], v1[3]); return w; }
; __device__ __forceinline__ float row_rstd(const float* ssq, int row) {
;     const f32x4* p = (const f32x4*)(ssq + (size_t)row * 16);
;     const f32x4 a = p[0], b = p[1], c = p[2], d = p[3];
;     const float s = ((a[0] + a[1]) + (a[2] + a[3])) + ((b[0] + b[1]) + (b[2] + b[3])) + ((c[0] + c[1]) + (c[2] + c[3])) + ((d[0] + d[1]) + (d[2] + d[3]));
;     return rsqrtf(s * (1.0f / 1024.0f) + 1e-6f);
;     __device__ __forceinline__ void operator()(const f32x4 (&acc)[2][2][4][2], const Unit& u, int wr, int wc, int fr, int fq) const {
;         const int row0 = u.pm * 256 + wr * 64 + fr, col0 = u.pn * 256 + wc * 32 + 8 * fq;
; #pragma unroll
;         for (int ai = 0; ai < 2; ++ai)
; #pragma unroll
;             for (int m = 0; m < 4; ++m) {
;                 const int row = row0 + ai * 128 + m * 16; const float rs = row_rstd(ssq, row);
;                 bf16_t* rowp = O + (size_t)row * ldc + col0;
; #pragma unroll
;                 for (int bj = 0; bj < 2; ++bj) { f32x4 v0 = acc[ai][bj][m][0] * rs, v1 = acc[ai][bj][m][1] * rs;
;                     if (ACT == 1) {
; #pragma unroll
;                         for (int j = 0; j < 4; ++j) { const float a = fmaxf(v0[j], 0.f), b = fmaxf(v1[j], 0.f); v0[j] = a * a; v1[j] = b * b; } }
;                     *(u32x4*)(rowp + bj * 128) = pack8(v0, v1); }
;             }
	v_mov_b32_e32 v96, v220
	v_mov_b32_e32 v97, v221
	v_mov_b32_e32 v98, v222
	v_mov_b32_e32 v99, v223
	v_mov_b32_e32 v100, v232
	v_mov_b32_e32 v101, v233
	v_mov_b32_e32 v102, v234
	v_mov_b32_e32 v103, v235
	v_mov_b32_e32 v104, v236
	v_mov_b32_e32 v105, v237
	v_mov_b32_e32 v106, v238
	v_mov_b32_e32 v107, v239
	v_mov_b32_e32 v108, v240
	v_mov_b32_e32 v109, v241
	v_mov_b32_e32 v110, v242
	v_mov_b32_e32 v111, v243
	v_add_u32_e32 v187, 0x2400, v186
	global_load_dwordx4 v[220:223], v187, s[18:19]
	v_add_u32_e32 v187, 0x2410, v186
	global_load_dwordx4 v[232:235], v187, s[18:19]
	v_add_u32_e32 v187, 0x2420, v186
	global_load_dwordx4 v[236:239], v187, s[18:19]
	v_add_u32_e32 v187, 0x2430, v186
	global_load_dwordx4 v[240:243], v187, s[18:19]
	v_mov_b32_e32 v116, v97
	v_mov_b32_e32 v117, v98
	v_mov_b32_e32 v97, v99
	v_mov_b32_e32 v98, v101
	v_mov_b32_e32 v99, v102
	v_mov_b32_e32 v101, v103
	v_pk_add_f32 v[96:97], v[116:117], v[96:97]
	v_pk_add_f32 v[98:99], v[98:99], v[100:101]
	v_pk_add_f32 v[96:97], v[96:97], v[96:97] op_sel:[0,1] op_sel_hi:[1,0]
	v_pk_add_f32 v[98:99], v[98:99], v[98:99] op_sel:[0,1] op_sel_hi:[1,0]
	v_add_f32_e32 v102, v104, v105
	v_add_f32_e32 v104, v106, v107
	v_mov_b32_e32 v103, v110
	v_mov_b32_e32 v105, v111
	v_mov_b32_e32 v97, v108
	v_mov_b32_e32 v99, v109
	v_pk_add_f32 v[100:101], v[102:103], v[104:105]
	v_pk_add_f32 v[96:97], v[96:97], v[98:99]
	v_lshlrev_b64 v[98:99], 6, v[112:113]
	v_pk_add_f32 v[96:97], v[96:97], v[100:101]
	v_lshl_add_u64 v[98:99], s[18:19], 0, v[98:99]
	v_add_f32_e32 v96, v96, v97
	v_fmamk_f32 v96, v96, 0x3a800000, v158
	v_mul_f32_e32 v97, 0x4b800000, v96
	v_cmp_gt_f32_e32 vcc, s65, v96
	s_nop 1
	v_cndmask_b32_e32 v96, v96, v97, vcc
	v_rsq_f32_e32 v100, v96
	v_lshl_add_u64 v[96:97], v[114:115], 0, v[148:149]
	v_mul_f32_e32 v101, 0x45800000, v100
	v_cndmask_b32_e32 v100, v100, v101, vcc
	v_pk_mul_f32 v[94:95], v[94:95], v[100:101] op_sel_hi:[1,0]
	v_pk_mul_f32 v[92:93], v[92:93], v[100:101] op_sel_hi:[1,0]
	v_pk_mul_f32 v[90:91], v[90:91], v[100:101] op_sel_hi:[1,0]
	v_pk_mul_f32 v[88:89], v[88:89], v[100:101] op_sel_hi:[1,0]
	v_pk_mul_f32 v[86:87], v[86:87], v[100:101] op_sel_hi:[1,0]
	v_pk_mul_f32 v[84:85], v[84:85], v[100:101] op_sel_hi:[1,0]
	v_pk_mul_f32 v[102:103], v[82:83], v[100:101] op_sel_hi:[1,0]
	v_pk_mul_f32 v[100:101], v[80:81], v[100:101] op_sel_hi:[1,0]
	v_cvt_pk_bf16_f32 v80, v92, v93
	v_cvt_pk_bf16_f32 v81, v94, v95
	v_cvt_pk_bf16_f32 v82, v88, v89
	v_cvt_pk_bf16_f32 v83, v90, v91
	global_store_dwordx4 v[96:97], v[80:83], off sc1
	s_nop 1
	v_cvt_pk_bf16_f32 v80, v84, v85
	v_cvt_pk_bf16_f32 v81, v86, v87
	v_cvt_pk_bf16_f32 v82, v100, v101
	v_cvt_pk_bf16_f32 v83, v102, v103
	global_store_dwordx4 v[96:97], v[80:83], off offset:256 sc1
	s_nop 0
	v_add_u32_e32 v96, 0x80, v150
	v_mad_i64_i32 v[98:99], s[6:7], v112, s66, v[146:147]
	v_ashrrev_i32_e32 v97, 31, v96
	s_waitcnt vmcnt(14)
	v_mov_b32_e32 v80, v188
	v_mov_b32_e32 v81, v189
	v_mov_b32_e32 v82, v190
	v_mov_b32_e32 v83, v191
	v_mov_b32_e32 v84, v192
	v_mov_b32_e32 v85, v193
	v_mov_b32_e32 v86, v194
	v_mov_b32_e32 v87, v195
	v_mov_b32_e32 v88, v196
	v_mov_b32_e32 v89, v197
	v_mov_b32_e32 v90, v198
	v_mov_b32_e32 v91, v199
	v_mov_b32_e32 v92, v200
	v_mov_b32_e32 v93, v201
	v_mov_b32_e32 v94, v202
	v_mov_b32_e32 v95, v203
	v_add_u32_e32 v187, 0x2800, v186
	global_load_dwordx4 v[188:191], v187, s[18:19]
	v_add_u32_e32 v187, 0x2810, v186
	global_load_dwordx4 v[192:195], v187, s[18:19]
	v_add_u32_e32 v187, 0x2820, v186
	global_load_dwordx4 v[196:199], v187, s[18:19]
	v_add_u32_e32 v187, 0x2830, v186
	global_load_dwordx4 v[200:203], v187, s[18:19]
	v_mov_b32_e32 v100, v81
	v_mov_b32_e32 v101, v82
	v_mov_b32_e32 v81, v83
	v_mov_b32_e32 v82, v85
	v_mov_b32_e32 v83, v86
	v_mov_b32_e32 v85, v87
	v_pk_add_f32 v[80:81], v[100:101], v[80:81]
	v_pk_add_f32 v[82:83], v[82:83], v[84:85]
	v_pk_add_f32 v[80:81], v[80:81], v[80:81] op_sel:[0,1] op_sel_hi:[1,0]
	v_pk_add_f32 v[82:83], v[82:83], v[82:83] op_sel:[0,1] op_sel_hi:[1,0]
	v_add_f32_e32 v86, v88, v89
	v_add_f32_e32 v88, v90, v91
	v_mov_b32_e32 v87, v94
	v_mov_b32_e32 v89, v95
	v_mov_b32_e32 v81, v92
	v_mov_b32_e32 v83, v93
	v_pk_add_f32 v[84:85], v[86:87], v[88:89]
	v_pk_add_f32 v[80:81], v[80:81], v[82:83]
	v_lshlrev_b64 v[82:83], 6, v[96:97]
	v_pk_add_f32 v[80:81], v[80:81], v[84:85]
	v_lshl_add_u64 v[82:83], s[18:19], 0, v[82:83]
	v_add_f32_e32 v80, v80, v81
	v_fmamk_f32 v80, v80, 0x3a800000, v158
	v_mul_f32_e32 v81, 0x4b800000, v80
	v_cmp_gt_f32_e32 vcc, s65, v80
	s_nop 1
	v_cndmask_b32_e32 v80, v80, v81, vcc
	v_rsq_f32_e32 v84, v80
	v_lshl_add_u64 v[80:81], v[98:99], 0, v[148:149]
	v_mul_f32_e32 v85, 0x45800000, v84
	v_cndmask_b32_e32 v84, v84, v85, vcc
	v_pk_mul_f32 v[78:79], v[78:79], v[84:85] op_sel_hi:[1,0]
	v_pk_mul_f32 v[76:77], v[76:77], v[84:85] op_sel_hi:[1,0]
	v_pk_mul_f32 v[74:75], v[74:75], v[84:85] op_sel_hi:[1,0]
	v_pk_mul_f32 v[72:73], v[72:73], v[84:85] op_sel_hi:[1,0]
	v_pk_mul_f32 v[70:71], v[70:71], v[84:85] op_sel_hi:[1,0]
	v_pk_mul_f32 v[68:69], v[68:69], v[84:85] op_sel_hi:[1,0]
	v_pk_mul_f32 v[86:87], v[66:67], v[84:85] op_sel_hi:[1,0]
	v_pk_mul_f32 v[84:85], v[64:65], v[84:85] op_sel_hi:[1,0]
	v_cvt_pk_bf16_f32 v64, v76, v77
	v_cvt_pk_bf16_f32 v65, v78, v79
	v_cvt_pk_bf16_f32 v66, v72, v73
	v_cvt_pk_bf16_f32 v67, v74, v75
	global_store_dwordx4 v[80:81], v[64:67], off sc1
	s_nop 1
	v_cvt_pk_bf16_f32 v64, v68, v69
	v_cvt_pk_bf16_f32 v65, v70, v71
	v_cvt_pk_bf16_f32 v66, v84, v85
	v_cvt_pk_bf16_f32 v67, v86, v87
	global_store_dwordx4 v[80:81], v[64:67], off offset:256 sc1
	s_nop 0
	v_add_u32_e32 v80, 0x90, v150
	v_mad_i64_i32 v[82:83], s[6:7], v96, s66, v[146:147]
	v_ashrrev_i32_e32 v81, 31, v80
	s_waitcnt vmcnt(14)
; __device__ __forceinline__ u32x4 pack8(const f32x4 v0, const f32x4 v1) { u32x4 w; w.x = pk2(v0[0], v0[1]); w.y = pk2(v0[2], v0[3]); w.z = pk2(v1[0], v1[1]); w.w = pk2(v1[2], v1[3]); return w; }
; __device__ __forceinline__ float row_rstd(const float* ssq, int row) {
;     const f32x4* p = (const f32x4*)(ssq + (size_t)row * 16);
;     const f32x4 a = p[0], b = p[1], c = p[2], d = p[3];
;     const float s = ((a[0] + a[1]) + (a[2] + a[3])) + ((b[0] + b[1]) + (b[2] + b[3])) + ((c[0] + c[1]) + (c[2] + c[3])) + ((d[0] + d[1]) + (d[2] + d[3]));
;     return rsqrtf(s * (1.0f / 1024.0f) + 1e-6f);
;     __device__ __forceinline__ void operator()(const f32x4 (&acc)[2][2][4][2], const Unit& u, int wr, int wc, int fr, int fq) const {
;         const int row0 = u.pm * 256 + wr * 64 + fr, col0 = u.pn * 256 + wc * 32 + 8 * fq;
; #pragma unroll
;         for (int ai = 0; ai < 2; ++ai)
; #pragma unroll
;             for (int m = 0; m < 4; ++m) {
;                 const int row = row0 + ai * 128 + m * 16; const float rs = row_rstd(ssq, row);
;                 bf16_t* rowp = O + (size_t)row * ldc + col0;
; #pragma unroll
;                 for (int bj = 0; bj < 2; ++bj) { f32x4 v0 = acc[ai][bj][m][0] * rs, v1 = acc[ai][bj][m][1] * rs;
;                     if (ACT == 1) {
; #pragma unroll
;                         for (int j = 0; j < 4; ++j) { const float a = fmaxf(v0[j], 0.f), b = fmaxf(v1[j], 0.f); v0[j] = a * a; v1[j] = b * b; } }
;                     *(u32x4*)(rowp + bj * 128) = pack8(v0, v1); }
;             }
	v_mov_b32_e32 v64, v204
	v_mov_b32_e32 v65, v205
	v_mov_b32_e32 v66, v206
	v_mov_b32_e32 v67, v207
	v_mov_b32_e32 v68, v208
	v_mov_b32_e32 v69, v209
	v_mov_b32_e32 v70, v210
	v_mov_b32_e32 v71, v211
	v_mov_b32_e32 v72, v212
	v_mov_b32_e32 v73, v213
	v_mov_b32_e32 v74, v214
	v_mov_b32_e32 v75, v215
	v_mov_b32_e32 v76, v216
	v_mov_b32_e32 v77, v217
	v_mov_b32_e32 v78, v218
	v_mov_b32_e32 v79, v219
	v_add_u32_e32 v187, 0x2c00, v186
	global_load_dwordx4 v[204:207], v187, s[18:19]
	v_add_u32_e32 v187, 0x2c10, v186
	global_load_dwordx4 v[208:211], v187, s[18:19]
	v_add_u32_e32 v187, 0x2c20, v186
	global_load_dwordx4 v[212:215], v187, s[18:19]
	v_add_u32_e32 v187, 0x2c30, v186
	global_load_dwordx4 v[216:219], v187, s[18:19]
	v_mov_b32_e32 v84, v65
	v_mov_b32_e32 v85, v66
	v_mov_b32_e32 v65, v67
	v_mov_b32_e32 v66, v69
	v_mov_b32_e32 v67, v70
	v_mov_b32_e32 v69, v71
	v_pk_add_f32 v[64:65], v[84:85], v[64:65]
	v_pk_add_f32 v[66:67], v[66:67], v[68:69]
	v_pk_add_f32 v[64:65], v[64:65], v[64:65] op_sel:[0,1] op_sel_hi:[1,0]
	v_pk_add_f32 v[66:67], v[66:67], v[66:67] op_sel:[0,1] op_sel_hi:[1,0]
	v_add_f32_e32 v70, v72, v73
	v_add_f32_e32 v72, v74, v75
	v_mov_b32_e32 v71, v78
	v_mov_b32_e32 v73, v79
	v_mov_b32_e32 v65, v76
	v_mov_b32_e32 v67, v77
	v_pk_add_f32 v[68:69], v[70:71], v[72:73]
	v_pk_add_f32 v[64:65], v[64:65], v[66:67]
	v_lshlrev_b64 v[66:67], 6, v[80:81]
	v_pk_add_f32 v[64:65], v[64:65], v[68:69]
	v_lshl_add_u64 v[66:67], s[18:19], 0, v[66:67]
	v_add_f32_e32 v64, v64, v65
	v_fmamk_f32 v64, v64, 0x3a800000, v158
	v_mul_f32_e32 v65, 0x4b800000, v64
	v_cmp_gt_f32_e32 vcc, s65, v64
	s_nop 1
	v_cndmask_b32_e32 v64, v64, v65, vcc
	v_rsq_f32_e32 v68, v64
	v_lshl_add_u64 v[64:65], v[82:83], 0, v[148:149]
	v_mul_f32_e32 v69, 0x45800000, v68
	v_cndmask_b32_e32 v68, v68, v69, vcc
	v_pk_mul_f32 v[62:63], v[62:63], v[68:69] op_sel_hi:[1,0]
	v_pk_mul_f32 v[60:61], v[60:61], v[68:69] op_sel_hi:[1,0]
	v_pk_mul_f32 v[58:59], v[58:59], v[68:69] op_sel_hi:[1,0]
	v_pk_mul_f32 v[56:57], v[56:57], v[68:69] op_sel_hi:[1,0]
	v_pk_mul_f32 v[54:55], v[54:55], v[68:69] op_sel_hi:[1,0]
	v_pk_mul_f32 v[52:53], v[52:53], v[68:69] op_sel_hi:[1,0]
	v_pk_mul_f32 v[70:71], v[50:51], v[68:69] op_sel_hi:[1,0]
	v_pk_mul_f32 v[68:69], v[48:49], v[68:69] op_sel_hi:[1,0]
	v_cvt_pk_bf16_f32 v48, v60, v61
	v_cvt_pk_bf16_f32 v49, v62, v63
	v_cvt_pk_bf16_f32 v50, v56, v57
	v_cvt_pk_bf16_f32 v51, v58, v59
	global_store_dwordx4 v[64:65], v[48:51], off sc1
	s_nop 1
	v_cvt_pk_bf16_f32 v48, v52, v53
	v_cvt_pk_bf16_f32 v49, v54, v55
	v_cvt_pk_bf16_f32 v50, v68, v69
	v_cvt_pk_bf16_f32 v51, v70, v71
	global_store_dwordx4 v[64:65], v[48:51], off offset:256 sc1
	s_nop 0
	v_add_u32_e32 v64, 0xa0, v150
	v_mad_i64_i32 v[66:67], s[6:7], v80, s66, v[146:147]
	v_ashrrev_i32_e32 v65, 31, v64
	s_waitcnt vmcnt(14)
	v_mov_b32_e32 v48, v220
	v_mov_b32_e32 v49, v221
	v_mov_b32_e32 v50, v222
	v_mov_b32_e32 v51, v223
	v_mov_b32_e32 v52, v232
	v_mov_b32_e32 v53, v233
	v_mov_b32_e32 v54, v234
	v_mov_b32_e32 v55, v235
	v_mov_b32_e32 v56, v236
	v_mov_b32_e32 v57, v237
	v_mov_b32_e32 v58, v238
	v_mov_b32_e32 v59, v239
	v_mov_b32_e32 v60, v240
	v_mov_b32_e32 v61, v241
	v_mov_b32_e32 v62, v242
	v_mov_b32_e32 v63, v243
	v_mov_b32_e32 v68, v49
	v_mov_b32_e32 v69, v50
	v_mov_b32_e32 v49, v51
	v_mov_b32_e32 v50, v53
	v_mov_b32_e32 v51, v54
	v_mov_b32_e32 v53, v55
	v_pk_add_f32 v[48:49], v[68:69], v[48:49]
	v_pk_add_f32 v[50:51], v[50:51], v[52:53]
	v_pk_add_f32 v[48:49], v[48:49], v[48:49] op_sel:[0,1] op_sel_hi:[1,0]
	v_pk_add_f32 v[50:51], v[50:51], v[50:51] op_sel:[0,1] op_sel_hi:[1,0]
	v_add_f32_e32 v54, v56, v57
	v_add_f32_e32 v56, v58, v59
	v_mov_b32_e32 v55, v62
	v_mov_b32_e32 v57, v63
	v_mov_b32_e32 v49, v60
	v_mov_b32_e32 v51, v61
	v_pk_add_f32 v[52:53], v[54:55], v[56:57]
	v_pk_add_f32 v[48:49], v[48:49], v[50:51]
	v_lshlrev_b64 v[50:51], 6, v[64:65]
	v_pk_add_f32 v[48:49], v[48:49], v[52:53]
	v_lshl_add_u64 v[50:51], s[18:19], 0, v[50:51]
	v_add_f32_e32 v48, v48, v49
	v_fmamk_f32 v48, v48, 0x3a800000, v158
	v_mul_f32_e32 v49, 0x4b800000, v48
	v_cmp_gt_f32_e32 vcc, s65, v48
	s_nop 1
	v_cndmask_b32_e32 v48, v48, v49, vcc
	v_rsq_f32_e32 v52, v48
	v_lshl_add_u64 v[48:49], v[66:67], 0, v[148:149]
	v_mul_f32_e32 v53, 0x45800000, v52
	v_cndmask_b32_e32 v52, v52, v53, vcc
	v_pk_mul_f32 v[46:47], v[46:47], v[52:53] op_sel_hi:[1,0]
	v_pk_mul_f32 v[44:45], v[44:45], v[52:53] op_sel_hi:[1,0]
	v_pk_mul_f32 v[42:43], v[42:43], v[52:53] op_sel_hi:[1,0]
	v_pk_mul_f32 v[40:41], v[40:41], v[52:53] op_sel_hi:[1,0]
	v_pk_mul_f32 v[38:39], v[38:39], v[52:53] op_sel_hi:[1,0]
	v_pk_mul_f32 v[36:37], v[36:37], v[52:53] op_sel_hi:[1,0]
	v_pk_mul_f32 v[54:55], v[34:35], v[52:53] op_sel_hi:[1,0]
	v_pk_mul_f32 v[52:53], v[32:33], v[52:53] op_sel_hi:[1,0]
	v_cvt_pk_bf16_f32 v32, v44, v45
	v_cvt_pk_bf16_f32 v33, v46, v47
	v_cvt_pk_bf16_f32 v34, v40, v41
	v_cvt_pk_bf16_f32 v35, v42, v43
	global_store_dwordx4 v[48:49], v[32:35], off sc1
	s_nop 1
	v_cvt_pk_bf16_f32 v32, v36, v37
	v_cvt_pk_bf16_f32 v33, v38, v39
	v_cvt_pk_bf16_f32 v34, v52, v53
	v_cvt_pk_bf16_f32 v35, v54, v55
	global_store_dwordx4 v[48:49], v[32:35], off offset:256 sc1
	s_nop 0
	v_add_u32_e32 v48, 0xb0, v150
	v_mad_i64_i32 v[50:51], s[6:7], v64, s66, v[146:147]
	v_ashrrev_i32_e32 v49, 31, v48
	s_mov_b32 s6, s22
	s_waitcnt vmcnt(10)
; __device__ __forceinline__ u32x4 pack8(const f32x4 v0, const f32x4 v1) { u32x4 w; w.x = pk2(v0[0], v0[1]); w.y = pk2(v0[2], v0[3]); w.z = pk2(v1[0], v1[1]); w.w = pk2(v1[2], v1[3]); return w; }
;     __device__ __forceinline__ void operator()(const f32x4 (&acc)[2][2][4][2], const Unit& u, int wr, int wc, int fr, int fq) const {
;         const int row0 = u.pm * 256 + wr * 64 + fr, col0 = u.pn * 256 + wc * 32 + 8 * fq;
; #pragma unroll
;         for (int ai = 0; ai < 2; ++ai)
; #pragma unroll
;             for (int m = 0; m < 4; ++m) {
;                 const int row = row0 + ai * 128 + m * 16; const float rs = row_rstd(ssq, row);
;                 bf16_t* rowp = O + (size_t)row * ldc + col0;
; #pragma unroll
;                 for (int bj = 0; bj < 2; ++bj) { f32x4 v0 = acc[ai][bj][m][0] * rs, v1 = acc[ai][bj][m][1] * rs;
;                     if (ACT == 1) {
; #pragma unroll
;                         for (int j = 0; j < 4; ++j) { const float a = fmaxf(v0[j], 0.f), b = fmaxf(v1[j], 0.f); v0[j] = a * a; v1[j] = b * b; } }
;                     *(u32x4*)(rowp + bj * 128) = pack8(v0, v1); }
;             }
	v_mov_b32_e32 v32, v188
	v_mov_b32_e32 v33, v189
	v_mov_b32_e32 v34, v190
	v_mov_b32_e32 v35, v191
	v_mov_b32_e32 v36, v192
	v_mov_b32_e32 v37, v193
	v_mov_b32_e32 v38, v194
	v_mov_b32_e32 v39, v195
	v_mov_b32_e32 v40, v196
	v_mov_b32_e32 v41, v197
	v_mov_b32_e32 v42, v198
	v_mov_b32_e32 v43, v199
	v_mov_b32_e32 v44, v200
	v_mov_b32_e32 v45, v201
	v_mov_b32_e32 v46, v202
	v_mov_b32_e32 v47, v203
	v_mov_b32_e32 v52, v33
	v_mov_b32_e32 v53, v34
	v_mov_b32_e32 v33, v35
	v_mov_b32_e32 v34, v37
	v_mov_b32_e32 v35, v38
	v_mov_b32_e32 v37, v39
	v_pk_add_f32 v[32:33], v[52:53], v[32:33]
	v_pk_add_f32 v[34:35], v[34:35], v[36:37]
	v_pk_add_f32 v[32:33], v[32:33], v[32:33] op_sel:[0,1] op_sel_hi:[1,0]
	v_pk_add_f32 v[34:35], v[34:35], v[34:35] op_sel:[0,1] op_sel_hi:[1,0]
	v_add_f32_e32 v38, v40, v41
	v_add_f32_e32 v40, v42, v43
	v_mov_b32_e32 v39, v46
	v_mov_b32_e32 v41, v47
	v_mov_b32_e32 v33, v44
	v_mov_b32_e32 v35, v45
	v_pk_add_f32 v[36:37], v[38:39], v[40:41]
	v_pk_add_f32 v[32:33], v[32:33], v[34:35]
	v_lshlrev_b64 v[34:35], 6, v[48:49]
	v_pk_add_f32 v[32:33], v[32:33], v[36:37]
	v_lshl_add_u64 v[34:35], s[18:19], 0, v[34:35]
	v_add_f32_e32 v32, v32, v33
	v_fmamk_f32 v32, v32, 0x3a800000, v158
	v_mul_f32_e32 v33, 0x4b800000, v32
	v_cmp_gt_f32_e32 vcc, s65, v32
	s_nop 1
	v_cndmask_b32_e32 v32, v32, v33, vcc
	v_rsq_f32_e32 v36, v32
	v_lshl_add_u64 v[32:33], v[50:51], 0, v[148:149]
	v_mul_f32_e32 v37, 0x45800000, v36
	v_cndmask_b32_e32 v36, v36, v37, vcc
	v_pk_mul_f32 v[30:31], v[30:31], v[36:37] op_sel_hi:[1,0]
	v_pk_mul_f32 v[28:29], v[28:29], v[36:37] op_sel_hi:[1,0]
	v_pk_mul_f32 v[26:27], v[26:27], v[36:37] op_sel_hi:[1,0]
	v_pk_mul_f32 v[24:25], v[24:25], v[36:37] op_sel_hi:[1,0]
	v_pk_mul_f32 v[22:23], v[22:23], v[36:37] op_sel_hi:[1,0]
	v_pk_mul_f32 v[20:21], v[20:21], v[36:37] op_sel_hi:[1,0]
	v_pk_mul_f32 v[38:39], v[18:19], v[36:37] op_sel_hi:[1,0]
	v_pk_mul_f32 v[36:37], v[16:17], v[36:37] op_sel_hi:[1,0]
	v_cvt_pk_bf16_f32 v16, v28, v29
	v_cvt_pk_bf16_f32 v17, v30, v31
	v_cvt_pk_bf16_f32 v18, v24, v25
	v_cvt_pk_bf16_f32 v19, v26, v27
	global_store_dwordx4 v[32:33], v[16:19], off sc1
	s_and_b64 vcc, exec, s[10:11]
	s_nop 0
	v_cvt_pk_bf16_f32 v16, v20, v21
	v_cvt_pk_bf16_f32 v17, v22, v23
	v_cvt_pk_bf16_f32 v18, v36, v37
	v_cvt_pk_bf16_f32 v19, v38, v39
	global_store_dwordx4 v[32:33], v[16:19], off offset:256 sc1
	s_nop 0
	s_waitcnt vmcnt(6)
	v_mov_b32_e32 v16, v204
	v_mov_b32_e32 v17, v205
	v_mov_b32_e32 v18, v206
	v_mov_b32_e32 v19, v207
	v_mov_b32_e32 v20, v208
	v_mov_b32_e32 v21, v209
	v_mov_b32_e32 v22, v210
	v_mov_b32_e32 v23, v211
	v_mov_b32_e32 v24, v212
	v_mov_b32_e32 v25, v213
	v_mov_b32_e32 v26, v214
	v_mov_b32_e32 v27, v215
	v_mov_b32_e32 v28, v216
	v_mov_b32_e32 v29, v217
	v_mov_b32_e32 v30, v218
	v_mov_b32_e32 v31, v219
	v_mov_b32_e32 v32, v17
	v_mov_b32_e32 v33, v18
	v_mov_b32_e32 v17, v19
	v_mov_b32_e32 v18, v21
	v_mov_b32_e32 v19, v22
	v_mov_b32_e32 v21, v23
	v_pk_add_f32 v[16:17], v[32:33], v[16:17]
	v_pk_add_f32 v[18:19], v[18:19], v[20:21]
	v_pk_add_f32 v[16:17], v[16:17], v[16:17] op_sel:[0,1] op_sel_hi:[1,0]
	v_pk_add_f32 v[18:19], v[18:19], v[18:19] op_sel:[0,1] op_sel_hi:[1,0]
	v_add_f32_e32 v22, v24, v25
	v_add_f32_e32 v24, v26, v27
	v_mov_b32_e32 v23, v30
	v_mov_b32_e32 v25, v31
	v_mov_b32_e32 v17, v28
	v_mov_b32_e32 v19, v29
	v_pk_add_f32 v[20:21], v[22:23], v[24:25]
	v_pk_add_f32 v[16:17], v[16:17], v[18:19]
	s_nop 0
	v_pk_add_f32 v[16:17], v[16:17], v[20:21]
	s_nop 0
	v_add_f32_e32 v16, v16, v17
	v_fmamk_f32 v16, v16, 0x3a800000, v158
	v_mul_f32_e32 v17, 0x4b800000, v16
	v_cmp_gt_f32_e64 s[10:11], s65, v16
	s_nop 1
	v_cndmask_b32_e64 v16, v16, v17, s[10:11]
	v_rsq_f32_e32 v18, v16
	v_mad_i64_i32 v[16:17], s[8:9], v48, s66, v[146:147]
	v_lshl_add_u64 v[16:17], v[16:17], 0, v[148:149]
	v_mul_f32_e32 v19, 0x45800000, v18
	v_cndmask_b32_e64 v18, v18, v19, s[10:11]
	v_pk_mul_f32 v[14:15], v[14:15], v[18:19] op_sel_hi:[1,0]
	v_pk_mul_f32 v[12:13], v[12:13], v[18:19] op_sel_hi:[1,0]
	v_pk_mul_f32 v[10:11], v[10:11], v[18:19] op_sel_hi:[1,0]
	v_pk_mul_f32 v[8:9], v[8:9], v[18:19] op_sel_hi:[1,0]
	v_pk_mul_f32 v[6:7], v[6:7], v[18:19] op_sel_hi:[1,0]
	v_pk_mul_f32 v[4:5], v[4:5], v[18:19] op_sel_hi:[1,0]
	v_pk_mul_f32 v[20:21], v[2:3], v[18:19] op_sel_hi:[1,0]
	v_pk_mul_f32 v[18:19], v[0:1], v[18:19] op_sel_hi:[1,0]
	v_cvt_pk_bf16_f32 v0, v12, v13
	v_cvt_pk_bf16_f32 v1, v14, v15
	v_cvt_pk_bf16_f32 v2, v8, v9
	v_cvt_pk_bf16_f32 v3, v10, v11
	global_store_dwordx4 v[16:17], v[0:3], off sc1
	s_nop 1
	v_cvt_pk_bf16_f32 v0, v4, v5
	v_cvt_pk_bf16_f32 v1, v6, v7
	v_cvt_pk_bf16_f32 v2, v18, v19
	v_cvt_pk_bf16_f32 v3, v20, v21
	global_store_dwordx4 v[16:17], v[0:3], off offset:256 sc1
	s_cbranch_vccz .LBB0_1281
	s_waitcnt vmcnt(0)
	s_cmpk_gt_u32 s53, 0xff
	s_cbranch_scc1 .LBB0_1292
	s_barrier

; __device__ __forceinline__ unsigned pk2(float lo, float hi) { unsigned r; asm volatile("v_cvt_pk_bf16_f32 %0, %1, %2" : "=v"(r) : "v"(lo), "v"(hi)); return r; }
; #define RAW_BARRIER() do { asm volatile("s_waitcnt lgkmcnt(0)" ::: "memory"); __builtin_amdgcn_s_barrier(); asm volatile("" ::: "memory"); } while (0)
;     ...
;         RAW_BARRIER();
;         { u32x4 w;
;           w.x = pk2(tile[(k8 + 0) * 65 + n], tile[(k8 + 1) * 65 + n]); w.y = pk2(tile[(k8 + 2) * 65 + n], tile[(k8 + 3) * 65 + n]);
;           w.z = pk2(tile[(k8 + 4) * 65 + n], tile[(k8 + 5) * 65 + n]); w.w = pk2(tile[(k8 + 6) * 65 + n], tile[(k8 + 7) * 65 + n]);
;           *(u32x4*)(dst + (size_t)(n0 + n) * K + k0 + k8) = w; }
;         RAW_BARRIER();
.LBB0_1296:
	s_waitcnt lgkmcnt(0)
	s_barrier
	ds_read_b32 v20, v16 offset:260
	ds_read_b32 v21, v15
	s_ashr_i32 s16, s6, 31
	s_lshr_b32 s16, s16, 28
	s_add_i32 s6, s6, s16
	s_ashr_i32 s6, s6, 4
	v_add_u32_e32 v26, s18, v13
	s_lshl_b32 s16, s6, 6
	s_lshl_b32 s6, s6, 10
	s_waitcnt lgkmcnt(0)
	v_cvt_pk_bf16_f32 v20, v21, v20
	ds_read2_b32 v[22:23], v16 offset0:130 offset1:195
	v_subrev_u32_e32 v26, s6, v26
	s_waitcnt lgkmcnt(0)
	v_cvt_pk_bf16_f32 v21, v22, v23
	ds_read2_b32 v[22:23], v19 offset0:4 offset1:69
	v_ashrrev_i32_e32 v27, 31, v26
	s_waitcnt lgkmcnt(0)
	v_cvt_pk_bf16_f32 v22, v22, v23
	ds_read2_b32 v[24:25], v19 offset0:134 offset1:199
	v_lshlrev_b64 v[26:27], 13, v[26:27]
	s_waitcnt lgkmcnt(0)
	v_cvt_pk_bf16_f32 v23, v24, v25
	v_lshl_add_u64 v[24:25], s[10:11], 0, v[26:27]
	s_ashr_i32 s17, s16, 31
	v_lshl_add_u64 v[24:25], s[16:17], 1, v[24:25]
	v_lshl_add_u64 v[24:25], v[24:25], 0, v[10:11]
	global_store_dwordx4 v[24:25], v[20:23], off sc1
	s_waitcnt lgkmcnt(0)
	s_barrier
	s_andn2_b64 vcc, exec, s[14:15]
	s_mov_b32 s18, s19
	s_mov_b32 s6, s9
	s_cbranch_vccz .LBB0_1301

; __device__ __forceinline__ float sigmoidf_(float x) { return 1.0f / (1.0f + __expf(-x)); }
; __device__ __forceinline__ float tanhf_(float x) { return 1.0f - 2.0f / (__expf(2.0f * x) + 1.0f); }
; __device__ __forceinline__ u32x4 pack8(const f32x4 v0, const f32x4 v1) { u32x4 w; w.x = pk2(v0[0], v0[1]); w.y = pk2(v0[2], v0[3]); w.z = pk2(v1[0], v1[1]); w.w = pk2(v1[2], v1[3]); return w; }
; __device__ __forceinline__ void unpack8(const u32x4 w, f32x4& v0, f32x4& v1) { v0 = (f32x4){bflo(w.x), bfhi(w.x), bflo(w.y), bfhi(w.y)}; v1 = (f32x4){bflo(w.z), bfhi(w.z), bflo(w.w), bfhi(w.w)}; }
; __device__ __forceinline__ Tok tok_decode(int tok) { Tok r; if (tok < T_P) { r.is_s = 0; r.seq = tok >> 11; r.t = tok & 2047; } else { r.is_s = 1; r.seq = (tok - T_P) >> 3; r.t = (tok - T_P) & 7; } return r; }
; __device__ void phase_e1(int l) {
;     ...
;         const int tok = it >> 5, v = it & 31; const Tok tk = tok_decode(tok);
;         const int c = O_LORA + v * 8; const bf16_t* zr = z + (size_t)tok * DIN + c;
;         f32x4 x0, x1, p0, p1; unpack8(*(const u32x4*)zr, x0, x1);
;         if (tk.t > 0) unpack8(*(const u32x4*)(zr - DIN), p0, p1);
;         else if (tk.is_s) { const float* sp = st_shift + (size_t)tk.seq * DSH + c; p0 = *(const f32x4*)sp; p1 = *(const f32x4*)(sp + 4); }
;         else { p0 = (f32x4){0.f, 0.f, 0.f, 0.f}; p1 = p0; }
;         const f32x4 m0 = *(const f32x4*)(mu + c), m1 = *(const f32x4*)(mu + c + 4);
;         x0 = x0 + (p0 - x0) * m0; x1 = x1 + (p1 - x1) * m1;
;         if (v < 8) {
; #pragma unroll
;             for (int j = 0; j < 4; ++j) { x0[j] = tanhf_(x0[j]); x1[j] = tanhf_(x1[j]); } }
;         else if (v >= 16) {
; #pragma unroll
;             for (int j = 0; j < 4; ++j) { x0[j] = sigmoidf_(x0[j]); x1[j] = sigmoidf_(x1[j]); } }
;         *(u32x4*)(Lb + (size_t)tok * 256 + v * 8) = pack8(x0, x1);
.LBB0_1357:
	s_or_b64 exec, exec, s[14:15]
	v_ashrrev_i32_e32 v23, 31, v22
	v_add_u32_e32 v24, s52, v24
	v_cvt_pk_bf16_f32 v4, v4, v5
	v_cvt_pk_bf16_f32 v5, v0, v1
	v_lshlrev_b64 v[0:1], 9, v[22:23]
	v_cmp_lt_i32_e32 vcc, s28, v24
	v_lshl_add_u64 v[0:1], v[20:21], 0, v[0:1]
	s_or_b64 s[20:21], vcc, s[20:21]
	v_cvt_pk_bf16_f32 v6, v6, v7
	v_cvt_pk_bf16_f32 v7, v2, v3
	global_store_dwordx4 v[0:1], v[4:7], off sc1
	s_andn2_b64 exec, exec, s[20:21]
	s_cbranch_execz .LBB0_1370

; __device__ __forceinline__ u32x4 pack8(const f32x4 v0, const f32x4 v1) { u32x4 w; w.x = pk2(v0[0], v0[1]); w.y = pk2(v0[2], v0[3]); w.z = pk2(v1[0], v1[1]); w.w = pk2(v1[2], v1[3]); return w; }
; __device__ void phase_e1(int l) {
;     ...
;         const int cnt = tk.is_s ? win : min(tk.t + 1, win);
;         const float inv = 1.0f / (float)cnt;
;         s0 = s0 * inv - u0; s1 = s1 * inv - u1;
;         *(u32x4*)(pbuf + (size_t)tok * 512 + c) = pack8(s0, s1);
.LBB0_1373:
	s_andn2_saveexec_b64 s[10:11], s[12:13]
	s_or_b64 exec, exec, s[10:11]
	s_waitcnt vmcnt(0)
	v_min_u32_e32 v8, v29, v28
	v_cndmask_b32_e32 v8, v28, v8, vcc
	v_cvt_f32_ubyte0_e32 v8, v8
	v_div_scale_f32 v9, s[10:11], v8, v8, 1.0
	v_rcp_f32_e32 v10, v9
	v_ashrrev_i32_e32 v19, 31, v18
	v_add_u32_e32 v51, s52, v51
	v_fma_f32 v11, -v9, v10, 1.0
	v_fmac_f32_e32 v10, v11, v10
	v_div_scale_f32 v11, vcc, 1.0, v8, 1.0
	v_mul_f32_e32 v28, v11, v10
	v_fma_f32 v29, -v9, v28, v11
	v_fmac_f32_e32 v28, v29, v10
	v_fma_f32 v9, -v9, v28, v11
	v_div_fmas_f32 v9, v9, v10, v28
	v_div_fixup_f32 v8, v9, v8, 1.0
	v_xor_b32_e32 v11, 0x80000000, v27
	v_xor_b32_e32 v10, 0x80000000, v26
	v_pk_fma_f32 v[2:3], v[2:3], v[8:9], v[10:11] op_sel_hi:[1,0,1]
	v_pk_fma_f32 v[0:1], v[0:1], v[8:9], v[22:23] op_sel_hi:[1,0,1] neg_lo:[0,0,1] neg_hi:[0,0,1]
	v_pk_fma_f32 v[4:5], v[4:5], v[8:9], v[20:21] op_sel_hi:[1,0,1] neg_lo:[0,0,1] neg_hi:[0,0,1]
	v_cvt_pk_bf16_f32 v0, v0, v1
	v_cvt_pk_bf16_f32 v1, v2, v3
	v_cmp_lt_i32_e32 vcc, s9, v51
	v_cvt_pk_bf16_f32 v2, v4, v5
	v_lshlrev_b64 v[4:5], 10, v[18:19]
	v_lshl_add_u64 v[4:5], s[58:59], 0, v[4:5]
	v_xor_b32_e32 v11, 0x80000000, v25
	v_xor_b32_e32 v10, 0x80000000, v24
	v_lshl_add_u64 v[4:5], v[4:5], 0, v[16:17]
	s_or_b64 s[64:65], vcc, s[64:65]
	v_pk_fma_f32 v[6:7], v[6:7], v[8:9], v[10:11] op_sel_hi:[1,0,1]
	s_nop 0
	v_cvt_pk_bf16_f32 v3, v6, v7
	global_store_dwordx4 v[4:5], v[0:3], off sc1
	s_andn2_b64 exec, exec, s[64:65]
	s_cbranch_execz .LBB0_1391

; #define PG8_STAGE(bufoff, gbase, voff) do { _Pragma("unroll") for (int _i = 0; _i < 2; ++_i) \
;         __builtin_amdgcn_global_load_lds((const unsigned*)((const char*)(gbase) + (voff)[_i]), (LAS unsigned*)(lds + (bufoff) + ldsw + _i * 8192), 16, 0, 0); } while (0)
; #define PG8_LDA(dst, b, h) do { _Pragma("unroll") for (int m = 0; m < 4; ++m) _Pragma("unroll") for (int k = 0; k < 2; ++k) dst[m][k] = *(const LAS bf16x8*)(lds + PG8_SA(b, h) + aoff + m * 2048 + k * 1024); } while (0)
; #define PG8_LDB(dst, b, h) do { _Pragma("unroll") for (int n = 0; n < 2; ++n) _Pragma("unroll") for (int k = 0; k < 2; ++k) dst[n][k] = *(const LAS bf16x8*)(lds + PG8_SB(b, h) + boff + n * 2048 + k * 1024); } while (0)
; #define PG8_MMA(ai, bj, At, Bt) do { __builtin_amdgcn_s_setprio(1); _Pragma("unroll") for (int m = 0; m < 4; ++m) _Pragma("unroll") for (int n = 0; n < 2; ++n) _Pragma("unroll") for (int k = 0; k < 2; ++k) \
;         acc[ai][bj][m][n] = __builtin_amdgcn_mfma_f32_16x16x32_bf16(Bt[n][k], At[m][k], acc[ai][bj][m][n], 0, 0, 0); __builtin_amdgcn_s_setprio(0); } while (0)
; #define PG8_WAIT_V(n) asm volatile("s_waitcnt vmcnt(" #n ")" ::: "memory")
; #define PG8_WAIT_L(n) asm volatile("s_waitcnt lgkmcnt(" #n ")" ::: "memory")
; #define PG8_BAR __builtin_amdgcn_s_barrier()
; #define PG8_SCHED __builtin_amdgcn_sched_barrier(0)
;     ...
;             PG8_LDB(B0, 0, 0); PG8_SCHED; PG8_LDA(At, 0, 0); PG8_STAGE(PG8_SA(1, 1), a1 + hA, voffA);
;             PG8_WAIT_L(8); PG8_BAR; PG8_WAIT_L(0); PG8_MMA(0, 0, At, B0); PG8_BAR; PG8_SCHED;
;             PG8_LDB(B1, 0, 1); PG8_STAGE(PG8_SB(0, 0), b2, voffB);
;             PG8_BAR; PG8_WAIT_L(0); PG8_MMA(0, 1, At, B1); PG8_BAR;
;             PG8_LDA(At, 0, 1); PG8_STAGE(PG8_SA(0, 0), a2, voffA);
;             PG8_BAR; PG8_WAIT_L(0); PG8_MMA(1, 0, At, B0); PG8_BAR; PG8_SCHED;
;             PG8_STAGE(PG8_SB(0, 1), b2 + hB, voffB);
;             PG8_WAIT_V(6); PG8_BAR; PG8_MMA(1, 1, At, B1); PG8_BAR;
.LBB0_1485:
	ds_read_b128 v[128:131], v172
	ds_read_b128 v[132:135], v172 offset:1024
	ds_read_b128 v[136:139], v172 offset:2048
	ds_read_b128 v[140:143], v172 offset:3072
	s_add_u32 s36, s34, 0xfffe0080
	s_addc_u32 s37, s35, -1
	s_cmp_eq_u32 s44, 4
	s_cselect_b32 s39, s7, s37
	s_cselect_b32 s38, s8, s36
	s_cselect_b32 s37, s9, s33
	s_cselect_b32 s36, s23, s25
	v_lshl_add_u64 v[204:205], s[34:35], 0, v[156:157]
	s_add_i32 m0, s31, 0xc000
	ds_read_b128 v[162:165], v173
	ds_read_b128 v[176:179], v173 offset:1024
	ds_read_b128 v[180:183], v173 offset:2048
	ds_read_b128 v[184:187], v173 offset:3072
	ds_read_b128 v[188:191], v173 offset:4096
	ds_read_b128 v[192:195], v173 offset:5120
	ds_read_b128 v[196:199], v173 offset:6144
	ds_read_b128 v[200:203], v173 offset:7168
	global_load_lds_dwordx4 v[204:205], off
	v_lshl_add_u64 v[204:205], s[34:35], 0, v[154:155]
	s_add_i32 m0, s31, 0xe000
	s_nop 0
	global_load_lds_dwordx4 v[204:205], off
	s_waitcnt lgkmcnt(8)
	s_barrier
	s_waitcnt lgkmcnt(0)
	s_setprio 1
	s_waitcnt lgkmcnt(0)
	v_mfma_f32_16x16x32_bf16 v[124:127], v[128:131], v[162:165], v[124:127]
	v_mfma_f32_16x16x32_bf16 v[120:123], v[136:139], v[162:165], v[120:123]
	v_mfma_f32_16x16x32_bf16 v[116:119], v[128:131], v[180:183], v[116:119]
	v_mfma_f32_16x16x32_bf16 v[112:115], v[136:139], v[180:183], v[112:115]
	v_mfma_f32_16x16x32_bf16 v[108:111], v[128:131], v[188:191], v[108:111]
	v_mfma_f32_16x16x32_bf16 v[100:103], v[136:139], v[188:191], v[100:103]
	v_mfma_f32_16x16x32_bf16 v[92:95], v[128:131], v[196:199], v[92:95]
	v_mfma_f32_16x16x32_bf16 v[80:83], v[136:139], v[196:199], v[80:83]
	v_mfma_f32_16x16x32_bf16 v[124:127], v[132:135], v[176:179], v[124:127]
	v_mfma_f32_16x16x32_bf16 v[120:123], v[140:143], v[176:179], v[120:123]
	v_mfma_f32_16x16x32_bf16 v[116:119], v[132:135], v[184:187], v[116:119]
	v_mfma_f32_16x16x32_bf16 v[112:115], v[140:143], v[184:187], v[112:115]
	v_mfma_f32_16x16x32_bf16 v[108:111], v[132:135], v[192:195], v[108:111]
	v_mfma_f32_16x16x32_bf16 v[100:103], v[140:143], v[192:195], v[100:103]
	v_mfma_f32_16x16x32_bf16 v[92:95], v[132:135], v[200:203], v[92:95]
	v_mfma_f32_16x16x32_bf16 v[80:83], v[140:143], v[200:203], v[80:83]
	s_setprio 0
	s_barrier
	s_add_i32 s45, s61, s42
	v_lshl_add_u64 v[220:221], s[36:37], 0, v[150:151]
	s_mov_b32 m0, s45
	ds_read_b128 v[204:207], v174
	ds_read_b128 v[208:211], v174 offset:1024
	ds_read_b128 v[212:215], v174 offset:2048
	ds_read_b128 v[216:219], v174 offset:3072
	global_load_lds_dwordx4 v[220:221], off
	v_lshl_add_u64 v[222:223], s[36:37], 0, v[146:147]
	s_add_i32 m0, s45, 0x2000
	s_nop 0
	global_load_lds_dwordx4 v[222:223], off
	s_barrier
	s_waitcnt lgkmcnt(0)
	s_setprio 1
	s_waitcnt lgkmcnt(0)
	v_mfma_f32_16x16x32_bf16 v[104:107], v[204:207], v[162:165], v[104:107]
	v_mfma_f32_16x16x32_bf16 v[96:99], v[212:215], v[162:165], v[96:99]
	v_mfma_f32_16x16x32_bf16 v[88:91], v[204:207], v[180:183], v[88:91]
	v_mfma_f32_16x16x32_bf16 v[84:87], v[212:215], v[180:183], v[84:87]
	v_mfma_f32_16x16x32_bf16 v[76:79], v[204:207], v[188:191], v[76:79]
	v_mfma_f32_16x16x32_bf16 v[72:75], v[212:215], v[188:191], v[72:75]
	v_mfma_f32_16x16x32_bf16 v[68:71], v[204:207], v[196:199], v[68:71]
	v_mfma_f32_16x16x32_bf16 v[64:67], v[212:215], v[196:199], v[64:67]
	v_mfma_f32_16x16x32_bf16 v[104:107], v[208:211], v[176:179], v[104:107]
	v_mfma_f32_16x16x32_bf16 v[96:99], v[216:219], v[176:179], v[96:99]
	v_mfma_f32_16x16x32_bf16 v[88:91], v[208:211], v[184:187], v[88:91]
	v_mfma_f32_16x16x32_bf16 v[84:87], v[216:219], v[184:187], v[84:87]
	v_mfma_f32_16x16x32_bf16 v[76:79], v[208:211], v[192:195], v[76:79]
	v_mfma_f32_16x16x32_bf16 v[72:75], v[216:219], v[192:195], v[72:75]
	v_mfma_f32_16x16x32_bf16 v[68:71], v[208:211], v[200:203], v[68:71]
	v_mfma_f32_16x16x32_bf16 v[64:67], v[216:219], v[200:203], v[64:67]
	s_setprio 0
	s_mov_b32 m0, s31
	v_lshl_add_u64 v[224:225], s[38:39], 0, v[152:153]
	s_barrier
	ds_read_b128 v[162:165], v173 offset:16384
	ds_read_b128 v[176:179], v173 offset:17408
	ds_read_b128 v[180:183], v173 offset:18432
	ds_read_b128 v[184:187], v173 offset:19456
	ds_read_b128 v[188:191], v173 offset:20480
	ds_read_b128 v[192:195], v173 offset:21504
	ds_read_b128 v[196:199], v173 offset:22528
	ds_read_b128 v[200:203], v173 offset:23552
	global_load_lds_dwordx4 v[224:225], off
	v_lshl_add_u64 v[226:227], s[38:39], 0, v[148:149]
	s_mov_b32 m0, s54
	s_nop 0
	global_load_lds_dwordx4 v[226:227], off
	s_barrier
	s_waitcnt lgkmcnt(0)
	s_setprio 1
	s_waitcnt lgkmcnt(0)
	v_mfma_f32_16x16x32_bf16 v[60:63], v[128:131], v[162:165], v[60:63]
	v_mfma_f32_16x16x32_bf16 v[56:59], v[136:139], v[162:165], v[56:59]
	v_mfma_f32_16x16x32_bf16 v[48:51], v[128:131], v[180:183], v[48:51]
	v_mfma_f32_16x16x32_bf16 v[40:43], v[136:139], v[180:183], v[40:43]
	v_mfma_f32_16x16x32_bf16 v[32:35], v[128:131], v[188:191], v[32:35]
	v_mfma_f32_16x16x32_bf16 v[24:27], v[136:139], v[188:191], v[24:27]
	v_mfma_f32_16x16x32_bf16 v[16:19], v[128:131], v[196:199], v[16:19]
	v_mfma_f32_16x16x32_bf16 v[8:11], v[136:139], v[196:199], v[8:11]
	v_mfma_f32_16x16x32_bf16 v[60:63], v[132:135], v[176:179], v[60:63]
	v_mfma_f32_16x16x32_bf16 v[56:59], v[140:143], v[176:179], v[56:59]
	v_mfma_f32_16x16x32_bf16 v[48:51], v[132:135], v[184:187], v[48:51]
	v_mfma_f32_16x16x32_bf16 v[40:43], v[140:143], v[184:187], v[40:43]
	v_mfma_f32_16x16x32_bf16 v[32:35], v[132:135], v[192:195], v[32:35]
	v_mfma_f32_16x16x32_bf16 v[24:27], v[140:143], v[192:195], v[24:27]
	v_mfma_f32_16x16x32_bf16 v[16:19], v[132:135], v[200:203], v[16:19]
	v_mfma_f32_16x16x32_bf16 v[8:11], v[140:143], v[200:203], v[8:11]
	s_setprio 0
	s_barrier
; #define PG8_STAGE(bufoff, gbase, voff) do { _Pragma("unroll") for (int _i = 0; _i < 2; ++_i) \
;         __builtin_amdgcn_global_load_lds((const unsigned*)((const char*)(gbase) + (voff)[_i]), (LAS unsigned*)(lds + (bufoff) + ldsw + _i * 8192), 16, 0, 0); } while (0)
; #define PG8_LDA(dst, b, h) do { _Pragma("unroll") for (int m = 0; m < 4; ++m) _Pragma("unroll") for (int k = 0; k < 2; ++k) dst[m][k] = *(const LAS bf16x8*)(lds + PG8_SA(b, h) + aoff + m * 2048 + k * 1024); } while (0)
; #define PG8_LDB(dst, b, h) do { _Pragma("unroll") for (int n = 0; n < 2; ++n) _Pragma("unroll") for (int k = 0; k < 2; ++k) dst[n][k] = *(const LAS bf16x8*)(lds + PG8_SB(b, h) + boff + n * 2048 + k * 1024); } while (0)
; #define PG8_MMA(ai, bj, At, Bt) do { __builtin_amdgcn_s_setprio(1); _Pragma("unroll") for (int m = 0; m < 4; ++m) _Pragma("unroll") for (int n = 0; n < 2; ++n) _Pragma("unroll") for (int k = 0; k < 2; ++k) \
;         acc[ai][bj][m][n] = __builtin_amdgcn_mfma_f32_16x16x32_bf16(Bt[n][k], At[m][k], acc[ai][bj][m][n], 0, 0, 0); __builtin_amdgcn_s_setprio(0); } while (0)
; #define PG8_WAIT_V(n) asm volatile("s_waitcnt vmcnt(" #n ")" ::: "memory")
; #define PG8_WAIT_L(n) asm volatile("s_waitcnt lgkmcnt(" #n ")" ::: "memory")
; #define PG8_BAR __builtin_amdgcn_s_barrier()
; #define PG8_SCHED __builtin_amdgcn_sched_barrier(0)
;     ...
;             PG8_WAIT_V(6); PG8_BAR; PG8_MMA(1, 1, At, B1); PG8_BAR;
;             PG8_LDB(B0, 1, 0); PG8_SCHED; PG8_LDA(At, 1, 0); PG8_STAGE(PG8_SA(0, 1), a2 + hA, voffA);
;             PG8_WAIT_L(8); PG8_BAR; PG8_WAIT_L(0); PG8_MMA(0, 0, At, B0); PG8_BAR; PG8_SCHED;
;             PG8_LDB(B1, 1, 1); PG8_STAGE(PG8_SB(1, 0), b3, voffB);
;             PG8_BAR; PG8_WAIT_L(0); PG8_MMA(0, 1, At, B1); PG8_BAR;
;             PG8_LDA(At, 1, 1); PG8_STAGE(PG8_SA(1, 0), a3, voffA);
;             PG8_BAR; PG8_WAIT_L(0); PG8_MMA(1, 0, At, B0); PG8_BAR; PG8_SCHED;
	s_add_u32 s64, s36, 0x20000
	s_addc_u32 s65, s37, 0
	s_add_i32 s45, s62, s42
	v_lshl_add_u64 v[128:129], s[64:65], 0, v[150:151]
	s_mov_b32 m0, s45
	s_nop 0
	global_load_lds_dwordx4 v[128:129], off
	v_lshl_add_u64 v[128:129], s[64:65], 0, v[146:147]
	s_add_i32 m0, s45, 0x2000
	s_nop 0
	global_load_lds_dwordx4 v[128:129], off
	s_waitcnt vmcnt(6)
	s_barrier
	s_setprio 1
	v_mfma_f32_16x16x32_bf16 v[52:55], v[204:207], v[162:165], v[52:55]
	v_mfma_f32_16x16x32_bf16 v[44:47], v[212:215], v[162:165], v[44:47]
	v_mfma_f32_16x16x32_bf16 v[36:39], v[204:207], v[180:183], v[36:39]
	v_mfma_f32_16x16x32_bf16 v[28:31], v[212:215], v[180:183], v[28:31]
	v_mfma_f32_16x16x32_bf16 v[20:23], v[204:207], v[188:191], v[20:23]
	v_mfma_f32_16x16x32_bf16 v[12:15], v[212:215], v[188:191], v[12:15]
	v_mfma_f32_16x16x32_bf16 v[4:7], v[204:207], v[196:199], v[4:7]
	v_mfma_f32_16x16x32_bf16 v[0:3], v[212:215], v[196:199], v[0:3]
	v_mfma_f32_16x16x32_bf16 v[52:55], v[208:211], v[176:179], v[52:55]
	v_mfma_f32_16x16x32_bf16 v[44:47], v[216:219], v[176:179], v[44:47]
	v_mfma_f32_16x16x32_bf16 v[36:39], v[208:211], v[184:187], v[36:39]
	v_mfma_f32_16x16x32_bf16 v[28:31], v[216:219], v[184:187], v[28:31]
	v_mfma_f32_16x16x32_bf16 v[20:23], v[208:211], v[192:195], v[20:23]
	v_mfma_f32_16x16x32_bf16 v[12:15], v[216:219], v[192:195], v[12:15]
	v_mfma_f32_16x16x32_bf16 v[4:7], v[208:211], v[200:203], v[4:7]
	v_mfma_f32_16x16x32_bf16 v[0:3], v[216:219], v[200:203], v[0:3]
	s_setprio 0
	s_add_i32 s45, 0, 0x18000
	v_add_u32_e32 v140, s45, v170
	s_barrier
	ds_read_b128 v[128:131], v140
	ds_read_b128 v[132:135], v140 offset:1024
	ds_read_b128 v[136:139], v140 offset:2048
	ds_read_b128 v[140:143], v140 offset:3072
	s_add_u32 s38, s38, 0x20000
	s_addc_u32 s39, s39, 0
	s_mov_b32 m0, s55
	v_lshl_add_u64 v[204:205], s[38:39], 0, v[152:153]
	ds_read_b128 v[162:165], v173 offset:32768
	ds_read_b128 v[176:179], v173 offset:33792
	ds_read_b128 v[180:183], v173 offset:34816
	ds_read_b128 v[184:187], v173 offset:35840
	ds_read_b128 v[188:191], v173 offset:36864
	ds_read_b128 v[192:195], v173 offset:37888
	ds_read_b128 v[196:199], v173 offset:38912
	ds_read_b128 v[200:203], v173 offset:39936
	global_load_lds_dwordx4 v[204:205], off
	v_lshl_add_u64 v[204:205], s[38:39], 0, v[148:149]
	s_mov_b32 m0, s56
	s_nop 0
	global_load_lds_dwordx4 v[204:205], off
	s_waitcnt lgkmcnt(8)
	s_barrier
	s_waitcnt lgkmcnt(0)
	s_setprio 1
	s_waitcnt lgkmcnt(0)
	v_mfma_f32_16x16x32_bf16 v[124:127], v[128:131], v[162:165], v[124:127]
	v_mfma_f32_16x16x32_bf16 v[120:123], v[136:139], v[162:165], v[120:123]
	v_mfma_f32_16x16x32_bf16 v[116:119], v[128:131], v[180:183], v[116:119]
	v_mfma_f32_16x16x32_bf16 v[112:115], v[136:139], v[180:183], v[112:115]
	v_mfma_f32_16x16x32_bf16 v[108:111], v[128:131], v[188:191], v[108:111]
	v_mfma_f32_16x16x32_bf16 v[100:103], v[136:139], v[188:191], v[100:103]
	v_mfma_f32_16x16x32_bf16 v[92:95], v[128:131], v[196:199], v[92:95]
	v_mfma_f32_16x16x32_bf16 v[80:83], v[136:139], v[196:199], v[80:83]
	v_mfma_f32_16x16x32_bf16 v[124:127], v[132:135], v[176:179], v[124:127]
	v_mfma_f32_16x16x32_bf16 v[120:123], v[140:143], v[176:179], v[120:123]
	v_mfma_f32_16x16x32_bf16 v[116:119], v[132:135], v[184:187], v[116:119]
	v_mfma_f32_16x16x32_bf16 v[112:115], v[140:143], v[184:187], v[112:115]
	v_mfma_f32_16x16x32_bf16 v[108:111], v[132:135], v[192:195], v[108:111]
	v_mfma_f32_16x16x32_bf16 v[100:103], v[140:143], v[192:195], v[100:103]
	v_mfma_f32_16x16x32_bf16 v[92:95], v[132:135], v[200:203], v[92:95]
	v_mfma_f32_16x16x32_bf16 v[80:83], v[140:143], v[200:203], v[80:83]
	s_setprio 0
	s_barrier
	s_add_i32 s38, 0, 0x1c000
	s_add_i32 s39, s45, s42
	v_add_u32_e32 v175, s38, v170
	v_lshl_add_u64 v[220:221], v[220:221], 0, s[20:21]
	s_mov_b32 m0, s39
	ds_read_b128 v[204:207], v175
	ds_read_b128 v[208:211], v175 offset:1024
	ds_read_b128 v[212:215], v175 offset:2048
	ds_read_b128 v[216:219], v175 offset:3072
	global_load_lds_dwordx4 v[220:221], off
	v_lshl_add_u64 v[220:221], v[222:223], 0, s[20:21]
	s_add_i32 m0, s39, 0x2000
	s_nop 0
	global_load_lds_dwordx4 v[220:221], off
	s_barrier
	s_waitcnt lgkmcnt(0)
	s_setprio 1
	s_waitcnt lgkmcnt(0)
	v_mfma_f32_16x16x32_bf16 v[104:107], v[204:207], v[162:165], v[104:107]
	v_mfma_f32_16x16x32_bf16 v[96:99], v[212:215], v[162:165], v[96:99]
	v_mfma_f32_16x16x32_bf16 v[88:91], v[204:207], v[180:183], v[88:91]
	v_mfma_f32_16x16x32_bf16 v[84:87], v[212:215], v[180:183], v[84:87]
	v_mfma_f32_16x16x32_bf16 v[76:79], v[204:207], v[188:191], v[76:79]
	v_mfma_f32_16x16x32_bf16 v[72:75], v[212:215], v[188:191], v[72:75]
	v_mfma_f32_16x16x32_bf16 v[68:71], v[204:207], v[196:199], v[68:71]
	v_mfma_f32_16x16x32_bf16 v[64:67], v[212:215], v[196:199], v[64:67]
	v_mfma_f32_16x16x32_bf16 v[104:107], v[208:211], v[176:179], v[104:107]
	v_mfma_f32_16x16x32_bf16 v[96:99], v[216:219], v[176:179], v[96:99]
	v_mfma_f32_16x16x32_bf16 v[88:91], v[208:211], v[184:187], v[88:91]
	v_mfma_f32_16x16x32_bf16 v[84:87], v[216:219], v[184:187], v[84:87]
	v_mfma_f32_16x16x32_bf16 v[76:79], v[208:211], v[192:195], v[76:79]
	v_mfma_f32_16x16x32_bf16 v[72:75], v[216:219], v[192:195], v[72:75]
	v_mfma_f32_16x16x32_bf16 v[68:71], v[208:211], v[200:203], v[68:71]
	v_mfma_f32_16x16x32_bf16 v[64:67], v[216:219], v[200:203], v[64:67]
	s_setprio 0
	s_mov_b32 m0, s57
	v_lshl_add_u64 v[220:221], v[224:225], 0, s[20:21]
	s_barrier
	ds_read_b128 v[162:165], v173 offset:49152
	ds_read_b128 v[176:179], v173 offset:50176
	ds_read_b128 v[180:183], v173 offset:51200
	ds_read_b128 v[184:187], v173 offset:52224
	ds_read_b128 v[188:191], v173 offset:53248
	ds_read_b128 v[192:195], v173 offset:54272
	ds_read_b128 v[196:199], v173 offset:55296
	ds_read_b128 v[200:203], v173 offset:56320
	global_load_lds_dwordx4 v[220:221], off
	v_lshl_add_u64 v[220:221], v[226:227], 0, s[20:21]
	s_mov_b32 m0, s58
	s_nop 0
	global_load_lds_dwordx4 v[220:221], off
	s_barrier
; #define PG8_STAGE(bufoff, gbase, voff) do { _Pragma("unroll") for (int _i = 0; _i < 2; ++_i) \
;         __builtin_amdgcn_global_load_lds((const unsigned*)((const char*)(gbase) + (voff)[_i]), (LAS unsigned*)(lds + (bufoff) + ldsw + _i * 8192), 16, 0, 0); } while (0)
; #define PG8_MMA(ai, bj, At, Bt) do { __builtin_amdgcn_s_setprio(1); _Pragma("unroll") for (int m = 0; m < 4; ++m) _Pragma("unroll") for (int n = 0; n < 2; ++n) _Pragma("unroll") for (int k = 0; k < 2; ++k) \
;         acc[ai][bj][m][n] = __builtin_amdgcn_mfma_f32_16x16x32_bf16(Bt[n][k], At[m][k], acc[ai][bj][m][n], 0, 0, 0); __builtin_amdgcn_s_setprio(0); } while (0)
; #define PG8_WAIT_V(n) asm volatile("s_waitcnt vmcnt(" #n ")" ::: "memory")
; #define PG8_WAIT_L(n) asm volatile("s_waitcnt lgkmcnt(" #n ")" ::: "memory")
; #define PG8_BAR __builtin_amdgcn_s_barrier()
; #define PG8_SCHED __builtin_amdgcn_sched_barrier(0)
;     ...
;             PG8_BAR; PG8_WAIT_L(0); PG8_MMA(1, 0, At, B0); PG8_BAR; PG8_SCHED;
;             PG8_STAGE(PG8_SB(1, 1), b3 + hB, voffB);
;             PG8_WAIT_V(6); PG8_BAR; PG8_MMA(1, 1, At, B1); PG8_BAR;
;         }
;     __device__ __forceinline__ void operator()(const f32x4 (&acc)[2][2][4][2], const Unit& u, int wr, int wc, int fr, int fq) const {
;         const int row0 = u.pm * 256 + wr * 64 + fr, col0 = u.pn * 256 + wc * 32 + 8 * fq;
;         f32x4 bv[2][2];
; #pragma unroll
;         for (int bj = 0; bj < 2; ++bj)
; #pragma unroll
;             for (int n = 0; n < 2; ++n) bv[bj][n] = *(const f32x4*)(scale + col0 + bj * 128 + 4 * n);
; #pragma unroll
;         for (int ai = 0; ai < 2; ++ai)
; #pragma unroll
;             for (int m = 0; m < 4; ++m) {
;                 bf16_t* rowp = z + (size_t)(row0 + ai * 128 + m * 16) * DIN + O_U + col0;
	s_waitcnt lgkmcnt(0)
	s_setprio 1
	s_waitcnt lgkmcnt(0)
	v_mfma_f32_16x16x32_bf16 v[60:63], v[128:131], v[162:165], v[60:63]
	v_mfma_f32_16x16x32_bf16 v[56:59], v[136:139], v[162:165], v[56:59]
	v_mfma_f32_16x16x32_bf16 v[48:51], v[128:131], v[180:183], v[48:51]
	v_mfma_f32_16x16x32_bf16 v[40:43], v[136:139], v[180:183], v[40:43]
	v_mfma_f32_16x16x32_bf16 v[32:35], v[128:131], v[188:191], v[32:35]
	v_mfma_f32_16x16x32_bf16 v[24:27], v[136:139], v[188:191], v[24:27]
	v_mfma_f32_16x16x32_bf16 v[16:19], v[128:131], v[196:199], v[16:19]
	v_mfma_f32_16x16x32_bf16 v[8:11], v[136:139], v[196:199], v[8:11]
	v_mfma_f32_16x16x32_bf16 v[60:63], v[132:135], v[176:179], v[60:63]
	v_mfma_f32_16x16x32_bf16 v[56:59], v[140:143], v[176:179], v[56:59]
	v_mfma_f32_16x16x32_bf16 v[48:51], v[132:135], v[184:187], v[48:51]
	v_mfma_f32_16x16x32_bf16 v[40:43], v[140:143], v[184:187], v[40:43]
	v_mfma_f32_16x16x32_bf16 v[32:35], v[132:135], v[192:195], v[32:35]
	v_mfma_f32_16x16x32_bf16 v[24:27], v[140:143], v[192:195], v[24:27]
	v_mfma_f32_16x16x32_bf16 v[16:19], v[132:135], v[200:203], v[16:19]
	v_mfma_f32_16x16x32_bf16 v[8:11], v[140:143], v[200:203], v[8:11]
	s_setprio 0
	s_barrier
	s_add_u32 s36, s36, 0x20080
	s_addc_u32 s37, s37, 0
	s_add_i32 s38, s38, s42
	v_lshl_add_u64 v[128:129], s[36:37], 0, v[150:151]
	s_mov_b32 m0, s38
	s_nop 0
	global_load_lds_dwordx4 v[128:129], off
	v_lshl_add_u64 v[128:129], s[36:37], 0, v[146:147]
	s_add_i32 m0, s38, 0x2000
	s_nop 0
	global_load_lds_dwordx4 v[128:129], off
	s_waitcnt vmcnt(6)
	s_barrier
	s_setprio 1
	v_mfma_f32_16x16x32_bf16 v[52:55], v[204:207], v[162:165], v[52:55]
	v_mfma_f32_16x16x32_bf16 v[44:47], v[212:215], v[162:165], v[44:47]
	v_mfma_f32_16x16x32_bf16 v[36:39], v[204:207], v[180:183], v[36:39]
	v_mfma_f32_16x16x32_bf16 v[28:31], v[212:215], v[180:183], v[28:31]
	v_mfma_f32_16x16x32_bf16 v[20:23], v[204:207], v[188:191], v[20:23]
	v_mfma_f32_16x16x32_bf16 v[12:15], v[212:215], v[188:191], v[12:15]
	v_mfma_f32_16x16x32_bf16 v[4:7], v[204:207], v[196:199], v[4:7]
	v_mfma_f32_16x16x32_bf16 v[0:3], v[212:215], v[196:199], v[0:3]
	v_mfma_f32_16x16x32_bf16 v[52:55], v[208:211], v[176:179], v[52:55]
	v_mfma_f32_16x16x32_bf16 v[44:47], v[216:219], v[176:179], v[44:47]
	v_mfma_f32_16x16x32_bf16 v[36:39], v[208:211], v[184:187], v[36:39]
	v_mfma_f32_16x16x32_bf16 v[28:31], v[216:219], v[184:187], v[28:31]
	v_mfma_f32_16x16x32_bf16 v[20:23], v[208:211], v[192:195], v[20:23]
	v_mfma_f32_16x16x32_bf16 v[12:15], v[216:219], v[192:195], v[12:15]
	v_mfma_f32_16x16x32_bf16 v[4:7], v[208:211], v[200:203], v[4:7]
	v_mfma_f32_16x16x32_bf16 v[0:3], v[216:219], v[200:203], v[0:3]
	s_setprio 0
	s_add_i32 s44, s44, 2
	s_add_u32 s25, s25, 0x100
	s_addc_u32 s33, s33, 0
	s_add_u32 s34, s34, 0x100
	s_addc_u32 s35, s35, 0
	s_cmp_gt_u32 s44, 5
	s_barrier
	s_cbranch_scc0 .LBB0_1485
	v_lshl_or_b32 v164, s6, 8, v171
	v_ashrrev_i32_e32 v165, 31, v164
	v_lshl_add_u64 v[128:129], v[164:165], 2, s[18:19]
	global_load_dwordx4 v[140:143], v[128:129], off offset:2048
	global_load_dwordx4 v[136:139], v[128:129], off offset:2064
	global_load_dwordx4 v[132:135], v[128:129], off offset:2560
	s_nop 0
	global_load_dwordx4 v[128:131], v[128:129], off offset:2576
	v_lshl_add_u32 v175, s30, 8, v169
	v_mov_b64_e32 v[162:163], s[16:17]
	v_mad_i64_i32 v[176:177], s[6:7], v175, s63, v[162:163]
	v_lshlrev_b64 v[164:165], 1, v[164:165]
	v_or_b32_e32 v178, 16, v175
	v_lshl_add_u64 v[176:177], v[176:177], 0, v[164:165]
	v_mad_i64_i32 v[178:179], s[6:7], v178, s63, v[162:163]
	v_or_b32_e32 v180, 32, v175
	v_lshl_add_u64 v[178:179], v[178:179], 0, v[164:165]
	v_mad_i64_i32 v[180:181], s[6:7], v180, s63, v[162:163]
	v_or_b32_e32 v182, 48, v175
	v_lshl_add_u64 v[180:181], v[180:181], 0, v[164:165]
	v_mad_i64_i32 v[182:183], s[6:7], v182, s63, v[162:163]
	v_lshl_add_u64 v[182:183], v[182:183], 0, v[164:165]
	s_and_b64 vcc, exec, s[10:11]
	s_mov_b32 s30, s24
	s_mov_b64 s[34:35], s[28:29]
	s_mov_b64 s[36:37], s[26:27]
	s_waitcnt vmcnt(0)
; __device__ __forceinline__ u32x4 pack8(const f32x4 v0, const f32x4 v1) { u32x4 w; w.x = pk2(v0[0], v0[1]); w.y = pk2(v0[2], v0[3]); w.z = pk2(v1[0], v1[1]); w.w = pk2(v1[2], v1[3]); return w; }
;     __device__ __forceinline__ void operator()(const f32x4 (&acc)[2][2][4][2], const Unit& u, int wr, int wc, int fr, int fq) const {
;     ...
; #pragma unroll
;         for (int ai = 0; ai < 2; ++ai)
; #pragma unroll
;             for (int m = 0; m < 4; ++m) {
;                 bf16_t* rowp = z + (size_t)(row0 + ai * 128 + m * 16) * DIN + O_U + col0;
; #pragma unroll
;                 for (int bj = 0; bj < 2; ++bj) *(u32x4*)(rowp + bj * 128) = pack8(acc[ai][bj][m][0] * bv[bj][0], acc[ai][bj][m][1] * bv[bj][1]);
;             }
	v_pk_mul_f32 v[124:125], v[124:125], v[140:141]
	v_pk_mul_f32 v[126:127], v[126:127], v[142:143]
	v_pk_mul_f32 v[122:123], v[122:123], v[138:139]
	v_pk_mul_f32 v[186:187], v[64:65], v[128:129]
	v_cvt_pk_bf16_f32 v64, v124, v125
	v_pk_mul_f32 v[120:121], v[120:121], v[136:137]
	v_pk_mul_f32 v[104:105], v[104:105], v[132:133]
	v_pk_mul_f32 v[184:185], v[66:67], v[130:131]
	v_cvt_pk_bf16_f32 v65, v126, v127
	v_cvt_pk_bf16_f32 v66, v120, v121
	v_cvt_pk_bf16_f32 v67, v122, v123
	global_store_dwordx4 v[176:177], v[64:67], off offset:3584 sc1
	v_pk_mul_f32 v[106:107], v[106:107], v[134:135]
	v_pk_mul_f32 v[98:99], v[98:99], v[130:131]
	v_cvt_pk_bf16_f32 v64, v104, v105
	v_pk_mul_f32 v[96:97], v[96:97], v[128:129]
	v_pk_mul_f32 v[116:117], v[116:117], v[140:141]
	v_cvt_pk_bf16_f32 v65, v106, v107
	v_cvt_pk_bf16_f32 v66, v96, v97
	v_cvt_pk_bf16_f32 v67, v98, v99
	global_store_dwordx4 v[176:177], v[64:67], off offset:3840 sc1
	v_pk_mul_f32 v[118:119], v[118:119], v[142:143]
	v_pk_mul_f32 v[114:115], v[114:115], v[138:139]
	v_cvt_pk_bf16_f32 v64, v116, v117
	v_pk_mul_f32 v[112:113], v[112:113], v[136:137]
	v_pk_mul_f32 v[88:89], v[88:89], v[132:133]
	v_cvt_pk_bf16_f32 v65, v118, v119
	v_cvt_pk_bf16_f32 v66, v112, v113
	v_cvt_pk_bf16_f32 v67, v114, v115
	global_store_dwordx4 v[178:179], v[64:67], off offset:3584 sc1
	v_pk_mul_f32 v[90:91], v[90:91], v[134:135]
	v_pk_mul_f32 v[86:87], v[86:87], v[130:131]
	v_cvt_pk_bf16_f32 v64, v88, v89
	v_pk_mul_f32 v[84:85], v[84:85], v[128:129]
	v_pk_mul_f32 v[108:109], v[108:109], v[140:141]
	v_cvt_pk_bf16_f32 v65, v90, v91
	v_cvt_pk_bf16_f32 v66, v84, v85
	v_cvt_pk_bf16_f32 v67, v86, v87
	global_store_dwordx4 v[178:179], v[64:67], off offset:3840 sc1
	v_pk_mul_f32 v[110:111], v[110:111], v[142:143]
	v_pk_mul_f32 v[102:103], v[102:103], v[138:139]
	v_cvt_pk_bf16_f32 v64, v108, v109
	v_pk_mul_f32 v[100:101], v[100:101], v[136:137]
	v_pk_mul_f32 v[76:77], v[76:77], v[132:133]
	v_cvt_pk_bf16_f32 v65, v110, v111
	v_cvt_pk_bf16_f32 v66, v100, v101
	v_cvt_pk_bf16_f32 v67, v102, v103
	global_store_dwordx4 v[180:181], v[64:67], off offset:3584 sc1
	v_pk_mul_f32 v[78:79], v[78:79], v[134:135]
	v_pk_mul_f32 v[74:75], v[74:75], v[130:131]
	v_cvt_pk_bf16_f32 v64, v76, v77
	v_pk_mul_f32 v[72:73], v[72:73], v[128:129]
	v_pk_mul_f32 v[92:93], v[92:93], v[140:141]
	v_cvt_pk_bf16_f32 v65, v78, v79
	v_cvt_pk_bf16_f32 v66, v72, v73
	v_cvt_pk_bf16_f32 v67, v74, v75
	global_store_dwordx4 v[180:181], v[64:67], off offset:3840 sc1
	v_pk_mul_f32 v[94:95], v[94:95], v[142:143]
	v_pk_mul_f32 v[82:83], v[82:83], v[138:139]
	v_cvt_pk_bf16_f32 v64, v92, v93
	v_pk_mul_f32 v[80:81], v[80:81], v[136:137]
	v_pk_mul_f32 v[68:69], v[68:69], v[132:133]
	v_cvt_pk_bf16_f32 v65, v94, v95
	v_cvt_pk_bf16_f32 v66, v80, v81
	v_cvt_pk_bf16_f32 v67, v82, v83
	global_store_dwordx4 v[182:183], v[64:67], off offset:3584 sc1
	v_pk_mul_f32 v[70:71], v[70:71], v[134:135]
	v_pk_mul_f32 v[62:63], v[62:63], v[142:143]
	v_cvt_pk_bf16_f32 v64, v68, v69
	v_cvt_pk_bf16_f32 v65, v70, v71
	v_cvt_pk_bf16_f32 v66, v186, v187
	v_cvt_pk_bf16_f32 v67, v184, v185
	global_store_dwordx4 v[182:183], v[64:67], off offset:3840 sc1
	v_pk_mul_f32 v[60:61], v[60:61], v[140:141]
	v_pk_mul_f32 v[52:53], v[52:53], v[132:133]
	v_add_u32_e32 v64, 0x80, v175
	v_mad_i64_i32 v[64:65], s[6:7], v64, s63, v[162:163]
	v_lshl_add_u64 v[64:65], v[64:65], 0, v[164:165]
	v_pk_mul_f32 v[66:67], v[58:59], v[138:139]
	v_pk_mul_f32 v[58:59], v[56:57], v[136:137]
	v_cvt_pk_bf16_f32 v56, v60, v61
	v_cvt_pk_bf16_f32 v57, v62, v63
	v_pk_mul_f32 v[54:55], v[54:55], v[134:135]
	v_cvt_pk_bf16_f32 v58, v58, v59
	v_cvt_pk_bf16_f32 v59, v66, v67
	global_store_dwordx4 v[64:65], v[56:59], off offset:3584 sc1
	v_pk_mul_f32 v[48:49], v[48:49], v[140:141]
	v_pk_mul_f32 v[36:37], v[36:37], v[132:133]
	v_pk_mul_f32 v[56:57], v[46:47], v[130:131]
	v_pk_mul_f32 v[46:47], v[44:45], v[128:129]
	v_cvt_pk_bf16_f32 v44, v52, v53
	v_cvt_pk_bf16_f32 v45, v54, v55
	v_pk_mul_f32 v[38:39], v[38:39], v[134:135]
	v_cvt_pk_bf16_f32 v46, v46, v47
	v_cvt_pk_bf16_f32 v47, v56, v57
	global_store_dwordx4 v[64:65], v[44:47], off offset:3840 sc1
	v_pk_mul_f32 v[32:33], v[32:33], v[140:141]
	v_pk_mul_f32 v[20:21], v[20:21], v[132:133]
	v_add_u32_e32 v44, 0x90, v175
	v_mad_i64_i32 v[44:45], s[6:7], v44, s63, v[162:163]
	v_lshl_add_u64 v[44:45], v[44:45], 0, v[164:165]
	v_pk_mul_f32 v[46:47], v[50:51], v[142:143]
	v_pk_mul_f32 v[50:51], v[42:43], v[138:139]
	v_pk_mul_f32 v[42:43], v[40:41], v[136:137]
	v_cvt_pk_bf16_f32 v40, v48, v49
	v_cvt_pk_bf16_f32 v41, v46, v47
	v_pk_mul_f32 v[22:23], v[22:23], v[134:135]
	v_cvt_pk_bf16_f32 v42, v42, v43
	v_cvt_pk_bf16_f32 v43, v50, v51
	global_store_dwordx4 v[44:45], v[40:43], off offset:3584 sc1
	v_pk_mul_f32 v[16:17], v[16:17], v[140:141]
	v_pk_mul_f32 v[6:7], v[6:7], v[134:135]
	v_pk_mul_f32 v[40:41], v[30:31], v[130:131]
	v_pk_mul_f32 v[30:31], v[28:29], v[128:129]
	v_cvt_pk_bf16_f32 v28, v36, v37
	v_cvt_pk_bf16_f32 v29, v38, v39
	v_pk_mul_f32 v[4:5], v[4:5], v[132:133]
	v_cvt_pk_bf16_f32 v30, v30, v31
	v_cvt_pk_bf16_f32 v31, v40, v41
	global_store_dwordx4 v[44:45], v[28:31], off offset:3840 sc1
	s_nop 1
	v_add_u32_e32 v28, 0xa0, v175
	v_mad_i64_i32 v[28:29], s[6:7], v28, s63, v[162:163]
	v_lshl_add_u64 v[28:29], v[28:29], 0, v[164:165]
	v_pk_mul_f32 v[30:31], v[34:35], v[142:143]
	v_pk_mul_f32 v[34:35], v[26:27], v[138:139]
	v_pk_mul_f32 v[26:27], v[24:25], v[136:137]
	v_cvt_pk_bf16_f32 v24, v32, v33
	v_cvt_pk_bf16_f32 v25, v30, v31
	s_nop 0
	v_cvt_pk_bf16_f32 v26, v26, v27
	v_cvt_pk_bf16_f32 v27, v34, v35
	global_store_dwordx4 v[28:29], v[24:27], off offset:3584 sc1
	s_nop 1
	v_pk_mul_f32 v[24:25], v[14:15], v[130:131]
	v_pk_mul_f32 v[14:15], v[12:13], v[128:129]
	v_cvt_pk_bf16_f32 v12, v20, v21
	v_cvt_pk_bf16_f32 v13, v22, v23
	s_nop 0
	v_cvt_pk_bf16_f32 v14, v14, v15
	v_cvt_pk_bf16_f32 v15, v24, v25
	global_store_dwordx4 v[28:29], v[12:15], off offset:3840 sc1
	s_nop 1
	v_add_u32_e32 v12, 0xb0, v175
	v_mad_i64_i32 v[12:13], s[6:7], v12, s63, v[162:163]
	v_lshl_add_u64 v[12:13], v[12:13], 0, v[164:165]
	v_pk_mul_f32 v[14:15], v[18:19], v[142:143]
	v_pk_mul_f32 v[18:19], v[10:11], v[138:139]
	v_pk_mul_f32 v[10:11], v[8:9], v[136:137]
	v_cvt_pk_bf16_f32 v8, v16, v17
	v_cvt_pk_bf16_f32 v9, v14, v15
	s_mov_b32 s6, s22
	v_cvt_pk_bf16_f32 v10, v10, v11
	v_cvt_pk_bf16_f32 v11, v18, v19
	global_store_dwordx4 v[12:13], v[8:11], off offset:3584 sc1
	s_nop 1
	v_pk_mul_f32 v[8:9], v[2:3], v[130:131]
	v_pk_mul_f32 v[2:3], v[0:1], v[128:129]
	v_cvt_pk_bf16_f32 v0, v4, v5
	v_cvt_pk_bf16_f32 v1, v6, v7
	s_nop 0
	v_cvt_pk_bf16_f32 v2, v2, v3
	v_cvt_pk_bf16_f32 v3, v8, v9
	global_store_dwordx4 v[12:13], v[0:3], off offset:3840 sc1
	s_cbranch_vccz .LBB0_1482
	s_waitcnt vmcnt(0)
	s_cmpk_gt_u32 s41, 0xff
	s_cbranch_scc1 .LBB0_1489
	s_barrier

; __device__ void phase_scan(int l, unsigned char* lds) {
;     ...
;             const size_t sidx = ((((size_t)l * (jb.is_s ? NSB : NB) + jb.seq) * 8 + jb.h) * 64 + row) * 64 + c0;
;     ...
;             if (jb.last) *(f32x4*)(out + (jb.is_s ? OUT_SWKV : OUT_PWKV) + sidx) = (f32x4){s01.x, s01.y, s23.x, s23.y};
.LBB0_1683:
	s_lshl_b64 s[16:17], 1, s16
	s_ashr_i32 s18, s7, 31
	s_add_u32 s16, s16, s7
	s_addc_u32 s17, s17, s18
	s_and_b64 s[18:19], s[62:63], exec
	s_cselect_b32 s7, s83, 0x4fd4000
	s_add_u32 s7, s42, s7
	s_addc_u32 s18, s43, 0
	s_lshl_b64 s[16:17], s[16:17], 17
	v_lshl_add_u64 v[20:21], v[20:21], 0, s[60:61]
	s_add_u32 s16, s7, s16
	s_addc_u32 s17, s18, s17
	v_lshlrev_b64 v[20:21], 8, v[20:21]
	v_lshl_add_u64 v[20:21], s[16:17], 0, v[20:21]
	v_mov_b32_e32 v91, v19
	v_lshl_add_u64 v[20:21], v[20:21], 0, v[90:91]
	global_store_dwordx4 v[20:21], v[22:25], off sc1
	s_branch .LBB0_1615

; #define PG8_STAGE(bufoff, gbase, voff) do { _Pragma("unroll") for (int _i = 0; _i < 2; ++_i) \
;         __builtin_amdgcn_global_load_lds((const unsigned*)((const char*)(gbase) + (voff)[_i]), (LAS unsigned*)(lds + (bufoff) + ldsw + _i * 8192), 16, 0, 0); } while (0)
; #define PG8_LDA(dst, b, h) do { _Pragma("unroll") for (int m = 0; m < 4; ++m) _Pragma("unroll") for (int k = 0; k < 2; ++k) dst[m][k] = *(const LAS bf16x8*)(lds + PG8_SA(b, h) + aoff + m * 2048 + k * 1024); } while (0)
; #define PG8_LDB(dst, b, h) do { _Pragma("unroll") for (int n = 0; n < 2; ++n) _Pragma("unroll") for (int k = 0; k < 2; ++k) dst[n][k] = *(const LAS bf16x8*)(lds + PG8_SB(b, h) + boff + n * 2048 + k * 1024); } while (0)
; #define PG8_MMA(ai, bj, At, Bt) do { __builtin_amdgcn_s_setprio(1); _Pragma("unroll") for (int m = 0; m < 4; ++m) _Pragma("unroll") for (int n = 0; n < 2; ++n) _Pragma("unroll") for (int k = 0; k < 2; ++k) \
;         acc[ai][bj][m][n] = __builtin_amdgcn_mfma_f32_16x16x32_bf16(Bt[n][k], At[m][k], acc[ai][bj][m][n], 0, 0, 0); __builtin_amdgcn_s_setprio(0); } while (0)
; #define PG8_WAIT_L(n) asm volatile("s_waitcnt lgkmcnt(" #n ")" ::: "memory")
; #define PG8_BAR __builtin_amdgcn_s_barrier()
; #define PG8_SCHED __builtin_amdgcn_sched_barrier(0)
;     ...
;             PG8_LDB(B0, 0, 0); PG8_SCHED; PG8_LDA(At, 0, 0); PG8_STAGE(PG8_SA(1, 1), a1 + hA, voffA);
;             PG8_WAIT_L(8); PG8_BAR; PG8_WAIT_L(0); PG8_MMA(0, 0, At, B0); PG8_BAR; PG8_SCHED;
;             PG8_LDB(B1, 0, 1); PG8_STAGE(PG8_SB(0, 0), b2, voffB);
;             PG8_BAR; PG8_WAIT_L(0); PG8_MMA(0, 1, At, B1); PG8_BAR;
;             PG8_LDA(At, 0, 1); PG8_STAGE(PG8_SA(0, 0), a2, voffA);
;             PG8_BAR; PG8_WAIT_L(0); PG8_MMA(1, 0, At, B0); PG8_BAR; PG8_SCHED;
.LBB0_1768:
	ds_read_b128 v[146:149], v157
	ds_read_b128 v[150:153], v157 offset:1024
	ds_read_b128 v[160:163], v157 offset:2048
	ds_read_b128 v[170:173], v157 offset:3072
	s_add_u32 s10, s12, 0x100
	s_addc_u32 s11, s13, 0
	s_cmp_eq_u32 s60, 4
	s_cselect_b32 s17, s29, s11
	s_cselect_b32 s16, s28, s10
	s_cselect_b32 s15, s27, s45
	s_cselect_b32 s14, s33, s44
	v_lshl_add_u64 v[164:165], s[12:13], 0, v[138:139]
	s_add_i32 m0, s37, 0xc000
	ds_read_b128 v[174:177], v158
	ds_read_b128 v[178:181], v158 offset:1024
	ds_read_b128 v[182:185], v158 offset:2048
	ds_read_b128 v[186:189], v158 offset:3072
	ds_read_b128 v[190:193], v158 offset:4096
	ds_read_b128 v[194:197], v158 offset:5120
	ds_read_b128 v[198:201], v158 offset:6144
	ds_read_b128 v[202:205], v158 offset:7168
	global_load_lds_dwordx4 v[164:165], off
	v_lshl_add_u64 v[164:165], s[12:13], 0, v[136:137]
	s_add_i32 m0, s37, 0xe000
	s_nop 0
	global_load_lds_dwordx4 v[164:165], off
	s_waitcnt lgkmcnt(8)
	s_barrier
	s_waitcnt lgkmcnt(0)
	s_setprio 1
	s_waitcnt lgkmcnt(0)
	v_mfma_f32_16x16x32_bf16 v[124:127], v[146:149], v[174:177], v[124:127]
	v_mfma_f32_16x16x32_bf16 v[120:123], v[160:163], v[174:177], v[120:123]
	v_mfma_f32_16x16x32_bf16 v[108:111], v[146:149], v[182:185], v[108:111]
	v_mfma_f32_16x16x32_bf16 v[104:107], v[160:163], v[182:185], v[104:107]
	v_mfma_f32_16x16x32_bf16 v[92:95], v[146:149], v[190:193], v[92:95]
	v_mfma_f32_16x16x32_bf16 v[88:91], v[160:163], v[190:193], v[88:91]
	v_mfma_f32_16x16x32_bf16 v[76:79], v[146:149], v[198:201], v[76:79]
	v_mfma_f32_16x16x32_bf16 v[72:75], v[160:163], v[198:201], v[72:75]
	v_mfma_f32_16x16x32_bf16 v[124:127], v[150:153], v[178:181], v[124:127]
	v_mfma_f32_16x16x32_bf16 v[120:123], v[170:173], v[178:181], v[120:123]
	v_mfma_f32_16x16x32_bf16 v[108:111], v[150:153], v[186:189], v[108:111]
	v_mfma_f32_16x16x32_bf16 v[104:107], v[170:173], v[186:189], v[104:107]
	v_mfma_f32_16x16x32_bf16 v[92:95], v[150:153], v[194:197], v[92:95]
	v_mfma_f32_16x16x32_bf16 v[88:91], v[170:173], v[194:197], v[88:91]
	v_mfma_f32_16x16x32_bf16 v[76:79], v[150:153], v[202:205], v[76:79]
	v_mfma_f32_16x16x32_bf16 v[72:75], v[170:173], v[202:205], v[72:75]
	s_setprio 0
	s_barrier
	s_add_i32 s12, s55, s35
	v_lshl_add_u64 v[164:165], s[14:15], 0, v[132:133]
	s_mov_b32 m0, s12
	ds_read_b128 v[206:209], v159
	ds_read_b128 v[210:213], v159 offset:1024
	ds_read_b128 v[214:217], v159 offset:2048
	ds_read_b128 v[218:221], v159 offset:3072
	global_load_lds_dwordx4 v[164:165], off
	v_lshl_add_u64 v[222:223], s[14:15], 0, v[128:129]
	s_add_i32 m0, s12, 0x2000
	s_nop 0
	global_load_lds_dwordx4 v[222:223], off
	s_barrier
	s_waitcnt lgkmcnt(0)
	s_setprio 1
	s_waitcnt lgkmcnt(0)
	v_mfma_f32_16x16x32_bf16 v[116:119], v[206:209], v[174:177], v[116:119]
	v_mfma_f32_16x16x32_bf16 v[112:115], v[214:217], v[174:177], v[112:115]
	v_mfma_f32_16x16x32_bf16 v[100:103], v[206:209], v[182:185], v[100:103]
	v_mfma_f32_16x16x32_bf16 v[96:99], v[214:217], v[182:185], v[96:99]
	v_mfma_f32_16x16x32_bf16 v[84:87], v[206:209], v[190:193], v[84:87]
	v_mfma_f32_16x16x32_bf16 v[80:83], v[214:217], v[190:193], v[80:83]
	v_mfma_f32_16x16x32_bf16 v[68:71], v[206:209], v[198:201], v[68:71]
	v_mfma_f32_16x16x32_bf16 v[64:67], v[214:217], v[198:201], v[64:67]
	v_mfma_f32_16x16x32_bf16 v[116:119], v[210:213], v[178:181], v[116:119]
	v_mfma_f32_16x16x32_bf16 v[112:115], v[218:221], v[178:181], v[112:115]
	v_mfma_f32_16x16x32_bf16 v[100:103], v[210:213], v[186:189], v[100:103]
	v_mfma_f32_16x16x32_bf16 v[96:99], v[218:221], v[186:189], v[96:99]
	v_mfma_f32_16x16x32_bf16 v[84:87], v[210:213], v[194:197], v[84:87]
	v_mfma_f32_16x16x32_bf16 v[80:83], v[218:221], v[194:197], v[80:83]
	v_mfma_f32_16x16x32_bf16 v[68:71], v[210:213], v[202:205], v[68:71]
	v_mfma_f32_16x16x32_bf16 v[64:67], v[218:221], v[202:205], v[64:67]
	s_setprio 0
	s_mov_b32 m0, s37
	v_lshl_add_u64 v[224:225], s[16:17], 0, v[134:135]
	s_barrier
	ds_read_b128 v[174:177], v158 offset:16384
	ds_read_b128 v[178:181], v158 offset:17408
	ds_read_b128 v[182:185], v158 offset:18432
	ds_read_b128 v[186:189], v158 offset:19456
	ds_read_b128 v[190:193], v158 offset:20480
	ds_read_b128 v[194:197], v158 offset:21504
	ds_read_b128 v[198:201], v158 offset:22528
	ds_read_b128 v[202:205], v158 offset:23552
	global_load_lds_dwordx4 v[224:225], off
	v_lshl_add_u64 v[226:227], s[16:17], 0, v[130:131]
	s_mov_b32 m0, s40
	s_nop 0
	global_load_lds_dwordx4 v[226:227], off
	s_barrier
	s_waitcnt lgkmcnt(0)
	s_setprio 1
	s_waitcnt lgkmcnt(0)
	v_mfma_f32_16x16x32_bf16 v[60:63], v[146:149], v[174:177], v[60:63]
	v_mfma_f32_16x16x32_bf16 v[56:59], v[160:163], v[174:177], v[56:59]
	v_mfma_f32_16x16x32_bf16 v[44:47], v[146:149], v[182:185], v[44:47]
	v_mfma_f32_16x16x32_bf16 v[40:43], v[160:163], v[182:185], v[40:43]
	v_mfma_f32_16x16x32_bf16 v[28:31], v[146:149], v[190:193], v[28:31]
	v_mfma_f32_16x16x32_bf16 v[24:27], v[160:163], v[190:193], v[24:27]
	v_mfma_f32_16x16x32_bf16 v[12:15], v[146:149], v[198:201], v[12:15]
	v_mfma_f32_16x16x32_bf16 v[8:11], v[160:163], v[198:201], v[8:11]
	v_mfma_f32_16x16x32_bf16 v[60:63], v[150:153], v[178:181], v[60:63]
	v_mfma_f32_16x16x32_bf16 v[56:59], v[170:173], v[178:181], v[56:59]
	v_mfma_f32_16x16x32_bf16 v[44:47], v[150:153], v[186:189], v[44:47]
	v_mfma_f32_16x16x32_bf16 v[40:43], v[170:173], v[186:189], v[40:43]
	v_mfma_f32_16x16x32_bf16 v[28:31], v[150:153], v[194:197], v[28:31]
	v_mfma_f32_16x16x32_bf16 v[24:27], v[170:173], v[194:197], v[24:27]
	v_mfma_f32_16x16x32_bf16 v[12:15], v[150:153], v[202:205], v[12:15]
	v_mfma_f32_16x16x32_bf16 v[8:11], v[170:173], v[202:205], v[8:11]
	s_setprio 0
	s_barrier
; #define PG8_STAGE(bufoff, gbase, voff) do { _Pragma("unroll") for (int _i = 0; _i < 2; ++_i) \
;         __builtin_amdgcn_global_load_lds((const unsigned*)((const char*)(gbase) + (voff)[_i]), (LAS unsigned*)(lds + (bufoff) + ldsw + _i * 8192), 16, 0, 0); } while (0)
; #define PG8_LDA(dst, b, h) do { _Pragma("unroll") for (int m = 0; m < 4; ++m) _Pragma("unroll") for (int k = 0; k < 2; ++k) dst[m][k] = *(const LAS bf16x8*)(lds + PG8_SA(b, h) + aoff + m * 2048 + k * 1024); } while (0)
; #define PG8_LDB(dst, b, h) do { _Pragma("unroll") for (int n = 0; n < 2; ++n) _Pragma("unroll") for (int k = 0; k < 2; ++k) dst[n][k] = *(const LAS bf16x8*)(lds + PG8_SB(b, h) + boff + n * 2048 + k * 1024); } while (0)
; #define PG8_MMA(ai, bj, At, Bt) do { __builtin_amdgcn_s_setprio(1); _Pragma("unroll") for (int m = 0; m < 4; ++m) _Pragma("unroll") for (int n = 0; n < 2; ++n) _Pragma("unroll") for (int k = 0; k < 2; ++k) \
;         acc[ai][bj][m][n] = __builtin_amdgcn_mfma_f32_16x16x32_bf16(Bt[n][k], At[m][k], acc[ai][bj][m][n], 0, 0, 0); __builtin_amdgcn_s_setprio(0); } while (0)
; #define PG8_WAIT_V(n) asm volatile("s_waitcnt vmcnt(" #n ")" ::: "memory")
; #define PG8_WAIT_L(n) asm volatile("s_waitcnt lgkmcnt(" #n ")" ::: "memory")
; #define PG8_BAR __builtin_amdgcn_s_barrier()
; #define PG8_SCHED __builtin_amdgcn_sched_barrier(0)
;     ...
;             PG8_STAGE(PG8_SB(0, 1), b2 + hB, voffB);
;             PG8_WAIT_V(6); PG8_BAR; PG8_MMA(1, 1, At, B1); PG8_BAR;
;             PG8_LDB(B0, 1, 0); PG8_SCHED; PG8_LDA(At, 1, 0); PG8_STAGE(PG8_SA(0, 1), a2 + hA, voffA);
;             PG8_WAIT_L(8); PG8_BAR; PG8_WAIT_L(0); PG8_MMA(0, 0, At, B0); PG8_BAR; PG8_SCHED;
;             PG8_LDB(B1, 1, 1); PG8_STAGE(PG8_SB(1, 0), b3, voffB);
;             PG8_BAR; PG8_WAIT_L(0); PG8_MMA(0, 1, At, B1); PG8_BAR;
;             PG8_LDA(At, 1, 1); PG8_STAGE(PG8_SA(1, 0), a3, voffA);
;             PG8_BAR; PG8_WAIT_L(0); PG8_MMA(1, 0, At, B0); PG8_BAR; PG8_SCHED;
	s_add_u32 s12, s14, 0x20000
	s_addc_u32 s13, s15, 0
	s_add_i32 s61, s56, s35
	v_lshl_add_u64 v[146:147], s[12:13], 0, v[132:133]
	s_mov_b32 m0, s61
	s_nop 0
	global_load_lds_dwordx4 v[146:147], off
	v_lshl_add_u64 v[146:147], s[12:13], 0, v[128:129]
	s_add_i32 m0, s61, 0x2000
	s_nop 0
	global_load_lds_dwordx4 v[146:147], off
	s_waitcnt vmcnt(6)
	s_barrier
	s_setprio 1
	v_mfma_f32_16x16x32_bf16 v[52:55], v[206:209], v[174:177], v[52:55]
	v_mfma_f32_16x16x32_bf16 v[48:51], v[214:217], v[174:177], v[48:51]
	v_mfma_f32_16x16x32_bf16 v[36:39], v[206:209], v[182:185], v[36:39]
	v_mfma_f32_16x16x32_bf16 v[32:35], v[214:217], v[182:185], v[32:35]
	v_mfma_f32_16x16x32_bf16 v[20:23], v[206:209], v[190:193], v[20:23]
	v_mfma_f32_16x16x32_bf16 v[16:19], v[214:217], v[190:193], v[16:19]
	v_mfma_f32_16x16x32_bf16 v[4:7], v[206:209], v[198:201], v[4:7]
	v_mfma_f32_16x16x32_bf16 v[0:3], v[214:217], v[198:201], v[0:3]
	v_mfma_f32_16x16x32_bf16 v[52:55], v[210:213], v[178:181], v[52:55]
	v_mfma_f32_16x16x32_bf16 v[48:51], v[218:221], v[178:181], v[48:51]
	v_mfma_f32_16x16x32_bf16 v[36:39], v[210:213], v[186:189], v[36:39]
	v_mfma_f32_16x16x32_bf16 v[32:35], v[218:221], v[186:189], v[32:35]
	v_mfma_f32_16x16x32_bf16 v[20:23], v[210:213], v[194:197], v[20:23]
	v_mfma_f32_16x16x32_bf16 v[16:19], v[218:221], v[194:197], v[16:19]
	v_mfma_f32_16x16x32_bf16 v[4:7], v[210:213], v[202:205], v[4:7]
	v_mfma_f32_16x16x32_bf16 v[0:3], v[218:221], v[202:205], v[0:3]
	s_setprio 0
	s_add_i32 s61, 0, 0x18000
	v_add_u32_e32 v169, s61, v155
	s_barrier
	ds_read_b128 v[146:149], v169
	ds_read_b128 v[150:153], v169 offset:1024
	ds_read_b128 v[160:163], v169 offset:2048
	ds_read_b128 v[170:173], v169 offset:3072
	s_add_u32 s12, s16, 0x110000
	s_addc_u32 s13, s17, 0
	s_mov_b32 m0, s41
	v_lshl_add_u64 v[206:207], s[12:13], 0, v[134:135]
	ds_read_b128 v[174:177], v158 offset:32768
	ds_read_b128 v[178:181], v158 offset:33792
	ds_read_b128 v[182:185], v158 offset:34816
	ds_read_b128 v[186:189], v158 offset:35840
	ds_read_b128 v[190:193], v158 offset:36864
	ds_read_b128 v[194:197], v158 offset:37888
	ds_read_b128 v[198:201], v158 offset:38912
	ds_read_b128 v[202:205], v158 offset:39936
	global_load_lds_dwordx4 v[206:207], off
	v_lshl_add_u64 v[206:207], s[12:13], 0, v[130:131]
	s_mov_b32 m0, s42
	s_nop 0
	global_load_lds_dwordx4 v[206:207], off
	s_waitcnt lgkmcnt(8)
	s_barrier
	s_waitcnt lgkmcnt(0)
	s_setprio 1
	s_waitcnt lgkmcnt(0)
	v_mfma_f32_16x16x32_bf16 v[124:127], v[146:149], v[174:177], v[124:127]
	v_mfma_f32_16x16x32_bf16 v[120:123], v[160:163], v[174:177], v[120:123]
	v_mfma_f32_16x16x32_bf16 v[108:111], v[146:149], v[182:185], v[108:111]
	v_mfma_f32_16x16x32_bf16 v[104:107], v[160:163], v[182:185], v[104:107]
	v_mfma_f32_16x16x32_bf16 v[92:95], v[146:149], v[190:193], v[92:95]
	v_mfma_f32_16x16x32_bf16 v[88:91], v[160:163], v[190:193], v[88:91]
	v_mfma_f32_16x16x32_bf16 v[76:79], v[146:149], v[198:201], v[76:79]
	v_mfma_f32_16x16x32_bf16 v[72:75], v[160:163], v[198:201], v[72:75]
	v_mfma_f32_16x16x32_bf16 v[124:127], v[150:153], v[178:181], v[124:127]
	v_mfma_f32_16x16x32_bf16 v[120:123], v[170:173], v[178:181], v[120:123]
	v_mfma_f32_16x16x32_bf16 v[108:111], v[150:153], v[186:189], v[108:111]
	v_mfma_f32_16x16x32_bf16 v[104:107], v[170:173], v[186:189], v[104:107]
	v_mfma_f32_16x16x32_bf16 v[92:95], v[150:153], v[194:197], v[92:95]
	v_mfma_f32_16x16x32_bf16 v[88:91], v[170:173], v[194:197], v[88:91]
	v_mfma_f32_16x16x32_bf16 v[76:79], v[150:153], v[202:205], v[76:79]
	v_mfma_f32_16x16x32_bf16 v[72:75], v[170:173], v[202:205], v[72:75]
	s_setprio 0
	s_barrier
	s_add_i32 s16, 0, 0x1c000
	s_add_i32 s12, s61, s35
	v_add_u32_e32 v169, s16, v155
	v_lshl_add_u64 v[164:165], v[164:165], 0, s[24:25]
	s_mov_b32 m0, s12
	ds_read_b128 v[206:209], v169
	ds_read_b128 v[210:213], v169 offset:1024
	ds_read_b128 v[214:217], v169 offset:2048
	ds_read_b128 v[218:221], v169 offset:3072
	global_load_lds_dwordx4 v[164:165], off
	v_lshl_add_u64 v[164:165], v[222:223], 0, s[24:25]
	s_add_i32 m0, s12, 0x2000
	s_nop 0
	global_load_lds_dwordx4 v[164:165], off
	s_barrier
	s_waitcnt lgkmcnt(0)
	s_setprio 1
	s_waitcnt lgkmcnt(0)
	v_mfma_f32_16x16x32_bf16 v[116:119], v[206:209], v[174:177], v[116:119]
	v_mfma_f32_16x16x32_bf16 v[112:115], v[214:217], v[174:177], v[112:115]
	v_mfma_f32_16x16x32_bf16 v[100:103], v[206:209], v[182:185], v[100:103]
	v_mfma_f32_16x16x32_bf16 v[96:99], v[214:217], v[182:185], v[96:99]
	v_mfma_f32_16x16x32_bf16 v[84:87], v[206:209], v[190:193], v[84:87]
	v_mfma_f32_16x16x32_bf16 v[80:83], v[214:217], v[190:193], v[80:83]
	v_mfma_f32_16x16x32_bf16 v[68:71], v[206:209], v[198:201], v[68:71]
	v_mfma_f32_16x16x32_bf16 v[64:67], v[214:217], v[198:201], v[64:67]
	v_mfma_f32_16x16x32_bf16 v[116:119], v[210:213], v[178:181], v[116:119]
	v_mfma_f32_16x16x32_bf16 v[112:115], v[218:221], v[178:181], v[112:115]
	v_mfma_f32_16x16x32_bf16 v[100:103], v[210:213], v[186:189], v[100:103]
	v_mfma_f32_16x16x32_bf16 v[96:99], v[218:221], v[186:189], v[96:99]
	v_mfma_f32_16x16x32_bf16 v[84:87], v[210:213], v[194:197], v[84:87]
	v_mfma_f32_16x16x32_bf16 v[80:83], v[218:221], v[194:197], v[80:83]
	v_mfma_f32_16x16x32_bf16 v[68:71], v[210:213], v[202:205], v[68:71]
	v_mfma_f32_16x16x32_bf16 v[64:67], v[218:221], v[202:205], v[64:67]
	s_setprio 0
	s_mov_b32 m0, s52
	v_lshl_add_u64 v[164:165], v[224:225], 0, s[24:25]
	s_barrier
	ds_read_b128 v[174:177], v158 offset:49152
	ds_read_b128 v[178:181], v158 offset:50176
	ds_read_b128 v[182:185], v158 offset:51200
	ds_read_b128 v[186:189], v158 offset:52224
	ds_read_b128 v[190:193], v158 offset:53248
	ds_read_b128 v[194:197], v158 offset:54272
	ds_read_b128 v[198:201], v158 offset:55296
	ds_read_b128 v[202:205], v158 offset:56320
	global_load_lds_dwordx4 v[164:165], off
	v_lshl_add_u64 v[164:165], v[226:227], 0, s[24:25]
	s_mov_b32 m0, s53
	s_nop 0
	global_load_lds_dwordx4 v[164:165], off
	s_barrier
; __device__ __forceinline__ float sigmoidf_(float x) { return 1.0f / (1.0f + __expf(-x)); }
; #define PG8_STAGE(bufoff, gbase, voff) do { _Pragma("unroll") for (int _i = 0; _i < 2; ++_i) \
;         __builtin_amdgcn_global_load_lds((const unsigned*)((const char*)(gbase) + (voff)[_i]), (LAS unsigned*)(lds + (bufoff) + ldsw + _i * 8192), 16, 0, 0); } while (0)
; #define PG8_MMA(ai, bj, At, Bt) do { __builtin_amdgcn_s_setprio(1); _Pragma("unroll") for (int m = 0; m < 4; ++m) _Pragma("unroll") for (int n = 0; n < 2; ++n) _Pragma("unroll") for (int k = 0; k < 2; ++k) \
;         acc[ai][bj][m][n] = __builtin_amdgcn_mfma_f32_16x16x32_bf16(Bt[n][k], At[m][k], acc[ai][bj][m][n], 0, 0, 0); __builtin_amdgcn_s_setprio(0); } while (0)
; #define PG8_WAIT_V(n) asm volatile("s_waitcnt vmcnt(" #n ")" ::: "memory")
; #define PG8_WAIT_L(n) asm volatile("s_waitcnt lgkmcnt(" #n ")" ::: "memory")
; #define PG8_BAR __builtin_amdgcn_s_barrier()
; #define PG8_SCHED __builtin_amdgcn_sched_barrier(0)
; __device__ __forceinline__ void unpack8(const u32x4 w, f32x4& v0, f32x4& v1) { v0 = (f32x4){bflo(w.x), bfhi(w.x), bflo(w.y), bfhi(w.y)}; v1 = (f32x4){bflo(w.z), bfhi(w.z), bflo(w.w), bfhi(w.w)}; }
;     ...
;             PG8_BAR; PG8_WAIT_L(0); PG8_MMA(1, 0, At, B0); PG8_BAR; PG8_SCHED;
;             PG8_STAGE(PG8_SB(1, 1), b3 + hB, voffB);
;             PG8_WAIT_V(6); PG8_BAR; PG8_MMA(1, 1, At, B1); PG8_BAR;
;         }
;     __device__ __forceinline__ void operator()(const f32x4 (&acc)[2][2][4][2], const Unit& u, int wr, int wc, int fr, int fq) const {
;         const int row0 = u.pm * 256 + wr * 64 + fr, col0 = u.pn * 256 + wc * 32 + 8 * fq;
; #pragma unroll
;         for (int ai = 0; ai < 2; ++ai)
; #pragma unroll
;             for (int m = 0; m < 4; ++m) {
;                 bf16_t* rowp = z + (size_t)(row0 + ai * 128 + m * 16) * DIN + col0;
; #pragma unroll
;                 for (int bj = 0; bj < 2; ++bj) {
;                     const u32x4 gw = *(const u32x4*)(rowp + (MODE == 0 ? O_GB : O_GA) + bj * 128);
;                     f32x4 g0, g1; unpack8(gw, g0, g1);
;                     f32x4 v0, v1;
; #pragma unroll
;                     for (int j = 0; j < 4; ++j) { v0[j] = sigmoidf_(g0[j]) * acc[ai][bj][m][0][j]; v1[j] = sigmoidf_(g1[j]) * acc[ai][bj][m][1][j]; }
	s_waitcnt lgkmcnt(0)
	s_setprio 1
	s_waitcnt lgkmcnt(0)
	v_mfma_f32_16x16x32_bf16 v[60:63], v[146:149], v[174:177], v[60:63]
	v_mfma_f32_16x16x32_bf16 v[56:59], v[160:163], v[174:177], v[56:59]
	v_mfma_f32_16x16x32_bf16 v[44:47], v[146:149], v[182:185], v[44:47]
	v_mfma_f32_16x16x32_bf16 v[40:43], v[160:163], v[182:185], v[40:43]
	v_mfma_f32_16x16x32_bf16 v[28:31], v[146:149], v[190:193], v[28:31]
	v_mfma_f32_16x16x32_bf16 v[24:27], v[160:163], v[190:193], v[24:27]
	v_mfma_f32_16x16x32_bf16 v[12:15], v[146:149], v[198:201], v[12:15]
	v_mfma_f32_16x16x32_bf16 v[8:11], v[160:163], v[198:201], v[8:11]
	v_mfma_f32_16x16x32_bf16 v[60:63], v[150:153], v[178:181], v[60:63]
	v_mfma_f32_16x16x32_bf16 v[56:59], v[170:173], v[178:181], v[56:59]
	v_mfma_f32_16x16x32_bf16 v[44:47], v[150:153], v[186:189], v[44:47]
	v_mfma_f32_16x16x32_bf16 v[40:43], v[170:173], v[186:189], v[40:43]
	v_mfma_f32_16x16x32_bf16 v[28:31], v[150:153], v[194:197], v[28:31]
	v_mfma_f32_16x16x32_bf16 v[24:27], v[170:173], v[194:197], v[24:27]
	v_mfma_f32_16x16x32_bf16 v[12:15], v[150:153], v[202:205], v[12:15]
	v_mfma_f32_16x16x32_bf16 v[8:11], v[170:173], v[202:205], v[8:11]
	s_setprio 0
	s_barrier
	s_add_u32 s12, s14, 0x20080
	s_addc_u32 s13, s15, 0
	s_add_i32 s14, s16, s35
	v_lshl_add_u64 v[146:147], s[12:13], 0, v[132:133]
	s_mov_b32 m0, s14
	s_nop 0
	global_load_lds_dwordx4 v[146:147], off
	v_lshl_add_u64 v[146:147], s[12:13], 0, v[128:129]
	s_add_i32 m0, s14, 0x2000
	s_nop 0
	global_load_lds_dwordx4 v[146:147], off
	s_waitcnt vmcnt(6)
	s_barrier
	s_setprio 1
	v_mfma_f32_16x16x32_bf16 v[52:55], v[206:209], v[174:177], v[52:55]
	v_mfma_f32_16x16x32_bf16 v[48:51], v[214:217], v[174:177], v[48:51]
	v_mfma_f32_16x16x32_bf16 v[36:39], v[206:209], v[182:185], v[36:39]
	v_mfma_f32_16x16x32_bf16 v[32:35], v[214:217], v[182:185], v[32:35]
	v_mfma_f32_16x16x32_bf16 v[20:23], v[206:209], v[190:193], v[20:23]
	v_mfma_f32_16x16x32_bf16 v[16:19], v[214:217], v[190:193], v[16:19]
	v_mfma_f32_16x16x32_bf16 v[4:7], v[206:209], v[198:201], v[4:7]
	v_mfma_f32_16x16x32_bf16 v[0:3], v[214:217], v[198:201], v[0:3]
	v_mfma_f32_16x16x32_bf16 v[52:55], v[210:213], v[178:181], v[52:55]
	v_mfma_f32_16x16x32_bf16 v[48:51], v[218:221], v[178:181], v[48:51]
	v_mfma_f32_16x16x32_bf16 v[36:39], v[210:213], v[186:189], v[36:39]
	v_mfma_f32_16x16x32_bf16 v[32:35], v[218:221], v[186:189], v[32:35]
	v_mfma_f32_16x16x32_bf16 v[20:23], v[210:213], v[194:197], v[20:23]
	v_mfma_f32_16x16x32_bf16 v[16:19], v[218:221], v[194:197], v[16:19]
	v_mfma_f32_16x16x32_bf16 v[4:7], v[210:213], v[202:205], v[4:7]
	v_mfma_f32_16x16x32_bf16 v[0:3], v[218:221], v[202:205], v[0:3]
	s_setprio 0
	s_add_i32 s60, s60, 2
	s_add_u32 s44, s44, 0x100
	s_addc_u32 s45, s45, 0
	s_cmp_gt_u32 s60, 5
	s_mov_b64 s[12:13], s[10:11]
	s_barrier
	s_cbranch_scc0 .LBB0_1768
	v_lshl_or_b32 v148, s7, 8, v156
	v_lshl_add_u32 v160, s6, 8, v154
	v_ashrrev_i32_e32 v149, 31, v148
	v_mov_b64_e32 v[146:147], s[22:23]
	v_mad_i64_i32 v[150:151], s[6:7], v160, s57, v[146:147]
	v_lshlrev_b64 v[148:149], 1, v[148:149]
	v_lshl_add_u64 v[150:151], v[150:151], 0, v[148:149]
	v_add_co_u32_e32 v152, vcc, 0x1000, v150
	s_nop 1
	v_addc_co_u32_e32 v153, vcc, 0, v151, vcc
	v_subrev_u32_e32 v197, s22, v150
	v_add_u32_e32 v198, 0x1a00, v197
	global_load_dwordx4 v[200:203], v198, s[22:23]
	v_add_u32_e32 v198, 0x1b00, v197
	global_load_dwordx4 v[204:207], v198, s[22:23]
	v_add_u32_e32 v198, 0x23a00, v197
	global_load_dwordx4 v[208:211], v198, s[22:23]
	v_add_u32_e32 v198, 0x23b00, v197
	global_load_dwordx4 v[212:215], v198, s[22:23]
	v_add_u32_e32 v198, 0x45a00, v197
	global_load_dwordx4 v[216:219], v198, s[22:23]
	v_add_u32_e32 v198, 0x45b00, v197
	global_load_dwordx4 v[232:235], v198, s[22:23]
	v_add_u32_e32 v198, 0x67a00, v197
	global_load_dwordx4 v[236:239], v198, s[22:23]
	v_add_u32_e32 v198, 0x67b00, v197
	global_load_dwordx4 v[240:243], v198, s[22:23]
	v_add_u32_e32 v198, 0x111a00, v197
	global_load_dwordx4 v[244:247], v198, s[22:23]
	v_add_u32_e32 v198, 0x111b00, v197
	global_load_dwordx4 v[248:251], v198, s[22:23]
	v_add_u32_e32 v198, 0x133a00, v197
	global_load_dwordx4 v[252:255], v198, s[22:23]
	s_waitcnt vmcnt(10)
	v_mov_b32_e32 v162, v200
	v_mov_b32_e32 v163, v201
	v_mov_b32_e32 v164, v202
	v_mov_b32_e32 v165, v203
	v_add_u32_e32 v198, 0x133b00, v197
	global_load_dwordx4 v[200:203], v198, s[22:23]
	v_lshlrev_b32_e32 v161, 16, v162
	v_lshlrev_b32_e32 v170, 16, v164
	v_mul_f32_e32 v161, 0xbfb8aa3b, v161
	v_and_b32_e32 v162, 0xffff0000, v162
	v_mul_f32_e32 v170, 0xbfb8aa3b, v170
	v_exp_f32_e32 v161, v161
	v_and_b32_e32 v164, 0xffff0000, v164
	v_mul_f32_e32 v162, 0xbfb8aa3b, v162
	v_exp_f32_e32 v170, v170
	v_mul_f32_e32 v164, 0xbfb8aa3b, v164
	v_exp_f32_e32 v162, v162
	v_exp_f32_e32 v164, v164
	v_add_f32_e32 v161, 1.0, v161
	v_add_f32_e32 v170, 1.0, v170
	v_div_scale_f32 v172, s[6:7], v161, v161, 1.0
	v_add_f32_e32 v162, 1.0, v162
	v_div_scale_f32 v174, s[6:7], v170, v170, 1.0
	v_rcp_f32_e32 v182, v172
	v_lshlrev_b32_e32 v169, 16, v163
	v_add_f32_e32 v164, 1.0, v164
	v_div_scale_f32 v176, s[6:7], v162, v162, 1.0
	v_rcp_f32_e32 v183, v174
	v_mul_f32_e32 v169, 0xbfb8aa3b, v169
	v_div_scale_f32 v178, s[6:7], v164, v164, 1.0
	v_rcp_f32_e32 v184, v176
	v_exp_f32_e32 v169, v169
	v_rcp_f32_e32 v185, v178
	v_fma_f32 v187, -v172, v182, 1.0
	v_div_scale_f32 v173, vcc, 1.0, v161, 1.0
	v_fma_f32 v188, -v174, v183, 1.0
	v_fmac_f32_e32 v182, v187, v182
	v_div_scale_f32 v175, s[10:11], 1.0, v170, 1.0
	v_fma_f32 v189, -v176, v184, 1.0
	v_fmac_f32_e32 v183, v188, v183
	v_mul_f32_e32 v187, v173, v182
	v_add_f32_e32 v169, 1.0, v169
	v_div_scale_f32 v177, s[12:13], 1.0, v162, 1.0
; __device__ __forceinline__ float sigmoidf_(float x) { return 1.0f / (1.0f + __expf(-x)); }
; __device__ __forceinline__ u32x4 pack8(const f32x4 v0, const f32x4 v1) { u32x4 w; w.x = pk2(v0[0], v0[1]); w.y = pk2(v0[2], v0[3]); w.z = pk2(v1[0], v1[1]); w.w = pk2(v1[2], v1[3]); return w; }
; __device__ __forceinline__ void unpack8(const u32x4 w, f32x4& v0, f32x4& v1) { v0 = (f32x4){bflo(w.x), bfhi(w.x), bflo(w.y), bfhi(w.y)}; v1 = (f32x4){bflo(w.z), bfhi(w.z), bflo(w.w), bfhi(w.w)}; }
;     __device__ __forceinline__ void operator()(const f32x4 (&acc)[2][2][4][2], const Unit& u, int wr, int wc, int fr, int fq) const {
;     ...
;         for (int ai = 0; ai < 2; ++ai)
; #pragma unroll
;             for (int m = 0; m < 4; ++m) {
;                 bf16_t* rowp = z + (size_t)(row0 + ai * 128 + m * 16) * DIN + col0;
; #pragma unroll
;                 for (int bj = 0; bj < 2; ++bj) {
;                     const u32x4 gw = *(const u32x4*)(rowp + (MODE == 0 ? O_GB : O_GA) + bj * 128);
;                     f32x4 g0, g1; unpack8(gw, g0, g1);
;                     f32x4 v0, v1;
; #pragma unroll
;                     for (int j = 0; j < 4; ++j) { v0[j] = sigmoidf_(g0[j]) * acc[ai][bj][m][0][j]; v1[j] = sigmoidf_(g1[j]) * acc[ai][bj][m][1][j]; }
;                     if (MODE == 1) { const u32x4 mw = *(const u32x4*)(rowp + bj * 128); f32x4 m0, m1; unpack8(mw, m0, m1); v0 += m0; v1 += m1; }
;                     *(u32x4*)(rowp + bj * 128) = pack8(v0, v1); }
	v_fma_f32 v190, -v178, v185, 1.0
	v_fmac_f32_e32 v184, v189, v184
	v_mul_f32_e32 v188, v175, v183
	v_fma_f32 v192, -v172, v187, v173
	v_div_scale_f32 v179, s[14:15], 1.0, v164, 1.0
	v_div_scale_f32 v180, s[6:7], v169, v169, 1.0
	v_fmac_f32_e32 v185, v190, v185
	v_mul_f32_e32 v189, v177, v184
	v_fma_f32 v193, -v174, v188, v175
	v_fmac_f32_e32 v187, v192, v182
	v_lshlrev_b32_e32 v171, 16, v165
	v_rcp_f32_e32 v186, v180
	v_mul_f32_e32 v190, v179, v185
	v_fma_f32 v194, -v176, v189, v177
	v_fmac_f32_e32 v188, v193, v183
	v_fma_f32 v172, -v172, v187, v173
	v_mul_f32_e32 v171, 0xbfb8aa3b, v171
	v_fma_f32 v195, -v178, v190, v179
	v_fmac_f32_e32 v189, v194, v184
	v_fma_f32 v173, -v174, v188, v175
	v_div_fmas_f32 v172, v172, v182, v187
	s_mov_b64 vcc, s[10:11]
	v_exp_f32_e32 v171, v171
	v_fmac_f32_e32 v190, v195, v185
	v_fma_f32 v174, -v176, v189, v177
	v_div_fixup_f32 v161, v172, v161, 1.0
	v_div_fmas_f32 v172, v173, v183, v188
	s_mov_b64 vcc, s[12:13]
	v_fma_f32 v175, -v178, v190, v179
	v_mul_f32_e32 v124, v124, v161
	v_div_fixup_f32 v161, v172, v170, 1.0
	v_div_fmas_f32 v170, v174, v184, v189
	s_mov_b64 vcc, s[14:15]
	v_fma_f32 v191, -v180, v186, 1.0
	v_mul_f32_e32 v161, v120, v161
	v_div_fixup_f32 v120, v170, v162, 1.0
	v_div_fmas_f32 v162, v175, v185, v190
	v_div_scale_f32 v181, s[16:17], 1.0, v169, 1.0
	v_fmac_f32_e32 v186, v191, v186
	v_mul_f32_e32 v120, v125, v120
	v_div_fixup_f32 v125, v162, v164, 1.0
	v_mul_f32_e32 v191, v181, v186
	v_mul_f32_e32 v125, v121, v125
	v_add_f32_e32 v121, 1.0, v171
	v_fma_f32 v196, -v180, v191, v181
	v_div_scale_f32 v162, s[6:7], v121, v121, 1.0
	v_fmac_f32_e32 v191, v196, v186
	v_rcp_f32_e32 v164, v162
	v_fma_f32 v176, -v180, v191, v181
	s_mov_b64 vcc, s[16:17]
	v_and_b32_e32 v163, 0xffff0000, v163
	v_div_fmas_f32 v170, v176, v186, v191
	v_div_fixup_f32 v169, v170, v169, 1.0
	v_mul_f32_e32 v163, 0xbfb8aa3b, v163
	v_mul_f32_e32 v126, v126, v169
	v_fma_f32 v169, -v162, v164, 1.0
	v_exp_f32_e32 v163, v163
	v_fmac_f32_e32 v164, v169, v164
	v_div_scale_f32 v169, vcc, 1.0, v121, 1.0
	v_mul_f32_e32 v170, v169, v164
	v_fma_f32 v171, -v162, v170, v169
	v_fmac_f32_e32 v170, v171, v164
	v_add_f32_e32 v163, 1.0, v163
	v_fma_f32 v162, -v162, v170, v169
	v_div_scale_f32 v169, s[6:7], v163, v163, 1.0
	v_rcp_f32_e32 v171, v169
	v_and_b32_e32 v165, 0xffff0000, v165
	v_div_fmas_f32 v162, v162, v164, v170
	v_mul_f32_e32 v164, 0xbfb8aa3b, v165
	v_div_fixup_f32 v121, v162, v121, 1.0
	v_exp_f32_e32 v164, v164
	v_mul_f32_e32 v162, v122, v121
	v_fma_f32 v121, -v169, v171, 1.0
	v_fmac_f32_e32 v171, v121, v171
	v_div_scale_f32 v121, vcc, 1.0, v163, 1.0
	v_mul_f32_e32 v122, v121, v171
	v_fma_f32 v165, -v169, v122, v121
	v_add_f32_e32 v164, 1.0, v164
	v_fmac_f32_e32 v122, v165, v171
	v_div_scale_f32 v165, s[6:7], v164, v164, 1.0
	v_fma_f32 v121, -v169, v122, v121
	v_rcp_f32_e32 v169, v165
	v_div_fmas_f32 v121, v121, v171, v122
	v_div_fixup_f32 v121, v121, v163, 1.0
	v_mul_f32_e32 v121, v127, v121
	v_fma_f32 v122, -v165, v169, 1.0
	v_fmac_f32_e32 v169, v122, v169
	v_div_scale_f32 v122, vcc, 1.0, v164, 1.0
	v_mul_f32_e32 v127, v122, v169
	v_fma_f32 v163, -v165, v127, v122
	v_fmac_f32_e32 v127, v163, v169
	v_fma_f32 v122, -v165, v127, v122
	v_div_fmas_f32 v122, v122, v169, v127
	v_div_fixup_f32 v122, v122, v164, 1.0
	v_mul_f32_e32 v123, v123, v122
	v_cvt_pk_bf16_f32 v120, v124, v120
	v_cvt_pk_bf16_f32 v121, v126, v121
	v_cvt_pk_bf16_f32 v122, v161, v125
	v_cvt_pk_bf16_f32 v123, v162, v123
	s_mov_b64 s[14:15], s[30:31]
	global_store_dwordx4 v[150:151], v[120:123], off sc1
	s_mov_b64 s[12:13], s[28:29]
	s_waitcnt vmcnt(11)
	v_mov_b32_e32 v124, v204
	v_mov_b32_e32 v125, v205
	v_mov_b32_e32 v126, v206
	v_mov_b32_e32 v127, v207
	v_add_u32_e32 v198, 0x155a00, v197
	global_load_dwordx4 v[204:207], v198, s[22:23]
	v_lshlrev_b32_e32 v120, 16, v124
	v_mul_f32_e32 v120, 0xbfb8aa3b, v120
	v_exp_f32_e32 v120, v120
	v_and_b32_e32 v121, 0xffff0000, v124
	v_lshlrev_b32_e32 v124, 16, v126
	v_mul_f32_e32 v124, 0xbfb8aa3b, v124
	v_add_f32_e32 v120, 1.0, v120
	v_exp_f32_e32 v124, v124
	v_div_scale_f32 v152, s[6:7], v120, v120, 1.0
	v_rcp_f32_e32 v162, v152
	v_add_f32_e32 v124, 1.0, v124
	v_div_scale_f32 v161, s[6:7], v124, v124, 1.0
	v_fma_f32 v165, -v152, v162, 1.0
	v_div_scale_f32 v153, vcc, 1.0, v120, 1.0
	v_rcp_f32_e32 v163, v161
	v_fmac_f32_e32 v162, v165, v162
	v_mul_f32_e32 v121, 0xbfb8aa3b, v121
	v_mul_f32_e32 v165, v153, v162
	v_exp_f32_e32 v121, v121
	v_fma_f32 v170, -v152, v165, v153
	v_fmac_f32_e32 v165, v170, v162
	v_fma_f32 v169, -v161, v163, 1.0
	v_fma_f32 v152, -v152, v165, v153
	v_div_scale_f32 v164, s[10:11], 1.0, v124, 1.0
	v_fmac_f32_e32 v163, v169, v163
	v_div_fmas_f32 v152, v152, v162, v165
	v_add_f32_e32 v121, 1.0, v121
	v_mul_f32_e32 v169, v164, v163
	v_div_fixup_f32 v120, v152, v120, 1.0
	v_fma_f32 v171, -v161, v169, v164
	v_mul_f32_e32 v116, v116, v120
	v_div_scale_f32 v120, s[6:7], v121, v121, 1.0
	v_fmac_f32_e32 v169, v171, v163
	v_rcp_f32_e32 v152, v120
	v_fma_f32 v153, -v161, v169, v164
	s_mov_b64 vcc, s[10:11]
	v_div_fmas_f32 v153, v153, v163, v169
	v_lshlrev_b32_e32 v122, 16, v125
	v_and_b32_e32 v123, 0xffff0000, v125
	v_and_b32_e32 v125, 0xffff0000, v126
	v_div_fixup_f32 v124, v153, v124, 1.0
	v_mul_f32_e32 v112, v112, v124
	v_fma_f32 v124, -v120, v152, 1.0
	v_mul_f32_e32 v125, 0xbfb8aa3b, v125
	v_fmac_f32_e32 v152, v124, v152
	v_div_scale_f32 v124, vcc, 1.0, v121, 1.0
	v_exp_f32_e32 v125, v125
	v_mul_f32_e32 v153, v124, v152
	v_fma_f32 v161, -v120, v153, v124
	v_fmac_f32_e32 v153, v161, v152
	v_fma_f32 v120, -v120, v153, v124
	v_add_f32_e32 v124, 1.0, v125
	v_div_scale_f32 v125, s[6:7], v124, v124, 1.0
	v_rcp_f32_e32 v161, v125
; __device__ __forceinline__ float sigmoidf_(float x) { return 1.0f / (1.0f + __expf(-x)); }
; __device__ __forceinline__ u32x4 pack8(const f32x4 v0, const f32x4 v1) { u32x4 w; w.x = pk2(v0[0], v0[1]); w.y = pk2(v0[2], v0[3]); w.z = pk2(v1[0], v1[1]); w.w = pk2(v1[2], v1[3]); return w; }
; __device__ __forceinline__ void unpack8(const u32x4 w, f32x4& v0, f32x4& v1) { v0 = (f32x4){bflo(w.x), bfhi(w.x), bflo(w.y), bfhi(w.y)}; v1 = (f32x4){bflo(w.z), bfhi(w.z), bflo(w.w), bfhi(w.w)}; }
;     __device__ __forceinline__ void operator()(const f32x4 (&acc)[2][2][4][2], const Unit& u, int wr, int wc, int fr, int fq) const {
;     ...
;         for (int ai = 0; ai < 2; ++ai)
; #pragma unroll
;             for (int m = 0; m < 4; ++m) {
;                 bf16_t* rowp = z + (size_t)(row0 + ai * 128 + m * 16) * DIN + col0;
; #pragma unroll
;                 for (int bj = 0; bj < 2; ++bj) {
;                     const u32x4 gw = *(const u32x4*)(rowp + (MODE == 0 ? O_GB : O_GA) + bj * 128);
;                     f32x4 g0, g1; unpack8(gw, g0, g1);
;                     f32x4 v0, v1;
; #pragma unroll
;                     for (int j = 0; j < 4; ++j) { v0[j] = sigmoidf_(g0[j]) * acc[ai][bj][m][0][j]; v1[j] = sigmoidf_(g1[j]) * acc[ai][bj][m][1][j]; }
;                     if (MODE == 1) { const u32x4 mw = *(const u32x4*)(rowp + bj * 128); f32x4 m0, m1; unpack8(mw, m0, m1); v0 += m0; v1 += m1; }
;                     *(u32x4*)(rowp + bj * 128) = pack8(v0, v1); }
	v_div_fmas_f32 v120, v120, v152, v153
	v_div_fixup_f32 v120, v120, v121, 1.0
	v_mul_f32_e32 v122, 0xbfb8aa3b, v122
	v_mul_f32_e32 v117, v117, v120
	v_fma_f32 v120, -v125, v161, 1.0
	v_exp_f32_e32 v122, v122
	v_fmac_f32_e32 v161, v120, v161
	v_div_scale_f32 v120, vcc, 1.0, v124, 1.0
	v_mul_f32_e32 v121, v120, v161
	v_fma_f32 v152, -v125, v121, v120
	v_fmac_f32_e32 v121, v152, v161
	v_add_f32_e32 v122, 1.0, v122
	v_fma_f32 v120, -v125, v121, v120
	v_div_scale_f32 v125, s[6:7], v122, v122, 1.0
	v_rcp_f32_e32 v152, v125
	v_lshlrev_b32_e32 v126, 16, v127
	v_div_fmas_f32 v120, v120, v161, v121
	v_div_fixup_f32 v120, v120, v124, 1.0
	v_mul_f32_e32 v124, 0xbfb8aa3b, v126
	v_mul_f32_e32 v113, v113, v120
	v_fma_f32 v120, -v125, v152, 1.0
	v_exp_f32_e32 v124, v124
	v_fmac_f32_e32 v152, v120, v152
	v_div_scale_f32 v120, vcc, 1.0, v122, 1.0
	v_mul_f32_e32 v121, v120, v152
	v_fma_f32 v126, -v125, v121, v120
	v_fmac_f32_e32 v121, v126, v152
	v_add_f32_e32 v124, 1.0, v124
	v_fma_f32 v120, -v125, v121, v120
	v_div_scale_f32 v125, s[6:7], v124, v124, 1.0
	v_rcp_f32_e32 v126, v125
	v_div_fmas_f32 v120, v120, v152, v121
	v_div_fixup_f32 v120, v120, v122, 1.0
	v_mul_f32_e32 v122, 0xbfb8aa3b, v123
	v_exp_f32_e32 v122, v122
	v_mul_f32_e32 v118, v118, v120
	v_fma_f32 v120, -v125, v126, 1.0
	v_fmac_f32_e32 v126, v120, v126
	v_div_scale_f32 v120, vcc, 1.0, v124, 1.0
	v_mul_f32_e32 v121, v120, v126
	v_fma_f32 v123, -v125, v121, v120
	v_add_f32_e32 v122, 1.0, v122
	v_fmac_f32_e32 v121, v123, v126
	v_div_scale_f32 v123, s[6:7], v122, v122, 1.0
	v_fma_f32 v120, -v125, v121, v120
	v_rcp_f32_e32 v125, v123
	v_div_fmas_f32 v120, v120, v126, v121
	v_and_b32_e32 v127, 0xffff0000, v127
	v_div_fixup_f32 v120, v120, v124, 1.0
	v_mul_f32_e32 v120, v114, v120
	v_fma_f32 v114, -v123, v125, 1.0
	v_mul_f32_e32 v124, 0xbfb8aa3b, v127
	v_fmac_f32_e32 v125, v114, v125
	v_div_scale_f32 v114, vcc, 1.0, v122, 1.0
	v_exp_f32_e32 v124, v124
	v_mul_f32_e32 v121, v114, v125
	v_fma_f32 v126, -v123, v121, v114
	v_fmac_f32_e32 v121, v126, v125
	v_fma_f32 v114, -v123, v121, v114
	v_add_f32_e32 v123, 1.0, v124
	v_div_scale_f32 v124, s[6:7], v123, v123, 1.0
	v_rcp_f32_e32 v126, v124
	v_div_fmas_f32 v114, v114, v125, v121
	v_div_fixup_f32 v114, v114, v122, 1.0
	v_mul_f32_e32 v119, v119, v114
	v_fma_f32 v114, -v124, v126, 1.0
	v_fmac_f32_e32 v126, v114, v126
	v_div_scale_f32 v114, vcc, 1.0, v123, 1.0
	v_mul_f32_e32 v121, v114, v126
	v_fma_f32 v122, -v124, v121, v114
	v_fmac_f32_e32 v121, v122, v126
	v_fma_f32 v114, -v124, v121, v114
	v_div_fmas_f32 v114, v114, v126, v121
	v_div_fixup_f32 v114, v114, v123, 1.0
	v_mul_f32_e32 v121, v115, v114
	v_cvt_pk_bf16_f32 v114, v116, v117
	v_cvt_pk_bf16_f32 v115, v118, v119
	v_cvt_pk_bf16_f32 v116, v112, v113
	v_or_b32_e32 v112, 16, v160
	v_mad_i64_i32 v[112:113], s[6:7], v112, s57, v[146:147]
	v_lshl_add_u64 v[112:113], v[112:113], 0, v[148:149]
	v_add_co_u32_e32 v122, vcc, s58, v112
	v_cvt_pk_bf16_f32 v117, v120, v121
	global_store_dwordx4 v[150:151], v[114:117], off offset:256 sc1
	s_nop 0
	v_addc_co_u32_e32 v123, vcc, 0, v113, vcc
	s_waitcnt vmcnt(12)
	v_mov_b32_e32 v118, v208
	v_mov_b32_e32 v119, v209
	v_mov_b32_e32 v120, v210
	v_mov_b32_e32 v121, v211
	v_add_u32_e32 v198, 0x155b00, v197
	global_load_dwordx4 v[208:211], v198, s[22:23]
	v_lshlrev_b32_e32 v114, 16, v118
	v_mul_f32_e32 v114, 0xbfb8aa3b, v114
	v_exp_f32_e32 v114, v114
	v_lshlrev_b32_e32 v116, 16, v119
	v_and_b32_e32 v117, 0xffff0000, v119
	v_and_b32_e32 v115, 0xffff0000, v118
	v_add_f32_e32 v114, 1.0, v114
	v_div_scale_f32 v119, s[6:7], v114, v114, 1.0
	v_rcp_f32_e32 v124, v119
	v_lshlrev_b32_e32 v118, 16, v120
	v_mul_f32_e32 v118, 0xbfb8aa3b, v118
	v_exp_f32_e32 v118, v118
	v_fma_f32 v126, -v119, v124, 1.0
	v_fmac_f32_e32 v124, v126, v124
	v_div_scale_f32 v126, vcc, 1.0, v114, 1.0
	v_mul_f32_e32 v127, v126, v124
	v_fma_f32 v150, -v119, v127, v126
	v_fmac_f32_e32 v127, v150, v124
	v_add_f32_e32 v118, 1.0, v118
	v_fma_f32 v119, -v119, v127, v126
	v_div_scale_f32 v126, s[6:7], v118, v118, 1.0
	v_rcp_f32_e32 v150, v126
	v_div_fmas_f32 v119, v119, v124, v127
	v_mul_f32_e32 v115, 0xbfb8aa3b, v115
	v_div_fixup_f32 v114, v119, v114, 1.0
	v_exp_f32_e32 v115, v115
	v_mul_f32_e32 v108, v108, v114
	v_fma_f32 v114, -v126, v150, 1.0
	v_fmac_f32_e32 v150, v114, v150
	v_div_scale_f32 v114, vcc, 1.0, v118, 1.0
	v_mul_f32_e32 v119, v114, v150
	v_fma_f32 v124, -v126, v119, v114
	v_add_f32_e32 v115, 1.0, v115
	v_fmac_f32_e32 v119, v124, v150
	v_div_scale_f32 v124, s[6:7], v115, v115, 1.0
	v_fma_f32 v114, -v126, v119, v114
	v_rcp_f32_e32 v126, v124
	v_and_b32_e32 v120, 0xffff0000, v120
	v_div_fmas_f32 v114, v114, v150, v119
	v_mul_f32_e32 v119, 0xbfb8aa3b, v120
	v_div_fixup_f32 v114, v114, v118, 1.0
	v_exp_f32_e32 v119, v119
	v_mul_f32_e32 v114, v104, v114
	v_fma_f32 v104, -v124, v126, 1.0
	v_fmac_f32_e32 v126, v104, v126
	v_div_scale_f32 v104, vcc, 1.0, v115, 1.0
	v_mul_f32_e32 v118, v104, v126
	v_fma_f32 v120, -v124, v118, v104
	v_add_f32_e32 v119, 1.0, v119
	v_fmac_f32_e32 v118, v120, v126
	v_div_scale_f32 v120, s[6:7], v119, v119, 1.0
	v_fma_f32 v104, -v124, v118, v104
	v_rcp_f32_e32 v124, v120
	v_div_fmas_f32 v104, v104, v126, v118
	v_mul_f32_e32 v116, 0xbfb8aa3b, v116
	v_div_fixup_f32 v104, v104, v115, 1.0
	v_exp_f32_e32 v116, v116
	v_mul_f32_e32 v104, v109, v104
	v_fma_f32 v109, -v120, v124, 1.0
	v_fmac_f32_e32 v124, v109, v124
	v_div_scale_f32 v109, vcc, 1.0, v119, 1.0
	v_mul_f32_e32 v115, v109, v124
	v_fma_f32 v118, -v120, v115, v109
	v_add_f32_e32 v116, 1.0, v116
	v_fmac_f32_e32 v115, v118, v124
	v_div_scale_f32 v118, s[6:7], v116, v116, 1.0
	v_fma_f32 v109, -v120, v115, v109
	v_rcp_f32_e32 v120, v118
; __device__ __forceinline__ float sigmoidf_(float x) { return 1.0f / (1.0f + __expf(-x)); }
; __device__ __forceinline__ u32x4 pack8(const f32x4 v0, const f32x4 v1) { u32x4 w; w.x = pk2(v0[0], v0[1]); w.y = pk2(v0[2], v0[3]); w.z = pk2(v1[0], v1[1]); w.w = pk2(v1[2], v1[3]); return w; }
; __device__ __forceinline__ void unpack8(const u32x4 w, f32x4& v0, f32x4& v1) { v0 = (f32x4){bflo(w.x), bfhi(w.x), bflo(w.y), bfhi(w.y)}; v1 = (f32x4){bflo(w.z), bfhi(w.z), bflo(w.w), bfhi(w.w)}; }
;     __device__ __forceinline__ void operator()(const f32x4 (&acc)[2][2][4][2], const Unit& u, int wr, int wc, int fr, int fq) const {
;     ...
;         for (int ai = 0; ai < 2; ++ai)
; #pragma unroll
;             for (int m = 0; m < 4; ++m) {
;                 bf16_t* rowp = z + (size_t)(row0 + ai * 128 + m * 16) * DIN + col0;
; #pragma unroll
;                 for (int bj = 0; bj < 2; ++bj) {
;                     const u32x4 gw = *(const u32x4*)(rowp + (MODE == 0 ? O_GB : O_GA) + bj * 128);
;                     f32x4 g0, g1; unpack8(gw, g0, g1);
;                     f32x4 v0, v1;
; #pragma unroll
;                     for (int j = 0; j < 4; ++j) { v0[j] = sigmoidf_(g0[j]) * acc[ai][bj][m][0][j]; v1[j] = sigmoidf_(g1[j]) * acc[ai][bj][m][1][j]; }
;                     if (MODE == 1) { const u32x4 mw = *(const u32x4*)(rowp + bj * 128); f32x4 m0, m1; unpack8(mw, m0, m1); v0 += m0; v1 += m1; }
;                     *(u32x4*)(rowp + bj * 128) = pack8(v0, v1); }
	v_div_fmas_f32 v109, v109, v124, v115
	v_lshlrev_b32_e32 v125, 16, v121
	v_div_fixup_f32 v109, v109, v119, 1.0
	v_mul_f32_e32 v109, v105, v109
	v_fma_f32 v105, -v118, v120, 1.0
	v_mul_f32_e32 v119, 0xbfb8aa3b, v125
	v_fmac_f32_e32 v120, v105, v120
	v_div_scale_f32 v105, vcc, 1.0, v116, 1.0
	v_exp_f32_e32 v119, v119
	v_mul_f32_e32 v115, v105, v120
	v_fma_f32 v124, -v118, v115, v105
	v_fmac_f32_e32 v115, v124, v120
	v_fma_f32 v105, -v118, v115, v105
	v_add_f32_e32 v118, 1.0, v119
	v_div_scale_f32 v119, s[6:7], v118, v118, 1.0
	v_rcp_f32_e32 v124, v119
	v_div_fmas_f32 v105, v105, v120, v115
	v_div_fixup_f32 v105, v105, v116, 1.0
	v_mul_f32_e32 v116, 0xbfb8aa3b, v117
	v_exp_f32_e32 v116, v116
	v_mul_f32_e32 v105, v110, v105
	v_fma_f32 v110, -v119, v124, 1.0
	v_fmac_f32_e32 v124, v110, v124
	v_div_scale_f32 v110, vcc, 1.0, v118, 1.0
	v_mul_f32_e32 v115, v110, v124
	v_fma_f32 v117, -v119, v115, v110
	v_add_f32_e32 v116, 1.0, v116
	v_fmac_f32_e32 v115, v117, v124
	v_div_scale_f32 v117, s[6:7], v116, v116, 1.0
	v_fma_f32 v110, -v119, v115, v110
	v_rcp_f32_e32 v119, v117
	v_div_fmas_f32 v110, v110, v124, v115
	v_and_b32_e32 v121, 0xffff0000, v121
	v_div_fixup_f32 v110, v110, v118, 1.0
	v_mul_f32_e32 v110, v106, v110
	v_fma_f32 v106, -v117, v119, 1.0
	v_mul_f32_e32 v118, 0xbfb8aa3b, v121
	v_fmac_f32_e32 v119, v106, v119
	v_div_scale_f32 v106, vcc, 1.0, v116, 1.0
	v_exp_f32_e32 v118, v118
	v_mul_f32_e32 v115, v106, v119
	v_fma_f32 v120, -v117, v115, v106
	v_fmac_f32_e32 v115, v120, v119
	v_fma_f32 v106, -v117, v115, v106
	v_add_f32_e32 v117, 1.0, v118
	v_div_scale_f32 v118, s[6:7], v117, v117, 1.0
	v_rcp_f32_e32 v120, v118
	v_div_fmas_f32 v106, v106, v119, v115
	v_div_fixup_f32 v106, v106, v116, 1.0
	v_mul_f32_e32 v106, v111, v106
	v_fma_f32 v111, -v118, v120, 1.0
	v_fmac_f32_e32 v120, v111, v120
	v_div_scale_f32 v111, vcc, 1.0, v117, 1.0
	v_mul_f32_e32 v115, v111, v120
	v_fma_f32 v116, -v118, v115, v111
	v_fmac_f32_e32 v115, v116, v120
	v_fma_f32 v111, -v118, v115, v111
	v_div_fmas_f32 v111, v111, v120, v115
	v_div_fixup_f32 v111, v111, v117, 1.0
	v_mul_f32_e32 v107, v107, v111
	v_cvt_pk_bf16_f32 v104, v108, v104
	v_cvt_pk_bf16_f32 v105, v105, v106
	v_cvt_pk_bf16_f32 v106, v114, v109
	v_cvt_pk_bf16_f32 v107, v110, v107
	s_waitcnt vmcnt(12)
	v_mov_b32_e32 v108, v212
	v_mov_b32_e32 v109, v213
	v_mov_b32_e32 v110, v214
	v_mov_b32_e32 v111, v215
	v_add_u32_e32 v198, 0x177a00, v197
	global_load_dwordx4 v[212:215], v198, s[22:23]
	v_lshlrev_b32_e32 v115, 16, v111
	global_store_dwordx4 v[112:113], v[104:107], off sc1
	v_and_b32_e32 v111, 0xffff0000, v111
	s_nop 0
	v_lshlrev_b32_e32 v104, 16, v108
	v_mul_f32_e32 v104, 0xbfb8aa3b, v104
	v_exp_f32_e32 v104, v104
	v_lshlrev_b32_e32 v106, 16, v109
	v_and_b32_e32 v107, 0xffff0000, v109
	v_and_b32_e32 v105, 0xffff0000, v108
	v_add_f32_e32 v104, 1.0, v104
	v_div_scale_f32 v109, s[6:7], v104, v104, 1.0
	v_rcp_f32_e32 v114, v109
	v_lshlrev_b32_e32 v108, 16, v110
	v_mul_f32_e32 v108, 0xbfb8aa3b, v108
	v_exp_f32_e32 v108, v108
	v_fma_f32 v116, -v109, v114, 1.0
	v_fmac_f32_e32 v114, v116, v114
	v_div_scale_f32 v116, vcc, 1.0, v104, 1.0
	v_mul_f32_e32 v117, v116, v114
	v_fma_f32 v118, -v109, v117, v116
	v_fmac_f32_e32 v117, v118, v114
	v_add_f32_e32 v108, 1.0, v108
	v_fma_f32 v109, -v109, v117, v116
	v_div_scale_f32 v116, s[6:7], v108, v108, 1.0
	v_rcp_f32_e32 v118, v116
	v_div_fmas_f32 v109, v109, v114, v117
	v_mul_f32_e32 v105, 0xbfb8aa3b, v105
	v_div_fixup_f32 v104, v109, v104, 1.0
	v_exp_f32_e32 v105, v105
	v_mul_f32_e32 v100, v100, v104
	v_fma_f32 v104, -v116, v118, 1.0
	v_fmac_f32_e32 v118, v104, v118
	v_div_scale_f32 v104, vcc, 1.0, v108, 1.0
	v_mul_f32_e32 v109, v104, v118
	v_fma_f32 v114, -v116, v109, v104
	v_add_f32_e32 v105, 1.0, v105
	v_fmac_f32_e32 v109, v114, v118
	v_div_scale_f32 v114, s[6:7], v105, v105, 1.0
	v_fma_f32 v104, -v116, v109, v104
	v_rcp_f32_e32 v116, v114
	v_and_b32_e32 v110, 0xffff0000, v110
	v_div_fmas_f32 v104, v104, v118, v109
	v_mul_f32_e32 v109, 0xbfb8aa3b, v110
	v_div_fixup_f32 v104, v104, v108, 1.0
	v_exp_f32_e32 v109, v109
	v_mul_f32_e32 v96, v96, v104
	v_fma_f32 v104, -v114, v116, 1.0
	v_fmac_f32_e32 v116, v104, v116
	v_div_scale_f32 v104, vcc, 1.0, v105, 1.0
	v_mul_f32_e32 v108, v104, v116
	v_fma_f32 v110, -v114, v108, v104
	v_add_f32_e32 v109, 1.0, v109
	v_fmac_f32_e32 v108, v110, v116
	v_div_scale_f32 v110, s[6:7], v109, v109, 1.0
	v_fma_f32 v104, -v114, v108, v104
	v_rcp_f32_e32 v114, v110
	v_div_fmas_f32 v104, v104, v116, v108
	v_mul_f32_e32 v106, 0xbfb8aa3b, v106
	v_div_fixup_f32 v104, v104, v105, 1.0
	v_exp_f32_e32 v106, v106
	v_mul_f32_e32 v101, v101, v104
	v_fma_f32 v104, -v110, v114, 1.0
	v_fmac_f32_e32 v114, v104, v114
	v_div_scale_f32 v104, vcc, 1.0, v109, 1.0
	v_mul_f32_e32 v105, v104, v114
	v_fma_f32 v108, -v110, v105, v104
	v_add_f32_e32 v106, 1.0, v106
	v_fmac_f32_e32 v105, v108, v114
	v_div_scale_f32 v108, s[6:7], v106, v106, 1.0
	v_fma_f32 v104, -v110, v105, v104
	v_rcp_f32_e32 v110, v108
	v_div_fmas_f32 v104, v104, v114, v105
	v_div_fixup_f32 v104, v104, v109, 1.0
	v_mul_f32_e32 v97, v97, v104
	v_fma_f32 v104, -v108, v110, 1.0
	v_mul_f32_e32 v109, 0xbfb8aa3b, v115
	v_fmac_f32_e32 v110, v104, v110
	v_div_scale_f32 v104, vcc, 1.0, v106, 1.0
	v_exp_f32_e32 v109, v109
	v_mul_f32_e32 v105, v104, v110
	v_fma_f32 v114, -v108, v105, v104
	v_fmac_f32_e32 v105, v114, v110
	v_fma_f32 v104, -v108, v105, v104
	v_add_f32_e32 v108, 1.0, v109
	v_div_scale_f32 v109, s[6:7], v108, v108, 1.0
	v_rcp_f32_e32 v114, v109
	v_div_fmas_f32 v104, v104, v110, v105
	v_div_fixup_f32 v104, v104, v106, 1.0
	v_mul_f32_e32 v106, 0xbfb8aa3b, v107
	v_exp_f32_e32 v106, v106
	v_mul_f32_e32 v102, v102, v104
; __device__ __forceinline__ float sigmoidf_(float x) { return 1.0f / (1.0f + __expf(-x)); }
; __device__ __forceinline__ u32x4 pack8(const f32x4 v0, const f32x4 v1) { u32x4 w; w.x = pk2(v0[0], v0[1]); w.y = pk2(v0[2], v0[3]); w.z = pk2(v1[0], v1[1]); w.w = pk2(v1[2], v1[3]); return w; }
; __device__ __forceinline__ void unpack8(const u32x4 w, f32x4& v0, f32x4& v1) { v0 = (f32x4){bflo(w.x), bfhi(w.x), bflo(w.y), bfhi(w.y)}; v1 = (f32x4){bflo(w.z), bfhi(w.z), bflo(w.w), bfhi(w.w)}; }
;     __device__ __forceinline__ void operator()(const f32x4 (&acc)[2][2][4][2], const Unit& u, int wr, int wc, int fr, int fq) const {
;     ...
;         for (int ai = 0; ai < 2; ++ai)
; #pragma unroll
;             for (int m = 0; m < 4; ++m) {
;                 bf16_t* rowp = z + (size_t)(row0 + ai * 128 + m * 16) * DIN + col0;
; #pragma unroll
;                 for (int bj = 0; bj < 2; ++bj) {
;                     const u32x4 gw = *(const u32x4*)(rowp + (MODE == 0 ? O_GB : O_GA) + bj * 128);
;                     f32x4 g0, g1; unpack8(gw, g0, g1);
;                     f32x4 v0, v1;
; #pragma unroll
;                     for (int j = 0; j < 4; ++j) { v0[j] = sigmoidf_(g0[j]) * acc[ai][bj][m][0][j]; v1[j] = sigmoidf_(g1[j]) * acc[ai][bj][m][1][j]; }
;                     if (MODE == 1) { const u32x4 mw = *(const u32x4*)(rowp + bj * 128); f32x4 m0, m1; unpack8(mw, m0, m1); v0 += m0; v1 += m1; }
;                     *(u32x4*)(rowp + bj * 128) = pack8(v0, v1); }
	v_fma_f32 v104, -v109, v114, 1.0
	v_fmac_f32_e32 v114, v104, v114
	v_div_scale_f32 v104, vcc, 1.0, v108, 1.0
	v_mul_f32_e32 v105, v104, v114
	v_fma_f32 v107, -v109, v105, v104
	v_add_f32_e32 v106, 1.0, v106
	v_fmac_f32_e32 v105, v107, v114
	v_div_scale_f32 v107, s[6:7], v106, v106, 1.0
	v_fma_f32 v104, -v109, v105, v104
	v_rcp_f32_e32 v109, v107
	v_div_fmas_f32 v104, v104, v114, v105
	v_div_fixup_f32 v104, v104, v108, 1.0
	v_mul_f32_e32 v104, v98, v104
	v_fma_f32 v98, -v107, v109, 1.0
	v_mul_f32_e32 v108, 0xbfb8aa3b, v111
	v_fmac_f32_e32 v109, v98, v109
	v_div_scale_f32 v98, vcc, 1.0, v106, 1.0
	v_exp_f32_e32 v108, v108
	v_mul_f32_e32 v105, v98, v109
	v_fma_f32 v110, -v107, v105, v98
	v_fmac_f32_e32 v105, v110, v109
	v_fma_f32 v98, -v107, v105, v98
	v_add_f32_e32 v107, 1.0, v108
	v_div_scale_f32 v108, s[6:7], v107, v107, 1.0
	v_rcp_f32_e32 v110, v108
	v_div_fmas_f32 v98, v98, v109, v105
	v_div_fixup_f32 v98, v98, v106, 1.0
	v_mul_f32_e32 v103, v103, v98
	v_fma_f32 v98, -v108, v110, 1.0
	v_fmac_f32_e32 v110, v98, v110
	v_div_scale_f32 v98, vcc, 1.0, v107, 1.0
	v_mul_f32_e32 v105, v98, v110
	v_fma_f32 v106, -v108, v105, v98
	v_fmac_f32_e32 v105, v106, v110
	v_fma_f32 v98, -v108, v105, v98
	v_div_fmas_f32 v98, v98, v110, v105
	v_div_fixup_f32 v98, v98, v107, 1.0
	v_mul_f32_e32 v105, v99, v98
	v_cvt_pk_bf16_f32 v98, v100, v101
	v_cvt_pk_bf16_f32 v99, v102, v103
	v_cvt_pk_bf16_f32 v100, v96, v97
	v_or_b32_e32 v96, 32, v160
	v_mad_i64_i32 v[96:97], s[6:7], v96, s57, v[146:147]
	v_lshl_add_u64 v[96:97], v[96:97], 0, v[148:149]
	v_add_co_u32_e32 v106, vcc, s58, v96
	v_cvt_pk_bf16_f32 v101, v104, v105
	global_store_dwordx4 v[112:113], v[98:101], off offset:256 sc1
	s_nop 0
	v_addc_co_u32_e32 v107, vcc, 0, v97, vcc
	s_waitcnt vmcnt(14)
	v_mov_b32_e32 v102, v216
	v_mov_b32_e32 v103, v217
	v_mov_b32_e32 v104, v218
	v_mov_b32_e32 v105, v219
	v_add_u32_e32 v198, 0x177b00, v197
	global_load_dwordx4 v[216:219], v198, s[22:23]
	v_lshlrev_b32_e32 v98, 16, v102
	v_mul_f32_e32 v98, 0xbfb8aa3b, v98
	v_exp_f32_e32 v98, v98
	v_lshlrev_b32_e32 v100, 16, v103
	v_and_b32_e32 v101, 0xffff0000, v103
	v_and_b32_e32 v99, 0xffff0000, v102
	v_add_f32_e32 v98, 1.0, v98
	v_div_scale_f32 v103, s[6:7], v98, v98, 1.0
	v_rcp_f32_e32 v108, v103
	v_lshlrev_b32_e32 v102, 16, v104
	v_mul_f32_e32 v102, 0xbfb8aa3b, v102
	v_exp_f32_e32 v102, v102
	v_fma_f32 v110, -v103, v108, 1.0
	v_fmac_f32_e32 v108, v110, v108
	v_div_scale_f32 v110, vcc, 1.0, v98, 1.0
	v_mul_f32_e32 v111, v110, v108
	v_fma_f32 v112, -v103, v111, v110
	v_fmac_f32_e32 v111, v112, v108
	v_add_f32_e32 v102, 1.0, v102
	v_fma_f32 v103, -v103, v111, v110
	v_div_scale_f32 v110, s[6:7], v102, v102, 1.0
	v_rcp_f32_e32 v112, v110
	v_div_fmas_f32 v103, v103, v108, v111
	v_mul_f32_e32 v99, 0xbfb8aa3b, v99
	v_div_fixup_f32 v98, v103, v98, 1.0
	v_exp_f32_e32 v99, v99
	v_mul_f32_e32 v92, v92, v98
	v_fma_f32 v98, -v110, v112, 1.0
	v_fmac_f32_e32 v112, v98, v112
	v_div_scale_f32 v98, vcc, 1.0, v102, 1.0
	v_mul_f32_e32 v103, v98, v112
	v_fma_f32 v108, -v110, v103, v98
	v_add_f32_e32 v99, 1.0, v99
	v_fmac_f32_e32 v103, v108, v112
	v_div_scale_f32 v108, s[6:7], v99, v99, 1.0
	v_fma_f32 v98, -v110, v103, v98
	v_rcp_f32_e32 v110, v108
	v_and_b32_e32 v104, 0xffff0000, v104
	v_div_fmas_f32 v98, v98, v112, v103
	v_mul_f32_e32 v103, 0xbfb8aa3b, v104
	v_div_fixup_f32 v98, v98, v102, 1.0
	v_exp_f32_e32 v103, v103
	v_mul_f32_e32 v98, v88, v98
	v_fma_f32 v88, -v108, v110, 1.0
	v_fmac_f32_e32 v110, v88, v110
	v_div_scale_f32 v88, vcc, 1.0, v99, 1.0
	v_mul_f32_e32 v102, v88, v110
	v_fma_f32 v104, -v108, v102, v88
	v_add_f32_e32 v103, 1.0, v103
	v_fmac_f32_e32 v102, v104, v110
	v_div_scale_f32 v104, s[6:7], v103, v103, 1.0
	v_fma_f32 v88, -v108, v102, v88
	v_rcp_f32_e32 v108, v104
	v_div_fmas_f32 v88, v88, v110, v102
	v_mul_f32_e32 v100, 0xbfb8aa3b, v100
	v_div_fixup_f32 v88, v88, v99, 1.0
	v_exp_f32_e32 v100, v100
	v_mul_f32_e32 v88, v93, v88
	v_fma_f32 v93, -v104, v108, 1.0
	v_fmac_f32_e32 v108, v93, v108
	v_div_scale_f32 v93, vcc, 1.0, v103, 1.0
	v_mul_f32_e32 v99, v93, v108
	v_fma_f32 v102, -v104, v99, v93
	v_add_f32_e32 v100, 1.0, v100
	v_fmac_f32_e32 v99, v102, v108
	v_div_scale_f32 v102, s[6:7], v100, v100, 1.0
	v_fma_f32 v93, -v104, v99, v93
	v_rcp_f32_e32 v104, v102
	v_div_fmas_f32 v93, v93, v108, v99
	v_lshlrev_b32_e32 v109, 16, v105
	v_div_fixup_f32 v93, v93, v103, 1.0
	v_mul_f32_e32 v93, v89, v93
	v_fma_f32 v89, -v102, v104, 1.0
	v_mul_f32_e32 v103, 0xbfb8aa3b, v109
	v_fmac_f32_e32 v104, v89, v104
	v_div_scale_f32 v89, vcc, 1.0, v100, 1.0
	v_exp_f32_e32 v103, v103
	v_mul_f32_e32 v99, v89, v104
	v_fma_f32 v108, -v102, v99, v89
	v_fmac_f32_e32 v99, v108, v104
	v_fma_f32 v89, -v102, v99, v89
	v_add_f32_e32 v102, 1.0, v103
	v_div_scale_f32 v103, s[6:7], v102, v102, 1.0
	v_rcp_f32_e32 v108, v103
	v_div_fmas_f32 v89, v89, v104, v99
	v_div_fixup_f32 v89, v89, v100, 1.0
	v_mul_f32_e32 v100, 0xbfb8aa3b, v101
	v_exp_f32_e32 v100, v100
	v_mul_f32_e32 v89, v94, v89
	v_fma_f32 v94, -v103, v108, 1.0
	v_fmac_f32_e32 v108, v94, v108
	v_div_scale_f32 v94, vcc, 1.0, v102, 1.0
	v_mul_f32_e32 v99, v94, v108
	v_fma_f32 v101, -v103, v99, v94
	v_add_f32_e32 v100, 1.0, v100
	v_fmac_f32_e32 v99, v101, v108
	v_div_scale_f32 v101, s[6:7], v100, v100, 1.0
	v_fma_f32 v94, -v103, v99, v94
	v_rcp_f32_e32 v103, v101
	v_div_fmas_f32 v94, v94, v108, v99
	v_and_b32_e32 v105, 0xffff0000, v105
	v_div_fixup_f32 v94, v94, v102, 1.0
	v_mul_f32_e32 v94, v90, v94
	v_fma_f32 v90, -v101, v103, 1.0
	v_mul_f32_e32 v102, 0xbfb8aa3b, v105
	v_fmac_f32_e32 v103, v90, v103
	v_div_scale_f32 v90, vcc, 1.0, v100, 1.0
	v_exp_f32_e32 v102, v102
	v_mul_f32_e32 v99, v90, v103
	v_fma_f32 v104, -v101, v99, v90
	v_fmac_f32_e32 v99, v104, v103
	v_fma_f32 v90, -v101, v99, v90
	v_add_f32_e32 v101, 1.0, v102
	v_div_scale_f32 v102, s[6:7], v101, v101, 1.0
	v_rcp_f32_e32 v104, v102
	v_div_fmas_f32 v90, v90, v103, v99
	v_div_fixup_f32 v90, v90, v100, 1.0
	v_mul_f32_e32 v90, v95, v90
	v_fma_f32 v95, -v102, v104, 1.0
	v_fmac_f32_e32 v104, v95, v104
	v_div_scale_f32 v95, vcc, 1.0, v101, 1.0
	v_mul_f32_e32 v99, v95, v104
	v_fma_f32 v100, -v102, v99, v95
	v_fmac_f32_e32 v99, v100, v104
	v_fma_f32 v95, -v102, v99, v95
	v_div_fmas_f32 v95, v95, v104, v99
	v_div_fixup_f32 v95, v95, v101, 1.0
	v_mul_f32_e32 v91, v91, v95
	v_cvt_pk_bf16_f32 v88, v92, v88
	v_cvt_pk_bf16_f32 v89, v89, v90
	v_cvt_pk_bf16_f32 v90, v98, v93
	v_cvt_pk_bf16_f32 v91, v94, v91
	s_waitcnt vmcnt(14)
; __device__ __forceinline__ float sigmoidf_(float x) { return 1.0f / (1.0f + __expf(-x)); }
; __device__ __forceinline__ u32x4 pack8(const f32x4 v0, const f32x4 v1) { u32x4 w; w.x = pk2(v0[0], v0[1]); w.y = pk2(v0[2], v0[3]); w.z = pk2(v1[0], v1[1]); w.w = pk2(v1[2], v1[3]); return w; }
; __device__ __forceinline__ void unpack8(const u32x4 w, f32x4& v0, f32x4& v1) { v0 = (f32x4){bflo(w.x), bfhi(w.x), bflo(w.y), bfhi(w.y)}; v1 = (f32x4){bflo(w.z), bfhi(w.z), bflo(w.w), bfhi(w.w)}; }
;     __device__ __forceinline__ void operator()(const f32x4 (&acc)[2][2][4][2], const Unit& u, int wr, int wc, int fr, int fq) const {
;     ...
;         for (int ai = 0; ai < 2; ++ai)
; #pragma unroll
;             for (int m = 0; m < 4; ++m) {
;                 bf16_t* rowp = z + (size_t)(row0 + ai * 128 + m * 16) * DIN + col0;
; #pragma unroll
;                 for (int bj = 0; bj < 2; ++bj) {
;                     const u32x4 gw = *(const u32x4*)(rowp + (MODE == 0 ? O_GB : O_GA) + bj * 128);
;                     f32x4 g0, g1; unpack8(gw, g0, g1);
;                     f32x4 v0, v1;
; #pragma unroll
;                     for (int j = 0; j < 4; ++j) { v0[j] = sigmoidf_(g0[j]) * acc[ai][bj][m][0][j]; v1[j] = sigmoidf_(g1[j]) * acc[ai][bj][m][1][j]; }
;                     if (MODE == 1) { const u32x4 mw = *(const u32x4*)(rowp + bj * 128); f32x4 m0, m1; unpack8(mw, m0, m1); v0 += m0; v1 += m1; }
;                     *(u32x4*)(rowp + bj * 128) = pack8(v0, v1); }
	v_mov_b32_e32 v92, v232
	v_mov_b32_e32 v93, v233
	v_mov_b32_e32 v94, v234
	v_mov_b32_e32 v95, v235
	v_lshlrev_b32_e32 v99, 16, v95
	global_store_dwordx4 v[96:97], v[88:91], off sc1
	v_and_b32_e32 v95, 0xffff0000, v95
	s_nop 0
	v_lshlrev_b32_e32 v88, 16, v92
	v_mul_f32_e32 v88, 0xbfb8aa3b, v88
	v_exp_f32_e32 v88, v88
	v_lshlrev_b32_e32 v90, 16, v93
	v_and_b32_e32 v91, 0xffff0000, v93
	v_and_b32_e32 v89, 0xffff0000, v92
	v_add_f32_e32 v88, 1.0, v88
	v_div_scale_f32 v93, s[6:7], v88, v88, 1.0
	v_rcp_f32_e32 v98, v93
	v_lshlrev_b32_e32 v92, 16, v94
	v_mul_f32_e32 v92, 0xbfb8aa3b, v92
	v_exp_f32_e32 v92, v92
	v_fma_f32 v100, -v93, v98, 1.0
	v_fmac_f32_e32 v98, v100, v98
	v_div_scale_f32 v100, vcc, 1.0, v88, 1.0
	v_mul_f32_e32 v101, v100, v98
	v_fma_f32 v102, -v93, v101, v100
	v_fmac_f32_e32 v101, v102, v98
	v_add_f32_e32 v92, 1.0, v92
	v_fma_f32 v93, -v93, v101, v100
	v_div_scale_f32 v100, s[6:7], v92, v92, 1.0
	v_rcp_f32_e32 v102, v100
	v_div_fmas_f32 v93, v93, v98, v101
	v_mul_f32_e32 v89, 0xbfb8aa3b, v89
	v_div_fixup_f32 v88, v93, v88, 1.0
	v_exp_f32_e32 v89, v89
	v_mul_f32_e32 v84, v84, v88
	v_fma_f32 v88, -v100, v102, 1.0
	v_fmac_f32_e32 v102, v88, v102
	v_div_scale_f32 v88, vcc, 1.0, v92, 1.0
	v_mul_f32_e32 v93, v88, v102
	v_fma_f32 v98, -v100, v93, v88
	v_add_f32_e32 v89, 1.0, v89
	v_fmac_f32_e32 v93, v98, v102
	v_div_scale_f32 v98, s[6:7], v89, v89, 1.0
	v_fma_f32 v88, -v100, v93, v88
	v_rcp_f32_e32 v100, v98
	v_and_b32_e32 v94, 0xffff0000, v94
	v_div_fmas_f32 v88, v88, v102, v93
	v_mul_f32_e32 v93, 0xbfb8aa3b, v94
	v_div_fixup_f32 v88, v88, v92, 1.0
	v_exp_f32_e32 v93, v93
	v_mul_f32_e32 v80, v80, v88
	v_fma_f32 v88, -v98, v100, 1.0
	v_fmac_f32_e32 v100, v88, v100
	v_div_scale_f32 v88, vcc, 1.0, v89, 1.0
	v_mul_f32_e32 v92, v88, v100
	v_fma_f32 v94, -v98, v92, v88
	v_add_f32_e32 v93, 1.0, v93
	v_fmac_f32_e32 v92, v94, v100
	v_div_scale_f32 v94, s[6:7], v93, v93, 1.0
	v_fma_f32 v88, -v98, v92, v88
	v_rcp_f32_e32 v98, v94
	v_div_fmas_f32 v88, v88, v100, v92
	v_mul_f32_e32 v90, 0xbfb8aa3b, v90
	v_div_fixup_f32 v88, v88, v89, 1.0
	v_exp_f32_e32 v90, v90
	v_mul_f32_e32 v85, v85, v88
	v_fma_f32 v88, -v94, v98, 1.0
	v_fmac_f32_e32 v98, v88, v98
	v_div_scale_f32 v88, vcc, 1.0, v93, 1.0
	v_mul_f32_e32 v89, v88, v98
	v_fma_f32 v92, -v94, v89, v88
	v_add_f32_e32 v90, 1.0, v90
	v_fmac_f32_e32 v89, v92, v98
	v_div_scale_f32 v92, s[6:7], v90, v90, 1.0
	v_fma_f32 v88, -v94, v89, v88
	v_rcp_f32_e32 v94, v92
	v_div_fmas_f32 v88, v88, v98, v89
	v_div_fixup_f32 v88, v88, v93, 1.0
	v_mul_f32_e32 v81, v81, v88
	v_fma_f32 v88, -v92, v94, 1.0
	v_mul_f32_e32 v93, 0xbfb8aa3b, v99
	v_fmac_f32_e32 v94, v88, v94
	v_div_scale_f32 v88, vcc, 1.0, v90, 1.0
	v_exp_f32_e32 v93, v93
	v_mul_f32_e32 v89, v88, v94
	v_fma_f32 v98, -v92, v89, v88
	v_fmac_f32_e32 v89, v98, v94
	v_fma_f32 v88, -v92, v89, v88
	v_add_f32_e32 v92, 1.0, v93
	v_div_scale_f32 v93, s[6:7], v92, v92, 1.0
	v_rcp_f32_e32 v98, v93
	v_div_fmas_f32 v88, v88, v94, v89
	v_div_fixup_f32 v88, v88, v90, 1.0
	v_mul_f32_e32 v90, 0xbfb8aa3b, v91
	v_exp_f32_e32 v90, v90
	v_mul_f32_e32 v86, v86, v88
	v_fma_f32 v88, -v93, v98, 1.0
	v_fmac_f32_e32 v98, v88, v98
	v_div_scale_f32 v88, vcc, 1.0, v92, 1.0
	v_mul_f32_e32 v89, v88, v98
	v_fma_f32 v91, -v93, v89, v88
	v_add_f32_e32 v90, 1.0, v90
	v_fmac_f32_e32 v89, v91, v98
	v_div_scale_f32 v91, s[6:7], v90, v90, 1.0
	v_fma_f32 v88, -v93, v89, v88
	v_rcp_f32_e32 v93, v91
	v_div_fmas_f32 v88, v88, v98, v89
	v_div_fixup_f32 v88, v88, v92, 1.0
	v_mul_f32_e32 v88, v82, v88
	v_fma_f32 v82, -v91, v93, 1.0
	v_mul_f32_e32 v92, 0xbfb8aa3b, v95
	v_fmac_f32_e32 v93, v82, v93
	v_div_scale_f32 v82, vcc, 1.0, v90, 1.0
	v_exp_f32_e32 v92, v92
	v_mul_f32_e32 v89, v82, v93
	v_fma_f32 v94, -v91, v89, v82
	v_fmac_f32_e32 v89, v94, v93
	v_fma_f32 v82, -v91, v89, v82
	v_add_f32_e32 v91, 1.0, v92
	v_div_scale_f32 v92, s[6:7], v91, v91, 1.0
	v_rcp_f32_e32 v94, v92
	v_div_fmas_f32 v82, v82, v93, v89
	v_div_fixup_f32 v82, v82, v90, 1.0
	v_mul_f32_e32 v87, v87, v82
	v_fma_f32 v82, -v92, v94, 1.0
	v_fmac_f32_e32 v94, v82, v94
	v_div_scale_f32 v82, vcc, 1.0, v91, 1.0
	v_mul_f32_e32 v89, v82, v94
	v_fma_f32 v90, -v92, v89, v82
	v_fmac_f32_e32 v89, v90, v94
	v_fma_f32 v82, -v92, v89, v82
	v_div_fmas_f32 v82, v82, v94, v89
	v_div_fixup_f32 v82, v82, v91, 1.0
	v_mul_f32_e32 v89, v83, v82
	v_cvt_pk_bf16_f32 v82, v84, v85
	v_cvt_pk_bf16_f32 v83, v86, v87
	v_cvt_pk_bf16_f32 v84, v80, v81
	v_or_b32_e32 v80, 48, v160
	v_mad_i64_i32 v[80:81], s[6:7], v80, s57, v[146:147]
	v_lshl_add_u64 v[80:81], v[80:81], 0, v[148:149]
	v_add_co_u32_e32 v90, vcc, s58, v80
	v_cvt_pk_bf16_f32 v85, v88, v89
	global_store_dwordx4 v[96:97], v[82:85], off offset:256 sc1
	s_nop 0
	v_addc_co_u32_e32 v91, vcc, 0, v81, vcc
	s_waitcnt vmcnt(15)
; __device__ __forceinline__ float sigmoidf_(float x) { return 1.0f / (1.0f + __expf(-x)); }
; __device__ __forceinline__ u32x4 pack8(const f32x4 v0, const f32x4 v1) { u32x4 w; w.x = pk2(v0[0], v0[1]); w.y = pk2(v0[2], v0[3]); w.z = pk2(v1[0], v1[1]); w.w = pk2(v1[2], v1[3]); return w; }
; __device__ __forceinline__ void unpack8(const u32x4 w, f32x4& v0, f32x4& v1) { v0 = (f32x4){bflo(w.x), bfhi(w.x), bflo(w.y), bfhi(w.y)}; v1 = (f32x4){bflo(w.z), bfhi(w.z), bflo(w.w), bfhi(w.w)}; }
;     __device__ __forceinline__ void operator()(const f32x4 (&acc)[2][2][4][2], const Unit& u, int wr, int wc, int fr, int fq) const {
;     ...
;         for (int ai = 0; ai < 2; ++ai)
; #pragma unroll
;             for (int m = 0; m < 4; ++m) {
;                 bf16_t* rowp = z + (size_t)(row0 + ai * 128 + m * 16) * DIN + col0;
; #pragma unroll
;                 for (int bj = 0; bj < 2; ++bj) {
;                     const u32x4 gw = *(const u32x4*)(rowp + (MODE == 0 ? O_GB : O_GA) + bj * 128);
;                     f32x4 g0, g1; unpack8(gw, g0, g1);
;                     f32x4 v0, v1;
; #pragma unroll
;                     for (int j = 0; j < 4; ++j) { v0[j] = sigmoidf_(g0[j]) * acc[ai][bj][m][0][j]; v1[j] = sigmoidf_(g1[j]) * acc[ai][bj][m][1][j]; }
;                     if (MODE == 1) { const u32x4 mw = *(const u32x4*)(rowp + bj * 128); f32x4 m0, m1; unpack8(mw, m0, m1); v0 += m0; v1 += m1; }
;                     *(u32x4*)(rowp + bj * 128) = pack8(v0, v1); }
	v_mov_b32_e32 v86, v236
	v_mov_b32_e32 v87, v237
	v_mov_b32_e32 v88, v238
	v_mov_b32_e32 v89, v239
	v_lshlrev_b32_e32 v82, 16, v86
	v_mul_f32_e32 v82, 0xbfb8aa3b, v82
	v_exp_f32_e32 v82, v82
	v_lshlrev_b32_e32 v84, 16, v87
	v_and_b32_e32 v85, 0xffff0000, v87
	v_and_b32_e32 v83, 0xffff0000, v86
	v_add_f32_e32 v82, 1.0, v82
	v_div_scale_f32 v87, s[6:7], v82, v82, 1.0
	v_rcp_f32_e32 v92, v87
	v_lshlrev_b32_e32 v86, 16, v88
	v_mul_f32_e32 v86, 0xbfb8aa3b, v86
	v_exp_f32_e32 v86, v86
	v_fma_f32 v94, -v87, v92, 1.0
	v_fmac_f32_e32 v92, v94, v92
	v_div_scale_f32 v94, vcc, 1.0, v82, 1.0
	v_mul_f32_e32 v95, v94, v92
	v_fma_f32 v96, -v87, v95, v94
	v_fmac_f32_e32 v95, v96, v92
	v_add_f32_e32 v86, 1.0, v86
	v_fma_f32 v87, -v87, v95, v94
	v_div_scale_f32 v94, s[6:7], v86, v86, 1.0
	v_rcp_f32_e32 v96, v94
	v_div_fmas_f32 v87, v87, v92, v95
	v_mul_f32_e32 v83, 0xbfb8aa3b, v83
	v_div_fixup_f32 v82, v87, v82, 1.0
	v_exp_f32_e32 v83, v83
	v_mul_f32_e32 v76, v76, v82
	v_fma_f32 v82, -v94, v96, 1.0
	v_fmac_f32_e32 v96, v82, v96
	v_div_scale_f32 v82, vcc, 1.0, v86, 1.0
	v_mul_f32_e32 v87, v82, v96
	v_fma_f32 v92, -v94, v87, v82
	v_add_f32_e32 v83, 1.0, v83
	v_fmac_f32_e32 v87, v92, v96
	v_div_scale_f32 v92, s[6:7], v83, v83, 1.0
	v_fma_f32 v82, -v94, v87, v82
	v_rcp_f32_e32 v94, v92
	v_and_b32_e32 v88, 0xffff0000, v88
	v_div_fmas_f32 v82, v82, v96, v87
	v_mul_f32_e32 v87, 0xbfb8aa3b, v88
	v_div_fixup_f32 v82, v82, v86, 1.0
	v_exp_f32_e32 v87, v87
	v_mul_f32_e32 v82, v72, v82
	v_fma_f32 v72, -v92, v94, 1.0
	v_fmac_f32_e32 v94, v72, v94
	v_div_scale_f32 v72, vcc, 1.0, v83, 1.0
	v_mul_f32_e32 v86, v72, v94
	v_fma_f32 v88, -v92, v86, v72
	v_add_f32_e32 v87, 1.0, v87
	v_fmac_f32_e32 v86, v88, v94
	v_div_scale_f32 v88, s[6:7], v87, v87, 1.0
	v_fma_f32 v72, -v92, v86, v72
	v_rcp_f32_e32 v92, v88
	v_div_fmas_f32 v72, v72, v94, v86
	v_mul_f32_e32 v84, 0xbfb8aa3b, v84
	v_div_fixup_f32 v72, v72, v83, 1.0
	v_exp_f32_e32 v84, v84
	v_mul_f32_e32 v72, v77, v72
	v_fma_f32 v77, -v88, v92, 1.0
	v_fmac_f32_e32 v92, v77, v92
	v_div_scale_f32 v77, vcc, 1.0, v87, 1.0
	v_mul_f32_e32 v83, v77, v92
	v_fma_f32 v86, -v88, v83, v77
	v_add_f32_e32 v84, 1.0, v84
	v_fmac_f32_e32 v83, v86, v92
	v_div_scale_f32 v86, s[6:7], v84, v84, 1.0
	v_fma_f32 v77, -v88, v83, v77
	v_rcp_f32_e32 v88, v86
	v_div_fmas_f32 v77, v77, v92, v83
	v_lshlrev_b32_e32 v93, 16, v89
	v_div_fixup_f32 v77, v77, v87, 1.0
	v_mul_f32_e32 v77, v73, v77
	v_fma_f32 v73, -v86, v88, 1.0
	v_mul_f32_e32 v87, 0xbfb8aa3b, v93
	v_fmac_f32_e32 v88, v73, v88
	v_div_scale_f32 v73, vcc, 1.0, v84, 1.0
	v_exp_f32_e32 v87, v87
	v_mul_f32_e32 v83, v73, v88
	v_fma_f32 v92, -v86, v83, v73
	v_fmac_f32_e32 v83, v92, v88
	v_fma_f32 v73, -v86, v83, v73
	v_add_f32_e32 v86, 1.0, v87
	v_div_scale_f32 v87, s[6:7], v86, v86, 1.0
	v_rcp_f32_e32 v92, v87
	v_div_fmas_f32 v73, v73, v88, v83
	v_div_fixup_f32 v73, v73, v84, 1.0
	v_mul_f32_e32 v84, 0xbfb8aa3b, v85
	v_exp_f32_e32 v84, v84
	v_mul_f32_e32 v73, v78, v73
	v_fma_f32 v78, -v87, v92, 1.0
	v_fmac_f32_e32 v92, v78, v92
	v_div_scale_f32 v78, vcc, 1.0, v86, 1.0
	v_mul_f32_e32 v83, v78, v92
	v_fma_f32 v85, -v87, v83, v78
	v_add_f32_e32 v84, 1.0, v84
	v_fmac_f32_e32 v83, v85, v92
	v_div_scale_f32 v85, s[6:7], v84, v84, 1.0
	v_fma_f32 v78, -v87, v83, v78
	v_rcp_f32_e32 v87, v85
	v_div_fmas_f32 v78, v78, v92, v83
	v_and_b32_e32 v89, 0xffff0000, v89
	v_div_fixup_f32 v78, v78, v86, 1.0
	v_mul_f32_e32 v78, v74, v78
	v_fma_f32 v74, -v85, v87, 1.0
	v_mul_f32_e32 v86, 0xbfb8aa3b, v89
	v_fmac_f32_e32 v87, v74, v87
	v_div_scale_f32 v74, vcc, 1.0, v84, 1.0
	v_exp_f32_e32 v86, v86
	v_mul_f32_e32 v83, v74, v87
	v_fma_f32 v88, -v85, v83, v74
	v_fmac_f32_e32 v83, v88, v87
	v_fma_f32 v74, -v85, v83, v74
	v_add_f32_e32 v85, 1.0, v86
	v_div_scale_f32 v86, s[6:7], v85, v85, 1.0
	v_rcp_f32_e32 v88, v86
	v_div_fmas_f32 v74, v74, v87, v83
	v_div_fixup_f32 v74, v74, v84, 1.0
	v_mul_f32_e32 v74, v79, v74
	v_fma_f32 v79, -v86, v88, 1.0
	v_fmac_f32_e32 v88, v79, v88
	v_div_scale_f32 v79, vcc, 1.0, v85, 1.0
	v_mul_f32_e32 v83, v79, v88
	v_fma_f32 v84, -v86, v83, v79
	v_fmac_f32_e32 v83, v84, v88
	v_fma_f32 v79, -v86, v83, v79
	v_div_fmas_f32 v79, v79, v88, v83
	v_div_fixup_f32 v79, v79, v85, 1.0
	v_mul_f32_e32 v75, v75, v79
	v_cvt_pk_bf16_f32 v72, v76, v72
	v_cvt_pk_bf16_f32 v73, v73, v74
	v_cvt_pk_bf16_f32 v74, v82, v77
	v_cvt_pk_bf16_f32 v75, v78, v75
	s_waitcnt vmcnt(14)
; __device__ __forceinline__ float sigmoidf_(float x) { return 1.0f / (1.0f + __expf(-x)); }
; __device__ __forceinline__ u32x4 pack8(const f32x4 v0, const f32x4 v1) { u32x4 w; w.x = pk2(v0[0], v0[1]); w.y = pk2(v0[2], v0[3]); w.z = pk2(v1[0], v1[1]); w.w = pk2(v1[2], v1[3]); return w; }
; __device__ __forceinline__ void unpack8(const u32x4 w, f32x4& v0, f32x4& v1) { v0 = (f32x4){bflo(w.x), bfhi(w.x), bflo(w.y), bfhi(w.y)}; v1 = (f32x4){bflo(w.z), bfhi(w.z), bflo(w.w), bfhi(w.w)}; }
;     __device__ __forceinline__ void operator()(const f32x4 (&acc)[2][2][4][2], const Unit& u, int wr, int wc, int fr, int fq) const {
;     ...
;         for (int ai = 0; ai < 2; ++ai)
; #pragma unroll
;             for (int m = 0; m < 4; ++m) {
;                 bf16_t* rowp = z + (size_t)(row0 + ai * 128 + m * 16) * DIN + col0;
; #pragma unroll
;                 for (int bj = 0; bj < 2; ++bj) {
;                     const u32x4 gw = *(const u32x4*)(rowp + (MODE == 0 ? O_GB : O_GA) + bj * 128);
;                     f32x4 g0, g1; unpack8(gw, g0, g1);
;                     f32x4 v0, v1;
; #pragma unroll
;                     for (int j = 0; j < 4; ++j) { v0[j] = sigmoidf_(g0[j]) * acc[ai][bj][m][0][j]; v1[j] = sigmoidf_(g1[j]) * acc[ai][bj][m][1][j]; }
;                     if (MODE == 1) { const u32x4 mw = *(const u32x4*)(rowp + bj * 128); f32x4 m0, m1; unpack8(mw, m0, m1); v0 += m0; v1 += m1; }
;                     *(u32x4*)(rowp + bj * 128) = pack8(v0, v1); }
	v_mov_b32_e32 v76, v240
	v_mov_b32_e32 v77, v241
	v_mov_b32_e32 v78, v242
	v_mov_b32_e32 v79, v243
	v_lshlrev_b32_e32 v83, 16, v79
	global_store_dwordx4 v[80:81], v[72:75], off sc1
	v_and_b32_e32 v79, 0xffff0000, v79
	s_nop 0
	v_lshlrev_b32_e32 v72, 16, v76
	v_mul_f32_e32 v72, 0xbfb8aa3b, v72
	v_exp_f32_e32 v72, v72
	v_lshlrev_b32_e32 v74, 16, v77
	v_and_b32_e32 v75, 0xffff0000, v77
	v_and_b32_e32 v73, 0xffff0000, v76
	v_add_f32_e32 v72, 1.0, v72
	v_div_scale_f32 v77, s[6:7], v72, v72, 1.0
	v_rcp_f32_e32 v82, v77
	v_lshlrev_b32_e32 v76, 16, v78
	v_mul_f32_e32 v76, 0xbfb8aa3b, v76
	v_exp_f32_e32 v76, v76
	v_fma_f32 v84, -v77, v82, 1.0
	v_fmac_f32_e32 v82, v84, v82
	v_div_scale_f32 v84, vcc, 1.0, v72, 1.0
	v_mul_f32_e32 v85, v84, v82
	v_fma_f32 v86, -v77, v85, v84
	v_fmac_f32_e32 v85, v86, v82
	v_add_f32_e32 v76, 1.0, v76
	v_fma_f32 v77, -v77, v85, v84
	v_div_scale_f32 v84, s[6:7], v76, v76, 1.0
	v_rcp_f32_e32 v86, v84
	v_div_fmas_f32 v77, v77, v82, v85
	v_mul_f32_e32 v73, 0xbfb8aa3b, v73
	v_div_fixup_f32 v72, v77, v72, 1.0
	v_exp_f32_e32 v73, v73
	v_mul_f32_e32 v68, v68, v72
	v_fma_f32 v72, -v84, v86, 1.0
	v_fmac_f32_e32 v86, v72, v86
	v_div_scale_f32 v72, vcc, 1.0, v76, 1.0
	v_mul_f32_e32 v77, v72, v86
	v_fma_f32 v82, -v84, v77, v72
	v_add_f32_e32 v73, 1.0, v73
	v_fmac_f32_e32 v77, v82, v86
	v_div_scale_f32 v82, s[6:7], v73, v73, 1.0
	v_fma_f32 v72, -v84, v77, v72
	v_rcp_f32_e32 v84, v82
	v_and_b32_e32 v78, 0xffff0000, v78
	v_div_fmas_f32 v72, v72, v86, v77
	v_mul_f32_e32 v77, 0xbfb8aa3b, v78
	v_div_fixup_f32 v72, v72, v76, 1.0
	v_exp_f32_e32 v77, v77
	v_mul_f32_e32 v64, v64, v72
	v_fma_f32 v72, -v82, v84, 1.0
	v_fmac_f32_e32 v84, v72, v84
	v_div_scale_f32 v72, vcc, 1.0, v73, 1.0
	v_mul_f32_e32 v76, v72, v84
	v_fma_f32 v78, -v82, v76, v72
	v_add_f32_e32 v77, 1.0, v77
	v_fmac_f32_e32 v76, v78, v84
	v_div_scale_f32 v78, s[6:7], v77, v77, 1.0
	v_fma_f32 v72, -v82, v76, v72
	v_rcp_f32_e32 v82, v78
	v_div_fmas_f32 v72, v72, v84, v76
	v_mul_f32_e32 v74, 0xbfb8aa3b, v74
	v_div_fixup_f32 v72, v72, v73, 1.0
	v_exp_f32_e32 v74, v74
	v_mul_f32_e32 v69, v69, v72
	v_fma_f32 v72, -v78, v82, 1.0
	v_fmac_f32_e32 v82, v72, v82
	v_div_scale_f32 v72, vcc, 1.0, v77, 1.0
	v_mul_f32_e32 v73, v72, v82
	v_fma_f32 v76, -v78, v73, v72
	v_add_f32_e32 v74, 1.0, v74
	v_fmac_f32_e32 v73, v76, v82
	v_div_scale_f32 v76, s[6:7], v74, v74, 1.0
	v_fma_f32 v72, -v78, v73, v72
	v_rcp_f32_e32 v78, v76
	v_div_fmas_f32 v72, v72, v82, v73
	v_div_fixup_f32 v72, v72, v77, 1.0
	v_mul_f32_e32 v65, v65, v72
	v_fma_f32 v72, -v76, v78, 1.0
	v_mul_f32_e32 v77, 0xbfb8aa3b, v83
	v_fmac_f32_e32 v78, v72, v78
	v_div_scale_f32 v72, vcc, 1.0, v74, 1.0
	v_exp_f32_e32 v77, v77
	v_mul_f32_e32 v73, v72, v78
	v_fma_f32 v82, -v76, v73, v72
	v_fmac_f32_e32 v73, v82, v78
	v_fma_f32 v72, -v76, v73, v72
	v_add_f32_e32 v76, 1.0, v77
	v_div_scale_f32 v77, s[6:7], v76, v76, 1.0
	v_rcp_f32_e32 v82, v77
	v_div_fmas_f32 v72, v72, v78, v73
	v_div_fixup_f32 v72, v72, v74, 1.0
	v_mul_f32_e32 v74, 0xbfb8aa3b, v75
	v_exp_f32_e32 v74, v74
	v_mul_f32_e32 v70, v70, v72
	v_fma_f32 v72, -v77, v82, 1.0
	v_fmac_f32_e32 v82, v72, v82
	v_div_scale_f32 v72, vcc, 1.0, v76, 1.0
	v_mul_f32_e32 v73, v72, v82
	v_fma_f32 v75, -v77, v73, v72
	v_add_f32_e32 v74, 1.0, v74
	v_fmac_f32_e32 v73, v75, v82
	v_div_scale_f32 v75, s[6:7], v74, v74, 1.0
	v_fma_f32 v72, -v77, v73, v72
	v_rcp_f32_e32 v77, v75
	v_div_fmas_f32 v72, v72, v82, v73
	v_div_fixup_f32 v72, v72, v76, 1.0
	v_mul_f32_e32 v72, v66, v72
	v_fma_f32 v66, -v75, v77, 1.0
	v_mul_f32_e32 v76, 0xbfb8aa3b, v79
	v_fmac_f32_e32 v77, v66, v77
	v_div_scale_f32 v66, vcc, 1.0, v74, 1.0
	v_exp_f32_e32 v76, v76
	v_mul_f32_e32 v73, v66, v77
	v_fma_f32 v78, -v75, v73, v66
	v_fmac_f32_e32 v73, v78, v77
	v_fma_f32 v66, -v75, v73, v66
	v_add_f32_e32 v75, 1.0, v76
	v_div_scale_f32 v76, s[6:7], v75, v75, 1.0
	v_rcp_f32_e32 v78, v76
	v_div_fmas_f32 v66, v66, v77, v73
	v_div_fixup_f32 v66, v66, v74, 1.0
	v_mul_f32_e32 v71, v71, v66
	v_fma_f32 v66, -v76, v78, 1.0
	v_fmac_f32_e32 v78, v66, v78
	v_div_scale_f32 v66, vcc, 1.0, v75, 1.0
	v_mul_f32_e32 v73, v66, v78
	v_fma_f32 v74, -v76, v73, v66
	v_fmac_f32_e32 v73, v74, v78
	v_fma_f32 v66, -v76, v73, v66
	v_div_fmas_f32 v66, v66, v78, v73
	v_div_fixup_f32 v66, v66, v75, 1.0
	v_mul_f32_e32 v73, v67, v66
	v_cvt_pk_bf16_f32 v66, v68, v69
	v_cvt_pk_bf16_f32 v67, v70, v71
	v_cvt_pk_bf16_f32 v68, v64, v65
	v_add_u32_e32 v64, 0x80, v160
	v_mad_i64_i32 v[64:65], s[6:7], v64, s57, v[146:147]
	v_lshl_add_u64 v[64:65], v[64:65], 0, v[148:149]
	v_add_co_u32_e32 v74, vcc, s58, v64
	v_cvt_pk_bf16_f32 v69, v72, v73
	global_store_dwordx4 v[80:81], v[66:69], off offset:256 sc1
	s_nop 0
	v_addc_co_u32_e32 v75, vcc, 0, v65, vcc
	s_waitcnt vmcnt(15)
; __device__ __forceinline__ float sigmoidf_(float x) { return 1.0f / (1.0f + __expf(-x)); }
; __device__ __forceinline__ u32x4 pack8(const f32x4 v0, const f32x4 v1) { u32x4 w; w.x = pk2(v0[0], v0[1]); w.y = pk2(v0[2], v0[3]); w.z = pk2(v1[0], v1[1]); w.w = pk2(v1[2], v1[3]); return w; }
; __device__ __forceinline__ void unpack8(const u32x4 w, f32x4& v0, f32x4& v1) { v0 = (f32x4){bflo(w.x), bfhi(w.x), bflo(w.y), bfhi(w.y)}; v1 = (f32x4){bflo(w.z), bfhi(w.z), bflo(w.w), bfhi(w.w)}; }
;     __device__ __forceinline__ void operator()(const f32x4 (&acc)[2][2][4][2], const Unit& u, int wr, int wc, int fr, int fq) const {
;     ...
;         for (int ai = 0; ai < 2; ++ai)
; #pragma unroll
;             for (int m = 0; m < 4; ++m) {
;                 bf16_t* rowp = z + (size_t)(row0 + ai * 128 + m * 16) * DIN + col0;
; #pragma unroll
;                 for (int bj = 0; bj < 2; ++bj) {
;                     const u32x4 gw = *(const u32x4*)(rowp + (MODE == 0 ? O_GB : O_GA) + bj * 128);
;                     f32x4 g0, g1; unpack8(gw, g0, g1);
;                     f32x4 v0, v1;
; #pragma unroll
;                     for (int j = 0; j < 4; ++j) { v0[j] = sigmoidf_(g0[j]) * acc[ai][bj][m][0][j]; v1[j] = sigmoidf_(g1[j]) * acc[ai][bj][m][1][j]; }
;                     if (MODE == 1) { const u32x4 mw = *(const u32x4*)(rowp + bj * 128); f32x4 m0, m1; unpack8(mw, m0, m1); v0 += m0; v1 += m1; }
;                     *(u32x4*)(rowp + bj * 128) = pack8(v0, v1); }
	v_mov_b32_e32 v70, v244
	v_mov_b32_e32 v71, v245
	v_mov_b32_e32 v72, v246
	v_mov_b32_e32 v73, v247
	v_lshlrev_b32_e32 v66, 16, v70
	v_mul_f32_e32 v66, 0xbfb8aa3b, v66
	v_exp_f32_e32 v66, v66
	v_lshlrev_b32_e32 v68, 16, v71
	v_and_b32_e32 v69, 0xffff0000, v71
	v_and_b32_e32 v67, 0xffff0000, v70
	v_add_f32_e32 v66, 1.0, v66
	v_div_scale_f32 v71, s[6:7], v66, v66, 1.0
	v_rcp_f32_e32 v76, v71
	v_lshlrev_b32_e32 v70, 16, v72
	v_mul_f32_e32 v70, 0xbfb8aa3b, v70
	v_exp_f32_e32 v70, v70
	v_fma_f32 v78, -v71, v76, 1.0
	v_fmac_f32_e32 v76, v78, v76
	v_div_scale_f32 v78, vcc, 1.0, v66, 1.0
	v_mul_f32_e32 v79, v78, v76
	v_fma_f32 v80, -v71, v79, v78
	v_fmac_f32_e32 v79, v80, v76
	v_add_f32_e32 v70, 1.0, v70
	v_fma_f32 v71, -v71, v79, v78
	v_div_scale_f32 v78, s[6:7], v70, v70, 1.0
	v_rcp_f32_e32 v80, v78
	v_div_fmas_f32 v71, v71, v76, v79
	v_mul_f32_e32 v67, 0xbfb8aa3b, v67
	v_div_fixup_f32 v66, v71, v66, 1.0
	v_exp_f32_e32 v67, v67
	v_mul_f32_e32 v60, v60, v66
	v_fma_f32 v66, -v78, v80, 1.0
	v_fmac_f32_e32 v80, v66, v80
	v_div_scale_f32 v66, vcc, 1.0, v70, 1.0
	v_mul_f32_e32 v71, v66, v80
	v_fma_f32 v76, -v78, v71, v66
	v_add_f32_e32 v67, 1.0, v67
	v_fmac_f32_e32 v71, v76, v80
	v_div_scale_f32 v76, s[6:7], v67, v67, 1.0
	v_fma_f32 v66, -v78, v71, v66
	v_rcp_f32_e32 v78, v76
	v_and_b32_e32 v72, 0xffff0000, v72
	v_div_fmas_f32 v66, v66, v80, v71
	v_mul_f32_e32 v71, 0xbfb8aa3b, v72
	v_div_fixup_f32 v66, v66, v70, 1.0
	v_exp_f32_e32 v71, v71
	v_mul_f32_e32 v66, v56, v66
	v_fma_f32 v56, -v76, v78, 1.0
	v_fmac_f32_e32 v78, v56, v78
	v_div_scale_f32 v56, vcc, 1.0, v67, 1.0
	v_mul_f32_e32 v70, v56, v78
	v_fma_f32 v72, -v76, v70, v56
	v_add_f32_e32 v71, 1.0, v71
	v_fmac_f32_e32 v70, v72, v78
	v_div_scale_f32 v72, s[6:7], v71, v71, 1.0
	v_fma_f32 v56, -v76, v70, v56
	v_rcp_f32_e32 v76, v72
	v_div_fmas_f32 v56, v56, v78, v70
	v_mul_f32_e32 v68, 0xbfb8aa3b, v68
	v_div_fixup_f32 v56, v56, v67, 1.0
	v_exp_f32_e32 v68, v68
	v_mul_f32_e32 v56, v61, v56
	v_fma_f32 v61, -v72, v76, 1.0
	v_fmac_f32_e32 v76, v61, v76
	v_div_scale_f32 v61, vcc, 1.0, v71, 1.0
	v_mul_f32_e32 v67, v61, v76
	v_fma_f32 v70, -v72, v67, v61
	v_add_f32_e32 v68, 1.0, v68
	v_fmac_f32_e32 v67, v70, v76
	v_div_scale_f32 v70, s[6:7], v68, v68, 1.0
	v_fma_f32 v61, -v72, v67, v61
	v_rcp_f32_e32 v72, v70
	v_div_fmas_f32 v61, v61, v76, v67
	v_lshlrev_b32_e32 v77, 16, v73
	v_div_fixup_f32 v61, v61, v71, 1.0
	v_mul_f32_e32 v61, v57, v61
	v_fma_f32 v57, -v70, v72, 1.0
	v_mul_f32_e32 v71, 0xbfb8aa3b, v77
	v_fmac_f32_e32 v72, v57, v72
	v_div_scale_f32 v57, vcc, 1.0, v68, 1.0
	v_exp_f32_e32 v71, v71
	v_mul_f32_e32 v67, v57, v72
	v_fma_f32 v76, -v70, v67, v57
	v_fmac_f32_e32 v67, v76, v72
	v_fma_f32 v57, -v70, v67, v57
	v_add_f32_e32 v70, 1.0, v71
	v_div_scale_f32 v71, s[6:7], v70, v70, 1.0
	v_rcp_f32_e32 v76, v71
	v_div_fmas_f32 v57, v57, v72, v67
	v_div_fixup_f32 v57, v57, v68, 1.0
	v_mul_f32_e32 v68, 0xbfb8aa3b, v69
	v_exp_f32_e32 v68, v68
	v_mul_f32_e32 v57, v62, v57
	v_fma_f32 v62, -v71, v76, 1.0
	v_fmac_f32_e32 v76, v62, v76
	v_div_scale_f32 v62, vcc, 1.0, v70, 1.0
	v_mul_f32_e32 v67, v62, v76
	v_fma_f32 v69, -v71, v67, v62
	v_add_f32_e32 v68, 1.0, v68
	v_fmac_f32_e32 v67, v69, v76
	v_div_scale_f32 v69, s[6:7], v68, v68, 1.0
	v_fma_f32 v62, -v71, v67, v62
	v_rcp_f32_e32 v71, v69
	v_div_fmas_f32 v62, v62, v76, v67
	v_and_b32_e32 v73, 0xffff0000, v73
	v_div_fixup_f32 v62, v62, v70, 1.0
	v_mul_f32_e32 v62, v58, v62
	v_fma_f32 v58, -v69, v71, 1.0
	v_mul_f32_e32 v70, 0xbfb8aa3b, v73
	v_fmac_f32_e32 v71, v58, v71
	v_div_scale_f32 v58, vcc, 1.0, v68, 1.0
	v_exp_f32_e32 v70, v70
	v_mul_f32_e32 v67, v58, v71
	v_fma_f32 v72, -v69, v67, v58
	v_fmac_f32_e32 v67, v72, v71
	v_fma_f32 v58, -v69, v67, v58
	v_add_f32_e32 v69, 1.0, v70
	v_div_scale_f32 v70, s[6:7], v69, v69, 1.0
	v_rcp_f32_e32 v72, v70
	v_div_fmas_f32 v58, v58, v71, v67
	v_div_fixup_f32 v58, v58, v68, 1.0
	v_mul_f32_e32 v58, v63, v58
	v_fma_f32 v63, -v70, v72, 1.0
	v_fmac_f32_e32 v72, v63, v72
	v_div_scale_f32 v63, vcc, 1.0, v69, 1.0
	v_mul_f32_e32 v67, v63, v72
	v_fma_f32 v68, -v70, v67, v63
	v_fmac_f32_e32 v67, v68, v72
	v_fma_f32 v63, -v70, v67, v63
	v_div_fmas_f32 v63, v63, v72, v67
	v_div_fixup_f32 v63, v63, v69, 1.0
	v_mul_f32_e32 v59, v59, v63
	v_cvt_pk_bf16_f32 v56, v60, v56
	v_cvt_pk_bf16_f32 v57, v57, v58
	v_cvt_pk_bf16_f32 v58, v66, v61
	v_cvt_pk_bf16_f32 v59, v62, v59
	s_waitcnt vmcnt(14)
; __device__ __forceinline__ float sigmoidf_(float x) { return 1.0f / (1.0f + __expf(-x)); }
; __device__ __forceinline__ u32x4 pack8(const f32x4 v0, const f32x4 v1) { u32x4 w; w.x = pk2(v0[0], v0[1]); w.y = pk2(v0[2], v0[3]); w.z = pk2(v1[0], v1[1]); w.w = pk2(v1[2], v1[3]); return w; }
; __device__ __forceinline__ void unpack8(const u32x4 w, f32x4& v0, f32x4& v1) { v0 = (f32x4){bflo(w.x), bfhi(w.x), bflo(w.y), bfhi(w.y)}; v1 = (f32x4){bflo(w.z), bfhi(w.z), bflo(w.w), bfhi(w.w)}; }
;     __device__ __forceinline__ void operator()(const f32x4 (&acc)[2][2][4][2], const Unit& u, int wr, int wc, int fr, int fq) const {
;     ...
;         for (int ai = 0; ai < 2; ++ai)
; #pragma unroll
;             for (int m = 0; m < 4; ++m) {
;                 bf16_t* rowp = z + (size_t)(row0 + ai * 128 + m * 16) * DIN + col0;
; #pragma unroll
;                 for (int bj = 0; bj < 2; ++bj) {
;                     const u32x4 gw = *(const u32x4*)(rowp + (MODE == 0 ? O_GB : O_GA) + bj * 128);
;                     f32x4 g0, g1; unpack8(gw, g0, g1);
;                     f32x4 v0, v1;
; #pragma unroll
;                     for (int j = 0; j < 4; ++j) { v0[j] = sigmoidf_(g0[j]) * acc[ai][bj][m][0][j]; v1[j] = sigmoidf_(g1[j]) * acc[ai][bj][m][1][j]; }
;                     if (MODE == 1) { const u32x4 mw = *(const u32x4*)(rowp + bj * 128); f32x4 m0, m1; unpack8(mw, m0, m1); v0 += m0; v1 += m1; }
;                     *(u32x4*)(rowp + bj * 128) = pack8(v0, v1); }
	v_mov_b32_e32 v60, v248
	v_mov_b32_e32 v61, v249
	v_mov_b32_e32 v62, v250
	v_mov_b32_e32 v63, v251
	v_lshlrev_b32_e32 v67, 16, v63
	global_store_dwordx4 v[64:65], v[56:59], off sc1
	v_and_b32_e32 v63, 0xffff0000, v63
	s_nop 0
	v_lshlrev_b32_e32 v56, 16, v60
	v_mul_f32_e32 v56, 0xbfb8aa3b, v56
	v_exp_f32_e32 v56, v56
	v_lshlrev_b32_e32 v58, 16, v61
	v_and_b32_e32 v59, 0xffff0000, v61
	v_and_b32_e32 v57, 0xffff0000, v60
	v_add_f32_e32 v56, 1.0, v56
	v_div_scale_f32 v61, s[6:7], v56, v56, 1.0
	v_rcp_f32_e32 v66, v61
	v_lshlrev_b32_e32 v60, 16, v62
	v_mul_f32_e32 v60, 0xbfb8aa3b, v60
	v_exp_f32_e32 v60, v60
	v_fma_f32 v68, -v61, v66, 1.0
	v_fmac_f32_e32 v66, v68, v66
	v_div_scale_f32 v68, vcc, 1.0, v56, 1.0
	v_mul_f32_e32 v69, v68, v66
	v_fma_f32 v70, -v61, v69, v68
	v_fmac_f32_e32 v69, v70, v66
	v_add_f32_e32 v60, 1.0, v60
	v_fma_f32 v61, -v61, v69, v68
	v_div_scale_f32 v68, s[6:7], v60, v60, 1.0
	v_rcp_f32_e32 v70, v68
	v_div_fmas_f32 v61, v61, v66, v69
	v_mul_f32_e32 v57, 0xbfb8aa3b, v57
	v_div_fixup_f32 v56, v61, v56, 1.0
	v_exp_f32_e32 v57, v57
	v_mul_f32_e32 v52, v52, v56
	v_fma_f32 v56, -v68, v70, 1.0
	v_fmac_f32_e32 v70, v56, v70
	v_div_scale_f32 v56, vcc, 1.0, v60, 1.0
	v_mul_f32_e32 v61, v56, v70
	v_fma_f32 v66, -v68, v61, v56
	v_add_f32_e32 v57, 1.0, v57
	v_fmac_f32_e32 v61, v66, v70
	v_div_scale_f32 v66, s[6:7], v57, v57, 1.0
	v_fma_f32 v56, -v68, v61, v56
	v_rcp_f32_e32 v68, v66
	v_and_b32_e32 v62, 0xffff0000, v62
	v_div_fmas_f32 v56, v56, v70, v61
	v_mul_f32_e32 v61, 0xbfb8aa3b, v62
	v_div_fixup_f32 v56, v56, v60, 1.0
	v_exp_f32_e32 v61, v61
	v_mul_f32_e32 v48, v48, v56
	v_fma_f32 v56, -v66, v68, 1.0
	v_fmac_f32_e32 v68, v56, v68
	v_div_scale_f32 v56, vcc, 1.0, v57, 1.0
	v_mul_f32_e32 v60, v56, v68
	v_fma_f32 v62, -v66, v60, v56
	v_add_f32_e32 v61, 1.0, v61
	v_fmac_f32_e32 v60, v62, v68
	v_div_scale_f32 v62, s[6:7], v61, v61, 1.0
	v_fma_f32 v56, -v66, v60, v56
	v_rcp_f32_e32 v66, v62
	v_div_fmas_f32 v56, v56, v68, v60
	v_mul_f32_e32 v58, 0xbfb8aa3b, v58
	v_div_fixup_f32 v56, v56, v57, 1.0
	v_exp_f32_e32 v58, v58
	v_mul_f32_e32 v53, v53, v56
	v_fma_f32 v56, -v62, v66, 1.0
	v_fmac_f32_e32 v66, v56, v66
	v_div_scale_f32 v56, vcc, 1.0, v61, 1.0
	v_mul_f32_e32 v57, v56, v66
	v_fma_f32 v60, -v62, v57, v56
	v_add_f32_e32 v58, 1.0, v58
	v_fmac_f32_e32 v57, v60, v66
	v_div_scale_f32 v60, s[6:7], v58, v58, 1.0
	v_fma_f32 v56, -v62, v57, v56
	v_rcp_f32_e32 v62, v60
	v_div_fmas_f32 v56, v56, v66, v57
	v_div_fixup_f32 v56, v56, v61, 1.0
	v_mul_f32_e32 v49, v49, v56
	v_fma_f32 v56, -v60, v62, 1.0
	v_mul_f32_e32 v61, 0xbfb8aa3b, v67
	v_fmac_f32_e32 v62, v56, v62
	v_div_scale_f32 v56, vcc, 1.0, v58, 1.0
	v_exp_f32_e32 v61, v61
	v_mul_f32_e32 v57, v56, v62
	v_fma_f32 v66, -v60, v57, v56
	v_fmac_f32_e32 v57, v66, v62
	v_fma_f32 v56, -v60, v57, v56
	v_add_f32_e32 v60, 1.0, v61
	v_div_scale_f32 v61, s[6:7], v60, v60, 1.0
	v_rcp_f32_e32 v66, v61
	v_div_fmas_f32 v56, v56, v62, v57
	v_div_fixup_f32 v56, v56, v58, 1.0
	v_mul_f32_e32 v58, 0xbfb8aa3b, v59
	v_exp_f32_e32 v58, v58
	v_mul_f32_e32 v54, v54, v56
	v_fma_f32 v56, -v61, v66, 1.0
	v_fmac_f32_e32 v66, v56, v66
	v_div_scale_f32 v56, vcc, 1.0, v60, 1.0
	v_mul_f32_e32 v57, v56, v66
	v_fma_f32 v59, -v61, v57, v56
	v_add_f32_e32 v58, 1.0, v58
	v_fmac_f32_e32 v57, v59, v66
	v_div_scale_f32 v59, s[6:7], v58, v58, 1.0
	v_fma_f32 v56, -v61, v57, v56
	v_rcp_f32_e32 v61, v59
	v_div_fmas_f32 v56, v56, v66, v57
	v_div_fixup_f32 v56, v56, v60, 1.0
	v_mul_f32_e32 v56, v50, v56
	v_fma_f32 v50, -v59, v61, 1.0
	v_mul_f32_e32 v60, 0xbfb8aa3b, v63
	v_fmac_f32_e32 v61, v50, v61
	v_div_scale_f32 v50, vcc, 1.0, v58, 1.0
	v_exp_f32_e32 v60, v60
	v_mul_f32_e32 v57, v50, v61
	v_fma_f32 v62, -v59, v57, v50
	v_fmac_f32_e32 v57, v62, v61
	v_fma_f32 v50, -v59, v57, v50
	v_add_f32_e32 v59, 1.0, v60
	v_div_scale_f32 v60, s[6:7], v59, v59, 1.0
	v_rcp_f32_e32 v62, v60
	v_div_fmas_f32 v50, v50, v61, v57
	v_div_fixup_f32 v50, v50, v58, 1.0
	v_mul_f32_e32 v55, v55, v50
	v_fma_f32 v50, -v60, v62, 1.0
	v_fmac_f32_e32 v62, v50, v62
	v_div_scale_f32 v50, vcc, 1.0, v59, 1.0
	v_mul_f32_e32 v57, v50, v62
	v_fma_f32 v58, -v60, v57, v50
	v_fmac_f32_e32 v57, v58, v62
	v_fma_f32 v50, -v60, v57, v50
	v_div_fmas_f32 v50, v50, v62, v57
	v_div_fixup_f32 v50, v50, v59, 1.0
	v_mul_f32_e32 v57, v51, v50
	v_cvt_pk_bf16_f32 v50, v52, v53
	v_cvt_pk_bf16_f32 v51, v54, v55
	v_cvt_pk_bf16_f32 v52, v48, v49
	v_add_u32_e32 v48, 0x90, v160
	v_mad_i64_i32 v[48:49], s[6:7], v48, s57, v[146:147]
	v_lshl_add_u64 v[48:49], v[48:49], 0, v[148:149]
	v_add_co_u32_e32 v58, vcc, s58, v48
	v_cvt_pk_bf16_f32 v53, v56, v57
	global_store_dwordx4 v[64:65], v[50:53], off offset:256 sc1
	s_nop 0
	v_addc_co_u32_e32 v59, vcc, 0, v49, vcc
	s_waitcnt vmcnt(15)
; __device__ __forceinline__ float sigmoidf_(float x) { return 1.0f / (1.0f + __expf(-x)); }
; __device__ __forceinline__ u32x4 pack8(const f32x4 v0, const f32x4 v1) { u32x4 w; w.x = pk2(v0[0], v0[1]); w.y = pk2(v0[2], v0[3]); w.z = pk2(v1[0], v1[1]); w.w = pk2(v1[2], v1[3]); return w; }
; __device__ __forceinline__ void unpack8(const u32x4 w, f32x4& v0, f32x4& v1) { v0 = (f32x4){bflo(w.x), bfhi(w.x), bflo(w.y), bfhi(w.y)}; v1 = (f32x4){bflo(w.z), bfhi(w.z), bflo(w.w), bfhi(w.w)}; }
;     __device__ __forceinline__ void operator()(const f32x4 (&acc)[2][2][4][2], const Unit& u, int wr, int wc, int fr, int fq) const {
;     ...
;         for (int ai = 0; ai < 2; ++ai)
; #pragma unroll
;             for (int m = 0; m < 4; ++m) {
;                 bf16_t* rowp = z + (size_t)(row0 + ai * 128 + m * 16) * DIN + col0;
; #pragma unroll
;                 for (int bj = 0; bj < 2; ++bj) {
;                     const u32x4 gw = *(const u32x4*)(rowp + (MODE == 0 ? O_GB : O_GA) + bj * 128);
;                     f32x4 g0, g1; unpack8(gw, g0, g1);
;                     f32x4 v0, v1;
; #pragma unroll
;                     for (int j = 0; j < 4; ++j) { v0[j] = sigmoidf_(g0[j]) * acc[ai][bj][m][0][j]; v1[j] = sigmoidf_(g1[j]) * acc[ai][bj][m][1][j]; }
;                     if (MODE == 1) { const u32x4 mw = *(const u32x4*)(rowp + bj * 128); f32x4 m0, m1; unpack8(mw, m0, m1); v0 += m0; v1 += m1; }
;                     *(u32x4*)(rowp + bj * 128) = pack8(v0, v1); }
	v_mov_b32_e32 v54, v252
	v_mov_b32_e32 v55, v253
	v_mov_b32_e32 v56, v254
	v_mov_b32_e32 v57, v255
	v_lshlrev_b32_e32 v50, 16, v54
	v_mul_f32_e32 v50, 0xbfb8aa3b, v50
	v_exp_f32_e32 v50, v50
	v_lshlrev_b32_e32 v52, 16, v55
	v_and_b32_e32 v53, 0xffff0000, v55
	v_and_b32_e32 v51, 0xffff0000, v54
	v_add_f32_e32 v50, 1.0, v50
	v_div_scale_f32 v55, s[6:7], v50, v50, 1.0
	v_rcp_f32_e32 v60, v55
	v_lshlrev_b32_e32 v54, 16, v56
	v_mul_f32_e32 v54, 0xbfb8aa3b, v54
	v_exp_f32_e32 v54, v54
	v_fma_f32 v62, -v55, v60, 1.0
	v_fmac_f32_e32 v60, v62, v60
	v_div_scale_f32 v62, vcc, 1.0, v50, 1.0
	v_mul_f32_e32 v63, v62, v60
	v_fma_f32 v64, -v55, v63, v62
	v_fmac_f32_e32 v63, v64, v60
	v_add_f32_e32 v54, 1.0, v54
	v_fma_f32 v55, -v55, v63, v62
	v_div_scale_f32 v62, s[6:7], v54, v54, 1.0
	v_rcp_f32_e32 v64, v62
	v_div_fmas_f32 v55, v55, v60, v63
	v_mul_f32_e32 v51, 0xbfb8aa3b, v51
	v_div_fixup_f32 v50, v55, v50, 1.0
	v_exp_f32_e32 v51, v51
	v_mul_f32_e32 v44, v44, v50
	v_fma_f32 v50, -v62, v64, 1.0
	v_fmac_f32_e32 v64, v50, v64
	v_div_scale_f32 v50, vcc, 1.0, v54, 1.0
	v_mul_f32_e32 v55, v50, v64
	v_fma_f32 v60, -v62, v55, v50
	v_add_f32_e32 v51, 1.0, v51
	v_fmac_f32_e32 v55, v60, v64
	v_div_scale_f32 v60, s[6:7], v51, v51, 1.0
	v_fma_f32 v50, -v62, v55, v50
	v_rcp_f32_e32 v62, v60
	v_and_b32_e32 v56, 0xffff0000, v56
	v_div_fmas_f32 v50, v50, v64, v55
	v_mul_f32_e32 v55, 0xbfb8aa3b, v56
	v_div_fixup_f32 v50, v50, v54, 1.0
	v_exp_f32_e32 v55, v55
	v_mul_f32_e32 v50, v40, v50
	v_fma_f32 v40, -v60, v62, 1.0
	v_fmac_f32_e32 v62, v40, v62
	v_div_scale_f32 v40, vcc, 1.0, v51, 1.0
	v_mul_f32_e32 v54, v40, v62
	v_fma_f32 v56, -v60, v54, v40
	v_add_f32_e32 v55, 1.0, v55
	v_fmac_f32_e32 v54, v56, v62
	v_div_scale_f32 v56, s[6:7], v55, v55, 1.0
	v_fma_f32 v40, -v60, v54, v40
	v_rcp_f32_e32 v60, v56
	v_div_fmas_f32 v40, v40, v62, v54
	v_mul_f32_e32 v52, 0xbfb8aa3b, v52
	v_div_fixup_f32 v40, v40, v51, 1.0
	v_exp_f32_e32 v52, v52
	v_mul_f32_e32 v40, v45, v40
	v_fma_f32 v45, -v56, v60, 1.0
	v_fmac_f32_e32 v60, v45, v60
	v_div_scale_f32 v45, vcc, 1.0, v55, 1.0
	v_mul_f32_e32 v51, v45, v60
	v_fma_f32 v54, -v56, v51, v45
	v_add_f32_e32 v52, 1.0, v52
	v_fmac_f32_e32 v51, v54, v60
	v_div_scale_f32 v54, s[6:7], v52, v52, 1.0
	v_fma_f32 v45, -v56, v51, v45
	v_rcp_f32_e32 v56, v54
	v_div_fmas_f32 v45, v45, v60, v51
	v_lshlrev_b32_e32 v61, 16, v57
	v_div_fixup_f32 v45, v45, v55, 1.0
	v_mul_f32_e32 v45, v41, v45
	v_fma_f32 v41, -v54, v56, 1.0
	v_mul_f32_e32 v55, 0xbfb8aa3b, v61
	v_fmac_f32_e32 v56, v41, v56
	v_div_scale_f32 v41, vcc, 1.0, v52, 1.0
	v_exp_f32_e32 v55, v55
	v_mul_f32_e32 v51, v41, v56
	v_fma_f32 v60, -v54, v51, v41
	v_fmac_f32_e32 v51, v60, v56
	v_fma_f32 v41, -v54, v51, v41
	v_add_f32_e32 v54, 1.0, v55
	v_div_scale_f32 v55, s[6:7], v54, v54, 1.0
	v_rcp_f32_e32 v60, v55
	v_div_fmas_f32 v41, v41, v56, v51
	v_div_fixup_f32 v41, v41, v52, 1.0
	v_mul_f32_e32 v52, 0xbfb8aa3b, v53
	v_exp_f32_e32 v52, v52
	v_mul_f32_e32 v41, v46, v41
	v_fma_f32 v46, -v55, v60, 1.0
	v_fmac_f32_e32 v60, v46, v60
	v_div_scale_f32 v46, vcc, 1.0, v54, 1.0
	v_mul_f32_e32 v51, v46, v60
	v_fma_f32 v53, -v55, v51, v46
	v_add_f32_e32 v52, 1.0, v52
	v_fmac_f32_e32 v51, v53, v60
	v_div_scale_f32 v53, s[6:7], v52, v52, 1.0
	v_fma_f32 v46, -v55, v51, v46
	v_rcp_f32_e32 v55, v53
	v_div_fmas_f32 v46, v46, v60, v51
	v_and_b32_e32 v57, 0xffff0000, v57
	v_div_fixup_f32 v46, v46, v54, 1.0
	v_mul_f32_e32 v46, v42, v46
	v_fma_f32 v42, -v53, v55, 1.0
	v_mul_f32_e32 v54, 0xbfb8aa3b, v57
	v_fmac_f32_e32 v55, v42, v55
	v_div_scale_f32 v42, vcc, 1.0, v52, 1.0
	v_exp_f32_e32 v54, v54
	v_mul_f32_e32 v51, v42, v55
	v_fma_f32 v56, -v53, v51, v42
	v_fmac_f32_e32 v51, v56, v55
	v_fma_f32 v42, -v53, v51, v42
	v_add_f32_e32 v53, 1.0, v54
	v_div_scale_f32 v54, s[6:7], v53, v53, 1.0
	v_rcp_f32_e32 v56, v54
	v_div_fmas_f32 v42, v42, v55, v51
	v_div_fixup_f32 v42, v42, v52, 1.0
	v_mul_f32_e32 v42, v47, v42
	v_fma_f32 v47, -v54, v56, 1.0
	v_fmac_f32_e32 v56, v47, v56
	v_div_scale_f32 v47, vcc, 1.0, v53, 1.0
	v_mul_f32_e32 v51, v47, v56
	v_fma_f32 v52, -v54, v51, v47
	v_fmac_f32_e32 v51, v52, v56
	v_fma_f32 v47, -v54, v51, v47
	v_div_fmas_f32 v47, v47, v56, v51
	v_div_fixup_f32 v47, v47, v53, 1.0
	v_mul_f32_e32 v43, v43, v47
	v_cvt_pk_bf16_f32 v40, v44, v40
	v_cvt_pk_bf16_f32 v41, v41, v42
	v_cvt_pk_bf16_f32 v42, v50, v45
	v_cvt_pk_bf16_f32 v43, v46, v43
	s_waitcnt vmcnt(14)
; __device__ __forceinline__ float sigmoidf_(float x) { return 1.0f / (1.0f + __expf(-x)); }
; __device__ __forceinline__ u32x4 pack8(const f32x4 v0, const f32x4 v1) { u32x4 w; w.x = pk2(v0[0], v0[1]); w.y = pk2(v0[2], v0[3]); w.z = pk2(v1[0], v1[1]); w.w = pk2(v1[2], v1[3]); return w; }
; __device__ __forceinline__ void unpack8(const u32x4 w, f32x4& v0, f32x4& v1) { v0 = (f32x4){bflo(w.x), bfhi(w.x), bflo(w.y), bfhi(w.y)}; v1 = (f32x4){bflo(w.z), bfhi(w.z), bflo(w.w), bfhi(w.w)}; }
;     __device__ __forceinline__ void operator()(const f32x4 (&acc)[2][2][4][2], const Unit& u, int wr, int wc, int fr, int fq) const {
;     ...
;         for (int ai = 0; ai < 2; ++ai)
; #pragma unroll
;             for (int m = 0; m < 4; ++m) {
;                 bf16_t* rowp = z + (size_t)(row0 + ai * 128 + m * 16) * DIN + col0;
; #pragma unroll
;                 for (int bj = 0; bj < 2; ++bj) {
;                     const u32x4 gw = *(const u32x4*)(rowp + (MODE == 0 ? O_GB : O_GA) + bj * 128);
;                     f32x4 g0, g1; unpack8(gw, g0, g1);
;                     f32x4 v0, v1;
; #pragma unroll
;                     for (int j = 0; j < 4; ++j) { v0[j] = sigmoidf_(g0[j]) * acc[ai][bj][m][0][j]; v1[j] = sigmoidf_(g1[j]) * acc[ai][bj][m][1][j]; }
;                     if (MODE == 1) { const u32x4 mw = *(const u32x4*)(rowp + bj * 128); f32x4 m0, m1; unpack8(mw, m0, m1); v0 += m0; v1 += m1; }
;                     *(u32x4*)(rowp + bj * 128) = pack8(v0, v1); }
	v_mov_b32_e32 v44, v200
	v_mov_b32_e32 v45, v201
	v_mov_b32_e32 v46, v202
	v_mov_b32_e32 v47, v203
	v_lshlrev_b32_e32 v51, 16, v47
	global_store_dwordx4 v[48:49], v[40:43], off sc1
	v_and_b32_e32 v47, 0xffff0000, v47
	s_nop 0
	v_lshlrev_b32_e32 v40, 16, v44
	v_mul_f32_e32 v40, 0xbfb8aa3b, v40
	v_exp_f32_e32 v40, v40
	v_lshlrev_b32_e32 v42, 16, v45
	v_and_b32_e32 v43, 0xffff0000, v45
	v_and_b32_e32 v41, 0xffff0000, v44
	v_add_f32_e32 v40, 1.0, v40
	v_div_scale_f32 v45, s[6:7], v40, v40, 1.0
	v_rcp_f32_e32 v50, v45
	v_lshlrev_b32_e32 v44, 16, v46
	v_mul_f32_e32 v44, 0xbfb8aa3b, v44
	v_exp_f32_e32 v44, v44
	v_fma_f32 v52, -v45, v50, 1.0
	v_fmac_f32_e32 v50, v52, v50
	v_div_scale_f32 v52, vcc, 1.0, v40, 1.0
	v_mul_f32_e32 v53, v52, v50
	v_fma_f32 v54, -v45, v53, v52
	v_fmac_f32_e32 v53, v54, v50
	v_add_f32_e32 v44, 1.0, v44
	v_fma_f32 v45, -v45, v53, v52
	v_div_scale_f32 v52, s[6:7], v44, v44, 1.0
	v_rcp_f32_e32 v54, v52
	v_div_fmas_f32 v45, v45, v50, v53
	v_mul_f32_e32 v41, 0xbfb8aa3b, v41
	v_div_fixup_f32 v40, v45, v40, 1.0
	v_exp_f32_e32 v41, v41
	v_mul_f32_e32 v36, v36, v40
	v_fma_f32 v40, -v52, v54, 1.0
	v_fmac_f32_e32 v54, v40, v54
	v_div_scale_f32 v40, vcc, 1.0, v44, 1.0
	v_mul_f32_e32 v45, v40, v54
	v_fma_f32 v50, -v52, v45, v40
	v_add_f32_e32 v41, 1.0, v41
	v_fmac_f32_e32 v45, v50, v54
	v_div_scale_f32 v50, s[6:7], v41, v41, 1.0
	v_fma_f32 v40, -v52, v45, v40
	v_rcp_f32_e32 v52, v50
	v_and_b32_e32 v46, 0xffff0000, v46
	v_div_fmas_f32 v40, v40, v54, v45
	v_mul_f32_e32 v45, 0xbfb8aa3b, v46
	v_div_fixup_f32 v40, v40, v44, 1.0
	v_exp_f32_e32 v45, v45
	v_mul_f32_e32 v32, v32, v40
	v_fma_f32 v40, -v50, v52, 1.0
	v_fmac_f32_e32 v52, v40, v52
	v_div_scale_f32 v40, vcc, 1.0, v41, 1.0
	v_mul_f32_e32 v44, v40, v52
	v_fma_f32 v46, -v50, v44, v40
	v_add_f32_e32 v45, 1.0, v45
	v_fmac_f32_e32 v44, v46, v52
	v_div_scale_f32 v46, s[6:7], v45, v45, 1.0
	v_fma_f32 v40, -v50, v44, v40
	v_rcp_f32_e32 v50, v46
	v_div_fmas_f32 v40, v40, v52, v44
	v_mul_f32_e32 v42, 0xbfb8aa3b, v42
	v_div_fixup_f32 v40, v40, v41, 1.0
	v_exp_f32_e32 v42, v42
	v_mul_f32_e32 v37, v37, v40
	v_fma_f32 v40, -v46, v50, 1.0
	v_fmac_f32_e32 v50, v40, v50
	v_div_scale_f32 v40, vcc, 1.0, v45, 1.0
	v_mul_f32_e32 v41, v40, v50
	v_fma_f32 v44, -v46, v41, v40
	v_add_f32_e32 v42, 1.0, v42
	v_fmac_f32_e32 v41, v44, v50
	v_div_scale_f32 v44, s[6:7], v42, v42, 1.0
	v_fma_f32 v40, -v46, v41, v40
	v_rcp_f32_e32 v46, v44
	v_div_fmas_f32 v40, v40, v50, v41
	v_div_fixup_f32 v40, v40, v45, 1.0
	v_mul_f32_e32 v33, v33, v40
	v_fma_f32 v40, -v44, v46, 1.0
	v_mul_f32_e32 v45, 0xbfb8aa3b, v51
	v_fmac_f32_e32 v46, v40, v46
	v_div_scale_f32 v40, vcc, 1.0, v42, 1.0
	v_exp_f32_e32 v45, v45
	v_mul_f32_e32 v41, v40, v46
	v_fma_f32 v50, -v44, v41, v40
	v_fmac_f32_e32 v41, v50, v46
	v_fma_f32 v40, -v44, v41, v40
	v_add_f32_e32 v44, 1.0, v45
	v_div_scale_f32 v45, s[6:7], v44, v44, 1.0
	v_rcp_f32_e32 v50, v45
	v_div_fmas_f32 v40, v40, v46, v41
	v_div_fixup_f32 v40, v40, v42, 1.0
	v_mul_f32_e32 v42, 0xbfb8aa3b, v43
	v_exp_f32_e32 v42, v42
	v_mul_f32_e32 v38, v38, v40
	v_fma_f32 v40, -v45, v50, 1.0
	v_fmac_f32_e32 v50, v40, v50
	v_div_scale_f32 v40, vcc, 1.0, v44, 1.0
	v_mul_f32_e32 v41, v40, v50
	v_fma_f32 v43, -v45, v41, v40
	v_add_f32_e32 v42, 1.0, v42
	v_fmac_f32_e32 v41, v43, v50
	v_div_scale_f32 v43, s[6:7], v42, v42, 1.0
	v_fma_f32 v40, -v45, v41, v40
	v_rcp_f32_e32 v45, v43
	v_div_fmas_f32 v40, v40, v50, v41
	v_div_fixup_f32 v40, v40, v44, 1.0
	v_mul_f32_e32 v40, v34, v40
	v_fma_f32 v34, -v43, v45, 1.0
	v_mul_f32_e32 v44, 0xbfb8aa3b, v47
	v_fmac_f32_e32 v45, v34, v45
	v_div_scale_f32 v34, vcc, 1.0, v42, 1.0
	v_exp_f32_e32 v44, v44
	v_mul_f32_e32 v41, v34, v45
	v_fma_f32 v46, -v43, v41, v34
	v_fmac_f32_e32 v41, v46, v45
	v_fma_f32 v34, -v43, v41, v34
	v_add_f32_e32 v43, 1.0, v44
	v_div_scale_f32 v44, s[6:7], v43, v43, 1.0
	v_rcp_f32_e32 v46, v44
	v_div_fmas_f32 v34, v34, v45, v41
	v_div_fixup_f32 v34, v34, v42, 1.0
	v_mul_f32_e32 v39, v39, v34
	v_fma_f32 v34, -v44, v46, 1.0
	v_fmac_f32_e32 v46, v34, v46
	v_div_scale_f32 v34, vcc, 1.0, v43, 1.0
	v_mul_f32_e32 v41, v34, v46
	v_fma_f32 v42, -v44, v41, v34
	v_fmac_f32_e32 v41, v42, v46
	v_fma_f32 v34, -v44, v41, v34
	v_div_fmas_f32 v34, v34, v46, v41
	v_div_fixup_f32 v34, v34, v43, 1.0
	v_mul_f32_e32 v41, v35, v34
	v_cvt_pk_bf16_f32 v34, v36, v37
	v_cvt_pk_bf16_f32 v35, v38, v39
	v_cvt_pk_bf16_f32 v36, v32, v33
	v_add_u32_e32 v32, 0xa0, v160
	v_mad_i64_i32 v[32:33], s[6:7], v32, s57, v[146:147]
	v_lshl_add_u64 v[32:33], v[32:33], 0, v[148:149]
	v_add_co_u32_e32 v42, vcc, s58, v32
	v_cvt_pk_bf16_f32 v37, v40, v41
	global_store_dwordx4 v[48:49], v[34:37], off offset:256 sc1
	s_nop 0
	v_addc_co_u32_e32 v43, vcc, 0, v33, vcc
	s_waitcnt vmcnt(14)
; __device__ __forceinline__ float sigmoidf_(float x) { return 1.0f / (1.0f + __expf(-x)); }
; __device__ __forceinline__ u32x4 pack8(const f32x4 v0, const f32x4 v1) { u32x4 w; w.x = pk2(v0[0], v0[1]); w.y = pk2(v0[2], v0[3]); w.z = pk2(v1[0], v1[1]); w.w = pk2(v1[2], v1[3]); return w; }
; __device__ __forceinline__ void unpack8(const u32x4 w, f32x4& v0, f32x4& v1) { v0 = (f32x4){bflo(w.x), bfhi(w.x), bflo(w.y), bfhi(w.y)}; v1 = (f32x4){bflo(w.z), bfhi(w.z), bflo(w.w), bfhi(w.w)}; }
;     __device__ __forceinline__ void operator()(const f32x4 (&acc)[2][2][4][2], const Unit& u, int wr, int wc, int fr, int fq) const {
;     ...
;         for (int ai = 0; ai < 2; ++ai)
; #pragma unroll
;             for (int m = 0; m < 4; ++m) {
;                 bf16_t* rowp = z + (size_t)(row0 + ai * 128 + m * 16) * DIN + col0;
; #pragma unroll
;                 for (int bj = 0; bj < 2; ++bj) {
;                     const u32x4 gw = *(const u32x4*)(rowp + (MODE == 0 ? O_GB : O_GA) + bj * 128);
;                     f32x4 g0, g1; unpack8(gw, g0, g1);
;                     f32x4 v0, v1;
; #pragma unroll
;                     for (int j = 0; j < 4; ++j) { v0[j] = sigmoidf_(g0[j]) * acc[ai][bj][m][0][j]; v1[j] = sigmoidf_(g1[j]) * acc[ai][bj][m][1][j]; }
;                     if (MODE == 1) { const u32x4 mw = *(const u32x4*)(rowp + bj * 128); f32x4 m0, m1; unpack8(mw, m0, m1); v0 += m0; v1 += m1; }
;                     *(u32x4*)(rowp + bj * 128) = pack8(v0, v1); }
	v_mov_b32_e32 v38, v204
	v_mov_b32_e32 v39, v205
	v_mov_b32_e32 v40, v206
	v_mov_b32_e32 v41, v207
	v_lshlrev_b32_e32 v34, 16, v38
	v_mul_f32_e32 v34, 0xbfb8aa3b, v34
	v_exp_f32_e32 v34, v34
	v_lshlrev_b32_e32 v36, 16, v39
	v_and_b32_e32 v37, 0xffff0000, v39
	v_and_b32_e32 v35, 0xffff0000, v38
	v_add_f32_e32 v34, 1.0, v34
	v_div_scale_f32 v39, s[6:7], v34, v34, 1.0
	v_rcp_f32_e32 v44, v39
	v_lshlrev_b32_e32 v38, 16, v40
	v_mul_f32_e32 v38, 0xbfb8aa3b, v38
	v_exp_f32_e32 v38, v38
	v_fma_f32 v46, -v39, v44, 1.0
	v_fmac_f32_e32 v44, v46, v44
	v_div_scale_f32 v46, vcc, 1.0, v34, 1.0
	v_mul_f32_e32 v47, v46, v44
	v_fma_f32 v48, -v39, v47, v46
	v_fmac_f32_e32 v47, v48, v44
	v_add_f32_e32 v38, 1.0, v38
	v_fma_f32 v39, -v39, v47, v46
	v_div_scale_f32 v46, s[6:7], v38, v38, 1.0
	v_rcp_f32_e32 v48, v46
	v_div_fmas_f32 v39, v39, v44, v47
	v_mul_f32_e32 v35, 0xbfb8aa3b, v35
	v_div_fixup_f32 v34, v39, v34, 1.0
	v_exp_f32_e32 v35, v35
	v_mul_f32_e32 v28, v28, v34
	v_fma_f32 v34, -v46, v48, 1.0
	v_fmac_f32_e32 v48, v34, v48
	v_div_scale_f32 v34, vcc, 1.0, v38, 1.0
	v_mul_f32_e32 v39, v34, v48
	v_fma_f32 v44, -v46, v39, v34
	v_add_f32_e32 v35, 1.0, v35
	v_fmac_f32_e32 v39, v44, v48
	v_div_scale_f32 v44, s[6:7], v35, v35, 1.0
	v_fma_f32 v34, -v46, v39, v34
	v_rcp_f32_e32 v46, v44
	v_and_b32_e32 v40, 0xffff0000, v40
	v_div_fmas_f32 v34, v34, v48, v39
	v_mul_f32_e32 v39, 0xbfb8aa3b, v40
	v_div_fixup_f32 v34, v34, v38, 1.0
	v_exp_f32_e32 v39, v39
	v_mul_f32_e32 v34, v24, v34
	v_fma_f32 v24, -v44, v46, 1.0
	v_fmac_f32_e32 v46, v24, v46
	v_div_scale_f32 v24, vcc, 1.0, v35, 1.0
	v_mul_f32_e32 v38, v24, v46
	v_fma_f32 v40, -v44, v38, v24
	v_add_f32_e32 v39, 1.0, v39
	v_fmac_f32_e32 v38, v40, v46
	v_div_scale_f32 v40, s[6:7], v39, v39, 1.0
	v_fma_f32 v24, -v44, v38, v24
	v_rcp_f32_e32 v44, v40
	v_div_fmas_f32 v24, v24, v46, v38
	v_mul_f32_e32 v36, 0xbfb8aa3b, v36
	v_div_fixup_f32 v24, v24, v35, 1.0
	v_exp_f32_e32 v36, v36
	v_mul_f32_e32 v24, v29, v24
	v_fma_f32 v29, -v40, v44, 1.0
	v_fmac_f32_e32 v44, v29, v44
	v_div_scale_f32 v29, vcc, 1.0, v39, 1.0
	v_mul_f32_e32 v35, v29, v44
	v_fma_f32 v38, -v40, v35, v29
	v_add_f32_e32 v36, 1.0, v36
	v_fmac_f32_e32 v35, v38, v44
	v_div_scale_f32 v38, s[6:7], v36, v36, 1.0
	v_fma_f32 v29, -v40, v35, v29
	v_rcp_f32_e32 v40, v38
	v_div_fmas_f32 v29, v29, v44, v35
	v_lshlrev_b32_e32 v45, 16, v41
	v_div_fixup_f32 v29, v29, v39, 1.0
	v_mul_f32_e32 v29, v25, v29
	v_fma_f32 v25, -v38, v40, 1.0
	v_mul_f32_e32 v39, 0xbfb8aa3b, v45
	v_fmac_f32_e32 v40, v25, v40
	v_div_scale_f32 v25, vcc, 1.0, v36, 1.0
	v_exp_f32_e32 v39, v39
	v_mul_f32_e32 v35, v25, v40
	v_fma_f32 v44, -v38, v35, v25
	v_fmac_f32_e32 v35, v44, v40
	v_fma_f32 v25, -v38, v35, v25
	v_add_f32_e32 v38, 1.0, v39
	v_div_scale_f32 v39, s[6:7], v38, v38, 1.0
	v_rcp_f32_e32 v44, v39
	v_div_fmas_f32 v25, v25, v40, v35
	v_div_fixup_f32 v25, v25, v36, 1.0
	v_mul_f32_e32 v36, 0xbfb8aa3b, v37
	v_exp_f32_e32 v36, v36
	v_mul_f32_e32 v25, v30, v25
	v_fma_f32 v30, -v39, v44, 1.0
	v_fmac_f32_e32 v44, v30, v44
	v_div_scale_f32 v30, vcc, 1.0, v38, 1.0
	v_mul_f32_e32 v35, v30, v44
	v_fma_f32 v37, -v39, v35, v30
	v_add_f32_e32 v36, 1.0, v36
	v_fmac_f32_e32 v35, v37, v44
	v_div_scale_f32 v37, s[6:7], v36, v36, 1.0
	v_fma_f32 v30, -v39, v35, v30
	v_rcp_f32_e32 v39, v37
	v_div_fmas_f32 v30, v30, v44, v35
	v_and_b32_e32 v41, 0xffff0000, v41
	v_div_fixup_f32 v30, v30, v38, 1.0
	v_mul_f32_e32 v30, v26, v30
	v_fma_f32 v26, -v37, v39, 1.0
	v_mul_f32_e32 v38, 0xbfb8aa3b, v41
	v_fmac_f32_e32 v39, v26, v39
	v_div_scale_f32 v26, vcc, 1.0, v36, 1.0
	v_exp_f32_e32 v38, v38
	v_mul_f32_e32 v35, v26, v39
	v_fma_f32 v40, -v37, v35, v26
	v_fmac_f32_e32 v35, v40, v39
	v_fma_f32 v26, -v37, v35, v26
	v_add_f32_e32 v37, 1.0, v38
	v_div_scale_f32 v38, s[6:7], v37, v37, 1.0
	v_rcp_f32_e32 v40, v38
	v_div_fmas_f32 v26, v26, v39, v35
	v_div_fixup_f32 v26, v26, v36, 1.0
	v_mul_f32_e32 v26, v31, v26
	v_fma_f32 v31, -v38, v40, 1.0
	v_fmac_f32_e32 v40, v31, v40
	v_div_scale_f32 v31, vcc, 1.0, v37, 1.0
	v_mul_f32_e32 v35, v31, v40
	v_fma_f32 v36, -v38, v35, v31
	v_fmac_f32_e32 v35, v36, v40
	v_fma_f32 v31, -v38, v35, v31
	v_div_fmas_f32 v31, v31, v40, v35
	v_div_fixup_f32 v31, v31, v37, 1.0
	v_mul_f32_e32 v27, v27, v31
	v_cvt_pk_bf16_f32 v24, v28, v24
	v_cvt_pk_bf16_f32 v25, v25, v26
	v_cvt_pk_bf16_f32 v26, v34, v29
	v_cvt_pk_bf16_f32 v27, v30, v27
	s_waitcnt vmcnt(12)
; __device__ __forceinline__ float sigmoidf_(float x) { return 1.0f / (1.0f + __expf(-x)); }
; __device__ __forceinline__ u32x4 pack8(const f32x4 v0, const f32x4 v1) { u32x4 w; w.x = pk2(v0[0], v0[1]); w.y = pk2(v0[2], v0[3]); w.z = pk2(v1[0], v1[1]); w.w = pk2(v1[2], v1[3]); return w; }
; __device__ __forceinline__ void unpack8(const u32x4 w, f32x4& v0, f32x4& v1) { v0 = (f32x4){bflo(w.x), bfhi(w.x), bflo(w.y), bfhi(w.y)}; v1 = (f32x4){bflo(w.z), bfhi(w.z), bflo(w.w), bfhi(w.w)}; }
;     __device__ __forceinline__ void operator()(const f32x4 (&acc)[2][2][4][2], const Unit& u, int wr, int wc, int fr, int fq) const {
;     ...
;         for (int ai = 0; ai < 2; ++ai)
; #pragma unroll
;             for (int m = 0; m < 4; ++m) {
;                 bf16_t* rowp = z + (size_t)(row0 + ai * 128 + m * 16) * DIN + col0;
; #pragma unroll
;                 for (int bj = 0; bj < 2; ++bj) {
;                     const u32x4 gw = *(const u32x4*)(rowp + (MODE == 0 ? O_GB : O_GA) + bj * 128);
;                     f32x4 g0, g1; unpack8(gw, g0, g1);
;                     f32x4 v0, v1;
; #pragma unroll
;                     for (int j = 0; j < 4; ++j) { v0[j] = sigmoidf_(g0[j]) * acc[ai][bj][m][0][j]; v1[j] = sigmoidf_(g1[j]) * acc[ai][bj][m][1][j]; }
;                     if (MODE == 1) { const u32x4 mw = *(const u32x4*)(rowp + bj * 128); f32x4 m0, m1; unpack8(mw, m0, m1); v0 += m0; v1 += m1; }
;                     *(u32x4*)(rowp + bj * 128) = pack8(v0, v1); }
	v_mov_b32_e32 v28, v208
	v_mov_b32_e32 v29, v209
	v_mov_b32_e32 v30, v210
	v_mov_b32_e32 v31, v211
	v_lshlrev_b32_e32 v35, 16, v31
	global_store_dwordx4 v[32:33], v[24:27], off sc1
	v_and_b32_e32 v31, 0xffff0000, v31
	s_nop 0
	v_lshlrev_b32_e32 v24, 16, v28
	v_mul_f32_e32 v24, 0xbfb8aa3b, v24
	v_exp_f32_e32 v24, v24
	v_lshlrev_b32_e32 v26, 16, v29
	v_and_b32_e32 v27, 0xffff0000, v29
	v_and_b32_e32 v25, 0xffff0000, v28
	v_add_f32_e32 v24, 1.0, v24
	v_div_scale_f32 v29, s[6:7], v24, v24, 1.0
	v_rcp_f32_e32 v34, v29
	v_lshlrev_b32_e32 v28, 16, v30
	v_mul_f32_e32 v28, 0xbfb8aa3b, v28
	v_exp_f32_e32 v28, v28
	v_fma_f32 v36, -v29, v34, 1.0
	v_fmac_f32_e32 v34, v36, v34
	v_div_scale_f32 v36, vcc, 1.0, v24, 1.0
	v_mul_f32_e32 v37, v36, v34
	v_fma_f32 v38, -v29, v37, v36
	v_fmac_f32_e32 v37, v38, v34
	v_add_f32_e32 v28, 1.0, v28
	v_fma_f32 v29, -v29, v37, v36
	v_div_scale_f32 v36, s[6:7], v28, v28, 1.0
	v_rcp_f32_e32 v38, v36
	v_div_fmas_f32 v29, v29, v34, v37
	v_mul_f32_e32 v25, 0xbfb8aa3b, v25
	v_div_fixup_f32 v24, v29, v24, 1.0
	v_exp_f32_e32 v25, v25
	v_mul_f32_e32 v20, v20, v24
	v_fma_f32 v24, -v36, v38, 1.0
	v_fmac_f32_e32 v38, v24, v38
	v_div_scale_f32 v24, vcc, 1.0, v28, 1.0
	v_mul_f32_e32 v29, v24, v38
	v_fma_f32 v34, -v36, v29, v24
	v_add_f32_e32 v25, 1.0, v25
	v_fmac_f32_e32 v29, v34, v38
	v_div_scale_f32 v34, s[6:7], v25, v25, 1.0
	v_fma_f32 v24, -v36, v29, v24
	v_rcp_f32_e32 v36, v34
	v_and_b32_e32 v30, 0xffff0000, v30
	v_div_fmas_f32 v24, v24, v38, v29
	v_mul_f32_e32 v29, 0xbfb8aa3b, v30
	v_div_fixup_f32 v24, v24, v28, 1.0
	v_exp_f32_e32 v29, v29
	v_mul_f32_e32 v16, v16, v24
	v_fma_f32 v24, -v34, v36, 1.0
	v_fmac_f32_e32 v36, v24, v36
	v_div_scale_f32 v24, vcc, 1.0, v25, 1.0
	v_mul_f32_e32 v28, v24, v36
	v_fma_f32 v30, -v34, v28, v24
	v_add_f32_e32 v29, 1.0, v29
	v_fmac_f32_e32 v28, v30, v36
	v_div_scale_f32 v30, s[6:7], v29, v29, 1.0
	v_fma_f32 v24, -v34, v28, v24
	v_rcp_f32_e32 v34, v30
	v_div_fmas_f32 v24, v24, v36, v28
	v_mul_f32_e32 v26, 0xbfb8aa3b, v26
	v_div_fixup_f32 v24, v24, v25, 1.0
	v_exp_f32_e32 v26, v26
	v_mul_f32_e32 v21, v21, v24
	v_fma_f32 v24, -v30, v34, 1.0
	v_fmac_f32_e32 v34, v24, v34
	v_div_scale_f32 v24, vcc, 1.0, v29, 1.0
	v_mul_f32_e32 v25, v24, v34
	v_fma_f32 v28, -v30, v25, v24
	v_add_f32_e32 v26, 1.0, v26
	v_fmac_f32_e32 v25, v28, v34
	v_div_scale_f32 v28, s[6:7], v26, v26, 1.0
	v_fma_f32 v24, -v30, v25, v24
	v_rcp_f32_e32 v30, v28
	v_div_fmas_f32 v24, v24, v34, v25
	v_div_fixup_f32 v24, v24, v29, 1.0
	v_mul_f32_e32 v17, v17, v24
	v_fma_f32 v24, -v28, v30, 1.0
	v_mul_f32_e32 v29, 0xbfb8aa3b, v35
	v_fmac_f32_e32 v30, v24, v30
	v_div_scale_f32 v24, vcc, 1.0, v26, 1.0
	v_exp_f32_e32 v29, v29
	v_mul_f32_e32 v25, v24, v30
	v_fma_f32 v34, -v28, v25, v24
	v_fmac_f32_e32 v25, v34, v30
	v_fma_f32 v24, -v28, v25, v24
	v_add_f32_e32 v28, 1.0, v29
	v_div_scale_f32 v29, s[6:7], v28, v28, 1.0
	v_rcp_f32_e32 v34, v29
	v_div_fmas_f32 v24, v24, v30, v25
	v_div_fixup_f32 v24, v24, v26, 1.0
	v_mul_f32_e32 v26, 0xbfb8aa3b, v27
	v_exp_f32_e32 v26, v26
	v_mul_f32_e32 v22, v22, v24
	v_fma_f32 v24, -v29, v34, 1.0
	v_fmac_f32_e32 v34, v24, v34
	v_div_scale_f32 v24, vcc, 1.0, v28, 1.0
	v_mul_f32_e32 v25, v24, v34
	v_fma_f32 v27, -v29, v25, v24
	v_add_f32_e32 v26, 1.0, v26
	v_fmac_f32_e32 v25, v27, v34
	v_div_scale_f32 v27, s[6:7], v26, v26, 1.0
	v_fma_f32 v24, -v29, v25, v24
	v_rcp_f32_e32 v29, v27
	v_div_fmas_f32 v24, v24, v34, v25
	v_div_fixup_f32 v24, v24, v28, 1.0
	v_mul_f32_e32 v24, v18, v24
	v_fma_f32 v18, -v27, v29, 1.0
	v_mul_f32_e32 v28, 0xbfb8aa3b, v31
	v_fmac_f32_e32 v29, v18, v29
	v_div_scale_f32 v18, vcc, 1.0, v26, 1.0
	v_exp_f32_e32 v28, v28
	v_mul_f32_e32 v25, v18, v29
	v_fma_f32 v30, -v27, v25, v18
	v_fmac_f32_e32 v25, v30, v29
	v_fma_f32 v18, -v27, v25, v18
	v_add_f32_e32 v27, 1.0, v28
	v_div_scale_f32 v28, s[6:7], v27, v27, 1.0
	v_rcp_f32_e32 v30, v28
	v_div_fmas_f32 v18, v18, v29, v25
	v_div_fixup_f32 v18, v18, v26, 1.0
	v_mul_f32_e32 v23, v23, v18
	v_fma_f32 v18, -v28, v30, 1.0
	v_fmac_f32_e32 v30, v18, v30
	v_div_scale_f32 v18, vcc, 1.0, v27, 1.0
	v_mul_f32_e32 v25, v18, v30
	v_fma_f32 v26, -v28, v25, v18
	v_fmac_f32_e32 v25, v26, v30
	v_fma_f32 v18, -v28, v25, v18
	v_div_fmas_f32 v18, v18, v30, v25
	v_div_fixup_f32 v18, v18, v27, 1.0
	v_mul_f32_e32 v25, v19, v18
	v_cvt_pk_bf16_f32 v18, v20, v21
	v_cvt_pk_bf16_f32 v19, v22, v23
	v_cvt_pk_bf16_f32 v20, v16, v17
	v_add_u32_e32 v16, 0xb0, v160
	v_mad_i64_i32 v[16:17], s[6:7], v16, s57, v[146:147]
	v_lshl_add_u64 v[16:17], v[16:17], 0, v[148:149]
	v_add_co_u32_e32 v26, vcc, s58, v16
	v_cvt_pk_bf16_f32 v21, v24, v25
	global_store_dwordx4 v[32:33], v[18:21], off offset:256 sc1
	s_nop 0
	v_addc_co_u32_e32 v27, vcc, 0, v17, vcc
	s_waitcnt vmcnt(13)
; __device__ __forceinline__ float sigmoidf_(float x) { return 1.0f / (1.0f + __expf(-x)); }
; __device__ __forceinline__ u32x4 pack8(const f32x4 v0, const f32x4 v1) { u32x4 w; w.x = pk2(v0[0], v0[1]); w.y = pk2(v0[2], v0[3]); w.z = pk2(v1[0], v1[1]); w.w = pk2(v1[2], v1[3]); return w; }
; __device__ __forceinline__ void unpack8(const u32x4 w, f32x4& v0, f32x4& v1) { v0 = (f32x4){bflo(w.x), bfhi(w.x), bflo(w.y), bfhi(w.y)}; v1 = (f32x4){bflo(w.z), bfhi(w.z), bflo(w.w), bfhi(w.w)}; }
;     __device__ __forceinline__ void operator()(const f32x4 (&acc)[2][2][4][2], const Unit& u, int wr, int wc, int fr, int fq) const {
;     ...
;         for (int ai = 0; ai < 2; ++ai)
; #pragma unroll
;             for (int m = 0; m < 4; ++m) {
;                 bf16_t* rowp = z + (size_t)(row0 + ai * 128 + m * 16) * DIN + col0;
; #pragma unroll
;                 for (int bj = 0; bj < 2; ++bj) {
;                     const u32x4 gw = *(const u32x4*)(rowp + (MODE == 0 ? O_GB : O_GA) + bj * 128);
;                     f32x4 g0, g1; unpack8(gw, g0, g1);
;                     f32x4 v0, v1;
; #pragma unroll
;                     for (int j = 0; j < 4; ++j) { v0[j] = sigmoidf_(g0[j]) * acc[ai][bj][m][0][j]; v1[j] = sigmoidf_(g1[j]) * acc[ai][bj][m][1][j]; }
;                     if (MODE == 1) { const u32x4 mw = *(const u32x4*)(rowp + bj * 128); f32x4 m0, m1; unpack8(mw, m0, m1); v0 += m0; v1 += m1; }
;                     *(u32x4*)(rowp + bj * 128) = pack8(v0, v1); }
	v_mov_b32_e32 v22, v212
	v_mov_b32_e32 v23, v213
	v_mov_b32_e32 v24, v214
	v_mov_b32_e32 v25, v215
	v_lshlrev_b32_e32 v18, 16, v22
	v_mul_f32_e32 v18, 0xbfb8aa3b, v18
	v_exp_f32_e32 v18, v18
	v_lshlrev_b32_e32 v20, 16, v23
	v_and_b32_e32 v21, 0xffff0000, v23
	v_and_b32_e32 v19, 0xffff0000, v22
	v_add_f32_e32 v18, 1.0, v18
	v_div_scale_f32 v23, s[6:7], v18, v18, 1.0
	v_rcp_f32_e32 v28, v23
	v_lshlrev_b32_e32 v22, 16, v24
	v_mul_f32_e32 v22, 0xbfb8aa3b, v22
	v_exp_f32_e32 v22, v22
	v_fma_f32 v30, -v23, v28, 1.0
	v_fmac_f32_e32 v28, v30, v28
	v_div_scale_f32 v30, vcc, 1.0, v18, 1.0
	v_mul_f32_e32 v31, v30, v28
	v_fma_f32 v32, -v23, v31, v30
	v_fmac_f32_e32 v31, v32, v28
	v_add_f32_e32 v22, 1.0, v22
	v_fma_f32 v23, -v23, v31, v30
	v_div_scale_f32 v30, s[6:7], v22, v22, 1.0
	v_rcp_f32_e32 v32, v30
	v_div_fmas_f32 v23, v23, v28, v31
	v_mul_f32_e32 v19, 0xbfb8aa3b, v19
	v_div_fixup_f32 v18, v23, v18, 1.0
	v_exp_f32_e32 v19, v19
	v_mul_f32_e32 v12, v12, v18
	v_fma_f32 v18, -v30, v32, 1.0
	v_fmac_f32_e32 v32, v18, v32
	v_div_scale_f32 v18, vcc, 1.0, v22, 1.0
	v_mul_f32_e32 v23, v18, v32
	v_fma_f32 v28, -v30, v23, v18
	v_add_f32_e32 v19, 1.0, v19
	v_fmac_f32_e32 v23, v28, v32
	v_div_scale_f32 v28, s[6:7], v19, v19, 1.0
	v_fma_f32 v18, -v30, v23, v18
	v_rcp_f32_e32 v30, v28
	v_and_b32_e32 v24, 0xffff0000, v24
	v_div_fmas_f32 v18, v18, v32, v23
	v_mul_f32_e32 v23, 0xbfb8aa3b, v24
	v_div_fixup_f32 v18, v18, v22, 1.0
	v_exp_f32_e32 v23, v23
	v_mul_f32_e32 v18, v8, v18
	v_fma_f32 v8, -v28, v30, 1.0
	v_fmac_f32_e32 v30, v8, v30
	v_div_scale_f32 v8, vcc, 1.0, v19, 1.0
	v_mul_f32_e32 v22, v8, v30
	v_fma_f32 v24, -v28, v22, v8
	v_add_f32_e32 v23, 1.0, v23
	v_fmac_f32_e32 v22, v24, v30
	v_div_scale_f32 v24, s[6:7], v23, v23, 1.0
	v_fma_f32 v8, -v28, v22, v8
	v_rcp_f32_e32 v28, v24
	v_div_fmas_f32 v8, v8, v30, v22
	v_mul_f32_e32 v20, 0xbfb8aa3b, v20
	v_div_fixup_f32 v8, v8, v19, 1.0
	v_exp_f32_e32 v20, v20
	v_mul_f32_e32 v8, v13, v8
	v_fma_f32 v13, -v24, v28, 1.0
	v_fmac_f32_e32 v28, v13, v28
	v_div_scale_f32 v13, vcc, 1.0, v23, 1.0
	v_mul_f32_e32 v19, v13, v28
	v_fma_f32 v22, -v24, v19, v13
	v_add_f32_e32 v20, 1.0, v20
	v_fmac_f32_e32 v19, v22, v28
	v_div_scale_f32 v22, s[6:7], v20, v20, 1.0
	v_fma_f32 v13, -v24, v19, v13
	v_rcp_f32_e32 v24, v22
	v_div_fmas_f32 v13, v13, v28, v19
	v_lshlrev_b32_e32 v29, 16, v25
	v_div_fixup_f32 v13, v13, v23, 1.0
	v_mul_f32_e32 v13, v9, v13
	v_fma_f32 v9, -v22, v24, 1.0
	v_mul_f32_e32 v23, 0xbfb8aa3b, v29
	v_fmac_f32_e32 v24, v9, v24
	v_div_scale_f32 v9, vcc, 1.0, v20, 1.0
	v_exp_f32_e32 v23, v23
	v_mul_f32_e32 v19, v9, v24
	v_fma_f32 v28, -v22, v19, v9
	v_fmac_f32_e32 v19, v28, v24
	v_fma_f32 v9, -v22, v19, v9
	v_add_f32_e32 v22, 1.0, v23
	v_div_scale_f32 v23, s[6:7], v22, v22, 1.0
	v_rcp_f32_e32 v28, v23
	v_div_fmas_f32 v9, v9, v24, v19
	v_div_fixup_f32 v9, v9, v20, 1.0
	v_mul_f32_e32 v20, 0xbfb8aa3b, v21
	v_exp_f32_e32 v20, v20
	v_mul_f32_e32 v9, v14, v9
	v_fma_f32 v14, -v23, v28, 1.0
	v_fmac_f32_e32 v28, v14, v28
	v_div_scale_f32 v14, vcc, 1.0, v22, 1.0
	v_mul_f32_e32 v19, v14, v28
	v_fma_f32 v21, -v23, v19, v14
	v_add_f32_e32 v20, 1.0, v20
	v_fmac_f32_e32 v19, v21, v28
	v_div_scale_f32 v21, s[6:7], v20, v20, 1.0
	v_fma_f32 v14, -v23, v19, v14
	v_rcp_f32_e32 v23, v21
	v_div_fmas_f32 v14, v14, v28, v19
	v_and_b32_e32 v25, 0xffff0000, v25
	v_div_fixup_f32 v14, v14, v22, 1.0
	v_mul_f32_e32 v14, v10, v14
	v_fma_f32 v10, -v21, v23, 1.0
	v_mul_f32_e32 v22, 0xbfb8aa3b, v25
	v_fmac_f32_e32 v23, v10, v23
	v_div_scale_f32 v10, vcc, 1.0, v20, 1.0
	v_exp_f32_e32 v22, v22
	v_mul_f32_e32 v19, v10, v23
	v_fma_f32 v24, -v21, v19, v10
	v_fmac_f32_e32 v19, v24, v23
	v_fma_f32 v10, -v21, v19, v10
	v_add_f32_e32 v21, 1.0, v22
	v_div_scale_f32 v22, s[6:7], v21, v21, 1.0
	v_rcp_f32_e32 v24, v22
	v_div_fmas_f32 v10, v10, v23, v19
	v_div_fixup_f32 v10, v10, v20, 1.0
	v_mul_f32_e32 v10, v15, v10
	v_fma_f32 v15, -v22, v24, 1.0
	v_fmac_f32_e32 v24, v15, v24
	v_div_scale_f32 v15, vcc, 1.0, v21, 1.0
	v_mul_f32_e32 v19, v15, v24
	v_fma_f32 v20, -v22, v19, v15
	v_fmac_f32_e32 v19, v20, v24
	v_fma_f32 v15, -v22, v19, v15
	v_div_fmas_f32 v15, v15, v24, v19
	v_div_fixup_f32 v15, v15, v21, 1.0
	v_mul_f32_e32 v11, v11, v15
	v_cvt_pk_bf16_f32 v8, v12, v8
	v_cvt_pk_bf16_f32 v9, v9, v10
	v_cvt_pk_bf16_f32 v10, v18, v13
	v_cvt_pk_bf16_f32 v11, v14, v11
	s_waitcnt vmcnt(10)
; __device__ __forceinline__ float sigmoidf_(float x) { return 1.0f / (1.0f + __expf(-x)); }
; #define PG8_WAIT_V(n) asm volatile("s_waitcnt vmcnt(" #n ")" ::: "memory")
; #define PG8_BAR __builtin_amdgcn_s_barrier()
; __device__ __forceinline__ u32x4 pack8(const f32x4 v0, const f32x4 v1) { u32x4 w; w.x = pk2(v0[0], v0[1]); w.y = pk2(v0[2], v0[3]); w.z = pk2(v1[0], v1[1]); w.w = pk2(v1[2], v1[3]); return w; }
; __device__ __forceinline__ void unpack8(const u32x4 w, f32x4& v0, f32x4& v1) { v0 = (f32x4){bflo(w.x), bfhi(w.x), bflo(w.y), bfhi(w.y)}; v1 = (f32x4){bflo(w.z), bfhi(w.z), bflo(w.w), bfhi(w.w)}; }
;     ...
;     }
;     PG8_WAIT_V(0);
;     if (wr == 0) PG8_BAR;
;     PG8_BAR;
;     __device__ __forceinline__ void operator()(const f32x4 (&acc)[2][2][4][2], const Unit& u, int wr, int wc, int fr, int fq) const {
;     ...
;         for (int ai = 0; ai < 2; ++ai)
; #pragma unroll
;             for (int m = 0; m < 4; ++m) {
;                 bf16_t* rowp = z + (size_t)(row0 + ai * 128 + m * 16) * DIN + col0;
; #pragma unroll
;                 for (int bj = 0; bj < 2; ++bj) {
;                     const u32x4 gw = *(const u32x4*)(rowp + (MODE == 0 ? O_GB : O_GA) + bj * 128);
;                     f32x4 g0, g1; unpack8(gw, g0, g1);
;                     f32x4 v0, v1;
; #pragma unroll
;                     for (int j = 0; j < 4; ++j) { v0[j] = sigmoidf_(g0[j]) * acc[ai][bj][m][0][j]; v1[j] = sigmoidf_(g1[j]) * acc[ai][bj][m][1][j]; }
;                     if (MODE == 1) { const u32x4 mw = *(const u32x4*)(rowp + bj * 128); f32x4 m0, m1; unpack8(mw, m0, m1); v0 += m0; v1 += m1; }
;                     *(u32x4*)(rowp + bj * 128) = pack8(v0, v1); }
	v_mov_b32_e32 v12, v216
	v_mov_b32_e32 v13, v217
	v_mov_b32_e32 v14, v218
	v_mov_b32_e32 v15, v219
	v_lshlrev_b32_e32 v19, 16, v15
	global_store_dwordx4 v[16:17], v[8:11], off sc1
	v_and_b32_e32 v15, 0xffff0000, v15
	s_nop 0
	v_lshlrev_b32_e32 v8, 16, v12
	v_mul_f32_e32 v8, 0xbfb8aa3b, v8
	v_exp_f32_e32 v8, v8
	v_lshlrev_b32_e32 v10, 16, v13
	v_and_b32_e32 v11, 0xffff0000, v13
	v_and_b32_e32 v9, 0xffff0000, v12
	v_add_f32_e32 v8, 1.0, v8
	v_div_scale_f32 v13, s[6:7], v8, v8, 1.0
	v_rcp_f32_e32 v18, v13
	v_lshlrev_b32_e32 v12, 16, v14
	v_mul_f32_e32 v12, 0xbfb8aa3b, v12
	v_exp_f32_e32 v12, v12
	v_fma_f32 v20, -v13, v18, 1.0
	v_fmac_f32_e32 v18, v20, v18
	v_div_scale_f32 v20, vcc, 1.0, v8, 1.0
	v_mul_f32_e32 v21, v20, v18
	v_fma_f32 v22, -v13, v21, v20
	v_fmac_f32_e32 v21, v22, v18
	v_add_f32_e32 v12, 1.0, v12
	v_fma_f32 v13, -v13, v21, v20
	v_div_scale_f32 v20, s[6:7], v12, v12, 1.0
	v_rcp_f32_e32 v22, v20
	v_div_fmas_f32 v13, v13, v18, v21
	v_mul_f32_e32 v9, 0xbfb8aa3b, v9
	v_div_fixup_f32 v8, v13, v8, 1.0
	v_exp_f32_e32 v9, v9
	v_mul_f32_e32 v4, v4, v8
	v_fma_f32 v8, -v20, v22, 1.0
	v_fmac_f32_e32 v22, v8, v22
	v_div_scale_f32 v8, vcc, 1.0, v12, 1.0
	v_mul_f32_e32 v13, v8, v22
	v_fma_f32 v18, -v20, v13, v8
	v_add_f32_e32 v9, 1.0, v9
	v_fmac_f32_e32 v13, v18, v22
	v_div_scale_f32 v18, s[6:7], v9, v9, 1.0
	v_fma_f32 v8, -v20, v13, v8
	v_rcp_f32_e32 v20, v18
	v_and_b32_e32 v14, 0xffff0000, v14
	v_div_fmas_f32 v8, v8, v22, v13
	v_mul_f32_e32 v13, 0xbfb8aa3b, v14
	v_div_fixup_f32 v8, v8, v12, 1.0
	v_exp_f32_e32 v13, v13
	v_mul_f32_e32 v8, v0, v8
	v_fma_f32 v0, -v18, v20, 1.0
	v_fmac_f32_e32 v20, v0, v20
	v_div_scale_f32 v0, vcc, 1.0, v9, 1.0
	v_mul_f32_e32 v12, v0, v20
	v_fma_f32 v14, -v18, v12, v0
	v_add_f32_e32 v13, 1.0, v13
	v_fmac_f32_e32 v12, v14, v20
	v_div_scale_f32 v14, s[6:7], v13, v13, 1.0
	v_fma_f32 v0, -v18, v12, v0
	v_rcp_f32_e32 v18, v14
	v_div_fmas_f32 v0, v0, v20, v12
	v_mul_f32_e32 v10, 0xbfb8aa3b, v10
	v_div_fixup_f32 v0, v0, v9, 1.0
	v_exp_f32_e32 v10, v10
	v_mul_f32_e32 v0, v5, v0
	v_fma_f32 v5, -v14, v18, 1.0
	v_fmac_f32_e32 v18, v5, v18
	v_div_scale_f32 v5, vcc, 1.0, v13, 1.0
	v_mul_f32_e32 v9, v5, v18
	v_fma_f32 v12, -v14, v9, v5
	v_add_f32_e32 v10, 1.0, v10
	v_fmac_f32_e32 v9, v12, v18
	v_div_scale_f32 v12, s[6:7], v10, v10, 1.0
	v_fma_f32 v5, -v14, v9, v5
	v_rcp_f32_e32 v14, v12
	v_div_fmas_f32 v5, v5, v18, v9
	v_div_fixup_f32 v5, v5, v13, 1.0
	v_mul_f32_e32 v5, v1, v5
	v_fma_f32 v1, -v12, v14, 1.0
	v_mul_f32_e32 v13, 0xbfb8aa3b, v19
	v_fmac_f32_e32 v14, v1, v14
	v_div_scale_f32 v1, vcc, 1.0, v10, 1.0
	v_exp_f32_e32 v13, v13
	v_mul_f32_e32 v9, v1, v14
	v_fma_f32 v18, -v12, v9, v1
	v_fmac_f32_e32 v9, v18, v14
	v_fma_f32 v1, -v12, v9, v1
	v_add_f32_e32 v12, 1.0, v13
	v_div_scale_f32 v13, s[6:7], v12, v12, 1.0
	v_rcp_f32_e32 v18, v13
	v_div_fmas_f32 v1, v1, v14, v9
	v_div_fixup_f32 v1, v1, v10, 1.0
	v_mul_f32_e32 v10, 0xbfb8aa3b, v11
	v_exp_f32_e32 v10, v10
	v_mul_f32_e32 v1, v6, v1
	v_fma_f32 v6, -v13, v18, 1.0
	v_fmac_f32_e32 v18, v6, v18
	v_div_scale_f32 v6, vcc, 1.0, v12, 1.0
	v_mul_f32_e32 v9, v6, v18
	v_fma_f32 v11, -v13, v9, v6
	v_add_f32_e32 v10, 1.0, v10
	v_fmac_f32_e32 v9, v11, v18
	v_div_scale_f32 v11, s[6:7], v10, v10, 1.0
	v_fma_f32 v6, -v13, v9, v6
	v_rcp_f32_e32 v13, v11
	v_div_fmas_f32 v6, v6, v18, v9
	v_div_fixup_f32 v6, v6, v12, 1.0
	v_mul_f32_e32 v6, v2, v6
	v_fma_f32 v2, -v11, v13, 1.0
	v_mul_f32_e32 v12, 0xbfb8aa3b, v15
	v_fmac_f32_e32 v13, v2, v13
	v_div_scale_f32 v2, vcc, 1.0, v10, 1.0
	v_exp_f32_e32 v12, v12
	v_mul_f32_e32 v9, v2, v13
	v_fma_f32 v14, -v11, v9, v2
	v_fmac_f32_e32 v9, v14, v13
	v_fma_f32 v2, -v11, v9, v2
	v_add_f32_e32 v11, 1.0, v12
	v_div_scale_f32 v12, s[6:7], v11, v11, 1.0
	v_rcp_f32_e32 v14, v12
	v_div_fmas_f32 v2, v2, v13, v9
	v_div_fixup_f32 v2, v2, v10, 1.0
	v_mul_f32_e32 v2, v7, v2
	v_fma_f32 v7, -v12, v14, 1.0
	v_fmac_f32_e32 v14, v7, v14
	v_div_scale_f32 v7, vcc, 1.0, v11, 1.0
	v_mul_f32_e32 v9, v7, v14
	v_fma_f32 v10, -v12, v9, v7
	v_fmac_f32_e32 v9, v10, v14
	v_fma_f32 v7, -v12, v9, v7
	v_div_fmas_f32 v7, v7, v14, v9
	v_div_fixup_f32 v7, v7, v11, 1.0
	v_mul_f32_e32 v3, v3, v7
	s_and_b64 vcc, exec, s[8:9]
	s_mov_b32 s7, s26
	s_mov_b32 s6, s59
	v_cvt_pk_bf16_f32 v0, v4, v0
	v_cvt_pk_bf16_f32 v1, v1, v2
	v_cvt_pk_bf16_f32 v2, v8, v5
	v_cvt_pk_bf16_f32 v3, v6, v3
	global_store_dwordx4 v[16:17], v[0:3], off offset:256 sc1
	s_cbranch_vccz .LBB0_1763
	s_waitcnt vmcnt(0)
	s_cmpk_gt_u32 s34, 0xff
	s_cbranch_scc1 .LBB0_1772
	s_barrier

; __device__ __forceinline__ unsigned pk2(float lo, float hi) { unsigned r; asm volatile("v_cvt_pk_bf16_f32 %0, %1, %2" : "=v"(r) : "v"(lo), "v"(hi)); return r; }
;     __device__ __forceinline__ void operator()(const f32x4 (&acc)[2][2][4][2], const Unit& u, int wr, int wc, int fr, int fq) const {
;         const int row0 = u.pm * 256 + wr * 64 + fr, col0 = u.pn * 256 + wc * 32 + 4 * fq;
;         const float* xo = (u.pm < 64) ? xoldA : (xoldB - (size_t)T_P * DM);
; #pragma unroll
;         for (int ai = 0; ai < 2; ++ai)
; #pragma unroll
;             for (int m = 0; m < 4; ++m) {
;                 const int row = row0 + ai * 128 + m * 16; const size_t ro = (size_t)row * DM + col0;
;                 float s = 0.f;
; #pragma unroll
;                 for (int bj = 0; bj < 2; ++bj)
; #pragma unroll
;                     for (int n = 0; n < 2; ++n) {
;                         const size_t o = ro + bj * 128 + n * 16;
;                         const f32x4 xn = *(const f32x4*)(xo + o) + acc[ai][bj][m][n];
;                         *(f32x4*)(xf + o) = xn;
;                         u32x2 w; w.x = pk2(xn[0], xn[1]); w.y = pk2(xn[2], xn[3]); *(u32x2*)(xb + o) = w;
;                         s += (xn[0] * xn[0] + xn[1] * xn[1]) + (xn[2] * xn[2] + xn[3] * xn[3]);
;                     }
;                 s += __shfl_xor(s, 16); s += __shfl_xor(s, 32);
;                 if (fq == 0) ssq[(size_t)row * 16 + u.pn * 4 + wc] = s;
.LBB0_1922:
	v_lshl_add_u32 v146, s77, 8, v148
	v_lshl_or_b32 v142, s40, 8, v150
	v_ashrrev_i32_e32 v147, 31, v146
	v_ashrrev_i32_e32 v143, 31, v142
	v_lshlrev_b64 v[154:155], 10, v[146:147]
	s_cmp_lt_i32 s77, 64
	v_lshl_add_u64 v[158:159], v[154:155], 0, v[142:143]
	s_cselect_b32 s15, s25, -1
	s_cselect_b32 s14, s24, 0xfc000000
	v_lshlrev_b64 v[160:161], 2, v[158:159]
	v_lshl_add_u64 v[162:163], s[14:15], 0, v[160:161]
	v_subrev_u32_e32 v172, s14, v162
	v_add_u32_e32 v173, 0x0, v172
	global_load_dwordx4 v[174:177], v173, s[14:15]
	v_add_u32_e32 v173, 0x40, v172
	global_load_dwordx4 v[178:181], v173, s[14:15]
	v_add_u32_e32 v173, 0x200, v172
	global_load_dwordx4 v[182:185], v173, s[14:15]
	v_add_u32_e32 v173, 0x240, v172
	global_load_dwordx4 v[186:189], v173, s[14:15]
	v_add_u32_e32 v173, 0x10000, v172
	global_load_dwordx4 v[190:193], v173, s[14:15]
	v_add_u32_e32 v173, 0x10040, v172
	global_load_dwordx4 v[194:197], v173, s[14:15]
	v_add_u32_e32 v173, 0x10200, v172
	global_load_dwordx4 v[198:201], v173, s[14:15]
	v_add_u32_e32 v173, 0x10240, v172
	global_load_dwordx4 v[202:205], v173, s[14:15]
	v_add_u32_e32 v173, 0x20000, v172
	global_load_dwordx4 v[206:209], v173, s[14:15]
	v_add_u32_e32 v173, 0x20040, v172
	global_load_dwordx4 v[210:213], v173, s[14:15]
	v_add_u32_e32 v173, 0x20200, v172
	global_load_dwordx4 v[214:217], v173, s[14:15]
	v_add_u32_e32 v173, 0x20240, v172
	global_load_dwordx4 v[218:221], v173, s[14:15]
	v_add_u32_e32 v173, 0x30000, v172
	global_load_dwordx4 v[232:235], v173, s[14:15]
	v_add_u32_e32 v173, 0x30040, v172
	global_load_dwordx4 v[236:239], v173, s[14:15]
	v_add_u32_e32 v173, 0x30200, v172
	global_load_dwordx4 v[240:243], v173, s[14:15]
	v_add_u32_e32 v173, 0x30240, v172
	global_load_dwordx4 v[244:247], v173, s[14:15]
	v_add_u32_e32 v173, 0x80000, v172
	global_load_dwordx4 v[248:251], v173, s[14:15]
	v_add_u32_e32 v173, 0x80040, v172
	global_load_dwordx4 v[252:255], v173, s[14:15]
	v_lshl_add_u64 v[164:165], v[158:159], 1, s[20:21]
	v_lshl_add_u64 v[170:171], s[24:25], 0, v[160:161]
	v_xor_b32_e32 v153, 32, v152
	s_lshl_b32 s40, s40, 2
	s_ashr_i32 s41, s40, 31
	s_waitcnt vmcnt(17)
	v_mov_b32_e32 v154, v174
	v_mov_b32_e32 v155, v175
	v_mov_b32_e32 v156, v176
	v_mov_b32_e32 v157, v177
	v_add_u32_e32 v173, 0x80200, v172
	global_load_dwordx4 v[174:177], v173, s[14:15]
	v_pk_add_f32 v[126:127], v[126:127], v[156:157]
	v_pk_add_f32 v[124:125], v[124:125], v[154:155]
	global_store_dwordx4 v[170:171], v[124:127], off sc1
	v_cvt_pk_bf16_f32 v154, v124, v125
	v_cvt_pk_bf16_f32 v155, v126, v127
	global_store_dwordx2 v[164:165], v[154:155], off
	s_waitcnt vmcnt(19)
	v_mov_b32_e32 v154, v178
	v_mov_b32_e32 v155, v179
	v_mov_b32_e32 v156, v180
	v_mov_b32_e32 v157, v181
	v_add_u32_e32 v173, 0x80240, v172
	global_load_dwordx4 v[178:181], v173, s[14:15]
	v_pk_add_f32 v[122:123], v[122:123], v[156:157]
	v_pk_add_f32 v[120:121], v[120:121], v[154:155]
	global_store_dwordx4 v[170:171], v[120:123], off offset:64 sc1
	v_cvt_pk_bf16_f32 v154, v120, v121
	v_cvt_pk_bf16_f32 v155, v122, v123
	global_store_dwordx2 v[164:165], v[154:155], off offset:32
	s_waitcnt vmcnt(21)
	v_mov_b32_e32 v154, v182
	v_mov_b32_e32 v155, v183
	v_mov_b32_e32 v156, v184
	v_mov_b32_e32 v157, v185
	v_add_u32_e32 v173, 0x90000, v172
	global_load_dwordx4 v[182:185], v173, s[14:15]
	v_pk_add_f32 v[156:157], v[118:119], v[156:157]
	v_pk_add_f32 v[154:155], v[116:117], v[154:155]
	global_store_dwordx4 v[170:171], v[154:157], off offset:512 sc1
	v_cvt_pk_bf16_f32 v116, v154, v155
	v_cvt_pk_bf16_f32 v117, v156, v157
	global_store_dwordx2 v[164:165], v[116:117], off offset:256
	v_mul_f32_e32 v118, v125, v125
	v_mul_f32_e32 v119, v127, v127
	v_fmac_f32_e32 v118, v124, v124
	v_fmac_f32_e32 v119, v126, v126
	v_add_f32_e32 v118, v118, v119
	v_mul_f32_e32 v119, v121, v121
	v_mul_f32_e32 v121, v123, v123
	v_fmac_f32_e32 v119, v120, v120
	v_fmac_f32_e32 v121, v122, v122
	v_add_f32_e32 v119, v119, v121
	v_add_f32_e32 v118, v118, v119
	v_mul_f32_e32 v119, v155, v155
	v_mul_f32_e32 v120, v157, v157
	v_fmac_f32_e32 v119, v154, v154
	v_fmac_f32_e32 v120, v156, v156
	v_add_f32_e32 v119, v119, v120
	v_and_b32_e32 v117, 64, v152
	v_add_f32_e32 v122, v118, v119
	v_xor_b32_e32 v116, 16, v152
	v_add_u32_e32 v117, 64, v117
	v_cmp_lt_i32_e32 vcc, v116, v117
	s_waitcnt vmcnt(23)
	v_mov_b32_e32 v158, v186
	v_mov_b32_e32 v159, v187
	v_mov_b32_e32 v160, v188
	v_mov_b32_e32 v161, v189
	v_add_u32_e32 v173, 0x90040, v172
	global_load_dwordx4 v[186:189], v173, s[14:15]
	v_pk_add_f32 v[120:121], v[114:115], v[160:161]
	v_pk_add_f32 v[118:119], v[112:113], v[158:159]
	v_mul_f32_e32 v113, v121, v121
	v_mul_f32_e32 v112, v119, v119
	v_fmac_f32_e32 v112, v118, v118
	v_fmac_f32_e32 v113, v120, v120
	v_cndmask_b32_e32 v116, v152, v116, vcc
	v_add_f32_e32 v112, v112, v113
	v_lshlrev_b32_e32 v116, 2, v116
	v_add_f32_e32 v112, v122, v112
	ds_bpermute_b32 v113, v116, v112
	v_cmp_lt_i32_e32 vcc, v153, v117
	global_store_dwordx4 v[170:171], v[118:121], off offset:576 sc1
	s_waitcnt lgkmcnt(0)
	v_add_f32_e32 v112, v112, v113
	v_cndmask_b32_e32 v114, v152, v153, vcc
	v_lshlrev_b32_e32 v114, 2, v114
	ds_bpermute_b32 v113, v114, v112
	v_cvt_pk_bf16_f32 v118, v118, v119
	v_cvt_pk_bf16_f32 v119, v120, v121
	global_store_dwordx2 v[164:165], v[118:119], off offset:288
	s_and_saveexec_b64 s[42:43], s[10:11]
	s_cbranch_execz .LBB0_1924
	s_waitcnt lgkmcnt(0)
	v_add_f32_e32 v115, v112, v113
	v_lshlrev_b64 v[112:113], 6, v[146:147]
	v_lshl_add_u64 v[112:113], s[22:23], 0, v[112:113]
	v_lshl_add_u64 v[112:113], s[40:41], 2, v[112:113]
	s_lshl_b32 s30, s67, 2
	v_lshl_add_u64 v[112:113], v[112:113], 0, s[30:31]
	global_store_dword v[112:113], v115, off
; __device__ __forceinline__ unsigned pk2(float lo, float hi) { unsigned r; asm volatile("v_cvt_pk_bf16_f32 %0, %1, %2" : "=v"(r) : "v"(lo), "v"(hi)); return r; }
;     __device__ __forceinline__ void operator()(const f32x4 (&acc)[2][2][4][2], const Unit& u, int wr, int wc, int fr, int fq) const {
;     ...
;         for (int ai = 0; ai < 2; ++ai)
; #pragma unroll
;             for (int m = 0; m < 4; ++m) {
;                 const int row = row0 + ai * 128 + m * 16; const size_t ro = (size_t)row * DM + col0;
;                 float s = 0.f;
; #pragma unroll
;                 for (int bj = 0; bj < 2; ++bj)
; #pragma unroll
;                     for (int n = 0; n < 2; ++n) {
;                         const size_t o = ro + bj * 128 + n * 16;
;                         const f32x4 xn = *(const f32x4*)(xo + o) + acc[ai][bj][m][n];
;                         *(f32x4*)(xf + o) = xn;
;                         u32x2 w; w.x = pk2(xn[0], xn[1]); w.y = pk2(xn[2], xn[3]); *(u32x2*)(xb + o) = w;
;                         s += (xn[0] * xn[0] + xn[1] * xn[1]) + (xn[2] * xn[2] + xn[3] * xn[3]);
;                     }
;                 s += __shfl_xor(s, 16); s += __shfl_xor(s, 32);
;                 if (fq == 0) ssq[(size_t)row * 16 + u.pn * 4 + wc] = s;
.LBB0_1924:
	s_or_b64 exec, exec, s[42:43]
	v_or_b32_e32 v112, 16, v146
	s_waitcnt lgkmcnt(0)
	v_ashrrev_i32_e32 v113, 31, v112
	v_lshlrev_b64 v[118:119], 10, v[112:113]
	v_lshl_add_u64 v[122:123], v[118:119], 0, v[142:143]
	v_lshlrev_b64 v[124:125], 2, v[122:123]
	v_lshl_add_u64 v[126:127], s[14:15], 0, v[124:125]
	v_lshl_add_u64 v[122:123], v[122:123], 1, s[20:21]
	v_lshl_add_u64 v[124:125], s[24:25], 0, v[124:125]
	s_waitcnt vmcnt(25)
	v_mov_b32_e32 v118, v190
	v_mov_b32_e32 v119, v191
	v_mov_b32_e32 v120, v192
	v_mov_b32_e32 v121, v193
	v_add_u32_e32 v173, 0x90200, v172
	global_load_dwordx4 v[190:193], v173, s[14:15]
	v_pk_add_f32 v[110:111], v[110:111], v[120:121]
	v_pk_add_f32 v[108:109], v[108:109], v[118:119]
	global_store_dwordx4 v[124:125], v[108:111], off sc1
	v_cvt_pk_bf16_f32 v118, v108, v109
	v_cvt_pk_bf16_f32 v119, v110, v111
	global_store_dwordx2 v[122:123], v[118:119], off
	v_mul_f32_e32 v109, v109, v109
	v_mul_f32_e32 v111, v111, v111
	v_fmac_f32_e32 v109, v108, v108
	v_fmac_f32_e32 v111, v110, v110
	v_add_f32_e32 v108, v109, v111
	s_waitcnt vmcnt(27)
	v_mov_b32_e32 v118, v194
	v_mov_b32_e32 v119, v195
	v_mov_b32_e32 v120, v196
	v_mov_b32_e32 v121, v197
	v_add_u32_e32 v173, 0x90240, v172
	global_load_dwordx4 v[194:197], v173, s[14:15]
	v_pk_add_f32 v[106:107], v[106:107], v[120:121]
	v_pk_add_f32 v[104:105], v[104:105], v[118:119]
	global_store_dwordx4 v[124:125], v[104:107], off offset:64 sc1
	v_cvt_pk_bf16_f32 v118, v104, v105
	v_cvt_pk_bf16_f32 v119, v106, v107
	global_store_dwordx2 v[122:123], v[118:119], off offset:32
	v_mul_f32_e32 v105, v105, v105
	v_mul_f32_e32 v107, v107, v107
	v_fmac_f32_e32 v105, v104, v104
	v_fmac_f32_e32 v107, v106, v106
	v_add_f32_e32 v104, v105, v107
	v_add_f32_e32 v104, v108, v104
	s_waitcnt vmcnt(29)
	v_mov_b32_e32 v118, v198
	v_mov_b32_e32 v119, v199
	v_mov_b32_e32 v120, v200
	v_mov_b32_e32 v121, v201
	v_add_u32_e32 v173, 0xa0000, v172
	global_load_dwordx4 v[198:201], v173, s[14:15]
	v_pk_add_f32 v[102:103], v[102:103], v[120:121]
	v_pk_add_f32 v[100:101], v[100:101], v[118:119]
	global_store_dwordx4 v[124:125], v[100:103], off offset:512 sc1
	v_cvt_pk_bf16_f32 v118, v100, v101
	v_cvt_pk_bf16_f32 v119, v102, v103
	global_store_dwordx2 v[122:123], v[118:119], off offset:256
	v_mul_f32_e32 v101, v101, v101
	v_mul_f32_e32 v103, v103, v103
	v_fmac_f32_e32 v101, v100, v100
	v_fmac_f32_e32 v103, v102, v102
	v_add_f32_e32 v100, v101, v103
	v_add_f32_e32 v102, v104, v100
	s_waitcnt vmcnt(31)
	v_mov_b32_e32 v118, v202
	v_mov_b32_e32 v119, v203
	v_mov_b32_e32 v120, v204
	v_mov_b32_e32 v121, v205
	v_add_u32_e32 v173, 0xa0040, v172
	global_load_dwordx4 v[202:205], v173, s[14:15]
	v_pk_add_f32 v[100:101], v[98:99], v[120:121]
	v_pk_add_f32 v[98:99], v[96:97], v[118:119]
	v_mul_f32_e32 v97, v101, v101
	v_mul_f32_e32 v96, v99, v99
	v_fmac_f32_e32 v96, v98, v98
	v_fmac_f32_e32 v97, v100, v100
	v_add_f32_e32 v96, v96, v97
	v_add_f32_e32 v96, v102, v96
	ds_bpermute_b32 v97, v116, v96
	global_store_dwordx4 v[124:125], v[98:101], off offset:576 sc1
	s_waitcnt lgkmcnt(0)
	v_add_f32_e32 v96, v96, v97
	ds_bpermute_b32 v97, v114, v96
	v_cvt_pk_bf16_f32 v98, v98, v99
	v_cvt_pk_bf16_f32 v99, v100, v101
	global_store_dwordx2 v[122:123], v[98:99], off offset:288
	s_and_saveexec_b64 s[42:43], s[10:11]
	s_cbranch_execz .LBB0_1926
	s_waitcnt lgkmcnt(0)
	v_add_f32_e32 v98, v96, v97
	v_lshlrev_b64 v[96:97], 6, v[112:113]
	v_lshl_add_u64 v[96:97], s[22:23], 0, v[96:97]
	v_lshl_add_u64 v[96:97], s[40:41], 2, v[96:97]
	s_lshl_b32 s30, s67, 2
	v_lshl_add_u64 v[96:97], v[96:97], 0, s[30:31]
	global_store_dword v[96:97], v98, off
.LBB0_1926:
	s_or_b64 exec, exec, s[42:43]
	v_or_b32_e32 v96, 32, v146
	s_waitcnt lgkmcnt(0)
	v_ashrrev_i32_e32 v97, 31, v96
	v_lshlrev_b64 v[98:99], 10, v[96:97]
	v_lshl_add_u64 v[102:103], v[98:99], 0, v[142:143]
	v_lshlrev_b64 v[104:105], 2, v[102:103]
	v_lshl_add_u64 v[106:107], s[14:15], 0, v[104:105]
	v_lshl_add_u64 v[102:103], v[102:103], 1, s[20:21]
	v_lshl_add_u64 v[104:105], s[24:25], 0, v[104:105]
	s_waitcnt vmcnt(33)
	v_mov_b32_e32 v98, v206
	v_mov_b32_e32 v99, v207
	v_mov_b32_e32 v100, v208
	v_mov_b32_e32 v101, v209
	v_add_u32_e32 v173, 0xa0200, v172
	global_load_dwordx4 v[206:209], v173, s[14:15]
	v_pk_add_f32 v[94:95], v[94:95], v[100:101]
	v_pk_add_f32 v[92:93], v[92:93], v[98:99]
	global_store_dwordx4 v[104:105], v[92:95], off sc1
	v_cvt_pk_bf16_f32 v98, v92, v93
	v_cvt_pk_bf16_f32 v99, v94, v95
	global_store_dwordx2 v[102:103], v[98:99], off
	v_mul_f32_e32 v93, v93, v93
	v_mul_f32_e32 v95, v95, v95
	v_fmac_f32_e32 v93, v92, v92
	v_fmac_f32_e32 v95, v94, v94
	v_add_f32_e32 v92, v93, v95
	s_waitcnt vmcnt(35)
	v_mov_b32_e32 v98, v210
	v_mov_b32_e32 v99, v211
	v_mov_b32_e32 v100, v212
	v_mov_b32_e32 v101, v213
	v_add_u32_e32 v173, 0xa0240, v172
	global_load_dwordx4 v[210:213], v173, s[14:15]
	v_pk_add_f32 v[90:91], v[90:91], v[100:101]
	v_pk_add_f32 v[88:89], v[88:89], v[98:99]
	global_store_dwordx4 v[104:105], v[88:91], off offset:64 sc1
	v_cvt_pk_bf16_f32 v98, v88, v89
	v_cvt_pk_bf16_f32 v99, v90, v91
	global_store_dwordx2 v[102:103], v[98:99], off offset:32
	v_mul_f32_e32 v89, v89, v89
	v_mul_f32_e32 v91, v91, v91
	v_fmac_f32_e32 v89, v88, v88
	v_fmac_f32_e32 v91, v90, v90
	v_add_f32_e32 v88, v89, v91
	v_add_f32_e32 v88, v92, v88
	s_waitcnt vmcnt(37)
	v_mov_b32_e32 v98, v214
	v_mov_b32_e32 v99, v215
	v_mov_b32_e32 v100, v216
	v_mov_b32_e32 v101, v217
	v_add_u32_e32 v173, 0xb0000, v172
	global_load_dwordx4 v[214:217], v173, s[14:15]
	v_pk_add_f32 v[86:87], v[86:87], v[100:101]
	v_pk_add_f32 v[84:85], v[84:85], v[98:99]
	global_store_dwordx4 v[104:105], v[84:87], off offset:512 sc1
	v_cvt_pk_bf16_f32 v98, v84, v85
	v_cvt_pk_bf16_f32 v99, v86, v87
	global_store_dwordx2 v[102:103], v[98:99], off offset:256
	v_mul_f32_e32 v85, v85, v85
	v_mul_f32_e32 v87, v87, v87
	v_fmac_f32_e32 v85, v84, v84
	v_fmac_f32_e32 v87, v86, v86
	v_add_f32_e32 v84, v85, v87
	v_add_f32_e32 v86, v88, v84
	s_waitcnt vmcnt(39)
	v_mov_b32_e32 v98, v218
	v_mov_b32_e32 v99, v219
	v_mov_b32_e32 v100, v220
	v_mov_b32_e32 v101, v221
	v_add_u32_e32 v173, 0xb0040, v172
	global_load_dwordx4 v[218:221], v173, s[14:15]
	v_pk_add_f32 v[84:85], v[82:83], v[100:101]
	v_pk_add_f32 v[82:83], v[80:81], v[98:99]
	v_mul_f32_e32 v81, v85, v85
	v_mul_f32_e32 v80, v83, v83
	v_fmac_f32_e32 v80, v82, v82
	v_fmac_f32_e32 v81, v84, v84
	v_add_f32_e32 v80, v80, v81
	v_add_f32_e32 v80, v86, v80
	ds_bpermute_b32 v81, v116, v80
	global_store_dwordx4 v[104:105], v[82:85], off offset:576 sc1
	s_waitcnt lgkmcnt(0)
	v_add_f32_e32 v80, v80, v81
	ds_bpermute_b32 v81, v114, v80
	v_cvt_pk_bf16_f32 v82, v82, v83
	v_cvt_pk_bf16_f32 v83, v84, v85
	global_store_dwordx2 v[102:103], v[82:83], off offset:288
	s_and_saveexec_b64 s[42:43], s[10:11]
	s_cbranch_execz .LBB0_1928
; __device__ __forceinline__ unsigned pk2(float lo, float hi) { unsigned r; asm volatile("v_cvt_pk_bf16_f32 %0, %1, %2" : "=v"(r) : "v"(lo), "v"(hi)); return r; }
;     __device__ __forceinline__ void operator()(const f32x4 (&acc)[2][2][4][2], const Unit& u, int wr, int wc, int fr, int fq) const {
;     ...
;         for (int ai = 0; ai < 2; ++ai)
; #pragma unroll
;             for (int m = 0; m < 4; ++m) {
;                 const int row = row0 + ai * 128 + m * 16; const size_t ro = (size_t)row * DM + col0;
;                 float s = 0.f;
; #pragma unroll
;                 for (int bj = 0; bj < 2; ++bj)
; #pragma unroll
;                     for (int n = 0; n < 2; ++n) {
;                         const size_t o = ro + bj * 128 + n * 16;
;                         const f32x4 xn = *(const f32x4*)(xo + o) + acc[ai][bj][m][n];
;                         *(f32x4*)(xf + o) = xn;
;                         u32x2 w; w.x = pk2(xn[0], xn[1]); w.y = pk2(xn[2], xn[3]); *(u32x2*)(xb + o) = w;
;                         s += (xn[0] * xn[0] + xn[1] * xn[1]) + (xn[2] * xn[2] + xn[3] * xn[3]);
;                     }
;                 s += __shfl_xor(s, 16); s += __shfl_xor(s, 32);
;                 if (fq == 0) ssq[(size_t)row * 16 + u.pn * 4 + wc] = s;
;             }
	s_waitcnt lgkmcnt(0)
	v_add_f32_e32 v82, v80, v81
	v_lshlrev_b64 v[80:81], 6, v[96:97]
	v_lshl_add_u64 v[80:81], s[22:23], 0, v[80:81]
	v_lshl_add_u64 v[80:81], s[40:41], 2, v[80:81]
	s_lshl_b32 s30, s67, 2
	v_lshl_add_u64 v[80:81], v[80:81], 0, s[30:31]
	global_store_dword v[80:81], v82, off
.LBB0_1928:
	s_or_b64 exec, exec, s[42:43]
	v_or_b32_e32 v80, 48, v146
	s_waitcnt lgkmcnt(0)
	v_ashrrev_i32_e32 v81, 31, v80
	v_lshlrev_b64 v[82:83], 10, v[80:81]
	v_lshl_add_u64 v[86:87], v[82:83], 0, v[142:143]
	v_lshlrev_b64 v[88:89], 2, v[86:87]
	v_lshl_add_u64 v[90:91], s[14:15], 0, v[88:89]
	v_lshl_add_u64 v[86:87], v[86:87], 1, s[20:21]
	v_lshl_add_u64 v[88:89], s[24:25], 0, v[88:89]
	s_waitcnt vmcnt(41)
	v_mov_b32_e32 v82, v232
	v_mov_b32_e32 v83, v233
	v_mov_b32_e32 v84, v234
	v_mov_b32_e32 v85, v235
	v_add_u32_e32 v173, 0xb0200, v172
	global_load_dwordx4 v[232:235], v173, s[14:15]
	v_pk_add_f32 v[78:79], v[78:79], v[84:85]
	v_pk_add_f32 v[76:77], v[76:77], v[82:83]
	global_store_dwordx4 v[88:89], v[76:79], off sc1
	v_cvt_pk_bf16_f32 v82, v76, v77
	v_cvt_pk_bf16_f32 v83, v78, v79
	global_store_dwordx2 v[86:87], v[82:83], off
	v_mul_f32_e32 v77, v77, v77
	v_mul_f32_e32 v79, v79, v79
	v_fmac_f32_e32 v77, v76, v76
	v_fmac_f32_e32 v79, v78, v78
	v_add_f32_e32 v76, v77, v79
	s_waitcnt vmcnt(43)
	v_mov_b32_e32 v82, v236
	v_mov_b32_e32 v83, v237
	v_mov_b32_e32 v84, v238
	v_mov_b32_e32 v85, v239
	v_add_u32_e32 v173, 0xb0240, v172
	global_load_dwordx4 v[236:239], v173, s[14:15]
	v_pk_add_f32 v[74:75], v[74:75], v[84:85]
	v_pk_add_f32 v[72:73], v[72:73], v[82:83]
	global_store_dwordx4 v[88:89], v[72:75], off offset:64 sc1
	v_cvt_pk_bf16_f32 v82, v72, v73
	v_cvt_pk_bf16_f32 v83, v74, v75
	global_store_dwordx2 v[86:87], v[82:83], off offset:32
	v_mul_f32_e32 v73, v73, v73
	v_mul_f32_e32 v75, v75, v75
	v_fmac_f32_e32 v73, v72, v72
	v_fmac_f32_e32 v75, v74, v74
	v_add_f32_e32 v72, v73, v75
	v_add_f32_e32 v72, v76, v72
	s_waitcnt vmcnt(45)
	v_mov_b32_e32 v82, v240
	v_mov_b32_e32 v83, v241
	v_mov_b32_e32 v84, v242
	v_mov_b32_e32 v85, v243
	v_pk_add_f32 v[70:71], v[70:71], v[84:85]
	v_pk_add_f32 v[68:69], v[68:69], v[82:83]
	global_store_dwordx4 v[88:89], v[68:71], off offset:512 sc1
	v_cvt_pk_bf16_f32 v82, v68, v69
	v_cvt_pk_bf16_f32 v83, v70, v71
	global_store_dwordx2 v[86:87], v[82:83], off offset:256
	v_mul_f32_e32 v69, v69, v69
	v_mul_f32_e32 v71, v71, v71
	v_fmac_f32_e32 v69, v68, v68
	v_fmac_f32_e32 v71, v70, v70
	v_add_f32_e32 v68, v69, v71
	v_add_f32_e32 v70, v72, v68
	s_waitcnt vmcnt(46)
	v_mov_b32_e32 v82, v244
	v_mov_b32_e32 v83, v245
	v_mov_b32_e32 v84, v246
	v_mov_b32_e32 v85, v247
	v_pk_add_f32 v[68:69], v[66:67], v[84:85]
	v_pk_add_f32 v[66:67], v[64:65], v[82:83]
	v_mul_f32_e32 v65, v69, v69
	v_mul_f32_e32 v64, v67, v67
	v_fmac_f32_e32 v64, v66, v66
	v_fmac_f32_e32 v65, v68, v68
	v_add_f32_e32 v64, v64, v65
	v_add_f32_e32 v64, v70, v64
	ds_bpermute_b32 v65, v116, v64
	global_store_dwordx4 v[88:89], v[66:69], off offset:576 sc1
	s_waitcnt lgkmcnt(0)
	v_add_f32_e32 v64, v64, v65
	ds_bpermute_b32 v65, v114, v64
	v_cvt_pk_bf16_f32 v66, v66, v67
	v_cvt_pk_bf16_f32 v67, v68, v69
	global_store_dwordx2 v[86:87], v[66:67], off offset:288
	s_and_saveexec_b64 s[42:43], s[10:11]
	s_cbranch_execz .LBB0_1930
	s_waitcnt lgkmcnt(0)
	v_add_f32_e32 v66, v64, v65
	v_lshlrev_b64 v[64:65], 6, v[80:81]
	v_lshl_add_u64 v[64:65], s[22:23], 0, v[64:65]
	v_lshl_add_u64 v[64:65], s[40:41], 2, v[64:65]
	s_lshl_b32 s30, s67, 2
	v_lshl_add_u64 v[64:65], v[64:65], 0, s[30:31]
	global_store_dword v[64:65], v66, off
.LBB0_1930:
	s_or_b64 exec, exec, s[42:43]
	v_add_u32_e32 v64, 0x80, v146
	s_waitcnt lgkmcnt(0)
	v_ashrrev_i32_e32 v65, 31, v64
	v_lshlrev_b64 v[66:67], 10, v[64:65]
	v_lshl_add_u64 v[70:71], v[66:67], 0, v[142:143]
	v_lshlrev_b64 v[72:73], 2, v[70:71]
	v_lshl_add_u64 v[74:75], s[14:15], 0, v[72:73]
	v_lshl_add_u64 v[70:71], v[70:71], 1, s[20:21]
	v_lshl_add_u64 v[72:73], s[24:25], 0, v[72:73]
	s_waitcnt vmcnt(47)
	v_mov_b32_e32 v66, v248
	v_mov_b32_e32 v67, v249
	v_mov_b32_e32 v68, v250
	v_mov_b32_e32 v69, v251
	v_pk_add_f32 v[62:63], v[62:63], v[68:69]
	v_pk_add_f32 v[60:61], v[60:61], v[66:67]
	global_store_dwordx4 v[72:73], v[60:63], off sc1
	v_cvt_pk_bf16_f32 v66, v60, v61
	v_cvt_pk_bf16_f32 v67, v62, v63
	global_store_dwordx2 v[70:71], v[66:67], off
	v_mul_f32_e32 v61, v61, v61
	v_mul_f32_e32 v63, v63, v63
	v_fmac_f32_e32 v61, v60, v60
	v_fmac_f32_e32 v63, v62, v62
	v_add_f32_e32 v60, v61, v63
	s_waitcnt vmcnt(48)
	v_mov_b32_e32 v66, v252
	v_mov_b32_e32 v67, v253
	v_mov_b32_e32 v68, v254
	v_mov_b32_e32 v69, v255
	v_pk_add_f32 v[58:59], v[58:59], v[68:69]
	v_pk_add_f32 v[56:57], v[56:57], v[66:67]
	global_store_dwordx4 v[72:73], v[56:59], off offset:64 sc1
	v_cvt_pk_bf16_f32 v66, v56, v57
	v_cvt_pk_bf16_f32 v67, v58, v59
	global_store_dwordx2 v[70:71], v[66:67], off offset:32
	v_mul_f32_e32 v57, v57, v57
	v_mul_f32_e32 v59, v59, v59
	v_fmac_f32_e32 v57, v56, v56
	v_fmac_f32_e32 v59, v58, v58
	v_add_f32_e32 v56, v57, v59
	v_add_f32_e32 v56, v60, v56
	s_waitcnt vmcnt(49)
	v_mov_b32_e32 v66, v174
	v_mov_b32_e32 v67, v175
	v_mov_b32_e32 v68, v176
	v_mov_b32_e32 v69, v177
	v_pk_add_f32 v[54:55], v[54:55], v[68:69]
	v_pk_add_f32 v[52:53], v[52:53], v[66:67]
	global_store_dwordx4 v[72:73], v[52:55], off offset:512 sc1
	v_cvt_pk_bf16_f32 v66, v52, v53
	v_cvt_pk_bf16_f32 v67, v54, v55
	global_store_dwordx2 v[70:71], v[66:67], off offset:256
	v_mul_f32_e32 v53, v53, v53
	v_mul_f32_e32 v55, v55, v55
	v_fmac_f32_e32 v53, v52, v52
	v_fmac_f32_e32 v55, v54, v54
	v_add_f32_e32 v52, v53, v55
	v_add_f32_e32 v54, v56, v52
	s_waitcnt vmcnt(48)
	v_mov_b32_e32 v66, v178
	v_mov_b32_e32 v67, v179
	v_mov_b32_e32 v68, v180
	v_mov_b32_e32 v69, v181
	v_pk_add_f32 v[52:53], v[50:51], v[68:69]
	v_pk_add_f32 v[50:51], v[48:49], v[66:67]
	v_mul_f32_e32 v49, v53, v53
	v_mul_f32_e32 v48, v51, v51
	v_fmac_f32_e32 v48, v50, v50
	v_fmac_f32_e32 v49, v52, v52
	v_add_f32_e32 v48, v48, v49
	v_add_f32_e32 v48, v54, v48
	ds_bpermute_b32 v49, v116, v48
	global_store_dwordx4 v[72:73], v[50:53], off offset:576 sc1
	s_waitcnt lgkmcnt(0)
	v_add_f32_e32 v48, v48, v49
	ds_bpermute_b32 v49, v114, v48
	v_cvt_pk_bf16_f32 v50, v50, v51
	v_cvt_pk_bf16_f32 v51, v52, v53
	global_store_dwordx2 v[70:71], v[50:51], off offset:288
	s_and_saveexec_b64 s[42:43], s[10:11]
	s_cbranch_execz .LBB0_1932
	s_waitcnt lgkmcnt(0)
	v_add_f32_e32 v50, v48, v49
	v_lshlrev_b64 v[48:49], 6, v[64:65]
	v_lshl_add_u64 v[48:49], s[22:23], 0, v[48:49]
	v_lshl_add_u64 v[48:49], s[40:41], 2, v[48:49]
	s_lshl_b32 s30, s67, 2
	v_lshl_add_u64 v[48:49], v[48:49], 0, s[30:31]
	global_store_dword v[48:49], v50, off
; __device__ __forceinline__ unsigned pk2(float lo, float hi) { unsigned r; asm volatile("v_cvt_pk_bf16_f32 %0, %1, %2" : "=v"(r) : "v"(lo), "v"(hi)); return r; }
;     __device__ __forceinline__ void operator()(const f32x4 (&acc)[2][2][4][2], const Unit& u, int wr, int wc, int fr, int fq) const {
;     ...
;                 const int row = row0 + ai * 128 + m * 16; const size_t ro = (size_t)row * DM + col0;
;                 float s = 0.f;
; #pragma unroll
;                 for (int bj = 0; bj < 2; ++bj)
; #pragma unroll
;                     for (int n = 0; n < 2; ++n) {
;                         const size_t o = ro + bj * 128 + n * 16;
;                         const f32x4 xn = *(const f32x4*)(xo + o) + acc[ai][bj][m][n];
;                         *(f32x4*)(xf + o) = xn;
;                         u32x2 w; w.x = pk2(xn[0], xn[1]); w.y = pk2(xn[2], xn[3]); *(u32x2*)(xb + o) = w;
;                         s += (xn[0] * xn[0] + xn[1] * xn[1]) + (xn[2] * xn[2] + xn[3] * xn[3]);
;                     }
;                 s += __shfl_xor(s, 16); s += __shfl_xor(s, 32);
;                 if (fq == 0) ssq[(size_t)row * 16 + u.pn * 4 + wc] = s;
;             }
.LBB0_1932:
	s_or_b64 exec, exec, s[42:43]
	v_add_u32_e32 v48, 0x90, v146
	s_waitcnt lgkmcnt(0)
	v_ashrrev_i32_e32 v49, 31, v48
	v_lshlrev_b64 v[50:51], 10, v[48:49]
	v_lshl_add_u64 v[54:55], v[50:51], 0, v[142:143]
	v_lshlrev_b64 v[56:57], 2, v[54:55]
	v_lshl_add_u64 v[58:59], s[14:15], 0, v[56:57]
	v_lshl_add_u64 v[54:55], v[54:55], 1, s[20:21]
	v_lshl_add_u64 v[56:57], s[24:25], 0, v[56:57]
	s_waitcnt vmcnt(47)
	v_mov_b32_e32 v50, v182
	v_mov_b32_e32 v51, v183
	v_mov_b32_e32 v52, v184
	v_mov_b32_e32 v53, v185
	v_pk_add_f32 v[46:47], v[46:47], v[52:53]
	v_pk_add_f32 v[44:45], v[44:45], v[50:51]
	global_store_dwordx4 v[56:57], v[44:47], off sc1
	v_cvt_pk_bf16_f32 v50, v44, v45
	v_cvt_pk_bf16_f32 v51, v46, v47
	global_store_dwordx2 v[54:55], v[50:51], off
	v_mul_f32_e32 v45, v45, v45
	v_mul_f32_e32 v47, v47, v47
	v_fmac_f32_e32 v45, v44, v44
	v_fmac_f32_e32 v47, v46, v46
	v_add_f32_e32 v44, v45, v47
	s_waitcnt vmcnt(46)
	v_mov_b32_e32 v50, v186
	v_mov_b32_e32 v51, v187
	v_mov_b32_e32 v52, v188
	v_mov_b32_e32 v53, v189
	v_pk_add_f32 v[42:43], v[42:43], v[52:53]
	v_pk_add_f32 v[40:41], v[40:41], v[50:51]
	global_store_dwordx4 v[56:57], v[40:43], off offset:64 sc1
	v_cvt_pk_bf16_f32 v50, v40, v41
	v_cvt_pk_bf16_f32 v51, v42, v43
	global_store_dwordx2 v[54:55], v[50:51], off offset:32
	v_mul_f32_e32 v41, v41, v41
	v_mul_f32_e32 v43, v43, v43
	v_fmac_f32_e32 v41, v40, v40
	v_fmac_f32_e32 v43, v42, v42
	v_add_f32_e32 v40, v41, v43
	v_add_f32_e32 v40, v44, v40
	s_waitcnt vmcnt(45)
	v_mov_b32_e32 v50, v190
	v_mov_b32_e32 v51, v191
	v_mov_b32_e32 v52, v192
	v_mov_b32_e32 v53, v193
	v_pk_add_f32 v[38:39], v[38:39], v[52:53]
	v_pk_add_f32 v[36:37], v[36:37], v[50:51]
	global_store_dwordx4 v[56:57], v[36:39], off offset:512 sc1
	v_cvt_pk_bf16_f32 v50, v36, v37
	v_cvt_pk_bf16_f32 v51, v38, v39
	global_store_dwordx2 v[54:55], v[50:51], off offset:256
	v_mul_f32_e32 v37, v37, v37
	v_mul_f32_e32 v39, v39, v39
	v_fmac_f32_e32 v37, v36, v36
	v_fmac_f32_e32 v39, v38, v38
	v_add_f32_e32 v36, v37, v39
	v_add_f32_e32 v38, v40, v36
	s_waitcnt vmcnt(44)
	v_mov_b32_e32 v50, v194
	v_mov_b32_e32 v51, v195
	v_mov_b32_e32 v52, v196
	v_mov_b32_e32 v53, v197
	v_pk_add_f32 v[36:37], v[34:35], v[52:53]
	v_pk_add_f32 v[34:35], v[32:33], v[50:51]
	v_mul_f32_e32 v33, v37, v37
	v_mul_f32_e32 v32, v35, v35
	v_fmac_f32_e32 v32, v34, v34
	v_fmac_f32_e32 v33, v36, v36
	v_add_f32_e32 v32, v32, v33
	v_add_f32_e32 v32, v38, v32
	ds_bpermute_b32 v33, v116, v32
	global_store_dwordx4 v[56:57], v[34:37], off offset:576 sc1
	s_waitcnt lgkmcnt(0)
	v_add_f32_e32 v32, v32, v33
	ds_bpermute_b32 v33, v114, v32
	v_cvt_pk_bf16_f32 v34, v34, v35
	v_cvt_pk_bf16_f32 v35, v36, v37
	global_store_dwordx2 v[54:55], v[34:35], off offset:288
	s_and_saveexec_b64 s[42:43], s[10:11]
	s_cbranch_execz .LBB0_1934
	s_waitcnt lgkmcnt(0)
	v_add_f32_e32 v34, v32, v33
	v_lshlrev_b64 v[32:33], 6, v[48:49]
	v_lshl_add_u64 v[32:33], s[22:23], 0, v[32:33]
	v_lshl_add_u64 v[32:33], s[40:41], 2, v[32:33]
	s_lshl_b32 s30, s67, 2
	v_lshl_add_u64 v[32:33], v[32:33], 0, s[30:31]
	global_store_dword v[32:33], v34, off
; __device__ __forceinline__ unsigned pk2(float lo, float hi) { unsigned r; asm volatile("v_cvt_pk_bf16_f32 %0, %1, %2" : "=v"(r) : "v"(lo), "v"(hi)); return r; }
;     __device__ __forceinline__ void operator()(const f32x4 (&acc)[2][2][4][2], const Unit& u, int wr, int wc, int fr, int fq) const {
;     ...
;                 const int row = row0 + ai * 128 + m * 16; const size_t ro = (size_t)row * DM + col0;
;                 float s = 0.f;
; #pragma unroll
;                 for (int bj = 0; bj < 2; ++bj)
; #pragma unroll
;                     for (int n = 0; n < 2; ++n) {
;                         const size_t o = ro + bj * 128 + n * 16;
;                         const f32x4 xn = *(const f32x4*)(xo + o) + acc[ai][bj][m][n];
;                         *(f32x4*)(xf + o) = xn;
;                         u32x2 w; w.x = pk2(xn[0], xn[1]); w.y = pk2(xn[2], xn[3]); *(u32x2*)(xb + o) = w;
;                         s += (xn[0] * xn[0] + xn[1] * xn[1]) + (xn[2] * xn[2] + xn[3] * xn[3]);
;                     }
;                 s += __shfl_xor(s, 16); s += __shfl_xor(s, 32);
;                 if (fq == 0) ssq[(size_t)row * 16 + u.pn * 4 + wc] = s;
;             }
.LBB0_1934:
	s_or_b64 exec, exec, s[42:43]
	v_add_u32_e32 v32, 0xa0, v146
	s_waitcnt lgkmcnt(0)
	v_ashrrev_i32_e32 v33, 31, v32
	v_lshlrev_b64 v[34:35], 10, v[32:33]
	v_lshl_add_u64 v[38:39], v[34:35], 0, v[142:143]
	v_lshlrev_b64 v[40:41], 2, v[38:39]
	v_lshl_add_u64 v[42:43], s[14:15], 0, v[40:41]
	v_lshl_add_u64 v[38:39], v[38:39], 1, s[20:21]
	v_lshl_add_u64 v[40:41], s[24:25], 0, v[40:41]
	s_waitcnt vmcnt(43)
	v_mov_b32_e32 v34, v198
	v_mov_b32_e32 v35, v199
	v_mov_b32_e32 v36, v200
	v_mov_b32_e32 v37, v201
	v_pk_add_f32 v[30:31], v[30:31], v[36:37]
	v_pk_add_f32 v[28:29], v[28:29], v[34:35]
	global_store_dwordx4 v[40:41], v[28:31], off sc1
	v_cvt_pk_bf16_f32 v34, v28, v29
	v_cvt_pk_bf16_f32 v35, v30, v31
	global_store_dwordx2 v[38:39], v[34:35], off
	v_mul_f32_e32 v29, v29, v29
	v_mul_f32_e32 v31, v31, v31
	v_fmac_f32_e32 v29, v28, v28
	v_fmac_f32_e32 v31, v30, v30
	v_add_f32_e32 v28, v29, v31
	s_waitcnt vmcnt(42)
	v_mov_b32_e32 v34, v202
	v_mov_b32_e32 v35, v203
	v_mov_b32_e32 v36, v204
	v_mov_b32_e32 v37, v205
	v_pk_add_f32 v[26:27], v[26:27], v[36:37]
	v_pk_add_f32 v[24:25], v[24:25], v[34:35]
	global_store_dwordx4 v[40:41], v[24:27], off offset:64 sc1
	v_cvt_pk_bf16_f32 v34, v24, v25
	v_cvt_pk_bf16_f32 v35, v26, v27
	global_store_dwordx2 v[38:39], v[34:35], off offset:32
	v_mul_f32_e32 v25, v25, v25
	v_mul_f32_e32 v27, v27, v27
	v_fmac_f32_e32 v25, v24, v24
	v_fmac_f32_e32 v27, v26, v26
	v_add_f32_e32 v24, v25, v27
	v_add_f32_e32 v24, v28, v24
	s_waitcnt vmcnt(41)
	v_mov_b32_e32 v34, v206
	v_mov_b32_e32 v35, v207
	v_mov_b32_e32 v36, v208
	v_mov_b32_e32 v37, v209
	v_pk_add_f32 v[22:23], v[22:23], v[36:37]
	v_pk_add_f32 v[20:21], v[20:21], v[34:35]
	global_store_dwordx4 v[40:41], v[20:23], off offset:512 sc1
	v_cvt_pk_bf16_f32 v34, v20, v21
	v_cvt_pk_bf16_f32 v35, v22, v23
	global_store_dwordx2 v[38:39], v[34:35], off offset:256
	v_mul_f32_e32 v21, v21, v21
	v_mul_f32_e32 v23, v23, v23
	v_fmac_f32_e32 v21, v20, v20
	v_fmac_f32_e32 v23, v22, v22
	v_add_f32_e32 v20, v21, v23
	v_add_f32_e32 v22, v24, v20
	s_waitcnt vmcnt(40)
	v_mov_b32_e32 v34, v210
	v_mov_b32_e32 v35, v211
	v_mov_b32_e32 v36, v212
	v_mov_b32_e32 v37, v213
	v_pk_add_f32 v[20:21], v[18:19], v[36:37]
	v_pk_add_f32 v[18:19], v[16:17], v[34:35]
	v_mul_f32_e32 v17, v21, v21
	v_mul_f32_e32 v16, v19, v19
	v_fmac_f32_e32 v16, v18, v18
	v_fmac_f32_e32 v17, v20, v20
	v_add_f32_e32 v16, v16, v17
	v_add_f32_e32 v16, v22, v16
	ds_bpermute_b32 v17, v116, v16
	global_store_dwordx4 v[40:41], v[18:21], off offset:576 sc1
	s_waitcnt lgkmcnt(0)
	v_add_f32_e32 v16, v16, v17
	ds_bpermute_b32 v17, v114, v16
	v_cvt_pk_bf16_f32 v18, v18, v19
	v_cvt_pk_bf16_f32 v19, v20, v21
	global_store_dwordx2 v[38:39], v[18:19], off offset:288
	s_and_saveexec_b64 s[42:43], s[10:11]
	s_cbranch_execz .LBB0_1936
	s_waitcnt lgkmcnt(0)
	v_add_f32_e32 v18, v16, v17
	v_lshlrev_b64 v[16:17], 6, v[32:33]
	v_lshl_add_u64 v[16:17], s[22:23], 0, v[16:17]
	v_lshl_add_u64 v[16:17], s[40:41], 2, v[16:17]
	s_lshl_b32 s30, s67, 2
	v_lshl_add_u64 v[16:17], v[16:17], 0, s[30:31]
	global_store_dword v[16:17], v18, off
.LBB0_1936:
	s_or_b64 exec, exec, s[42:43]
	v_add_u32_e32 v16, 0xb0, v146
	s_waitcnt lgkmcnt(0)
	v_ashrrev_i32_e32 v17, 31, v16
	v_lshlrev_b64 v[18:19], 10, v[16:17]
	v_lshl_add_u64 v[22:23], v[18:19], 0, v[142:143]
	v_lshlrev_b64 v[24:25], 2, v[22:23]
	v_lshl_add_u64 v[26:27], s[14:15], 0, v[24:25]
	v_lshl_add_u64 v[22:23], v[22:23], 1, s[20:21]
	v_lshl_add_u64 v[24:25], s[24:25], 0, v[24:25]
	s_waitcnt vmcnt(39)
	v_mov_b32_e32 v18, v214
	v_mov_b32_e32 v19, v215
	v_mov_b32_e32 v20, v216
	v_mov_b32_e32 v21, v217
	v_pk_add_f32 v[14:15], v[14:15], v[20:21]
	v_pk_add_f32 v[12:13], v[12:13], v[18:19]
	global_store_dwordx4 v[24:25], v[12:15], off sc1
	v_cvt_pk_bf16_f32 v18, v12, v13
	v_cvt_pk_bf16_f32 v19, v14, v15
	global_store_dwordx2 v[22:23], v[18:19], off
	v_mul_f32_e32 v13, v13, v13
	v_mul_f32_e32 v15, v15, v15
	v_fmac_f32_e32 v13, v12, v12
	v_fmac_f32_e32 v15, v14, v14
	v_add_f32_e32 v12, v13, v15
	s_waitcnt vmcnt(38)
	v_mov_b32_e32 v18, v218
	v_mov_b32_e32 v19, v219
	v_mov_b32_e32 v20, v220
	v_mov_b32_e32 v21, v221
	v_pk_add_f32 v[10:11], v[10:11], v[20:21]
	v_pk_add_f32 v[8:9], v[8:9], v[18:19]
	global_store_dwordx4 v[24:25], v[8:11], off offset:64 sc1
	v_cvt_pk_bf16_f32 v18, v8, v9
	v_cvt_pk_bf16_f32 v19, v10, v11
	global_store_dwordx2 v[22:23], v[18:19], off offset:32
	v_mul_f32_e32 v9, v9, v9
	v_mul_f32_e32 v11, v11, v11
	v_fmac_f32_e32 v9, v8, v8
	v_fmac_f32_e32 v11, v10, v10
	v_add_f32_e32 v8, v9, v11
	v_add_f32_e32 v8, v12, v8
	s_waitcnt vmcnt(37)
	v_mov_b32_e32 v18, v232
	v_mov_b32_e32 v19, v233
	v_mov_b32_e32 v20, v234
	v_mov_b32_e32 v21, v235
	v_pk_add_f32 v[6:7], v[6:7], v[20:21]
	v_pk_add_f32 v[4:5], v[4:5], v[18:19]
	global_store_dwordx4 v[24:25], v[4:7], off offset:512 sc1
	v_cvt_pk_bf16_f32 v18, v4, v5
	v_cvt_pk_bf16_f32 v19, v6, v7
	global_store_dwordx2 v[22:23], v[18:19], off offset:256
	v_mul_f32_e32 v5, v5, v5
	v_mul_f32_e32 v7, v7, v7
	v_fmac_f32_e32 v5, v4, v4
	v_fmac_f32_e32 v7, v6, v6
	v_add_f32_e32 v4, v5, v7
	v_add_f32_e32 v6, v8, v4
	s_waitcnt vmcnt(36)
	v_mov_b32_e32 v18, v236
	v_mov_b32_e32 v19, v237
	v_mov_b32_e32 v20, v238
	v_mov_b32_e32 v21, v239
	v_pk_add_f32 v[4:5], v[2:3], v[20:21]
	v_pk_add_f32 v[2:3], v[0:1], v[18:19]
	v_mul_f32_e32 v1, v5, v5
	v_mul_f32_e32 v0, v3, v3
	v_fmac_f32_e32 v0, v2, v2
	v_fmac_f32_e32 v1, v4, v4
	v_add_f32_e32 v0, v0, v1
	v_add_f32_e32 v0, v6, v0
	ds_bpermute_b32 v1, v116, v0
	global_store_dwordx4 v[24:25], v[2:5], off offset:576 sc1
	s_waitcnt lgkmcnt(0)
	v_add_f32_e32 v0, v0, v1
	ds_bpermute_b32 v1, v114, v0
	v_cvt_pk_bf16_f32 v2, v2, v3
	v_cvt_pk_bf16_f32 v3, v4, v5
	global_store_dwordx2 v[22:23], v[2:3], off offset:288
	s_and_saveexec_b64 s[14:15], s[10:11]
	s_cbranch_execz .LBB0_1895
	s_waitcnt lgkmcnt(0)
	v_add_f32_e32 v2, v0, v1
	v_lshlrev_b64 v[0:1], 6, v[16:17]
	v_lshl_add_u64 v[0:1], s[22:23], 0, v[0:1]
	v_lshl_add_u64 v[0:1], s[40:41], 2, v[0:1]
	s_lshl_b32 s30, s67, 2
	v_lshl_add_u64 v[0:1], v[0:1], 0, s[30:31]
	global_store_dword v[0:1], v2, off
	s_branch .LBB0_1895

;     __device__ __forceinline__ void operator()(const f32x4 (&acc)[2][2][4][2], const Unit& u, int wr, int wc, int fr, int fq) const {
;         const int row0 = u.pm * 256 + wr * 64 + fr, col0 = u.pn * 256 + wc * 32 + 4 * fq;
; #pragma unroll
;         for (int ai = 0; ai < 2; ++ai)
; #pragma unroll
;             for (int m = 0; m < 4; ++m) { float* rowp = part + (size_t)(row0 + ai * 128 + m * 16) * DM + col0;
; #pragma unroll
;                 for (int bj = 0; bj < 2; ++bj)
; #pragma unroll
;                     for (int n = 0; n < 2; ++n) *(f32x4*)(rowp + bj * 128 + n * 16) = acc[ai][bj][m][n]; }
;     }
.LBB0_1968:
	v_lshl_add_u32 v146, s85, 8, v139
	v_lshl_or_b32 v148, s30, 8, v141
	v_ashrrev_i32_e32 v147, 31, v146
	v_ashrrev_i32_e32 v149, 31, v148
	v_lshlrev_b64 v[150:151], 12, v[146:147]
	v_lshl_add_u64 v[150:151], s[38:39], 0, v[150:151]
	v_lshlrev_b64 v[148:149], 2, v[148:149]
	v_lshl_add_u64 v[150:151], v[150:151], 0, v[148:149]
	global_store_dwordx4 v[150:151], v[124:127], off sc1
	global_store_dwordx4 v[150:151], v[120:123], off offset:64 sc1
	global_store_dwordx4 v[150:151], v[108:111], off offset:512 sc1
	global_store_dwordx4 v[150:151], v[100:103], off offset:576 sc1
	s_mov_b32 s30, 0x80000
	s_mov_b64 s[34:35], 0x80000
	v_or_b32_e32 v100, 16, v146
	v_ashrrev_i32_e32 v101, 31, v100
	v_lshlrev_b64 v[100:101], 12, v[100:101]
	v_lshl_add_u64 v[100:101], s[38:39], 0, v[100:101]
	v_lshl_add_u64 v[100:101], v[100:101], 0, v[148:149]
	global_store_dwordx4 v[100:101], v[116:119], off sc1
	global_store_dwordx4 v[100:101], v[112:115], off offset:64 sc1
	global_store_dwordx4 v[100:101], v[92:95], off offset:512 sc1
	global_store_dwordx4 v[100:101], v[84:87], off offset:576 sc1
	s_mov_b32 s85, s92
	s_mov_b64 s[36:37], s[56:57]
	v_or_b32_e32 v84, 32, v146
	v_ashrrev_i32_e32 v85, 31, v84
	v_lshlrev_b64 v[84:85], 12, v[84:85]
	v_lshl_add_u64 v[84:85], s[38:39], 0, v[84:85]
	v_lshl_add_u64 v[84:85], v[84:85], 0, v[148:149]
	global_store_dwordx4 v[84:85], v[104:107], off sc1
	global_store_dwordx4 v[84:85], v[96:99], off offset:64 sc1
	global_store_dwordx4 v[84:85], v[76:79], off offset:512 sc1
	global_store_dwordx4 v[84:85], v[72:75], off offset:576 sc1
	s_nop 1
	v_or_b32_e32 v72, 48, v146
	v_ashrrev_i32_e32 v73, 31, v72
	v_lshlrev_b64 v[72:73], 12, v[72:73]
	v_lshl_add_u64 v[72:73], s[38:39], 0, v[72:73]
	v_lshl_add_u64 v[72:73], v[72:73], 0, v[148:149]
	global_store_dwordx4 v[72:73], v[88:91], off sc1
	global_store_dwordx4 v[72:73], v[80:83], off offset:64 sc1
	global_store_dwordx4 v[72:73], v[68:71], off offset:512 sc1
	global_store_dwordx4 v[72:73], v[64:67], off offset:576 sc1
	s_nop 1
	v_add_co_u32_e32 v66, vcc, s30, v150
	s_mov_b32 s30, 0x90000
	s_nop 0
	v_addc_co_u32_e32 v67, vcc, 0, v151, vcc
	v_lshl_add_u64 v[64:65], v[150:151], 0, s[34:35]
	global_store_dwordx4 v[66:67], v[60:63], off sc1
	global_store_dwordx4 v[64:65], v[56:59], off offset:64 sc1
	global_store_dwordx4 v[64:65], v[44:47], off offset:512 sc1
	global_store_dwordx4 v[64:65], v[36:39], off offset:576 sc1
	s_mov_b64 s[34:35], 0x90000
	s_nop 0
	v_add_co_u32_e32 v38, vcc, s30, v150
	s_mov_b32 s30, 0xa0000
	s_nop 0
	v_addc_co_u32_e32 v39, vcc, 0, v151, vcc
	v_lshl_add_u64 v[36:37], v[150:151], 0, s[34:35]
	global_store_dwordx4 v[38:39], v[52:55], off sc1
	global_store_dwordx4 v[36:37], v[48:51], off offset:64 sc1
	global_store_dwordx4 v[36:37], v[28:31], off offset:512 sc1
	global_store_dwordx4 v[36:37], v[20:23], off offset:576 sc1
	s_mov_b64 s[34:35], 0xa0000
	s_nop 0
	v_add_co_u32_e32 v22, vcc, s30, v150
	v_lshl_add_u64 v[20:21], v[150:151], 0, s[34:35]
	s_nop 0
	v_addc_co_u32_e32 v23, vcc, 0, v151, vcc
	global_store_dwordx4 v[22:23], v[40:43], off sc1
	global_store_dwordx4 v[20:21], v[32:35], off offset:64 sc1
	global_store_dwordx4 v[20:21], v[12:15], off offset:512 sc1
	global_store_dwordx4 v[20:21], v[8:11], off offset:576 sc1
	s_mov_b64 s[34:35], 0xb0000
	s_mov_b32 s30, s42
	v_add_co_u32_e32 v10, vcc, 0xb0000, v150
	v_lshl_add_u64 v[8:9], v[150:151], 0, s[34:35]
	s_nop 0
	v_addc_co_u32_e32 v11, vcc, 0, v151, vcc
	s_and_b64 vcc, exec, s[40:41]
	s_mov_b64 s[34:35], s[54:55]
	global_store_dwordx4 v[10:11], v[24:27], off sc1
	global_store_dwordx4 v[8:9], v[16:19], off offset:64 sc1
	global_store_dwordx4 v[8:9], v[4:7], off offset:512 sc1
	global_store_dwordx4 v[8:9], v[0:3], off offset:576 sc1
	s_cbranch_vccnz .LBB0_1995

; __device__ __forceinline__ unsigned pk2(float lo, float hi) { unsigned r; asm volatile("v_cvt_pk_bf16_f32 %0, %1, %2" : "=v"(r) : "v"(lo), "v"(hi)); return r; }
; #define RAW_BARRIER() do { asm volatile("s_waitcnt lgkmcnt(0)" ::: "memory"); __builtin_amdgcn_s_barrier(); asm volatile("" ::: "memory"); } while (0)
;     ...
;         RAW_BARRIER();
;         { u32x4 w;
;           w.x = pk2(tile[(k8 + 0) * 65 + n], tile[(k8 + 1) * 65 + n]); w.y = pk2(tile[(k8 + 2) * 65 + n], tile[(k8 + 3) * 65 + n]);
;           w.z = pk2(tile[(k8 + 4) * 65 + n], tile[(k8 + 5) * 65 + n]); w.w = pk2(tile[(k8 + 6) * 65 + n], tile[(k8 + 7) * 65 + n]);
;           *(u32x4*)(dst + (size_t)(n0 + n) * K + k0 + k8) = w; }
;         RAW_BARRIER();
.LBB0_2013:
	s_waitcnt lgkmcnt(0)
	s_barrier
	ds_read_b32 v11, v18 offset:260
	ds_read_b32 v21, v17
	s_ashr_i32 s14, s18, 31
	s_lshr_b32 s14, s14, 26
	s_add_i32 s15, s18, s14
	s_and_b32 s14, s15, 0xffffffc0
	s_lshl_b32 s15, s15, 6
	s_waitcnt lgkmcnt(0)
	v_cvt_pk_bf16_f32 v22, v21, v11
	ds_read2_b32 v[24:25], v18 offset0:130 offset1:195
	v_add_u32_e32 v11, 0x400, v18
	v_add_u32_e32 v21, s17, v15
	s_and_b32 s15, s15, 0xfffff000
	s_waitcnt lgkmcnt(0)
	v_cvt_pk_bf16_f32 v23, v24, v25
	ds_read2_b32 v[24:25], v11 offset0:4 offset1:69
	v_subrev_u32_e32 v28, s15, v21
	s_waitcnt lgkmcnt(0)
	v_cvt_pk_bf16_f32 v24, v24, v25
	ds_read2_b32 v[26:27], v11 offset0:134 offset1:199
	v_ashrrev_i32_e32 v29, 31, v28
	s_waitcnt lgkmcnt(0)
	v_cvt_pk_bf16_f32 v25, v26, v27
	v_lshlrev_b64 v[26:27], 11, v[28:29]
	v_lshl_add_u64 v[26:27], s[8:9], 0, v[26:27]
	s_ashr_i32 s15, s14, 31
	v_lshl_add_u64 v[26:27], s[14:15], 1, v[26:27]
	v_lshl_add_u64 v[26:27], v[26:27], 0, v[8:9]
	global_store_dwordx4 v[26:27], v[22:25], off sc1
	s_waitcnt lgkmcnt(0)
	s_barrier
	s_andn2_b64 vcc, exec, s[12:13]
	s_mov_b32 s17, s20
	s_mov_b32 s18, s19
	s_cbranch_vccz .LBB0_2018

; __device__ __forceinline__ unsigned pk2(float lo, float hi) { unsigned r; asm volatile("v_cvt_pk_bf16_f32 %0, %1, %2" : "=v"(r) : "v"(lo), "v"(hi)); return r; }
;     ...
;         __syncthreads();
;         const int lane = threadIdx.x & 63, wv = threadIdx.x >> 6;
;         const int rbase = u.pm * 256 + (kq * 4 + u.pn) * 16 + wv * 2;
; #pragma unroll
;         for (int rr = 0; rr < 2; ++rr) {
;             const int row = rbase + rr; float sq = 0.f;
; #pragma unroll
;             for (int i = 0; i < 4; ++i) {
;                 const size_t o = (size_t)row * DM + i * 256 + lane * 4;
;                 f32x4 v = *(const f32x4*)(xold + o);
; #pragma unroll
;                 for (int q = 0; q < 4; ++q) v += *(const f32x4*)(part + (size_t)q * 1024 * DM + o);
;                 *(f32x4*)(xf_s + o) = v;
;                 u32x2 w; w.x = pk2(v[0], v[1]); w.y = pk2(v[2], v[3]); *(u32x2*)(xb_s + o) = w;
;                 sq += (v[0] * v[0] + v[1] * v[1]) + (v[2] * v[2] + v[3] * v[3]);
;             }
; #pragma unroll
;             for (int o = 32; o >= 1; o >>= 1) sq += __shfl_xor(sq, o);
;             if (lane < 16) ssq_s[(size_t)row * 16 + lane] = lane == 0 ? sq : 0.f;
;         }
.LBB0_2020:
	s_or_b64 exec, exec, s[8:9]
	s_add_u32 s18, s24, 0x4000000
	s_addc_u32 s19, s25, 0
	s_add_u32 s16, s16, 0x2000000
	s_addc_u32 s17, s17, 0
	s_lshr_b32 s8, s71, 2
	v_lshrrev_b32_e32 v0, 5, v166
	s_and_b32 s8, s8, 0xffffffc
	v_and_b32_e32 v0, 30, v0
	s_add_i32 s6, s6, s8
	v_lshl_or_b32 v0, s7, 8, v0
	v_lshl_add_u32 v2, s6, 4, v0
	v_ashrrev_i32_e32 v3, 31, v2
	v_lshlrev_b32_e32 v0, 2, v167
	v_lshlrev_b64 v[4:5], 10, v[2:3]
	v_or_b32_e32 v4, v4, v0
	v_lshlrev_b64 v[10:11], 2, v[4:5]
	v_lshl_add_u64 v[38:39], s[12:13], 0, v[10:11]
	s_mov_b32 s6, 0x400000
	v_add_co_u32_e32 v40, vcc, s6, v38
	s_mov_b32 s7, 0x800000
	s_nop 0
	v_addc_co_u32_e32 v41, vcc, 0, v39, vcc
	v_lshl_add_u64 v[26:27], s[18:19], 0, v[10:11]
	v_add_co_u32_e32 v42, vcc, s7, v38
	s_barrier
	global_load_dwordx4 v[6:9], v[26:27], off
	v_addc_co_u32_e32 v43, vcc, 0, v39, vcc
	s_mov_b32 s22, 0xc00000
	global_load_dwordx4 v[10:13], v[38:39], off
	global_load_dwordx4 v[14:17], v[40:41], off
	v_add_co_u32_e32 v44, vcc, s22, v38
	global_load_dwordx4 v[18:21], v[42:43], off
	s_nop 0
	v_addc_co_u32_e32 v45, vcc, 0, v39, vcc
	global_load_dwordx4 v[22:25], v[44:45], off
	v_mov_b32_e32 v31, v5
	v_lshl_add_u64 v[28:29], v[4:5], 1, s[16:17]
	v_or_b32_e32 v30, 0x100, v4
	v_lshl_add_u64 v[32:33], v[30:31], 2, s[18:19]
	v_mov_b32_e32 v35, v5
	v_or_b32_e32 v34, 0x200, v4
	v_lshl_add_u64 v[30:31], v[30:31], 1, s[16:17]
	v_lshl_add_u64 v[36:37], v[34:35], 2, s[18:19]
	v_or_b32_e32 v4, 0x300, v4
	v_lshl_add_u64 v[34:35], v[34:35], 1, s[16:17]
	v_lshl_add_u64 v[46:47], v[4:5], 2, s[18:19]
	v_mov_b32_e32 v1, 0
	s_mov_b64 s[20:21], 0x100000
	v_cmp_gt_u32_e64 s[8:9], 16, v167
	v_cmp_eq_u32_e32 vcc, 0, v167
	v_lshl_add_u64 v[4:5], v[4:5], 1, s[16:17]
	global_load_dwordx4 v[186:189], v[32:33], off
	global_load_dwordx4 v[190:193], v[38:39], off offset:1024
	global_load_dwordx4 v[194:197], v[40:41], off offset:1024
	global_load_dwordx4 v[198:201], v[42:43], off offset:1024
	global_load_dwordx4 v[202:205], v[44:45], off offset:1024
	global_load_dwordx4 v[206:209], v[36:37], off
	global_load_dwordx4 v[210:213], v[38:39], off offset:2048
	global_load_dwordx4 v[214:217], v[40:41], off offset:2048
	global_load_dwordx4 v[218:221], v[42:43], off offset:2048
	global_load_dwordx4 v[222:225], v[44:45], off offset:2048
	global_load_dwordx4 v[226:229], v[46:47], off
	global_load_dwordx4 v[232:235], v[38:39], off offset:3072
	global_load_dwordx4 v[236:239], v[40:41], off offset:3072
	global_load_dwordx4 v[240:243], v[42:43], off offset:3072
	global_load_dwordx4 v[244:247], v[44:45], off offset:3072
	s_waitcnt vmcnt(18)
	v_pk_add_f32 v[8:9], v[8:9], v[12:13]
	v_pk_add_f32 v[6:7], v[6:7], v[10:11]
	s_waitcnt vmcnt(17)
	v_pk_add_f32 v[8:9], v[8:9], v[16:17]
	v_pk_add_f32 v[6:7], v[6:7], v[14:15]
	s_waitcnt vmcnt(16)
	v_pk_add_f32 v[8:9], v[8:9], v[20:21]
	v_pk_add_f32 v[6:7], v[6:7], v[18:19]
	s_waitcnt vmcnt(15)
	v_pk_add_f32 v[8:9], v[8:9], v[24:25]
	v_pk_add_f32 v[6:7], v[6:7], v[22:23]
	global_store_dwordx4 v[26:27], v[6:9], off sc1
	v_cvt_pk_bf16_f32 v10, v6, v7
	v_cvt_pk_bf16_f32 v11, v8, v9
	global_store_dwordx2 v[28:29], v[10:11], off
	s_nop 0
	v_mul_f32_e32 v7, v7, v7
	v_mul_f32_e32 v9, v9, v9
	v_fmac_f32_e32 v7, v6, v6
	v_fmac_f32_e32 v9, v8, v8
	v_add_f32_e32 v6, v7, v9
	s_waitcnt vmcnt(12)
	v_mov_b32_e32 v10, v186
	v_mov_b32_e32 v11, v187
	v_mov_b32_e32 v12, v188
	v_mov_b32_e32 v13, v189
	v_mov_b32_e32 v14, v190
	v_mov_b32_e32 v15, v191
	v_mov_b32_e32 v16, v192
	v_mov_b32_e32 v17, v193
	v_mov_b32_e32 v18, v194
	v_mov_b32_e32 v19, v195
	v_mov_b32_e32 v20, v196
	v_mov_b32_e32 v21, v197
	v_mov_b32_e32 v22, v198
	v_mov_b32_e32 v23, v199
	v_mov_b32_e32 v24, v200
	v_mov_b32_e32 v25, v201
	v_mov_b32_e32 v26, v202
	v_mov_b32_e32 v27, v203
	v_mov_b32_e32 v28, v204
	v_mov_b32_e32 v29, v205
	v_pk_add_f32 v[12:13], v[12:13], v[16:17]
	v_pk_add_f32 v[10:11], v[10:11], v[14:15]
	v_pk_add_f32 v[12:13], v[12:13], v[20:21]
	v_pk_add_f32 v[10:11], v[10:11], v[18:19]
	v_pk_add_f32 v[12:13], v[12:13], v[24:25]
	v_pk_add_f32 v[10:11], v[10:11], v[22:23]
	v_pk_add_f32 v[12:13], v[12:13], v[28:29]
	v_pk_add_f32 v[10:11], v[10:11], v[26:27]
	global_store_dwordx4 v[32:33], v[10:13], off sc1
	v_cvt_pk_bf16_f32 v14, v10, v11
	v_cvt_pk_bf16_f32 v15, v12, v13
	global_store_dwordx2 v[30:31], v[14:15], off
	s_nop 0
	v_mul_f32_e32 v7, v11, v11
	v_mul_f32_e32 v8, v13, v13
	v_fmac_f32_e32 v7, v10, v10
	v_fmac_f32_e32 v8, v12, v12
	v_add_f32_e32 v7, v7, v8
	v_add_f32_e32 v6, v6, v7
	s_waitcnt vmcnt(9)
	v_mov_b32_e32 v14, v206
	v_mov_b32_e32 v15, v207
	v_mov_b32_e32 v16, v208
	v_mov_b32_e32 v17, v209
	v_mov_b32_e32 v18, v210
	v_mov_b32_e32 v19, v211
	v_mov_b32_e32 v20, v212
	v_mov_b32_e32 v21, v213
	v_mov_b32_e32 v22, v214
	v_mov_b32_e32 v23, v215
	v_mov_b32_e32 v24, v216
	v_mov_b32_e32 v25, v217
	v_mov_b32_e32 v26, v218
	v_mov_b32_e32 v27, v219
	v_mov_b32_e32 v28, v220
	v_mov_b32_e32 v29, v221
	v_mov_b32_e32 v30, v222
	v_mov_b32_e32 v31, v223
	v_mov_b32_e32 v32, v224
	v_mov_b32_e32 v33, v225
	v_pk_add_f32 v[16:17], v[16:17], v[20:21]
	v_pk_add_f32 v[14:15], v[14:15], v[18:19]
	v_pk_add_f32 v[16:17], v[16:17], v[24:25]
	v_pk_add_f32 v[14:15], v[14:15], v[22:23]
	v_pk_add_f32 v[16:17], v[16:17], v[28:29]
	v_pk_add_f32 v[14:15], v[14:15], v[26:27]
	v_pk_add_f32 v[16:17], v[16:17], v[32:33]
	v_pk_add_f32 v[14:15], v[14:15], v[30:31]
	global_store_dwordx4 v[36:37], v[14:17], off sc1
	v_cvt_pk_bf16_f32 v18, v14, v15
	v_cvt_pk_bf16_f32 v19, v16, v17
	global_store_dwordx2 v[34:35], v[18:19], off
	s_nop 0
	v_mul_f32_e32 v7, v15, v15
	v_mul_f32_e32 v8, v17, v17
	v_fmac_f32_e32 v7, v14, v14
	v_fmac_f32_e32 v8, v16, v16
	v_add_f32_e32 v7, v7, v8
	v_add_f32_e32 v10, v6, v7
	v_mbcnt_hi_u32_b32 v40, -1, v168
	v_lshl_add_u64 v[38:39], s[14:15], 0, v[0:1]
	v_and_b32_e32 v1, 64, v40
	v_xor_b32_e32 v41, 32, v40
	v_add_u32_e32 v43, 64, v1
	v_cmp_lt_i32_e64 s[10:11], v41, v43
	v_xor_b32_e32 v42, 16, v40
	v_xor_b32_e32 v11, 2, v40
	v_cndmask_b32_e64 v1, v40, v41, s[10:11]
	v_lshlrev_b32_e32 v1, 2, v1
	v_cmp_lt_i32_e64 s[10:11], v42, v43
	v_xor_b32_e32 v12, 1, v40
	s_waitcnt vmcnt(6)
; __device__ __forceinline__ unsigned pk2(float lo, float hi) { unsigned r; asm volatile("v_cvt_pk_bf16_f32 %0, %1, %2" : "=v"(r) : "v"(lo), "v"(hi)); return r; }
;     ...
;             const int row = rbase + rr; float sq = 0.f;
; #pragma unroll
;             for (int i = 0; i < 4; ++i) {
;                 const size_t o = (size_t)row * DM + i * 256 + lane * 4;
;                 f32x4 v = *(const f32x4*)(xold + o);
; #pragma unroll
;                 for (int q = 0; q < 4; ++q) v += *(const f32x4*)(part + (size_t)q * 1024 * DM + o);
;                 *(f32x4*)(xf_s + o) = v;
;                 u32x2 w; w.x = pk2(v[0], v[1]); w.y = pk2(v[2], v[3]); *(u32x2*)(xb_s + o) = w;
;                 sq += (v[0] * v[0] + v[1] * v[1]) + (v[2] * v[2] + v[3] * v[3]);
;             }
; #pragma unroll
;             for (int o = 32; o >= 1; o >>= 1) sq += __shfl_xor(sq, o);
;             if (lane < 16) ssq_s[(size_t)row * 16 + lane] = lane == 0 ? sq : 0.f;
;         }
	v_mov_b32_e32 v18, v226
	v_mov_b32_e32 v19, v227
	v_mov_b32_e32 v20, v228
	v_mov_b32_e32 v21, v229
	v_mov_b32_e32 v22, v232
	v_mov_b32_e32 v23, v233
	v_mov_b32_e32 v24, v234
	v_mov_b32_e32 v25, v235
	v_mov_b32_e32 v26, v236
	v_mov_b32_e32 v27, v237
	v_mov_b32_e32 v28, v238
	v_mov_b32_e32 v29, v239
	v_mov_b32_e32 v30, v240
	v_mov_b32_e32 v31, v241
	v_mov_b32_e32 v32, v242
	v_mov_b32_e32 v33, v243
	v_mov_b32_e32 v34, v244
	v_mov_b32_e32 v35, v245
	v_mov_b32_e32 v36, v246
	v_mov_b32_e32 v37, v247
	v_pk_add_f32 v[6:7], v[20:21], v[24:25]
	v_pk_add_f32 v[8:9], v[18:19], v[22:23]
	v_pk_add_f32 v[6:7], v[6:7], v[28:29]
	v_pk_add_f32 v[8:9], v[8:9], v[26:27]
	v_pk_add_f32 v[6:7], v[6:7], v[32:33]
	v_pk_add_f32 v[8:9], v[8:9], v[30:31]
	v_pk_add_f32 v[18:19], v[6:7], v[36:37]
	v_pk_add_f32 v[16:17], v[8:9], v[34:35]
	v_mul_f32_e32 v7, v19, v19
	v_mul_f32_e32 v6, v17, v17
	v_fmac_f32_e32 v6, v16, v16
	v_fmac_f32_e32 v7, v18, v18
	v_add_f32_e32 v6, v6, v7
	v_add_f32_e32 v6, v10, v6
	ds_bpermute_b32 v7, v1, v6
	v_cndmask_b32_e64 v8, v40, v42, s[10:11]
	v_lshlrev_b32_e32 v8, 2, v8
	v_xor_b32_e32 v9, 8, v40
	v_cmp_lt_i32_e64 s[10:11], v9, v43
	s_waitcnt lgkmcnt(0)
	v_add_f32_e32 v6, v6, v7
	ds_bpermute_b32 v7, v8, v6
	v_cndmask_b32_e64 v9, v40, v9, s[10:11]
	v_lshlrev_b32_e32 v9, 2, v9
	v_xor_b32_e32 v10, 4, v40
	v_cmp_lt_i32_e64 s[10:11], v10, v43
	s_waitcnt lgkmcnt(0)
	v_add_f32_e32 v6, v6, v7
	ds_bpermute_b32 v7, v9, v6
	v_cndmask_b32_e64 v10, v40, v10, s[10:11]
	v_lshlrev_b32_e32 v10, 2, v10
	v_cmp_lt_i32_e64 s[10:11], v11, v43
	global_store_dwordx4 v[46:47], v[16:19], off sc1
	s_waitcnt lgkmcnt(0)
	v_add_f32_e32 v6, v6, v7
	ds_bpermute_b32 v7, v10, v6
	v_cndmask_b32_e64 v11, v40, v11, s[10:11]
	v_lshlrev_b32_e32 v11, 2, v11
	v_cmp_lt_i32_e64 s[10:11], v12, v43
	v_cvt_pk_bf16_f32 v16, v16, v17
	s_waitcnt lgkmcnt(0)
	v_add_f32_e32 v13, v6, v7
	ds_bpermute_b32 v14, v11, v13
	v_cndmask_b32_e64 v12, v40, v12, s[10:11]
	v_lshlrev_b32_e32 v12, 2, v12
	v_lshl_add_u64 v[6:7], v[38:39], 0, s[20:21]
	v_cvt_pk_bf16_f32 v17, v18, v19
	s_waitcnt lgkmcnt(0)
	v_add_f32_e32 v13, v13, v14
	ds_bpermute_b32 v14, v12, v13
	global_store_dwordx2 v[4:5], v[16:17], off
	s_and_saveexec_b64 s[10:11], s[8:9]
	s_cbranch_execz .LBB0_2022
	v_lshlrev_b64 v[4:5], 6, v[2:3]
	s_waitcnt lgkmcnt(0)
	v_add_f32_e32 v3, v13, v14
	v_lshl_add_u64 v[4:5], v[6:7], 0, v[4:5]
	v_cndmask_b32_e32 v3, 0, v3, vcc
	global_store_dword v[4:5], v3, off
.LBB0_2022:
	s_or_b64 exec, exec, s[10:11]
	v_or_b32_e32 v2, 1, v2
	v_ashrrev_i32_e32 v3, 31, v2
	v_lshlrev_b64 v[4:5], 10, v[2:3]
	v_or_b32_e32 v4, v4, v0
	v_lshlrev_b64 v[18:19], 2, v[4:5]
	v_lshl_add_u64 v[46:47], s[12:13], 0, v[18:19]
	v_add_co_u32_e64 v48, s[10:11], s6, v46
	v_lshl_add_u64 v[34:35], s[18:19], 0, v[18:19]
	s_nop 0
	v_addc_co_u32_e64 v49, s[10:11], 0, v47, s[10:11]
	v_add_co_u32_e64 v50, s[10:11], s7, v46
	s_waitcnt lgkmcnt(0)
	global_load_dwordx4 v[14:17], v[34:35], off
	v_addc_co_u32_e64 v51, s[10:11], 0, v47, s[10:11]
	global_load_dwordx4 v[18:21], v[46:47], off
	global_load_dwordx4 v[22:25], v[48:49], off
	v_add_co_u32_e64 v52, s[10:11], s22, v46
	global_load_dwordx4 v[26:29], v[50:51], off
	s_nop 0
	v_addc_co_u32_e64 v53, s[10:11], 0, v47, s[10:11]
	global_load_dwordx4 v[30:33], v[52:53], off
	v_mov_b32_e32 v39, v5
	v_lshl_add_u64 v[36:37], v[4:5], 1, s[16:17]
	v_or_b32_e32 v38, 0x100, v4
	v_lshl_add_u64 v[40:41], v[38:39], 2, s[18:19]
	v_mov_b32_e32 v43, v5
	v_or_b32_e32 v42, 0x200, v4
	v_lshl_add_u64 v[38:39], v[38:39], 1, s[16:17]
	v_lshl_add_u64 v[44:45], v[42:43], 2, s[18:19]
	v_or_b32_e32 v4, 0x300, v4
	v_lshl_add_u64 v[42:43], v[42:43], 1, s[16:17]
	v_lshl_add_u64 v[54:55], v[4:5], 2, s[18:19]
	v_lshl_add_u64 v[4:5], v[4:5], 1, s[16:17]
	global_load_dwordx4 v[186:189], v[40:41], off
	global_load_dwordx4 v[190:193], v[46:47], off offset:1024
	global_load_dwordx4 v[194:197], v[48:49], off offset:1024
	global_load_dwordx4 v[198:201], v[50:51], off offset:1024
	global_load_dwordx4 v[202:205], v[52:53], off offset:1024
	global_load_dwordx4 v[206:209], v[44:45], off
	global_load_dwordx4 v[210:213], v[46:47], off offset:2048
	global_load_dwordx4 v[214:217], v[48:49], off offset:2048
	global_load_dwordx4 v[218:221], v[50:51], off offset:2048
	global_load_dwordx4 v[222:225], v[52:53], off offset:2048
	global_load_dwordx4 v[226:229], v[54:55], off
	global_load_dwordx4 v[232:235], v[46:47], off offset:3072
	global_load_dwordx4 v[236:239], v[48:49], off offset:3072
	global_load_dwordx4 v[240:243], v[50:51], off offset:3072
	global_load_dwordx4 v[244:247], v[52:53], off offset:3072
	s_waitcnt vmcnt(18)
	v_pk_add_f32 v[16:17], v[16:17], v[20:21]
	v_pk_add_f32 v[14:15], v[14:15], v[18:19]
	s_waitcnt vmcnt(17)
	v_pk_add_f32 v[16:17], v[16:17], v[24:25]
	v_pk_add_f32 v[14:15], v[14:15], v[22:23]
	s_waitcnt vmcnt(16)
; __device__ __forceinline__ unsigned pk2(float lo, float hi) { unsigned r; asm volatile("v_cvt_pk_bf16_f32 %0, %1, %2" : "=v"(r) : "v"(lo), "v"(hi)); return r; }
;     ...
;             const int row = rbase + rr; float sq = 0.f;
; #pragma unroll
;             for (int i = 0; i < 4; ++i) {
;                 const size_t o = (size_t)row * DM + i * 256 + lane * 4;
;                 f32x4 v = *(const f32x4*)(xold + o);
; #pragma unroll
;                 for (int q = 0; q < 4; ++q) v += *(const f32x4*)(part + (size_t)q * 1024 * DM + o);
;                 *(f32x4*)(xf_s + o) = v;
;                 u32x2 w; w.x = pk2(v[0], v[1]); w.y = pk2(v[2], v[3]); *(u32x2*)(xb_s + o) = w;
;                 sq += (v[0] * v[0] + v[1] * v[1]) + (v[2] * v[2] + v[3] * v[3]);
;             }
; #pragma unroll
;             for (int o = 32; o >= 1; o >>= 1) sq += __shfl_xor(sq, o);
;             if (lane < 16) ssq_s[(size_t)row * 16 + lane] = lane == 0 ? sq : 0.f;
;         }
	v_pk_add_f32 v[16:17], v[16:17], v[28:29]
	v_pk_add_f32 v[14:15], v[14:15], v[26:27]
	s_waitcnt vmcnt(15)
	v_pk_add_f32 v[16:17], v[16:17], v[32:33]
	v_pk_add_f32 v[14:15], v[14:15], v[30:31]
	global_store_dwordx4 v[34:35], v[14:17], off sc1
	v_cvt_pk_bf16_f32 v18, v14, v15
	v_cvt_pk_bf16_f32 v19, v16, v17
	global_store_dwordx2 v[36:37], v[18:19], off
	s_nop 0
	v_mul_f32_e32 v0, v15, v15
	v_mul_f32_e32 v13, v17, v17
	v_fmac_f32_e32 v0, v14, v14
	v_fmac_f32_e32 v13, v16, v16
	v_add_f32_e32 v0, v0, v13
	s_waitcnt vmcnt(12)
	v_mov_b32_e32 v18, v186
	v_mov_b32_e32 v19, v187
	v_mov_b32_e32 v20, v188
	v_mov_b32_e32 v21, v189
	v_mov_b32_e32 v22, v190
	v_mov_b32_e32 v23, v191
	v_mov_b32_e32 v24, v192
	v_mov_b32_e32 v25, v193
	v_mov_b32_e32 v26, v194
	v_mov_b32_e32 v27, v195
	v_mov_b32_e32 v28, v196
	v_mov_b32_e32 v29, v197
	v_mov_b32_e32 v30, v198
	v_mov_b32_e32 v31, v199
	v_mov_b32_e32 v32, v200
	v_mov_b32_e32 v33, v201
	v_mov_b32_e32 v34, v202
	v_mov_b32_e32 v35, v203
	v_mov_b32_e32 v36, v204
	v_mov_b32_e32 v37, v205
	v_pk_add_f32 v[20:21], v[20:21], v[24:25]
	v_pk_add_f32 v[18:19], v[18:19], v[22:23]
	v_pk_add_f32 v[20:21], v[20:21], v[28:29]
	v_pk_add_f32 v[18:19], v[18:19], v[26:27]
	v_pk_add_f32 v[20:21], v[20:21], v[32:33]
	v_pk_add_f32 v[18:19], v[18:19], v[30:31]
	v_pk_add_f32 v[20:21], v[20:21], v[36:37]
	v_pk_add_f32 v[18:19], v[18:19], v[34:35]
	global_store_dwordx4 v[40:41], v[18:21], off sc1
	v_cvt_pk_bf16_f32 v22, v18, v19
	v_cvt_pk_bf16_f32 v23, v20, v21
	global_store_dwordx2 v[38:39], v[22:23], off
	s_nop 0
	v_mul_f32_e32 v13, v19, v19
	v_mul_f32_e32 v14, v21, v21
	v_fmac_f32_e32 v13, v18, v18
	v_fmac_f32_e32 v14, v20, v20
	v_add_f32_e32 v13, v13, v14
	v_add_f32_e32 v0, v0, v13
	s_waitcnt vmcnt(9)
	v_mov_b32_e32 v22, v206
	v_mov_b32_e32 v23, v207
	v_mov_b32_e32 v24, v208
	v_mov_b32_e32 v25, v209
	v_mov_b32_e32 v26, v210
	v_mov_b32_e32 v27, v211
	v_mov_b32_e32 v28, v212
	v_mov_b32_e32 v29, v213
	v_mov_b32_e32 v30, v214
	v_mov_b32_e32 v31, v215
	v_mov_b32_e32 v32, v216
	v_mov_b32_e32 v33, v217
	v_mov_b32_e32 v34, v218
	v_mov_b32_e32 v35, v219
	v_mov_b32_e32 v36, v220
	v_mov_b32_e32 v37, v221
	v_mov_b32_e32 v38, v222
	v_mov_b32_e32 v39, v223
	v_mov_b32_e32 v40, v224
	v_mov_b32_e32 v41, v225
	v_pk_add_f32 v[24:25], v[24:25], v[28:29]
	v_pk_add_f32 v[22:23], v[22:23], v[26:27]
	v_pk_add_f32 v[24:25], v[24:25], v[32:33]
	v_pk_add_f32 v[22:23], v[22:23], v[30:31]
	v_pk_add_f32 v[24:25], v[24:25], v[36:37]
	v_pk_add_f32 v[22:23], v[22:23], v[34:35]
	v_pk_add_f32 v[24:25], v[24:25], v[40:41]
	v_pk_add_f32 v[22:23], v[22:23], v[38:39]
	global_store_dwordx4 v[44:45], v[22:25], off sc1
	v_cvt_pk_bf16_f32 v26, v22, v23
	v_cvt_pk_bf16_f32 v27, v24, v25
	global_store_dwordx2 v[42:43], v[26:27], off
	s_nop 0
	v_mul_f32_e32 v13, v23, v23
	v_mul_f32_e32 v14, v25, v25
	v_fmac_f32_e32 v13, v22, v22
	v_fmac_f32_e32 v14, v24, v24
	v_add_f32_e32 v13, v13, v14
	v_add_f32_e32 v0, v0, v13
	s_waitcnt vmcnt(6)
	v_mov_b32_e32 v26, v226
	v_mov_b32_e32 v27, v227
	v_mov_b32_e32 v28, v228
	v_mov_b32_e32 v29, v229
	v_mov_b32_e32 v30, v232
	v_mov_b32_e32 v31, v233
	v_mov_b32_e32 v32, v234
	v_mov_b32_e32 v33, v235
	v_mov_b32_e32 v34, v236
	v_mov_b32_e32 v35, v237
	v_mov_b32_e32 v36, v238
	v_mov_b32_e32 v37, v239
	v_mov_b32_e32 v38, v240
	v_mov_b32_e32 v39, v241
	v_mov_b32_e32 v40, v242
	v_mov_b32_e32 v41, v243
	v_mov_b32_e32 v42, v244
	v_mov_b32_e32 v43, v245
	v_mov_b32_e32 v44, v246
	v_mov_b32_e32 v45, v247
	v_pk_add_f32 v[14:15], v[28:29], v[32:33]
	v_pk_add_f32 v[16:17], v[26:27], v[30:31]
	v_pk_add_f32 v[14:15], v[14:15], v[36:37]
	v_pk_add_f32 v[16:17], v[16:17], v[34:35]
	v_pk_add_f32 v[14:15], v[14:15], v[40:41]
	v_pk_add_f32 v[18:19], v[16:17], v[38:39]
	v_pk_add_f32 v[16:17], v[14:15], v[44:45]
	v_pk_add_f32 v[14:15], v[18:19], v[42:43]
	v_mul_f32_e32 v18, v17, v17
	v_mul_f32_e32 v13, v15, v15
	v_fmac_f32_e32 v13, v14, v14
	v_fmac_f32_e32 v18, v16, v16
	v_add_f32_e32 v13, v13, v18
	v_add_f32_e32 v0, v0, v13
	ds_bpermute_b32 v1, v1, v0
	global_store_dwordx4 v[54:55], v[14:17], off sc1
	s_waitcnt lgkmcnt(0)
	v_add_f32_e32 v0, v0, v1
	ds_bpermute_b32 v1, v8, v0
	v_cvt_pk_bf16_f32 v8, v14, v15
	s_waitcnt lgkmcnt(0)
	v_add_f32_e32 v0, v0, v1
	ds_bpermute_b32 v1, v9, v0
	v_cvt_pk_bf16_f32 v9, v16, v17
	global_store_dwordx2 v[4:5], v[8:9], off
	s_waitcnt lgkmcnt(0)
	v_add_f32_e32 v0, v0, v1
	ds_bpermute_b32 v1, v10, v0
	s_waitcnt lgkmcnt(0)
	v_add_f32_e32 v0, v0, v1
	ds_bpermute_b32 v1, v11, v0
	s_waitcnt lgkmcnt(0)
	v_add_f32_e32 v0, v0, v1
	ds_bpermute_b32 v1, v12, v0
	s_and_saveexec_b64 s[10:11], s[8:9]
	s_cbranch_execz .LBB0_2024
	v_lshlrev_b64 v[2:3], 6, v[2:3]
	s_waitcnt lgkmcnt(0)
	v_add_f32_e32 v0, v0, v1
	v_lshl_add_u64 v[2:3], v[6:7], 0, v[2:3]
	v_cndmask_b32_e32 v0, 0, v0, vcc
	global_store_dword v[2:3], v0, off

; __device__ __forceinline__ unsigned pk2(float lo, float hi) { unsigned r; asm volatile("v_cvt_pk_bf16_f32 %0, %1, %2" : "=v"(r) : "v"(lo), "v"(hi)); return r; }
; #define RAW_BARRIER() do { asm volatile("s_waitcnt lgkmcnt(0)" ::: "memory"); __builtin_amdgcn_s_barrier(); asm volatile("" ::: "memory"); } while (0)
;     ...
;         RAW_BARRIER();
;         { u32x4 w;
;           w.x = pk2(tile[(k8 + 0) * 65 + n], tile[(k8 + 1) * 65 + n]); w.y = pk2(tile[(k8 + 2) * 65 + n], tile[(k8 + 3) * 65 + n]);
;           w.z = pk2(tile[(k8 + 4) * 65 + n], tile[(k8 + 5) * 65 + n]); w.w = pk2(tile[(k8 + 6) * 65 + n], tile[(k8 + 7) * 65 + n]);
;           *(u32x4*)(dst + (size_t)(n0 + n) * K + k0 + k8) = w; }
;         RAW_BARRIER();
.LBB0_2028:
	s_waitcnt lgkmcnt(0)
	s_barrier
	ds_read_b32 v11, v18 offset:260
	ds_read_b32 v21, v17
	v_add_u32_e32 v26, s19, v15
	v_ashrrev_i32_e32 v27, 31, v26
	s_and_b32 s12, s16, 0x7fffffc0
	v_lshlrev_b64 v[26:27], 11, v[26:27]
	s_lshl_b32 s12, s12, 1
	v_lshl_add_u64 v[26:27], s[6:7], 0, v[26:27]
	s_waitcnt lgkmcnt(0)
	v_cvt_pk_bf16_f32 v22, v21, v11
	ds_read2_b32 v[24:25], v18 offset0:130 offset1:195
	v_add_u32_e32 v11, 0x400, v18
	v_lshl_add_u64 v[26:27], v[26:27], 0, s[12:13]
	s_waitcnt lgkmcnt(0)
	v_cvt_pk_bf16_f32 v23, v24, v25
	ds_read2_b32 v[24:25], v11 offset0:4 offset1:69
	v_lshl_add_u64 v[26:27], v[26:27], 0, v[8:9]
	s_waitcnt lgkmcnt(0)
	v_cvt_pk_bf16_f32 v24, v24, v25
	ds_read2_b32 v[28:29], v11 offset0:134 offset1:199
	s_waitcnt lgkmcnt(0)
	v_cvt_pk_bf16_f32 v25, v28, v29
	global_store_dwordx4 v[26:27], v[22:25], off sc1
	s_waitcnt lgkmcnt(0)
	s_barrier
	s_addk_i32 s17, 0x2000
	s_and_b64 vcc, exec, s[14:15]
	s_mov_b32 s16, s18
	s_cbranch_vccnz .LBB0_2031

; __device__ __forceinline__ unsigned pk2(float lo, float hi) { unsigned r; asm volatile("v_cvt_pk_bf16_f32 %0, %1, %2" : "=v"(r) : "v"(lo), "v"(hi)); return r; }
;     __device__ __forceinline__ void operator()(const f32x4 (&acc)[2][2][4][2], const Unit& u, int wr, int wc, int fr, int fq) const {
;         const int row0 = u.pm * 256 + wr * 64 + fr, col0 = u.pn * 256 + wc * 32 + 4 * fq;
;         const float* xo = (u.pm < 64) ? xoldA : (xoldB - (size_t)T_P * DM);
; #pragma unroll
;         for (int ai = 0; ai < 2; ++ai)
; #pragma unroll
;             for (int m = 0; m < 4; ++m) {
;                 const int row = row0 + ai * 128 + m * 16; const size_t ro = (size_t)row * DM + col0;
;                 float s = 0.f;
; #pragma unroll
;                 for (int bj = 0; bj < 2; ++bj)
; #pragma unroll
;                     for (int n = 0; n < 2; ++n) {
;                         const size_t o = ro + bj * 128 + n * 16;
;                         const f32x4 xn = *(const f32x4*)(xo + o) + acc[ai][bj][m][n];
;                         *(f32x4*)(xf + o) = xn;
;                         u32x2 w; w.x = pk2(xn[0], xn[1]); w.y = pk2(xn[2], xn[3]); *(u32x2*)(xb + o) = w;
;                         s += (xn[0] * xn[0] + xn[1] * xn[1]) + (xn[2] * xn[2] + xn[3] * xn[3]);
;                     }
;                 s += __shfl_xor(s, 16); s += __shfl_xor(s, 32);
;                 if (fq == 0) ssq[(size_t)row * 16 + u.pn * 4 + wc] = s;
;             }
.LBB0_2178:
	v_lshl_add_u32 v138, s42, 8, v140
	v_lshl_or_b32 v136, s40, 8, v142
	v_ashrrev_i32_e32 v139, 31, v138
	v_ashrrev_i32_e32 v137, 31, v136
	v_lshlrev_b64 v[148:149], 10, v[138:139]
	s_cmp_lt_i32 s42, 64
	v_lshl_add_u64 v[152:153], v[148:149], 0, v[136:137]
	s_cselect_b32 s13, s17, -1
	s_cselect_b32 s12, s16, 0xfc000000
	v_lshlrev_b64 v[154:155], 2, v[152:153]
	v_lshl_add_u64 v[156:157], s[12:13], 0, v[154:155]
	v_subrev_u32_e32 v162, s12, v156
	v_add_u32_e32 v163, 0x0, v162
	global_load_dwordx4 v[170:173], v163, s[12:13]
	v_add_u32_e32 v163, 0x40, v162
	global_load_dwordx4 v[174:177], v163, s[12:13]
	v_add_u32_e32 v163, 0x200, v162
	global_load_dwordx4 v[178:181], v163, s[12:13]
	v_add_u32_e32 v163, 0x240, v162
	global_load_dwordx4 v[182:185], v163, s[12:13]
	v_add_u32_e32 v163, 0x10000, v162
	global_load_dwordx4 v[186:189], v163, s[12:13]
	v_add_u32_e32 v163, 0x10040, v162
	global_load_dwordx4 v[190:193], v163, s[12:13]
	v_add_u32_e32 v163, 0x10200, v162
	global_load_dwordx4 v[194:197], v163, s[12:13]
	v_add_u32_e32 v163, 0x10240, v162
	global_load_dwordx4 v[198:201], v163, s[12:13]
	v_add_u32_e32 v163, 0x20000, v162
	global_load_dwordx4 v[202:205], v163, s[12:13]
	v_add_u32_e32 v163, 0x20040, v162
	global_load_dwordx4 v[206:209], v163, s[12:13]
	v_add_u32_e32 v163, 0x20200, v162
	global_load_dwordx4 v[210:213], v163, s[12:13]
	v_add_u32_e32 v163, 0x20240, v162
	global_load_dwordx4 v[232:235], v163, s[12:13]
	v_add_u32_e32 v163, 0x30000, v162
	global_load_dwordx4 v[236:239], v163, s[12:13]
	v_add_u32_e32 v163, 0x30040, v162
	global_load_dwordx4 v[240:243], v163, s[12:13]
	v_add_u32_e32 v163, 0x30200, v162
	global_load_dwordx4 v[244:247], v163, s[12:13]
	v_add_u32_e32 v163, 0x30240, v162
	global_load_dwordx4 v[248:251], v163, s[12:13]
	v_add_u32_e32 v163, 0x80000, v162
	global_load_dwordx4 v[252:255], v163, s[12:13]
	v_lshl_add_u64 v[158:159], v[152:153], 1, s[22:23]
	v_lshl_add_u64 v[160:161], s[16:17], 0, v[154:155]
	v_xor_b32_e32 v147, 32, v146
	s_lshl_b32 s40, s40, 2
	s_ashr_i32 s41, s40, 31
	s_waitcnt vmcnt(16)
	v_mov_b32_e32 v148, v170
	v_mov_b32_e32 v149, v171
	v_mov_b32_e32 v150, v172
	v_mov_b32_e32 v151, v173
	v_add_u32_e32 v163, 0x80040, v162
	global_load_dwordx4 v[170:173], v163, s[12:13]
	v_pk_add_f32 v[126:127], v[126:127], v[150:151]
	v_pk_add_f32 v[124:125], v[124:125], v[148:149]
	global_store_dwordx4 v[160:161], v[124:127], off sc1
	v_cvt_pk_bf16_f32 v148, v124, v125
	v_cvt_pk_bf16_f32 v149, v126, v127
	global_store_dwordx2 v[158:159], v[148:149], off
	s_waitcnt vmcnt(18)
	v_mov_b32_e32 v148, v174
	v_mov_b32_e32 v149, v175
	v_mov_b32_e32 v150, v176
	v_mov_b32_e32 v151, v177
	v_add_u32_e32 v163, 0x80200, v162
	global_load_dwordx4 v[174:177], v163, s[12:13]
	v_pk_add_f32 v[122:123], v[122:123], v[150:151]
	v_pk_add_f32 v[120:121], v[120:121], v[148:149]
	global_store_dwordx4 v[160:161], v[120:123], off offset:64 sc1
	v_cvt_pk_bf16_f32 v148, v120, v121
	v_cvt_pk_bf16_f32 v149, v122, v123
	global_store_dwordx2 v[158:159], v[148:149], off offset:32
	s_waitcnt vmcnt(20)
	v_mov_b32_e32 v148, v178
	v_mov_b32_e32 v149, v179
	v_mov_b32_e32 v150, v180
	v_mov_b32_e32 v151, v181
	v_add_u32_e32 v163, 0x80240, v162
	global_load_dwordx4 v[178:181], v163, s[12:13]
	v_pk_add_f32 v[150:151], v[118:119], v[150:151]
	v_pk_add_f32 v[148:149], v[116:117], v[148:149]
	global_store_dwordx4 v[160:161], v[148:151], off offset:512 sc1
	v_cvt_pk_bf16_f32 v116, v148, v149
	v_cvt_pk_bf16_f32 v117, v150, v151
	global_store_dwordx2 v[158:159], v[116:117], off offset:256
	v_mul_f32_e32 v118, v125, v125
	v_mul_f32_e32 v119, v127, v127
	v_fmac_f32_e32 v118, v124, v124
	v_fmac_f32_e32 v119, v126, v126
	v_add_f32_e32 v118, v118, v119
	v_mul_f32_e32 v119, v121, v121
	v_mul_f32_e32 v121, v123, v123
	v_fmac_f32_e32 v119, v120, v120
	v_fmac_f32_e32 v121, v122, v122
	v_add_f32_e32 v119, v119, v121
	v_add_f32_e32 v118, v118, v119
	v_mul_f32_e32 v119, v149, v149
	v_mul_f32_e32 v120, v151, v151
	v_fmac_f32_e32 v119, v148, v148
	v_fmac_f32_e32 v120, v150, v150
	v_add_f32_e32 v119, v119, v120
	v_and_b32_e32 v117, 64, v146
	v_add_f32_e32 v122, v118, v119
	v_xor_b32_e32 v116, 16, v146
	v_add_u32_e32 v117, 64, v117
	v_cmp_lt_i32_e32 vcc, v116, v117
	s_waitcnt vmcnt(22)
	v_mov_b32_e32 v152, v182
	v_mov_b32_e32 v153, v183
	v_mov_b32_e32 v154, v184
	v_mov_b32_e32 v155, v185
	v_add_u32_e32 v163, 0x90000, v162
	global_load_dwordx4 v[182:185], v163, s[12:13]
	v_pk_add_f32 v[120:121], v[114:115], v[154:155]
	v_pk_add_f32 v[118:119], v[112:113], v[152:153]
	v_mul_f32_e32 v113, v121, v121
	v_mul_f32_e32 v112, v119, v119
	v_fmac_f32_e32 v112, v118, v118
	v_fmac_f32_e32 v113, v120, v120
	v_cndmask_b32_e32 v116, v146, v116, vcc
	v_add_f32_e32 v112, v112, v113
	v_lshlrev_b32_e32 v116, 2, v116
	v_add_f32_e32 v112, v122, v112
	ds_bpermute_b32 v113, v116, v112
	v_cmp_lt_i32_e32 vcc, v147, v117
	global_store_dwordx4 v[160:161], v[118:121], off offset:576 sc1
	s_waitcnt lgkmcnt(0)
	v_add_f32_e32 v112, v112, v113
	v_cndmask_b32_e32 v114, v146, v147, vcc
	v_lshlrev_b32_e32 v114, 2, v114
	ds_bpermute_b32 v113, v114, v112
	v_cvt_pk_bf16_f32 v118, v118, v119
	v_cvt_pk_bf16_f32 v119, v120, v121
	global_store_dwordx2 v[158:159], v[118:119], off offset:288
	s_and_saveexec_b64 s[42:43], s[8:9]
	s_cbranch_execz .LBB0_2180
	s_waitcnt lgkmcnt(0)
	v_add_f32_e32 v115, v112, v113
	v_lshlrev_b64 v[112:113], 6, v[138:139]
	v_lshl_add_u64 v[112:113], s[24:25], 0, v[112:113]
	v_lshl_add_u64 v[112:113], s[40:41], 2, v[112:113]
	s_lshl_b32 s26, s74, 2
	v_lshl_add_u64 v[112:113], v[112:113], 0, s[26:27]
	global_store_dword v[112:113], v115, off
; __device__ __forceinline__ unsigned pk2(float lo, float hi) { unsigned r; asm volatile("v_cvt_pk_bf16_f32 %0, %1, %2" : "=v"(r) : "v"(lo), "v"(hi)); return r; }
;     __device__ __forceinline__ void operator()(const f32x4 (&acc)[2][2][4][2], const Unit& u, int wr, int wc, int fr, int fq) const {
;     ...
;                 const int row = row0 + ai * 128 + m * 16; const size_t ro = (size_t)row * DM + col0;
;                 float s = 0.f;
; #pragma unroll
;                 for (int bj = 0; bj < 2; ++bj)
; #pragma unroll
;                     for (int n = 0; n < 2; ++n) {
;                         const size_t o = ro + bj * 128 + n * 16;
;                         const f32x4 xn = *(const f32x4*)(xo + o) + acc[ai][bj][m][n];
;                         *(f32x4*)(xf + o) = xn;
;                         u32x2 w; w.x = pk2(xn[0], xn[1]); w.y = pk2(xn[2], xn[3]); *(u32x2*)(xb + o) = w;
;                         s += (xn[0] * xn[0] + xn[1] * xn[1]) + (xn[2] * xn[2] + xn[3] * xn[3]);
;                     }
;                 s += __shfl_xor(s, 16); s += __shfl_xor(s, 32);
;                 if (fq == 0) ssq[(size_t)row * 16 + u.pn * 4 + wc] = s;
;             }
.LBB0_2180:
	s_or_b64 exec, exec, s[42:43]
	v_or_b32_e32 v112, 16, v138
	s_waitcnt lgkmcnt(0)
	v_ashrrev_i32_e32 v113, 31, v112
	v_lshlrev_b64 v[118:119], 10, v[112:113]
	v_lshl_add_u64 v[122:123], v[118:119], 0, v[136:137]
	v_lshlrev_b64 v[124:125], 2, v[122:123]
	v_lshl_add_u64 v[126:127], s[12:13], 0, v[124:125]
	v_lshl_add_u64 v[122:123], v[122:123], 1, s[22:23]
	v_lshl_add_u64 v[124:125], s[16:17], 0, v[124:125]
	s_waitcnt vmcnt(24)
	v_mov_b32_e32 v118, v186
	v_mov_b32_e32 v119, v187
	v_mov_b32_e32 v120, v188
	v_mov_b32_e32 v121, v189
	v_add_u32_e32 v163, 0x90040, v162
	global_load_dwordx4 v[186:189], v163, s[12:13]
	v_pk_add_f32 v[110:111], v[110:111], v[120:121]
	v_pk_add_f32 v[108:109], v[108:109], v[118:119]
	global_store_dwordx4 v[124:125], v[108:111], off sc1
	v_cvt_pk_bf16_f32 v118, v108, v109
	v_cvt_pk_bf16_f32 v119, v110, v111
	global_store_dwordx2 v[122:123], v[118:119], off
	v_mul_f32_e32 v109, v109, v109
	v_mul_f32_e32 v111, v111, v111
	v_fmac_f32_e32 v109, v108, v108
	v_fmac_f32_e32 v111, v110, v110
	v_add_f32_e32 v108, v109, v111
	s_waitcnt vmcnt(26)
	v_mov_b32_e32 v118, v190
	v_mov_b32_e32 v119, v191
	v_mov_b32_e32 v120, v192
	v_mov_b32_e32 v121, v193
	v_add_u32_e32 v163, 0x90200, v162
	global_load_dwordx4 v[190:193], v163, s[12:13]
	v_pk_add_f32 v[106:107], v[106:107], v[120:121]
	v_pk_add_f32 v[104:105], v[104:105], v[118:119]
	global_store_dwordx4 v[124:125], v[104:107], off offset:64 sc1
	v_cvt_pk_bf16_f32 v118, v104, v105
	v_cvt_pk_bf16_f32 v119, v106, v107
	global_store_dwordx2 v[122:123], v[118:119], off offset:32
	v_mul_f32_e32 v105, v105, v105
	v_mul_f32_e32 v107, v107, v107
	v_fmac_f32_e32 v105, v104, v104
	v_fmac_f32_e32 v107, v106, v106
	v_add_f32_e32 v104, v105, v107
	v_add_f32_e32 v104, v108, v104
	s_waitcnt vmcnt(28)
	v_mov_b32_e32 v118, v194
	v_mov_b32_e32 v119, v195
	v_mov_b32_e32 v120, v196
	v_mov_b32_e32 v121, v197
	v_add_u32_e32 v163, 0x90240, v162
	global_load_dwordx4 v[194:197], v163, s[12:13]
	v_pk_add_f32 v[102:103], v[102:103], v[120:121]
	v_pk_add_f32 v[100:101], v[100:101], v[118:119]
	global_store_dwordx4 v[124:125], v[100:103], off offset:512 sc1
	v_cvt_pk_bf16_f32 v118, v100, v101
	v_cvt_pk_bf16_f32 v119, v102, v103
	global_store_dwordx2 v[122:123], v[118:119], off offset:256
	v_mul_f32_e32 v101, v101, v101
	v_mul_f32_e32 v103, v103, v103
	v_fmac_f32_e32 v101, v100, v100
	v_fmac_f32_e32 v103, v102, v102
	v_add_f32_e32 v100, v101, v103
	v_add_f32_e32 v102, v104, v100
	s_waitcnt vmcnt(30)
	v_mov_b32_e32 v118, v198
	v_mov_b32_e32 v119, v199
	v_mov_b32_e32 v120, v200
	v_mov_b32_e32 v121, v201
	v_add_u32_e32 v163, 0xa0000, v162
	global_load_dwordx4 v[198:201], v163, s[12:13]
	v_pk_add_f32 v[100:101], v[98:99], v[120:121]
	v_pk_add_f32 v[98:99], v[96:97], v[118:119]
	v_mul_f32_e32 v97, v101, v101
	v_mul_f32_e32 v96, v99, v99
	v_fmac_f32_e32 v96, v98, v98
	v_fmac_f32_e32 v97, v100, v100
	v_add_f32_e32 v96, v96, v97
	v_add_f32_e32 v96, v102, v96
	ds_bpermute_b32 v97, v116, v96
	global_store_dwordx4 v[124:125], v[98:101], off offset:576 sc1
	s_waitcnt lgkmcnt(0)
	v_add_f32_e32 v96, v96, v97
	ds_bpermute_b32 v97, v114, v96
	v_cvt_pk_bf16_f32 v98, v98, v99
	v_cvt_pk_bf16_f32 v99, v100, v101
	global_store_dwordx2 v[122:123], v[98:99], off offset:288
	s_and_saveexec_b64 s[42:43], s[8:9]
	s_cbranch_execz .LBB0_2182
	s_waitcnt lgkmcnt(0)
	v_add_f32_e32 v98, v96, v97
	v_lshlrev_b64 v[96:97], 6, v[112:113]
	v_lshl_add_u64 v[96:97], s[24:25], 0, v[96:97]
	v_lshl_add_u64 v[96:97], s[40:41], 2, v[96:97]
	s_lshl_b32 s26, s74, 2
	v_lshl_add_u64 v[96:97], v[96:97], 0, s[26:27]
	global_store_dword v[96:97], v98, off
.LBB0_2182:
	s_or_b64 exec, exec, s[42:43]
	v_or_b32_e32 v96, 32, v138
	s_waitcnt lgkmcnt(0)
	v_ashrrev_i32_e32 v97, 31, v96
	v_lshlrev_b64 v[98:99], 10, v[96:97]
	v_lshl_add_u64 v[102:103], v[98:99], 0, v[136:137]
	v_lshlrev_b64 v[104:105], 2, v[102:103]
	v_lshl_add_u64 v[106:107], s[12:13], 0, v[104:105]
	v_lshl_add_u64 v[102:103], v[102:103], 1, s[22:23]
	v_lshl_add_u64 v[104:105], s[16:17], 0, v[104:105]
	s_waitcnt vmcnt(32)
	v_mov_b32_e32 v98, v202
	v_mov_b32_e32 v99, v203
	v_mov_b32_e32 v100, v204
	v_mov_b32_e32 v101, v205
	v_add_u32_e32 v163, 0xa0040, v162
	global_load_dwordx4 v[202:205], v163, s[12:13]
	v_pk_add_f32 v[94:95], v[94:95], v[100:101]
	v_pk_add_f32 v[92:93], v[92:93], v[98:99]
	global_store_dwordx4 v[104:105], v[92:95], off sc1
	v_cvt_pk_bf16_f32 v98, v92, v93
	v_cvt_pk_bf16_f32 v99, v94, v95
	global_store_dwordx2 v[102:103], v[98:99], off
	v_mul_f32_e32 v93, v93, v93
	v_mul_f32_e32 v95, v95, v95
	v_fmac_f32_e32 v93, v92, v92
	v_fmac_f32_e32 v95, v94, v94
	v_add_f32_e32 v92, v93, v95
	s_waitcnt vmcnt(34)
	v_mov_b32_e32 v98, v206
	v_mov_b32_e32 v99, v207
	v_mov_b32_e32 v100, v208
	v_mov_b32_e32 v101, v209
	v_add_u32_e32 v163, 0xa0200, v162
	global_load_dwordx4 v[206:209], v163, s[12:13]
	v_pk_add_f32 v[90:91], v[90:91], v[100:101]
	v_pk_add_f32 v[88:89], v[88:89], v[98:99]
	global_store_dwordx4 v[104:105], v[88:91], off offset:64 sc1
	v_cvt_pk_bf16_f32 v98, v88, v89
	v_cvt_pk_bf16_f32 v99, v90, v91
	global_store_dwordx2 v[102:103], v[98:99], off offset:32
	v_mul_f32_e32 v89, v89, v89
	v_mul_f32_e32 v91, v91, v91
	v_fmac_f32_e32 v89, v88, v88
	v_fmac_f32_e32 v91, v90, v90
	v_add_f32_e32 v88, v89, v91
	v_add_f32_e32 v88, v92, v88
	s_waitcnt vmcnt(36)
	v_mov_b32_e32 v98, v210
	v_mov_b32_e32 v99, v211
	v_mov_b32_e32 v100, v212
	v_mov_b32_e32 v101, v213
	v_add_u32_e32 v163, 0xa0240, v162
	global_load_dwordx4 v[210:213], v163, s[12:13]
	v_pk_add_f32 v[86:87], v[86:87], v[100:101]
	v_pk_add_f32 v[84:85], v[84:85], v[98:99]
	global_store_dwordx4 v[104:105], v[84:87], off offset:512 sc1
	v_cvt_pk_bf16_f32 v98, v84, v85
	v_cvt_pk_bf16_f32 v99, v86, v87
	global_store_dwordx2 v[102:103], v[98:99], off offset:256
	v_mul_f32_e32 v85, v85, v85
	v_mul_f32_e32 v87, v87, v87
	v_fmac_f32_e32 v85, v84, v84
	v_fmac_f32_e32 v87, v86, v86
	v_add_f32_e32 v84, v85, v87
	v_add_f32_e32 v86, v88, v84
	s_waitcnt vmcnt(38)
	v_mov_b32_e32 v98, v232
	v_mov_b32_e32 v99, v233
	v_mov_b32_e32 v100, v234
	v_mov_b32_e32 v101, v235
	v_add_u32_e32 v163, 0xb0000, v162
	global_load_dwordx4 v[232:235], v163, s[12:13]
	v_pk_add_f32 v[84:85], v[82:83], v[100:101]
	v_pk_add_f32 v[82:83], v[80:81], v[98:99]
	v_mul_f32_e32 v81, v85, v85
	v_mul_f32_e32 v80, v83, v83
	v_fmac_f32_e32 v80, v82, v82
	v_fmac_f32_e32 v81, v84, v84
	v_add_f32_e32 v80, v80, v81
	v_add_f32_e32 v80, v86, v80
	ds_bpermute_b32 v81, v116, v80
	global_store_dwordx4 v[104:105], v[82:85], off offset:576 sc1
	s_waitcnt lgkmcnt(0)
	v_add_f32_e32 v80, v80, v81
	ds_bpermute_b32 v81, v114, v80
	v_cvt_pk_bf16_f32 v82, v82, v83
	v_cvt_pk_bf16_f32 v83, v84, v85
	global_store_dwordx2 v[102:103], v[82:83], off offset:288
	s_and_saveexec_b64 s[42:43], s[8:9]
	s_cbranch_execz .LBB0_2184
; __device__ __forceinline__ unsigned pk2(float lo, float hi) { unsigned r; asm volatile("v_cvt_pk_bf16_f32 %0, %1, %2" : "=v"(r) : "v"(lo), "v"(hi)); return r; }
;     __device__ __forceinline__ void operator()(const f32x4 (&acc)[2][2][4][2], const Unit& u, int wr, int wc, int fr, int fq) const {
;     ...
;                 const int row = row0 + ai * 128 + m * 16; const size_t ro = (size_t)row * DM + col0;
;                 float s = 0.f;
; #pragma unroll
;                 for (int bj = 0; bj < 2; ++bj)
; #pragma unroll
;                     for (int n = 0; n < 2; ++n) {
;                         const size_t o = ro + bj * 128 + n * 16;
;                         const f32x4 xn = *(const f32x4*)(xo + o) + acc[ai][bj][m][n];
;                         *(f32x4*)(xf + o) = xn;
;                         u32x2 w; w.x = pk2(xn[0], xn[1]); w.y = pk2(xn[2], xn[3]); *(u32x2*)(xb + o) = w;
;                         s += (xn[0] * xn[0] + xn[1] * xn[1]) + (xn[2] * xn[2] + xn[3] * xn[3]);
;                     }
;                 s += __shfl_xor(s, 16); s += __shfl_xor(s, 32);
;                 if (fq == 0) ssq[(size_t)row * 16 + u.pn * 4 + wc] = s;
;             }
	s_waitcnt lgkmcnt(0)
	v_add_f32_e32 v82, v80, v81
	v_lshlrev_b64 v[80:81], 6, v[96:97]
	v_lshl_add_u64 v[80:81], s[24:25], 0, v[80:81]
	v_lshl_add_u64 v[80:81], s[40:41], 2, v[80:81]
	s_lshl_b32 s26, s74, 2
	v_lshl_add_u64 v[80:81], v[80:81], 0, s[26:27]
	global_store_dword v[80:81], v82, off
.LBB0_2184:
	s_or_b64 exec, exec, s[42:43]
	v_or_b32_e32 v80, 48, v138
	s_waitcnt lgkmcnt(0)
	v_ashrrev_i32_e32 v81, 31, v80
	v_lshlrev_b64 v[82:83], 10, v[80:81]
	v_lshl_add_u64 v[86:87], v[82:83], 0, v[136:137]
	v_lshlrev_b64 v[88:89], 2, v[86:87]
	v_lshl_add_u64 v[90:91], s[12:13], 0, v[88:89]
	v_lshl_add_u64 v[86:87], v[86:87], 1, s[22:23]
	v_lshl_add_u64 v[88:89], s[16:17], 0, v[88:89]
	s_waitcnt vmcnt(40)
	v_mov_b32_e32 v82, v236
	v_mov_b32_e32 v83, v237
	v_mov_b32_e32 v84, v238
	v_mov_b32_e32 v85, v239
	v_add_u32_e32 v163, 0xb0040, v162
	global_load_dwordx4 v[236:239], v163, s[12:13]
	v_pk_add_f32 v[78:79], v[78:79], v[84:85]
	v_pk_add_f32 v[76:77], v[76:77], v[82:83]
	global_store_dwordx4 v[88:89], v[76:79], off sc1
	v_cvt_pk_bf16_f32 v82, v76, v77
	v_cvt_pk_bf16_f32 v83, v78, v79
	global_store_dwordx2 v[86:87], v[82:83], off
	v_mul_f32_e32 v77, v77, v77
	v_mul_f32_e32 v79, v79, v79
	v_fmac_f32_e32 v77, v76, v76
	v_fmac_f32_e32 v79, v78, v78
	v_add_f32_e32 v76, v77, v79
	s_waitcnt vmcnt(42)
	v_mov_b32_e32 v82, v240
	v_mov_b32_e32 v83, v241
	v_mov_b32_e32 v84, v242
	v_mov_b32_e32 v85, v243
	v_add_u32_e32 v163, 0xb0200, v162
	global_load_dwordx4 v[240:243], v163, s[12:13]
	v_pk_add_f32 v[74:75], v[74:75], v[84:85]
	v_pk_add_f32 v[72:73], v[72:73], v[82:83]
	global_store_dwordx4 v[88:89], v[72:75], off offset:64 sc1
	v_cvt_pk_bf16_f32 v82, v72, v73
	v_cvt_pk_bf16_f32 v83, v74, v75
	global_store_dwordx2 v[86:87], v[82:83], off offset:32
	v_mul_f32_e32 v73, v73, v73
	v_mul_f32_e32 v75, v75, v75
	v_fmac_f32_e32 v73, v72, v72
	v_fmac_f32_e32 v75, v74, v74
	v_add_f32_e32 v72, v73, v75
	v_add_f32_e32 v72, v76, v72
	s_waitcnt vmcnt(44)
	v_mov_b32_e32 v82, v244
	v_mov_b32_e32 v83, v245
	v_mov_b32_e32 v84, v246
	v_mov_b32_e32 v85, v247
	v_add_u32_e32 v163, 0xb0240, v162
	global_load_dwordx4 v[244:247], v163, s[12:13]
	v_pk_add_f32 v[70:71], v[70:71], v[84:85]
	v_pk_add_f32 v[68:69], v[68:69], v[82:83]
	global_store_dwordx4 v[88:89], v[68:71], off offset:512 sc1
	v_cvt_pk_bf16_f32 v82, v68, v69
	v_cvt_pk_bf16_f32 v83, v70, v71
	global_store_dwordx2 v[86:87], v[82:83], off offset:256
	v_mul_f32_e32 v69, v69, v69
	v_mul_f32_e32 v71, v71, v71
	v_fmac_f32_e32 v69, v68, v68
	v_fmac_f32_e32 v71, v70, v70
	v_add_f32_e32 v68, v69, v71
	v_add_f32_e32 v70, v72, v68
	s_waitcnt vmcnt(46)
	v_mov_b32_e32 v82, v248
	v_mov_b32_e32 v83, v249
	v_mov_b32_e32 v84, v250
	v_mov_b32_e32 v85, v251
	v_pk_add_f32 v[68:69], v[66:67], v[84:85]
	v_pk_add_f32 v[66:67], v[64:65], v[82:83]
	v_mul_f32_e32 v65, v69, v69
	v_mul_f32_e32 v64, v67, v67
	v_fmac_f32_e32 v64, v66, v66
	v_fmac_f32_e32 v65, v68, v68
	v_add_f32_e32 v64, v64, v65
	v_add_f32_e32 v64, v70, v64
	ds_bpermute_b32 v65, v116, v64
	global_store_dwordx4 v[88:89], v[66:69], off offset:576 sc1
	s_waitcnt lgkmcnt(0)
	v_add_f32_e32 v64, v64, v65
	ds_bpermute_b32 v65, v114, v64
	v_cvt_pk_bf16_f32 v66, v66, v67
	v_cvt_pk_bf16_f32 v67, v68, v69
	global_store_dwordx2 v[86:87], v[66:67], off offset:288
	s_and_saveexec_b64 s[42:43], s[8:9]
	s_cbranch_execz .LBB0_2186
	s_waitcnt lgkmcnt(0)
	v_add_f32_e32 v66, v64, v65
	v_lshlrev_b64 v[64:65], 6, v[80:81]
	v_lshl_add_u64 v[64:65], s[24:25], 0, v[64:65]
	v_lshl_add_u64 v[64:65], s[40:41], 2, v[64:65]
	s_lshl_b32 s26, s74, 2
	v_lshl_add_u64 v[64:65], v[64:65], 0, s[26:27]
	global_store_dword v[64:65], v66, off
.LBB0_2186:
	s_or_b64 exec, exec, s[42:43]
	v_add_u32_e32 v64, 0x80, v138
	s_waitcnt lgkmcnt(0)
	v_ashrrev_i32_e32 v65, 31, v64
	v_lshlrev_b64 v[66:67], 10, v[64:65]
	v_lshl_add_u64 v[70:71], v[66:67], 0, v[136:137]
	v_lshlrev_b64 v[72:73], 2, v[70:71]
	v_lshl_add_u64 v[74:75], s[12:13], 0, v[72:73]
	v_lshl_add_u64 v[70:71], v[70:71], 1, s[22:23]
	v_lshl_add_u64 v[72:73], s[16:17], 0, v[72:73]
	s_waitcnt vmcnt(47)
	v_mov_b32_e32 v66, v252
	v_mov_b32_e32 v67, v253
	v_mov_b32_e32 v68, v254
	v_mov_b32_e32 v69, v255
	v_pk_add_f32 v[62:63], v[62:63], v[68:69]
	v_pk_add_f32 v[60:61], v[60:61], v[66:67]
	global_store_dwordx4 v[72:73], v[60:63], off sc1
	v_cvt_pk_bf16_f32 v66, v60, v61
	v_cvt_pk_bf16_f32 v67, v62, v63
	global_store_dwordx2 v[70:71], v[66:67], off
	v_mul_f32_e32 v61, v61, v61
	v_mul_f32_e32 v63, v63, v63
	v_fmac_f32_e32 v61, v60, v60
	v_fmac_f32_e32 v63, v62, v62
	v_add_f32_e32 v60, v61, v63
	s_waitcnt vmcnt(48)
	v_mov_b32_e32 v66, v170
	v_mov_b32_e32 v67, v171
	v_mov_b32_e32 v68, v172
	v_mov_b32_e32 v69, v173
	v_pk_add_f32 v[58:59], v[58:59], v[68:69]
	v_pk_add_f32 v[56:57], v[56:57], v[66:67]
	global_store_dwordx4 v[72:73], v[56:59], off offset:64 sc1
	v_cvt_pk_bf16_f32 v66, v56, v57
	v_cvt_pk_bf16_f32 v67, v58, v59
	global_store_dwordx2 v[70:71], v[66:67], off offset:32
	v_mul_f32_e32 v57, v57, v57
	v_mul_f32_e32 v59, v59, v59
	v_fmac_f32_e32 v57, v56, v56
	v_fmac_f32_e32 v59, v58, v58
	v_add_f32_e32 v56, v57, v59
	v_add_f32_e32 v56, v60, v56
	s_waitcnt vmcnt(47)
	v_mov_b32_e32 v66, v174
	v_mov_b32_e32 v67, v175
	v_mov_b32_e32 v68, v176
	v_mov_b32_e32 v69, v177
	v_pk_add_f32 v[54:55], v[54:55], v[68:69]
	v_pk_add_f32 v[52:53], v[52:53], v[66:67]
	global_store_dwordx4 v[72:73], v[52:55], off offset:512 sc1
	v_cvt_pk_bf16_f32 v66, v52, v53
	v_cvt_pk_bf16_f32 v67, v54, v55
	global_store_dwordx2 v[70:71], v[66:67], off offset:256
	v_mul_f32_e32 v53, v53, v53
	v_mul_f32_e32 v55, v55, v55
	v_fmac_f32_e32 v53, v52, v52
	v_fmac_f32_e32 v55, v54, v54
	v_add_f32_e32 v52, v53, v55
	v_add_f32_e32 v54, v56, v52
	s_waitcnt vmcnt(46)
	v_mov_b32_e32 v66, v178
	v_mov_b32_e32 v67, v179
	v_mov_b32_e32 v68, v180
	v_mov_b32_e32 v69, v181
	v_pk_add_f32 v[52:53], v[50:51], v[68:69]
	v_pk_add_f32 v[50:51], v[48:49], v[66:67]
	v_mul_f32_e32 v49, v53, v53
	v_mul_f32_e32 v48, v51, v51
	v_fmac_f32_e32 v48, v50, v50
	v_fmac_f32_e32 v49, v52, v52
	v_add_f32_e32 v48, v48, v49
	v_add_f32_e32 v48, v54, v48
	ds_bpermute_b32 v49, v116, v48
	global_store_dwordx4 v[72:73], v[50:53], off offset:576 sc1
	s_waitcnt lgkmcnt(0)
	v_add_f32_e32 v48, v48, v49
	ds_bpermute_b32 v49, v114, v48
	v_cvt_pk_bf16_f32 v50, v50, v51
	v_cvt_pk_bf16_f32 v51, v52, v53
	global_store_dwordx2 v[70:71], v[50:51], off offset:288
	s_and_saveexec_b64 s[42:43], s[8:9]
	s_cbranch_execz .LBB0_2188
	s_waitcnt lgkmcnt(0)
	v_add_f32_e32 v50, v48, v49
	v_lshlrev_b64 v[48:49], 6, v[64:65]
	v_lshl_add_u64 v[48:49], s[24:25], 0, v[48:49]
	v_lshl_add_u64 v[48:49], s[40:41], 2, v[48:49]
	s_lshl_b32 s26, s74, 2
	v_lshl_add_u64 v[48:49], v[48:49], 0, s[26:27]
	global_store_dword v[48:49], v50, off
; __device__ __forceinline__ unsigned pk2(float lo, float hi) { unsigned r; asm volatile("v_cvt_pk_bf16_f32 %0, %1, %2" : "=v"(r) : "v"(lo), "v"(hi)); return r; }
;     __device__ __forceinline__ void operator()(const f32x4 (&acc)[2][2][4][2], const Unit& u, int wr, int wc, int fr, int fq) const {
;     ...
;                 const int row = row0 + ai * 128 + m * 16; const size_t ro = (size_t)row * DM + col0;
;                 float s = 0.f;
; #pragma unroll
;                 for (int bj = 0; bj < 2; ++bj)
; #pragma unroll
;                     for (int n = 0; n < 2; ++n) {
;                         const size_t o = ro + bj * 128 + n * 16;
;                         const f32x4 xn = *(const f32x4*)(xo + o) + acc[ai][bj][m][n];
;                         *(f32x4*)(xf + o) = xn;
;                         u32x2 w; w.x = pk2(xn[0], xn[1]); w.y = pk2(xn[2], xn[3]); *(u32x2*)(xb + o) = w;
;                         s += (xn[0] * xn[0] + xn[1] * xn[1]) + (xn[2] * xn[2] + xn[3] * xn[3]);
;                     }
;                 s += __shfl_xor(s, 16); s += __shfl_xor(s, 32);
;                 if (fq == 0) ssq[(size_t)row * 16 + u.pn * 4 + wc] = s;
;             }
.LBB0_2188:
	s_or_b64 exec, exec, s[42:43]
	v_add_u32_e32 v48, 0x90, v138
	s_waitcnt lgkmcnt(0)
	v_ashrrev_i32_e32 v49, 31, v48
	v_lshlrev_b64 v[50:51], 10, v[48:49]
	v_lshl_add_u64 v[54:55], v[50:51], 0, v[136:137]
	v_lshlrev_b64 v[56:57], 2, v[54:55]
	v_lshl_add_u64 v[58:59], s[12:13], 0, v[56:57]
	v_lshl_add_u64 v[54:55], v[54:55], 1, s[22:23]
	v_lshl_add_u64 v[56:57], s[16:17], 0, v[56:57]
	s_waitcnt vmcnt(45)
	v_mov_b32_e32 v50, v182
	v_mov_b32_e32 v51, v183
	v_mov_b32_e32 v52, v184
	v_mov_b32_e32 v53, v185
	v_pk_add_f32 v[46:47], v[46:47], v[52:53]
	v_pk_add_f32 v[44:45], v[44:45], v[50:51]
	global_store_dwordx4 v[56:57], v[44:47], off sc1
	v_cvt_pk_bf16_f32 v50, v44, v45
	v_cvt_pk_bf16_f32 v51, v46, v47
	global_store_dwordx2 v[54:55], v[50:51], off
	v_mul_f32_e32 v45, v45, v45
	v_mul_f32_e32 v47, v47, v47
	v_fmac_f32_e32 v45, v44, v44
	v_fmac_f32_e32 v47, v46, v46
	v_add_f32_e32 v44, v45, v47
	s_waitcnt vmcnt(44)
	v_mov_b32_e32 v50, v186
	v_mov_b32_e32 v51, v187
	v_mov_b32_e32 v52, v188
	v_mov_b32_e32 v53, v189
	v_pk_add_f32 v[42:43], v[42:43], v[52:53]
	v_pk_add_f32 v[40:41], v[40:41], v[50:51]
	global_store_dwordx4 v[56:57], v[40:43], off offset:64 sc1
	v_cvt_pk_bf16_f32 v50, v40, v41
	v_cvt_pk_bf16_f32 v51, v42, v43
	global_store_dwordx2 v[54:55], v[50:51], off offset:32
	v_mul_f32_e32 v41, v41, v41
	v_mul_f32_e32 v43, v43, v43
	v_fmac_f32_e32 v41, v40, v40
	v_fmac_f32_e32 v43, v42, v42
	v_add_f32_e32 v40, v41, v43
	v_add_f32_e32 v40, v44, v40
	s_waitcnt vmcnt(43)
	v_mov_b32_e32 v50, v190
	v_mov_b32_e32 v51, v191
	v_mov_b32_e32 v52, v192
	v_mov_b32_e32 v53, v193
	v_pk_add_f32 v[38:39], v[38:39], v[52:53]
	v_pk_add_f32 v[36:37], v[36:37], v[50:51]
	global_store_dwordx4 v[56:57], v[36:39], off offset:512 sc1
	v_cvt_pk_bf16_f32 v50, v36, v37
	v_cvt_pk_bf16_f32 v51, v38, v39
	global_store_dwordx2 v[54:55], v[50:51], off offset:256
	v_mul_f32_e32 v37, v37, v37
	v_mul_f32_e32 v39, v39, v39
	v_fmac_f32_e32 v37, v36, v36
	v_fmac_f32_e32 v39, v38, v38
	v_add_f32_e32 v36, v37, v39
	v_add_f32_e32 v38, v40, v36
	s_waitcnt vmcnt(42)
	v_mov_b32_e32 v50, v194
	v_mov_b32_e32 v51, v195
	v_mov_b32_e32 v52, v196
	v_mov_b32_e32 v53, v197
	v_pk_add_f32 v[36:37], v[34:35], v[52:53]
	v_pk_add_f32 v[34:35], v[32:33], v[50:51]
	v_mul_f32_e32 v33, v37, v37
	v_mul_f32_e32 v32, v35, v35
	v_fmac_f32_e32 v32, v34, v34
	v_fmac_f32_e32 v33, v36, v36
	v_add_f32_e32 v32, v32, v33
	v_add_f32_e32 v32, v38, v32
	ds_bpermute_b32 v33, v116, v32
	global_store_dwordx4 v[56:57], v[34:37], off offset:576 sc1
	s_waitcnt lgkmcnt(0)
	v_add_f32_e32 v32, v32, v33
	ds_bpermute_b32 v33, v114, v32
	v_cvt_pk_bf16_f32 v34, v34, v35
	v_cvt_pk_bf16_f32 v35, v36, v37
	global_store_dwordx2 v[54:55], v[34:35], off offset:288
	s_and_saveexec_b64 s[42:43], s[8:9]
	s_cbranch_execz .LBB0_2190
	s_waitcnt lgkmcnt(0)
	v_add_f32_e32 v34, v32, v33
	v_lshlrev_b64 v[32:33], 6, v[48:49]
	v_lshl_add_u64 v[32:33], s[24:25], 0, v[32:33]
	v_lshl_add_u64 v[32:33], s[40:41], 2, v[32:33]
	s_lshl_b32 s26, s74, 2
	v_lshl_add_u64 v[32:33], v[32:33], 0, s[26:27]
	global_store_dword v[32:33], v34, off
; __device__ __forceinline__ unsigned pk2(float lo, float hi) { unsigned r; asm volatile("v_cvt_pk_bf16_f32 %0, %1, %2" : "=v"(r) : "v"(lo), "v"(hi)); return r; }
;     __device__ __forceinline__ void operator()(const f32x4 (&acc)[2][2][4][2], const Unit& u, int wr, int wc, int fr, int fq) const {
;     ...
;                 const int row = row0 + ai * 128 + m * 16; const size_t ro = (size_t)row * DM + col0;
;                 float s = 0.f;
; #pragma unroll
;                 for (int bj = 0; bj < 2; ++bj)
; #pragma unroll
;                     for (int n = 0; n < 2; ++n) {
;                         const size_t o = ro + bj * 128 + n * 16;
;                         const f32x4 xn = *(const f32x4*)(xo + o) + acc[ai][bj][m][n];
;                         *(f32x4*)(xf + o) = xn;
;                         u32x2 w; w.x = pk2(xn[0], xn[1]); w.y = pk2(xn[2], xn[3]); *(u32x2*)(xb + o) = w;
;                         s += (xn[0] * xn[0] + xn[1] * xn[1]) + (xn[2] * xn[2] + xn[3] * xn[3]);
;                     }
;                 s += __shfl_xor(s, 16); s += __shfl_xor(s, 32);
;                 if (fq == 0) ssq[(size_t)row * 16 + u.pn * 4 + wc] = s;
;             }
.LBB0_2190:
	s_or_b64 exec, exec, s[42:43]
	v_add_u32_e32 v32, 0xa0, v138
	s_waitcnt lgkmcnt(0)
	v_ashrrev_i32_e32 v33, 31, v32
	v_lshlrev_b64 v[34:35], 10, v[32:33]
	v_lshl_add_u64 v[38:39], v[34:35], 0, v[136:137]
	v_lshlrev_b64 v[40:41], 2, v[38:39]
	v_lshl_add_u64 v[42:43], s[12:13], 0, v[40:41]
	v_lshl_add_u64 v[38:39], v[38:39], 1, s[22:23]
	v_lshl_add_u64 v[40:41], s[16:17], 0, v[40:41]
	s_waitcnt vmcnt(41)
	v_mov_b32_e32 v34, v198
	v_mov_b32_e32 v35, v199
	v_mov_b32_e32 v36, v200
	v_mov_b32_e32 v37, v201
	v_pk_add_f32 v[30:31], v[30:31], v[36:37]
	v_pk_add_f32 v[28:29], v[28:29], v[34:35]
	global_store_dwordx4 v[40:41], v[28:31], off sc1
	v_cvt_pk_bf16_f32 v34, v28, v29
	v_cvt_pk_bf16_f32 v35, v30, v31
	global_store_dwordx2 v[38:39], v[34:35], off
	v_mul_f32_e32 v29, v29, v29
	v_mul_f32_e32 v31, v31, v31
	v_fmac_f32_e32 v29, v28, v28
	v_fmac_f32_e32 v31, v30, v30
	v_add_f32_e32 v28, v29, v31
	s_waitcnt vmcnt(40)
	v_mov_b32_e32 v34, v202
	v_mov_b32_e32 v35, v203
	v_mov_b32_e32 v36, v204
	v_mov_b32_e32 v37, v205
	v_pk_add_f32 v[26:27], v[26:27], v[36:37]
	v_pk_add_f32 v[24:25], v[24:25], v[34:35]
	global_store_dwordx4 v[40:41], v[24:27], off offset:64 sc1
	v_cvt_pk_bf16_f32 v34, v24, v25
	v_cvt_pk_bf16_f32 v35, v26, v27
	global_store_dwordx2 v[38:39], v[34:35], off offset:32
	v_mul_f32_e32 v25, v25, v25
	v_mul_f32_e32 v27, v27, v27
	v_fmac_f32_e32 v25, v24, v24
	v_fmac_f32_e32 v27, v26, v26
	v_add_f32_e32 v24, v25, v27
	v_add_f32_e32 v24, v28, v24
	s_waitcnt vmcnt(39)
	v_mov_b32_e32 v34, v206
	v_mov_b32_e32 v35, v207
	v_mov_b32_e32 v36, v208
	v_mov_b32_e32 v37, v209
	v_pk_add_f32 v[22:23], v[22:23], v[36:37]
	v_pk_add_f32 v[20:21], v[20:21], v[34:35]
	global_store_dwordx4 v[40:41], v[20:23], off offset:512 sc1
	v_cvt_pk_bf16_f32 v34, v20, v21
	v_cvt_pk_bf16_f32 v35, v22, v23
	global_store_dwordx2 v[38:39], v[34:35], off offset:256
	v_mul_f32_e32 v21, v21, v21
	v_mul_f32_e32 v23, v23, v23
	v_fmac_f32_e32 v21, v20, v20
	v_fmac_f32_e32 v23, v22, v22
	v_add_f32_e32 v20, v21, v23
	v_add_f32_e32 v22, v24, v20
	s_waitcnt vmcnt(38)
	v_mov_b32_e32 v34, v210
	v_mov_b32_e32 v35, v211
	v_mov_b32_e32 v36, v212
	v_mov_b32_e32 v37, v213
	v_pk_add_f32 v[20:21], v[18:19], v[36:37]
	v_pk_add_f32 v[18:19], v[16:17], v[34:35]
	v_mul_f32_e32 v17, v21, v21
	v_mul_f32_e32 v16, v19, v19
	v_fmac_f32_e32 v16, v18, v18
	v_fmac_f32_e32 v17, v20, v20
	v_add_f32_e32 v16, v16, v17
	v_add_f32_e32 v16, v22, v16
	ds_bpermute_b32 v17, v116, v16
	global_store_dwordx4 v[40:41], v[18:21], off offset:576 sc1
	s_waitcnt lgkmcnt(0)
	v_add_f32_e32 v16, v16, v17
	ds_bpermute_b32 v17, v114, v16
	v_cvt_pk_bf16_f32 v18, v18, v19
	v_cvt_pk_bf16_f32 v19, v20, v21
	global_store_dwordx2 v[38:39], v[18:19], off offset:288
	s_and_saveexec_b64 s[42:43], s[8:9]
	s_cbranch_execz .LBB0_2192
	s_waitcnt lgkmcnt(0)
	v_add_f32_e32 v18, v16, v17
	v_lshlrev_b64 v[16:17], 6, v[32:33]
	v_lshl_add_u64 v[16:17], s[24:25], 0, v[16:17]
	v_lshl_add_u64 v[16:17], s[40:41], 2, v[16:17]
	s_lshl_b32 s26, s74, 2
	v_lshl_add_u64 v[16:17], v[16:17], 0, s[26:27]
	global_store_dword v[16:17], v18, off
.LBB0_2192:
	s_or_b64 exec, exec, s[42:43]
	v_add_u32_e32 v16, 0xb0, v138
	s_waitcnt lgkmcnt(0)
	v_ashrrev_i32_e32 v17, 31, v16
	v_lshlrev_b64 v[18:19], 10, v[16:17]
	v_lshl_add_u64 v[22:23], v[18:19], 0, v[136:137]
	v_lshlrev_b64 v[24:25], 2, v[22:23]
	v_lshl_add_u64 v[26:27], s[12:13], 0, v[24:25]
	v_lshl_add_u64 v[22:23], v[22:23], 1, s[22:23]
	v_lshl_add_u64 v[24:25], s[16:17], 0, v[24:25]
	s_waitcnt vmcnt(37)
	v_mov_b32_e32 v18, v232
	v_mov_b32_e32 v19, v233
	v_mov_b32_e32 v20, v234
	v_mov_b32_e32 v21, v235
	v_pk_add_f32 v[14:15], v[14:15], v[20:21]
	v_pk_add_f32 v[12:13], v[12:13], v[18:19]
	global_store_dwordx4 v[24:25], v[12:15], off sc1
	v_cvt_pk_bf16_f32 v18, v12, v13
	v_cvt_pk_bf16_f32 v19, v14, v15
	global_store_dwordx2 v[22:23], v[18:19], off
	v_mul_f32_e32 v13, v13, v13
	v_mul_f32_e32 v15, v15, v15
	v_fmac_f32_e32 v13, v12, v12
	v_fmac_f32_e32 v15, v14, v14
	v_add_f32_e32 v12, v13, v15
	s_waitcnt vmcnt(36)
	v_mov_b32_e32 v18, v236
	v_mov_b32_e32 v19, v237
	v_mov_b32_e32 v20, v238
	v_mov_b32_e32 v21, v239
	v_pk_add_f32 v[10:11], v[10:11], v[20:21]
	v_pk_add_f32 v[8:9], v[8:9], v[18:19]
	global_store_dwordx4 v[24:25], v[8:11], off offset:64 sc1
	v_cvt_pk_bf16_f32 v18, v8, v9
	v_cvt_pk_bf16_f32 v19, v10, v11
	global_store_dwordx2 v[22:23], v[18:19], off offset:32
	v_mul_f32_e32 v9, v9, v9
	v_mul_f32_e32 v11, v11, v11
	v_fmac_f32_e32 v9, v8, v8
	v_fmac_f32_e32 v11, v10, v10
	v_add_f32_e32 v8, v9, v11
	v_add_f32_e32 v8, v12, v8
	s_waitcnt vmcnt(35)
	v_mov_b32_e32 v18, v240
	v_mov_b32_e32 v19, v241
	v_mov_b32_e32 v20, v242
	v_mov_b32_e32 v21, v243
	v_pk_add_f32 v[6:7], v[6:7], v[20:21]
	v_pk_add_f32 v[4:5], v[4:5], v[18:19]
	global_store_dwordx4 v[24:25], v[4:7], off offset:512 sc1
	v_cvt_pk_bf16_f32 v18, v4, v5
	v_cvt_pk_bf16_f32 v19, v6, v7
	global_store_dwordx2 v[22:23], v[18:19], off offset:256
	v_mul_f32_e32 v5, v5, v5
	v_mul_f32_e32 v7, v7, v7
	v_fmac_f32_e32 v5, v4, v4
	v_fmac_f32_e32 v7, v6, v6
	v_add_f32_e32 v4, v5, v7
	v_add_f32_e32 v6, v8, v4
	s_waitcnt vmcnt(34)
	v_mov_b32_e32 v18, v244
	v_mov_b32_e32 v19, v245
	v_mov_b32_e32 v20, v246
	v_mov_b32_e32 v21, v247
	v_pk_add_f32 v[4:5], v[2:3], v[20:21]
	v_pk_add_f32 v[2:3], v[0:1], v[18:19]
	v_mul_f32_e32 v1, v5, v5
	v_mul_f32_e32 v0, v3, v3
	v_fmac_f32_e32 v0, v2, v2
	v_fmac_f32_e32 v1, v4, v4
	v_add_f32_e32 v0, v0, v1
	v_add_f32_e32 v0, v6, v0
	ds_bpermute_b32 v1, v116, v0
	global_store_dwordx4 v[24:25], v[2:5], off offset:576 sc1
	s_waitcnt lgkmcnt(0)
	v_add_f32_e32 v0, v0, v1
	ds_bpermute_b32 v1, v114, v0
	v_cvt_pk_bf16_f32 v2, v2, v3
	v_cvt_pk_bf16_f32 v3, v4, v5
	global_store_dwordx2 v[22:23], v[2:3], off offset:288
	s_and_saveexec_b64 s[12:13], s[8:9]
	s_cbranch_execz .LBB0_2153
	s_waitcnt lgkmcnt(0)
	v_add_f32_e32 v2, v0, v1
	v_lshlrev_b64 v[0:1], 6, v[16:17]
	v_lshl_add_u64 v[0:1], s[24:25], 0, v[0:1]
	v_lshl_add_u64 v[0:1], s[40:41], 2, v[0:1]
	s_lshl_b32 s26, s74, 2
	v_lshl_add_u64 v[0:1], v[0:1], 0, s[26:27]
	global_store_dword v[0:1], v2, off
	s_branch .LBB0_2153

;     __device__ __forceinline__ void operator()(const f32x4 (&acc)[2][2][4][2], const Unit& u, int wr, int wc, int fr, int fq) const {
;         const int row0 = u.pm * 256 + wr * 64 + fr, col0 = u.pn * 256 + wc * 32 + 4 * fq;
; #pragma unroll
;         for (int ai = 0; ai < 2; ++ai)
; #pragma unroll
;             for (int m = 0; m < 4; ++m) { float* rowp = part + (size_t)(row0 + ai * 128 + m * 16) * DM + col0;
; #pragma unroll
;                 for (int bj = 0; bj < 2; ++bj)
; #pragma unroll
;                     for (int n = 0; n < 2; ++n) *(f32x4*)(rowp + bj * 128 + n * 16) = acc[ai][bj][m][n]; }
;     }
.LBB0_2222:
	v_lshl_add_u32 v138, s28, 8, v133
	v_lshl_or_b32 v140, s89, 8, v135
	v_ashrrev_i32_e32 v139, 31, v138
	v_ashrrev_i32_e32 v141, 31, v140
	v_lshlrev_b64 v[142:143], 12, v[138:139]
	v_lshl_add_u64 v[142:143], s[36:37], 0, v[142:143]
	v_lshlrev_b64 v[140:141], 2, v[140:141]
	v_lshl_add_u64 v[142:143], v[142:143], 0, v[140:141]
	global_store_dwordx4 v[142:143], v[124:127], off sc1
	global_store_dwordx4 v[142:143], v[120:123], off offset:64 sc1
	global_store_dwordx4 v[142:143], v[108:111], off offset:512 sc1
	global_store_dwordx4 v[142:143], v[100:103], off offset:576 sc1
	s_mov_b32 s18, 0x80000
	s_mov_b64 s[30:31], 0x80000
	v_or_b32_e32 v100, 16, v138
	v_ashrrev_i32_e32 v101, 31, v100
	v_lshlrev_b64 v[100:101], 12, v[100:101]
	v_lshl_add_u64 v[100:101], s[36:37], 0, v[100:101]
	v_lshl_add_u64 v[100:101], v[100:101], 0, v[140:141]
	global_store_dwordx4 v[100:101], v[116:119], off sc1
	global_store_dwordx4 v[100:101], v[112:115], off offset:64 sc1
	global_store_dwordx4 v[100:101], v[92:95], off offset:512 sc1
	global_store_dwordx4 v[100:101], v[84:87], off offset:576 sc1
	s_mov_b32 s89, s40
	s_mov_b32 s28, s42
	v_or_b32_e32 v84, 32, v138
	v_ashrrev_i32_e32 v85, 31, v84
	v_lshlrev_b64 v[84:85], 12, v[84:85]
	v_lshl_add_u64 v[84:85], s[36:37], 0, v[84:85]
	v_lshl_add_u64 v[84:85], v[84:85], 0, v[140:141]
	global_store_dwordx4 v[84:85], v[104:107], off sc1
	global_store_dwordx4 v[84:85], v[96:99], off offset:64 sc1
	global_store_dwordx4 v[84:85], v[76:79], off offset:512 sc1
	global_store_dwordx4 v[84:85], v[72:75], off offset:576 sc1
	s_mov_b64 s[34:35], s[56:57]
	s_nop 0
	v_or_b32_e32 v72, 48, v138
	v_ashrrev_i32_e32 v73, 31, v72
	v_lshlrev_b64 v[72:73], 12, v[72:73]
	v_lshl_add_u64 v[72:73], s[36:37], 0, v[72:73]
	v_lshl_add_u64 v[72:73], v[72:73], 0, v[140:141]
	global_store_dwordx4 v[72:73], v[88:91], off sc1
	global_store_dwordx4 v[72:73], v[80:83], off offset:64 sc1
	global_store_dwordx4 v[72:73], v[68:71], off offset:512 sc1
	global_store_dwordx4 v[72:73], v[64:67], off offset:576 sc1
	s_nop 1
	v_add_co_u32_e32 v66, vcc, s18, v142
	v_lshl_add_u64 v[64:65], v[142:143], 0, s[30:31]
	s_nop 0
	v_addc_co_u32_e32 v67, vcc, 0, v143, vcc
	global_store_dwordx4 v[66:67], v[60:63], off sc1
	global_store_dwordx4 v[64:65], v[56:59], off offset:64 sc1
	global_store_dwordx4 v[64:65], v[44:47], off offset:512 sc1
	global_store_dwordx4 v[64:65], v[36:39], off offset:576 sc1
	s_mov_b64 s[30:31], 0x90000
	s_nop 0
	v_add_co_u32_e32 v38, vcc, s75, v142
	v_lshl_add_u64 v[36:37], v[142:143], 0, s[30:31]
	s_nop 0
	v_addc_co_u32_e32 v39, vcc, 0, v143, vcc
	global_store_dwordx4 v[38:39], v[52:55], off sc1
	global_store_dwordx4 v[36:37], v[48:51], off offset:64 sc1
	global_store_dwordx4 v[36:37], v[28:31], off offset:512 sc1
	global_store_dwordx4 v[36:37], v[20:23], off offset:576 sc1
	s_mov_b64 s[30:31], s[54:55]
	s_nop 0
	v_add_co_u32_e32 v22, vcc, s76, v142
	v_lshl_add_u64 v[20:21], v[142:143], 0, s[24:25]
	s_nop 0
	v_addc_co_u32_e32 v23, vcc, 0, v143, vcc
	global_store_dwordx4 v[22:23], v[40:43], off sc1
	global_store_dwordx4 v[20:21], v[32:35], off offset:64 sc1
	global_store_dwordx4 v[20:21], v[12:15], off offset:512 sc1
	global_store_dwordx4 v[20:21], v[8:11], off offset:576 sc1
	s_nop 1
	v_add_co_u32_e32 v10, vcc, 0xb0000, v142
	v_lshl_add_u64 v[8:9], v[142:143], 0, s[26:27]
	s_nop 0
	v_addc_co_u32_e32 v11, vcc, 0, v143, vcc
	s_and_b64 vcc, exec, s[38:39]
	global_store_dwordx4 v[10:11], v[24:27], off sc1
	global_store_dwordx4 v[8:9], v[16:19], off offset:64 sc1
	global_store_dwordx4 v[8:9], v[4:7], off offset:512 sc1
	global_store_dwordx4 v[8:9], v[0:3], off offset:576 sc1
	s_cbranch_vccnz .LBB0_2247

; __device__ __forceinline__ unsigned pk2(float lo, float hi) { unsigned r; asm volatile("v_cvt_pk_bf16_f32 %0, %1, %2" : "=v"(r) : "v"(lo), "v"(hi)); return r; }
;     ...
;         __syncthreads();
;         const int lane = threadIdx.x & 63, wv = threadIdx.x >> 6;
;         const int rbase = u.pm * 256 + (kq * 4 + u.pn) * 16 + wv * 2;
; #pragma unroll
;         for (int rr = 0; rr < 2; ++rr) {
;             const int row = rbase + rr; float sq = 0.f;
; #pragma unroll
;             for (int i = 0; i < 4; ++i) {
;                 const size_t o = (size_t)row * DM + i * 256 + lane * 4;
;                 f32x4 v = *(const f32x4*)(xold + o);
; #pragma unroll
;                 for (int q = 0; q < 4; ++q) v += *(const f32x4*)(part + (size_t)q * 1024 * DM + o);
;                 *(f32x4*)(xf_s + o) = v;
;                 u32x2 w; w.x = pk2(v[0], v[1]); w.y = pk2(v[2], v[3]); *(u32x2*)(xb_s + o) = w;
;                 sq += (v[0] * v[0] + v[1] * v[1]) + (v[2] * v[2] + v[3] * v[3]);
;             }
; #pragma unroll
;             for (int o = 32; o >= 1; o >>= 1) sq += __shfl_xor(sq, o);
;             if (lane < 16) ssq_s[(size_t)row * 16 + lane] = lane == 0 ? sq : 0.f;
;         }
.LBB0_2262:
	s_or_b64 exec, exec, s[6:7]
	s_add_u32 s14, s16, 0x4000000
	s_addc_u32 s15, s17, 0
	s_add_u32 s12, s12, 0x2000000
	s_addc_u32 s13, s13, 0
	s_lshr_b32 s6, s51, 2
	v_lshrrev_b32_e32 v0, 5, v166
	s_and_b32 s6, s6, 0xffffffc
	v_and_b32_e32 v0, 30, v0
	s_add_i32 s22, s22, s6
	v_lshl_or_b32 v0, s23, 8, v0
	v_lshl_add_u32 v2, s22, 4, v0
	v_ashrrev_i32_e32 v3, 31, v2
	v_lshlrev_b32_e32 v0, 2, v167
	v_lshlrev_b64 v[4:5], 10, v[2:3]
	v_or_b32_e32 v4, v4, v0
	v_lshlrev_b64 v[10:11], 2, v[4:5]
	v_lshl_add_u64 v[38:39], s[10:11], 0, v[10:11]
	s_mov_b32 s18, 0x400000
	v_add_co_u32_e32 v40, vcc, s18, v38
	s_mov_b32 s19, 0x800000
	s_nop 0
	v_addc_co_u32_e32 v41, vcc, 0, v39, vcc
	v_lshl_add_u64 v[26:27], s[14:15], 0, v[10:11]
	v_add_co_u32_e32 v42, vcc, s19, v38
	s_barrier
	global_load_dwordx4 v[6:9], v[26:27], off
	v_addc_co_u32_e32 v43, vcc, 0, v39, vcc
	s_mov_b32 s20, 0xc00000
	global_load_dwordx4 v[10:13], v[38:39], off
	global_load_dwordx4 v[14:17], v[40:41], off
	v_add_co_u32_e32 v44, vcc, s20, v38
	global_load_dwordx4 v[18:21], v[42:43], off
	s_nop 0
	v_addc_co_u32_e32 v45, vcc, 0, v39, vcc
	global_load_dwordx4 v[22:25], v[44:45], off
	v_mov_b32_e32 v31, v5
	v_lshl_add_u64 v[28:29], v[4:5], 1, s[12:13]
	v_or_b32_e32 v30, 0x100, v4
	v_lshl_add_u64 v[32:33], v[30:31], 2, s[14:15]
	v_mov_b32_e32 v35, v5
	v_or_b32_e32 v34, 0x200, v4
	v_lshl_add_u64 v[30:31], v[30:31], 1, s[12:13]
	v_lshl_add_u64 v[36:37], v[34:35], 2, s[14:15]
	v_or_b32_e32 v4, 0x300, v4
	v_lshl_add_u64 v[34:35], v[34:35], 1, s[12:13]
	v_lshl_add_u64 v[46:47], v[4:5], 2, s[14:15]
	v_mov_b32_e32 v1, 0
	s_mov_b64 s[16:17], 0x100000
	v_cmp_gt_u32_e64 s[6:7], 16, v167
	v_cmp_eq_u32_e32 vcc, 0, v167
	v_lshl_add_u64 v[4:5], v[4:5], 1, s[12:13]
	global_load_dwordx4 v[186:189], v[32:33], off
	global_load_dwordx4 v[190:193], v[38:39], off offset:1024
	global_load_dwordx4 v[194:197], v[40:41], off offset:1024
	global_load_dwordx4 v[198:201], v[42:43], off offset:1024
	global_load_dwordx4 v[202:205], v[44:45], off offset:1024
	global_load_dwordx4 v[206:209], v[36:37], off
	global_load_dwordx4 v[210:213], v[38:39], off offset:2048
	global_load_dwordx4 v[214:217], v[40:41], off offset:2048
	global_load_dwordx4 v[218:221], v[42:43], off offset:2048
	global_load_dwordx4 v[222:225], v[44:45], off offset:2048
	global_load_dwordx4 v[226:229], v[46:47], off
	global_load_dwordx4 v[232:235], v[38:39], off offset:3072
	global_load_dwordx4 v[236:239], v[40:41], off offset:3072
	global_load_dwordx4 v[240:243], v[42:43], off offset:3072
	global_load_dwordx4 v[244:247], v[44:45], off offset:3072
	s_waitcnt vmcnt(18)
	v_pk_add_f32 v[8:9], v[8:9], v[12:13]
	v_pk_add_f32 v[6:7], v[6:7], v[10:11]
	s_waitcnt vmcnt(17)
	v_pk_add_f32 v[8:9], v[8:9], v[16:17]
	v_pk_add_f32 v[6:7], v[6:7], v[14:15]
	s_waitcnt vmcnt(16)
	v_pk_add_f32 v[8:9], v[8:9], v[20:21]
	v_pk_add_f32 v[6:7], v[6:7], v[18:19]
	s_waitcnt vmcnt(15)
	v_pk_add_f32 v[8:9], v[8:9], v[24:25]
	v_pk_add_f32 v[6:7], v[6:7], v[22:23]
	global_store_dwordx4 v[26:27], v[6:9], off sc1
	v_cvt_pk_bf16_f32 v10, v6, v7
	v_cvt_pk_bf16_f32 v11, v8, v9
	global_store_dwordx2 v[28:29], v[10:11], off
	s_nop 0
	v_mul_f32_e32 v7, v7, v7
	v_mul_f32_e32 v9, v9, v9
	v_fmac_f32_e32 v7, v6, v6
	v_fmac_f32_e32 v9, v8, v8
	v_add_f32_e32 v6, v7, v9
	s_waitcnt vmcnt(12)
	v_mov_b32_e32 v10, v186
	v_mov_b32_e32 v11, v187
	v_mov_b32_e32 v12, v188
	v_mov_b32_e32 v13, v189
	v_mov_b32_e32 v14, v190
	v_mov_b32_e32 v15, v191
	v_mov_b32_e32 v16, v192
	v_mov_b32_e32 v17, v193
	v_mov_b32_e32 v18, v194
	v_mov_b32_e32 v19, v195
	v_mov_b32_e32 v20, v196
	v_mov_b32_e32 v21, v197
	v_mov_b32_e32 v22, v198
	v_mov_b32_e32 v23, v199
	v_mov_b32_e32 v24, v200
	v_mov_b32_e32 v25, v201
	v_mov_b32_e32 v26, v202
	v_mov_b32_e32 v27, v203
	v_mov_b32_e32 v28, v204
	v_mov_b32_e32 v29, v205
	v_pk_add_f32 v[12:13], v[12:13], v[16:17]
	v_pk_add_f32 v[10:11], v[10:11], v[14:15]
	v_pk_add_f32 v[12:13], v[12:13], v[20:21]
	v_pk_add_f32 v[10:11], v[10:11], v[18:19]
	v_pk_add_f32 v[12:13], v[12:13], v[24:25]
	v_pk_add_f32 v[10:11], v[10:11], v[22:23]
	v_pk_add_f32 v[12:13], v[12:13], v[28:29]
	v_pk_add_f32 v[10:11], v[10:11], v[26:27]
	global_store_dwordx4 v[32:33], v[10:13], off sc1
	v_cvt_pk_bf16_f32 v14, v10, v11
	v_cvt_pk_bf16_f32 v15, v12, v13
	global_store_dwordx2 v[30:31], v[14:15], off
	s_nop 0
	v_mul_f32_e32 v7, v11, v11
	v_mul_f32_e32 v8, v13, v13
	v_fmac_f32_e32 v7, v10, v10
	v_fmac_f32_e32 v8, v12, v12
	v_add_f32_e32 v7, v7, v8
	v_add_f32_e32 v6, v6, v7
	s_waitcnt vmcnt(9)
	v_mov_b32_e32 v14, v206
	v_mov_b32_e32 v15, v207
	v_mov_b32_e32 v16, v208
	v_mov_b32_e32 v17, v209
	v_mov_b32_e32 v18, v210
	v_mov_b32_e32 v19, v211
	v_mov_b32_e32 v20, v212
	v_mov_b32_e32 v21, v213
	v_mov_b32_e32 v22, v214
	v_mov_b32_e32 v23, v215
	v_mov_b32_e32 v24, v216
	v_mov_b32_e32 v25, v217
	v_mov_b32_e32 v26, v218
	v_mov_b32_e32 v27, v219
	v_mov_b32_e32 v28, v220
	v_mov_b32_e32 v29, v221
	v_mov_b32_e32 v30, v222
	v_mov_b32_e32 v31, v223
	v_mov_b32_e32 v32, v224
	v_mov_b32_e32 v33, v225
	v_pk_add_f32 v[16:17], v[16:17], v[20:21]
	v_pk_add_f32 v[14:15], v[14:15], v[18:19]
	v_pk_add_f32 v[16:17], v[16:17], v[24:25]
	v_pk_add_f32 v[14:15], v[14:15], v[22:23]
	v_pk_add_f32 v[16:17], v[16:17], v[28:29]
	v_pk_add_f32 v[14:15], v[14:15], v[26:27]
	v_pk_add_f32 v[16:17], v[16:17], v[32:33]
	v_pk_add_f32 v[14:15], v[14:15], v[30:31]
	global_store_dwordx4 v[36:37], v[14:17], off sc1
	v_cvt_pk_bf16_f32 v18, v14, v15
	v_cvt_pk_bf16_f32 v19, v16, v17
	global_store_dwordx2 v[34:35], v[18:19], off
	s_nop 0
	v_mul_f32_e32 v7, v15, v15
	v_mul_f32_e32 v8, v17, v17
	v_fmac_f32_e32 v7, v14, v14
	v_fmac_f32_e32 v8, v16, v16
	v_add_f32_e32 v7, v7, v8
	v_add_f32_e32 v10, v6, v7
	v_mbcnt_hi_u32_b32 v40, -1, v168
	v_lshl_add_u64 v[38:39], s[8:9], 0, v[0:1]
	v_and_b32_e32 v1, 64, v40
	v_xor_b32_e32 v41, 32, v40
	v_add_u32_e32 v43, 64, v1
	v_cmp_lt_i32_e64 s[8:9], v41, v43
	v_xor_b32_e32 v42, 16, v40
	v_xor_b32_e32 v11, 2, v40
	v_cndmask_b32_e64 v1, v40, v41, s[8:9]
	v_lshlrev_b32_e32 v1, 2, v1
	v_cmp_lt_i32_e64 s[8:9], v42, v43
	v_xor_b32_e32 v12, 1, v40
	s_waitcnt vmcnt(6)
; __device__ __forceinline__ unsigned pk2(float lo, float hi) { unsigned r; asm volatile("v_cvt_pk_bf16_f32 %0, %1, %2" : "=v"(r) : "v"(lo), "v"(hi)); return r; }
;     ...
;             const int row = rbase + rr; float sq = 0.f;
; #pragma unroll
;             for (int i = 0; i < 4; ++i) {
;                 const size_t o = (size_t)row * DM + i * 256 + lane * 4;
;                 f32x4 v = *(const f32x4*)(xold + o);
; #pragma unroll
;                 for (int q = 0; q < 4; ++q) v += *(const f32x4*)(part + (size_t)q * 1024 * DM + o);
;                 *(f32x4*)(xf_s + o) = v;
;                 u32x2 w; w.x = pk2(v[0], v[1]); w.y = pk2(v[2], v[3]); *(u32x2*)(xb_s + o) = w;
;                 sq += (v[0] * v[0] + v[1] * v[1]) + (v[2] * v[2] + v[3] * v[3]);
;             }
; #pragma unroll
;             for (int o = 32; o >= 1; o >>= 1) sq += __shfl_xor(sq, o);
;             if (lane < 16) ssq_s[(size_t)row * 16 + lane] = lane == 0 ? sq : 0.f;
;         }
	v_mov_b32_e32 v18, v226
	v_mov_b32_e32 v19, v227
	v_mov_b32_e32 v20, v228
	v_mov_b32_e32 v21, v229
	v_mov_b32_e32 v22, v232
	v_mov_b32_e32 v23, v233
	v_mov_b32_e32 v24, v234
	v_mov_b32_e32 v25, v235
	v_mov_b32_e32 v26, v236
	v_mov_b32_e32 v27, v237
	v_mov_b32_e32 v28, v238
	v_mov_b32_e32 v29, v239
	v_mov_b32_e32 v30, v240
	v_mov_b32_e32 v31, v241
	v_mov_b32_e32 v32, v242
	v_mov_b32_e32 v33, v243
	v_mov_b32_e32 v34, v244
	v_mov_b32_e32 v35, v245
	v_mov_b32_e32 v36, v246
	v_mov_b32_e32 v37, v247
	v_pk_add_f32 v[6:7], v[20:21], v[24:25]
	v_pk_add_f32 v[8:9], v[18:19], v[22:23]
	v_pk_add_f32 v[6:7], v[6:7], v[28:29]
	v_pk_add_f32 v[8:9], v[8:9], v[26:27]
	v_pk_add_f32 v[6:7], v[6:7], v[32:33]
	v_pk_add_f32 v[8:9], v[8:9], v[30:31]
	v_pk_add_f32 v[18:19], v[6:7], v[36:37]
	v_pk_add_f32 v[16:17], v[8:9], v[34:35]
	v_mul_f32_e32 v7, v19, v19
	v_mul_f32_e32 v6, v17, v17
	v_fmac_f32_e32 v6, v16, v16
	v_fmac_f32_e32 v7, v18, v18
	v_add_f32_e32 v6, v6, v7
	v_add_f32_e32 v6, v10, v6
	ds_bpermute_b32 v7, v1, v6
	v_cndmask_b32_e64 v8, v40, v42, s[8:9]
	v_lshlrev_b32_e32 v8, 2, v8
	v_xor_b32_e32 v9, 8, v40
	v_cmp_lt_i32_e64 s[8:9], v9, v43
	s_waitcnt lgkmcnt(0)
	v_add_f32_e32 v6, v6, v7
	ds_bpermute_b32 v7, v8, v6
	v_cndmask_b32_e64 v9, v40, v9, s[8:9]
	v_lshlrev_b32_e32 v9, 2, v9
	v_xor_b32_e32 v10, 4, v40
	v_cmp_lt_i32_e64 s[8:9], v10, v43
	s_waitcnt lgkmcnt(0)
	v_add_f32_e32 v6, v6, v7
	ds_bpermute_b32 v7, v9, v6
	v_cndmask_b32_e64 v10, v40, v10, s[8:9]
	v_lshlrev_b32_e32 v10, 2, v10
	v_cmp_lt_i32_e64 s[8:9], v11, v43
	global_store_dwordx4 v[46:47], v[16:19], off sc1
	s_waitcnt lgkmcnt(0)
	v_add_f32_e32 v6, v6, v7
	ds_bpermute_b32 v7, v10, v6
	v_cndmask_b32_e64 v11, v40, v11, s[8:9]
	v_lshlrev_b32_e32 v11, 2, v11
	v_cmp_lt_i32_e64 s[8:9], v12, v43
	v_cvt_pk_bf16_f32 v16, v16, v17
	s_waitcnt lgkmcnt(0)
	v_add_f32_e32 v13, v6, v7
	ds_bpermute_b32 v14, v11, v13
	v_cndmask_b32_e64 v12, v40, v12, s[8:9]
	v_lshlrev_b32_e32 v12, 2, v12
	v_lshl_add_u64 v[6:7], v[38:39], 0, s[16:17]
	v_cvt_pk_bf16_f32 v17, v18, v19
	s_waitcnt lgkmcnt(0)
	v_add_f32_e32 v13, v13, v14
	ds_bpermute_b32 v14, v12, v13
	global_store_dwordx2 v[4:5], v[16:17], off
	s_and_saveexec_b64 s[8:9], s[6:7]
	s_cbranch_execz .LBB0_2264
	v_lshlrev_b64 v[4:5], 6, v[2:3]
	s_waitcnt lgkmcnt(0)
	v_add_f32_e32 v3, v13, v14
	v_lshl_add_u64 v[4:5], v[6:7], 0, v[4:5]
	v_cndmask_b32_e32 v3, 0, v3, vcc
	global_store_dword v[4:5], v3, off
.LBB0_2264:
	s_or_b64 exec, exec, s[8:9]
	v_or_b32_e32 v2, 1, v2
	v_ashrrev_i32_e32 v3, 31, v2
	v_lshlrev_b64 v[4:5], 10, v[2:3]
	v_or_b32_e32 v4, v4, v0
	v_lshlrev_b64 v[18:19], 2, v[4:5]
	v_lshl_add_u64 v[46:47], s[10:11], 0, v[18:19]
	v_add_co_u32_e64 v48, s[8:9], s18, v46
	v_lshl_add_u64 v[34:35], s[14:15], 0, v[18:19]
	s_nop 0
	v_addc_co_u32_e64 v49, s[8:9], 0, v47, s[8:9]
	v_add_co_u32_e64 v50, s[8:9], s19, v46
	s_waitcnt lgkmcnt(0)
	global_load_dwordx4 v[14:17], v[34:35], off
	v_addc_co_u32_e64 v51, s[8:9], 0, v47, s[8:9]
	global_load_dwordx4 v[18:21], v[46:47], off
	global_load_dwordx4 v[22:25], v[48:49], off
	v_add_co_u32_e64 v52, s[8:9], s20, v46
	global_load_dwordx4 v[26:29], v[50:51], off
	s_nop 0
	v_addc_co_u32_e64 v53, s[8:9], 0, v47, s[8:9]
	global_load_dwordx4 v[30:33], v[52:53], off
	v_mov_b32_e32 v39, v5
	v_lshl_add_u64 v[36:37], v[4:5], 1, s[12:13]
	v_or_b32_e32 v38, 0x100, v4
	v_lshl_add_u64 v[40:41], v[38:39], 2, s[14:15]
	v_mov_b32_e32 v43, v5
	v_or_b32_e32 v42, 0x200, v4
	v_lshl_add_u64 v[38:39], v[38:39], 1, s[12:13]
	v_lshl_add_u64 v[44:45], v[42:43], 2, s[14:15]
	v_or_b32_e32 v4, 0x300, v4
	v_lshl_add_u64 v[42:43], v[42:43], 1, s[12:13]
	v_lshl_add_u64 v[54:55], v[4:5], 2, s[14:15]
	v_lshl_add_u64 v[4:5], v[4:5], 1, s[12:13]
	global_load_dwordx4 v[186:189], v[40:41], off
	global_load_dwordx4 v[190:193], v[46:47], off offset:1024
	global_load_dwordx4 v[194:197], v[48:49], off offset:1024
	global_load_dwordx4 v[198:201], v[50:51], off offset:1024
	global_load_dwordx4 v[202:205], v[52:53], off offset:1024
	global_load_dwordx4 v[206:209], v[44:45], off
	global_load_dwordx4 v[210:213], v[46:47], off offset:2048
	global_load_dwordx4 v[214:217], v[48:49], off offset:2048
	global_load_dwordx4 v[218:221], v[50:51], off offset:2048
	global_load_dwordx4 v[222:225], v[52:53], off offset:2048
	global_load_dwordx4 v[226:229], v[54:55], off
	global_load_dwordx4 v[232:235], v[46:47], off offset:3072
	global_load_dwordx4 v[236:239], v[48:49], off offset:3072
	global_load_dwordx4 v[240:243], v[50:51], off offset:3072
	global_load_dwordx4 v[244:247], v[52:53], off offset:3072
	s_waitcnt vmcnt(18)
	v_pk_add_f32 v[16:17], v[16:17], v[20:21]
	v_pk_add_f32 v[14:15], v[14:15], v[18:19]
	s_waitcnt vmcnt(17)
	v_pk_add_f32 v[16:17], v[16:17], v[24:25]
	v_pk_add_f32 v[14:15], v[14:15], v[22:23]
	s_waitcnt vmcnt(16)
; __device__ __forceinline__ unsigned pk2(float lo, float hi) { unsigned r; asm volatile("v_cvt_pk_bf16_f32 %0, %1, %2" : "=v"(r) : "v"(lo), "v"(hi)); return r; }
;     ...
;             const int row = rbase + rr; float sq = 0.f;
; #pragma unroll
;             for (int i = 0; i < 4; ++i) {
;                 const size_t o = (size_t)row * DM + i * 256 + lane * 4;
;                 f32x4 v = *(const f32x4*)(xold + o);
; #pragma unroll
;                 for (int q = 0; q < 4; ++q) v += *(const f32x4*)(part + (size_t)q * 1024 * DM + o);
;                 *(f32x4*)(xf_s + o) = v;
;                 u32x2 w; w.x = pk2(v[0], v[1]); w.y = pk2(v[2], v[3]); *(u32x2*)(xb_s + o) = w;
;                 sq += (v[0] * v[0] + v[1] * v[1]) + (v[2] * v[2] + v[3] * v[3]);
;             }
; #pragma unroll
;             for (int o = 32; o >= 1; o >>= 1) sq += __shfl_xor(sq, o);
;             if (lane < 16) ssq_s[(size_t)row * 16 + lane] = lane == 0 ? sq : 0.f;
;         }
	v_pk_add_f32 v[16:17], v[16:17], v[28:29]
	v_pk_add_f32 v[14:15], v[14:15], v[26:27]
	s_waitcnt vmcnt(15)
	v_pk_add_f32 v[16:17], v[16:17], v[32:33]
	v_pk_add_f32 v[14:15], v[14:15], v[30:31]
	global_store_dwordx4 v[34:35], v[14:17], off sc1
	v_cvt_pk_bf16_f32 v18, v14, v15
	v_cvt_pk_bf16_f32 v19, v16, v17
	global_store_dwordx2 v[36:37], v[18:19], off
	s_nop 0
	v_mul_f32_e32 v0, v15, v15
	v_mul_f32_e32 v13, v17, v17
	v_fmac_f32_e32 v0, v14, v14
	v_fmac_f32_e32 v13, v16, v16
	v_add_f32_e32 v0, v0, v13
	s_waitcnt vmcnt(12)
	v_mov_b32_e32 v18, v186
	v_mov_b32_e32 v19, v187
	v_mov_b32_e32 v20, v188
	v_mov_b32_e32 v21, v189
	v_mov_b32_e32 v22, v190
	v_mov_b32_e32 v23, v191
	v_mov_b32_e32 v24, v192
	v_mov_b32_e32 v25, v193
	v_mov_b32_e32 v26, v194
	v_mov_b32_e32 v27, v195
	v_mov_b32_e32 v28, v196
	v_mov_b32_e32 v29, v197
	v_mov_b32_e32 v30, v198
	v_mov_b32_e32 v31, v199
	v_mov_b32_e32 v32, v200
	v_mov_b32_e32 v33, v201
	v_mov_b32_e32 v34, v202
	v_mov_b32_e32 v35, v203
	v_mov_b32_e32 v36, v204
	v_mov_b32_e32 v37, v205
	v_pk_add_f32 v[20:21], v[20:21], v[24:25]
	v_pk_add_f32 v[18:19], v[18:19], v[22:23]
	v_pk_add_f32 v[20:21], v[20:21], v[28:29]
	v_pk_add_f32 v[18:19], v[18:19], v[26:27]
	v_pk_add_f32 v[20:21], v[20:21], v[32:33]
	v_pk_add_f32 v[18:19], v[18:19], v[30:31]
	v_pk_add_f32 v[20:21], v[20:21], v[36:37]
	v_pk_add_f32 v[18:19], v[18:19], v[34:35]
	global_store_dwordx4 v[40:41], v[18:21], off sc1
	v_cvt_pk_bf16_f32 v22, v18, v19
	v_cvt_pk_bf16_f32 v23, v20, v21
	global_store_dwordx2 v[38:39], v[22:23], off
	s_nop 0
	v_mul_f32_e32 v13, v19, v19
	v_mul_f32_e32 v14, v21, v21
	v_fmac_f32_e32 v13, v18, v18
	v_fmac_f32_e32 v14, v20, v20
	v_add_f32_e32 v13, v13, v14
	v_add_f32_e32 v0, v0, v13
	s_waitcnt vmcnt(9)
	v_mov_b32_e32 v22, v206
	v_mov_b32_e32 v23, v207
	v_mov_b32_e32 v24, v208
	v_mov_b32_e32 v25, v209
	v_mov_b32_e32 v26, v210
	v_mov_b32_e32 v27, v211
	v_mov_b32_e32 v28, v212
	v_mov_b32_e32 v29, v213
	v_mov_b32_e32 v30, v214
	v_mov_b32_e32 v31, v215
	v_mov_b32_e32 v32, v216
	v_mov_b32_e32 v33, v217
	v_mov_b32_e32 v34, v218
	v_mov_b32_e32 v35, v219
	v_mov_b32_e32 v36, v220
	v_mov_b32_e32 v37, v221
	v_mov_b32_e32 v38, v222
	v_mov_b32_e32 v39, v223
	v_mov_b32_e32 v40, v224
	v_mov_b32_e32 v41, v225
	v_pk_add_f32 v[24:25], v[24:25], v[28:29]
	v_pk_add_f32 v[22:23], v[22:23], v[26:27]
	v_pk_add_f32 v[24:25], v[24:25], v[32:33]
	v_pk_add_f32 v[22:23], v[22:23], v[30:31]
	v_pk_add_f32 v[24:25], v[24:25], v[36:37]
	v_pk_add_f32 v[22:23], v[22:23], v[34:35]
	v_pk_add_f32 v[24:25], v[24:25], v[40:41]
	v_pk_add_f32 v[22:23], v[22:23], v[38:39]
	global_store_dwordx4 v[44:45], v[22:25], off sc1
	v_cvt_pk_bf16_f32 v26, v22, v23
	v_cvt_pk_bf16_f32 v27, v24, v25
	global_store_dwordx2 v[42:43], v[26:27], off
	s_nop 0
	v_mul_f32_e32 v13, v23, v23
	v_mul_f32_e32 v14, v25, v25
	v_fmac_f32_e32 v13, v22, v22
	v_fmac_f32_e32 v14, v24, v24
	v_add_f32_e32 v13, v13, v14
	v_add_f32_e32 v0, v0, v13
	s_waitcnt vmcnt(6)
	v_mov_b32_e32 v26, v226
	v_mov_b32_e32 v27, v227
	v_mov_b32_e32 v28, v228
	v_mov_b32_e32 v29, v229
	v_mov_b32_e32 v30, v232
	v_mov_b32_e32 v31, v233
	v_mov_b32_e32 v32, v234
	v_mov_b32_e32 v33, v235
	v_mov_b32_e32 v34, v236
	v_mov_b32_e32 v35, v237
	v_mov_b32_e32 v36, v238
	v_mov_b32_e32 v37, v239
	v_mov_b32_e32 v38, v240
	v_mov_b32_e32 v39, v241
	v_mov_b32_e32 v40, v242
	v_mov_b32_e32 v41, v243
	v_mov_b32_e32 v42, v244
	v_mov_b32_e32 v43, v245
	v_mov_b32_e32 v44, v246
	v_mov_b32_e32 v45, v247
	v_pk_add_f32 v[14:15], v[28:29], v[32:33]
	v_pk_add_f32 v[16:17], v[26:27], v[30:31]
	v_pk_add_f32 v[14:15], v[14:15], v[36:37]
	v_pk_add_f32 v[16:17], v[16:17], v[34:35]
	v_pk_add_f32 v[14:15], v[14:15], v[40:41]
	v_pk_add_f32 v[18:19], v[16:17], v[38:39]
	v_pk_add_f32 v[16:17], v[14:15], v[44:45]
	v_pk_add_f32 v[14:15], v[18:19], v[42:43]
	v_mul_f32_e32 v18, v17, v17
	v_mul_f32_e32 v13, v15, v15
	v_fmac_f32_e32 v13, v14, v14
	v_fmac_f32_e32 v18, v16, v16
	v_add_f32_e32 v13, v13, v18
	v_add_f32_e32 v0, v0, v13
	ds_bpermute_b32 v1, v1, v0
	global_store_dwordx4 v[54:55], v[14:17], off sc1
	s_waitcnt lgkmcnt(0)
	v_add_f32_e32 v0, v0, v1
	ds_bpermute_b32 v1, v8, v0
	v_cvt_pk_bf16_f32 v8, v14, v15
	s_waitcnt lgkmcnt(0)
	v_add_f32_e32 v0, v0, v1
	ds_bpermute_b32 v1, v9, v0
	v_cvt_pk_bf16_f32 v9, v16, v17
	global_store_dwordx2 v[4:5], v[8:9], off
	s_waitcnt lgkmcnt(0)
	v_add_f32_e32 v0, v0, v1
	ds_bpermute_b32 v1, v10, v0
	s_waitcnt lgkmcnt(0)
	v_add_f32_e32 v0, v0, v1
	ds_bpermute_b32 v1, v11, v0
	s_waitcnt lgkmcnt(0)
	v_add_f32_e32 v0, v0, v1
	ds_bpermute_b32 v1, v12, v0
	s_and_saveexec_b64 s[8:9], s[6:7]
	s_cbranch_execz .LBB0_2266
	v_lshlrev_b64 v[2:3], 6, v[2:3]
	s_waitcnt lgkmcnt(0)
	v_add_f32_e32 v0, v0, v1
	v_lshl_add_u64 v[2:3], v[6:7], 0, v[2:3]
	v_cndmask_b32_e32 v0, 0, v0, vcc
	global_store_dword v[2:3], v0, off

; #define KP(f) ((decltype(Params::f))karg_ptr<(int)offsetof(Params, f)>())
; __device__ __forceinline__ float row_rstd(const float* ssq, int row) {
;     const f32x4* p = (const f32x4*)(ssq + (size_t)row * 16);
;     const f32x4 a = p[0], b = p[1], c = p[2], d = p[3];
;     const float s = ((a[0] + a[1]) + (a[2] + a[3])) + ((b[0] + b[1]) + (b[2] + b[3])) + ((c[0] + c[1]) + (c[2] + c[3])) + ((d[0] + d[1]) + (d[2] + d[3]));
;     return rsqrtf(s * (1.0f / 1024.0f) + 1e-6f);
; }
; __device__ void phase_final() {
;     float* out = KP(out); const float* ssq = KP(ssq); const float* fg = KP(final_g);
;     const int lane = threadIdx.x & 63, gw = blockIdx.x * 8 + (threadIdx.x >> 6), nw = gridDim.x * 8;
;     for (int row = gw; row < T_ALL; row += nw) {
;         const float rs = row_rstd(ssq, row);
;         float* xr = out + (size_t)row * DM;
; #pragma unroll
;         for (int i = 0; i < 4; ++i) { const int c = i * 256 + lane * 4; const f32x4 v = *(const f32x4*)(xr + c); const f32x4 g = *(const f32x4*)(fg + c);
;             *(f32x4*)(xr + c) = v * rs * g; }
;     }
; }
.LBB0_2319:
	s_or_b64 exec, exec, s[6:7]
	s_waitcnt lgkmcnt(0)
	s_barrier
	v_readlane_b32 s8, v230, 4
	s_load_dwordx2 s[2:3], s[0:1], 0xd8
	s_waitcnt lgkmcnt(0)
	s_load_dwordx2 s[4:5], s[0:1], 0x128
	s_waitcnt lgkmcnt(0)
	s_load_dwordx2 s[0:1], s[0:1], 0xd0
	s_waitcnt lgkmcnt(0)
	v_readlane_b32 s9, v230, 5
	s_and_saveexec_b64 s[6:7], s[8:9]
	s_cbranch_execz .LBB0_2322
	v_lshlrev_b32_e32 v0, 4, v166
	v_lshlrev_b64 v[2:3], 6, v[144:145]
	v_lshlrev_b64 v[4:5], 12, v[144:145]
	v_and_b32_e32 v0, 0x3f0, v0
	v_mov_b32_e32 v1, 0
	v_lshl_add_u64 v[2:3], s[4:5], 0, v[2:3]
	s_ashr_i32 s51, s50, 31
	v_lshl_or_b32 v4, v167, 4, v4
	v_lshl_add_u64 v[0:1], s[0:1], 0, v[0:1]
	v_lshl_add_u64 v[2:3], v[2:3], 0, 32
	s_lshl_b64 s[0:1], s[50:51], 6
	v_lshl_add_u64 v[4:5], s[2:3], 0, v[4:5]
	s_lshl_b64 s[2:3], s[50:51], 12
	s_mov_b64 s[4:5], 0
	v_mov_b32_e32 v6, 0x358637bd
	s_mov_b32 s6, 0x800000
	s_movk_i32 s7, 0x43ff
	global_load_dwordx4 v[40:43], v[0:1], off
	global_load_dwordx4 v[44:47], v[0:1], off offset:1024
	global_load_dwordx4 v[48:51], v[0:1], off offset:2048
	global_load_dwordx4 v[52:55], v[0:1], off offset:3072
	v_mov_b64_e32 v[92:93], v[4:5]
	global_load_dwordx4 v[8:11], v[2:3], off offset:-32
	global_load_dwordx4 v[12:15], v[2:3], off offset:-16
	global_load_dwordx4 v[16:19], v[2:3], off
	global_load_dwordx4 v[20:23], v[2:3], off offset:16
	global_load_dwordx4 v[24:27], v[4:5], off
	global_load_dwordx4 v[28:31], v[4:5], off offset:1024
	global_load_dwordx4 v[32:35], v[4:5], off offset:2048
	global_load_dwordx4 v[36:39], v[4:5], off offset:3072
	v_add_u32_e32 v144, s50, v144
	v_lshl_add_u64 v[2:3], v[2:3], 0, s[0:1]
	v_lshl_add_u64 v[4:5], v[4:5], 0, s[2:3]
	v_cmp_ge_i32_e32 vcc, s7, v144
	s_cbranch_vccz .Lfin_lastA
	v_mov_b64_e32 v[94:95], v[4:5]
	global_load_dwordx4 v[56:59], v[2:3], off offset:-32
	global_load_dwordx4 v[60:63], v[2:3], off offset:-16
	global_load_dwordx4 v[64:67], v[2:3], off
	global_load_dwordx4 v[68:71], v[2:3], off offset:16
	global_load_dwordx4 v[72:75], v[4:5], off
	global_load_dwordx4 v[76:79], v[4:5], off offset:1024
	global_load_dwordx4 v[80:83], v[4:5], off offset:2048
	global_load_dwordx4 v[84:87], v[4:5], off offset:3072
	s_waitcnt vmcnt(8)
	v_add_f32_e32 v96, v8, v9
	v_add_f32_e32 v97, v10, v11
	v_add_f32_e32 v98, v12, v13
	v_add_f32_e32 v99, v14, v15
	v_add_f32_e32 v100, v16, v17
	v_add_f32_e32 v101, v18, v19
	v_add_f32_e32 v102, v20, v21
	v_add_f32_e32 v103, v22, v23
	v_add_f32_e32 v96, v96, v97
	v_add_f32_e32 v98, v98, v99
	v_add_f32_e32 v100, v100, v101
	v_add_f32_e32 v102, v102, v103
	v_add_f32_e32 v96, v96, v98
	v_add_f32_e32 v96, v96, v100
	v_add_f32_e32 v96, v96, v102
	v_fmamk_f32 v96, v96, 0x3a800000, v6
	v_mul_f32_e32 v97, 0x4b800000, v96
	v_cmp_gt_f32_e32 vcc, s6, v96
	s_nop 1
	v_cndmask_b32_e32 v96, v96, v97, vcc
	v_rsq_f32_e32 v96, v96
	s_nop 0
	v_mul_f32_e32 v97, 0x45800000, v96
	v_cndmask_b32_e32 v90, v96, v97, vcc
	v_pk_mul_f32 v[24:25], v[24:25], v[90:91] op_sel_hi:[1,0]
	v_pk_mul_f32 v[26:27], v[26:27], v[90:91] op_sel_hi:[1,0]
	v_pk_mul_f32 v[24:25], v[40:41], v[24:25]
	v_pk_mul_f32 v[26:27], v[42:43], v[26:27]
	global_store_dwordx4 v[92:93], v[24:27], off sc1
	v_pk_mul_f32 v[28:29], v[28:29], v[90:91] op_sel_hi:[1,0]
	v_pk_mul_f32 v[30:31], v[30:31], v[90:91] op_sel_hi:[1,0]
	v_pk_mul_f32 v[28:29], v[44:45], v[28:29]
	v_pk_mul_f32 v[30:31], v[46:47], v[30:31]
	global_store_dwordx4 v[92:93], v[28:31], off offset:1024 sc1
	v_pk_mul_f32 v[32:33], v[32:33], v[90:91] op_sel_hi:[1,0]
	v_pk_mul_f32 v[34:35], v[34:35], v[90:91] op_sel_hi:[1,0]
	v_pk_mul_f32 v[32:33], v[48:49], v[32:33]
	v_pk_mul_f32 v[34:35], v[50:51], v[34:35]
	global_store_dwordx4 v[92:93], v[32:35], off offset:2048 sc1
	v_pk_mul_f32 v[36:37], v[36:37], v[90:91] op_sel_hi:[1,0]
	v_pk_mul_f32 v[38:39], v[38:39], v[90:91] op_sel_hi:[1,0]
	v_pk_mul_f32 v[36:37], v[52:53], v[36:37]
	v_pk_mul_f32 v[38:39], v[54:55], v[38:39]
	global_store_dwordx4 v[92:93], v[36:39], off offset:3072 sc1
.Lfin_loop:
	v_add_u32_e32 v144, s50, v144
	v_lshl_add_u64 v[2:3], v[2:3], 0, s[0:1]
	v_lshl_add_u64 v[4:5], v[4:5], 0, s[2:3]
	v_cmp_ge_i32_e32 vcc, s7, v144
	s_cbranch_vccz .Lfin_lastB
	v_mov_b64_e32 v[92:93], v[4:5]
	global_load_dwordx4 v[8:11], v[2:3], off offset:-32
	global_load_dwordx4 v[12:15], v[2:3], off offset:-16
	global_load_dwordx4 v[16:19], v[2:3], off
	global_load_dwordx4 v[20:23], v[2:3], off offset:16
	global_load_dwordx4 v[24:27], v[4:5], off
	global_load_dwordx4 v[28:31], v[4:5], off offset:1024
	global_load_dwordx4 v[32:35], v[4:5], off offset:2048
	global_load_dwordx4 v[36:39], v[4:5], off offset:3072
	s_waitcnt vmcnt(12)
	v_add_f32_e32 v96, v56, v57
	v_add_f32_e32 v97, v58, v59
	v_add_f32_e32 v98, v60, v61
	v_add_f32_e32 v99, v62, v63
	v_add_f32_e32 v100, v64, v65
	v_add_f32_e32 v101, v66, v67
	v_add_f32_e32 v102, v68, v69
	v_add_f32_e32 v103, v70, v71
	v_add_f32_e32 v96, v96, v97
	v_add_f32_e32 v98, v98, v99
	v_add_f32_e32 v100, v100, v101
	v_add_f32_e32 v102, v102, v103
	v_add_f32_e32 v96, v96, v98
	v_add_f32_e32 v96, v96, v100
	v_add_f32_e32 v96, v96, v102
	v_fmamk_f32 v96, v96, 0x3a800000, v6
	v_mul_f32_e32 v97, 0x4b800000, v96
	v_cmp_gt_f32_e32 vcc, s6, v96
	s_nop 1
	v_cndmask_b32_e32 v96, v96, v97, vcc
	v_rsq_f32_e32 v96, v96
	s_nop 0
	v_mul_f32_e32 v97, 0x45800000, v96
	v_cndmask_b32_e32 v90, v96, v97, vcc
	v_pk_mul_f32 v[72:73], v[72:73], v[90:91] op_sel_hi:[1,0]
	v_pk_mul_f32 v[74:75], v[74:75], v[90:91] op_sel_hi:[1,0]
	v_pk_mul_f32 v[72:73], v[40:41], v[72:73]
	v_pk_mul_f32 v[74:75], v[42:43], v[74:75]
	global_store_dwordx4 v[94:95], v[72:75], off sc1
	v_pk_mul_f32 v[76:77], v[76:77], v[90:91] op_sel_hi:[1,0]
	v_pk_mul_f32 v[78:79], v[78:79], v[90:91] op_sel_hi:[1,0]
	v_pk_mul_f32 v[76:77], v[44:45], v[76:77]
	v_pk_mul_f32 v[78:79], v[46:47], v[78:79]
	global_store_dwordx4 v[94:95], v[76:79], off offset:1024 sc1
	v_pk_mul_f32 v[80:81], v[80:81], v[90:91] op_sel_hi:[1,0]
	v_pk_mul_f32 v[82:83], v[82:83], v[90:91] op_sel_hi:[1,0]
	v_pk_mul_f32 v[80:81], v[48:49], v[80:81]
	v_pk_mul_f32 v[82:83], v[50:51], v[82:83]
	global_store_dwordx4 v[94:95], v[80:83], off offset:2048 sc1
	v_pk_mul_f32 v[84:85], v[84:85], v[90:91] op_sel_hi:[1,0]
	v_pk_mul_f32 v[86:87], v[86:87], v[90:91] op_sel_hi:[1,0]
	v_pk_mul_f32 v[84:85], v[52:53], v[84:85]
	v_pk_mul_f32 v[86:87], v[54:55], v[86:87]
	global_store_dwordx4 v[94:95], v[84:87], off offset:3072 sc1
	v_add_u32_e32 v144, s50, v144
	v_lshl_add_u64 v[2:3], v[2:3], 0, s[0:1]
	v_lshl_add_u64 v[4:5], v[4:5], 0, s[2:3]
	v_cmp_ge_i32_e32 vcc, s7, v144
	s_cbranch_vccz .Lfin_lastA
; #define KP(f) ((decltype(Params::f))karg_ptr<(int)offsetof(Params, f)>())
; __device__ __forceinline__ float row_rstd(const float* ssq, int row) {
;     const f32x4* p = (const f32x4*)(ssq + (size_t)row * 16);
;     const f32x4 a = p[0], b = p[1], c = p[2], d = p[3];
;     const float s = ((a[0] + a[1]) + (a[2] + a[3])) + ((b[0] + b[1]) + (b[2] + b[3])) + ((c[0] + c[1]) + (c[2] + c[3])) + ((d[0] + d[1]) + (d[2] + d[3]));
;     return rsqrtf(s * (1.0f / 1024.0f) + 1e-6f);
; }
; __device__ void phase_final() {
;     float* out = KP(out); const float* ssq = KP(ssq); const float* fg = KP(final_g);
;     const int lane = threadIdx.x & 63, gw = blockIdx.x * 8 + (threadIdx.x >> 6), nw = gridDim.x * 8;
;     for (int row = gw; row < T_ALL; row += nw) {
;         const float rs = row_rstd(ssq, row);
;         float* xr = out + (size_t)row * DM;
; #pragma unroll
;         for (int i = 0; i < 4; ++i) { const int c = i * 256 + lane * 4; const f32x4 v = *(const f32x4*)(xr + c); const f32x4 g = *(const f32x4*)(fg + c);
;             *(f32x4*)(xr + c) = v * rs * g; }
;     }
; }
	v_mov_b64_e32 v[94:95], v[4:5]
	global_load_dwordx4 v[56:59], v[2:3], off offset:-32
	global_load_dwordx4 v[60:63], v[2:3], off offset:-16
	global_load_dwordx4 v[64:67], v[2:3], off
	global_load_dwordx4 v[68:71], v[2:3], off offset:16
	global_load_dwordx4 v[72:75], v[4:5], off
	global_load_dwordx4 v[76:79], v[4:5], off offset:1024
	global_load_dwordx4 v[80:83], v[4:5], off offset:2048
	global_load_dwordx4 v[84:87], v[4:5], off offset:3072
	s_waitcnt vmcnt(12)
	v_add_f32_e32 v96, v8, v9
	v_add_f32_e32 v97, v10, v11
	v_add_f32_e32 v98, v12, v13
	v_add_f32_e32 v99, v14, v15
	v_add_f32_e32 v100, v16, v17
	v_add_f32_e32 v101, v18, v19
	v_add_f32_e32 v102, v20, v21
	v_add_f32_e32 v103, v22, v23
	v_add_f32_e32 v96, v96, v97
	v_add_f32_e32 v98, v98, v99
	v_add_f32_e32 v100, v100, v101
	v_add_f32_e32 v102, v102, v103
	v_add_f32_e32 v96, v96, v98
	v_add_f32_e32 v96, v96, v100
	v_add_f32_e32 v96, v96, v102
	v_fmamk_f32 v96, v96, 0x3a800000, v6
	v_mul_f32_e32 v97, 0x4b800000, v96
	v_cmp_gt_f32_e32 vcc, s6, v96
	s_nop 1
	v_cndmask_b32_e32 v96, v96, v97, vcc
	v_rsq_f32_e32 v96, v96
	s_nop 0
	v_mul_f32_e32 v97, 0x45800000, v96
	v_cndmask_b32_e32 v90, v96, v97, vcc
	v_pk_mul_f32 v[24:25], v[24:25], v[90:91] op_sel_hi:[1,0]
	v_pk_mul_f32 v[26:27], v[26:27], v[90:91] op_sel_hi:[1,0]
	v_pk_mul_f32 v[24:25], v[40:41], v[24:25]
	v_pk_mul_f32 v[26:27], v[42:43], v[26:27]
	global_store_dwordx4 v[92:93], v[24:27], off sc1
	v_pk_mul_f32 v[28:29], v[28:29], v[90:91] op_sel_hi:[1,0]
	v_pk_mul_f32 v[30:31], v[30:31], v[90:91] op_sel_hi:[1,0]
	v_pk_mul_f32 v[28:29], v[44:45], v[28:29]
	v_pk_mul_f32 v[30:31], v[46:47], v[30:31]
	global_store_dwordx4 v[92:93], v[28:31], off offset:1024 sc1
	v_pk_mul_f32 v[32:33], v[32:33], v[90:91] op_sel_hi:[1,0]
	v_pk_mul_f32 v[34:35], v[34:35], v[90:91] op_sel_hi:[1,0]
	v_pk_mul_f32 v[32:33], v[48:49], v[32:33]
	v_pk_mul_f32 v[34:35], v[50:51], v[34:35]
	global_store_dwordx4 v[92:93], v[32:35], off offset:2048 sc1
	v_pk_mul_f32 v[36:37], v[36:37], v[90:91] op_sel_hi:[1,0]
	v_pk_mul_f32 v[38:39], v[38:39], v[90:91] op_sel_hi:[1,0]
	v_pk_mul_f32 v[36:37], v[52:53], v[36:37]
	v_pk_mul_f32 v[38:39], v[54:55], v[38:39]
	global_store_dwordx4 v[92:93], v[36:39], off offset:3072 sc1
	s_branch .Lfin_loop
.Lfin_lastA:
	s_waitcnt vmcnt(0)
	v_add_f32_e32 v96, v8, v9
	v_add_f32_e32 v97, v10, v11
	v_add_f32_e32 v98, v12, v13
	v_add_f32_e32 v99, v14, v15
	v_add_f32_e32 v100, v16, v17
	v_add_f32_e32 v101, v18, v19
	v_add_f32_e32 v102, v20, v21
	v_add_f32_e32 v103, v22, v23
	v_add_f32_e32 v96, v96, v97
	v_add_f32_e32 v98, v98, v99
	v_add_f32_e32 v100, v100, v101
	v_add_f32_e32 v102, v102, v103
	v_add_f32_e32 v96, v96, v98
	v_add_f32_e32 v96, v96, v100
	v_add_f32_e32 v96, v96, v102
	v_fmamk_f32 v96, v96, 0x3a800000, v6
	v_mul_f32_e32 v97, 0x4b800000, v96
	v_cmp_gt_f32_e32 vcc, s6, v96
	s_nop 1
	v_cndmask_b32_e32 v96, v96, v97, vcc
	v_rsq_f32_e32 v96, v96
	s_nop 0
	v_mul_f32_e32 v97, 0x45800000, v96
	v_cndmask_b32_e32 v90, v96, v97, vcc
	v_pk_mul_f32 v[24:25], v[24:25], v[90:91] op_sel_hi:[1,0]
	v_pk_mul_f32 v[26:27], v[26:27], v[90:91] op_sel_hi:[1,0]
	v_pk_mul_f32 v[24:25], v[40:41], v[24:25]
	v_pk_mul_f32 v[26:27], v[42:43], v[26:27]
	global_store_dwordx4 v[92:93], v[24:27], off sc1
	v_pk_mul_f32 v[28:29], v[28:29], v[90:91] op_sel_hi:[1,0]
	v_pk_mul_f32 v[30:31], v[30:31], v[90:91] op_sel_hi:[1,0]
	v_pk_mul_f32 v[28:29], v[44:45], v[28:29]
	v_pk_mul_f32 v[30:31], v[46:47], v[30:31]
	global_store_dwordx4 v[92:93], v[28:31], off offset:1024 sc1
	v_pk_mul_f32 v[32:33], v[32:33], v[90:91] op_sel_hi:[1,0]
	v_pk_mul_f32 v[34:35], v[34:35], v[90:91] op_sel_hi:[1,0]
	v_pk_mul_f32 v[32:33], v[48:49], v[32:33]
	v_pk_mul_f32 v[34:35], v[50:51], v[34:35]
	global_store_dwordx4 v[92:93], v[32:35], off offset:2048 sc1
	v_pk_mul_f32 v[36:37], v[36:37], v[90:91] op_sel_hi:[1,0]
	v_pk_mul_f32 v[38:39], v[38:39], v[90:91] op_sel_hi:[1,0]
	v_pk_mul_f32 v[36:37], v[52:53], v[36:37]
	v_pk_mul_f32 v[38:39], v[54:55], v[38:39]
	global_store_dwordx4 v[92:93], v[36:39], off offset:3072 sc1
	s_branch .LBB0_2322
.Lfin_lastB:
	s_waitcnt vmcnt(0)
	v_add_f32_e32 v96, v56, v57
	v_add_f32_e32 v97, v58, v59
	v_add_f32_e32 v98, v60, v61
	v_add_f32_e32 v99, v62, v63
	v_add_f32_e32 v100, v64, v65
	v_add_f32_e32 v101, v66, v67
	v_add_f32_e32 v102, v68, v69
	v_add_f32_e32 v103, v70, v71
	v_add_f32_e32 v96, v96, v97
	v_add_f32_e32 v98, v98, v99
	v_add_f32_e32 v100, v100, v101
	v_add_f32_e32 v102, v102, v103
	v_add_f32_e32 v96, v96, v98
	v_add_f32_e32 v96, v96, v100
	v_add_f32_e32 v96, v96, v102
	v_fmamk_f32 v96, v96, 0x3a800000, v6
	v_mul_f32_e32 v97, 0x4b800000, v96
	v_cmp_gt_f32_e32 vcc, s6, v96
	s_nop 1
	v_cndmask_b32_e32 v96, v96, v97, vcc
	v_rsq_f32_e32 v96, v96
	s_nop 0
	v_mul_f32_e32 v97, 0x45800000, v96
	v_cndmask_b32_e32 v90, v96, v97, vcc
	v_pk_mul_f32 v[72:73], v[72:73], v[90:91] op_sel_hi:[1,0]
	v_pk_mul_f32 v[74:75], v[74:75], v[90:91] op_sel_hi:[1,0]
	v_pk_mul_f32 v[72:73], v[40:41], v[72:73]
	v_pk_mul_f32 v[74:75], v[42:43], v[74:75]
	global_store_dwordx4 v[94:95], v[72:75], off sc1
	v_pk_mul_f32 v[76:77], v[76:77], v[90:91] op_sel_hi:[1,0]
	v_pk_mul_f32 v[78:79], v[78:79], v[90:91] op_sel_hi:[1,0]
	v_pk_mul_f32 v[76:77], v[44:45], v[76:77]
	v_pk_mul_f32 v[78:79], v[46:47], v[78:79]
	global_store_dwordx4 v[94:95], v[76:79], off offset:1024 sc1
	v_pk_mul_f32 v[80:81], v[80:81], v[90:91] op_sel_hi:[1,0]
	v_pk_mul_f32 v[82:83], v[82:83], v[90:91] op_sel_hi:[1,0]
	v_pk_mul_f32 v[80:81], v[48:49], v[80:81]
	v_pk_mul_f32 v[82:83], v[50:51], v[82:83]
	global_store_dwordx4 v[94:95], v[80:83], off offset:2048 sc1
	v_pk_mul_f32 v[84:85], v[84:85], v[90:91] op_sel_hi:[1,0]
	v_pk_mul_f32 v[86:87], v[86:87], v[90:91] op_sel_hi:[1,0]
	v_pk_mul_f32 v[84:85], v[52:53], v[84:85]
	v_pk_mul_f32 v[86:87], v[54:55], v[86:87]
	global_store_dwordx4 v[94:95], v[84:87], off offset:3072 sc1
